# pipelined dil loop: 6 of the group's exps issued before the wait on the next group's K write/readback LDS round trip
# speedup vs baseline: 1.0046x; 1.0011x over previous
; #define LAS __attribute__((address_space(3)))
; #define GAS __attribute__((address_space(1)))
; __device__ __forceinline__ void dil_unit(LAS unsigned char* lds, bf16_t* proj, int seq, int hd, int T0, int rho) {
;     ...
;     const int tid = tid_, lane = tid & 63, r32 = lane & 31, hi = lane >> 5, wid = __builtin_amdgcn_readfirstlane(tid >> 6);
;     bf16_t* base = proj + (size_t)seq * SEQ * NIN;
;     LAS unsigned char* wbuf = lds + wid * 4096;
;     const LAS unsigned char* vp = wbuf + ((lane >> 4) & 1) * 32 + (lane & 3) * 8 + (4 * hi + ((lane & 15) >> 2)) * 64;
;     const int P0 = T0 + rho;
;     bf16x8 qr[4];
; #pragma unroll
;     for (int ks = 0; ks < 4; ++ks) qr[ks] = *(const GAS bf16x8*)(base + (size_t)(P0 + 16 * r32) * NIN + PC_LQ + hd * 64 + 16 * ks + 8 * hi);
;     f32x16 o0 = {}, o1 = {}; float l = 0.f;
;     const bool bound = (T0 < 1024) || (T0 >= 15360);
; __device__ __forceinline__ void attn_phase(unsigned char* ws, int l, LAS unsigned char* lds, int G) {
;     ...
;         const int sh = bu >> 6, rem = bu & 63, T0 = (rem >> 1) * 512, rho = (rem & 1) * 8 + wid;
;         dil_unit(lds, proj, sh / 6, sh % 6, T0, rho);
.LBB0_554:
	s_lshr_b32 s82, s33, 8
	s_mul_i32 s82, s82, 13
	s_add_i32 s82, s82, s33
	s_ashr_i32 s2, s33, 6
	s_mul_hi_i32 s7, s2, 0x2aaaaaab
	s_lshl_b32 s3, s82, 8
	s_lshr_b32 s8, s7, 31
	s_and_b32 s6, s3, 0x3e00
	s_lshl_b32 s3, s82, 3
	s_add_i32 s7, s7, s8
	s_and_b32 s3, s3, 8
	s_mul_i32 s8, s7, 6
	s_add_i32 s3, s3, s64
	s_sub_i32 s8, s2, s8
	s_mul_hi_i32 s2, s7, 0x6000000
	s_mul_i32 s7, s7, 0x6000000
	v_mov_b32_e32 v2, v154
	s_add_u32 s56, s48, s7
	s_addc_u32 s57, s49, s2
	v_and_b32_e32 v105, 31, v2
	s_add_i32 s76, s3, s6
	v_lshl_add_u32 v3, v105, 4, s76
	v_mov_b64_e32 v[0:1], s[56:57]
	s_lshl_b32 s58, s8, 6
	v_bfe_u32 v106, v2, 5, 1
	v_mad_u64_u32 v[0:1], s[2:3], v3, s65, v[0:1]
	s_ashr_i32 s59, s58, 31
	v_lshl_add_u64 v[0:1], s[58:59], 1, v[0:1]
	v_lshlrev_b32_e32 v80, 4, v106
	v_lshl_add_u64 v[0:1], v[0:1], 0, v[80:81]
	global_load_dwordx4 v[48:51], v[0:1], off offset:1280
	global_load_dwordx4 v[52:55], v[0:1], off offset:1312
	global_load_dwordx4 v[56:59], v[0:1], off offset:1344
	global_load_dwordx4 v[60:63], v[0:1], off offset:1376
	v_readfirstlane_b32 s2, v2
	s_lshl_b32 s2, s2, 6
	s_and_b32 s2, s2, 0xfffff000
	v_lshlrev_b32_e32 v0, 1, v2
	v_lshlrev_b32_e32 v104, 3, v2
	v_lshlrev_b32_e32 v107, 2, v106
	v_lshrrev_b32_e32 v1, 2, v2
	v_and_b32_e32 v103, 63, v2
	v_and_b32_e32 v0, 32, v0
	v_and_b32_e32 v98, 24, v104
	v_and_or_b32 v1, v1, 3, v107
	s_add_i32 s77, s2, 0
	v_lshlrev_b32_e32 v108, 6, v1
	v_lshlrev_b32_e32 v1, 3, v106
	v_add3_u32 v109, s77, v0, v98
	s_addk_i32 s6, 0xc400
	v_lshrrev_b32_e32 v110, 2, v103
	v_lshlrev_b32_e32 v0, 4, v103
	s_mov_b64 s[2:3], -1
	s_cmp_gt_u32 s6, 0xffffc7ff
	v_lshlrev_b32_e32 v100, 1, v98
	s_mul_i32 s6, s8, 0x1c00
	v_lshlrev_b32_e32 v82, 1, v1
	v_or_b32_e32 v111, 16, v110
	v_add_u32_e32 v112, s77, v0
	s_cbranch_scc0 .LBB0_558
	s_movk_i32 s100, 0x1800
	s_add_i32 s101, s6, 0x15c00
	s_lshl_b32 s90, s58, 1
	s_add_u32 s82, s56, s90
	s_addc_u32 s83, s57, 0
	s_add_u32 s82, s82, 0x1200
	s_addc_u32 s83, s83, 0
	s_sub_i32 s90, s76, 64
	s_mul_i32 s90, s90, 0x1800
	s_add_u32 s84, s82, s90
	s_addc_u32 s85, s83, 0
	s_sub_i32 s90, s76, 256
	s_mul_i32 s90, s90, 0x1800
	s_add_u32 s86, s82, s90
	s_addc_u32 s87, s83, 0
	s_sub_i32 s90, s76, 1024
	s_mul_i32 s90, s90, 0x1800
	s_add_u32 s88, s82, s90
	s_addc_u32 s89, s83, 0
	v_lshlrev_b32_e32 v153, 1, v98
	v_mad_u32_u24 v80, v105, s100, v82
	v_mad_u32_u24 v100, v110, s100, v153
	v_add_u32_e32 v149, 0x18000, v100
	v_lshlrev_b32_e32 v83, 2, v105
	v_mad_u32_u24 v83, v83, s100, v82
	v_lshlrev_b32_e32 v101, 2, v110
	v_mad_u32_u24 v101, v101, s100, v153
	v_add_u32_e32 v150, 0x60000, v101
	v_lshlrev_b32_e32 v99, 4, v105
	v_mad_u32_u24 v99, v99, s100, v82
	v_lshlrev_b32_e32 v148, 4, v110
	v_mad_u32_u24 v148, v148, s100, v153
	v_add_u32_e32 v151, 0x180000, v148
	v_lshrrev_b32_e32 v249, 3, v103
	v_and_b32_e32 v250, 7, v103
	v_lshlrev_b32_e32 v250, 4, v250
	v_add_u32_e32 v235, 0, v249
	v_mad_u32_u24 v235, v235, s100, v250
	v_add_u32_e32 v236, 8, v249
	v_mad_u32_u24 v236, v236, s100, v250
	v_add_u32_e32 v237, 16, v249
	v_mad_u32_u24 v237, v237, s100, v250
	v_add_u32_e32 v238, 24, v249
	v_mad_u32_u24 v238, v238, s100, v250
	v_add_u32_e32 v239, 0, v249
	v_lshlrev_b32_e32 v239, 2, v239
	v_mad_u32_u24 v239, v239, s100, v250
	v_add_u32_e32 v240, 8, v249
	v_lshlrev_b32_e32 v240, 2, v240
	v_mad_u32_u24 v240, v240, s100, v250
	v_add_u32_e32 v241, 16, v249
	v_lshlrev_b32_e32 v241, 2, v241
	v_mad_u32_u24 v241, v241, s100, v250
	v_add_u32_e32 v242, 24, v249
	v_lshlrev_b32_e32 v242, 2, v242
	v_mad_u32_u24 v242, v242, s100, v250
	v_add_u32_e32 v243, 0, v249
	v_lshlrev_b32_e32 v243, 4, v243
	v_mad_u32_u24 v243, v243, s100, v250
	v_add_u32_e32 v244, 8, v249
	v_lshlrev_b32_e32 v244, 4, v244
	v_mad_u32_u24 v244, v244, s100, v250
	v_add_u32_e32 v245, 16, v249
	v_lshlrev_b32_e32 v245, 4, v245
	v_mad_u32_u24 v245, v245, s100, v250
	v_add_u32_e32 v246, 24, v249
	v_lshlrev_b32_e32 v246, 4, v246
	v_mad_u32_u24 v246, v246, s100, v250
	v_and_b32_e32 v247, 7, v249
	v_lshlrev_b32_e32 v247, 4, v247
	v_xor_b32_e32 v247, v247, v112
	v_and_b32_e32 v153, 7, v105
	v_or_b32_e32 v248, 0, v106
	v_xor_b32_e32 v248, v248, v153
	v_lshlrev_b32_e32 v248, 4, v248
	v_lshl_add_u32 v248, v105, 7, v248
	v_add_u32_e32 v248, s77, v248
	v_or_b32_e32 v249, 2, v106
	v_xor_b32_e32 v249, v249, v153
	v_lshlrev_b32_e32 v249, 4, v249
	v_lshl_add_u32 v249, v105, 7, v249
	v_add_u32_e32 v249, s77, v249
	v_or_b32_e32 v250, 4, v106
	v_xor_b32_e32 v250, v250, v153
	v_lshlrev_b32_e32 v250, 4, v250
	v_lshl_add_u32 v250, v105, 7, v250
	v_add_u32_e32 v250, s77, v250
	v_or_b32_e32 v251, 6, v106
	v_xor_b32_e32 v251, v251, v153
	v_lshlrev_b32_e32 v251, 4, v251
	v_lshl_add_u32 v251, v105, 7, v251
	v_add_u32_e32 v251, s77, v251
	v_lshlrev_b32_e32 v153, 1, v98
	v_mul_u32_u24_e32 v228, 17, v105
	v_sub_u32_e32 v228, v107, v228
	s_mul_i32 s90, s58, 153
	s_lshr_b32 s90, s90, 1
	s_add_i32 s90, s90, 34876
	v_lshl_add_u32 v228, v228, 2, s90
	v_lshlrev_b32_e32 v229, 2, v105
	v_sub_u32_e32 v229, v107, v229
	s_add_i32 s90, s101, 5104
	v_lshl_add_u32 v229, v229, 2, s90
	v_sub_u32_e32 v230, v107, v105
	s_add_i32 s90, s101, 6364
	v_lshl_add_u32 v230, v230, 2, s90
	v_add_u32_e32 v231, v109, v108
	v_mov_b64_e32 v[232:233], 0
	v_mov_b64_e32 v[0:1], 0
	v_mov_b64_e32 v[2:3], 0
	v_mov_b64_e32 v[4:5], 0
	v_mov_b64_e32 v[6:7], 0
	v_mov_b64_e32 v[8:9], 0
	v_mov_b64_e32 v[10:11], 0
	v_mov_b64_e32 v[12:13], 0
	v_mov_b64_e32 v[14:15], 0
	v_mov_b64_e32 v[16:17], 0
	v_mov_b64_e32 v[18:19], 0
	v_mov_b64_e32 v[20:21], 0
	v_mov_b64_e32 v[22:23], 0
	v_mov_b64_e32 v[24:25], 0
	v_mov_b64_e32 v[26:27], 0
	v_mov_b64_e32 v[28:29], 0
	v_mov_b64_e32 v[30:31], 0
	global_load_dwordx4 v[116:119], v235, s[84:85]
	global_load_dwordx4 v[120:123], v236, s[84:85]
	global_load_dwordx4 v[124:127], v237, s[84:85]
	global_load_dwordx4 v[128:131], v238, s[84:85]
	global_load_dwordx4 v[132:135], v100, s[84:85] offset:768
	global_load_dwordx4 v[136:139], v149, s[84:85] offset:768
	global_load_dwordx4 v[140:143], v100, s[84:85] offset:832
	global_load_dwordx4 v[144:147], v149, s[84:85] offset:832
	s_add_u32 s84, s84, 0x30000
	s_addc_u32 s85, s85, 0
	global_load_dwordx4 v[156:159], v235, s[84:85]
	global_load_dwordx4 v[160:163], v236, s[84:85]
	global_load_dwordx4 v[164:167], v237, s[84:85]
	global_load_dwordx4 v[168:171], v238, s[84:85]
	global_load_dwordx4 v[172:175], v100, s[84:85] offset:768
	global_load_dwordx4 v[176:179], v149, s[84:85] offset:768
	global_load_dwordx4 v[180:183], v100, s[84:85] offset:832
	global_load_dwordx4 v[184:187], v149, s[84:85] offset:832
	s_add_u32 s84, s84, 0x30000
	s_addc_u32 s85, s85, 0
	v_mov_b32_e32 v115, v228
	ds_read2_b32 v[32:33], v115 offset0:0 offset1:1
	ds_read2_b32 v[34:35], v115 offset0:2 offset1:3
	ds_read2_b32 v[36:37], v115 offset0:8 offset1:9
	ds_read2_b32 v[38:39], v115 offset0:10 offset1:11
	ds_read2_b32 v[40:41], v115 offset0:17 offset1:18
	ds_read2_b32 v[42:43], v115 offset0:19 offset1:20
	ds_read2_b32 v[44:45], v115 offset0:25 offset1:26
	ds_read2_b32 v[46:47], v115 offset0:27 offset1:28
	s_waitcnt vmcnt(8)
	ds_write_b128 v247, v[116:119]
	ds_write_b128 v247, v[120:123] offset:1024
	ds_write_b128 v247, v[124:127] offset:2048
	ds_write_b128 v247, v[128:131] offset:3072
	ds_read_b128 v[116:119], v248
	ds_read_b128 v[120:123], v249
	ds_read_b128 v[124:127], v250
	ds_read_b128 v[128:131], v251
	ds_write_b128 v112, v[132:135]
	ds_write_b128 v112, v[136:139] offset:1024
	ds_write_b128 v112, v[140:143] offset:2048
	ds_write_b128 v112, v[144:147] offset:3072
	s_waitcnt lgkmcnt(4)
	v_mfma_f32_32x32x16_bf16 v[32:47], v[116:119], v[48:51], v[32:47]
	v_mfma_f32_32x32x16_bf16 v[32:47], v[120:123], v[52:55], v[32:47]
	v_mfma_f32_32x32x16_bf16 v[32:47], v[124:127], v[56:59], v[32:47]
	v_mfma_f32_32x32x16_bf16 v[32:47], v[128:131], v[60:63], v[32:47]
	ds_read2_b32 v[188:189], v115 offset0:34 offset1:35
	ds_read2_b32 v[190:191], v115 offset0:36 offset1:37
	ds_read2_b32 v[192:193], v115 offset0:42 offset1:43
	ds_read2_b32 v[194:195], v115 offset0:44 offset1:45
	ds_read2_b32 v[196:197], v115 offset0:51 offset1:52
	ds_read2_b32 v[198:199], v115 offset0:53 offset1:54
	ds_read2_b32 v[200:201], v115 offset0:59 offset1:60
	ds_read2_b32 v[202:203], v115 offset0:61 offset1:62
	global_load_dwordx4 v[116:119], v235, s[84:85]
	global_load_dwordx4 v[120:123], v236, s[84:85]
	global_load_dwordx4 v[124:127], v237, s[84:85]
	global_load_dwordx4 v[128:131], v238, s[84:85]
	global_load_dwordx4 v[132:135], v100, s[84:85] offset:768
	global_load_dwordx4 v[136:139], v149, s[84:85] offset:768
	global_load_dwordx4 v[140:143], v100, s[84:85] offset:832
	global_load_dwordx4 v[144:147], v149, s[84:85] offset:832
	s_add_u32 s84, s84, 0x30000
	s_addc_u32 s85, s85, 0
	ds_read_b64_tr_b16 v[72:73], v231
	ds_read_b64_tr_b16 v[74:75], v231 offset:512
	ds_read_b64_tr_b16 v[76:77], v231 offset:2048
	ds_read_b64_tr_b16 v[78:79], v231 offset:2560
	ds_read_b64_tr_b16 v[220:221], v231 offset:1024
	ds_read_b64_tr_b16 v[222:223], v231 offset:1536
	ds_read_b64_tr_b16 v[224:225], v231 offset:3072
	ds_read_b64_tr_b16 v[226:227], v231 offset:3584
	s_waitcnt vmcnt(8)
	ds_write_b128 v247, v[156:159]
	ds_write_b128 v247, v[160:163] offset:1024
	ds_write_b128 v247, v[164:167] offset:2048
	ds_write_b128 v247, v[168:171] offset:3072
	ds_read_b128 v[156:159], v248
	ds_read_b128 v[160:163], v249
	ds_read_b128 v[164:167], v250
	ds_read_b128 v[168:171], v251
	ds_write_b128 v112, v[172:175]
	ds_write_b128 v112, v[176:179] offset:1024
	ds_write_b128 v112, v[180:183] offset:2048
	ds_write_b128 v112, v[184:187] offset:3072
	v_exp_f32_e32 v32, v32
	v_exp_f32_e32 v33, v33
	v_exp_f32_e32 v34, v34
	v_exp_f32_e32 v35, v35
	v_exp_f32_e32 v36, v36
	v_exp_f32_e32 v37, v37
	s_waitcnt lgkmcnt(4)
	v_mfma_f32_32x32x16_bf16 v[188:203], v[156:159], v[48:51], v[188:203]
	v_exp_f32_e32 v38, v38
	v_exp_f32_e32 v39, v39
	v_mfma_f32_32x32x16_bf16 v[188:203], v[160:163], v[52:55], v[188:203]
	v_exp_f32_e32 v40, v40
	v_exp_f32_e32 v41, v41
	v_exp_f32_e32 v42, v42
	v_mfma_f32_32x32x16_bf16 v[188:203], v[164:167], v[56:59], v[188:203]
	v_exp_f32_e32 v43, v43
	v_exp_f32_e32 v44, v44
	v_mfma_f32_32x32x16_bf16 v[188:203], v[168:171], v[60:63], v[188:203]
	v_exp_f32_e32 v45, v45
	v_exp_f32_e32 v46, v46
	v_exp_f32_e32 v47, v47
	v_cvt_pk_bf16_f32 v64, v32, v33
	v_cvt_pk_bf16_f32 v65, v34, v35
	v_cvt_pk_bf16_f32 v66, v36, v37
	v_cvt_pk_bf16_f32 v67, v38, v39
	v_cvt_pk_bf16_f32 v68, v40, v41
	v_cvt_pk_bf16_f32 v69, v42, v43
	v_cvt_pk_bf16_f32 v70, v44, v45
	v_cvt_pk_bf16_f32 v71, v46, v47
	v_pk_add_f32 v[232:233], v[232:233], v[32:33]
	v_pk_add_f32 v[232:233], v[232:233], v[34:35]
	v_pk_add_f32 v[232:233], v[232:233], v[36:37]
	v_pk_add_f32 v[232:233], v[232:233], v[38:39]
	v_pk_add_f32 v[232:233], v[232:233], v[40:41]
	v_pk_add_f32 v[232:233], v[232:233], v[42:43]
	v_pk_add_f32 v[232:233], v[232:233], v[44:45]
	v_pk_add_f32 v[232:233], v[232:233], v[46:47]
	ds_read2_b32 v[32:33], v115 offset0:68 offset1:69
	ds_read2_b32 v[34:35], v115 offset0:70 offset1:71
	ds_read2_b32 v[36:37], v115 offset0:76 offset1:77
	ds_read2_b32 v[38:39], v115 offset0:78 offset1:79
	ds_read2_b32 v[40:41], v115 offset0:85 offset1:86
	ds_read2_b32 v[42:43], v115 offset0:87 offset1:88
	ds_read2_b32 v[44:45], v115 offset0:93 offset1:94
	ds_read2_b32 v[46:47], v115 offset0:95 offset1:96
	v_mfma_f32_32x32x16_bf16 v[0:15], v[64:67], v[72:75], v[0:15]
	v_mfma_f32_32x32x16_bf16 v[16:31], v[64:67], v[76:79], v[16:31]
	v_mfma_f32_32x32x16_bf16 v[0:15], v[68:71], v[220:223], v[0:15]
	v_mfma_f32_32x32x16_bf16 v[16:31], v[68:71], v[224:227], v[16:31]
	global_load_dwordx4 v[156:159], v235, s[84:85]
	global_load_dwordx4 v[160:163], v236, s[84:85]
	global_load_dwordx4 v[164:167], v237, s[84:85]
	global_load_dwordx4 v[168:171], v238, s[84:85]
	global_load_dwordx4 v[172:175], v100, s[84:85] offset:768
	global_load_dwordx4 v[176:179], v149, s[84:85] offset:768
	global_load_dwordx4 v[180:183], v100, s[84:85] offset:832
	global_load_dwordx4 v[184:187], v149, s[84:85] offset:832
	s_add_u32 s84, s84, 0x30000
	s_addc_u32 s85, s85, 0
	ds_read_b64_tr_b16 v[72:73], v231
	ds_read_b64_tr_b16 v[74:75], v231 offset:512
	ds_read_b64_tr_b16 v[76:77], v231 offset:2048
	ds_read_b64_tr_b16 v[78:79], v231 offset:2560
	ds_read_b64_tr_b16 v[220:221], v231 offset:1024
	ds_read_b64_tr_b16 v[222:223], v231 offset:1536
	ds_read_b64_tr_b16 v[224:225], v231 offset:3072
	ds_read_b64_tr_b16 v[226:227], v231 offset:3584
	s_waitcnt vmcnt(8)
	ds_write_b128 v247, v[116:119]
	ds_write_b128 v247, v[120:123] offset:1024
	ds_write_b128 v247, v[124:127] offset:2048
	ds_write_b128 v247, v[128:131] offset:3072
	ds_read_b128 v[116:119], v248
	ds_read_b128 v[120:123], v249
	ds_read_b128 v[124:127], v250
	ds_read_b128 v[128:131], v251
	ds_write_b128 v112, v[132:135]
	ds_write_b128 v112, v[136:139] offset:1024
	ds_write_b128 v112, v[140:143] offset:2048
	ds_write_b128 v112, v[144:147] offset:3072
	v_exp_f32_e32 v188, v188
	v_exp_f32_e32 v189, v189
	v_exp_f32_e32 v190, v190
	v_exp_f32_e32 v191, v191
	v_exp_f32_e32 v192, v192
	v_exp_f32_e32 v193, v193
	s_waitcnt lgkmcnt(4)
	v_mfma_f32_32x32x16_bf16 v[32:47], v[116:119], v[48:51], v[32:47]
	v_exp_f32_e32 v194, v194
	v_exp_f32_e32 v195, v195
	v_mfma_f32_32x32x16_bf16 v[32:47], v[120:123], v[52:55], v[32:47]
	v_exp_f32_e32 v196, v196
	v_exp_f32_e32 v197, v197
	v_exp_f32_e32 v198, v198
	v_mfma_f32_32x32x16_bf16 v[32:47], v[124:127], v[56:59], v[32:47]
	v_exp_f32_e32 v199, v199
	v_exp_f32_e32 v200, v200
	v_mfma_f32_32x32x16_bf16 v[32:47], v[128:131], v[60:63], v[32:47]
	v_exp_f32_e32 v201, v201
	v_exp_f32_e32 v202, v202
	v_exp_f32_e32 v203, v203
	v_cvt_pk_bf16_f32 v64, v188, v189
	v_cvt_pk_bf16_f32 v65, v190, v191
	v_cvt_pk_bf16_f32 v66, v192, v193
	v_cvt_pk_bf16_f32 v67, v194, v195
	v_cvt_pk_bf16_f32 v68, v196, v197
	v_cvt_pk_bf16_f32 v69, v198, v199
	v_cvt_pk_bf16_f32 v70, v200, v201
	v_cvt_pk_bf16_f32 v71, v202, v203
	v_pk_add_f32 v[232:233], v[232:233], v[188:189]
	v_pk_add_f32 v[232:233], v[232:233], v[190:191]
	v_pk_add_f32 v[232:233], v[232:233], v[192:193]
	v_pk_add_f32 v[232:233], v[232:233], v[194:195]
	v_pk_add_f32 v[232:233], v[232:233], v[196:197]
	v_pk_add_f32 v[232:233], v[232:233], v[198:199]
	v_pk_add_f32 v[232:233], v[232:233], v[200:201]
	v_pk_add_f32 v[232:233], v[232:233], v[202:203]
	ds_read2_b32 v[188:189], v115 offset0:102 offset1:103
	ds_read2_b32 v[190:191], v115 offset0:104 offset1:105
	ds_read2_b32 v[192:193], v115 offset0:110 offset1:111
	ds_read2_b32 v[194:195], v115 offset0:112 offset1:113
	ds_read2_b32 v[196:197], v115 offset0:119 offset1:120
	ds_read2_b32 v[198:199], v115 offset0:121 offset1:122
	ds_read2_b32 v[200:201], v115 offset0:127 offset1:128
	ds_read2_b32 v[202:203], v115 offset0:129 offset1:130
	v_mfma_f32_32x32x16_bf16 v[0:15], v[64:67], v[72:75], v[0:15]
	v_mfma_f32_32x32x16_bf16 v[16:31], v[64:67], v[76:79], v[16:31]
	v_mfma_f32_32x32x16_bf16 v[0:15], v[68:71], v[220:223], v[0:15]
	v_mfma_f32_32x32x16_bf16 v[16:31], v[68:71], v[224:227], v[16:31]
	global_load_dwordx4 v[116:119], v235, s[84:85]
	global_load_dwordx4 v[120:123], v236, s[84:85]
	global_load_dwordx4 v[124:127], v237, s[84:85]
	global_load_dwordx4 v[128:131], v238, s[84:85]
	global_load_dwordx4 v[132:135], v100, s[84:85] offset:768
	global_load_dwordx4 v[136:139], v149, s[84:85] offset:768
	global_load_dwordx4 v[140:143], v100, s[84:85] offset:832
	global_load_dwordx4 v[144:147], v149, s[84:85] offset:832
	s_add_u32 s84, s84, 0x30000
	s_addc_u32 s85, s85, 0
	ds_read_b64_tr_b16 v[72:73], v231
	ds_read_b64_tr_b16 v[74:75], v231 offset:512
	ds_read_b64_tr_b16 v[76:77], v231 offset:2048
	ds_read_b64_tr_b16 v[78:79], v231 offset:2560
	ds_read_b64_tr_b16 v[220:221], v231 offset:1024
	ds_read_b64_tr_b16 v[222:223], v231 offset:1536
	ds_read_b64_tr_b16 v[224:225], v231 offset:3072
	ds_read_b64_tr_b16 v[226:227], v231 offset:3584
	s_waitcnt vmcnt(8)
	ds_write_b128 v247, v[156:159]
	ds_write_b128 v247, v[160:163] offset:1024
	ds_write_b128 v247, v[164:167] offset:2048
	ds_write_b128 v247, v[168:171] offset:3072
	ds_read_b128 v[156:159], v248
	ds_read_b128 v[160:163], v249
	ds_read_b128 v[164:167], v250
	ds_read_b128 v[168:171], v251
	ds_write_b128 v112, v[172:175]
	ds_write_b128 v112, v[176:179] offset:1024
	ds_write_b128 v112, v[180:183] offset:2048
	ds_write_b128 v112, v[184:187] offset:3072
	v_exp_f32_e32 v32, v32
	v_exp_f32_e32 v33, v33
	v_exp_f32_e32 v34, v34
	v_exp_f32_e32 v35, v35
	v_exp_f32_e32 v36, v36
	v_exp_f32_e32 v37, v37
	s_waitcnt lgkmcnt(4)
	v_mfma_f32_32x32x16_bf16 v[188:203], v[156:159], v[48:51], v[188:203]
	v_exp_f32_e32 v38, v38
	v_exp_f32_e32 v39, v39
	v_mfma_f32_32x32x16_bf16 v[188:203], v[160:163], v[52:55], v[188:203]
	v_exp_f32_e32 v40, v40
	v_exp_f32_e32 v41, v41
	v_exp_f32_e32 v42, v42
	v_mfma_f32_32x32x16_bf16 v[188:203], v[164:167], v[56:59], v[188:203]
	v_exp_f32_e32 v43, v43
	v_exp_f32_e32 v44, v44
	v_mfma_f32_32x32x16_bf16 v[188:203], v[168:171], v[60:63], v[188:203]
	v_exp_f32_e32 v45, v45
	v_exp_f32_e32 v46, v46
	v_exp_f32_e32 v47, v47
	v_cvt_pk_bf16_f32 v64, v32, v33
	v_cvt_pk_bf16_f32 v65, v34, v35
	v_cvt_pk_bf16_f32 v66, v36, v37
	v_cvt_pk_bf16_f32 v67, v38, v39
	v_cvt_pk_bf16_f32 v68, v40, v41
	v_cvt_pk_bf16_f32 v69, v42, v43
	v_cvt_pk_bf16_f32 v70, v44, v45
	v_cvt_pk_bf16_f32 v71, v46, v47
	v_pk_add_f32 v[232:233], v[232:233], v[32:33]
	v_pk_add_f32 v[232:233], v[232:233], v[34:35]
	v_pk_add_f32 v[232:233], v[232:233], v[36:37]
	v_pk_add_f32 v[232:233], v[232:233], v[38:39]
	v_pk_add_f32 v[232:233], v[232:233], v[40:41]
	v_pk_add_f32 v[232:233], v[232:233], v[42:43]
	v_pk_add_f32 v[232:233], v[232:233], v[44:45]
	v_pk_add_f32 v[232:233], v[232:233], v[46:47]
	ds_read2_b32 v[32:33], v115 offset0:136 offset1:137
	ds_read2_b32 v[34:35], v115 offset0:138 offset1:139
	ds_read2_b32 v[36:37], v115 offset0:144 offset1:145
	ds_read2_b32 v[38:39], v115 offset0:146 offset1:147
	ds_read2_b32 v[40:41], v115 offset0:153 offset1:154
	ds_read2_b32 v[42:43], v115 offset0:155 offset1:156
	ds_read2_b32 v[44:45], v115 offset0:161 offset1:162
	ds_read2_b32 v[46:47], v115 offset0:163 offset1:164
	v_mfma_f32_32x32x16_bf16 v[0:15], v[64:67], v[72:75], v[0:15]
	v_mfma_f32_32x32x16_bf16 v[16:31], v[64:67], v[76:79], v[16:31]
	v_mfma_f32_32x32x16_bf16 v[0:15], v[68:71], v[220:223], v[0:15]
	v_mfma_f32_32x32x16_bf16 v[16:31], v[68:71], v[224:227], v[16:31]
	global_load_dwordx4 v[156:159], v235, s[84:85]
	global_load_dwordx4 v[160:163], v236, s[84:85]
	global_load_dwordx4 v[164:167], v237, s[84:85]
	global_load_dwordx4 v[168:171], v238, s[84:85]
	global_load_dwordx4 v[172:175], v100, s[84:85] offset:768
	global_load_dwordx4 v[176:179], v149, s[84:85] offset:768
	global_load_dwordx4 v[180:183], v100, s[84:85] offset:832
	global_load_dwordx4 v[184:187], v149, s[84:85] offset:832
	s_add_u32 s84, s84, 0x30000
	s_addc_u32 s85, s85, 0
	ds_read_b64_tr_b16 v[72:73], v231
	ds_read_b64_tr_b16 v[74:75], v231 offset:512
	ds_read_b64_tr_b16 v[76:77], v231 offset:2048
	ds_read_b64_tr_b16 v[78:79], v231 offset:2560
	ds_read_b64_tr_b16 v[220:221], v231 offset:1024
	ds_read_b64_tr_b16 v[222:223], v231 offset:1536
	ds_read_b64_tr_b16 v[224:225], v231 offset:3072
	ds_read_b64_tr_b16 v[226:227], v231 offset:3584
	s_waitcnt vmcnt(8)
	ds_write_b128 v247, v[116:119]
	ds_write_b128 v247, v[120:123] offset:1024
	ds_write_b128 v247, v[124:127] offset:2048
	ds_write_b128 v247, v[128:131] offset:3072
	ds_read_b128 v[116:119], v248
	ds_read_b128 v[120:123], v249
	ds_read_b128 v[124:127], v250
	ds_read_b128 v[128:131], v251
	ds_write_b128 v112, v[132:135]
	ds_write_b128 v112, v[136:139] offset:1024
	ds_write_b128 v112, v[140:143] offset:2048
	ds_write_b128 v112, v[144:147] offset:3072
	v_exp_f32_e32 v188, v188
	v_exp_f32_e32 v189, v189
	v_exp_f32_e32 v190, v190
	v_exp_f32_e32 v191, v191
	v_exp_f32_e32 v192, v192
	v_exp_f32_e32 v193, v193
	s_waitcnt lgkmcnt(4)
	v_mfma_f32_32x32x16_bf16 v[32:47], v[116:119], v[48:51], v[32:47]
	v_exp_f32_e32 v194, v194
	v_exp_f32_e32 v195, v195
	v_mfma_f32_32x32x16_bf16 v[32:47], v[120:123], v[52:55], v[32:47]
	v_exp_f32_e32 v196, v196
	v_exp_f32_e32 v197, v197
	v_exp_f32_e32 v198, v198
	v_mfma_f32_32x32x16_bf16 v[32:47], v[124:127], v[56:59], v[32:47]
	v_exp_f32_e32 v199, v199
	v_exp_f32_e32 v200, v200
	v_mfma_f32_32x32x16_bf16 v[32:47], v[128:131], v[60:63], v[32:47]
	v_exp_f32_e32 v201, v201
	v_exp_f32_e32 v202, v202
	v_exp_f32_e32 v203, v203
	v_cvt_pk_bf16_f32 v64, v188, v189
	v_cvt_pk_bf16_f32 v65, v190, v191
	v_cvt_pk_bf16_f32 v66, v192, v193
	v_cvt_pk_bf16_f32 v67, v194, v195
	v_cvt_pk_bf16_f32 v68, v196, v197
	v_cvt_pk_bf16_f32 v69, v198, v199
	v_cvt_pk_bf16_f32 v70, v200, v201
	v_cvt_pk_bf16_f32 v71, v202, v203
	v_pk_add_f32 v[232:233], v[232:233], v[188:189]
	v_pk_add_f32 v[232:233], v[232:233], v[190:191]
	v_pk_add_f32 v[232:233], v[232:233], v[192:193]
	v_pk_add_f32 v[232:233], v[232:233], v[194:195]
	v_pk_add_f32 v[232:233], v[232:233], v[196:197]
	v_pk_add_f32 v[232:233], v[232:233], v[198:199]
	v_pk_add_f32 v[232:233], v[232:233], v[200:201]
	v_pk_add_f32 v[232:233], v[232:233], v[202:203]
	ds_read2_b32 v[188:189], v115 offset0:170 offset1:171
	ds_read2_b32 v[190:191], v115 offset0:172 offset1:173
	ds_read2_b32 v[192:193], v115 offset0:178 offset1:179
	ds_read2_b32 v[194:195], v115 offset0:180 offset1:181
	ds_read2_b32 v[196:197], v115 offset0:187 offset1:188
	ds_read2_b32 v[198:199], v115 offset0:189 offset1:190
	ds_read2_b32 v[200:201], v115 offset0:195 offset1:196
	ds_read2_b32 v[202:203], v115 offset0:197 offset1:198
	v_mfma_f32_32x32x16_bf16 v[0:15], v[64:67], v[72:75], v[0:15]
	v_mfma_f32_32x32x16_bf16 v[16:31], v[64:67], v[76:79], v[16:31]
	v_mfma_f32_32x32x16_bf16 v[0:15], v[68:71], v[220:223], v[0:15]
	v_mfma_f32_32x32x16_bf16 v[16:31], v[68:71], v[224:227], v[16:31]
	global_load_dwordx4 v[116:119], v235, s[84:85]
	global_load_dwordx4 v[120:123], v236, s[84:85]
	global_load_dwordx4 v[124:127], v237, s[84:85]
	global_load_dwordx4 v[128:131], v238, s[84:85]
	global_load_dwordx4 v[132:135], v100, s[84:85] offset:768
	global_load_dwordx4 v[136:139], v149, s[84:85] offset:768
	global_load_dwordx4 v[140:143], v100, s[84:85] offset:832
	global_load_dwordx4 v[144:147], v149, s[84:85] offset:832
	s_add_u32 s84, s84, 0x30000
	s_addc_u32 s85, s85, 0
	ds_read_b64_tr_b16 v[72:73], v231
	ds_read_b64_tr_b16 v[74:75], v231 offset:512
	ds_read_b64_tr_b16 v[76:77], v231 offset:2048
	ds_read_b64_tr_b16 v[78:79], v231 offset:2560
	ds_read_b64_tr_b16 v[220:221], v231 offset:1024
	ds_read_b64_tr_b16 v[222:223], v231 offset:1536
	ds_read_b64_tr_b16 v[224:225], v231 offset:3072
	ds_read_b64_tr_b16 v[226:227], v231 offset:3584
	s_waitcnt vmcnt(8)
	ds_write_b128 v247, v[156:159]
	ds_write_b128 v247, v[160:163] offset:1024
	ds_write_b128 v247, v[164:167] offset:2048
	ds_write_b128 v247, v[168:171] offset:3072
	ds_read_b128 v[156:159], v248
	ds_read_b128 v[160:163], v249
	ds_read_b128 v[164:167], v250
	ds_read_b128 v[168:171], v251
	ds_write_b128 v112, v[172:175]
	ds_write_b128 v112, v[176:179] offset:1024
	ds_write_b128 v112, v[180:183] offset:2048
	ds_write_b128 v112, v[184:187] offset:3072
	v_exp_f32_e32 v32, v32
	v_exp_f32_e32 v33, v33
	v_exp_f32_e32 v34, v34
	v_exp_f32_e32 v35, v35
	v_exp_f32_e32 v36, v36
	v_exp_f32_e32 v37, v37
	s_waitcnt lgkmcnt(4)
	v_mfma_f32_32x32x16_bf16 v[188:203], v[156:159], v[48:51], v[188:203]
	v_exp_f32_e32 v38, v38
	v_exp_f32_e32 v39, v39
	v_mfma_f32_32x32x16_bf16 v[188:203], v[160:163], v[52:55], v[188:203]
	v_exp_f32_e32 v40, v40
	v_exp_f32_e32 v41, v41
	v_exp_f32_e32 v42, v42
	v_mfma_f32_32x32x16_bf16 v[188:203], v[164:167], v[56:59], v[188:203]
	v_exp_f32_e32 v43, v43
	v_exp_f32_e32 v44, v44
	v_mfma_f32_32x32x16_bf16 v[188:203], v[168:171], v[60:63], v[188:203]
	v_exp_f32_e32 v45, v45
	v_exp_f32_e32 v46, v46
	v_exp_f32_e32 v47, v47
	v_cvt_pk_bf16_f32 v64, v32, v33
	v_cvt_pk_bf16_f32 v65, v34, v35
	v_cvt_pk_bf16_f32 v66, v36, v37
	v_cvt_pk_bf16_f32 v67, v38, v39
	v_cvt_pk_bf16_f32 v68, v40, v41
	v_cvt_pk_bf16_f32 v69, v42, v43
	v_cvt_pk_bf16_f32 v70, v44, v45
	v_cvt_pk_bf16_f32 v71, v46, v47
	v_pk_add_f32 v[232:233], v[232:233], v[32:33]
	v_pk_add_f32 v[232:233], v[232:233], v[34:35]
	v_pk_add_f32 v[232:233], v[232:233], v[36:37]
	v_pk_add_f32 v[232:233], v[232:233], v[38:39]
	v_pk_add_f32 v[232:233], v[232:233], v[40:41]
	v_pk_add_f32 v[232:233], v[232:233], v[42:43]
	v_pk_add_f32 v[232:233], v[232:233], v[44:45]
	v_pk_add_f32 v[232:233], v[232:233], v[46:47]
	ds_read2_b32 v[32:33], v115 offset0:204 offset1:205
	ds_read2_b32 v[34:35], v115 offset0:206 offset1:207
	ds_read2_b32 v[36:37], v115 offset0:212 offset1:213
	ds_read2_b32 v[38:39], v115 offset0:214 offset1:215
	ds_read2_b32 v[40:41], v115 offset0:221 offset1:222
	ds_read2_b32 v[42:43], v115 offset0:223 offset1:224
	ds_read2_b32 v[44:45], v115 offset0:229 offset1:230
	ds_read2_b32 v[46:47], v115 offset0:231 offset1:232
	v_mfma_f32_32x32x16_bf16 v[0:15], v[64:67], v[72:75], v[0:15]
	v_mfma_f32_32x32x16_bf16 v[16:31], v[64:67], v[76:79], v[16:31]
	v_mfma_f32_32x32x16_bf16 v[0:15], v[68:71], v[220:223], v[0:15]
	v_mfma_f32_32x32x16_bf16 v[16:31], v[68:71], v[224:227], v[16:31]
	global_load_dwordx4 v[156:159], v235, s[84:85]
	global_load_dwordx4 v[160:163], v236, s[84:85]
	global_load_dwordx4 v[164:167], v237, s[84:85]
	global_load_dwordx4 v[168:171], v238, s[84:85]
	global_load_dwordx4 v[172:175], v100, s[84:85] offset:768
	global_load_dwordx4 v[176:179], v149, s[84:85] offset:768
	global_load_dwordx4 v[180:183], v100, s[84:85] offset:832
	global_load_dwordx4 v[184:187], v149, s[84:85] offset:832
	s_add_u32 s84, s84, 0x30000
	s_addc_u32 s85, s85, 0
	ds_read_b64_tr_b16 v[72:73], v231
	ds_read_b64_tr_b16 v[74:75], v231 offset:512
	ds_read_b64_tr_b16 v[76:77], v231 offset:2048
	ds_read_b64_tr_b16 v[78:79], v231 offset:2560
	ds_read_b64_tr_b16 v[220:221], v231 offset:1024
	ds_read_b64_tr_b16 v[222:223], v231 offset:1536
	ds_read_b64_tr_b16 v[224:225], v231 offset:3072
	ds_read_b64_tr_b16 v[226:227], v231 offset:3584
	s_waitcnt vmcnt(8)
	ds_write_b128 v247, v[116:119]
	ds_write_b128 v247, v[120:123] offset:1024
	ds_write_b128 v247, v[124:127] offset:2048
	ds_write_b128 v247, v[128:131] offset:3072
	ds_read_b128 v[116:119], v248
	ds_read_b128 v[120:123], v249
	ds_read_b128 v[124:127], v250
	ds_read_b128 v[128:131], v251
	ds_write_b128 v112, v[132:135]
	ds_write_b128 v112, v[136:139] offset:1024
	ds_write_b128 v112, v[140:143] offset:2048
	ds_write_b128 v112, v[144:147] offset:3072
	v_exp_f32_e32 v188, v188
	v_exp_f32_e32 v189, v189
	v_exp_f32_e32 v190, v190
	v_exp_f32_e32 v191, v191
	v_exp_f32_e32 v192, v192
	v_exp_f32_e32 v193, v193
	s_waitcnt lgkmcnt(4)
	v_mfma_f32_32x32x16_bf16 v[32:47], v[116:119], v[48:51], v[32:47]
	v_exp_f32_e32 v194, v194
	v_exp_f32_e32 v195, v195
	v_mfma_f32_32x32x16_bf16 v[32:47], v[120:123], v[52:55], v[32:47]
	v_exp_f32_e32 v196, v196
	v_exp_f32_e32 v197, v197
	v_exp_f32_e32 v198, v198
	v_mfma_f32_32x32x16_bf16 v[32:47], v[124:127], v[56:59], v[32:47]
	v_exp_f32_e32 v199, v199
	v_exp_f32_e32 v200, v200
	v_mfma_f32_32x32x16_bf16 v[32:47], v[128:131], v[60:63], v[32:47]
	v_exp_f32_e32 v201, v201
	v_exp_f32_e32 v202, v202
	v_exp_f32_e32 v203, v203
	v_cvt_pk_bf16_f32 v64, v188, v189
	v_cvt_pk_bf16_f32 v65, v190, v191
	v_cvt_pk_bf16_f32 v66, v192, v193
	v_cvt_pk_bf16_f32 v67, v194, v195
	v_cvt_pk_bf16_f32 v68, v196, v197
	v_cvt_pk_bf16_f32 v69, v198, v199
	v_cvt_pk_bf16_f32 v70, v200, v201
	v_cvt_pk_bf16_f32 v71, v202, v203
	v_pk_add_f32 v[232:233], v[232:233], v[188:189]
	v_pk_add_f32 v[232:233], v[232:233], v[190:191]
	v_pk_add_f32 v[232:233], v[232:233], v[192:193]
	v_pk_add_f32 v[232:233], v[232:233], v[194:195]
	v_pk_add_f32 v[232:233], v[232:233], v[196:197]
	v_pk_add_f32 v[232:233], v[232:233], v[198:199]
	v_pk_add_f32 v[232:233], v[232:233], v[200:201]
	v_pk_add_f32 v[232:233], v[232:233], v[202:203]
	v_add_u32_e32 v115, 952, v115
	ds_read2_b32 v[188:189], v115 offset0:0 offset1:1
	ds_read2_b32 v[190:191], v115 offset0:2 offset1:3
	ds_read2_b32 v[192:193], v115 offset0:8 offset1:9
	ds_read2_b32 v[194:195], v115 offset0:10 offset1:11
	ds_read2_b32 v[196:197], v115 offset0:17 offset1:18
	ds_read2_b32 v[198:199], v115 offset0:19 offset1:20
	ds_read2_b32 v[200:201], v115 offset0:25 offset1:26
	ds_read2_b32 v[202:203], v115 offset0:27 offset1:28
	v_mfma_f32_32x32x16_bf16 v[0:15], v[64:67], v[72:75], v[0:15]
	v_mfma_f32_32x32x16_bf16 v[16:31], v[64:67], v[76:79], v[16:31]
	v_mfma_f32_32x32x16_bf16 v[0:15], v[68:71], v[220:223], v[0:15]
	v_mfma_f32_32x32x16_bf16 v[16:31], v[68:71], v[224:227], v[16:31]
	global_load_dwordx4 v[116:119], v235, s[84:85]
	global_load_dwordx4 v[120:123], v236, s[84:85]
	global_load_dwordx4 v[124:127], v237, s[84:85]
	global_load_dwordx4 v[128:131], v238, s[84:85]
	global_load_dwordx4 v[132:135], v100, s[84:85] offset:768
	global_load_dwordx4 v[136:139], v149, s[84:85] offset:768
	global_load_dwordx4 v[140:143], v100, s[84:85] offset:832
	global_load_dwordx4 v[144:147], v149, s[84:85] offset:832
	s_add_u32 s84, s84, 0x30000
	s_addc_u32 s85, s85, 0
	ds_read_b64_tr_b16 v[72:73], v231
	ds_read_b64_tr_b16 v[74:75], v231 offset:512
	ds_read_b64_tr_b16 v[76:77], v231 offset:2048
	ds_read_b64_tr_b16 v[78:79], v231 offset:2560
	ds_read_b64_tr_b16 v[220:221], v231 offset:1024
	ds_read_b64_tr_b16 v[222:223], v231 offset:1536
	ds_read_b64_tr_b16 v[224:225], v231 offset:3072
	ds_read_b64_tr_b16 v[226:227], v231 offset:3584
	s_waitcnt vmcnt(8)
	ds_write_b128 v247, v[156:159]
	ds_write_b128 v247, v[160:163] offset:1024
	ds_write_b128 v247, v[164:167] offset:2048
	ds_write_b128 v247, v[168:171] offset:3072
	ds_read_b128 v[156:159], v248
	ds_read_b128 v[160:163], v249
	ds_read_b128 v[164:167], v250
	ds_read_b128 v[168:171], v251
	ds_write_b128 v112, v[172:175]
	ds_write_b128 v112, v[176:179] offset:1024
	ds_write_b128 v112, v[180:183] offset:2048
	ds_write_b128 v112, v[184:187] offset:3072
	v_exp_f32_e32 v32, v32
	v_exp_f32_e32 v33, v33
	v_exp_f32_e32 v34, v34
	v_exp_f32_e32 v35, v35
	v_exp_f32_e32 v36, v36
	v_exp_f32_e32 v37, v37
	s_waitcnt lgkmcnt(4)
	v_mfma_f32_32x32x16_bf16 v[188:203], v[156:159], v[48:51], v[188:203]
	v_exp_f32_e32 v38, v38
	v_exp_f32_e32 v39, v39
	v_mfma_f32_32x32x16_bf16 v[188:203], v[160:163], v[52:55], v[188:203]
	v_exp_f32_e32 v40, v40
	v_exp_f32_e32 v41, v41
	v_exp_f32_e32 v42, v42
	v_mfma_f32_32x32x16_bf16 v[188:203], v[164:167], v[56:59], v[188:203]
	v_exp_f32_e32 v43, v43
	v_exp_f32_e32 v44, v44
	v_mfma_f32_32x32x16_bf16 v[188:203], v[168:171], v[60:63], v[188:203]
	v_exp_f32_e32 v45, v45
	v_exp_f32_e32 v46, v46
	v_exp_f32_e32 v47, v47
	v_cvt_pk_bf16_f32 v64, v32, v33
	v_cvt_pk_bf16_f32 v65, v34, v35
	v_cvt_pk_bf16_f32 v66, v36, v37
	v_cvt_pk_bf16_f32 v67, v38, v39
	v_cvt_pk_bf16_f32 v68, v40, v41
	v_cvt_pk_bf16_f32 v69, v42, v43
	v_cvt_pk_bf16_f32 v70, v44, v45
	v_cvt_pk_bf16_f32 v71, v46, v47
	v_pk_add_f32 v[232:233], v[232:233], v[32:33]
	v_pk_add_f32 v[232:233], v[232:233], v[34:35]
	v_pk_add_f32 v[232:233], v[232:233], v[36:37]
	v_pk_add_f32 v[232:233], v[232:233], v[38:39]
	v_pk_add_f32 v[232:233], v[232:233], v[40:41]
	v_pk_add_f32 v[232:233], v[232:233], v[42:43]
	v_pk_add_f32 v[232:233], v[232:233], v[44:45]
	v_pk_add_f32 v[232:233], v[232:233], v[46:47]
	ds_read2_b32 v[32:33], v115 offset0:34 offset1:35
	ds_read2_b32 v[34:35], v115 offset0:36 offset1:37
	ds_read2_b32 v[36:37], v115 offset0:42 offset1:43
	ds_read2_b32 v[38:39], v115 offset0:44 offset1:45
	ds_read2_b32 v[40:41], v115 offset0:51 offset1:52
	ds_read2_b32 v[42:43], v115 offset0:53 offset1:54
	ds_read2_b32 v[44:45], v115 offset0:59 offset1:60
	ds_read2_b32 v[46:47], v115 offset0:61 offset1:62
	v_mfma_f32_32x32x16_bf16 v[0:15], v[64:67], v[72:75], v[0:15]
	v_mfma_f32_32x32x16_bf16 v[16:31], v[64:67], v[76:79], v[16:31]
	v_mfma_f32_32x32x16_bf16 v[0:15], v[68:71], v[220:223], v[0:15]
	v_mfma_f32_32x32x16_bf16 v[16:31], v[68:71], v[224:227], v[16:31]
	global_load_dwordx4 v[156:159], v235, s[84:85]
	global_load_dwordx4 v[160:163], v236, s[84:85]
	global_load_dwordx4 v[164:167], v237, s[84:85]
	global_load_dwordx4 v[168:171], v238, s[84:85]
	global_load_dwordx4 v[172:175], v100, s[84:85] offset:768
	global_load_dwordx4 v[176:179], v149, s[84:85] offset:768
	global_load_dwordx4 v[180:183], v100, s[84:85] offset:832
	global_load_dwordx4 v[184:187], v149, s[84:85] offset:832
	s_add_u32 s84, s84, 0x30000
	s_addc_u32 s85, s85, 0
	ds_read_b64_tr_b16 v[72:73], v231
	ds_read_b64_tr_b16 v[74:75], v231 offset:512
	ds_read_b64_tr_b16 v[76:77], v231 offset:2048
	ds_read_b64_tr_b16 v[78:79], v231 offset:2560
	ds_read_b64_tr_b16 v[220:221], v231 offset:1024
	ds_read_b64_tr_b16 v[222:223], v231 offset:1536
	ds_read_b64_tr_b16 v[224:225], v231 offset:3072
	ds_read_b64_tr_b16 v[226:227], v231 offset:3584
	s_waitcnt vmcnt(8)
	ds_write_b128 v247, v[116:119]
	ds_write_b128 v247, v[120:123] offset:1024
	ds_write_b128 v247, v[124:127] offset:2048
	ds_write_b128 v247, v[128:131] offset:3072
	ds_read_b128 v[116:119], v248
	ds_read_b128 v[120:123], v249
	ds_read_b128 v[124:127], v250
	ds_read_b128 v[128:131], v251
	ds_write_b128 v112, v[132:135]
	ds_write_b128 v112, v[136:139] offset:1024
	ds_write_b128 v112, v[140:143] offset:2048
	ds_write_b128 v112, v[144:147] offset:3072
	v_exp_f32_e32 v188, v188
	v_exp_f32_e32 v189, v189
	v_exp_f32_e32 v190, v190
	v_exp_f32_e32 v191, v191
	v_exp_f32_e32 v192, v192
	v_exp_f32_e32 v193, v193
	s_waitcnt lgkmcnt(4)
	v_mfma_f32_32x32x16_bf16 v[32:47], v[116:119], v[48:51], v[32:47]
	v_exp_f32_e32 v194, v194
	v_exp_f32_e32 v195, v195
	v_mfma_f32_32x32x16_bf16 v[32:47], v[120:123], v[52:55], v[32:47]
	v_exp_f32_e32 v196, v196
	v_exp_f32_e32 v197, v197
	v_exp_f32_e32 v198, v198
	v_mfma_f32_32x32x16_bf16 v[32:47], v[124:127], v[56:59], v[32:47]
	v_exp_f32_e32 v199, v199
	v_exp_f32_e32 v200, v200
	v_mfma_f32_32x32x16_bf16 v[32:47], v[128:131], v[60:63], v[32:47]
	v_exp_f32_e32 v201, v201
	v_exp_f32_e32 v202, v202
	v_exp_f32_e32 v203, v203
	v_cvt_pk_bf16_f32 v64, v188, v189
	v_cvt_pk_bf16_f32 v65, v190, v191
	v_cvt_pk_bf16_f32 v66, v192, v193
	v_cvt_pk_bf16_f32 v67, v194, v195
	v_cvt_pk_bf16_f32 v68, v196, v197
	v_cvt_pk_bf16_f32 v69, v198, v199
	v_cvt_pk_bf16_f32 v70, v200, v201
	v_cvt_pk_bf16_f32 v71, v202, v203
	v_pk_add_f32 v[232:233], v[232:233], v[188:189]
	v_pk_add_f32 v[232:233], v[232:233], v[190:191]
	v_pk_add_f32 v[232:233], v[232:233], v[192:193]
	v_pk_add_f32 v[232:233], v[232:233], v[194:195]
	v_pk_add_f32 v[232:233], v[232:233], v[196:197]
	v_pk_add_f32 v[232:233], v[232:233], v[198:199]
	v_pk_add_f32 v[232:233], v[232:233], v[200:201]
	v_pk_add_f32 v[232:233], v[232:233], v[202:203]
	ds_read2_b32 v[188:189], v115 offset0:68 offset1:69
	ds_read2_b32 v[190:191], v115 offset0:70 offset1:71
	ds_read2_b32 v[192:193], v115 offset0:76 offset1:77
	ds_read2_b32 v[194:195], v115 offset0:78 offset1:79
	ds_read2_b32 v[196:197], v115 offset0:85 offset1:86
	ds_read2_b32 v[198:199], v115 offset0:87 offset1:88
	ds_read2_b32 v[200:201], v115 offset0:93 offset1:94
	ds_read2_b32 v[202:203], v115 offset0:95 offset1:96
	v_mfma_f32_32x32x16_bf16 v[0:15], v[64:67], v[72:75], v[0:15]
	v_mfma_f32_32x32x16_bf16 v[16:31], v[64:67], v[76:79], v[16:31]
	v_mfma_f32_32x32x16_bf16 v[0:15], v[68:71], v[220:223], v[0:15]
	v_mfma_f32_32x32x16_bf16 v[16:31], v[68:71], v[224:227], v[16:31]
	global_load_dwordx4 v[116:119], v235, s[84:85]
	global_load_dwordx4 v[120:123], v236, s[84:85]
	global_load_dwordx4 v[124:127], v237, s[84:85]
	global_load_dwordx4 v[128:131], v238, s[84:85]
	global_load_dwordx4 v[132:135], v100, s[84:85] offset:768
	global_load_dwordx4 v[136:139], v149, s[84:85] offset:768
	global_load_dwordx4 v[140:143], v100, s[84:85] offset:832
	global_load_dwordx4 v[144:147], v149, s[84:85] offset:832
	s_add_u32 s84, s84, 0x30000
	s_addc_u32 s85, s85, 0
	ds_read_b64_tr_b16 v[72:73], v231
	ds_read_b64_tr_b16 v[74:75], v231 offset:512
	ds_read_b64_tr_b16 v[76:77], v231 offset:2048
	ds_read_b64_tr_b16 v[78:79], v231 offset:2560
	ds_read_b64_tr_b16 v[220:221], v231 offset:1024
	ds_read_b64_tr_b16 v[222:223], v231 offset:1536
	ds_read_b64_tr_b16 v[224:225], v231 offset:3072
	ds_read_b64_tr_b16 v[226:227], v231 offset:3584
	s_waitcnt vmcnt(8)
	ds_write_b128 v247, v[156:159]
	ds_write_b128 v247, v[160:163] offset:1024
	ds_write_b128 v247, v[164:167] offset:2048
	ds_write_b128 v247, v[168:171] offset:3072
	ds_read_b128 v[156:159], v248
	ds_read_b128 v[160:163], v249
	ds_read_b128 v[164:167], v250
	ds_read_b128 v[168:171], v251
	ds_write_b128 v112, v[172:175]
	ds_write_b128 v112, v[176:179] offset:1024
	ds_write_b128 v112, v[180:183] offset:2048
	ds_write_b128 v112, v[184:187] offset:3072
	v_exp_f32_e32 v32, v32
	v_exp_f32_e32 v33, v33
	v_exp_f32_e32 v34, v34
	v_exp_f32_e32 v35, v35
	v_exp_f32_e32 v36, v36
	v_exp_f32_e32 v37, v37
	s_waitcnt lgkmcnt(4)
	v_mfma_f32_32x32x16_bf16 v[188:203], v[156:159], v[48:51], v[188:203]
	v_exp_f32_e32 v38, v38
	v_exp_f32_e32 v39, v39
	v_mfma_f32_32x32x16_bf16 v[188:203], v[160:163], v[52:55], v[188:203]
	v_exp_f32_e32 v40, v40
	v_exp_f32_e32 v41, v41
	v_exp_f32_e32 v42, v42
	v_mfma_f32_32x32x16_bf16 v[188:203], v[164:167], v[56:59], v[188:203]
	v_exp_f32_e32 v43, v43
	v_exp_f32_e32 v44, v44
	v_mfma_f32_32x32x16_bf16 v[188:203], v[168:171], v[60:63], v[188:203]
	v_exp_f32_e32 v45, v45
	v_exp_f32_e32 v46, v46
	v_exp_f32_e32 v47, v47
	v_cvt_pk_bf16_f32 v64, v32, v33
	v_cvt_pk_bf16_f32 v65, v34, v35
	v_cvt_pk_bf16_f32 v66, v36, v37
	v_cvt_pk_bf16_f32 v67, v38, v39
	v_cvt_pk_bf16_f32 v68, v40, v41
	v_cvt_pk_bf16_f32 v69, v42, v43
	v_cvt_pk_bf16_f32 v70, v44, v45
	v_cvt_pk_bf16_f32 v71, v46, v47
	v_pk_add_f32 v[232:233], v[232:233], v[32:33]
	v_pk_add_f32 v[232:233], v[232:233], v[34:35]
	v_pk_add_f32 v[232:233], v[232:233], v[36:37]
	v_pk_add_f32 v[232:233], v[232:233], v[38:39]
	v_pk_add_f32 v[232:233], v[232:233], v[40:41]
	v_pk_add_f32 v[232:233], v[232:233], v[42:43]
	v_pk_add_f32 v[232:233], v[232:233], v[44:45]
	v_pk_add_f32 v[232:233], v[232:233], v[46:47]
	ds_read2_b32 v[32:33], v115 offset0:102 offset1:103
	ds_read2_b32 v[34:35], v115 offset0:104 offset1:105
	ds_read2_b32 v[36:37], v115 offset0:110 offset1:111
	ds_read2_b32 v[38:39], v115 offset0:112 offset1:113
	ds_read2_b32 v[40:41], v115 offset0:119 offset1:120
	ds_read2_b32 v[42:43], v115 offset0:121 offset1:122
	ds_read2_b32 v[44:45], v115 offset0:127 offset1:128
	ds_read2_b32 v[46:47], v115 offset0:129 offset1:130
	v_mfma_f32_32x32x16_bf16 v[0:15], v[64:67], v[72:75], v[0:15]
	v_mfma_f32_32x32x16_bf16 v[16:31], v[64:67], v[76:79], v[16:31]
	v_mfma_f32_32x32x16_bf16 v[0:15], v[68:71], v[220:223], v[0:15]
	v_mfma_f32_32x32x16_bf16 v[16:31], v[68:71], v[224:227], v[16:31]
	global_load_dwordx4 v[156:159], v235, s[84:85]
	global_load_dwordx4 v[160:163], v236, s[84:85]
	global_load_dwordx4 v[164:167], v237, s[84:85]
	global_load_dwordx4 v[168:171], v238, s[84:85]
	global_load_dwordx4 v[172:175], v100, s[84:85] offset:768
	global_load_dwordx4 v[176:179], v149, s[84:85] offset:768
	global_load_dwordx4 v[180:183], v100, s[84:85] offset:832
	global_load_dwordx4 v[184:187], v149, s[84:85] offset:832
	s_add_u32 s84, s84, 0x30000
	s_addc_u32 s85, s85, 0
	ds_read_b64_tr_b16 v[72:73], v231
	ds_read_b64_tr_b16 v[74:75], v231 offset:512
	ds_read_b64_tr_b16 v[76:77], v231 offset:2048
	ds_read_b64_tr_b16 v[78:79], v231 offset:2560
	ds_read_b64_tr_b16 v[220:221], v231 offset:1024
	ds_read_b64_tr_b16 v[222:223], v231 offset:1536
	ds_read_b64_tr_b16 v[224:225], v231 offset:3072
	ds_read_b64_tr_b16 v[226:227], v231 offset:3584
	s_waitcnt vmcnt(8)
	ds_write_b128 v247, v[116:119]
	ds_write_b128 v247, v[120:123] offset:1024
	ds_write_b128 v247, v[124:127] offset:2048
	ds_write_b128 v247, v[128:131] offset:3072
	ds_read_b128 v[116:119], v248
	ds_read_b128 v[120:123], v249
	ds_read_b128 v[124:127], v250
	ds_read_b128 v[128:131], v251
	ds_write_b128 v112, v[132:135]
	ds_write_b128 v112, v[136:139] offset:1024
	ds_write_b128 v112, v[140:143] offset:2048
	ds_write_b128 v112, v[144:147] offset:3072
	v_exp_f32_e32 v188, v188
	v_exp_f32_e32 v189, v189
	v_exp_f32_e32 v190, v190
	v_exp_f32_e32 v191, v191
	v_exp_f32_e32 v192, v192
	v_exp_f32_e32 v193, v193
	s_waitcnt lgkmcnt(4)
	v_mfma_f32_32x32x16_bf16 v[32:47], v[116:119], v[48:51], v[32:47]
	v_exp_f32_e32 v194, v194
	v_exp_f32_e32 v195, v195
	v_mfma_f32_32x32x16_bf16 v[32:47], v[120:123], v[52:55], v[32:47]
	v_exp_f32_e32 v196, v196
	v_exp_f32_e32 v197, v197
	v_exp_f32_e32 v198, v198
	v_mfma_f32_32x32x16_bf16 v[32:47], v[124:127], v[56:59], v[32:47]
	v_exp_f32_e32 v199, v199
	v_exp_f32_e32 v200, v200
	v_mfma_f32_32x32x16_bf16 v[32:47], v[128:131], v[60:63], v[32:47]
	v_exp_f32_e32 v201, v201
	v_exp_f32_e32 v202, v202
	v_exp_f32_e32 v203, v203
	v_cvt_pk_bf16_f32 v64, v188, v189
	v_cvt_pk_bf16_f32 v65, v190, v191
	v_cvt_pk_bf16_f32 v66, v192, v193
	v_cvt_pk_bf16_f32 v67, v194, v195
	v_cvt_pk_bf16_f32 v68, v196, v197
	v_cvt_pk_bf16_f32 v69, v198, v199
	v_cvt_pk_bf16_f32 v70, v200, v201
	v_cvt_pk_bf16_f32 v71, v202, v203
	v_pk_add_f32 v[232:233], v[232:233], v[188:189]
	v_pk_add_f32 v[232:233], v[232:233], v[190:191]
	v_pk_add_f32 v[232:233], v[232:233], v[192:193]
	v_pk_add_f32 v[232:233], v[232:233], v[194:195]
	v_pk_add_f32 v[232:233], v[232:233], v[196:197]
	v_pk_add_f32 v[232:233], v[232:233], v[198:199]
	v_pk_add_f32 v[232:233], v[232:233], v[200:201]
	v_pk_add_f32 v[232:233], v[232:233], v[202:203]
	ds_read2_b32 v[188:189], v115 offset0:136 offset1:137
	ds_read2_b32 v[190:191], v115 offset0:138 offset1:139
	ds_read2_b32 v[192:193], v115 offset0:144 offset1:145
	ds_read2_b32 v[194:195], v115 offset0:146 offset1:147
	ds_read2_b32 v[196:197], v115 offset0:153 offset1:154
	ds_read2_b32 v[198:199], v115 offset0:155 offset1:156
	ds_read2_b32 v[200:201], v115 offset0:161 offset1:162
	ds_read2_b32 v[202:203], v115 offset0:163 offset1:164
	v_mfma_f32_32x32x16_bf16 v[0:15], v[64:67], v[72:75], v[0:15]
	v_mfma_f32_32x32x16_bf16 v[16:31], v[64:67], v[76:79], v[16:31]
	v_mfma_f32_32x32x16_bf16 v[0:15], v[68:71], v[220:223], v[0:15]
	v_mfma_f32_32x32x16_bf16 v[16:31], v[68:71], v[224:227], v[16:31]
	global_load_dwordx4 v[116:119], v235, s[84:85]
	global_load_dwordx4 v[120:123], v236, s[84:85]
	global_load_dwordx4 v[124:127], v237, s[84:85]
	global_load_dwordx4 v[128:131], v238, s[84:85]
	global_load_dwordx4 v[132:135], v100, s[84:85] offset:768
	global_load_dwordx4 v[136:139], v149, s[84:85] offset:768
	global_load_dwordx4 v[140:143], v100, s[84:85] offset:832
	global_load_dwordx4 v[144:147], v149, s[84:85] offset:832
	s_add_u32 s84, s84, 0x30000
	s_addc_u32 s85, s85, 0
	ds_read_b64_tr_b16 v[72:73], v231
	ds_read_b64_tr_b16 v[74:75], v231 offset:512
	ds_read_b64_tr_b16 v[76:77], v231 offset:2048
	ds_read_b64_tr_b16 v[78:79], v231 offset:2560
	ds_read_b64_tr_b16 v[220:221], v231 offset:1024
	ds_read_b64_tr_b16 v[222:223], v231 offset:1536
	ds_read_b64_tr_b16 v[224:225], v231 offset:3072
	ds_read_b64_tr_b16 v[226:227], v231 offset:3584
	s_waitcnt vmcnt(8)
	ds_write_b128 v247, v[156:159]
	ds_write_b128 v247, v[160:163] offset:1024
	ds_write_b128 v247, v[164:167] offset:2048
	ds_write_b128 v247, v[168:171] offset:3072
	ds_read_b128 v[156:159], v248
	ds_read_b128 v[160:163], v249
	ds_read_b128 v[164:167], v250
	ds_read_b128 v[168:171], v251
	ds_write_b128 v112, v[172:175]
	ds_write_b128 v112, v[176:179] offset:1024
	ds_write_b128 v112, v[180:183] offset:2048
	ds_write_b128 v112, v[184:187] offset:3072
	v_exp_f32_e32 v32, v32
	v_exp_f32_e32 v33, v33
	v_exp_f32_e32 v34, v34
	v_exp_f32_e32 v35, v35
	v_exp_f32_e32 v36, v36
	v_exp_f32_e32 v37, v37
	s_waitcnt lgkmcnt(4)
	v_mfma_f32_32x32x16_bf16 v[188:203], v[156:159], v[48:51], v[188:203]
	v_exp_f32_e32 v38, v38
	v_exp_f32_e32 v39, v39
	v_mfma_f32_32x32x16_bf16 v[188:203], v[160:163], v[52:55], v[188:203]
	v_exp_f32_e32 v40, v40
	v_exp_f32_e32 v41, v41
	v_exp_f32_e32 v42, v42
	v_mfma_f32_32x32x16_bf16 v[188:203], v[164:167], v[56:59], v[188:203]
	v_exp_f32_e32 v43, v43
	v_exp_f32_e32 v44, v44
	v_mfma_f32_32x32x16_bf16 v[188:203], v[168:171], v[60:63], v[188:203]
	v_exp_f32_e32 v45, v45
	v_exp_f32_e32 v46, v46
	v_exp_f32_e32 v47, v47
	v_cvt_pk_bf16_f32 v64, v32, v33
	v_cvt_pk_bf16_f32 v65, v34, v35
	v_cvt_pk_bf16_f32 v66, v36, v37
	v_cvt_pk_bf16_f32 v67, v38, v39
	v_cvt_pk_bf16_f32 v68, v40, v41
	v_cvt_pk_bf16_f32 v69, v42, v43
	v_cvt_pk_bf16_f32 v70, v44, v45
	v_cvt_pk_bf16_f32 v71, v46, v47
	v_pk_add_f32 v[232:233], v[232:233], v[32:33]
	v_pk_add_f32 v[232:233], v[232:233], v[34:35]
	v_pk_add_f32 v[232:233], v[232:233], v[36:37]
	v_pk_add_f32 v[232:233], v[232:233], v[38:39]
	v_pk_add_f32 v[232:233], v[232:233], v[40:41]
	v_pk_add_f32 v[232:233], v[232:233], v[42:43]
	v_pk_add_f32 v[232:233], v[232:233], v[44:45]
	v_pk_add_f32 v[232:233], v[232:233], v[46:47]
	ds_read2_b32 v[32:33], v115 offset0:170 offset1:171
	ds_read2_b32 v[34:35], v115 offset0:172 offset1:173
	ds_read2_b32 v[36:37], v115 offset0:178 offset1:179
	ds_read2_b32 v[38:39], v115 offset0:180 offset1:181
	ds_read2_b32 v[40:41], v115 offset0:187 offset1:188
	ds_read2_b32 v[42:43], v115 offset0:189 offset1:190
	ds_read2_b32 v[44:45], v115 offset0:195 offset1:196
	ds_read2_b32 v[46:47], v115 offset0:197 offset1:198
	v_mfma_f32_32x32x16_bf16 v[0:15], v[64:67], v[72:75], v[0:15]
	v_mfma_f32_32x32x16_bf16 v[16:31], v[64:67], v[76:79], v[16:31]
	v_mfma_f32_32x32x16_bf16 v[0:15], v[68:71], v[220:223], v[0:15]
	v_mfma_f32_32x32x16_bf16 v[16:31], v[68:71], v[224:227], v[16:31]
	global_load_dwordx4 v[156:159], v235, s[84:85]
	global_load_dwordx4 v[160:163], v236, s[84:85]
	global_load_dwordx4 v[164:167], v237, s[84:85]
	global_load_dwordx4 v[168:171], v238, s[84:85]
	global_load_dwordx4 v[172:175], v100, s[84:85] offset:768
	global_load_dwordx4 v[176:179], v149, s[84:85] offset:768
	global_load_dwordx4 v[180:183], v100, s[84:85] offset:832
	global_load_dwordx4 v[184:187], v149, s[84:85] offset:832
	s_add_u32 s84, s84, 0x30000
	s_addc_u32 s85, s85, 0
	ds_read_b64_tr_b16 v[72:73], v231
	ds_read_b64_tr_b16 v[74:75], v231 offset:512
	ds_read_b64_tr_b16 v[76:77], v231 offset:2048
	ds_read_b64_tr_b16 v[78:79], v231 offset:2560
	ds_read_b64_tr_b16 v[220:221], v231 offset:1024
	ds_read_b64_tr_b16 v[222:223], v231 offset:1536
	ds_read_b64_tr_b16 v[224:225], v231 offset:3072
	ds_read_b64_tr_b16 v[226:227], v231 offset:3584
	s_waitcnt vmcnt(8)
	ds_write_b128 v247, v[116:119]
	ds_write_b128 v247, v[120:123] offset:1024
	ds_write_b128 v247, v[124:127] offset:2048
	ds_write_b128 v247, v[128:131] offset:3072
	ds_read_b128 v[116:119], v248
	ds_read_b128 v[120:123], v249
	ds_read_b128 v[124:127], v250
	ds_read_b128 v[128:131], v251
	ds_write_b128 v112, v[132:135]
	ds_write_b128 v112, v[136:139] offset:1024
	ds_write_b128 v112, v[140:143] offset:2048
	ds_write_b128 v112, v[144:147] offset:3072
	v_exp_f32_e32 v188, v188
	v_exp_f32_e32 v189, v189
	v_exp_f32_e32 v190, v190
	v_exp_f32_e32 v191, v191
	v_exp_f32_e32 v192, v192
	v_exp_f32_e32 v193, v193
	s_waitcnt lgkmcnt(4)
	v_mfma_f32_32x32x16_bf16 v[32:47], v[116:119], v[48:51], v[32:47]
	v_exp_f32_e32 v194, v194
	v_exp_f32_e32 v195, v195
	v_mfma_f32_32x32x16_bf16 v[32:47], v[120:123], v[52:55], v[32:47]
	v_exp_f32_e32 v196, v196
	v_exp_f32_e32 v197, v197
	v_exp_f32_e32 v198, v198
	v_mfma_f32_32x32x16_bf16 v[32:47], v[124:127], v[56:59], v[32:47]
	v_exp_f32_e32 v199, v199
	v_exp_f32_e32 v200, v200
	v_mfma_f32_32x32x16_bf16 v[32:47], v[128:131], v[60:63], v[32:47]
	v_exp_f32_e32 v201, v201
	v_exp_f32_e32 v202, v202
	v_exp_f32_e32 v203, v203
	v_cvt_pk_bf16_f32 v64, v188, v189
	v_cvt_pk_bf16_f32 v65, v190, v191
	v_cvt_pk_bf16_f32 v66, v192, v193
	v_cvt_pk_bf16_f32 v67, v194, v195
	v_cvt_pk_bf16_f32 v68, v196, v197
	v_cvt_pk_bf16_f32 v69, v198, v199
	v_cvt_pk_bf16_f32 v70, v200, v201
	v_cvt_pk_bf16_f32 v71, v202, v203
	v_pk_add_f32 v[232:233], v[232:233], v[188:189]
	v_pk_add_f32 v[232:233], v[232:233], v[190:191]
	v_pk_add_f32 v[232:233], v[232:233], v[192:193]
	v_pk_add_f32 v[232:233], v[232:233], v[194:195]
	v_pk_add_f32 v[232:233], v[232:233], v[196:197]
	v_pk_add_f32 v[232:233], v[232:233], v[198:199]
	v_pk_add_f32 v[232:233], v[232:233], v[200:201]
	v_pk_add_f32 v[232:233], v[232:233], v[202:203]
	ds_read2_b32 v[188:189], v115 offset0:204 offset1:205
	ds_read2_b32 v[190:191], v115 offset0:206 offset1:207
	ds_read2_b32 v[192:193], v115 offset0:212 offset1:213
	ds_read2_b32 v[194:195], v115 offset0:214 offset1:215
	ds_read2_b32 v[196:197], v115 offset0:221 offset1:222
	ds_read2_b32 v[198:199], v115 offset0:223 offset1:224
	ds_read2_b32 v[200:201], v115 offset0:229 offset1:230
	ds_read2_b32 v[202:203], v115 offset0:231 offset1:232
	v_mfma_f32_32x32x16_bf16 v[0:15], v[64:67], v[72:75], v[0:15]
	v_mfma_f32_32x32x16_bf16 v[16:31], v[64:67], v[76:79], v[16:31]
	v_mfma_f32_32x32x16_bf16 v[0:15], v[68:71], v[220:223], v[0:15]
	v_mfma_f32_32x32x16_bf16 v[16:31], v[68:71], v[224:227], v[16:31]
	global_load_dwordx4 v[116:119], v235, s[84:85]
	global_load_dwordx4 v[120:123], v236, s[84:85]
	global_load_dwordx4 v[124:127], v237, s[84:85]
	global_load_dwordx4 v[128:131], v238, s[84:85]
	global_load_dwordx4 v[132:135], v100, s[84:85] offset:768
	global_load_dwordx4 v[136:139], v149, s[84:85] offset:768
	global_load_dwordx4 v[140:143], v100, s[84:85] offset:832
	global_load_dwordx4 v[144:147], v149, s[84:85] offset:832
	s_add_u32 s84, s84, 0x30000
	s_addc_u32 s85, s85, 0
	ds_read_b64_tr_b16 v[72:73], v231
	ds_read_b64_tr_b16 v[74:75], v231 offset:512
	ds_read_b64_tr_b16 v[76:77], v231 offset:2048
	ds_read_b64_tr_b16 v[78:79], v231 offset:2560
	ds_read_b64_tr_b16 v[220:221], v231 offset:1024
	ds_read_b64_tr_b16 v[222:223], v231 offset:1536
	ds_read_b64_tr_b16 v[224:225], v231 offset:3072
	ds_read_b64_tr_b16 v[226:227], v231 offset:3584
	s_waitcnt vmcnt(8)
	ds_write_b128 v247, v[156:159]
	ds_write_b128 v247, v[160:163] offset:1024
	ds_write_b128 v247, v[164:167] offset:2048
	ds_write_b128 v247, v[168:171] offset:3072
	ds_read_b128 v[156:159], v248
	ds_read_b128 v[160:163], v249
	ds_read_b128 v[164:167], v250
	ds_read_b128 v[168:171], v251
	ds_write_b128 v112, v[172:175]
	ds_write_b128 v112, v[176:179] offset:1024
	ds_write_b128 v112, v[180:183] offset:2048
	ds_write_b128 v112, v[184:187] offset:3072
	v_exp_f32_e32 v32, v32
	v_exp_f32_e32 v33, v33
	v_exp_f32_e32 v34, v34
	v_exp_f32_e32 v35, v35
	v_exp_f32_e32 v36, v36
	v_exp_f32_e32 v37, v37
	s_waitcnt lgkmcnt(4)
	v_mfma_f32_32x32x16_bf16 v[188:203], v[156:159], v[48:51], v[188:203]
	v_exp_f32_e32 v38, v38
	v_exp_f32_e32 v39, v39
	v_mfma_f32_32x32x16_bf16 v[188:203], v[160:163], v[52:55], v[188:203]
	v_exp_f32_e32 v40, v40
	v_exp_f32_e32 v41, v41
	v_exp_f32_e32 v42, v42
	v_mfma_f32_32x32x16_bf16 v[188:203], v[164:167], v[56:59], v[188:203]
	v_exp_f32_e32 v43, v43
	v_exp_f32_e32 v44, v44
	v_mfma_f32_32x32x16_bf16 v[188:203], v[168:171], v[60:63], v[188:203]
	v_exp_f32_e32 v45, v45
	v_exp_f32_e32 v46, v46
	v_exp_f32_e32 v47, v47
	v_cvt_pk_bf16_f32 v64, v32, v33
	v_cvt_pk_bf16_f32 v65, v34, v35
	v_cvt_pk_bf16_f32 v66, v36, v37
	v_cvt_pk_bf16_f32 v67, v38, v39
	v_cvt_pk_bf16_f32 v68, v40, v41
	v_cvt_pk_bf16_f32 v69, v42, v43
	v_cvt_pk_bf16_f32 v70, v44, v45
	v_cvt_pk_bf16_f32 v71, v46, v47
	v_pk_add_f32 v[232:233], v[232:233], v[32:33]
	v_pk_add_f32 v[232:233], v[232:233], v[34:35]
	v_pk_add_f32 v[232:233], v[232:233], v[36:37]
	v_pk_add_f32 v[232:233], v[232:233], v[38:39]
	v_pk_add_f32 v[232:233], v[232:233], v[40:41]
	v_pk_add_f32 v[232:233], v[232:233], v[42:43]
	v_pk_add_f32 v[232:233], v[232:233], v[44:45]
	v_pk_add_f32 v[232:233], v[232:233], v[46:47]
	v_add_u32_e32 v115, 952, v115
	ds_read2_b32 v[32:33], v115 offset0:0 offset1:1
	ds_read2_b32 v[34:35], v115 offset0:2 offset1:3
	ds_read2_b32 v[36:37], v115 offset0:8 offset1:9
	ds_read2_b32 v[38:39], v115 offset0:10 offset1:11
	ds_read2_b32 v[40:41], v115 offset0:17 offset1:18
	ds_read2_b32 v[42:43], v115 offset0:19 offset1:20
	ds_read2_b32 v[44:45], v115 offset0:25 offset1:26
	ds_read2_b32 v[46:47], v115 offset0:27 offset1:28
	v_mfma_f32_32x32x16_bf16 v[0:15], v[64:67], v[72:75], v[0:15]
	v_mfma_f32_32x32x16_bf16 v[16:31], v[64:67], v[76:79], v[16:31]
	v_mfma_f32_32x32x16_bf16 v[0:15], v[68:71], v[220:223], v[0:15]
	v_mfma_f32_32x32x16_bf16 v[16:31], v[68:71], v[224:227], v[16:31]
	global_load_dwordx4 v[156:159], v235, s[84:85]
	global_load_dwordx4 v[160:163], v236, s[84:85]
	global_load_dwordx4 v[164:167], v237, s[84:85]
	global_load_dwordx4 v[168:171], v238, s[84:85]
	global_load_dwordx4 v[172:175], v100, s[84:85] offset:768
	global_load_dwordx4 v[176:179], v149, s[84:85] offset:768
	global_load_dwordx4 v[180:183], v100, s[84:85] offset:832
	global_load_dwordx4 v[184:187], v149, s[84:85] offset:832
	s_add_u32 s84, s84, 0x30000
	s_addc_u32 s85, s85, 0
	ds_read_b64_tr_b16 v[72:73], v231
	ds_read_b64_tr_b16 v[74:75], v231 offset:512
	ds_read_b64_tr_b16 v[76:77], v231 offset:2048
	ds_read_b64_tr_b16 v[78:79], v231 offset:2560
	ds_read_b64_tr_b16 v[220:221], v231 offset:1024
	ds_read_b64_tr_b16 v[222:223], v231 offset:1536
	ds_read_b64_tr_b16 v[224:225], v231 offset:3072
	ds_read_b64_tr_b16 v[226:227], v231 offset:3584
	s_waitcnt vmcnt(8)
	ds_write_b128 v247, v[116:119]
	ds_write_b128 v247, v[120:123] offset:1024
	ds_write_b128 v247, v[124:127] offset:2048
	ds_write_b128 v247, v[128:131] offset:3072
	ds_read_b128 v[116:119], v248
	ds_read_b128 v[120:123], v249
	ds_read_b128 v[124:127], v250
	ds_read_b128 v[128:131], v251
	ds_write_b128 v112, v[132:135]
	ds_write_b128 v112, v[136:139] offset:1024
	ds_write_b128 v112, v[140:143] offset:2048
	ds_write_b128 v112, v[144:147] offset:3072
	v_exp_f32_e32 v188, v188
	v_exp_f32_e32 v189, v189
	v_exp_f32_e32 v190, v190
	v_exp_f32_e32 v191, v191
	v_exp_f32_e32 v192, v192
	v_exp_f32_e32 v193, v193
	s_waitcnt lgkmcnt(4)
	v_mfma_f32_32x32x16_bf16 v[32:47], v[116:119], v[48:51], v[32:47]
	v_exp_f32_e32 v194, v194
	v_exp_f32_e32 v195, v195
	v_mfma_f32_32x32x16_bf16 v[32:47], v[120:123], v[52:55], v[32:47]
	v_exp_f32_e32 v196, v196
	v_exp_f32_e32 v197, v197
	v_exp_f32_e32 v198, v198
	v_mfma_f32_32x32x16_bf16 v[32:47], v[124:127], v[56:59], v[32:47]
	v_exp_f32_e32 v199, v199
	v_exp_f32_e32 v200, v200
	v_mfma_f32_32x32x16_bf16 v[32:47], v[128:131], v[60:63], v[32:47]
	v_exp_f32_e32 v201, v201
	v_exp_f32_e32 v202, v202
	v_exp_f32_e32 v203, v203
	v_cvt_pk_bf16_f32 v64, v188, v189
	v_cvt_pk_bf16_f32 v65, v190, v191
	v_cvt_pk_bf16_f32 v66, v192, v193
	v_cvt_pk_bf16_f32 v67, v194, v195
	v_cvt_pk_bf16_f32 v68, v196, v197
	v_cvt_pk_bf16_f32 v69, v198, v199
	v_cvt_pk_bf16_f32 v70, v200, v201
	v_cvt_pk_bf16_f32 v71, v202, v203
	v_pk_add_f32 v[232:233], v[232:233], v[188:189]
	v_pk_add_f32 v[232:233], v[232:233], v[190:191]
	v_pk_add_f32 v[232:233], v[232:233], v[192:193]
	v_pk_add_f32 v[232:233], v[232:233], v[194:195]
	v_pk_add_f32 v[232:233], v[232:233], v[196:197]
	v_pk_add_f32 v[232:233], v[232:233], v[198:199]
	v_pk_add_f32 v[232:233], v[232:233], v[200:201]
	v_pk_add_f32 v[232:233], v[232:233], v[202:203]
	ds_read2_b32 v[188:189], v115 offset0:34 offset1:35
	ds_read2_b32 v[190:191], v115 offset0:36 offset1:37
	ds_read2_b32 v[192:193], v115 offset0:42 offset1:43
	ds_read2_b32 v[194:195], v115 offset0:44 offset1:45
	ds_read2_b32 v[196:197], v115 offset0:51 offset1:52
	ds_read2_b32 v[198:199], v115 offset0:53 offset1:54
	ds_read2_b32 v[200:201], v115 offset0:59 offset1:60
	ds_read2_b32 v[202:203], v115 offset0:61 offset1:62
	v_mfma_f32_32x32x16_bf16 v[0:15], v[64:67], v[72:75], v[0:15]
	v_mfma_f32_32x32x16_bf16 v[16:31], v[64:67], v[76:79], v[16:31]
	v_mfma_f32_32x32x16_bf16 v[0:15], v[68:71], v[220:223], v[0:15]
	v_mfma_f32_32x32x16_bf16 v[16:31], v[68:71], v[224:227], v[16:31]
	global_load_dwordx4 v[116:119], v235, s[84:85]
	global_load_dwordx4 v[120:123], v236, s[84:85]
	global_load_dwordx4 v[124:127], v237, s[84:85]
	global_load_dwordx4 v[128:131], v238, s[84:85]
	global_load_dwordx4 v[132:135], v100, s[84:85] offset:768
	global_load_dwordx4 v[136:139], v149, s[84:85] offset:768
	global_load_dwordx4 v[140:143], v100, s[84:85] offset:832
	global_load_dwordx4 v[144:147], v149, s[84:85] offset:832
	s_add_u32 s84, s84, 0x30000
	s_addc_u32 s85, s85, 0
	ds_read_b64_tr_b16 v[72:73], v231
	ds_read_b64_tr_b16 v[74:75], v231 offset:512
	ds_read_b64_tr_b16 v[76:77], v231 offset:2048
	ds_read_b64_tr_b16 v[78:79], v231 offset:2560
	ds_read_b64_tr_b16 v[220:221], v231 offset:1024
	ds_read_b64_tr_b16 v[222:223], v231 offset:1536
	ds_read_b64_tr_b16 v[224:225], v231 offset:3072
	ds_read_b64_tr_b16 v[226:227], v231 offset:3584
	s_waitcnt vmcnt(8)
	ds_write_b128 v247, v[156:159]
	ds_write_b128 v247, v[160:163] offset:1024
	ds_write_b128 v247, v[164:167] offset:2048
	ds_write_b128 v247, v[168:171] offset:3072
	ds_read_b128 v[156:159], v248
	ds_read_b128 v[160:163], v249
	ds_read_b128 v[164:167], v250
	ds_read_b128 v[168:171], v251
	ds_write_b128 v112, v[172:175]
	ds_write_b128 v112, v[176:179] offset:1024
	ds_write_b128 v112, v[180:183] offset:2048
	ds_write_b128 v112, v[184:187] offset:3072
	v_exp_f32_e32 v32, v32
	v_exp_f32_e32 v33, v33
	v_exp_f32_e32 v34, v34
	v_exp_f32_e32 v35, v35
	v_exp_f32_e32 v36, v36
	v_exp_f32_e32 v37, v37
	s_waitcnt lgkmcnt(4)
	v_mfma_f32_32x32x16_bf16 v[188:203], v[156:159], v[48:51], v[188:203]
	v_exp_f32_e32 v38, v38
	v_exp_f32_e32 v39, v39
	v_mfma_f32_32x32x16_bf16 v[188:203], v[160:163], v[52:55], v[188:203]
	v_exp_f32_e32 v40, v40
	v_exp_f32_e32 v41, v41
	v_exp_f32_e32 v42, v42
	v_mfma_f32_32x32x16_bf16 v[188:203], v[164:167], v[56:59], v[188:203]
	v_exp_f32_e32 v43, v43
	v_exp_f32_e32 v44, v44
	v_mfma_f32_32x32x16_bf16 v[188:203], v[168:171], v[60:63], v[188:203]
	v_exp_f32_e32 v45, v45
	v_exp_f32_e32 v46, v46
	v_exp_f32_e32 v47, v47
	v_cvt_pk_bf16_f32 v64, v32, v33
	v_cvt_pk_bf16_f32 v65, v34, v35
	v_cvt_pk_bf16_f32 v66, v36, v37
	v_cvt_pk_bf16_f32 v67, v38, v39
	v_cvt_pk_bf16_f32 v68, v40, v41
	v_cvt_pk_bf16_f32 v69, v42, v43
	v_cvt_pk_bf16_f32 v70, v44, v45
	v_cvt_pk_bf16_f32 v71, v46, v47
	v_pk_add_f32 v[232:233], v[232:233], v[32:33]
	v_pk_add_f32 v[232:233], v[232:233], v[34:35]
	v_pk_add_f32 v[232:233], v[232:233], v[36:37]
	v_pk_add_f32 v[232:233], v[232:233], v[38:39]
	v_pk_add_f32 v[232:233], v[232:233], v[40:41]
	v_pk_add_f32 v[232:233], v[232:233], v[42:43]
	v_pk_add_f32 v[232:233], v[232:233], v[44:45]
	v_pk_add_f32 v[232:233], v[232:233], v[46:47]
	ds_read2_b32 v[32:33], v115 offset0:68 offset1:69
	ds_read2_b32 v[34:35], v115 offset0:70 offset1:71
	ds_read2_b32 v[36:37], v115 offset0:76 offset1:77
	ds_read2_b32 v[38:39], v115 offset0:78 offset1:79
	ds_read2_b32 v[40:41], v115 offset0:85 offset1:86
	ds_read2_b32 v[42:43], v115 offset0:87 offset1:88
	ds_read2_b32 v[44:45], v115 offset0:93 offset1:94
	ds_read2_b32 v[46:47], v115 offset0:95 offset1:96
	v_mfma_f32_32x32x16_bf16 v[0:15], v[64:67], v[72:75], v[0:15]
	v_mfma_f32_32x32x16_bf16 v[16:31], v[64:67], v[76:79], v[16:31]
	v_mfma_f32_32x32x16_bf16 v[0:15], v[68:71], v[220:223], v[0:15]
	v_mfma_f32_32x32x16_bf16 v[16:31], v[68:71], v[224:227], v[16:31]
	global_load_dwordx4 v[156:159], v235, s[84:85]
	global_load_dwordx4 v[160:163], v236, s[84:85]
	global_load_dwordx4 v[164:167], v237, s[84:85]
	global_load_dwordx4 v[168:171], v238, s[84:85]
	global_load_dwordx4 v[172:175], v100, s[84:85] offset:768
	global_load_dwordx4 v[176:179], v149, s[84:85] offset:768
	global_load_dwordx4 v[180:183], v100, s[84:85] offset:832
	global_load_dwordx4 v[184:187], v149, s[84:85] offset:832
	s_add_u32 s84, s84, 0x30000
	s_addc_u32 s85, s85, 0
	ds_read_b64_tr_b16 v[72:73], v231
	ds_read_b64_tr_b16 v[74:75], v231 offset:512
	ds_read_b64_tr_b16 v[76:77], v231 offset:2048
	ds_read_b64_tr_b16 v[78:79], v231 offset:2560
	ds_read_b64_tr_b16 v[220:221], v231 offset:1024
	ds_read_b64_tr_b16 v[222:223], v231 offset:1536
	ds_read_b64_tr_b16 v[224:225], v231 offset:3072
	ds_read_b64_tr_b16 v[226:227], v231 offset:3584
	s_waitcnt vmcnt(8)
	ds_write_b128 v247, v[116:119]
	ds_write_b128 v247, v[120:123] offset:1024
	ds_write_b128 v247, v[124:127] offset:2048
	ds_write_b128 v247, v[128:131] offset:3072
	ds_read_b128 v[116:119], v248
	ds_read_b128 v[120:123], v249
	ds_read_b128 v[124:127], v250
	ds_read_b128 v[128:131], v251
	ds_write_b128 v112, v[132:135]
	ds_write_b128 v112, v[136:139] offset:1024
	ds_write_b128 v112, v[140:143] offset:2048
	ds_write_b128 v112, v[144:147] offset:3072
	v_exp_f32_e32 v188, v188
	v_exp_f32_e32 v189, v189
	v_exp_f32_e32 v190, v190
	v_exp_f32_e32 v191, v191
	v_exp_f32_e32 v192, v192
	v_exp_f32_e32 v193, v193
	s_waitcnt lgkmcnt(4)
	v_mfma_f32_32x32x16_bf16 v[32:47], v[116:119], v[48:51], v[32:47]
	v_exp_f32_e32 v194, v194
	v_exp_f32_e32 v195, v195
	v_mfma_f32_32x32x16_bf16 v[32:47], v[120:123], v[52:55], v[32:47]
	v_exp_f32_e32 v196, v196
	v_exp_f32_e32 v197, v197
	v_exp_f32_e32 v198, v198
	v_mfma_f32_32x32x16_bf16 v[32:47], v[124:127], v[56:59], v[32:47]
	v_exp_f32_e32 v199, v199
	v_exp_f32_e32 v200, v200
	v_mfma_f32_32x32x16_bf16 v[32:47], v[128:131], v[60:63], v[32:47]
	v_exp_f32_e32 v201, v201
	v_exp_f32_e32 v202, v202
	v_exp_f32_e32 v203, v203
	v_cvt_pk_bf16_f32 v64, v188, v189
	v_cvt_pk_bf16_f32 v65, v190, v191
	v_cvt_pk_bf16_f32 v66, v192, v193
	v_cvt_pk_bf16_f32 v67, v194, v195
	v_cvt_pk_bf16_f32 v68, v196, v197
	v_cvt_pk_bf16_f32 v69, v198, v199
	v_cvt_pk_bf16_f32 v70, v200, v201
	v_cvt_pk_bf16_f32 v71, v202, v203
	v_pk_add_f32 v[232:233], v[232:233], v[188:189]
	v_pk_add_f32 v[232:233], v[232:233], v[190:191]
	v_pk_add_f32 v[232:233], v[232:233], v[192:193]
	v_pk_add_f32 v[232:233], v[232:233], v[194:195]
	v_pk_add_f32 v[232:233], v[232:233], v[196:197]
	v_pk_add_f32 v[232:233], v[232:233], v[198:199]
	v_pk_add_f32 v[232:233], v[232:233], v[200:201]
	v_pk_add_f32 v[232:233], v[232:233], v[202:203]
	ds_read2_b32 v[188:189], v115 offset0:102 offset1:103
	ds_read2_b32 v[190:191], v115 offset0:104 offset1:105
	ds_read2_b32 v[192:193], v115 offset0:110 offset1:111
	ds_read2_b32 v[194:195], v115 offset0:112 offset1:113
	ds_read2_b32 v[196:197], v115 offset0:119 offset1:120
	ds_read2_b32 v[198:199], v115 offset0:121 offset1:122
	ds_read2_b32 v[200:201], v115 offset0:127 offset1:128
	ds_read2_b32 v[202:203], v115 offset0:129 offset1:130
	v_mfma_f32_32x32x16_bf16 v[0:15], v[64:67], v[72:75], v[0:15]
	v_mfma_f32_32x32x16_bf16 v[16:31], v[64:67], v[76:79], v[16:31]
	v_mfma_f32_32x32x16_bf16 v[0:15], v[68:71], v[220:223], v[0:15]
	v_mfma_f32_32x32x16_bf16 v[16:31], v[68:71], v[224:227], v[16:31]
	global_load_dwordx4 v[116:119], v235, s[84:85]
	global_load_dwordx4 v[120:123], v236, s[84:85]
	global_load_dwordx4 v[124:127], v237, s[84:85]
	global_load_dwordx4 v[128:131], v238, s[84:85]
	global_load_dwordx4 v[132:135], v100, s[84:85] offset:768
	global_load_dwordx4 v[136:139], v149, s[84:85] offset:768
	global_load_dwordx4 v[140:143], v100, s[84:85] offset:832
	global_load_dwordx4 v[144:147], v149, s[84:85] offset:832
	s_add_u32 s84, s84, 0x30000
	s_addc_u32 s85, s85, 0
	ds_read_b64_tr_b16 v[72:73], v231
	ds_read_b64_tr_b16 v[74:75], v231 offset:512
	ds_read_b64_tr_b16 v[76:77], v231 offset:2048
	ds_read_b64_tr_b16 v[78:79], v231 offset:2560
	ds_read_b64_tr_b16 v[220:221], v231 offset:1024
	ds_read_b64_tr_b16 v[222:223], v231 offset:1536
	ds_read_b64_tr_b16 v[224:225], v231 offset:3072
	ds_read_b64_tr_b16 v[226:227], v231 offset:3584
	s_waitcnt vmcnt(8)
	ds_write_b128 v247, v[156:159]
	ds_write_b128 v247, v[160:163] offset:1024
	ds_write_b128 v247, v[164:167] offset:2048
	ds_write_b128 v247, v[168:171] offset:3072
	ds_read_b128 v[156:159], v248
	ds_read_b128 v[160:163], v249
	ds_read_b128 v[164:167], v250
	ds_read_b128 v[168:171], v251
	ds_write_b128 v112, v[172:175]
	ds_write_b128 v112, v[176:179] offset:1024
	ds_write_b128 v112, v[180:183] offset:2048
	ds_write_b128 v112, v[184:187] offset:3072
	v_exp_f32_e32 v32, v32
	v_exp_f32_e32 v33, v33
	v_exp_f32_e32 v34, v34
	v_exp_f32_e32 v35, v35
	v_exp_f32_e32 v36, v36
	v_exp_f32_e32 v37, v37
	s_waitcnt lgkmcnt(4)
	v_mfma_f32_32x32x16_bf16 v[188:203], v[156:159], v[48:51], v[188:203]
	v_exp_f32_e32 v38, v38
	v_exp_f32_e32 v39, v39
	v_mfma_f32_32x32x16_bf16 v[188:203], v[160:163], v[52:55], v[188:203]
	v_exp_f32_e32 v40, v40
	v_exp_f32_e32 v41, v41
	v_exp_f32_e32 v42, v42
	v_mfma_f32_32x32x16_bf16 v[188:203], v[164:167], v[56:59], v[188:203]
	v_exp_f32_e32 v43, v43
	v_exp_f32_e32 v44, v44
	v_mfma_f32_32x32x16_bf16 v[188:203], v[168:171], v[60:63], v[188:203]
	v_exp_f32_e32 v45, v45
	v_exp_f32_e32 v46, v46
	v_exp_f32_e32 v47, v47
	v_cvt_pk_bf16_f32 v64, v32, v33
	v_cvt_pk_bf16_f32 v65, v34, v35
	v_cvt_pk_bf16_f32 v66, v36, v37
	v_cvt_pk_bf16_f32 v67, v38, v39
	v_cvt_pk_bf16_f32 v68, v40, v41
	v_cvt_pk_bf16_f32 v69, v42, v43
	v_cvt_pk_bf16_f32 v70, v44, v45
	v_cvt_pk_bf16_f32 v71, v46, v47
	v_pk_add_f32 v[232:233], v[232:233], v[32:33]
	v_pk_add_f32 v[232:233], v[232:233], v[34:35]
	v_pk_add_f32 v[232:233], v[232:233], v[36:37]
	v_pk_add_f32 v[232:233], v[232:233], v[38:39]
	v_pk_add_f32 v[232:233], v[232:233], v[40:41]
	v_pk_add_f32 v[232:233], v[232:233], v[42:43]
	v_pk_add_f32 v[232:233], v[232:233], v[44:45]
	v_pk_add_f32 v[232:233], v[232:233], v[46:47]
	ds_read2_b32 v[32:33], v115 offset0:136 offset1:137
	ds_read2_b32 v[34:35], v115 offset0:138 offset1:139
	ds_read2_b32 v[36:37], v115 offset0:144 offset1:145
	ds_read2_b32 v[38:39], v115 offset0:146 offset1:147
	ds_read2_b32 v[40:41], v115 offset0:153 offset1:154
	ds_read2_b32 v[42:43], v115 offset0:155 offset1:156
	ds_read2_b32 v[44:45], v115 offset0:161 offset1:162
	ds_read2_b32 v[46:47], v115 offset0:163 offset1:164
	v_mfma_f32_32x32x16_bf16 v[0:15], v[64:67], v[72:75], v[0:15]
	v_mfma_f32_32x32x16_bf16 v[16:31], v[64:67], v[76:79], v[16:31]
	v_mfma_f32_32x32x16_bf16 v[0:15], v[68:71], v[220:223], v[0:15]
	v_mfma_f32_32x32x16_bf16 v[16:31], v[68:71], v[224:227], v[16:31]
	global_load_dwordx4 v[156:159], v235, s[84:85]
	global_load_dwordx4 v[160:163], v236, s[84:85]
	global_load_dwordx4 v[164:167], v237, s[84:85]
	global_load_dwordx4 v[168:171], v238, s[84:85]
	global_load_dwordx4 v[172:175], v100, s[84:85] offset:768
	global_load_dwordx4 v[176:179], v149, s[84:85] offset:768
	global_load_dwordx4 v[180:183], v100, s[84:85] offset:832
	global_load_dwordx4 v[184:187], v149, s[84:85] offset:832
	ds_read_b64_tr_b16 v[72:73], v231
	ds_read_b64_tr_b16 v[74:75], v231 offset:512
	ds_read_b64_tr_b16 v[76:77], v231 offset:2048
	ds_read_b64_tr_b16 v[78:79], v231 offset:2560
	ds_read_b64_tr_b16 v[220:221], v231 offset:1024
	ds_read_b64_tr_b16 v[222:223], v231 offset:1536
	ds_read_b64_tr_b16 v[224:225], v231 offset:3072
	ds_read_b64_tr_b16 v[226:227], v231 offset:3584
	s_waitcnt vmcnt(8)
	ds_write_b128 v247, v[116:119]
	ds_write_b128 v247, v[120:123] offset:1024
	ds_write_b128 v247, v[124:127] offset:2048
	ds_write_b128 v247, v[128:131] offset:3072
	ds_read_b128 v[116:119], v248
	ds_read_b128 v[120:123], v249
	ds_read_b128 v[124:127], v250
	ds_read_b128 v[128:131], v251
	ds_write_b128 v112, v[132:135]
	ds_write_b128 v112, v[136:139] offset:1024
	ds_write_b128 v112, v[140:143] offset:2048
	ds_write_b128 v112, v[144:147] offset:3072
	v_exp_f32_e32 v188, v188
	v_exp_f32_e32 v189, v189
	v_exp_f32_e32 v190, v190
	v_exp_f32_e32 v191, v191
	v_exp_f32_e32 v192, v192
	v_exp_f32_e32 v193, v193
	s_waitcnt lgkmcnt(4)
	v_mfma_f32_32x32x16_bf16 v[32:47], v[116:119], v[48:51], v[32:47]
	v_exp_f32_e32 v194, v194
	v_exp_f32_e32 v195, v195
	v_mfma_f32_32x32x16_bf16 v[32:47], v[120:123], v[52:55], v[32:47]
	v_exp_f32_e32 v196, v196
	v_exp_f32_e32 v197, v197
	v_exp_f32_e32 v198, v198
	v_mfma_f32_32x32x16_bf16 v[32:47], v[124:127], v[56:59], v[32:47]
	v_exp_f32_e32 v199, v199
	v_exp_f32_e32 v200, v200
	v_mfma_f32_32x32x16_bf16 v[32:47], v[128:131], v[60:63], v[32:47]
	v_exp_f32_e32 v201, v201
	v_exp_f32_e32 v202, v202
	v_exp_f32_e32 v203, v203
	v_cvt_pk_bf16_f32 v64, v188, v189
	v_cvt_pk_bf16_f32 v65, v190, v191
	v_cvt_pk_bf16_f32 v66, v192, v193
	v_cvt_pk_bf16_f32 v67, v194, v195
	v_cvt_pk_bf16_f32 v68, v196, v197
	v_cvt_pk_bf16_f32 v69, v198, v199
	v_cvt_pk_bf16_f32 v70, v200, v201
	v_cvt_pk_bf16_f32 v71, v202, v203
	v_pk_add_f32 v[232:233], v[232:233], v[188:189]
	v_pk_add_f32 v[232:233], v[232:233], v[190:191]
	v_pk_add_f32 v[232:233], v[232:233], v[192:193]
	v_pk_add_f32 v[232:233], v[232:233], v[194:195]
	v_pk_add_f32 v[232:233], v[232:233], v[196:197]
	v_pk_add_f32 v[232:233], v[232:233], v[198:199]
	v_pk_add_f32 v[232:233], v[232:233], v[200:201]
	v_pk_add_f32 v[232:233], v[232:233], v[202:203]
	ds_read2_b32 v[188:189], v115 offset0:170 offset1:171
	ds_read2_b32 v[190:191], v115 offset0:172 offset1:173
	ds_read2_b32 v[192:193], v115 offset0:178 offset1:179
	ds_read2_b32 v[194:195], v115 offset0:180 offset1:181
	ds_read2_b32 v[196:197], v115 offset0:187 offset1:188
	ds_read2_b32 v[198:199], v115 offset0:189 offset1:190
	ds_read2_b32 v[200:201], v115 offset0:195 offset1:196
	ds_read2_b32 v[202:203], v115 offset0:197 offset1:198
	v_mfma_f32_32x32x16_bf16 v[0:15], v[64:67], v[72:75], v[0:15]
	v_mfma_f32_32x32x16_bf16 v[16:31], v[64:67], v[76:79], v[16:31]
	v_mfma_f32_32x32x16_bf16 v[0:15], v[68:71], v[220:223], v[0:15]
	v_mfma_f32_32x32x16_bf16 v[16:31], v[68:71], v[224:227], v[16:31]
	global_load_dwordx4 v[116:119], v239, s[86:87]
	global_load_dwordx4 v[120:123], v240, s[86:87]
	global_load_dwordx4 v[124:127], v241, s[86:87]
	global_load_dwordx4 v[128:131], v242, s[86:87]
	global_load_dwordx4 v[132:135], v101, s[86:87] offset:768
	global_load_dwordx4 v[136:139], v150, s[86:87] offset:768
	global_load_dwordx4 v[140:143], v101, s[86:87] offset:832
	global_load_dwordx4 v[144:147], v150, s[86:87] offset:832
	s_add_u32 s86, s86, 0xc0000
	s_addc_u32 s87, s87, 0
	ds_read_b64_tr_b16 v[72:73], v231
	ds_read_b64_tr_b16 v[74:75], v231 offset:512
	ds_read_b64_tr_b16 v[76:77], v231 offset:2048
	ds_read_b64_tr_b16 v[78:79], v231 offset:2560
	ds_read_b64_tr_b16 v[220:221], v231 offset:1024
	ds_read_b64_tr_b16 v[222:223], v231 offset:1536
	ds_read_b64_tr_b16 v[224:225], v231 offset:3072
	ds_read_b64_tr_b16 v[226:227], v231 offset:3584
	s_waitcnt vmcnt(8)
	ds_write_b128 v247, v[156:159]
	ds_write_b128 v247, v[160:163] offset:1024
	ds_write_b128 v247, v[164:167] offset:2048
	ds_write_b128 v247, v[168:171] offset:3072
	ds_read_b128 v[156:159], v248
	ds_read_b128 v[160:163], v249
	ds_read_b128 v[164:167], v250
	ds_read_b128 v[168:171], v251
	ds_write_b128 v112, v[172:175]
	ds_write_b128 v112, v[176:179] offset:1024
	ds_write_b128 v112, v[180:183] offset:2048
	ds_write_b128 v112, v[184:187] offset:3072
	v_exp_f32_e32 v32, v32
	v_exp_f32_e32 v33, v33
	v_exp_f32_e32 v34, v34
	v_exp_f32_e32 v35, v35
	v_exp_f32_e32 v36, v36
	v_exp_f32_e32 v37, v37
	s_waitcnt lgkmcnt(4)
	v_mfma_f32_32x32x16_bf16 v[188:203], v[156:159], v[48:51], v[188:203]
	v_exp_f32_e32 v38, v38
	v_exp_f32_e32 v39, v39
	v_mfma_f32_32x32x16_bf16 v[188:203], v[160:163], v[52:55], v[188:203]
	v_exp_f32_e32 v40, v40
	v_exp_f32_e32 v41, v41
	v_exp_f32_e32 v42, v42
	v_mfma_f32_32x32x16_bf16 v[188:203], v[164:167], v[56:59], v[188:203]
	v_exp_f32_e32 v43, v43
	v_exp_f32_e32 v44, v44
	v_mfma_f32_32x32x16_bf16 v[188:203], v[168:171], v[60:63], v[188:203]
	v_exp_f32_e32 v45, v45
	v_exp_f32_e32 v46, v46
	v_exp_f32_e32 v47, v47
	v_cvt_pk_bf16_f32 v64, v32, v33
	v_cvt_pk_bf16_f32 v65, v34, v35
	v_cvt_pk_bf16_f32 v66, v36, v37
	v_cvt_pk_bf16_f32 v67, v38, v39
	v_cvt_pk_bf16_f32 v68, v40, v41
	v_cvt_pk_bf16_f32 v69, v42, v43
	v_cvt_pk_bf16_f32 v70, v44, v45
	v_cvt_pk_bf16_f32 v71, v46, v47
	v_pk_add_f32 v[232:233], v[232:233], v[32:33]
	v_pk_add_f32 v[232:233], v[232:233], v[34:35]
	v_pk_add_f32 v[232:233], v[232:233], v[36:37]
	v_pk_add_f32 v[232:233], v[232:233], v[38:39]
	v_pk_add_f32 v[232:233], v[232:233], v[40:41]
	v_pk_add_f32 v[232:233], v[232:233], v[42:43]
	v_pk_add_f32 v[232:233], v[232:233], v[44:45]
	v_pk_add_f32 v[232:233], v[232:233], v[46:47]
	v_mov_b32_e32 v115, v229
	ds_read2_b32 v[32:33], v115 offset0:0 offset1:1
	ds_read2_b32 v[34:35], v115 offset0:2 offset1:3
	ds_read2_b32 v[36:37], v115 offset0:8 offset1:9
	ds_read2_b32 v[38:39], v115 offset0:10 offset1:11
	ds_read2_b32 v[40:41], v115 offset0:16 offset1:17
	ds_read2_b32 v[42:43], v115 offset0:18 offset1:19
	ds_read2_b32 v[44:45], v115 offset0:24 offset1:25
	ds_read2_b32 v[46:47], v115 offset0:26 offset1:27
	v_mfma_f32_32x32x16_bf16 v[0:15], v[64:67], v[72:75], v[0:15]
	v_mfma_f32_32x32x16_bf16 v[16:31], v[64:67], v[76:79], v[16:31]
	v_mfma_f32_32x32x16_bf16 v[0:15], v[68:71], v[220:223], v[0:15]
	v_mfma_f32_32x32x16_bf16 v[16:31], v[68:71], v[224:227], v[16:31]
	global_load_dwordx4 v[156:159], v239, s[86:87]
	global_load_dwordx4 v[160:163], v240, s[86:87]
	global_load_dwordx4 v[164:167], v241, s[86:87]
	global_load_dwordx4 v[168:171], v242, s[86:87]
	global_load_dwordx4 v[172:175], v101, s[86:87] offset:768
	global_load_dwordx4 v[176:179], v150, s[86:87] offset:768
	global_load_dwordx4 v[180:183], v101, s[86:87] offset:832
	global_load_dwordx4 v[184:187], v150, s[86:87] offset:832
	s_add_u32 s86, s86, 0xc0000
	s_addc_u32 s87, s87, 0
	ds_read_b64_tr_b16 v[72:73], v231
	ds_read_b64_tr_b16 v[74:75], v231 offset:512
	ds_read_b64_tr_b16 v[76:77], v231 offset:2048
	ds_read_b64_tr_b16 v[78:79], v231 offset:2560
	ds_read_b64_tr_b16 v[220:221], v231 offset:1024
	ds_read_b64_tr_b16 v[222:223], v231 offset:1536
	ds_read_b64_tr_b16 v[224:225], v231 offset:3072
	ds_read_b64_tr_b16 v[226:227], v231 offset:3584
	s_waitcnt vmcnt(8)
	ds_write_b128 v247, v[116:119]
	ds_write_b128 v247, v[120:123] offset:1024
	ds_write_b128 v247, v[124:127] offset:2048
	ds_write_b128 v247, v[128:131] offset:3072
	ds_read_b128 v[116:119], v248
	ds_read_b128 v[120:123], v249
	ds_read_b128 v[124:127], v250
	ds_read_b128 v[128:131], v251
	ds_write_b128 v112, v[132:135]
	ds_write_b128 v112, v[136:139] offset:1024
	ds_write_b128 v112, v[140:143] offset:2048
	ds_write_b128 v112, v[144:147] offset:3072
	v_exp_f32_e32 v188, v188
	v_exp_f32_e32 v189, v189
	v_exp_f32_e32 v190, v190
	v_exp_f32_e32 v191, v191
	v_exp_f32_e32 v192, v192
	v_exp_f32_e32 v193, v193
	s_waitcnt lgkmcnt(4)
	v_mfma_f32_32x32x16_bf16 v[32:47], v[116:119], v[48:51], v[32:47]
	v_exp_f32_e32 v194, v194
	v_exp_f32_e32 v195, v195
	v_mfma_f32_32x32x16_bf16 v[32:47], v[120:123], v[52:55], v[32:47]
	v_exp_f32_e32 v196, v196
	v_exp_f32_e32 v197, v197
	v_exp_f32_e32 v198, v198
	v_mfma_f32_32x32x16_bf16 v[32:47], v[124:127], v[56:59], v[32:47]
	v_exp_f32_e32 v199, v199
	v_exp_f32_e32 v200, v200
	v_mfma_f32_32x32x16_bf16 v[32:47], v[128:131], v[60:63], v[32:47]
	v_exp_f32_e32 v201, v201
	v_exp_f32_e32 v202, v202
	v_exp_f32_e32 v203, v203
	v_cvt_pk_bf16_f32 v64, v188, v189
	v_cvt_pk_bf16_f32 v65, v190, v191
	v_cvt_pk_bf16_f32 v66, v192, v193
	v_cvt_pk_bf16_f32 v67, v194, v195
	v_cvt_pk_bf16_f32 v68, v196, v197
	v_cvt_pk_bf16_f32 v69, v198, v199
	v_cvt_pk_bf16_f32 v70, v200, v201
	v_cvt_pk_bf16_f32 v71, v202, v203
	v_pk_add_f32 v[232:233], v[232:233], v[188:189]
	v_pk_add_f32 v[232:233], v[232:233], v[190:191]
	v_pk_add_f32 v[232:233], v[232:233], v[192:193]
	v_pk_add_f32 v[232:233], v[232:233], v[194:195]
	v_pk_add_f32 v[232:233], v[232:233], v[196:197]
	v_pk_add_f32 v[232:233], v[232:233], v[198:199]
	v_pk_add_f32 v[232:233], v[232:233], v[200:201]
	v_pk_add_f32 v[232:233], v[232:233], v[202:203]
	ds_read2_b32 v[188:189], v115 offset0:32 offset1:33
	ds_read2_b32 v[190:191], v115 offset0:34 offset1:35
	ds_read2_b32 v[192:193], v115 offset0:40 offset1:41
	ds_read2_b32 v[194:195], v115 offset0:42 offset1:43
	ds_read2_b32 v[196:197], v115 offset0:48 offset1:49
	ds_read2_b32 v[198:199], v115 offset0:50 offset1:51
	ds_read2_b32 v[200:201], v115 offset0:56 offset1:57
	ds_read2_b32 v[202:203], v115 offset0:58 offset1:59
	v_mfma_f32_32x32x16_bf16 v[0:15], v[64:67], v[72:75], v[0:15]
	v_mfma_f32_32x32x16_bf16 v[16:31], v[64:67], v[76:79], v[16:31]
	v_mfma_f32_32x32x16_bf16 v[0:15], v[68:71], v[220:223], v[0:15]
	v_mfma_f32_32x32x16_bf16 v[16:31], v[68:71], v[224:227], v[16:31]
	global_load_dwordx4 v[116:119], v239, s[86:87]
	global_load_dwordx4 v[120:123], v240, s[86:87]
	global_load_dwordx4 v[124:127], v241, s[86:87]
	global_load_dwordx4 v[128:131], v242, s[86:87]
	global_load_dwordx4 v[132:135], v101, s[86:87] offset:768
	global_load_dwordx4 v[136:139], v150, s[86:87] offset:768
	global_load_dwordx4 v[140:143], v101, s[86:87] offset:832
	global_load_dwordx4 v[144:147], v150, s[86:87] offset:832
	s_add_u32 s86, s86, 0xc0000
	s_addc_u32 s87, s87, 0
	ds_read_b64_tr_b16 v[72:73], v231
	ds_read_b64_tr_b16 v[74:75], v231 offset:512
	ds_read_b64_tr_b16 v[76:77], v231 offset:2048
	ds_read_b64_tr_b16 v[78:79], v231 offset:2560
	ds_read_b64_tr_b16 v[220:221], v231 offset:1024
	ds_read_b64_tr_b16 v[222:223], v231 offset:1536
	ds_read_b64_tr_b16 v[224:225], v231 offset:3072
	ds_read_b64_tr_b16 v[226:227], v231 offset:3584
	s_waitcnt vmcnt(8)
	ds_write_b128 v247, v[156:159]
	ds_write_b128 v247, v[160:163] offset:1024
	ds_write_b128 v247, v[164:167] offset:2048
	ds_write_b128 v247, v[168:171] offset:3072
	ds_read_b128 v[156:159], v248
	ds_read_b128 v[160:163], v249
	ds_read_b128 v[164:167], v250
	ds_read_b128 v[168:171], v251
	ds_write_b128 v112, v[172:175]
	ds_write_b128 v112, v[176:179] offset:1024
	ds_write_b128 v112, v[180:183] offset:2048
	ds_write_b128 v112, v[184:187] offset:3072
	v_exp_f32_e32 v32, v32
	v_exp_f32_e32 v33, v33
	v_exp_f32_e32 v34, v34
	v_exp_f32_e32 v35, v35
	v_exp_f32_e32 v36, v36
	v_exp_f32_e32 v37, v37
	s_waitcnt lgkmcnt(4)
	v_mfma_f32_32x32x16_bf16 v[188:203], v[156:159], v[48:51], v[188:203]
	v_exp_f32_e32 v38, v38
	v_exp_f32_e32 v39, v39
	v_mfma_f32_32x32x16_bf16 v[188:203], v[160:163], v[52:55], v[188:203]
	v_exp_f32_e32 v40, v40
	v_exp_f32_e32 v41, v41
	v_exp_f32_e32 v42, v42
	v_mfma_f32_32x32x16_bf16 v[188:203], v[164:167], v[56:59], v[188:203]
	v_exp_f32_e32 v43, v43
	v_exp_f32_e32 v44, v44
	v_mfma_f32_32x32x16_bf16 v[188:203], v[168:171], v[60:63], v[188:203]
	v_exp_f32_e32 v45, v45
	v_exp_f32_e32 v46, v46
	v_exp_f32_e32 v47, v47
	v_cvt_pk_bf16_f32 v64, v32, v33
	v_cvt_pk_bf16_f32 v65, v34, v35
	v_cvt_pk_bf16_f32 v66, v36, v37
	v_cvt_pk_bf16_f32 v67, v38, v39
	v_cvt_pk_bf16_f32 v68, v40, v41
	v_cvt_pk_bf16_f32 v69, v42, v43
	v_cvt_pk_bf16_f32 v70, v44, v45
	v_cvt_pk_bf16_f32 v71, v46, v47
	v_pk_add_f32 v[232:233], v[232:233], v[32:33]
	v_pk_add_f32 v[232:233], v[232:233], v[34:35]
	v_pk_add_f32 v[232:233], v[232:233], v[36:37]
	v_pk_add_f32 v[232:233], v[232:233], v[38:39]
	v_pk_add_f32 v[232:233], v[232:233], v[40:41]
	v_pk_add_f32 v[232:233], v[232:233], v[42:43]
	v_pk_add_f32 v[232:233], v[232:233], v[44:45]
	v_pk_add_f32 v[232:233], v[232:233], v[46:47]
	ds_read2_b32 v[32:33], v115 offset0:64 offset1:65
	ds_read2_b32 v[34:35], v115 offset0:66 offset1:67
	ds_read2_b32 v[36:37], v115 offset0:72 offset1:73
	ds_read2_b32 v[38:39], v115 offset0:74 offset1:75
	ds_read2_b32 v[40:41], v115 offset0:80 offset1:81
	ds_read2_b32 v[42:43], v115 offset0:82 offset1:83
	ds_read2_b32 v[44:45], v115 offset0:88 offset1:89
	ds_read2_b32 v[46:47], v115 offset0:90 offset1:91
	v_mfma_f32_32x32x16_bf16 v[0:15], v[64:67], v[72:75], v[0:15]
	v_mfma_f32_32x32x16_bf16 v[16:31], v[64:67], v[76:79], v[16:31]
	v_mfma_f32_32x32x16_bf16 v[0:15], v[68:71], v[220:223], v[0:15]
	v_mfma_f32_32x32x16_bf16 v[16:31], v[68:71], v[224:227], v[16:31]
	global_load_dwordx4 v[156:159], v239, s[86:87]
	global_load_dwordx4 v[160:163], v240, s[86:87]
	global_load_dwordx4 v[164:167], v241, s[86:87]
	global_load_dwordx4 v[168:171], v242, s[86:87]
	global_load_dwordx4 v[172:175], v101, s[86:87] offset:768
	global_load_dwordx4 v[176:179], v150, s[86:87] offset:768
	global_load_dwordx4 v[180:183], v101, s[86:87] offset:832
	global_load_dwordx4 v[184:187], v150, s[86:87] offset:832
	s_add_u32 s86, s86, 0xc0000
	s_addc_u32 s87, s87, 0
	ds_read_b64_tr_b16 v[72:73], v231
	ds_read_b64_tr_b16 v[74:75], v231 offset:512
	ds_read_b64_tr_b16 v[76:77], v231 offset:2048
	ds_read_b64_tr_b16 v[78:79], v231 offset:2560
	ds_read_b64_tr_b16 v[220:221], v231 offset:1024
	ds_read_b64_tr_b16 v[222:223], v231 offset:1536
	ds_read_b64_tr_b16 v[224:225], v231 offset:3072
	ds_read_b64_tr_b16 v[226:227], v231 offset:3584
	s_waitcnt vmcnt(8)
	ds_write_b128 v247, v[116:119]
	ds_write_b128 v247, v[120:123] offset:1024
	ds_write_b128 v247, v[124:127] offset:2048
	ds_write_b128 v247, v[128:131] offset:3072
	ds_read_b128 v[116:119], v248
	ds_read_b128 v[120:123], v249
	ds_read_b128 v[124:127], v250
	ds_read_b128 v[128:131], v251
	ds_write_b128 v112, v[132:135]
	ds_write_b128 v112, v[136:139] offset:1024
	ds_write_b128 v112, v[140:143] offset:2048
	ds_write_b128 v112, v[144:147] offset:3072
	v_exp_f32_e32 v188, v188
	v_exp_f32_e32 v189, v189
	v_exp_f32_e32 v190, v190
	v_exp_f32_e32 v191, v191
	v_exp_f32_e32 v192, v192
	v_exp_f32_e32 v193, v193
	s_waitcnt lgkmcnt(4)
	v_mfma_f32_32x32x16_bf16 v[32:47], v[116:119], v[48:51], v[32:47]
	v_exp_f32_e32 v194, v194
	v_exp_f32_e32 v195, v195
	v_mfma_f32_32x32x16_bf16 v[32:47], v[120:123], v[52:55], v[32:47]
	v_exp_f32_e32 v196, v196
	v_exp_f32_e32 v197, v197
	v_exp_f32_e32 v198, v198
	v_mfma_f32_32x32x16_bf16 v[32:47], v[124:127], v[56:59], v[32:47]
	v_exp_f32_e32 v199, v199
	v_exp_f32_e32 v200, v200
	v_mfma_f32_32x32x16_bf16 v[32:47], v[128:131], v[60:63], v[32:47]
	v_exp_f32_e32 v201, v201
	v_exp_f32_e32 v202, v202
	v_exp_f32_e32 v203, v203
	v_cvt_pk_bf16_f32 v64, v188, v189
	v_cvt_pk_bf16_f32 v65, v190, v191
	v_cvt_pk_bf16_f32 v66, v192, v193
	v_cvt_pk_bf16_f32 v67, v194, v195
	v_cvt_pk_bf16_f32 v68, v196, v197
	v_cvt_pk_bf16_f32 v69, v198, v199
	v_cvt_pk_bf16_f32 v70, v200, v201
	v_cvt_pk_bf16_f32 v71, v202, v203
	v_pk_add_f32 v[232:233], v[232:233], v[188:189]
	v_pk_add_f32 v[232:233], v[232:233], v[190:191]
	v_pk_add_f32 v[232:233], v[232:233], v[192:193]
	v_pk_add_f32 v[232:233], v[232:233], v[194:195]
	v_pk_add_f32 v[232:233], v[232:233], v[196:197]
	v_pk_add_f32 v[232:233], v[232:233], v[198:199]
	v_pk_add_f32 v[232:233], v[232:233], v[200:201]
	v_pk_add_f32 v[232:233], v[232:233], v[202:203]
	ds_read2_b32 v[188:189], v115 offset0:96 offset1:97
	ds_read2_b32 v[190:191], v115 offset0:98 offset1:99
	ds_read2_b32 v[192:193], v115 offset0:104 offset1:105
	ds_read2_b32 v[194:195], v115 offset0:106 offset1:107
	ds_read2_b32 v[196:197], v115 offset0:112 offset1:113
	ds_read2_b32 v[198:199], v115 offset0:114 offset1:115
	ds_read2_b32 v[200:201], v115 offset0:120 offset1:121
	ds_read2_b32 v[202:203], v115 offset0:122 offset1:123
	v_mfma_f32_32x32x16_bf16 v[0:15], v[64:67], v[72:75], v[0:15]
	v_mfma_f32_32x32x16_bf16 v[16:31], v[64:67], v[76:79], v[16:31]
	v_mfma_f32_32x32x16_bf16 v[0:15], v[68:71], v[220:223], v[0:15]
	v_mfma_f32_32x32x16_bf16 v[16:31], v[68:71], v[224:227], v[16:31]
	global_load_dwordx4 v[116:119], v239, s[86:87]
	global_load_dwordx4 v[120:123], v240, s[86:87]
	global_load_dwordx4 v[124:127], v241, s[86:87]
	global_load_dwordx4 v[128:131], v242, s[86:87]
	global_load_dwordx4 v[132:135], v101, s[86:87] offset:768
	global_load_dwordx4 v[136:139], v150, s[86:87] offset:768
	global_load_dwordx4 v[140:143], v101, s[86:87] offset:832
	global_load_dwordx4 v[144:147], v150, s[86:87] offset:832
	s_add_u32 s86, s86, 0xc0000
	s_addc_u32 s87, s87, 0
	ds_read_b64_tr_b16 v[72:73], v231
	ds_read_b64_tr_b16 v[74:75], v231 offset:512
	ds_read_b64_tr_b16 v[76:77], v231 offset:2048
	ds_read_b64_tr_b16 v[78:79], v231 offset:2560
	ds_read_b64_tr_b16 v[220:221], v231 offset:1024
	ds_read_b64_tr_b16 v[222:223], v231 offset:1536
	ds_read_b64_tr_b16 v[224:225], v231 offset:3072
	ds_read_b64_tr_b16 v[226:227], v231 offset:3584
	s_waitcnt vmcnt(8)
	ds_write_b128 v247, v[156:159]
	ds_write_b128 v247, v[160:163] offset:1024
	ds_write_b128 v247, v[164:167] offset:2048
	ds_write_b128 v247, v[168:171] offset:3072
	ds_read_b128 v[156:159], v248
	ds_read_b128 v[160:163], v249
	ds_read_b128 v[164:167], v250
	ds_read_b128 v[168:171], v251
	ds_write_b128 v112, v[172:175]
	ds_write_b128 v112, v[176:179] offset:1024
	ds_write_b128 v112, v[180:183] offset:2048
	ds_write_b128 v112, v[184:187] offset:3072
	v_exp_f32_e32 v32, v32
	v_exp_f32_e32 v33, v33
	v_exp_f32_e32 v34, v34
	v_exp_f32_e32 v35, v35
	v_exp_f32_e32 v36, v36
	v_exp_f32_e32 v37, v37
	s_waitcnt lgkmcnt(4)
	v_mfma_f32_32x32x16_bf16 v[188:203], v[156:159], v[48:51], v[188:203]
	v_exp_f32_e32 v38, v38
	v_exp_f32_e32 v39, v39
	v_mfma_f32_32x32x16_bf16 v[188:203], v[160:163], v[52:55], v[188:203]
	v_exp_f32_e32 v40, v40
	v_exp_f32_e32 v41, v41
	v_exp_f32_e32 v42, v42
	v_mfma_f32_32x32x16_bf16 v[188:203], v[164:167], v[56:59], v[188:203]
	v_exp_f32_e32 v43, v43
	v_exp_f32_e32 v44, v44
	v_mfma_f32_32x32x16_bf16 v[188:203], v[168:171], v[60:63], v[188:203]
	v_exp_f32_e32 v45, v45
	v_exp_f32_e32 v46, v46
	v_exp_f32_e32 v47, v47
	v_cvt_pk_bf16_f32 v64, v32, v33
	v_cvt_pk_bf16_f32 v65, v34, v35
	v_cvt_pk_bf16_f32 v66, v36, v37
	v_cvt_pk_bf16_f32 v67, v38, v39
	v_cvt_pk_bf16_f32 v68, v40, v41
	v_cvt_pk_bf16_f32 v69, v42, v43
	v_cvt_pk_bf16_f32 v70, v44, v45
	v_cvt_pk_bf16_f32 v71, v46, v47
	v_pk_add_f32 v[232:233], v[232:233], v[32:33]
	v_pk_add_f32 v[232:233], v[232:233], v[34:35]
	v_pk_add_f32 v[232:233], v[232:233], v[36:37]
	v_pk_add_f32 v[232:233], v[232:233], v[38:39]
	v_pk_add_f32 v[232:233], v[232:233], v[40:41]
	v_pk_add_f32 v[232:233], v[232:233], v[42:43]
	v_pk_add_f32 v[232:233], v[232:233], v[44:45]
	v_pk_add_f32 v[232:233], v[232:233], v[46:47]
	ds_read2_b32 v[32:33], v115 offset0:128 offset1:129
	ds_read2_b32 v[34:35], v115 offset0:130 offset1:131
	ds_read2_b32 v[36:37], v115 offset0:136 offset1:137
	ds_read2_b32 v[38:39], v115 offset0:138 offset1:139
	ds_read2_b32 v[40:41], v115 offset0:144 offset1:145
	ds_read2_b32 v[42:43], v115 offset0:146 offset1:147
	ds_read2_b32 v[44:45], v115 offset0:152 offset1:153
	ds_read2_b32 v[46:47], v115 offset0:154 offset1:155
	v_mfma_f32_32x32x16_bf16 v[0:15], v[64:67], v[72:75], v[0:15]
	v_mfma_f32_32x32x16_bf16 v[16:31], v[64:67], v[76:79], v[16:31]
	v_mfma_f32_32x32x16_bf16 v[0:15], v[68:71], v[220:223], v[0:15]
	v_mfma_f32_32x32x16_bf16 v[16:31], v[68:71], v[224:227], v[16:31]
	global_load_dwordx4 v[156:159], v239, s[86:87]
	global_load_dwordx4 v[160:163], v240, s[86:87]
	global_load_dwordx4 v[164:167], v241, s[86:87]
	global_load_dwordx4 v[168:171], v242, s[86:87]
	global_load_dwordx4 v[172:175], v101, s[86:87] offset:768
	global_load_dwordx4 v[176:179], v150, s[86:87] offset:768
	global_load_dwordx4 v[180:183], v101, s[86:87] offset:832
	global_load_dwordx4 v[184:187], v150, s[86:87] offset:832
	s_add_u32 s86, s86, 0xc0000
	s_addc_u32 s87, s87, 0
	ds_read_b64_tr_b16 v[72:73], v231
	ds_read_b64_tr_b16 v[74:75], v231 offset:512
	ds_read_b64_tr_b16 v[76:77], v231 offset:2048
	ds_read_b64_tr_b16 v[78:79], v231 offset:2560
	ds_read_b64_tr_b16 v[220:221], v231 offset:1024
	ds_read_b64_tr_b16 v[222:223], v231 offset:1536
	ds_read_b64_tr_b16 v[224:225], v231 offset:3072
	ds_read_b64_tr_b16 v[226:227], v231 offset:3584
	s_waitcnt vmcnt(8)
	ds_write_b128 v247, v[116:119]
	ds_write_b128 v247, v[120:123] offset:1024
	ds_write_b128 v247, v[124:127] offset:2048
	ds_write_b128 v247, v[128:131] offset:3072
	ds_read_b128 v[116:119], v248
	ds_read_b128 v[120:123], v249
	ds_read_b128 v[124:127], v250
	ds_read_b128 v[128:131], v251
	ds_write_b128 v112, v[132:135]
	ds_write_b128 v112, v[136:139] offset:1024
	ds_write_b128 v112, v[140:143] offset:2048
	ds_write_b128 v112, v[144:147] offset:3072
	v_exp_f32_e32 v188, v188
	v_exp_f32_e32 v189, v189
	v_exp_f32_e32 v190, v190
	v_exp_f32_e32 v191, v191
	v_exp_f32_e32 v192, v192
	v_exp_f32_e32 v193, v193
	s_waitcnt lgkmcnt(4)
	v_mfma_f32_32x32x16_bf16 v[32:47], v[116:119], v[48:51], v[32:47]
	v_exp_f32_e32 v194, v194
	v_exp_f32_e32 v195, v195
	v_mfma_f32_32x32x16_bf16 v[32:47], v[120:123], v[52:55], v[32:47]
	v_exp_f32_e32 v196, v196
	v_exp_f32_e32 v197, v197
	v_exp_f32_e32 v198, v198
	v_mfma_f32_32x32x16_bf16 v[32:47], v[124:127], v[56:59], v[32:47]
	v_exp_f32_e32 v199, v199
	v_exp_f32_e32 v200, v200
	v_mfma_f32_32x32x16_bf16 v[32:47], v[128:131], v[60:63], v[32:47]
	v_exp_f32_e32 v201, v201
	v_exp_f32_e32 v202, v202
	v_exp_f32_e32 v203, v203
	v_cvt_pk_bf16_f32 v64, v188, v189
	v_cvt_pk_bf16_f32 v65, v190, v191
	v_cvt_pk_bf16_f32 v66, v192, v193
	v_cvt_pk_bf16_f32 v67, v194, v195
	v_cvt_pk_bf16_f32 v68, v196, v197
	v_cvt_pk_bf16_f32 v69, v198, v199
	v_cvt_pk_bf16_f32 v70, v200, v201
	v_cvt_pk_bf16_f32 v71, v202, v203
	v_pk_add_f32 v[232:233], v[232:233], v[188:189]
	v_pk_add_f32 v[232:233], v[232:233], v[190:191]
	v_pk_add_f32 v[232:233], v[232:233], v[192:193]
	v_pk_add_f32 v[232:233], v[232:233], v[194:195]
	v_pk_add_f32 v[232:233], v[232:233], v[196:197]
	v_pk_add_f32 v[232:233], v[232:233], v[198:199]
	v_pk_add_f32 v[232:233], v[232:233], v[200:201]
	v_pk_add_f32 v[232:233], v[232:233], v[202:203]
	ds_read2_b32 v[188:189], v115 offset0:160 offset1:161
	ds_read2_b32 v[190:191], v115 offset0:162 offset1:163
	ds_read2_b32 v[192:193], v115 offset0:168 offset1:169
	ds_read2_b32 v[194:195], v115 offset0:170 offset1:171
	ds_read2_b32 v[196:197], v115 offset0:176 offset1:177
	ds_read2_b32 v[198:199], v115 offset0:178 offset1:179
	ds_read2_b32 v[200:201], v115 offset0:184 offset1:185
	ds_read2_b32 v[202:203], v115 offset0:186 offset1:187
	v_mfma_f32_32x32x16_bf16 v[0:15], v[64:67], v[72:75], v[0:15]
	v_mfma_f32_32x32x16_bf16 v[16:31], v[64:67], v[76:79], v[16:31]
	v_mfma_f32_32x32x16_bf16 v[0:15], v[68:71], v[220:223], v[0:15]
	v_mfma_f32_32x32x16_bf16 v[16:31], v[68:71], v[224:227], v[16:31]
	global_load_dwordx4 v[116:119], v239, s[86:87]
	global_load_dwordx4 v[120:123], v240, s[86:87]
	global_load_dwordx4 v[124:127], v241, s[86:87]
	global_load_dwordx4 v[128:131], v242, s[86:87]
	global_load_dwordx4 v[132:135], v101, s[86:87] offset:768
	global_load_dwordx4 v[136:139], v150, s[86:87] offset:768
	global_load_dwordx4 v[140:143], v101, s[86:87] offset:832
	global_load_dwordx4 v[144:147], v150, s[86:87] offset:832
	s_add_u32 s86, s86, 0xc0000
	s_addc_u32 s87, s87, 0
	ds_read_b64_tr_b16 v[72:73], v231
	ds_read_b64_tr_b16 v[74:75], v231 offset:512
	ds_read_b64_tr_b16 v[76:77], v231 offset:2048
	ds_read_b64_tr_b16 v[78:79], v231 offset:2560
	ds_read_b64_tr_b16 v[220:221], v231 offset:1024
	ds_read_b64_tr_b16 v[222:223], v231 offset:1536
	ds_read_b64_tr_b16 v[224:225], v231 offset:3072
	ds_read_b64_tr_b16 v[226:227], v231 offset:3584
	s_waitcnt vmcnt(8)
	ds_write_b128 v247, v[156:159]
	ds_write_b128 v247, v[160:163] offset:1024
	ds_write_b128 v247, v[164:167] offset:2048
	ds_write_b128 v247, v[168:171] offset:3072
	ds_read_b128 v[156:159], v248
	ds_read_b128 v[160:163], v249
	ds_read_b128 v[164:167], v250
	ds_read_b128 v[168:171], v251
	ds_write_b128 v112, v[172:175]
	ds_write_b128 v112, v[176:179] offset:1024
	ds_write_b128 v112, v[180:183] offset:2048
	ds_write_b128 v112, v[184:187] offset:3072
	v_exp_f32_e32 v32, v32
	v_exp_f32_e32 v33, v33
	v_exp_f32_e32 v34, v34
	v_exp_f32_e32 v35, v35
	v_exp_f32_e32 v36, v36
	v_exp_f32_e32 v37, v37
	s_waitcnt lgkmcnt(4)
	v_mfma_f32_32x32x16_bf16 v[188:203], v[156:159], v[48:51], v[188:203]
	v_exp_f32_e32 v38, v38
	v_exp_f32_e32 v39, v39
	v_mfma_f32_32x32x16_bf16 v[188:203], v[160:163], v[52:55], v[188:203]
	v_exp_f32_e32 v40, v40
	v_exp_f32_e32 v41, v41
	v_exp_f32_e32 v42, v42
	v_mfma_f32_32x32x16_bf16 v[188:203], v[164:167], v[56:59], v[188:203]
	v_exp_f32_e32 v43, v43
	v_exp_f32_e32 v44, v44
	v_mfma_f32_32x32x16_bf16 v[188:203], v[168:171], v[60:63], v[188:203]
	v_exp_f32_e32 v45, v45
	v_exp_f32_e32 v46, v46
	v_exp_f32_e32 v47, v47
	v_cvt_pk_bf16_f32 v64, v32, v33
	v_cvt_pk_bf16_f32 v65, v34, v35
	v_cvt_pk_bf16_f32 v66, v36, v37
	v_cvt_pk_bf16_f32 v67, v38, v39
	v_cvt_pk_bf16_f32 v68, v40, v41
	v_cvt_pk_bf16_f32 v69, v42, v43
	v_cvt_pk_bf16_f32 v70, v44, v45
	v_cvt_pk_bf16_f32 v71, v46, v47
	v_pk_add_f32 v[232:233], v[232:233], v[32:33]
	v_pk_add_f32 v[232:233], v[232:233], v[34:35]
	v_pk_add_f32 v[232:233], v[232:233], v[36:37]
	v_pk_add_f32 v[232:233], v[232:233], v[38:39]
	v_pk_add_f32 v[232:233], v[232:233], v[40:41]
	v_pk_add_f32 v[232:233], v[232:233], v[42:43]
	v_pk_add_f32 v[232:233], v[232:233], v[44:45]
	v_pk_add_f32 v[232:233], v[232:233], v[46:47]
	ds_read2_b32 v[32:33], v115 offset0:192 offset1:193
	ds_read2_b32 v[34:35], v115 offset0:194 offset1:195
	ds_read2_b32 v[36:37], v115 offset0:200 offset1:201
	ds_read2_b32 v[38:39], v115 offset0:202 offset1:203
	ds_read2_b32 v[40:41], v115 offset0:208 offset1:209
	ds_read2_b32 v[42:43], v115 offset0:210 offset1:211
	ds_read2_b32 v[44:45], v115 offset0:216 offset1:217
	ds_read2_b32 v[46:47], v115 offset0:218 offset1:219
	v_mfma_f32_32x32x16_bf16 v[0:15], v[64:67], v[72:75], v[0:15]
	v_mfma_f32_32x32x16_bf16 v[16:31], v[64:67], v[76:79], v[16:31]
	v_mfma_f32_32x32x16_bf16 v[0:15], v[68:71], v[220:223], v[0:15]
	v_mfma_f32_32x32x16_bf16 v[16:31], v[68:71], v[224:227], v[16:31]
	global_load_dwordx4 v[156:159], v239, s[86:87]
	global_load_dwordx4 v[160:163], v240, s[86:87]
	global_load_dwordx4 v[164:167], v241, s[86:87]
	global_load_dwordx4 v[168:171], v242, s[86:87]
	global_load_dwordx4 v[172:175], v101, s[86:87] offset:768
	global_load_dwordx4 v[176:179], v150, s[86:87] offset:768
	global_load_dwordx4 v[180:183], v101, s[86:87] offset:832
	global_load_dwordx4 v[184:187], v150, s[86:87] offset:832
	ds_read_b64_tr_b16 v[72:73], v231
	ds_read_b64_tr_b16 v[74:75], v231 offset:512
	ds_read_b64_tr_b16 v[76:77], v231 offset:2048
	ds_read_b64_tr_b16 v[78:79], v231 offset:2560
	ds_read_b64_tr_b16 v[220:221], v231 offset:1024
	ds_read_b64_tr_b16 v[222:223], v231 offset:1536
	ds_read_b64_tr_b16 v[224:225], v231 offset:3072
	ds_read_b64_tr_b16 v[226:227], v231 offset:3584
	s_waitcnt vmcnt(8)
	ds_write_b128 v247, v[116:119]
	ds_write_b128 v247, v[120:123] offset:1024
	ds_write_b128 v247, v[124:127] offset:2048
	ds_write_b128 v247, v[128:131] offset:3072
	ds_read_b128 v[116:119], v248
	ds_read_b128 v[120:123], v249
	ds_read_b128 v[124:127], v250
	ds_read_b128 v[128:131], v251
	ds_write_b128 v112, v[132:135]
	ds_write_b128 v112, v[136:139] offset:1024
	ds_write_b128 v112, v[140:143] offset:2048
	ds_write_b128 v112, v[144:147] offset:3072
	v_exp_f32_e32 v188, v188
	v_exp_f32_e32 v189, v189
	v_exp_f32_e32 v190, v190
	v_exp_f32_e32 v191, v191
	v_exp_f32_e32 v192, v192
	v_exp_f32_e32 v193, v193
	s_waitcnt lgkmcnt(4)
	v_mfma_f32_32x32x16_bf16 v[32:47], v[116:119], v[48:51], v[32:47]
	v_exp_f32_e32 v194, v194
	v_exp_f32_e32 v195, v195
	v_mfma_f32_32x32x16_bf16 v[32:47], v[120:123], v[52:55], v[32:47]
	v_exp_f32_e32 v196, v196
	v_exp_f32_e32 v197, v197
	v_exp_f32_e32 v198, v198
	v_mfma_f32_32x32x16_bf16 v[32:47], v[124:127], v[56:59], v[32:47]
	v_exp_f32_e32 v199, v199
	v_exp_f32_e32 v200, v200
	v_mfma_f32_32x32x16_bf16 v[32:47], v[128:131], v[60:63], v[32:47]
	v_exp_f32_e32 v201, v201
	v_exp_f32_e32 v202, v202
	v_exp_f32_e32 v203, v203
	v_cvt_pk_bf16_f32 v64, v188, v189
	v_cvt_pk_bf16_f32 v65, v190, v191
	v_cvt_pk_bf16_f32 v66, v192, v193
	v_cvt_pk_bf16_f32 v67, v194, v195
	v_cvt_pk_bf16_f32 v68, v196, v197
	v_cvt_pk_bf16_f32 v69, v198, v199
	v_cvt_pk_bf16_f32 v70, v200, v201
	v_cvt_pk_bf16_f32 v71, v202, v203
	v_pk_add_f32 v[232:233], v[232:233], v[188:189]
	v_pk_add_f32 v[232:233], v[232:233], v[190:191]
	v_pk_add_f32 v[232:233], v[232:233], v[192:193]
	v_pk_add_f32 v[232:233], v[232:233], v[194:195]
	v_pk_add_f32 v[232:233], v[232:233], v[196:197]
	v_pk_add_f32 v[232:233], v[232:233], v[198:199]
	v_pk_add_f32 v[232:233], v[232:233], v[200:201]
	v_pk_add_f32 v[232:233], v[232:233], v[202:203]
	ds_read2_b32 v[188:189], v115 offset0:224 offset1:225
	ds_read2_b32 v[190:191], v115 offset0:226 offset1:227
	ds_read2_b32 v[192:193], v115 offset0:232 offset1:233
	ds_read2_b32 v[194:195], v115 offset0:234 offset1:235
	ds_read2_b32 v[196:197], v115 offset0:240 offset1:241
	ds_read2_b32 v[198:199], v115 offset0:242 offset1:243
	ds_read2_b32 v[200:201], v115 offset0:248 offset1:249
	ds_read2_b32 v[202:203], v115 offset0:250 offset1:251
	v_mfma_f32_32x32x16_bf16 v[0:15], v[64:67], v[72:75], v[0:15]
	v_mfma_f32_32x32x16_bf16 v[16:31], v[64:67], v[76:79], v[16:31]
	v_mfma_f32_32x32x16_bf16 v[0:15], v[68:71], v[220:223], v[0:15]
	v_mfma_f32_32x32x16_bf16 v[16:31], v[68:71], v[224:227], v[16:31]
	global_load_dwordx4 v[116:119], v243, s[88:89]
	global_load_dwordx4 v[120:123], v244, s[88:89]
	global_load_dwordx4 v[124:127], v245, s[88:89]
	global_load_dwordx4 v[128:131], v246, s[88:89]
	global_load_dwordx4 v[132:135], v148, s[88:89] offset:768
	global_load_dwordx4 v[136:139], v151, s[88:89] offset:768
	global_load_dwordx4 v[140:143], v148, s[88:89] offset:832
	global_load_dwordx4 v[144:147], v151, s[88:89] offset:832
	s_add_u32 s88, s88, 0x300000
	s_addc_u32 s89, s89, 0
	ds_read_b64_tr_b16 v[72:73], v231
	ds_read_b64_tr_b16 v[74:75], v231 offset:512
	ds_read_b64_tr_b16 v[76:77], v231 offset:2048
	ds_read_b64_tr_b16 v[78:79], v231 offset:2560
	ds_read_b64_tr_b16 v[220:221], v231 offset:1024
	ds_read_b64_tr_b16 v[222:223], v231 offset:1536
	ds_read_b64_tr_b16 v[224:225], v231 offset:3072
	ds_read_b64_tr_b16 v[226:227], v231 offset:3584
	s_waitcnt vmcnt(8)
	ds_write_b128 v247, v[156:159]
	ds_write_b128 v247, v[160:163] offset:1024
	ds_write_b128 v247, v[164:167] offset:2048
	ds_write_b128 v247, v[168:171] offset:3072
	ds_read_b128 v[156:159], v248
	ds_read_b128 v[160:163], v249
	ds_read_b128 v[164:167], v250
	ds_read_b128 v[168:171], v251
	ds_write_b128 v112, v[172:175]
	ds_write_b128 v112, v[176:179] offset:1024
	ds_write_b128 v112, v[180:183] offset:2048
	ds_write_b128 v112, v[184:187] offset:3072
	v_exp_f32_e32 v32, v32
	v_exp_f32_e32 v33, v33
	v_exp_f32_e32 v34, v34
	v_exp_f32_e32 v35, v35
	v_exp_f32_e32 v36, v36
	v_exp_f32_e32 v37, v37
	s_waitcnt lgkmcnt(4)
	v_mfma_f32_32x32x16_bf16 v[188:203], v[156:159], v[48:51], v[188:203]
	v_exp_f32_e32 v38, v38
	v_exp_f32_e32 v39, v39
	v_mfma_f32_32x32x16_bf16 v[188:203], v[160:163], v[52:55], v[188:203]
	v_exp_f32_e32 v40, v40
	v_exp_f32_e32 v41, v41
	v_exp_f32_e32 v42, v42
	v_mfma_f32_32x32x16_bf16 v[188:203], v[164:167], v[56:59], v[188:203]
	v_exp_f32_e32 v43, v43
	v_exp_f32_e32 v44, v44
	v_mfma_f32_32x32x16_bf16 v[188:203], v[168:171], v[60:63], v[188:203]
	v_exp_f32_e32 v45, v45
	v_exp_f32_e32 v46, v46
	v_exp_f32_e32 v47, v47
	v_cvt_pk_bf16_f32 v64, v32, v33
	v_cvt_pk_bf16_f32 v65, v34, v35
	v_cvt_pk_bf16_f32 v66, v36, v37
	v_cvt_pk_bf16_f32 v67, v38, v39
	v_cvt_pk_bf16_f32 v68, v40, v41
	v_cvt_pk_bf16_f32 v69, v42, v43
	v_cvt_pk_bf16_f32 v70, v44, v45
	v_cvt_pk_bf16_f32 v71, v46, v47
	v_pk_add_f32 v[232:233], v[232:233], v[32:33]
	v_pk_add_f32 v[232:233], v[232:233], v[34:35]
	v_pk_add_f32 v[232:233], v[232:233], v[36:37]
	v_pk_add_f32 v[232:233], v[232:233], v[38:39]
	v_pk_add_f32 v[232:233], v[232:233], v[40:41]
	v_pk_add_f32 v[232:233], v[232:233], v[42:43]
	v_pk_add_f32 v[232:233], v[232:233], v[44:45]
	v_pk_add_f32 v[232:233], v[232:233], v[46:47]
	v_mov_b32_e32 v115, v230
	ds_read2_b32 v[32:33], v115 offset0:0 offset1:1
	ds_read2_b32 v[34:35], v115 offset0:2 offset1:3
	ds_read2_b32 v[36:37], v115 offset0:8 offset1:9
	ds_read2_b32 v[38:39], v115 offset0:10 offset1:11
	ds_read2_b32 v[40:41], v115 offset0:16 offset1:17
	ds_read2_b32 v[42:43], v115 offset0:18 offset1:19
	ds_read2_b32 v[44:45], v115 offset0:24 offset1:25
	ds_read2_b32 v[46:47], v115 offset0:26 offset1:27
	v_mfma_f32_32x32x16_bf16 v[0:15], v[64:67], v[72:75], v[0:15]
	v_mfma_f32_32x32x16_bf16 v[16:31], v[64:67], v[76:79], v[16:31]
	v_mfma_f32_32x32x16_bf16 v[0:15], v[68:71], v[220:223], v[0:15]
	v_mfma_f32_32x32x16_bf16 v[16:31], v[68:71], v[224:227], v[16:31]
	global_load_dwordx4 v[156:159], v243, s[88:89]
	global_load_dwordx4 v[160:163], v244, s[88:89]
	global_load_dwordx4 v[164:167], v245, s[88:89]
	global_load_dwordx4 v[168:171], v246, s[88:89]
	global_load_dwordx4 v[172:175], v148, s[88:89] offset:768
	global_load_dwordx4 v[176:179], v151, s[88:89] offset:768
	global_load_dwordx4 v[180:183], v148, s[88:89] offset:832
	global_load_dwordx4 v[184:187], v151, s[88:89] offset:832
	s_add_u32 s88, s88, 0x300000
	s_addc_u32 s89, s89, 0
	ds_read_b64_tr_b16 v[72:73], v231
	ds_read_b64_tr_b16 v[74:75], v231 offset:512
	ds_read_b64_tr_b16 v[76:77], v231 offset:2048
	ds_read_b64_tr_b16 v[78:79], v231 offset:2560
	ds_read_b64_tr_b16 v[220:221], v231 offset:1024
	ds_read_b64_tr_b16 v[222:223], v231 offset:1536
	ds_read_b64_tr_b16 v[224:225], v231 offset:3072
	ds_read_b64_tr_b16 v[226:227], v231 offset:3584
	s_waitcnt vmcnt(8)
	ds_write_b128 v247, v[116:119]
	ds_write_b128 v247, v[120:123] offset:1024
	ds_write_b128 v247, v[124:127] offset:2048
	ds_write_b128 v247, v[128:131] offset:3072
	ds_read_b128 v[116:119], v248
	ds_read_b128 v[120:123], v249
	ds_read_b128 v[124:127], v250
	ds_read_b128 v[128:131], v251
	ds_write_b128 v112, v[132:135]
	ds_write_b128 v112, v[136:139] offset:1024
	ds_write_b128 v112, v[140:143] offset:2048
	ds_write_b128 v112, v[144:147] offset:3072
	v_exp_f32_e32 v188, v188
	v_exp_f32_e32 v189, v189
	v_exp_f32_e32 v190, v190
	v_exp_f32_e32 v191, v191
	v_exp_f32_e32 v192, v192
	v_exp_f32_e32 v193, v193
	s_waitcnt lgkmcnt(4)
	v_mfma_f32_32x32x16_bf16 v[32:47], v[116:119], v[48:51], v[32:47]
	v_exp_f32_e32 v194, v194
	v_exp_f32_e32 v195, v195
	v_mfma_f32_32x32x16_bf16 v[32:47], v[120:123], v[52:55], v[32:47]
	v_exp_f32_e32 v196, v196
	v_exp_f32_e32 v197, v197
	v_exp_f32_e32 v198, v198
	v_mfma_f32_32x32x16_bf16 v[32:47], v[124:127], v[56:59], v[32:47]
	v_exp_f32_e32 v199, v199
	v_exp_f32_e32 v200, v200
	v_mfma_f32_32x32x16_bf16 v[32:47], v[128:131], v[60:63], v[32:47]
	v_exp_f32_e32 v201, v201
	v_exp_f32_e32 v202, v202
	v_exp_f32_e32 v203, v203
	v_cvt_pk_bf16_f32 v64, v188, v189
	v_cvt_pk_bf16_f32 v65, v190, v191
	v_cvt_pk_bf16_f32 v66, v192, v193
	v_cvt_pk_bf16_f32 v67, v194, v195
	v_cvt_pk_bf16_f32 v68, v196, v197
	v_cvt_pk_bf16_f32 v69, v198, v199
	v_cvt_pk_bf16_f32 v70, v200, v201
	v_cvt_pk_bf16_f32 v71, v202, v203
	v_pk_add_f32 v[232:233], v[232:233], v[188:189]
	v_pk_add_f32 v[232:233], v[232:233], v[190:191]
	v_pk_add_f32 v[232:233], v[232:233], v[192:193]
	v_pk_add_f32 v[232:233], v[232:233], v[194:195]
	v_pk_add_f32 v[232:233], v[232:233], v[196:197]
	v_pk_add_f32 v[232:233], v[232:233], v[198:199]
	v_pk_add_f32 v[232:233], v[232:233], v[200:201]
	v_pk_add_f32 v[232:233], v[232:233], v[202:203]
	ds_read2_b32 v[188:189], v115 offset0:32 offset1:33
	ds_read2_b32 v[190:191], v115 offset0:34 offset1:35
	ds_read2_b32 v[192:193], v115 offset0:40 offset1:41
	ds_read2_b32 v[194:195], v115 offset0:42 offset1:43
	ds_read2_b32 v[196:197], v115 offset0:48 offset1:49
	ds_read2_b32 v[198:199], v115 offset0:50 offset1:51
	ds_read2_b32 v[200:201], v115 offset0:56 offset1:57
	ds_read2_b32 v[202:203], v115 offset0:58 offset1:59
	v_mfma_f32_32x32x16_bf16 v[0:15], v[64:67], v[72:75], v[0:15]
	v_mfma_f32_32x32x16_bf16 v[16:31], v[64:67], v[76:79], v[16:31]
	v_mfma_f32_32x32x16_bf16 v[0:15], v[68:71], v[220:223], v[0:15]
	v_mfma_f32_32x32x16_bf16 v[16:31], v[68:71], v[224:227], v[16:31]
	global_load_dwordx4 v[116:119], v243, s[88:89]
	global_load_dwordx4 v[120:123], v244, s[88:89]
	global_load_dwordx4 v[124:127], v245, s[88:89]
	global_load_dwordx4 v[128:131], v246, s[88:89]
	global_load_dwordx4 v[132:135], v148, s[88:89] offset:768
	global_load_dwordx4 v[136:139], v151, s[88:89] offset:768
	global_load_dwordx4 v[140:143], v148, s[88:89] offset:832
	global_load_dwordx4 v[144:147], v151, s[88:89] offset:832
	s_add_u32 s88, s88, 0x300000
	s_addc_u32 s89, s89, 0
	ds_read_b64_tr_b16 v[72:73], v231
	ds_read_b64_tr_b16 v[74:75], v231 offset:512
	ds_read_b64_tr_b16 v[76:77], v231 offset:2048
	ds_read_b64_tr_b16 v[78:79], v231 offset:2560
	ds_read_b64_tr_b16 v[220:221], v231 offset:1024
	ds_read_b64_tr_b16 v[222:223], v231 offset:1536
	ds_read_b64_tr_b16 v[224:225], v231 offset:3072
	ds_read_b64_tr_b16 v[226:227], v231 offset:3584
	s_waitcnt vmcnt(8)
	ds_write_b128 v247, v[156:159]
	ds_write_b128 v247, v[160:163] offset:1024
	ds_write_b128 v247, v[164:167] offset:2048
	ds_write_b128 v247, v[168:171] offset:3072
	ds_read_b128 v[156:159], v248
	ds_read_b128 v[160:163], v249
	ds_read_b128 v[164:167], v250
	ds_read_b128 v[168:171], v251
	ds_write_b128 v112, v[172:175]
	ds_write_b128 v112, v[176:179] offset:1024
	ds_write_b128 v112, v[180:183] offset:2048
	ds_write_b128 v112, v[184:187] offset:3072
	v_exp_f32_e32 v32, v32
	v_exp_f32_e32 v33, v33
	v_exp_f32_e32 v34, v34
	v_exp_f32_e32 v35, v35
	v_exp_f32_e32 v36, v36
	v_exp_f32_e32 v37, v37
	s_waitcnt lgkmcnt(4)
	v_mfma_f32_32x32x16_bf16 v[188:203], v[156:159], v[48:51], v[188:203]
	v_exp_f32_e32 v38, v38
	v_exp_f32_e32 v39, v39
	v_mfma_f32_32x32x16_bf16 v[188:203], v[160:163], v[52:55], v[188:203]
	v_exp_f32_e32 v40, v40
	v_exp_f32_e32 v41, v41
	v_exp_f32_e32 v42, v42
	v_mfma_f32_32x32x16_bf16 v[188:203], v[164:167], v[56:59], v[188:203]
	v_exp_f32_e32 v43, v43
	v_exp_f32_e32 v44, v44
	v_mfma_f32_32x32x16_bf16 v[188:203], v[168:171], v[60:63], v[188:203]
	v_exp_f32_e32 v45, v45
	v_exp_f32_e32 v46, v46
	v_exp_f32_e32 v47, v47
	v_cvt_pk_bf16_f32 v64, v32, v33
	v_cvt_pk_bf16_f32 v65, v34, v35
	v_cvt_pk_bf16_f32 v66, v36, v37
	v_cvt_pk_bf16_f32 v67, v38, v39
	v_cvt_pk_bf16_f32 v68, v40, v41
	v_cvt_pk_bf16_f32 v69, v42, v43
	v_cvt_pk_bf16_f32 v70, v44, v45
	v_cvt_pk_bf16_f32 v71, v46, v47
	v_pk_add_f32 v[232:233], v[232:233], v[32:33]
	v_pk_add_f32 v[232:233], v[232:233], v[34:35]
	v_pk_add_f32 v[232:233], v[232:233], v[36:37]
	v_pk_add_f32 v[232:233], v[232:233], v[38:39]
	v_pk_add_f32 v[232:233], v[232:233], v[40:41]
	v_pk_add_f32 v[232:233], v[232:233], v[42:43]
	v_pk_add_f32 v[232:233], v[232:233], v[44:45]
	v_pk_add_f32 v[232:233], v[232:233], v[46:47]
	ds_read2_b32 v[32:33], v115 offset0:64 offset1:65
	ds_read2_b32 v[34:35], v115 offset0:66 offset1:67
	ds_read2_b32 v[36:37], v115 offset0:72 offset1:73
	ds_read2_b32 v[38:39], v115 offset0:74 offset1:75
	ds_read2_b32 v[40:41], v115 offset0:80 offset1:81
	ds_read2_b32 v[42:43], v115 offset0:82 offset1:83
	ds_read2_b32 v[44:45], v115 offset0:88 offset1:89
	ds_read2_b32 v[46:47], v115 offset0:90 offset1:91
	v_mfma_f32_32x32x16_bf16 v[0:15], v[64:67], v[72:75], v[0:15]
	v_mfma_f32_32x32x16_bf16 v[16:31], v[64:67], v[76:79], v[16:31]
	v_mfma_f32_32x32x16_bf16 v[0:15], v[68:71], v[220:223], v[0:15]
	v_mfma_f32_32x32x16_bf16 v[16:31], v[68:71], v[224:227], v[16:31]
	global_load_dwordx4 v[156:159], v243, s[88:89]
	global_load_dwordx4 v[160:163], v244, s[88:89]
	global_load_dwordx4 v[164:167], v245, s[88:89]
	global_load_dwordx4 v[168:171], v246, s[88:89]
	global_load_dwordx4 v[172:175], v148, s[88:89] offset:768
	global_load_dwordx4 v[176:179], v151, s[88:89] offset:768
	global_load_dwordx4 v[180:183], v148, s[88:89] offset:832
	global_load_dwordx4 v[184:187], v151, s[88:89] offset:832
	s_add_u32 s88, s88, 0x300000
	s_addc_u32 s89, s89, 0
	ds_read_b64_tr_b16 v[72:73], v231
	ds_read_b64_tr_b16 v[74:75], v231 offset:512
	ds_read_b64_tr_b16 v[76:77], v231 offset:2048
	ds_read_b64_tr_b16 v[78:79], v231 offset:2560
	ds_read_b64_tr_b16 v[220:221], v231 offset:1024
	ds_read_b64_tr_b16 v[222:223], v231 offset:1536
	ds_read_b64_tr_b16 v[224:225], v231 offset:3072
	ds_read_b64_tr_b16 v[226:227], v231 offset:3584
	s_waitcnt vmcnt(8)
	ds_write_b128 v247, v[116:119]
	ds_write_b128 v247, v[120:123] offset:1024
	ds_write_b128 v247, v[124:127] offset:2048
	ds_write_b128 v247, v[128:131] offset:3072
	ds_read_b128 v[116:119], v248
	ds_read_b128 v[120:123], v249
	ds_read_b128 v[124:127], v250
	ds_read_b128 v[128:131], v251
	ds_write_b128 v112, v[132:135]
	ds_write_b128 v112, v[136:139] offset:1024
	ds_write_b128 v112, v[140:143] offset:2048
	ds_write_b128 v112, v[144:147] offset:3072
	v_exp_f32_e32 v188, v188
	v_exp_f32_e32 v189, v189
	v_exp_f32_e32 v190, v190
	v_exp_f32_e32 v191, v191
	v_exp_f32_e32 v192, v192
	v_exp_f32_e32 v193, v193
	s_waitcnt lgkmcnt(4)
	v_mfma_f32_32x32x16_bf16 v[32:47], v[116:119], v[48:51], v[32:47]
	v_exp_f32_e32 v194, v194
	v_exp_f32_e32 v195, v195
	v_mfma_f32_32x32x16_bf16 v[32:47], v[120:123], v[52:55], v[32:47]
	v_exp_f32_e32 v196, v196
	v_exp_f32_e32 v197, v197
	v_exp_f32_e32 v198, v198
	v_mfma_f32_32x32x16_bf16 v[32:47], v[124:127], v[56:59], v[32:47]
	v_exp_f32_e32 v199, v199
	v_exp_f32_e32 v200, v200
	v_mfma_f32_32x32x16_bf16 v[32:47], v[128:131], v[60:63], v[32:47]
	v_exp_f32_e32 v201, v201
	v_exp_f32_e32 v202, v202
	v_exp_f32_e32 v203, v203
	v_cvt_pk_bf16_f32 v64, v188, v189
	v_cvt_pk_bf16_f32 v65, v190, v191
	v_cvt_pk_bf16_f32 v66, v192, v193
	v_cvt_pk_bf16_f32 v67, v194, v195
	v_cvt_pk_bf16_f32 v68, v196, v197
	v_cvt_pk_bf16_f32 v69, v198, v199
	v_cvt_pk_bf16_f32 v70, v200, v201
	v_cvt_pk_bf16_f32 v71, v202, v203
	v_pk_add_f32 v[232:233], v[232:233], v[188:189]
	v_pk_add_f32 v[232:233], v[232:233], v[190:191]
	v_pk_add_f32 v[232:233], v[232:233], v[192:193]
	v_pk_add_f32 v[232:233], v[232:233], v[194:195]
	v_pk_add_f32 v[232:233], v[232:233], v[196:197]
	v_pk_add_f32 v[232:233], v[232:233], v[198:199]
	v_pk_add_f32 v[232:233], v[232:233], v[200:201]
	v_pk_add_f32 v[232:233], v[232:233], v[202:203]
	ds_read2_b32 v[188:189], v115 offset0:96 offset1:97
	ds_read2_b32 v[190:191], v115 offset0:98 offset1:99
	ds_read2_b32 v[192:193], v115 offset0:104 offset1:105
	ds_read2_b32 v[194:195], v115 offset0:106 offset1:107
	ds_read2_b32 v[196:197], v115 offset0:112 offset1:113
	ds_read2_b32 v[198:199], v115 offset0:114 offset1:115
	ds_read2_b32 v[200:201], v115 offset0:120 offset1:121
	ds_read2_b32 v[202:203], v115 offset0:122 offset1:123
	v_mfma_f32_32x32x16_bf16 v[0:15], v[64:67], v[72:75], v[0:15]
	v_mfma_f32_32x32x16_bf16 v[16:31], v[64:67], v[76:79], v[16:31]
	v_mfma_f32_32x32x16_bf16 v[0:15], v[68:71], v[220:223], v[0:15]
	v_mfma_f32_32x32x16_bf16 v[16:31], v[68:71], v[224:227], v[16:31]
	global_load_dwordx4 v[116:119], v243, s[88:89]
	global_load_dwordx4 v[120:123], v244, s[88:89]
	global_load_dwordx4 v[124:127], v245, s[88:89]
	global_load_dwordx4 v[128:131], v246, s[88:89]
	global_load_dwordx4 v[132:135], v148, s[88:89] offset:768
	global_load_dwordx4 v[136:139], v151, s[88:89] offset:768
	global_load_dwordx4 v[140:143], v148, s[88:89] offset:832
	global_load_dwordx4 v[144:147], v151, s[88:89] offset:832
	ds_read_b64_tr_b16 v[72:73], v231
	ds_read_b64_tr_b16 v[74:75], v231 offset:512
	ds_read_b64_tr_b16 v[76:77], v231 offset:2048
	ds_read_b64_tr_b16 v[78:79], v231 offset:2560
	ds_read_b64_tr_b16 v[220:221], v231 offset:1024
	ds_read_b64_tr_b16 v[222:223], v231 offset:1536
	ds_read_b64_tr_b16 v[224:225], v231 offset:3072
	ds_read_b64_tr_b16 v[226:227], v231 offset:3584
	s_waitcnt vmcnt(8)
	ds_write_b128 v247, v[156:159]
	ds_write_b128 v247, v[160:163] offset:1024
	ds_write_b128 v247, v[164:167] offset:2048
	ds_write_b128 v247, v[168:171] offset:3072
	ds_read_b128 v[156:159], v248
	ds_read_b128 v[160:163], v249
	ds_read_b128 v[164:167], v250
	ds_read_b128 v[168:171], v251
	ds_write_b128 v112, v[172:175]
	ds_write_b128 v112, v[176:179] offset:1024
	ds_write_b128 v112, v[180:183] offset:2048
	ds_write_b128 v112, v[184:187] offset:3072
	v_exp_f32_e32 v32, v32
	v_exp_f32_e32 v33, v33
	v_exp_f32_e32 v34, v34
	v_exp_f32_e32 v35, v35
	v_exp_f32_e32 v36, v36
	v_exp_f32_e32 v37, v37
	s_waitcnt lgkmcnt(4)
	v_mfma_f32_32x32x16_bf16 v[188:203], v[156:159], v[48:51], v[188:203]
	v_exp_f32_e32 v38, v38
	v_exp_f32_e32 v39, v39
	v_mfma_f32_32x32x16_bf16 v[188:203], v[160:163], v[52:55], v[188:203]
	v_exp_f32_e32 v40, v40
	v_exp_f32_e32 v41, v41
	v_exp_f32_e32 v42, v42
	v_mfma_f32_32x32x16_bf16 v[188:203], v[164:167], v[56:59], v[188:203]
	v_exp_f32_e32 v43, v43
	v_exp_f32_e32 v44, v44
	v_mfma_f32_32x32x16_bf16 v[188:203], v[168:171], v[60:63], v[188:203]
	v_exp_f32_e32 v45, v45
	v_exp_f32_e32 v46, v46
	v_exp_f32_e32 v47, v47
	v_cvt_pk_bf16_f32 v64, v32, v33
	v_cvt_pk_bf16_f32 v65, v34, v35
	v_cvt_pk_bf16_f32 v66, v36, v37
	v_cvt_pk_bf16_f32 v67, v38, v39
	v_cvt_pk_bf16_f32 v68, v40, v41
	v_cvt_pk_bf16_f32 v69, v42, v43
	v_cvt_pk_bf16_f32 v70, v44, v45
	v_cvt_pk_bf16_f32 v71, v46, v47
	v_pk_add_f32 v[232:233], v[232:233], v[32:33]
	v_pk_add_f32 v[232:233], v[232:233], v[34:35]
	v_pk_add_f32 v[232:233], v[232:233], v[36:37]
	v_pk_add_f32 v[232:233], v[232:233], v[38:39]
	v_pk_add_f32 v[232:233], v[232:233], v[40:41]
	v_pk_add_f32 v[232:233], v[232:233], v[42:43]
	v_pk_add_f32 v[232:233], v[232:233], v[44:45]
	v_pk_add_f32 v[232:233], v[232:233], v[46:47]
	ds_read2_b32 v[32:33], v115 offset0:128 offset1:129
	ds_read2_b32 v[34:35], v115 offset0:130 offset1:131
	ds_read2_b32 v[36:37], v115 offset0:136 offset1:137
	ds_read2_b32 v[38:39], v115 offset0:138 offset1:139
	ds_read2_b32 v[40:41], v115 offset0:144 offset1:145
	ds_read2_b32 v[42:43], v115 offset0:146 offset1:147
	ds_read2_b32 v[44:45], v115 offset0:152 offset1:153
	ds_read2_b32 v[46:47], v115 offset0:154 offset1:155
	v_mfma_f32_32x32x16_bf16 v[0:15], v[64:67], v[72:75], v[0:15]
	v_mfma_f32_32x32x16_bf16 v[16:31], v[64:67], v[76:79], v[16:31]
	v_mfma_f32_32x32x16_bf16 v[0:15], v[68:71], v[220:223], v[0:15]
	v_mfma_f32_32x32x16_bf16 v[16:31], v[68:71], v[224:227], v[16:31]
	ds_read_b64_tr_b16 v[72:73], v231
	ds_read_b64_tr_b16 v[74:75], v231 offset:512
	ds_read_b64_tr_b16 v[76:77], v231 offset:2048
	ds_read_b64_tr_b16 v[78:79], v231 offset:2560
	ds_read_b64_tr_b16 v[220:221], v231 offset:1024
	ds_read_b64_tr_b16 v[222:223], v231 offset:1536
	ds_read_b64_tr_b16 v[224:225], v231 offset:3072
	ds_read_b64_tr_b16 v[226:227], v231 offset:3584
	s_waitcnt vmcnt(0)
; __device__ __forceinline__ int crow(int r, int hi) { return (r & 3) + 8 * (r >> 2) + 4 * hi; }
; __device__ __forceinline__ void dil_unit(LAS unsigned char* lds, bf16_t* proj, int seq, int hd, int T0, int rho) {
;     ...
;     l += __shfl_xor(l, 32);
; #pragma unroll
;     for (int rr = 0; rr < 16; ++rr) {
;         const int j = crow(rr, hi);
;         const float il = __builtin_amdgcn_rcpf(__shfl(l, j));
	ds_write_b128 v247, v[116:119]
	ds_write_b128 v247, v[120:123] offset:1024
	ds_write_b128 v247, v[124:127] offset:2048
	ds_write_b128 v247, v[128:131] offset:3072
	ds_read_b128 v[116:119], v248
	ds_read_b128 v[120:123], v249
	ds_read_b128 v[124:127], v250
	ds_read_b128 v[128:131], v251
	ds_write_b128 v112, v[132:135]
	ds_write_b128 v112, v[136:139] offset:1024
	ds_write_b128 v112, v[140:143] offset:2048
	ds_write_b128 v112, v[144:147] offset:3072
	v_exp_f32_e32 v188, v188
	v_exp_f32_e32 v189, v189
	v_exp_f32_e32 v190, v190
	v_exp_f32_e32 v191, v191
	v_exp_f32_e32 v192, v192
	v_exp_f32_e32 v193, v193
	s_waitcnt lgkmcnt(4)
	v_mfma_f32_32x32x16_bf16 v[32:47], v[116:119], v[48:51], v[32:47]
	v_exp_f32_e32 v194, v194
	v_exp_f32_e32 v195, v195
	v_mfma_f32_32x32x16_bf16 v[32:47], v[120:123], v[52:55], v[32:47]
	v_exp_f32_e32 v196, v196
	v_exp_f32_e32 v197, v197
	v_exp_f32_e32 v198, v198
	v_mfma_f32_32x32x16_bf16 v[32:47], v[124:127], v[56:59], v[32:47]
	v_exp_f32_e32 v199, v199
	v_exp_f32_e32 v200, v200
	v_mfma_f32_32x32x16_bf16 v[32:47], v[128:131], v[60:63], v[32:47]
	v_exp_f32_e32 v201, v201
	v_exp_f32_e32 v202, v202
	v_exp_f32_e32 v203, v203
	v_cvt_pk_bf16_f32 v64, v188, v189
	v_cvt_pk_bf16_f32 v65, v190, v191
	v_cvt_pk_bf16_f32 v66, v192, v193
	v_cvt_pk_bf16_f32 v67, v194, v195
	v_cvt_pk_bf16_f32 v68, v196, v197
	v_cvt_pk_bf16_f32 v69, v198, v199
	v_cvt_pk_bf16_f32 v70, v200, v201
	v_cvt_pk_bf16_f32 v71, v202, v203
	v_pk_add_f32 v[232:233], v[232:233], v[188:189]
	v_pk_add_f32 v[232:233], v[232:233], v[190:191]
	v_pk_add_f32 v[232:233], v[232:233], v[192:193]
	v_pk_add_f32 v[232:233], v[232:233], v[194:195]
	v_pk_add_f32 v[232:233], v[232:233], v[196:197]
	v_pk_add_f32 v[232:233], v[232:233], v[198:199]
	v_pk_add_f32 v[232:233], v[232:233], v[200:201]
	v_pk_add_f32 v[232:233], v[232:233], v[202:203]
	v_mfma_f32_32x32x16_bf16 v[0:15], v[64:67], v[72:75], v[0:15]
	v_mfma_f32_32x32x16_bf16 v[16:31], v[64:67], v[76:79], v[16:31]
	v_mfma_f32_32x32x16_bf16 v[0:15], v[68:71], v[220:223], v[0:15]
	v_mfma_f32_32x32x16_bf16 v[16:31], v[68:71], v[224:227], v[16:31]
	ds_read_b64_tr_b16 v[72:73], v231
	ds_read_b64_tr_b16 v[74:75], v231 offset:512
	ds_read_b64_tr_b16 v[76:77], v231 offset:2048
	ds_read_b64_tr_b16 v[78:79], v231 offset:2560
	ds_read_b64_tr_b16 v[220:221], v231 offset:1024
	ds_read_b64_tr_b16 v[222:223], v231 offset:1536
	ds_read_b64_tr_b16 v[224:225], v231 offset:3072
	ds_read_b64_tr_b16 v[226:227], v231 offset:3584
	s_waitcnt lgkmcnt(0)
	v_exp_f32_e32 v32, v32
	v_exp_f32_e32 v33, v33
	v_exp_f32_e32 v34, v34
	v_exp_f32_e32 v35, v35
	v_exp_f32_e32 v36, v36
	v_exp_f32_e32 v37, v37
	v_exp_f32_e32 v38, v38
	v_exp_f32_e32 v39, v39
	v_exp_f32_e32 v40, v40
	v_exp_f32_e32 v41, v41
	v_exp_f32_e32 v42, v42
	v_exp_f32_e32 v43, v43
	v_exp_f32_e32 v44, v44
	v_exp_f32_e32 v45, v45
	v_exp_f32_e32 v46, v46
	v_exp_f32_e32 v47, v47
	v_cvt_pk_bf16_f32 v64, v32, v33
	v_cvt_pk_bf16_f32 v65, v34, v35
	v_cvt_pk_bf16_f32 v66, v36, v37
	v_cvt_pk_bf16_f32 v67, v38, v39
	v_cvt_pk_bf16_f32 v68, v40, v41
	v_cvt_pk_bf16_f32 v69, v42, v43
	v_cvt_pk_bf16_f32 v70, v44, v45
	v_cvt_pk_bf16_f32 v71, v46, v47
	v_pk_add_f32 v[232:233], v[232:233], v[32:33]
	v_pk_add_f32 v[232:233], v[232:233], v[34:35]
	v_pk_add_f32 v[232:233], v[232:233], v[36:37]
	v_pk_add_f32 v[232:233], v[232:233], v[38:39]
	v_pk_add_f32 v[232:233], v[232:233], v[40:41]
	v_pk_add_f32 v[232:233], v[232:233], v[42:43]
	v_pk_add_f32 v[232:233], v[232:233], v[44:45]
	v_pk_add_f32 v[232:233], v[232:233], v[46:47]
	v_mfma_f32_32x32x16_bf16 v[0:15], v[64:67], v[72:75], v[0:15]
	v_mfma_f32_32x32x16_bf16 v[16:31], v[64:67], v[76:79], v[16:31]
	v_mfma_f32_32x32x16_bf16 v[0:15], v[68:71], v[220:223], v[0:15]
	v_mfma_f32_32x32x16_bf16 v[16:31], v[68:71], v[224:227], v[16:31]
	v_add_f32_e32 v113, v232, v233
	v_or_b32_e32 v114, 1, v107
	v_or_b32_e32 v97, 2, v107
	v_or_b32_e32 v96, 3, v107
	v_or_b32_e32 v95, 8, v107
	v_or_b32_e32 v94, 9, v107
	v_or_b32_e32 v93, 10, v107
	v_or_b32_e32 v92, 11, v107
	v_or_b32_e32 v91, 16, v107
	v_or_b32_e32 v90, 17, v107
	v_or_b32_e32 v89, 18, v107
	v_or_b32_e32 v88, 19, v107
	v_or_b32_e32 v87, 24, v107
	v_or_b32_e32 v86, 25, v107
	v_or_b32_e32 v85, 26, v107
	v_or_b32_e32 v84, 27, v107
	s_nop 11
	s_branch .LBB0_553
; #define LAS __attribute__((address_space(3)))
; #define GAS __attribute__((address_space(1)))
; __device__ __forceinline__ void dil_unit(LAS unsigned char* lds, bf16_t* proj, int seq, int hd, int T0, int rho) {
;     int tid_ = threadIdx.x; asm volatile("" : "+v"(tid_));
;     const int tid = tid_, lane = tid & 63, r32 = lane & 31, hi = lane >> 5, wid = __builtin_amdgcn_readfirstlane(tid >> 6);
;     bf16_t* base = proj + (size_t)seq * SEQ * NIN;
;     LAS unsigned char* wbuf = lds + wid * 4096;
;     const LAS unsigned char* vp = wbuf + ((lane >> 4) & 1) * 32 + (lane & 3) * 8 + (4 * hi + ((lane & 15) >> 2)) * 64;
;     const int P0 = T0 + rho;
;     bf16x8 qr[4];
; #pragma unroll
;     for (int ks = 0; ks < 4; ++ks) qr[ks] = *(const GAS bf16x8*)(base + (size_t)(P0 + 16 * r32) * NIN + PC_LQ + hd * 64 + 16 * ks + 8 * hi);
;     f32x16 o0 = {}, o1 = {}; float l = 0.f;
;     const bool bound = (T0 < 1024) || (T0 >= 15360);
.LBB0_558:
	s_movk_i32 s100, 0x1800
	s_add_i32 s101, s6, 0x15c00
	s_lshl_b32 s90, s58, 1
	s_add_u32 s82, s56, s90
	s_addc_u32 s83, s57, 0
	s_add_u32 s82, s82, 0x1200
	s_addc_u32 s83, s83, 0
	s_sub_i32 s90, s76, 64
	s_mul_i32 s90, s90, 0x1800
	s_add_u32 s84, s82, s90
	s_addc_u32 s85, s83, 0
	s_sub_i32 s90, s76, 256
	s_mul_i32 s90, s90, 0x1800
	s_add_u32 s86, s82, s90
	s_addc_u32 s87, s83, 0
	s_sub_i32 s90, s76, 1024
	s_mul_i32 s90, s90, 0x1800
	s_add_u32 s88, s82, s90
	s_addc_u32 s89, s83, 0
	v_lshlrev_b32_e32 v153, 1, v98
	v_mad_u32_u24 v80, v105, s100, v82
	v_mad_u32_u24 v100, v110, s100, v153
	v_add_u32_e32 v149, 0x18000, v100
	v_lshlrev_b32_e32 v83, 2, v105
	v_mad_u32_u24 v83, v83, s100, v82
	v_lshlrev_b32_e32 v101, 2, v110
	v_mad_u32_u24 v101, v101, s100, v153
	v_add_u32_e32 v150, 0x60000, v101
	v_lshlrev_b32_e32 v99, 4, v105
	v_mad_u32_u24 v99, v99, s100, v82
	v_lshlrev_b32_e32 v148, 4, v110
	v_mad_u32_u24 v148, v148, s100, v153
	v_add_u32_e32 v151, 0x180000, v148
	v_lshrrev_b32_e32 v249, 3, v103
	v_and_b32_e32 v250, 7, v103
	v_lshlrev_b32_e32 v250, 4, v250
	v_add_u32_e32 v235, 0, v249
	v_add_u32_e32 v236, 8, v249
	v_add_u32_e32 v237, 16, v249
	v_add_u32_e32 v238, 24, v249
	v_add_u32_e32 v239, 0, v249
	v_lshlrev_b32_e32 v239, 2, v239
	v_add_u32_e32 v240, 8, v249
	v_lshlrev_b32_e32 v240, 2, v240
	v_add_u32_e32 v241, 16, v249
	v_lshlrev_b32_e32 v241, 2, v241
	v_add_u32_e32 v242, 24, v249
	v_lshlrev_b32_e32 v242, 2, v242
	v_add_u32_e32 v243, 0, v249
	v_lshlrev_b32_e32 v243, 4, v243
	v_add_u32_e32 v244, 8, v249
	v_lshlrev_b32_e32 v244, 4, v244
	v_add_u32_e32 v245, 16, v249
	v_lshlrev_b32_e32 v245, 4, v245
	v_add_u32_e32 v246, 24, v249
	v_lshlrev_b32_e32 v246, 4, v246
	v_mov_b32_e32 v252, v250
	v_mov_b32_e32 v100, v110
	v_add_u32_e32 v149, 16, v100
	v_lshlrev_b32_e32 v101, 2, v110
	v_add_u32_e32 v150, 64, v101
	v_lshlrev_b32_e32 v148, 4, v110
	v_add_u32_e32 v151, 256, v148
	s_mov_b32 s98, 0x4000
	s_mov_b32 s99, 0x3fff
	v_and_b32_e32 v247, 7, v249
	v_lshlrev_b32_e32 v247, 4, v247
	v_xor_b32_e32 v247, v247, v112
	v_and_b32_e32 v153, 7, v105
	v_or_b32_e32 v248, 0, v106
	v_xor_b32_e32 v248, v248, v153
	v_lshlrev_b32_e32 v248, 4, v248
	v_lshl_add_u32 v248, v105, 7, v248
	v_add_u32_e32 v248, s77, v248
	v_or_b32_e32 v249, 2, v106
	v_xor_b32_e32 v249, v249, v153
	v_lshlrev_b32_e32 v249, 4, v249
	v_lshl_add_u32 v249, v105, 7, v249
	v_add_u32_e32 v249, s77, v249
	v_or_b32_e32 v250, 4, v106
	v_xor_b32_e32 v250, v250, v153
	v_lshlrev_b32_e32 v250, 4, v250
	v_lshl_add_u32 v250, v105, 7, v250
	v_add_u32_e32 v250, s77, v250
	v_or_b32_e32 v251, 6, v106
	v_xor_b32_e32 v251, v251, v153
	v_lshlrev_b32_e32 v251, 4, v251
	v_lshl_add_u32 v251, v105, 7, v251
	v_add_u32_e32 v251, s77, v251
	v_lshlrev_b32_e32 v153, 1, v98
	v_mul_u32_u24_e32 v228, 17, v105
	v_sub_u32_e32 v228, v107, v228
	s_mul_i32 s90, s58, 153
	s_lshr_b32 s90, s90, 1
	s_add_i32 s90, s90, 34876
	v_lshl_add_u32 v228, v228, 2, s90
	v_lshlrev_b32_e32 v229, 2, v105
	v_sub_u32_e32 v229, v107, v229
	s_add_i32 s90, s101, 5104
	v_lshl_add_u32 v229, v229, 2, s90
	v_sub_u32_e32 v230, v107, v105
	s_add_i32 s90, s101, 6364
	v_lshl_add_u32 v230, v230, 2, s90
	v_add_u32_e32 v231, v109, v108
	v_mov_b64_e32 v[232:233], 0
	v_mov_b64_e32 v[0:1], 0
	v_mov_b64_e32 v[2:3], 0
	v_mov_b64_e32 v[4:5], 0
	v_mov_b64_e32 v[6:7], 0
	v_mov_b64_e32 v[8:9], 0
	v_mov_b64_e32 v[10:11], 0
	v_mov_b64_e32 v[12:13], 0
	v_mov_b64_e32 v[14:15], 0
	v_mov_b64_e32 v[16:17], 0
	v_mov_b64_e32 v[18:19], 0
	v_mov_b64_e32 v[20:21], 0
	v_mov_b64_e32 v[22:23], 0
	v_mov_b64_e32 v[24:25], 0
	v_mov_b64_e32 v[26:27], 0
	v_mov_b64_e32 v[28:29], 0
	v_mov_b64_e32 v[30:31], 0
	s_add_i32 s90, s76, -64
	v_add_u32_e32 v80, s90, v235
	v_add_u32_e32 v83, s90, v236
	v_add_u32_e32 v99, s90, v237
	v_add_u32_e32 v253, s90, v238
	v_add_u32_e32 v254, s90, v100
	v_add_u32_e32 v255, s90, v149
	v_med3_i32 v80, v80, 0, s99
	v_med3_i32 v83, v83, 0, s99
	v_med3_i32 v99, v99, 0, s99
	v_med3_i32 v253, v253, 0, s99
	v_med3_i32 v254, v254, 0, s99
	v_med3_i32 v255, v255, 0, s99
	v_mad_u32_u24 v80, v80, s100, v252
	v_mad_u32_u24 v83, v83, s100, v252
	v_mad_u32_u24 v99, v99, s100, v252
	v_mad_u32_u24 v253, v253, s100, v252
	v_mad_u32_u24 v254, v254, s100, v153
	v_mad_u32_u24 v255, v255, s100, v153
	global_load_dwordx4 v[116:119], v80, s[82:83]
	global_load_dwordx4 v[120:123], v83, s[82:83]
	global_load_dwordx4 v[124:127], v99, s[82:83]
	global_load_dwordx4 v[128:131], v253, s[82:83]
	global_load_dwordx4 v[132:135], v254, s[82:83] offset:768
	global_load_dwordx4 v[136:139], v255, s[82:83] offset:768
	global_load_dwordx4 v[140:143], v254, s[82:83] offset:832
	global_load_dwordx4 v[144:147], v255, s[82:83] offset:832
	s_add_i32 s90, s76, -32
	v_add_u32_e32 v80, s90, v235
	v_add_u32_e32 v83, s90, v236
	v_add_u32_e32 v99, s90, v237
	v_add_u32_e32 v253, s90, v238
	v_add_u32_e32 v254, s90, v100
	v_add_u32_e32 v255, s90, v149
	v_med3_i32 v80, v80, 0, s99
	v_med3_i32 v83, v83, 0, s99
	v_med3_i32 v99, v99, 0, s99
	v_med3_i32 v253, v253, 0, s99
	v_med3_i32 v254, v254, 0, s99
	v_med3_i32 v255, v255, 0, s99
	v_mad_u32_u24 v80, v80, s100, v252
	v_mad_u32_u24 v83, v83, s100, v252
	v_mad_u32_u24 v99, v99, s100, v252
	v_mad_u32_u24 v253, v253, s100, v252
	v_mad_u32_u24 v254, v254, s100, v153
	v_mad_u32_u24 v255, v255, s100, v153
	global_load_dwordx4 v[156:159], v80, s[82:83]
	global_load_dwordx4 v[160:163], v83, s[82:83]
	global_load_dwordx4 v[164:167], v99, s[82:83]
	global_load_dwordx4 v[168:171], v253, s[82:83]
	global_load_dwordx4 v[172:175], v254, s[82:83] offset:768
	global_load_dwordx4 v[176:179], v255, s[82:83] offset:768
	global_load_dwordx4 v[180:183], v254, s[82:83] offset:832
	global_load_dwordx4 v[184:187], v255, s[82:83] offset:832
	v_mov_b32_e32 v115, v228
	ds_read2_b32 v[32:33], v115 offset0:0 offset1:1
	ds_read2_b32 v[34:35], v115 offset0:2 offset1:3
	ds_read2_b32 v[36:37], v115 offset0:8 offset1:9
	ds_read2_b32 v[38:39], v115 offset0:10 offset1:11
	ds_read2_b32 v[40:41], v115 offset0:17 offset1:18
	ds_read2_b32 v[42:43], v115 offset0:19 offset1:20
	ds_read2_b32 v[44:45], v115 offset0:25 offset1:26
	ds_read2_b32 v[46:47], v115 offset0:27 offset1:28
	s_waitcnt vmcnt(8)
	ds_write_b128 v247, v[116:119]
	ds_write_b128 v247, v[120:123] offset:1024
	ds_write_b128 v247, v[124:127] offset:2048
	ds_write_b128 v247, v[128:131] offset:3072
	ds_read_b128 v[116:119], v248
	ds_read_b128 v[120:123], v249
	ds_read_b128 v[124:127], v250
	ds_read_b128 v[128:131], v251
	ds_write_b128 v112, v[132:135]
	ds_write_b128 v112, v[136:139] offset:1024
	ds_write_b128 v112, v[140:143] offset:2048
	ds_write_b128 v112, v[144:147] offset:3072
	s_waitcnt lgkmcnt(4)
	v_mfma_f32_32x32x16_bf16 v[32:47], v[116:119], v[48:51], v[32:47]
	v_mfma_f32_32x32x16_bf16 v[32:47], v[120:123], v[52:55], v[32:47]
	v_mfma_f32_32x32x16_bf16 v[32:47], v[124:127], v[56:59], v[32:47]
	v_mfma_f32_32x32x16_bf16 v[32:47], v[128:131], v[60:63], v[32:47]
	ds_read2_b32 v[188:189], v115 offset0:34 offset1:35
	ds_read2_b32 v[190:191], v115 offset0:36 offset1:37
	ds_read2_b32 v[192:193], v115 offset0:42 offset1:43
	ds_read2_b32 v[194:195], v115 offset0:44 offset1:45
	ds_read2_b32 v[196:197], v115 offset0:51 offset1:52
	ds_read2_b32 v[198:199], v115 offset0:53 offset1:54
	ds_read2_b32 v[200:201], v115 offset0:59 offset1:60
	ds_read2_b32 v[202:203], v115 offset0:61 offset1:62
	s_add_i32 s90, s76, 0
	v_add_u32_e32 v80, s90, v235
	v_add_u32_e32 v83, s90, v236
	v_add_u32_e32 v99, s90, v237
	v_add_u32_e32 v253, s90, v238
	v_add_u32_e32 v254, s90, v100
	v_add_u32_e32 v255, s90, v149
	v_med3_i32 v80, v80, 0, s99
	v_med3_i32 v83, v83, 0, s99
	v_med3_i32 v99, v99, 0, s99
	v_med3_i32 v253, v253, 0, s99
	v_med3_i32 v254, v254, 0, s99
	v_med3_i32 v255, v255, 0, s99
	v_mad_u32_u24 v80, v80, s100, v252
	v_mad_u32_u24 v83, v83, s100, v252
	v_mad_u32_u24 v99, v99, s100, v252
	v_mad_u32_u24 v253, v253, s100, v252
	v_mad_u32_u24 v254, v254, s100, v153
	v_mad_u32_u24 v255, v255, s100, v153
	global_load_dwordx4 v[116:119], v80, s[82:83]
	global_load_dwordx4 v[120:123], v83, s[82:83]
	global_load_dwordx4 v[124:127], v99, s[82:83]
	global_load_dwordx4 v[128:131], v253, s[82:83]
	global_load_dwordx4 v[132:135], v254, s[82:83] offset:768
	global_load_dwordx4 v[136:139], v255, s[82:83] offset:768
	global_load_dwordx4 v[140:143], v254, s[82:83] offset:832
	global_load_dwordx4 v[144:147], v255, s[82:83] offset:832
	ds_read_b64_tr_b16 v[72:73], v231
	ds_read_b64_tr_b16 v[74:75], v231 offset:512
	ds_read_b64_tr_b16 v[76:77], v231 offset:2048
	ds_read_b64_tr_b16 v[78:79], v231 offset:2560
	ds_read_b64_tr_b16 v[220:221], v231 offset:1024
	ds_read_b64_tr_b16 v[222:223], v231 offset:1536
	ds_read_b64_tr_b16 v[224:225], v231 offset:3072
	ds_read_b64_tr_b16 v[226:227], v231 offset:3584
	s_waitcnt vmcnt(8)
	ds_write_b128 v247, v[156:159]
	ds_write_b128 v247, v[160:163] offset:1024
	ds_write_b128 v247, v[164:167] offset:2048
	ds_write_b128 v247, v[168:171] offset:3072
	ds_read_b128 v[156:159], v248
	ds_read_b128 v[160:163], v249
	ds_read_b128 v[164:167], v250
	ds_read_b128 v[168:171], v251
	ds_write_b128 v112, v[172:175]
	ds_write_b128 v112, v[176:179] offset:1024
	ds_write_b128 v112, v[180:183] offset:2048
	ds_write_b128 v112, v[184:187] offset:3072
	v_exp_f32_e32 v32, v32
	v_exp_f32_e32 v33, v33
	v_exp_f32_e32 v34, v34
	v_exp_f32_e32 v35, v35
	v_exp_f32_e32 v36, v36
	v_exp_f32_e32 v37, v37
	s_waitcnt lgkmcnt(4)
	v_mfma_f32_32x32x16_bf16 v[188:203], v[156:159], v[48:51], v[188:203]
	v_exp_f32_e32 v38, v38
	v_exp_f32_e32 v39, v39
	v_mfma_f32_32x32x16_bf16 v[188:203], v[160:163], v[52:55], v[188:203]
	v_exp_f32_e32 v40, v40
	v_exp_f32_e32 v41, v41
	v_exp_f32_e32 v42, v42
	v_mfma_f32_32x32x16_bf16 v[188:203], v[164:167], v[56:59], v[188:203]
	v_exp_f32_e32 v43, v43
	v_exp_f32_e32 v44, v44
	v_mfma_f32_32x32x16_bf16 v[188:203], v[168:171], v[60:63], v[188:203]
	v_exp_f32_e32 v45, v45
	v_exp_f32_e32 v46, v46
	v_exp_f32_e32 v47, v47
	s_add_i32 s90, s76, -64
	v_add_u32_e32 v84, s90, v107
	v_add_u32_e32 v85, 0, v84
	v_add_u32_e32 v86, 1, v84
	v_add_u32_e32 v87, 2, v84
	v_add_u32_e32 v88, 3, v84
	v_cmp_gt_u32_e64 s[30:31], s98, v85
	v_cmp_gt_u32_e64 s[36:37], s98, v86
	v_cmp_gt_u32_e64 s[78:79], s98, v87
	v_cmp_gt_u32_e64 s[50:51], s98, v88
	v_cndmask_b32_e64 v32, 0, v32, s[30:31]
	v_add_u32_e32 v85, 8, v84
	v_cmp_gt_u32_e64 s[30:31], s98, v85
	v_cndmask_b32_e64 v33, 0, v33, s[36:37]
	v_add_u32_e32 v86, 9, v84
	v_cmp_gt_u32_e64 s[36:37], s98, v86
	v_cndmask_b32_e64 v34, 0, v34, s[78:79]
	v_add_u32_e32 v87, 10, v84
	v_cmp_gt_u32_e64 s[78:79], s98, v87
	v_cndmask_b32_e64 v35, 0, v35, s[50:51]
	v_add_u32_e32 v88, 11, v84
	v_cmp_gt_u32_e64 s[50:51], s98, v88
	v_cndmask_b32_e64 v36, 0, v36, s[30:31]
	v_add_u32_e32 v85, 16, v84
	v_cmp_gt_u32_e64 s[30:31], s98, v85
	v_cndmask_b32_e64 v37, 0, v37, s[36:37]
	v_add_u32_e32 v86, 17, v84
	v_cmp_gt_u32_e64 s[36:37], s98, v86
	v_cndmask_b32_e64 v38, 0, v38, s[78:79]
	v_add_u32_e32 v87, 18, v84
	v_cmp_gt_u32_e64 s[78:79], s98, v87
	v_cndmask_b32_e64 v39, 0, v39, s[50:51]
	v_add_u32_e32 v88, 19, v84
	v_cmp_gt_u32_e64 s[50:51], s98, v88
	v_cndmask_b32_e64 v40, 0, v40, s[30:31]
	v_add_u32_e32 v85, 24, v84
	v_cmp_gt_u32_e64 s[30:31], s98, v85
	v_cndmask_b32_e64 v41, 0, v41, s[36:37]
	v_add_u32_e32 v86, 25, v84
	v_cmp_gt_u32_e64 s[36:37], s98, v86
	v_cndmask_b32_e64 v42, 0, v42, s[78:79]
	v_add_u32_e32 v87, 26, v84
	v_cmp_gt_u32_e64 s[78:79], s98, v87
	v_cndmask_b32_e64 v43, 0, v43, s[50:51]
	v_add_u32_e32 v88, 27, v84
	v_cmp_gt_u32_e64 s[50:51], s98, v88
	v_nop
	v_cndmask_b32_e64 v44, 0, v44, s[30:31]
	v_cndmask_b32_e64 v45, 0, v45, s[36:37]
	v_cndmask_b32_e64 v46, 0, v46, s[78:79]
	v_cndmask_b32_e64 v47, 0, v47, s[50:51]
	v_cvt_pk_bf16_f32 v64, v32, v33
	v_cvt_pk_bf16_f32 v65, v34, v35
	v_cvt_pk_bf16_f32 v66, v36, v37
	v_cvt_pk_bf16_f32 v67, v38, v39
	v_cvt_pk_bf16_f32 v68, v40, v41
	v_cvt_pk_bf16_f32 v69, v42, v43
	v_cvt_pk_bf16_f32 v70, v44, v45
	v_cvt_pk_bf16_f32 v71, v46, v47
	v_pk_add_f32 v[232:233], v[232:233], v[32:33]
	v_pk_add_f32 v[232:233], v[232:233], v[34:35]
	v_pk_add_f32 v[232:233], v[232:233], v[36:37]
	v_pk_add_f32 v[232:233], v[232:233], v[38:39]
	v_pk_add_f32 v[232:233], v[232:233], v[40:41]
	v_pk_add_f32 v[232:233], v[232:233], v[42:43]
	v_pk_add_f32 v[232:233], v[232:233], v[44:45]
	v_pk_add_f32 v[232:233], v[232:233], v[46:47]
	ds_read2_b32 v[32:33], v115 offset0:68 offset1:69
	ds_read2_b32 v[34:35], v115 offset0:70 offset1:71
	ds_read2_b32 v[36:37], v115 offset0:76 offset1:77
	ds_read2_b32 v[38:39], v115 offset0:78 offset1:79
	ds_read2_b32 v[40:41], v115 offset0:85 offset1:86
	ds_read2_b32 v[42:43], v115 offset0:87 offset1:88
	ds_read2_b32 v[44:45], v115 offset0:93 offset1:94
	ds_read2_b32 v[46:47], v115 offset0:95 offset1:96
	v_mfma_f32_32x32x16_bf16 v[0:15], v[64:67], v[72:75], v[0:15]
	v_mfma_f32_32x32x16_bf16 v[16:31], v[64:67], v[76:79], v[16:31]
	v_mfma_f32_32x32x16_bf16 v[0:15], v[68:71], v[220:223], v[0:15]
	v_mfma_f32_32x32x16_bf16 v[16:31], v[68:71], v[224:227], v[16:31]
	s_add_i32 s90, s76, 32
	v_add_u32_e32 v80, s90, v235
	v_add_u32_e32 v83, s90, v236
	v_add_u32_e32 v99, s90, v237
	v_add_u32_e32 v253, s90, v238
	v_add_u32_e32 v254, s90, v100
	v_add_u32_e32 v255, s90, v149
	v_med3_i32 v80, v80, 0, s99
	v_med3_i32 v83, v83, 0, s99
	v_med3_i32 v99, v99, 0, s99
	v_med3_i32 v253, v253, 0, s99
	v_med3_i32 v254, v254, 0, s99
	v_med3_i32 v255, v255, 0, s99
	v_mad_u32_u24 v80, v80, s100, v252
	v_mad_u32_u24 v83, v83, s100, v252
	v_mad_u32_u24 v99, v99, s100, v252
	v_mad_u32_u24 v253, v253, s100, v252
	v_mad_u32_u24 v254, v254, s100, v153
	v_mad_u32_u24 v255, v255, s100, v153
	global_load_dwordx4 v[156:159], v80, s[82:83]
	global_load_dwordx4 v[160:163], v83, s[82:83]
	global_load_dwordx4 v[164:167], v99, s[82:83]
	global_load_dwordx4 v[168:171], v253, s[82:83]
	global_load_dwordx4 v[172:175], v254, s[82:83] offset:768
	global_load_dwordx4 v[176:179], v255, s[82:83] offset:768
	global_load_dwordx4 v[180:183], v254, s[82:83] offset:832
	global_load_dwordx4 v[184:187], v255, s[82:83] offset:832
	ds_read_b64_tr_b16 v[72:73], v231
	ds_read_b64_tr_b16 v[74:75], v231 offset:512
	ds_read_b64_tr_b16 v[76:77], v231 offset:2048
	ds_read_b64_tr_b16 v[78:79], v231 offset:2560
	ds_read_b64_tr_b16 v[220:221], v231 offset:1024
	ds_read_b64_tr_b16 v[222:223], v231 offset:1536
	ds_read_b64_tr_b16 v[224:225], v231 offset:3072
	ds_read_b64_tr_b16 v[226:227], v231 offset:3584
	s_waitcnt vmcnt(8)
	ds_write_b128 v247, v[116:119]
	ds_write_b128 v247, v[120:123] offset:1024
	ds_write_b128 v247, v[124:127] offset:2048
	ds_write_b128 v247, v[128:131] offset:3072
	ds_read_b128 v[116:119], v248
	ds_read_b128 v[120:123], v249
	ds_read_b128 v[124:127], v250
	ds_read_b128 v[128:131], v251
	ds_write_b128 v112, v[132:135]
	ds_write_b128 v112, v[136:139] offset:1024
	ds_write_b128 v112, v[140:143] offset:2048
	ds_write_b128 v112, v[144:147] offset:3072
	v_exp_f32_e32 v188, v188
	v_exp_f32_e32 v189, v189
	v_exp_f32_e32 v190, v190
	v_exp_f32_e32 v191, v191
	v_exp_f32_e32 v192, v192
	v_exp_f32_e32 v193, v193
	s_waitcnt lgkmcnt(4)
	v_mfma_f32_32x32x16_bf16 v[32:47], v[116:119], v[48:51], v[32:47]
	v_exp_f32_e32 v194, v194
	v_exp_f32_e32 v195, v195
	v_mfma_f32_32x32x16_bf16 v[32:47], v[120:123], v[52:55], v[32:47]
	v_exp_f32_e32 v196, v196
	v_exp_f32_e32 v197, v197
	v_exp_f32_e32 v198, v198
	v_mfma_f32_32x32x16_bf16 v[32:47], v[124:127], v[56:59], v[32:47]
	v_exp_f32_e32 v199, v199
	v_exp_f32_e32 v200, v200
	v_mfma_f32_32x32x16_bf16 v[32:47], v[128:131], v[60:63], v[32:47]
	v_exp_f32_e32 v201, v201
	v_exp_f32_e32 v202, v202
	v_exp_f32_e32 v203, v203
	s_add_i32 s90, s76, -32
	v_add_u32_e32 v84, s90, v107
	v_add_u32_e32 v85, 0, v84
	v_add_u32_e32 v86, 1, v84
	v_add_u32_e32 v87, 2, v84
	v_add_u32_e32 v88, 3, v84
	v_cmp_gt_u32_e64 s[30:31], s98, v85
	v_cmp_gt_u32_e64 s[36:37], s98, v86
	v_cmp_gt_u32_e64 s[78:79], s98, v87
	v_cmp_gt_u32_e64 s[50:51], s98, v88
	v_cndmask_b32_e64 v188, 0, v188, s[30:31]
	v_add_u32_e32 v85, 8, v84
	v_cmp_gt_u32_e64 s[30:31], s98, v85
	v_cndmask_b32_e64 v189, 0, v189, s[36:37]
	v_add_u32_e32 v86, 9, v84
	v_cmp_gt_u32_e64 s[36:37], s98, v86
	v_cndmask_b32_e64 v190, 0, v190, s[78:79]
	v_add_u32_e32 v87, 10, v84
	v_cmp_gt_u32_e64 s[78:79], s98, v87
	v_cndmask_b32_e64 v191, 0, v191, s[50:51]
	v_add_u32_e32 v88, 11, v84
	v_cmp_gt_u32_e64 s[50:51], s98, v88
	v_cndmask_b32_e64 v192, 0, v192, s[30:31]
	v_add_u32_e32 v85, 16, v84
	v_cmp_gt_u32_e64 s[30:31], s98, v85
	v_cndmask_b32_e64 v193, 0, v193, s[36:37]
	v_add_u32_e32 v86, 17, v84
	v_cmp_gt_u32_e64 s[36:37], s98, v86
	v_cndmask_b32_e64 v194, 0, v194, s[78:79]
	v_add_u32_e32 v87, 18, v84
	v_cmp_gt_u32_e64 s[78:79], s98, v87
	v_cndmask_b32_e64 v195, 0, v195, s[50:51]
	v_add_u32_e32 v88, 19, v84
	v_cmp_gt_u32_e64 s[50:51], s98, v88
	v_cndmask_b32_e64 v196, 0, v196, s[30:31]
	v_add_u32_e32 v85, 24, v84
	v_cmp_gt_u32_e64 s[30:31], s98, v85
	v_cndmask_b32_e64 v197, 0, v197, s[36:37]
	v_add_u32_e32 v86, 25, v84
	v_cmp_gt_u32_e64 s[36:37], s98, v86
	v_cndmask_b32_e64 v198, 0, v198, s[78:79]
	v_add_u32_e32 v87, 26, v84
	v_cmp_gt_u32_e64 s[78:79], s98, v87
	v_cndmask_b32_e64 v199, 0, v199, s[50:51]
	v_add_u32_e32 v88, 27, v84
	v_cmp_gt_u32_e64 s[50:51], s98, v88
	v_nop
	v_cndmask_b32_e64 v200, 0, v200, s[30:31]
	v_cndmask_b32_e64 v201, 0, v201, s[36:37]
	v_cndmask_b32_e64 v202, 0, v202, s[78:79]
	v_cndmask_b32_e64 v203, 0, v203, s[50:51]
	v_cvt_pk_bf16_f32 v64, v188, v189
	v_cvt_pk_bf16_f32 v65, v190, v191
	v_cvt_pk_bf16_f32 v66, v192, v193
	v_cvt_pk_bf16_f32 v67, v194, v195
	v_cvt_pk_bf16_f32 v68, v196, v197
	v_cvt_pk_bf16_f32 v69, v198, v199
	v_cvt_pk_bf16_f32 v70, v200, v201
	v_cvt_pk_bf16_f32 v71, v202, v203
	v_pk_add_f32 v[232:233], v[232:233], v[188:189]
	v_pk_add_f32 v[232:233], v[232:233], v[190:191]
	v_pk_add_f32 v[232:233], v[232:233], v[192:193]
	v_pk_add_f32 v[232:233], v[232:233], v[194:195]
	v_pk_add_f32 v[232:233], v[232:233], v[196:197]
	v_pk_add_f32 v[232:233], v[232:233], v[198:199]
	v_pk_add_f32 v[232:233], v[232:233], v[200:201]
	v_pk_add_f32 v[232:233], v[232:233], v[202:203]
	ds_read2_b32 v[188:189], v115 offset0:102 offset1:103
	ds_read2_b32 v[190:191], v115 offset0:104 offset1:105
	ds_read2_b32 v[192:193], v115 offset0:110 offset1:111
	ds_read2_b32 v[194:195], v115 offset0:112 offset1:113
	ds_read2_b32 v[196:197], v115 offset0:119 offset1:120
	ds_read2_b32 v[198:199], v115 offset0:121 offset1:122
	ds_read2_b32 v[200:201], v115 offset0:127 offset1:128
	ds_read2_b32 v[202:203], v115 offset0:129 offset1:130
	v_mfma_f32_32x32x16_bf16 v[0:15], v[64:67], v[72:75], v[0:15]
	v_mfma_f32_32x32x16_bf16 v[16:31], v[64:67], v[76:79], v[16:31]
	v_mfma_f32_32x32x16_bf16 v[0:15], v[68:71], v[220:223], v[0:15]
	v_mfma_f32_32x32x16_bf16 v[16:31], v[68:71], v[224:227], v[16:31]
	s_add_i32 s90, s76, 64
	v_add_u32_e32 v80, s90, v235
	v_add_u32_e32 v83, s90, v236
	v_add_u32_e32 v99, s90, v237
	v_add_u32_e32 v253, s90, v238
	v_add_u32_e32 v254, s90, v100
	v_add_u32_e32 v255, s90, v149
	v_med3_i32 v80, v80, 0, s99
	v_med3_i32 v83, v83, 0, s99
	v_med3_i32 v99, v99, 0, s99
	v_med3_i32 v253, v253, 0, s99
	v_med3_i32 v254, v254, 0, s99
	v_med3_i32 v255, v255, 0, s99
	v_mad_u32_u24 v80, v80, s100, v252
	v_mad_u32_u24 v83, v83, s100, v252
	v_mad_u32_u24 v99, v99, s100, v252
	v_mad_u32_u24 v253, v253, s100, v252
	v_mad_u32_u24 v254, v254, s100, v153
	v_mad_u32_u24 v255, v255, s100, v153
	global_load_dwordx4 v[116:119], v80, s[82:83]
	global_load_dwordx4 v[120:123], v83, s[82:83]
	global_load_dwordx4 v[124:127], v99, s[82:83]
	global_load_dwordx4 v[128:131], v253, s[82:83]
	global_load_dwordx4 v[132:135], v254, s[82:83] offset:768
	global_load_dwordx4 v[136:139], v255, s[82:83] offset:768
	global_load_dwordx4 v[140:143], v254, s[82:83] offset:832
	global_load_dwordx4 v[144:147], v255, s[82:83] offset:832
	ds_read_b64_tr_b16 v[72:73], v231
	ds_read_b64_tr_b16 v[74:75], v231 offset:512
	ds_read_b64_tr_b16 v[76:77], v231 offset:2048
	ds_read_b64_tr_b16 v[78:79], v231 offset:2560
	ds_read_b64_tr_b16 v[220:221], v231 offset:1024
	ds_read_b64_tr_b16 v[222:223], v231 offset:1536
	ds_read_b64_tr_b16 v[224:225], v231 offset:3072
	ds_read_b64_tr_b16 v[226:227], v231 offset:3584
	s_waitcnt vmcnt(8)
	ds_write_b128 v247, v[156:159]
	ds_write_b128 v247, v[160:163] offset:1024
	ds_write_b128 v247, v[164:167] offset:2048
	ds_write_b128 v247, v[168:171] offset:3072
	ds_read_b128 v[156:159], v248
	ds_read_b128 v[160:163], v249
	ds_read_b128 v[164:167], v250
	ds_read_b128 v[168:171], v251
	ds_write_b128 v112, v[172:175]
	ds_write_b128 v112, v[176:179] offset:1024
	ds_write_b128 v112, v[180:183] offset:2048
	ds_write_b128 v112, v[184:187] offset:3072
	v_exp_f32_e32 v32, v32
	v_exp_f32_e32 v33, v33
	v_exp_f32_e32 v34, v34
	v_exp_f32_e32 v35, v35
	v_exp_f32_e32 v36, v36
	v_exp_f32_e32 v37, v37
	s_waitcnt lgkmcnt(4)
	v_mfma_f32_32x32x16_bf16 v[188:203], v[156:159], v[48:51], v[188:203]
	v_exp_f32_e32 v38, v38
	v_exp_f32_e32 v39, v39
	v_mfma_f32_32x32x16_bf16 v[188:203], v[160:163], v[52:55], v[188:203]
	v_exp_f32_e32 v40, v40
	v_exp_f32_e32 v41, v41
	v_exp_f32_e32 v42, v42
	v_mfma_f32_32x32x16_bf16 v[188:203], v[164:167], v[56:59], v[188:203]
	v_exp_f32_e32 v43, v43
	v_exp_f32_e32 v44, v44
	v_mfma_f32_32x32x16_bf16 v[188:203], v[168:171], v[60:63], v[188:203]
	v_exp_f32_e32 v45, v45
	v_exp_f32_e32 v46, v46
	v_exp_f32_e32 v47, v47
	s_add_i32 s90, s76, 0
	v_add_u32_e32 v84, s90, v107
	v_add_u32_e32 v85, 0, v84
	v_add_u32_e32 v86, 1, v84
	v_add_u32_e32 v87, 2, v84
	v_add_u32_e32 v88, 3, v84
	v_cmp_gt_u32_e64 s[30:31], s98, v85
	v_cmp_gt_u32_e64 s[36:37], s98, v86
	v_cmp_gt_u32_e64 s[78:79], s98, v87
	v_cmp_gt_u32_e64 s[50:51], s98, v88
	v_cndmask_b32_e64 v32, 0, v32, s[30:31]
	v_add_u32_e32 v85, 8, v84
	v_cmp_gt_u32_e64 s[30:31], s98, v85
	v_cndmask_b32_e64 v33, 0, v33, s[36:37]
	v_add_u32_e32 v86, 9, v84
	v_cmp_gt_u32_e64 s[36:37], s98, v86
	v_cndmask_b32_e64 v34, 0, v34, s[78:79]
	v_add_u32_e32 v87, 10, v84
	v_cmp_gt_u32_e64 s[78:79], s98, v87
	v_cndmask_b32_e64 v35, 0, v35, s[50:51]
	v_add_u32_e32 v88, 11, v84
	v_cmp_gt_u32_e64 s[50:51], s98, v88
	v_cndmask_b32_e64 v36, 0, v36, s[30:31]
	v_add_u32_e32 v85, 16, v84
	v_cmp_gt_u32_e64 s[30:31], s98, v85
	v_cndmask_b32_e64 v37, 0, v37, s[36:37]
	v_add_u32_e32 v86, 17, v84
	v_cmp_gt_u32_e64 s[36:37], s98, v86
	v_cndmask_b32_e64 v38, 0, v38, s[78:79]
	v_add_u32_e32 v87, 18, v84
	v_cmp_gt_u32_e64 s[78:79], s98, v87
	v_cndmask_b32_e64 v39, 0, v39, s[50:51]
	v_add_u32_e32 v88, 19, v84
	v_cmp_gt_u32_e64 s[50:51], s98, v88
	v_cndmask_b32_e64 v40, 0, v40, s[30:31]
	v_add_u32_e32 v85, 24, v84
	v_cmp_gt_u32_e64 s[30:31], s98, v85
	v_cndmask_b32_e64 v41, 0, v41, s[36:37]
	v_add_u32_e32 v86, 25, v84
	v_cmp_gt_u32_e64 s[36:37], s98, v86
	v_cndmask_b32_e64 v42, 0, v42, s[78:79]
	v_add_u32_e32 v87, 26, v84
	v_cmp_gt_u32_e64 s[78:79], s98, v87
	v_cndmask_b32_e64 v43, 0, v43, s[50:51]
	v_add_u32_e32 v88, 27, v84
	v_cmp_gt_u32_e64 s[50:51], s98, v88
	v_nop
	v_cndmask_b32_e64 v44, 0, v44, s[30:31]
	v_cndmask_b32_e64 v45, 0, v45, s[36:37]
	v_cndmask_b32_e64 v46, 0, v46, s[78:79]
	v_cndmask_b32_e64 v47, 0, v47, s[50:51]
	v_cvt_pk_bf16_f32 v64, v32, v33
	v_cvt_pk_bf16_f32 v65, v34, v35
	v_cvt_pk_bf16_f32 v66, v36, v37
	v_cvt_pk_bf16_f32 v67, v38, v39
	v_cvt_pk_bf16_f32 v68, v40, v41
	v_cvt_pk_bf16_f32 v69, v42, v43
	v_cvt_pk_bf16_f32 v70, v44, v45
	v_cvt_pk_bf16_f32 v71, v46, v47
	v_pk_add_f32 v[232:233], v[232:233], v[32:33]
	v_pk_add_f32 v[232:233], v[232:233], v[34:35]
	v_pk_add_f32 v[232:233], v[232:233], v[36:37]
	v_pk_add_f32 v[232:233], v[232:233], v[38:39]
	v_pk_add_f32 v[232:233], v[232:233], v[40:41]
	v_pk_add_f32 v[232:233], v[232:233], v[42:43]
	v_pk_add_f32 v[232:233], v[232:233], v[44:45]
	v_pk_add_f32 v[232:233], v[232:233], v[46:47]
	ds_read2_b32 v[32:33], v115 offset0:136 offset1:137
	ds_read2_b32 v[34:35], v115 offset0:138 offset1:139
	ds_read2_b32 v[36:37], v115 offset0:144 offset1:145
	ds_read2_b32 v[38:39], v115 offset0:146 offset1:147
	ds_read2_b32 v[40:41], v115 offset0:153 offset1:154
	ds_read2_b32 v[42:43], v115 offset0:155 offset1:156
	ds_read2_b32 v[44:45], v115 offset0:161 offset1:162
	ds_read2_b32 v[46:47], v115 offset0:163 offset1:164
	v_mfma_f32_32x32x16_bf16 v[0:15], v[64:67], v[72:75], v[0:15]
	v_mfma_f32_32x32x16_bf16 v[16:31], v[64:67], v[76:79], v[16:31]
	v_mfma_f32_32x32x16_bf16 v[0:15], v[68:71], v[220:223], v[0:15]
	v_mfma_f32_32x32x16_bf16 v[16:31], v[68:71], v[224:227], v[16:31]
	s_add_i32 s90, s76, 96
	v_add_u32_e32 v80, s90, v235
	v_add_u32_e32 v83, s90, v236
	v_add_u32_e32 v99, s90, v237
	v_add_u32_e32 v253, s90, v238
	v_add_u32_e32 v254, s90, v100
	v_add_u32_e32 v255, s90, v149
	v_med3_i32 v80, v80, 0, s99
	v_med3_i32 v83, v83, 0, s99
	v_med3_i32 v99, v99, 0, s99
	v_med3_i32 v253, v253, 0, s99
	v_med3_i32 v254, v254, 0, s99
	v_med3_i32 v255, v255, 0, s99
	v_mad_u32_u24 v80, v80, s100, v252
	v_mad_u32_u24 v83, v83, s100, v252
	v_mad_u32_u24 v99, v99, s100, v252
	v_mad_u32_u24 v253, v253, s100, v252
	v_mad_u32_u24 v254, v254, s100, v153
	v_mad_u32_u24 v255, v255, s100, v153
	global_load_dwordx4 v[156:159], v80, s[82:83]
	global_load_dwordx4 v[160:163], v83, s[82:83]
	global_load_dwordx4 v[164:167], v99, s[82:83]
	global_load_dwordx4 v[168:171], v253, s[82:83]
	global_load_dwordx4 v[172:175], v254, s[82:83] offset:768
	global_load_dwordx4 v[176:179], v255, s[82:83] offset:768
	global_load_dwordx4 v[180:183], v254, s[82:83] offset:832
	global_load_dwordx4 v[184:187], v255, s[82:83] offset:832
	ds_read_b64_tr_b16 v[72:73], v231
	ds_read_b64_tr_b16 v[74:75], v231 offset:512
	ds_read_b64_tr_b16 v[76:77], v231 offset:2048
	ds_read_b64_tr_b16 v[78:79], v231 offset:2560
	ds_read_b64_tr_b16 v[220:221], v231 offset:1024
	ds_read_b64_tr_b16 v[222:223], v231 offset:1536
	ds_read_b64_tr_b16 v[224:225], v231 offset:3072
	ds_read_b64_tr_b16 v[226:227], v231 offset:3584
	s_waitcnt vmcnt(8)
	ds_write_b128 v247, v[116:119]
	ds_write_b128 v247, v[120:123] offset:1024
	ds_write_b128 v247, v[124:127] offset:2048
	ds_write_b128 v247, v[128:131] offset:3072
	ds_read_b128 v[116:119], v248
	ds_read_b128 v[120:123], v249
	ds_read_b128 v[124:127], v250
	ds_read_b128 v[128:131], v251
	ds_write_b128 v112, v[132:135]
	ds_write_b128 v112, v[136:139] offset:1024
	ds_write_b128 v112, v[140:143] offset:2048
	ds_write_b128 v112, v[144:147] offset:3072
	v_exp_f32_e32 v188, v188
	v_exp_f32_e32 v189, v189
	v_exp_f32_e32 v190, v190
	v_exp_f32_e32 v191, v191
	v_exp_f32_e32 v192, v192
	v_exp_f32_e32 v193, v193
	s_waitcnt lgkmcnt(4)
	v_mfma_f32_32x32x16_bf16 v[32:47], v[116:119], v[48:51], v[32:47]
	v_exp_f32_e32 v194, v194
	v_exp_f32_e32 v195, v195
	v_mfma_f32_32x32x16_bf16 v[32:47], v[120:123], v[52:55], v[32:47]
	v_exp_f32_e32 v196, v196
	v_exp_f32_e32 v197, v197
	v_exp_f32_e32 v198, v198
	v_mfma_f32_32x32x16_bf16 v[32:47], v[124:127], v[56:59], v[32:47]
	v_exp_f32_e32 v199, v199
	v_exp_f32_e32 v200, v200
	v_mfma_f32_32x32x16_bf16 v[32:47], v[128:131], v[60:63], v[32:47]
	v_exp_f32_e32 v201, v201
	v_exp_f32_e32 v202, v202
	v_exp_f32_e32 v203, v203
	s_add_i32 s90, s76, 32
	v_add_u32_e32 v84, s90, v107
	v_add_u32_e32 v85, 0, v84
	v_add_u32_e32 v86, 1, v84
	v_add_u32_e32 v87, 2, v84
	v_add_u32_e32 v88, 3, v84
	v_cmp_gt_u32_e64 s[30:31], s98, v85
	v_cmp_gt_u32_e64 s[36:37], s98, v86
	v_cmp_gt_u32_e64 s[78:79], s98, v87
	v_cmp_gt_u32_e64 s[50:51], s98, v88
	v_cndmask_b32_e64 v188, 0, v188, s[30:31]
	v_add_u32_e32 v85, 8, v84
	v_cmp_gt_u32_e64 s[30:31], s98, v85
	v_cndmask_b32_e64 v189, 0, v189, s[36:37]
	v_add_u32_e32 v86, 9, v84
	v_cmp_gt_u32_e64 s[36:37], s98, v86
	v_cndmask_b32_e64 v190, 0, v190, s[78:79]
	v_add_u32_e32 v87, 10, v84
	v_cmp_gt_u32_e64 s[78:79], s98, v87
	v_cndmask_b32_e64 v191, 0, v191, s[50:51]
	v_add_u32_e32 v88, 11, v84
	v_cmp_gt_u32_e64 s[50:51], s98, v88
	v_cndmask_b32_e64 v192, 0, v192, s[30:31]
	v_add_u32_e32 v85, 16, v84
	v_cmp_gt_u32_e64 s[30:31], s98, v85
	v_cndmask_b32_e64 v193, 0, v193, s[36:37]
	v_add_u32_e32 v86, 17, v84
	v_cmp_gt_u32_e64 s[36:37], s98, v86
	v_cndmask_b32_e64 v194, 0, v194, s[78:79]
	v_add_u32_e32 v87, 18, v84
	v_cmp_gt_u32_e64 s[78:79], s98, v87
	v_cndmask_b32_e64 v195, 0, v195, s[50:51]
	v_add_u32_e32 v88, 19, v84
	v_cmp_gt_u32_e64 s[50:51], s98, v88
	v_cndmask_b32_e64 v196, 0, v196, s[30:31]
	v_add_u32_e32 v85, 24, v84
	v_cmp_gt_u32_e64 s[30:31], s98, v85
	v_cndmask_b32_e64 v197, 0, v197, s[36:37]
	v_add_u32_e32 v86, 25, v84
	v_cmp_gt_u32_e64 s[36:37], s98, v86
	v_cndmask_b32_e64 v198, 0, v198, s[78:79]
	v_add_u32_e32 v87, 26, v84
	v_cmp_gt_u32_e64 s[78:79], s98, v87
	v_cndmask_b32_e64 v199, 0, v199, s[50:51]
	v_add_u32_e32 v88, 27, v84
	v_cmp_gt_u32_e64 s[50:51], s98, v88
	v_nop
	v_cndmask_b32_e64 v200, 0, v200, s[30:31]
	v_cndmask_b32_e64 v201, 0, v201, s[36:37]
	v_cndmask_b32_e64 v202, 0, v202, s[78:79]
	v_cndmask_b32_e64 v203, 0, v203, s[50:51]
	v_cvt_pk_bf16_f32 v64, v188, v189
	v_cvt_pk_bf16_f32 v65, v190, v191
	v_cvt_pk_bf16_f32 v66, v192, v193
	v_cvt_pk_bf16_f32 v67, v194, v195
	v_cvt_pk_bf16_f32 v68, v196, v197
	v_cvt_pk_bf16_f32 v69, v198, v199
	v_cvt_pk_bf16_f32 v70, v200, v201
	v_cvt_pk_bf16_f32 v71, v202, v203
	v_pk_add_f32 v[232:233], v[232:233], v[188:189]
	v_pk_add_f32 v[232:233], v[232:233], v[190:191]
	v_pk_add_f32 v[232:233], v[232:233], v[192:193]
	v_pk_add_f32 v[232:233], v[232:233], v[194:195]
	v_pk_add_f32 v[232:233], v[232:233], v[196:197]
	v_pk_add_f32 v[232:233], v[232:233], v[198:199]
	v_pk_add_f32 v[232:233], v[232:233], v[200:201]
	v_pk_add_f32 v[232:233], v[232:233], v[202:203]
	ds_read2_b32 v[188:189], v115 offset0:170 offset1:171
	ds_read2_b32 v[190:191], v115 offset0:172 offset1:173
	ds_read2_b32 v[192:193], v115 offset0:178 offset1:179
	ds_read2_b32 v[194:195], v115 offset0:180 offset1:181
	ds_read2_b32 v[196:197], v115 offset0:187 offset1:188
	ds_read2_b32 v[198:199], v115 offset0:189 offset1:190
	ds_read2_b32 v[200:201], v115 offset0:195 offset1:196
	ds_read2_b32 v[202:203], v115 offset0:197 offset1:198
	v_mfma_f32_32x32x16_bf16 v[0:15], v[64:67], v[72:75], v[0:15]
	v_mfma_f32_32x32x16_bf16 v[16:31], v[64:67], v[76:79], v[16:31]
	v_mfma_f32_32x32x16_bf16 v[0:15], v[68:71], v[220:223], v[0:15]
	v_mfma_f32_32x32x16_bf16 v[16:31], v[68:71], v[224:227], v[16:31]
	s_add_i32 s90, s76, 128
	v_add_u32_e32 v80, s90, v235
	v_add_u32_e32 v83, s90, v236
	v_add_u32_e32 v99, s90, v237
	v_add_u32_e32 v253, s90, v238
	v_add_u32_e32 v254, s90, v100
	v_add_u32_e32 v255, s90, v149
	v_med3_i32 v80, v80, 0, s99
	v_med3_i32 v83, v83, 0, s99
	v_med3_i32 v99, v99, 0, s99
	v_med3_i32 v253, v253, 0, s99
	v_med3_i32 v254, v254, 0, s99
	v_med3_i32 v255, v255, 0, s99
	v_mad_u32_u24 v80, v80, s100, v252
	v_mad_u32_u24 v83, v83, s100, v252
	v_mad_u32_u24 v99, v99, s100, v252
	v_mad_u32_u24 v253, v253, s100, v252
	v_mad_u32_u24 v254, v254, s100, v153
	v_mad_u32_u24 v255, v255, s100, v153
	global_load_dwordx4 v[116:119], v80, s[82:83]
	global_load_dwordx4 v[120:123], v83, s[82:83]
	global_load_dwordx4 v[124:127], v99, s[82:83]
	global_load_dwordx4 v[128:131], v253, s[82:83]
	global_load_dwordx4 v[132:135], v254, s[82:83] offset:768
	global_load_dwordx4 v[136:139], v255, s[82:83] offset:768
	global_load_dwordx4 v[140:143], v254, s[82:83] offset:832
	global_load_dwordx4 v[144:147], v255, s[82:83] offset:832
	ds_read_b64_tr_b16 v[72:73], v231
	ds_read_b64_tr_b16 v[74:75], v231 offset:512
	ds_read_b64_tr_b16 v[76:77], v231 offset:2048
	ds_read_b64_tr_b16 v[78:79], v231 offset:2560
	ds_read_b64_tr_b16 v[220:221], v231 offset:1024
	ds_read_b64_tr_b16 v[222:223], v231 offset:1536
	ds_read_b64_tr_b16 v[224:225], v231 offset:3072
	ds_read_b64_tr_b16 v[226:227], v231 offset:3584
	s_waitcnt vmcnt(8)
	ds_write_b128 v247, v[156:159]
	ds_write_b128 v247, v[160:163] offset:1024
	ds_write_b128 v247, v[164:167] offset:2048
	ds_write_b128 v247, v[168:171] offset:3072
	ds_read_b128 v[156:159], v248
	ds_read_b128 v[160:163], v249
	ds_read_b128 v[164:167], v250
	ds_read_b128 v[168:171], v251
	ds_write_b128 v112, v[172:175]
	ds_write_b128 v112, v[176:179] offset:1024
	ds_write_b128 v112, v[180:183] offset:2048
	ds_write_b128 v112, v[184:187] offset:3072
	v_exp_f32_e32 v32, v32
	v_exp_f32_e32 v33, v33
	v_exp_f32_e32 v34, v34
	v_exp_f32_e32 v35, v35
	v_exp_f32_e32 v36, v36
	v_exp_f32_e32 v37, v37
	s_waitcnt lgkmcnt(4)
	v_mfma_f32_32x32x16_bf16 v[188:203], v[156:159], v[48:51], v[188:203]
	v_exp_f32_e32 v38, v38
	v_exp_f32_e32 v39, v39
	v_mfma_f32_32x32x16_bf16 v[188:203], v[160:163], v[52:55], v[188:203]
	v_exp_f32_e32 v40, v40
	v_exp_f32_e32 v41, v41
	v_exp_f32_e32 v42, v42
	v_mfma_f32_32x32x16_bf16 v[188:203], v[164:167], v[56:59], v[188:203]
	v_exp_f32_e32 v43, v43
	v_exp_f32_e32 v44, v44
	v_mfma_f32_32x32x16_bf16 v[188:203], v[168:171], v[60:63], v[188:203]
	v_exp_f32_e32 v45, v45
	v_exp_f32_e32 v46, v46
	v_exp_f32_e32 v47, v47
	s_add_i32 s90, s76, 64
	v_add_u32_e32 v84, s90, v107
	v_add_u32_e32 v85, 0, v84
	v_add_u32_e32 v86, 1, v84
	v_add_u32_e32 v87, 2, v84
	v_add_u32_e32 v88, 3, v84
	v_cmp_gt_u32_e64 s[30:31], s98, v85
	v_cmp_gt_u32_e64 s[36:37], s98, v86
	v_cmp_gt_u32_e64 s[78:79], s98, v87
	v_cmp_gt_u32_e64 s[50:51], s98, v88
	v_cndmask_b32_e64 v32, 0, v32, s[30:31]
	v_add_u32_e32 v85, 8, v84
	v_cmp_gt_u32_e64 s[30:31], s98, v85
	v_cndmask_b32_e64 v33, 0, v33, s[36:37]
	v_add_u32_e32 v86, 9, v84
	v_cmp_gt_u32_e64 s[36:37], s98, v86
	v_cndmask_b32_e64 v34, 0, v34, s[78:79]
	v_add_u32_e32 v87, 10, v84
	v_cmp_gt_u32_e64 s[78:79], s98, v87
	v_cndmask_b32_e64 v35, 0, v35, s[50:51]
	v_add_u32_e32 v88, 11, v84
	v_cmp_gt_u32_e64 s[50:51], s98, v88
	v_cndmask_b32_e64 v36, 0, v36, s[30:31]
	v_add_u32_e32 v85, 16, v84
	v_cmp_gt_u32_e64 s[30:31], s98, v85
	v_cndmask_b32_e64 v37, 0, v37, s[36:37]
	v_add_u32_e32 v86, 17, v84
	v_cmp_gt_u32_e64 s[36:37], s98, v86
	v_cndmask_b32_e64 v38, 0, v38, s[78:79]
	v_add_u32_e32 v87, 18, v84
	v_cmp_gt_u32_e64 s[78:79], s98, v87
	v_cndmask_b32_e64 v39, 0, v39, s[50:51]
	v_add_u32_e32 v88, 19, v84
	v_cmp_gt_u32_e64 s[50:51], s98, v88
	v_cndmask_b32_e64 v40, 0, v40, s[30:31]
	v_add_u32_e32 v85, 24, v84
	v_cmp_gt_u32_e64 s[30:31], s98, v85
	v_cndmask_b32_e64 v41, 0, v41, s[36:37]
	v_add_u32_e32 v86, 25, v84
	v_cmp_gt_u32_e64 s[36:37], s98, v86
	v_cndmask_b32_e64 v42, 0, v42, s[78:79]
	v_add_u32_e32 v87, 26, v84
	v_cmp_gt_u32_e64 s[78:79], s98, v87
	v_cndmask_b32_e64 v43, 0, v43, s[50:51]
	v_add_u32_e32 v88, 27, v84
	v_cmp_gt_u32_e64 s[50:51], s98, v88
	v_nop
	v_cndmask_b32_e64 v44, 0, v44, s[30:31]
	v_cndmask_b32_e64 v45, 0, v45, s[36:37]
	v_cndmask_b32_e64 v46, 0, v46, s[78:79]
	v_cndmask_b32_e64 v47, 0, v47, s[50:51]
	v_cvt_pk_bf16_f32 v64, v32, v33
	v_cvt_pk_bf16_f32 v65, v34, v35
	v_cvt_pk_bf16_f32 v66, v36, v37
	v_cvt_pk_bf16_f32 v67, v38, v39
	v_cvt_pk_bf16_f32 v68, v40, v41
	v_cvt_pk_bf16_f32 v69, v42, v43
	v_cvt_pk_bf16_f32 v70, v44, v45
	v_cvt_pk_bf16_f32 v71, v46, v47
	v_pk_add_f32 v[232:233], v[232:233], v[32:33]
	v_pk_add_f32 v[232:233], v[232:233], v[34:35]
	v_pk_add_f32 v[232:233], v[232:233], v[36:37]
	v_pk_add_f32 v[232:233], v[232:233], v[38:39]
	v_pk_add_f32 v[232:233], v[232:233], v[40:41]
	v_pk_add_f32 v[232:233], v[232:233], v[42:43]
	v_pk_add_f32 v[232:233], v[232:233], v[44:45]
	v_pk_add_f32 v[232:233], v[232:233], v[46:47]
	ds_read2_b32 v[32:33], v115 offset0:204 offset1:205
	ds_read2_b32 v[34:35], v115 offset0:206 offset1:207
	ds_read2_b32 v[36:37], v115 offset0:212 offset1:213
	ds_read2_b32 v[38:39], v115 offset0:214 offset1:215
	ds_read2_b32 v[40:41], v115 offset0:221 offset1:222
	ds_read2_b32 v[42:43], v115 offset0:223 offset1:224
	ds_read2_b32 v[44:45], v115 offset0:229 offset1:230
	ds_read2_b32 v[46:47], v115 offset0:231 offset1:232
	v_mfma_f32_32x32x16_bf16 v[0:15], v[64:67], v[72:75], v[0:15]
	v_mfma_f32_32x32x16_bf16 v[16:31], v[64:67], v[76:79], v[16:31]
	v_mfma_f32_32x32x16_bf16 v[0:15], v[68:71], v[220:223], v[0:15]
	v_mfma_f32_32x32x16_bf16 v[16:31], v[68:71], v[224:227], v[16:31]
	s_add_i32 s90, s76, 160
	v_add_u32_e32 v80, s90, v235
	v_add_u32_e32 v83, s90, v236
	v_add_u32_e32 v99, s90, v237
	v_add_u32_e32 v253, s90, v238
	v_add_u32_e32 v254, s90, v100
	v_add_u32_e32 v255, s90, v149
	v_med3_i32 v80, v80, 0, s99
	v_med3_i32 v83, v83, 0, s99
	v_med3_i32 v99, v99, 0, s99
	v_med3_i32 v253, v253, 0, s99
	v_med3_i32 v254, v254, 0, s99
	v_med3_i32 v255, v255, 0, s99
	v_mad_u32_u24 v80, v80, s100, v252
	v_mad_u32_u24 v83, v83, s100, v252
	v_mad_u32_u24 v99, v99, s100, v252
	v_mad_u32_u24 v253, v253, s100, v252
	v_mad_u32_u24 v254, v254, s100, v153
	v_mad_u32_u24 v255, v255, s100, v153
	global_load_dwordx4 v[156:159], v80, s[82:83]
	global_load_dwordx4 v[160:163], v83, s[82:83]
	global_load_dwordx4 v[164:167], v99, s[82:83]
	global_load_dwordx4 v[168:171], v253, s[82:83]
	global_load_dwordx4 v[172:175], v254, s[82:83] offset:768
	global_load_dwordx4 v[176:179], v255, s[82:83] offset:768
	global_load_dwordx4 v[180:183], v254, s[82:83] offset:832
	global_load_dwordx4 v[184:187], v255, s[82:83] offset:832
	ds_read_b64_tr_b16 v[72:73], v231
	ds_read_b64_tr_b16 v[74:75], v231 offset:512
	ds_read_b64_tr_b16 v[76:77], v231 offset:2048
	ds_read_b64_tr_b16 v[78:79], v231 offset:2560
	ds_read_b64_tr_b16 v[220:221], v231 offset:1024
	ds_read_b64_tr_b16 v[222:223], v231 offset:1536
	ds_read_b64_tr_b16 v[224:225], v231 offset:3072
	ds_read_b64_tr_b16 v[226:227], v231 offset:3584
	s_waitcnt vmcnt(8)
	ds_write_b128 v247, v[116:119]
	ds_write_b128 v247, v[120:123] offset:1024
	ds_write_b128 v247, v[124:127] offset:2048
	ds_write_b128 v247, v[128:131] offset:3072
	ds_read_b128 v[116:119], v248
	ds_read_b128 v[120:123], v249
	ds_read_b128 v[124:127], v250
	ds_read_b128 v[128:131], v251
	ds_write_b128 v112, v[132:135]
	ds_write_b128 v112, v[136:139] offset:1024
	ds_write_b128 v112, v[140:143] offset:2048
	ds_write_b128 v112, v[144:147] offset:3072
	v_exp_f32_e32 v188, v188
	v_exp_f32_e32 v189, v189
	v_exp_f32_e32 v190, v190
	v_exp_f32_e32 v191, v191
	v_exp_f32_e32 v192, v192
	v_exp_f32_e32 v193, v193
	s_waitcnt lgkmcnt(4)
	v_mfma_f32_32x32x16_bf16 v[32:47], v[116:119], v[48:51], v[32:47]
	v_exp_f32_e32 v194, v194
	v_exp_f32_e32 v195, v195
	v_mfma_f32_32x32x16_bf16 v[32:47], v[120:123], v[52:55], v[32:47]
	v_exp_f32_e32 v196, v196
	v_exp_f32_e32 v197, v197
	v_exp_f32_e32 v198, v198
	v_mfma_f32_32x32x16_bf16 v[32:47], v[124:127], v[56:59], v[32:47]
	v_exp_f32_e32 v199, v199
	v_exp_f32_e32 v200, v200
	v_mfma_f32_32x32x16_bf16 v[32:47], v[128:131], v[60:63], v[32:47]
	v_exp_f32_e32 v201, v201
	v_exp_f32_e32 v202, v202
	v_exp_f32_e32 v203, v203
	s_add_i32 s90, s76, 96
	v_add_u32_e32 v84, s90, v107
	v_add_u32_e32 v85, 0, v84
	v_add_u32_e32 v86, 1, v84
	v_add_u32_e32 v87, 2, v84
	v_add_u32_e32 v88, 3, v84
	v_cmp_gt_u32_e64 s[30:31], s98, v85
	v_cmp_gt_u32_e64 s[36:37], s98, v86
	v_cmp_gt_u32_e64 s[78:79], s98, v87
	v_cmp_gt_u32_e64 s[50:51], s98, v88
	v_cndmask_b32_e64 v188, 0, v188, s[30:31]
	v_add_u32_e32 v85, 8, v84
	v_cmp_gt_u32_e64 s[30:31], s98, v85
	v_cndmask_b32_e64 v189, 0, v189, s[36:37]
	v_add_u32_e32 v86, 9, v84
	v_cmp_gt_u32_e64 s[36:37], s98, v86
	v_cndmask_b32_e64 v190, 0, v190, s[78:79]
	v_add_u32_e32 v87, 10, v84
	v_cmp_gt_u32_e64 s[78:79], s98, v87
	v_cndmask_b32_e64 v191, 0, v191, s[50:51]
	v_add_u32_e32 v88, 11, v84
	v_cmp_gt_u32_e64 s[50:51], s98, v88
	v_cndmask_b32_e64 v192, 0, v192, s[30:31]
	v_add_u32_e32 v85, 16, v84
	v_cmp_gt_u32_e64 s[30:31], s98, v85
	v_cndmask_b32_e64 v193, 0, v193, s[36:37]
	v_add_u32_e32 v86, 17, v84
	v_cmp_gt_u32_e64 s[36:37], s98, v86
	v_cndmask_b32_e64 v194, 0, v194, s[78:79]
	v_add_u32_e32 v87, 18, v84
	v_cmp_gt_u32_e64 s[78:79], s98, v87
	v_cndmask_b32_e64 v195, 0, v195, s[50:51]
	v_add_u32_e32 v88, 19, v84
	v_cmp_gt_u32_e64 s[50:51], s98, v88
	v_cndmask_b32_e64 v196, 0, v196, s[30:31]
	v_add_u32_e32 v85, 24, v84
	v_cmp_gt_u32_e64 s[30:31], s98, v85
	v_cndmask_b32_e64 v197, 0, v197, s[36:37]
	v_add_u32_e32 v86, 25, v84
	v_cmp_gt_u32_e64 s[36:37], s98, v86
	v_cndmask_b32_e64 v198, 0, v198, s[78:79]
	v_add_u32_e32 v87, 26, v84
	v_cmp_gt_u32_e64 s[78:79], s98, v87
	v_cndmask_b32_e64 v199, 0, v199, s[50:51]
	v_add_u32_e32 v88, 27, v84
	v_cmp_gt_u32_e64 s[50:51], s98, v88
	v_nop
	v_cndmask_b32_e64 v200, 0, v200, s[30:31]
	v_cndmask_b32_e64 v201, 0, v201, s[36:37]
	v_cndmask_b32_e64 v202, 0, v202, s[78:79]
	v_cndmask_b32_e64 v203, 0, v203, s[50:51]
	v_cvt_pk_bf16_f32 v64, v188, v189
	v_cvt_pk_bf16_f32 v65, v190, v191
	v_cvt_pk_bf16_f32 v66, v192, v193
	v_cvt_pk_bf16_f32 v67, v194, v195
	v_cvt_pk_bf16_f32 v68, v196, v197
	v_cvt_pk_bf16_f32 v69, v198, v199
	v_cvt_pk_bf16_f32 v70, v200, v201
	v_cvt_pk_bf16_f32 v71, v202, v203
	v_pk_add_f32 v[232:233], v[232:233], v[188:189]
	v_pk_add_f32 v[232:233], v[232:233], v[190:191]
	v_pk_add_f32 v[232:233], v[232:233], v[192:193]
	v_pk_add_f32 v[232:233], v[232:233], v[194:195]
	v_pk_add_f32 v[232:233], v[232:233], v[196:197]
	v_pk_add_f32 v[232:233], v[232:233], v[198:199]
	v_pk_add_f32 v[232:233], v[232:233], v[200:201]
	v_pk_add_f32 v[232:233], v[232:233], v[202:203]
	v_add_u32_e32 v115, 952, v115
	ds_read2_b32 v[188:189], v115 offset0:0 offset1:1
	ds_read2_b32 v[190:191], v115 offset0:2 offset1:3
	ds_read2_b32 v[192:193], v115 offset0:8 offset1:9
	ds_read2_b32 v[194:195], v115 offset0:10 offset1:11
	ds_read2_b32 v[196:197], v115 offset0:17 offset1:18
	ds_read2_b32 v[198:199], v115 offset0:19 offset1:20
	ds_read2_b32 v[200:201], v115 offset0:25 offset1:26
	ds_read2_b32 v[202:203], v115 offset0:27 offset1:28
	v_mfma_f32_32x32x16_bf16 v[0:15], v[64:67], v[72:75], v[0:15]
	v_mfma_f32_32x32x16_bf16 v[16:31], v[64:67], v[76:79], v[16:31]
	v_mfma_f32_32x32x16_bf16 v[0:15], v[68:71], v[220:223], v[0:15]
	v_mfma_f32_32x32x16_bf16 v[16:31], v[68:71], v[224:227], v[16:31]
	s_add_i32 s90, s76, 192
	v_add_u32_e32 v80, s90, v235
	v_add_u32_e32 v83, s90, v236
	v_add_u32_e32 v99, s90, v237
	v_add_u32_e32 v253, s90, v238
	v_add_u32_e32 v254, s90, v100
	v_add_u32_e32 v255, s90, v149
	v_med3_i32 v80, v80, 0, s99
	v_med3_i32 v83, v83, 0, s99
	v_med3_i32 v99, v99, 0, s99
	v_med3_i32 v253, v253, 0, s99
	v_med3_i32 v254, v254, 0, s99
	v_med3_i32 v255, v255, 0, s99
	v_mad_u32_u24 v80, v80, s100, v252
	v_mad_u32_u24 v83, v83, s100, v252
	v_mad_u32_u24 v99, v99, s100, v252
	v_mad_u32_u24 v253, v253, s100, v252
	v_mad_u32_u24 v254, v254, s100, v153
	v_mad_u32_u24 v255, v255, s100, v153
	global_load_dwordx4 v[116:119], v80, s[82:83]
	global_load_dwordx4 v[120:123], v83, s[82:83]
	global_load_dwordx4 v[124:127], v99, s[82:83]
	global_load_dwordx4 v[128:131], v253, s[82:83]
	global_load_dwordx4 v[132:135], v254, s[82:83] offset:768
	global_load_dwordx4 v[136:139], v255, s[82:83] offset:768
	global_load_dwordx4 v[140:143], v254, s[82:83] offset:832
	global_load_dwordx4 v[144:147], v255, s[82:83] offset:832
	ds_read_b64_tr_b16 v[72:73], v231
	ds_read_b64_tr_b16 v[74:75], v231 offset:512
	ds_read_b64_tr_b16 v[76:77], v231 offset:2048
	ds_read_b64_tr_b16 v[78:79], v231 offset:2560
	ds_read_b64_tr_b16 v[220:221], v231 offset:1024
	ds_read_b64_tr_b16 v[222:223], v231 offset:1536
	ds_read_b64_tr_b16 v[224:225], v231 offset:3072
	ds_read_b64_tr_b16 v[226:227], v231 offset:3584
	s_waitcnt vmcnt(8)
	ds_write_b128 v247, v[156:159]
	ds_write_b128 v247, v[160:163] offset:1024
	ds_write_b128 v247, v[164:167] offset:2048
	ds_write_b128 v247, v[168:171] offset:3072
	ds_read_b128 v[156:159], v248
	ds_read_b128 v[160:163], v249
	ds_read_b128 v[164:167], v250
	ds_read_b128 v[168:171], v251
	ds_write_b128 v112, v[172:175]
	ds_write_b128 v112, v[176:179] offset:1024
	ds_write_b128 v112, v[180:183] offset:2048
	ds_write_b128 v112, v[184:187] offset:3072
	v_exp_f32_e32 v32, v32
	v_exp_f32_e32 v33, v33
	v_exp_f32_e32 v34, v34
	v_exp_f32_e32 v35, v35
	v_exp_f32_e32 v36, v36
	v_exp_f32_e32 v37, v37
	s_waitcnt lgkmcnt(4)
	v_mfma_f32_32x32x16_bf16 v[188:203], v[156:159], v[48:51], v[188:203]
	v_exp_f32_e32 v38, v38
	v_exp_f32_e32 v39, v39
	v_mfma_f32_32x32x16_bf16 v[188:203], v[160:163], v[52:55], v[188:203]
	v_exp_f32_e32 v40, v40
	v_exp_f32_e32 v41, v41
	v_exp_f32_e32 v42, v42
	v_mfma_f32_32x32x16_bf16 v[188:203], v[164:167], v[56:59], v[188:203]
	v_exp_f32_e32 v43, v43
	v_exp_f32_e32 v44, v44
	v_mfma_f32_32x32x16_bf16 v[188:203], v[168:171], v[60:63], v[188:203]
	v_exp_f32_e32 v45, v45
	v_exp_f32_e32 v46, v46
	v_exp_f32_e32 v47, v47
	s_add_i32 s90, s76, 128
	v_add_u32_e32 v84, s90, v107
	v_add_u32_e32 v85, 0, v84
	v_add_u32_e32 v86, 1, v84
	v_add_u32_e32 v87, 2, v84
	v_add_u32_e32 v88, 3, v84
	v_cmp_gt_u32_e64 s[30:31], s98, v85
	v_cmp_gt_u32_e64 s[36:37], s98, v86
	v_cmp_gt_u32_e64 s[78:79], s98, v87
	v_cmp_gt_u32_e64 s[50:51], s98, v88
	v_cndmask_b32_e64 v32, 0, v32, s[30:31]
	v_add_u32_e32 v85, 8, v84
	v_cmp_gt_u32_e64 s[30:31], s98, v85
	v_cndmask_b32_e64 v33, 0, v33, s[36:37]
	v_add_u32_e32 v86, 9, v84
	v_cmp_gt_u32_e64 s[36:37], s98, v86
	v_cndmask_b32_e64 v34, 0, v34, s[78:79]
	v_add_u32_e32 v87, 10, v84
	v_cmp_gt_u32_e64 s[78:79], s98, v87
	v_cndmask_b32_e64 v35, 0, v35, s[50:51]
	v_add_u32_e32 v88, 11, v84
	v_cmp_gt_u32_e64 s[50:51], s98, v88
	v_cndmask_b32_e64 v36, 0, v36, s[30:31]
	v_add_u32_e32 v85, 16, v84
	v_cmp_gt_u32_e64 s[30:31], s98, v85
	v_cndmask_b32_e64 v37, 0, v37, s[36:37]
	v_add_u32_e32 v86, 17, v84
	v_cmp_gt_u32_e64 s[36:37], s98, v86
	v_cndmask_b32_e64 v38, 0, v38, s[78:79]
	v_add_u32_e32 v87, 18, v84
	v_cmp_gt_u32_e64 s[78:79], s98, v87
	v_cndmask_b32_e64 v39, 0, v39, s[50:51]
	v_add_u32_e32 v88, 19, v84
	v_cmp_gt_u32_e64 s[50:51], s98, v88
	v_cndmask_b32_e64 v40, 0, v40, s[30:31]
	v_add_u32_e32 v85, 24, v84
	v_cmp_gt_u32_e64 s[30:31], s98, v85
	v_cndmask_b32_e64 v41, 0, v41, s[36:37]
	v_add_u32_e32 v86, 25, v84
	v_cmp_gt_u32_e64 s[36:37], s98, v86
	v_cndmask_b32_e64 v42, 0, v42, s[78:79]
	v_add_u32_e32 v87, 26, v84
	v_cmp_gt_u32_e64 s[78:79], s98, v87
	v_cndmask_b32_e64 v43, 0, v43, s[50:51]
	v_add_u32_e32 v88, 27, v84
	v_cmp_gt_u32_e64 s[50:51], s98, v88
	v_nop
	v_cndmask_b32_e64 v44, 0, v44, s[30:31]
	v_cndmask_b32_e64 v45, 0, v45, s[36:37]
	v_cndmask_b32_e64 v46, 0, v46, s[78:79]
	v_cndmask_b32_e64 v47, 0, v47, s[50:51]
	v_cvt_pk_bf16_f32 v64, v32, v33
	v_cvt_pk_bf16_f32 v65, v34, v35
	v_cvt_pk_bf16_f32 v66, v36, v37
	v_cvt_pk_bf16_f32 v67, v38, v39
	v_cvt_pk_bf16_f32 v68, v40, v41
	v_cvt_pk_bf16_f32 v69, v42, v43
	v_cvt_pk_bf16_f32 v70, v44, v45
	v_cvt_pk_bf16_f32 v71, v46, v47
	v_pk_add_f32 v[232:233], v[232:233], v[32:33]
	v_pk_add_f32 v[232:233], v[232:233], v[34:35]
	v_pk_add_f32 v[232:233], v[232:233], v[36:37]
	v_pk_add_f32 v[232:233], v[232:233], v[38:39]
	v_pk_add_f32 v[232:233], v[232:233], v[40:41]
	v_pk_add_f32 v[232:233], v[232:233], v[42:43]
	v_pk_add_f32 v[232:233], v[232:233], v[44:45]
	v_pk_add_f32 v[232:233], v[232:233], v[46:47]
	ds_read2_b32 v[32:33], v115 offset0:34 offset1:35
	ds_read2_b32 v[34:35], v115 offset0:36 offset1:37
	ds_read2_b32 v[36:37], v115 offset0:42 offset1:43
	ds_read2_b32 v[38:39], v115 offset0:44 offset1:45
	ds_read2_b32 v[40:41], v115 offset0:51 offset1:52
	ds_read2_b32 v[42:43], v115 offset0:53 offset1:54
	ds_read2_b32 v[44:45], v115 offset0:59 offset1:60
	ds_read2_b32 v[46:47], v115 offset0:61 offset1:62
	v_mfma_f32_32x32x16_bf16 v[0:15], v[64:67], v[72:75], v[0:15]
	v_mfma_f32_32x32x16_bf16 v[16:31], v[64:67], v[76:79], v[16:31]
	v_mfma_f32_32x32x16_bf16 v[0:15], v[68:71], v[220:223], v[0:15]
	v_mfma_f32_32x32x16_bf16 v[16:31], v[68:71], v[224:227], v[16:31]
	s_add_i32 s90, s76, 224
	v_add_u32_e32 v80, s90, v235
	v_add_u32_e32 v83, s90, v236
	v_add_u32_e32 v99, s90, v237
	v_add_u32_e32 v253, s90, v238
	v_add_u32_e32 v254, s90, v100
	v_add_u32_e32 v255, s90, v149
	v_med3_i32 v80, v80, 0, s99
	v_med3_i32 v83, v83, 0, s99
	v_med3_i32 v99, v99, 0, s99
	v_med3_i32 v253, v253, 0, s99
	v_med3_i32 v254, v254, 0, s99
	v_med3_i32 v255, v255, 0, s99
	v_mad_u32_u24 v80, v80, s100, v252
	v_mad_u32_u24 v83, v83, s100, v252
	v_mad_u32_u24 v99, v99, s100, v252
	v_mad_u32_u24 v253, v253, s100, v252
	v_mad_u32_u24 v254, v254, s100, v153
	v_mad_u32_u24 v255, v255, s100, v153
	global_load_dwordx4 v[156:159], v80, s[82:83]
	global_load_dwordx4 v[160:163], v83, s[82:83]
	global_load_dwordx4 v[164:167], v99, s[82:83]
	global_load_dwordx4 v[168:171], v253, s[82:83]
	global_load_dwordx4 v[172:175], v254, s[82:83] offset:768
	global_load_dwordx4 v[176:179], v255, s[82:83] offset:768
	global_load_dwordx4 v[180:183], v254, s[82:83] offset:832
	global_load_dwordx4 v[184:187], v255, s[82:83] offset:832
	ds_read_b64_tr_b16 v[72:73], v231
	ds_read_b64_tr_b16 v[74:75], v231 offset:512
	ds_read_b64_tr_b16 v[76:77], v231 offset:2048
	ds_read_b64_tr_b16 v[78:79], v231 offset:2560
	ds_read_b64_tr_b16 v[220:221], v231 offset:1024
	ds_read_b64_tr_b16 v[222:223], v231 offset:1536
	ds_read_b64_tr_b16 v[224:225], v231 offset:3072
	ds_read_b64_tr_b16 v[226:227], v231 offset:3584
	s_waitcnt vmcnt(8)
	ds_write_b128 v247, v[116:119]
	ds_write_b128 v247, v[120:123] offset:1024
	ds_write_b128 v247, v[124:127] offset:2048
	ds_write_b128 v247, v[128:131] offset:3072
	ds_read_b128 v[116:119], v248
	ds_read_b128 v[120:123], v249
	ds_read_b128 v[124:127], v250
	ds_read_b128 v[128:131], v251
	ds_write_b128 v112, v[132:135]
	ds_write_b128 v112, v[136:139] offset:1024
	ds_write_b128 v112, v[140:143] offset:2048
	ds_write_b128 v112, v[144:147] offset:3072
	v_exp_f32_e32 v188, v188
	v_exp_f32_e32 v189, v189
	v_exp_f32_e32 v190, v190
	v_exp_f32_e32 v191, v191
	v_exp_f32_e32 v192, v192
	v_exp_f32_e32 v193, v193
	s_waitcnt lgkmcnt(4)
	v_mfma_f32_32x32x16_bf16 v[32:47], v[116:119], v[48:51], v[32:47]
	v_exp_f32_e32 v194, v194
	v_exp_f32_e32 v195, v195
	v_mfma_f32_32x32x16_bf16 v[32:47], v[120:123], v[52:55], v[32:47]
	v_exp_f32_e32 v196, v196
	v_exp_f32_e32 v197, v197
	v_exp_f32_e32 v198, v198
	v_mfma_f32_32x32x16_bf16 v[32:47], v[124:127], v[56:59], v[32:47]
	v_exp_f32_e32 v199, v199
	v_exp_f32_e32 v200, v200
	v_mfma_f32_32x32x16_bf16 v[32:47], v[128:131], v[60:63], v[32:47]
	v_exp_f32_e32 v201, v201
	v_exp_f32_e32 v202, v202
	v_exp_f32_e32 v203, v203
	s_add_i32 s90, s76, 160
	v_add_u32_e32 v84, s90, v107
	v_add_u32_e32 v85, 0, v84
	v_add_u32_e32 v86, 1, v84
	v_add_u32_e32 v87, 2, v84
	v_add_u32_e32 v88, 3, v84
	v_cmp_gt_u32_e64 s[30:31], s98, v85
	v_cmp_gt_u32_e64 s[36:37], s98, v86
	v_cmp_gt_u32_e64 s[78:79], s98, v87
	v_cmp_gt_u32_e64 s[50:51], s98, v88
	v_cndmask_b32_e64 v188, 0, v188, s[30:31]
	v_add_u32_e32 v85, 8, v84
	v_cmp_gt_u32_e64 s[30:31], s98, v85
	v_cndmask_b32_e64 v189, 0, v189, s[36:37]
	v_add_u32_e32 v86, 9, v84
	v_cmp_gt_u32_e64 s[36:37], s98, v86
	v_cndmask_b32_e64 v190, 0, v190, s[78:79]
	v_add_u32_e32 v87, 10, v84
	v_cmp_gt_u32_e64 s[78:79], s98, v87
	v_cndmask_b32_e64 v191, 0, v191, s[50:51]
	v_add_u32_e32 v88, 11, v84
	v_cmp_gt_u32_e64 s[50:51], s98, v88
	v_cndmask_b32_e64 v192, 0, v192, s[30:31]
	v_add_u32_e32 v85, 16, v84
	v_cmp_gt_u32_e64 s[30:31], s98, v85
	v_cndmask_b32_e64 v193, 0, v193, s[36:37]
	v_add_u32_e32 v86, 17, v84
	v_cmp_gt_u32_e64 s[36:37], s98, v86
	v_cndmask_b32_e64 v194, 0, v194, s[78:79]
	v_add_u32_e32 v87, 18, v84
	v_cmp_gt_u32_e64 s[78:79], s98, v87
	v_cndmask_b32_e64 v195, 0, v195, s[50:51]
	v_add_u32_e32 v88, 19, v84
	v_cmp_gt_u32_e64 s[50:51], s98, v88
	v_cndmask_b32_e64 v196, 0, v196, s[30:31]
	v_add_u32_e32 v85, 24, v84
	v_cmp_gt_u32_e64 s[30:31], s98, v85
	v_cndmask_b32_e64 v197, 0, v197, s[36:37]
	v_add_u32_e32 v86, 25, v84
	v_cmp_gt_u32_e64 s[36:37], s98, v86
	v_cndmask_b32_e64 v198, 0, v198, s[78:79]
	v_add_u32_e32 v87, 26, v84
	v_cmp_gt_u32_e64 s[78:79], s98, v87
	v_cndmask_b32_e64 v199, 0, v199, s[50:51]
	v_add_u32_e32 v88, 27, v84
	v_cmp_gt_u32_e64 s[50:51], s98, v88
	v_nop
	v_cndmask_b32_e64 v200, 0, v200, s[30:31]
	v_cndmask_b32_e64 v201, 0, v201, s[36:37]
	v_cndmask_b32_e64 v202, 0, v202, s[78:79]
	v_cndmask_b32_e64 v203, 0, v203, s[50:51]
	v_cvt_pk_bf16_f32 v64, v188, v189
	v_cvt_pk_bf16_f32 v65, v190, v191
	v_cvt_pk_bf16_f32 v66, v192, v193
	v_cvt_pk_bf16_f32 v67, v194, v195
	v_cvt_pk_bf16_f32 v68, v196, v197
	v_cvt_pk_bf16_f32 v69, v198, v199
	v_cvt_pk_bf16_f32 v70, v200, v201
	v_cvt_pk_bf16_f32 v71, v202, v203
	v_pk_add_f32 v[232:233], v[232:233], v[188:189]
	v_pk_add_f32 v[232:233], v[232:233], v[190:191]
	v_pk_add_f32 v[232:233], v[232:233], v[192:193]
	v_pk_add_f32 v[232:233], v[232:233], v[194:195]
	v_pk_add_f32 v[232:233], v[232:233], v[196:197]
	v_pk_add_f32 v[232:233], v[232:233], v[198:199]
	v_pk_add_f32 v[232:233], v[232:233], v[200:201]
	v_pk_add_f32 v[232:233], v[232:233], v[202:203]
	ds_read2_b32 v[188:189], v115 offset0:68 offset1:69
	ds_read2_b32 v[190:191], v115 offset0:70 offset1:71
	ds_read2_b32 v[192:193], v115 offset0:76 offset1:77
	ds_read2_b32 v[194:195], v115 offset0:78 offset1:79
	ds_read2_b32 v[196:197], v115 offset0:85 offset1:86
	ds_read2_b32 v[198:199], v115 offset0:87 offset1:88
	ds_read2_b32 v[200:201], v115 offset0:93 offset1:94
	ds_read2_b32 v[202:203], v115 offset0:95 offset1:96
	v_mfma_f32_32x32x16_bf16 v[0:15], v[64:67], v[72:75], v[0:15]
	v_mfma_f32_32x32x16_bf16 v[16:31], v[64:67], v[76:79], v[16:31]
	v_mfma_f32_32x32x16_bf16 v[0:15], v[68:71], v[220:223], v[0:15]
	v_mfma_f32_32x32x16_bf16 v[16:31], v[68:71], v[224:227], v[16:31]
	s_add_i32 s90, s76, 256
	v_add_u32_e32 v80, s90, v235
	v_add_u32_e32 v83, s90, v236
	v_add_u32_e32 v99, s90, v237
	v_add_u32_e32 v253, s90, v238
	v_add_u32_e32 v254, s90, v100
	v_add_u32_e32 v255, s90, v149
	v_med3_i32 v80, v80, 0, s99
	v_med3_i32 v83, v83, 0, s99
	v_med3_i32 v99, v99, 0, s99
	v_med3_i32 v253, v253, 0, s99
	v_med3_i32 v254, v254, 0, s99
	v_med3_i32 v255, v255, 0, s99
	v_mad_u32_u24 v80, v80, s100, v252
	v_mad_u32_u24 v83, v83, s100, v252
	v_mad_u32_u24 v99, v99, s100, v252
	v_mad_u32_u24 v253, v253, s100, v252
	v_mad_u32_u24 v254, v254, s100, v153
	v_mad_u32_u24 v255, v255, s100, v153
	global_load_dwordx4 v[116:119], v80, s[82:83]
	global_load_dwordx4 v[120:123], v83, s[82:83]
	global_load_dwordx4 v[124:127], v99, s[82:83]
	global_load_dwordx4 v[128:131], v253, s[82:83]
	global_load_dwordx4 v[132:135], v254, s[82:83] offset:768
	global_load_dwordx4 v[136:139], v255, s[82:83] offset:768
	global_load_dwordx4 v[140:143], v254, s[82:83] offset:832
	global_load_dwordx4 v[144:147], v255, s[82:83] offset:832
	ds_read_b64_tr_b16 v[72:73], v231
	ds_read_b64_tr_b16 v[74:75], v231 offset:512
	ds_read_b64_tr_b16 v[76:77], v231 offset:2048
	ds_read_b64_tr_b16 v[78:79], v231 offset:2560
	ds_read_b64_tr_b16 v[220:221], v231 offset:1024
	ds_read_b64_tr_b16 v[222:223], v231 offset:1536
	ds_read_b64_tr_b16 v[224:225], v231 offset:3072
	ds_read_b64_tr_b16 v[226:227], v231 offset:3584
	s_waitcnt vmcnt(8)
	ds_write_b128 v247, v[156:159]
	ds_write_b128 v247, v[160:163] offset:1024
	ds_write_b128 v247, v[164:167] offset:2048
	ds_write_b128 v247, v[168:171] offset:3072
	ds_read_b128 v[156:159], v248
	ds_read_b128 v[160:163], v249
	ds_read_b128 v[164:167], v250
	ds_read_b128 v[168:171], v251
	ds_write_b128 v112, v[172:175]
	ds_write_b128 v112, v[176:179] offset:1024
	ds_write_b128 v112, v[180:183] offset:2048
	ds_write_b128 v112, v[184:187] offset:3072
	v_exp_f32_e32 v32, v32
	v_exp_f32_e32 v33, v33
	v_exp_f32_e32 v34, v34
	v_exp_f32_e32 v35, v35
	v_exp_f32_e32 v36, v36
	v_exp_f32_e32 v37, v37
	s_waitcnt lgkmcnt(4)
	v_mfma_f32_32x32x16_bf16 v[188:203], v[156:159], v[48:51], v[188:203]
	v_exp_f32_e32 v38, v38
	v_exp_f32_e32 v39, v39
	v_mfma_f32_32x32x16_bf16 v[188:203], v[160:163], v[52:55], v[188:203]
	v_exp_f32_e32 v40, v40
	v_exp_f32_e32 v41, v41
	v_exp_f32_e32 v42, v42
	v_mfma_f32_32x32x16_bf16 v[188:203], v[164:167], v[56:59], v[188:203]
	v_exp_f32_e32 v43, v43
	v_exp_f32_e32 v44, v44
	v_mfma_f32_32x32x16_bf16 v[188:203], v[168:171], v[60:63], v[188:203]
	v_exp_f32_e32 v45, v45
	v_exp_f32_e32 v46, v46
	v_exp_f32_e32 v47, v47
	s_add_i32 s90, s76, 192
	v_add_u32_e32 v84, s90, v107
	v_add_u32_e32 v85, 0, v84
	v_add_u32_e32 v86, 1, v84
	v_add_u32_e32 v87, 2, v84
	v_add_u32_e32 v88, 3, v84
	v_cmp_gt_u32_e64 s[30:31], s98, v85
	v_cmp_gt_u32_e64 s[36:37], s98, v86
	v_cmp_gt_u32_e64 s[78:79], s98, v87
	v_cmp_gt_u32_e64 s[50:51], s98, v88
	v_cndmask_b32_e64 v32, 0, v32, s[30:31]
	v_add_u32_e32 v85, 8, v84
	v_cmp_gt_u32_e64 s[30:31], s98, v85
	v_cndmask_b32_e64 v33, 0, v33, s[36:37]
	v_add_u32_e32 v86, 9, v84
	v_cmp_gt_u32_e64 s[36:37], s98, v86
	v_cndmask_b32_e64 v34, 0, v34, s[78:79]
	v_add_u32_e32 v87, 10, v84
	v_cmp_gt_u32_e64 s[78:79], s98, v87
	v_cndmask_b32_e64 v35, 0, v35, s[50:51]
	v_add_u32_e32 v88, 11, v84
	v_cmp_gt_u32_e64 s[50:51], s98, v88
	v_cndmask_b32_e64 v36, 0, v36, s[30:31]
	v_add_u32_e32 v85, 16, v84
	v_cmp_gt_u32_e64 s[30:31], s98, v85
	v_cndmask_b32_e64 v37, 0, v37, s[36:37]
	v_add_u32_e32 v86, 17, v84
	v_cmp_gt_u32_e64 s[36:37], s98, v86
	v_cndmask_b32_e64 v38, 0, v38, s[78:79]
	v_add_u32_e32 v87, 18, v84
	v_cmp_gt_u32_e64 s[78:79], s98, v87
	v_cndmask_b32_e64 v39, 0, v39, s[50:51]
	v_add_u32_e32 v88, 19, v84
	v_cmp_gt_u32_e64 s[50:51], s98, v88
	v_cndmask_b32_e64 v40, 0, v40, s[30:31]
	v_add_u32_e32 v85, 24, v84
	v_cmp_gt_u32_e64 s[30:31], s98, v85
	v_cndmask_b32_e64 v41, 0, v41, s[36:37]
	v_add_u32_e32 v86, 25, v84
	v_cmp_gt_u32_e64 s[36:37], s98, v86
	v_cndmask_b32_e64 v42, 0, v42, s[78:79]
	v_add_u32_e32 v87, 26, v84
	v_cmp_gt_u32_e64 s[78:79], s98, v87
	v_cndmask_b32_e64 v43, 0, v43, s[50:51]
	v_add_u32_e32 v88, 27, v84
	v_cmp_gt_u32_e64 s[50:51], s98, v88
	v_nop
	v_cndmask_b32_e64 v44, 0, v44, s[30:31]
	v_cndmask_b32_e64 v45, 0, v45, s[36:37]
	v_cndmask_b32_e64 v46, 0, v46, s[78:79]
	v_cndmask_b32_e64 v47, 0, v47, s[50:51]
	v_cvt_pk_bf16_f32 v64, v32, v33
	v_cvt_pk_bf16_f32 v65, v34, v35
	v_cvt_pk_bf16_f32 v66, v36, v37
	v_cvt_pk_bf16_f32 v67, v38, v39
	v_cvt_pk_bf16_f32 v68, v40, v41
	v_cvt_pk_bf16_f32 v69, v42, v43
	v_cvt_pk_bf16_f32 v70, v44, v45
	v_cvt_pk_bf16_f32 v71, v46, v47
	v_pk_add_f32 v[232:233], v[232:233], v[32:33]
	v_pk_add_f32 v[232:233], v[232:233], v[34:35]
	v_pk_add_f32 v[232:233], v[232:233], v[36:37]
	v_pk_add_f32 v[232:233], v[232:233], v[38:39]
	v_pk_add_f32 v[232:233], v[232:233], v[40:41]
	v_pk_add_f32 v[232:233], v[232:233], v[42:43]
	v_pk_add_f32 v[232:233], v[232:233], v[44:45]
	v_pk_add_f32 v[232:233], v[232:233], v[46:47]
	ds_read2_b32 v[32:33], v115 offset0:102 offset1:103
	ds_read2_b32 v[34:35], v115 offset0:104 offset1:105
	ds_read2_b32 v[36:37], v115 offset0:110 offset1:111
	ds_read2_b32 v[38:39], v115 offset0:112 offset1:113
	ds_read2_b32 v[40:41], v115 offset0:119 offset1:120
	ds_read2_b32 v[42:43], v115 offset0:121 offset1:122
	ds_read2_b32 v[44:45], v115 offset0:127 offset1:128
	ds_read2_b32 v[46:47], v115 offset0:129 offset1:130
	v_mfma_f32_32x32x16_bf16 v[0:15], v[64:67], v[72:75], v[0:15]
	v_mfma_f32_32x32x16_bf16 v[16:31], v[64:67], v[76:79], v[16:31]
	v_mfma_f32_32x32x16_bf16 v[0:15], v[68:71], v[220:223], v[0:15]
	v_mfma_f32_32x32x16_bf16 v[16:31], v[68:71], v[224:227], v[16:31]
	s_add_i32 s90, s76, 288
	v_add_u32_e32 v80, s90, v235
	v_add_u32_e32 v83, s90, v236
	v_add_u32_e32 v99, s90, v237
	v_add_u32_e32 v253, s90, v238
	v_add_u32_e32 v254, s90, v100
	v_add_u32_e32 v255, s90, v149
	v_med3_i32 v80, v80, 0, s99
	v_med3_i32 v83, v83, 0, s99
	v_med3_i32 v99, v99, 0, s99
	v_med3_i32 v253, v253, 0, s99
	v_med3_i32 v254, v254, 0, s99
	v_med3_i32 v255, v255, 0, s99
	v_mad_u32_u24 v80, v80, s100, v252
	v_mad_u32_u24 v83, v83, s100, v252
	v_mad_u32_u24 v99, v99, s100, v252
	v_mad_u32_u24 v253, v253, s100, v252
	v_mad_u32_u24 v254, v254, s100, v153
	v_mad_u32_u24 v255, v255, s100, v153
	global_load_dwordx4 v[156:159], v80, s[82:83]
	global_load_dwordx4 v[160:163], v83, s[82:83]
	global_load_dwordx4 v[164:167], v99, s[82:83]
	global_load_dwordx4 v[168:171], v253, s[82:83]
	global_load_dwordx4 v[172:175], v254, s[82:83] offset:768
	global_load_dwordx4 v[176:179], v255, s[82:83] offset:768
	global_load_dwordx4 v[180:183], v254, s[82:83] offset:832
	global_load_dwordx4 v[184:187], v255, s[82:83] offset:832
	ds_read_b64_tr_b16 v[72:73], v231
	ds_read_b64_tr_b16 v[74:75], v231 offset:512
	ds_read_b64_tr_b16 v[76:77], v231 offset:2048
	ds_read_b64_tr_b16 v[78:79], v231 offset:2560
	ds_read_b64_tr_b16 v[220:221], v231 offset:1024
	ds_read_b64_tr_b16 v[222:223], v231 offset:1536
	ds_read_b64_tr_b16 v[224:225], v231 offset:3072
	ds_read_b64_tr_b16 v[226:227], v231 offset:3584
	s_waitcnt vmcnt(8)
	ds_write_b128 v247, v[116:119]
	ds_write_b128 v247, v[120:123] offset:1024
	ds_write_b128 v247, v[124:127] offset:2048
	ds_write_b128 v247, v[128:131] offset:3072
	ds_read_b128 v[116:119], v248
	ds_read_b128 v[120:123], v249
	ds_read_b128 v[124:127], v250
	ds_read_b128 v[128:131], v251
	ds_write_b128 v112, v[132:135]
	ds_write_b128 v112, v[136:139] offset:1024
	ds_write_b128 v112, v[140:143] offset:2048
	ds_write_b128 v112, v[144:147] offset:3072
	v_exp_f32_e32 v188, v188
	v_exp_f32_e32 v189, v189
	v_exp_f32_e32 v190, v190
	v_exp_f32_e32 v191, v191
	v_exp_f32_e32 v192, v192
	v_exp_f32_e32 v193, v193
	s_waitcnt lgkmcnt(4)
	v_mfma_f32_32x32x16_bf16 v[32:47], v[116:119], v[48:51], v[32:47]
	v_exp_f32_e32 v194, v194
	v_exp_f32_e32 v195, v195
	v_mfma_f32_32x32x16_bf16 v[32:47], v[120:123], v[52:55], v[32:47]
	v_exp_f32_e32 v196, v196
	v_exp_f32_e32 v197, v197
	v_exp_f32_e32 v198, v198
	v_mfma_f32_32x32x16_bf16 v[32:47], v[124:127], v[56:59], v[32:47]
	v_exp_f32_e32 v199, v199
	v_exp_f32_e32 v200, v200
	v_mfma_f32_32x32x16_bf16 v[32:47], v[128:131], v[60:63], v[32:47]
	v_exp_f32_e32 v201, v201
	v_exp_f32_e32 v202, v202
	v_exp_f32_e32 v203, v203
	s_add_i32 s90, s76, 224
	v_add_u32_e32 v84, s90, v107
	v_add_u32_e32 v85, 0, v84
	v_add_u32_e32 v86, 1, v84
	v_add_u32_e32 v87, 2, v84
	v_add_u32_e32 v88, 3, v84
	v_cmp_gt_u32_e64 s[30:31], s98, v85
	v_cmp_gt_u32_e64 s[36:37], s98, v86
	v_cmp_gt_u32_e64 s[78:79], s98, v87
	v_cmp_gt_u32_e64 s[50:51], s98, v88
	v_cndmask_b32_e64 v188, 0, v188, s[30:31]
	v_add_u32_e32 v85, 8, v84
	v_cmp_gt_u32_e64 s[30:31], s98, v85
	v_cndmask_b32_e64 v189, 0, v189, s[36:37]
	v_add_u32_e32 v86, 9, v84
	v_cmp_gt_u32_e64 s[36:37], s98, v86
	v_cndmask_b32_e64 v190, 0, v190, s[78:79]
	v_add_u32_e32 v87, 10, v84
	v_cmp_gt_u32_e64 s[78:79], s98, v87
	v_cndmask_b32_e64 v191, 0, v191, s[50:51]
	v_add_u32_e32 v88, 11, v84
	v_cmp_gt_u32_e64 s[50:51], s98, v88
	v_cndmask_b32_e64 v192, 0, v192, s[30:31]
	v_add_u32_e32 v85, 16, v84
	v_cmp_gt_u32_e64 s[30:31], s98, v85
	v_cndmask_b32_e64 v193, 0, v193, s[36:37]
	v_add_u32_e32 v86, 17, v84
	v_cmp_gt_u32_e64 s[36:37], s98, v86
	v_cndmask_b32_e64 v194, 0, v194, s[78:79]
	v_add_u32_e32 v87, 18, v84
	v_cmp_gt_u32_e64 s[78:79], s98, v87
	v_cndmask_b32_e64 v195, 0, v195, s[50:51]
	v_add_u32_e32 v88, 19, v84
	v_cmp_gt_u32_e64 s[50:51], s98, v88
	v_cndmask_b32_e64 v196, 0, v196, s[30:31]
	v_add_u32_e32 v85, 24, v84
	v_cmp_gt_u32_e64 s[30:31], s98, v85
	v_cndmask_b32_e64 v197, 0, v197, s[36:37]
	v_add_u32_e32 v86, 25, v84
	v_cmp_gt_u32_e64 s[36:37], s98, v86
	v_cndmask_b32_e64 v198, 0, v198, s[78:79]
	v_add_u32_e32 v87, 26, v84
	v_cmp_gt_u32_e64 s[78:79], s98, v87
	v_cndmask_b32_e64 v199, 0, v199, s[50:51]
	v_add_u32_e32 v88, 27, v84
	v_cmp_gt_u32_e64 s[50:51], s98, v88
	v_nop
	v_cndmask_b32_e64 v200, 0, v200, s[30:31]
	v_cndmask_b32_e64 v201, 0, v201, s[36:37]
	v_cndmask_b32_e64 v202, 0, v202, s[78:79]
	v_cndmask_b32_e64 v203, 0, v203, s[50:51]
	v_cvt_pk_bf16_f32 v64, v188, v189
	v_cvt_pk_bf16_f32 v65, v190, v191
	v_cvt_pk_bf16_f32 v66, v192, v193
	v_cvt_pk_bf16_f32 v67, v194, v195
	v_cvt_pk_bf16_f32 v68, v196, v197
	v_cvt_pk_bf16_f32 v69, v198, v199
	v_cvt_pk_bf16_f32 v70, v200, v201
	v_cvt_pk_bf16_f32 v71, v202, v203
	v_pk_add_f32 v[232:233], v[232:233], v[188:189]
	v_pk_add_f32 v[232:233], v[232:233], v[190:191]
	v_pk_add_f32 v[232:233], v[232:233], v[192:193]
	v_pk_add_f32 v[232:233], v[232:233], v[194:195]
	v_pk_add_f32 v[232:233], v[232:233], v[196:197]
	v_pk_add_f32 v[232:233], v[232:233], v[198:199]
	v_pk_add_f32 v[232:233], v[232:233], v[200:201]
	v_pk_add_f32 v[232:233], v[232:233], v[202:203]
	ds_read2_b32 v[188:189], v115 offset0:136 offset1:137
	ds_read2_b32 v[190:191], v115 offset0:138 offset1:139
	ds_read2_b32 v[192:193], v115 offset0:144 offset1:145
	ds_read2_b32 v[194:195], v115 offset0:146 offset1:147
	ds_read2_b32 v[196:197], v115 offset0:153 offset1:154
	ds_read2_b32 v[198:199], v115 offset0:155 offset1:156
	ds_read2_b32 v[200:201], v115 offset0:161 offset1:162
	ds_read2_b32 v[202:203], v115 offset0:163 offset1:164
	v_mfma_f32_32x32x16_bf16 v[0:15], v[64:67], v[72:75], v[0:15]
	v_mfma_f32_32x32x16_bf16 v[16:31], v[64:67], v[76:79], v[16:31]
	v_mfma_f32_32x32x16_bf16 v[0:15], v[68:71], v[220:223], v[0:15]
	v_mfma_f32_32x32x16_bf16 v[16:31], v[68:71], v[224:227], v[16:31]
	s_add_i32 s90, s76, 320
	v_add_u32_e32 v80, s90, v235
	v_add_u32_e32 v83, s90, v236
	v_add_u32_e32 v99, s90, v237
	v_add_u32_e32 v253, s90, v238
	v_add_u32_e32 v254, s90, v100
	v_add_u32_e32 v255, s90, v149
	v_med3_i32 v80, v80, 0, s99
	v_med3_i32 v83, v83, 0, s99
	v_med3_i32 v99, v99, 0, s99
	v_med3_i32 v253, v253, 0, s99
	v_med3_i32 v254, v254, 0, s99
	v_med3_i32 v255, v255, 0, s99
	v_mad_u32_u24 v80, v80, s100, v252
	v_mad_u32_u24 v83, v83, s100, v252
	v_mad_u32_u24 v99, v99, s100, v252
	v_mad_u32_u24 v253, v253, s100, v252
	v_mad_u32_u24 v254, v254, s100, v153
	v_mad_u32_u24 v255, v255, s100, v153
	global_load_dwordx4 v[116:119], v80, s[82:83]
	global_load_dwordx4 v[120:123], v83, s[82:83]
	global_load_dwordx4 v[124:127], v99, s[82:83]
	global_load_dwordx4 v[128:131], v253, s[82:83]
	global_load_dwordx4 v[132:135], v254, s[82:83] offset:768
	global_load_dwordx4 v[136:139], v255, s[82:83] offset:768
	global_load_dwordx4 v[140:143], v254, s[82:83] offset:832
	global_load_dwordx4 v[144:147], v255, s[82:83] offset:832
	ds_read_b64_tr_b16 v[72:73], v231
	ds_read_b64_tr_b16 v[74:75], v231 offset:512
	ds_read_b64_tr_b16 v[76:77], v231 offset:2048
	ds_read_b64_tr_b16 v[78:79], v231 offset:2560
	ds_read_b64_tr_b16 v[220:221], v231 offset:1024
	ds_read_b64_tr_b16 v[222:223], v231 offset:1536
	ds_read_b64_tr_b16 v[224:225], v231 offset:3072
	ds_read_b64_tr_b16 v[226:227], v231 offset:3584
	s_waitcnt vmcnt(8)
	ds_write_b128 v247, v[156:159]
	ds_write_b128 v247, v[160:163] offset:1024
	ds_write_b128 v247, v[164:167] offset:2048
	ds_write_b128 v247, v[168:171] offset:3072
	ds_read_b128 v[156:159], v248
	ds_read_b128 v[160:163], v249
	ds_read_b128 v[164:167], v250
	ds_read_b128 v[168:171], v251
	ds_write_b128 v112, v[172:175]
	ds_write_b128 v112, v[176:179] offset:1024
	ds_write_b128 v112, v[180:183] offset:2048
	ds_write_b128 v112, v[184:187] offset:3072
	v_exp_f32_e32 v32, v32
	v_exp_f32_e32 v33, v33
	v_exp_f32_e32 v34, v34
	v_exp_f32_e32 v35, v35
	v_exp_f32_e32 v36, v36
	v_exp_f32_e32 v37, v37
	s_waitcnt lgkmcnt(4)
	v_mfma_f32_32x32x16_bf16 v[188:203], v[156:159], v[48:51], v[188:203]
	v_exp_f32_e32 v38, v38
	v_exp_f32_e32 v39, v39
	v_mfma_f32_32x32x16_bf16 v[188:203], v[160:163], v[52:55], v[188:203]
	v_exp_f32_e32 v40, v40
	v_exp_f32_e32 v41, v41
	v_exp_f32_e32 v42, v42
	v_mfma_f32_32x32x16_bf16 v[188:203], v[164:167], v[56:59], v[188:203]
	v_exp_f32_e32 v43, v43
	v_exp_f32_e32 v44, v44
	v_mfma_f32_32x32x16_bf16 v[188:203], v[168:171], v[60:63], v[188:203]
	v_exp_f32_e32 v45, v45
	v_exp_f32_e32 v46, v46
	v_exp_f32_e32 v47, v47
	s_add_i32 s90, s76, 256
	v_add_u32_e32 v84, s90, v107
	v_add_u32_e32 v85, 0, v84
	v_add_u32_e32 v86, 1, v84
	v_add_u32_e32 v87, 2, v84
	v_add_u32_e32 v88, 3, v84
	v_cmp_gt_u32_e64 s[30:31], s98, v85
	v_cmp_gt_u32_e64 s[36:37], s98, v86
	v_cmp_gt_u32_e64 s[78:79], s98, v87
	v_cmp_gt_u32_e64 s[50:51], s98, v88
	v_cndmask_b32_e64 v32, 0, v32, s[30:31]
	v_add_u32_e32 v85, 8, v84
	v_cmp_gt_u32_e64 s[30:31], s98, v85
	v_cndmask_b32_e64 v33, 0, v33, s[36:37]
	v_add_u32_e32 v86, 9, v84
	v_cmp_gt_u32_e64 s[36:37], s98, v86
	v_cndmask_b32_e64 v34, 0, v34, s[78:79]
	v_add_u32_e32 v87, 10, v84
	v_cmp_gt_u32_e64 s[78:79], s98, v87
	v_cndmask_b32_e64 v35, 0, v35, s[50:51]
	v_add_u32_e32 v88, 11, v84
	v_cmp_gt_u32_e64 s[50:51], s98, v88
	v_cndmask_b32_e64 v36, 0, v36, s[30:31]
	v_add_u32_e32 v85, 16, v84
	v_cmp_gt_u32_e64 s[30:31], s98, v85
	v_cndmask_b32_e64 v37, 0, v37, s[36:37]
	v_add_u32_e32 v86, 17, v84
	v_cmp_gt_u32_e64 s[36:37], s98, v86
	v_cndmask_b32_e64 v38, 0, v38, s[78:79]
	v_add_u32_e32 v87, 18, v84
	v_cmp_gt_u32_e64 s[78:79], s98, v87
	v_cndmask_b32_e64 v39, 0, v39, s[50:51]
	v_add_u32_e32 v88, 19, v84
	v_cmp_gt_u32_e64 s[50:51], s98, v88
	v_cndmask_b32_e64 v40, 0, v40, s[30:31]
	v_add_u32_e32 v85, 24, v84
	v_cmp_gt_u32_e64 s[30:31], s98, v85
	v_cndmask_b32_e64 v41, 0, v41, s[36:37]
	v_add_u32_e32 v86, 25, v84
	v_cmp_gt_u32_e64 s[36:37], s98, v86
	v_cndmask_b32_e64 v42, 0, v42, s[78:79]
	v_add_u32_e32 v87, 26, v84
	v_cmp_gt_u32_e64 s[78:79], s98, v87
	v_cndmask_b32_e64 v43, 0, v43, s[50:51]
	v_add_u32_e32 v88, 27, v84
	v_cmp_gt_u32_e64 s[50:51], s98, v88
	v_nop
	v_cndmask_b32_e64 v44, 0, v44, s[30:31]
	v_cndmask_b32_e64 v45, 0, v45, s[36:37]
	v_cndmask_b32_e64 v46, 0, v46, s[78:79]
	v_cndmask_b32_e64 v47, 0, v47, s[50:51]
	v_cvt_pk_bf16_f32 v64, v32, v33
	v_cvt_pk_bf16_f32 v65, v34, v35
	v_cvt_pk_bf16_f32 v66, v36, v37
	v_cvt_pk_bf16_f32 v67, v38, v39
	v_cvt_pk_bf16_f32 v68, v40, v41
	v_cvt_pk_bf16_f32 v69, v42, v43
	v_cvt_pk_bf16_f32 v70, v44, v45
	v_cvt_pk_bf16_f32 v71, v46, v47
	v_pk_add_f32 v[232:233], v[232:233], v[32:33]
	v_pk_add_f32 v[232:233], v[232:233], v[34:35]
	v_pk_add_f32 v[232:233], v[232:233], v[36:37]
	v_pk_add_f32 v[232:233], v[232:233], v[38:39]
	v_pk_add_f32 v[232:233], v[232:233], v[40:41]
	v_pk_add_f32 v[232:233], v[232:233], v[42:43]
	v_pk_add_f32 v[232:233], v[232:233], v[44:45]
	v_pk_add_f32 v[232:233], v[232:233], v[46:47]
	ds_read2_b32 v[32:33], v115 offset0:170 offset1:171
	ds_read2_b32 v[34:35], v115 offset0:172 offset1:173
	ds_read2_b32 v[36:37], v115 offset0:178 offset1:179
	ds_read2_b32 v[38:39], v115 offset0:180 offset1:181
	ds_read2_b32 v[40:41], v115 offset0:187 offset1:188
	ds_read2_b32 v[42:43], v115 offset0:189 offset1:190
	ds_read2_b32 v[44:45], v115 offset0:195 offset1:196
	ds_read2_b32 v[46:47], v115 offset0:197 offset1:198
	v_mfma_f32_32x32x16_bf16 v[0:15], v[64:67], v[72:75], v[0:15]
	v_mfma_f32_32x32x16_bf16 v[16:31], v[64:67], v[76:79], v[16:31]
	v_mfma_f32_32x32x16_bf16 v[0:15], v[68:71], v[220:223], v[0:15]
	v_mfma_f32_32x32x16_bf16 v[16:31], v[68:71], v[224:227], v[16:31]
	s_add_i32 s90, s76, 352
	v_add_u32_e32 v80, s90, v235
	v_add_u32_e32 v83, s90, v236
	v_add_u32_e32 v99, s90, v237
	v_add_u32_e32 v253, s90, v238
	v_add_u32_e32 v254, s90, v100
	v_add_u32_e32 v255, s90, v149
	v_med3_i32 v80, v80, 0, s99
	v_med3_i32 v83, v83, 0, s99
	v_med3_i32 v99, v99, 0, s99
	v_med3_i32 v253, v253, 0, s99
	v_med3_i32 v254, v254, 0, s99
	v_med3_i32 v255, v255, 0, s99
	v_mad_u32_u24 v80, v80, s100, v252
	v_mad_u32_u24 v83, v83, s100, v252
	v_mad_u32_u24 v99, v99, s100, v252
	v_mad_u32_u24 v253, v253, s100, v252
	v_mad_u32_u24 v254, v254, s100, v153
	v_mad_u32_u24 v255, v255, s100, v153
	global_load_dwordx4 v[156:159], v80, s[82:83]
	global_load_dwordx4 v[160:163], v83, s[82:83]
	global_load_dwordx4 v[164:167], v99, s[82:83]
	global_load_dwordx4 v[168:171], v253, s[82:83]
	global_load_dwordx4 v[172:175], v254, s[82:83] offset:768
	global_load_dwordx4 v[176:179], v255, s[82:83] offset:768
	global_load_dwordx4 v[180:183], v254, s[82:83] offset:832
	global_load_dwordx4 v[184:187], v255, s[82:83] offset:832
	ds_read_b64_tr_b16 v[72:73], v231
	ds_read_b64_tr_b16 v[74:75], v231 offset:512
	ds_read_b64_tr_b16 v[76:77], v231 offset:2048
	ds_read_b64_tr_b16 v[78:79], v231 offset:2560
	ds_read_b64_tr_b16 v[220:221], v231 offset:1024
	ds_read_b64_tr_b16 v[222:223], v231 offset:1536
	ds_read_b64_tr_b16 v[224:225], v231 offset:3072
	ds_read_b64_tr_b16 v[226:227], v231 offset:3584
	s_waitcnt vmcnt(8)
	ds_write_b128 v247, v[116:119]
	ds_write_b128 v247, v[120:123] offset:1024
	ds_write_b128 v247, v[124:127] offset:2048
	ds_write_b128 v247, v[128:131] offset:3072
	ds_read_b128 v[116:119], v248
	ds_read_b128 v[120:123], v249
	ds_read_b128 v[124:127], v250
	ds_read_b128 v[128:131], v251
	ds_write_b128 v112, v[132:135]
	ds_write_b128 v112, v[136:139] offset:1024
	ds_write_b128 v112, v[140:143] offset:2048
	ds_write_b128 v112, v[144:147] offset:3072
	v_exp_f32_e32 v188, v188
	v_exp_f32_e32 v189, v189
	v_exp_f32_e32 v190, v190
	v_exp_f32_e32 v191, v191
	v_exp_f32_e32 v192, v192
	v_exp_f32_e32 v193, v193
	s_waitcnt lgkmcnt(4)
	v_mfma_f32_32x32x16_bf16 v[32:47], v[116:119], v[48:51], v[32:47]
	v_exp_f32_e32 v194, v194
	v_exp_f32_e32 v195, v195
	v_mfma_f32_32x32x16_bf16 v[32:47], v[120:123], v[52:55], v[32:47]
	v_exp_f32_e32 v196, v196
	v_exp_f32_e32 v197, v197
	v_exp_f32_e32 v198, v198
	v_mfma_f32_32x32x16_bf16 v[32:47], v[124:127], v[56:59], v[32:47]
	v_exp_f32_e32 v199, v199
	v_exp_f32_e32 v200, v200
	v_mfma_f32_32x32x16_bf16 v[32:47], v[128:131], v[60:63], v[32:47]
	v_exp_f32_e32 v201, v201
	v_exp_f32_e32 v202, v202
	v_exp_f32_e32 v203, v203
	s_add_i32 s90, s76, 288
	v_add_u32_e32 v84, s90, v107
	v_add_u32_e32 v85, 0, v84
	v_add_u32_e32 v86, 1, v84
	v_add_u32_e32 v87, 2, v84
	v_add_u32_e32 v88, 3, v84
	v_cmp_gt_u32_e64 s[30:31], s98, v85
	v_cmp_gt_u32_e64 s[36:37], s98, v86
	v_cmp_gt_u32_e64 s[78:79], s98, v87
	v_cmp_gt_u32_e64 s[50:51], s98, v88
	v_cndmask_b32_e64 v188, 0, v188, s[30:31]
	v_add_u32_e32 v85, 8, v84
	v_cmp_gt_u32_e64 s[30:31], s98, v85
	v_cndmask_b32_e64 v189, 0, v189, s[36:37]
	v_add_u32_e32 v86, 9, v84
	v_cmp_gt_u32_e64 s[36:37], s98, v86
	v_cndmask_b32_e64 v190, 0, v190, s[78:79]
	v_add_u32_e32 v87, 10, v84
	v_cmp_gt_u32_e64 s[78:79], s98, v87
	v_cndmask_b32_e64 v191, 0, v191, s[50:51]
	v_add_u32_e32 v88, 11, v84
	v_cmp_gt_u32_e64 s[50:51], s98, v88
	v_cndmask_b32_e64 v192, 0, v192, s[30:31]
	v_add_u32_e32 v85, 16, v84
	v_cmp_gt_u32_e64 s[30:31], s98, v85
	v_cndmask_b32_e64 v193, 0, v193, s[36:37]
	v_add_u32_e32 v86, 17, v84
	v_cmp_gt_u32_e64 s[36:37], s98, v86
	v_cndmask_b32_e64 v194, 0, v194, s[78:79]
	v_add_u32_e32 v87, 18, v84
	v_cmp_gt_u32_e64 s[78:79], s98, v87
	v_cndmask_b32_e64 v195, 0, v195, s[50:51]
	v_add_u32_e32 v88, 19, v84
	v_cmp_gt_u32_e64 s[50:51], s98, v88
	v_cndmask_b32_e64 v196, 0, v196, s[30:31]
	v_add_u32_e32 v85, 24, v84
	v_cmp_gt_u32_e64 s[30:31], s98, v85
	v_cndmask_b32_e64 v197, 0, v197, s[36:37]
	v_add_u32_e32 v86, 25, v84
	v_cmp_gt_u32_e64 s[36:37], s98, v86
	v_cndmask_b32_e64 v198, 0, v198, s[78:79]
	v_add_u32_e32 v87, 26, v84
	v_cmp_gt_u32_e64 s[78:79], s98, v87
	v_cndmask_b32_e64 v199, 0, v199, s[50:51]
	v_add_u32_e32 v88, 27, v84
	v_cmp_gt_u32_e64 s[50:51], s98, v88
	v_nop
	v_cndmask_b32_e64 v200, 0, v200, s[30:31]
	v_cndmask_b32_e64 v201, 0, v201, s[36:37]
	v_cndmask_b32_e64 v202, 0, v202, s[78:79]
	v_cndmask_b32_e64 v203, 0, v203, s[50:51]
	v_cvt_pk_bf16_f32 v64, v188, v189
	v_cvt_pk_bf16_f32 v65, v190, v191
	v_cvt_pk_bf16_f32 v66, v192, v193
	v_cvt_pk_bf16_f32 v67, v194, v195
	v_cvt_pk_bf16_f32 v68, v196, v197
	v_cvt_pk_bf16_f32 v69, v198, v199
	v_cvt_pk_bf16_f32 v70, v200, v201
	v_cvt_pk_bf16_f32 v71, v202, v203
	v_pk_add_f32 v[232:233], v[232:233], v[188:189]
	v_pk_add_f32 v[232:233], v[232:233], v[190:191]
	v_pk_add_f32 v[232:233], v[232:233], v[192:193]
	v_pk_add_f32 v[232:233], v[232:233], v[194:195]
	v_pk_add_f32 v[232:233], v[232:233], v[196:197]
	v_pk_add_f32 v[232:233], v[232:233], v[198:199]
	v_pk_add_f32 v[232:233], v[232:233], v[200:201]
	v_pk_add_f32 v[232:233], v[232:233], v[202:203]
	ds_read2_b32 v[188:189], v115 offset0:204 offset1:205
	ds_read2_b32 v[190:191], v115 offset0:206 offset1:207
	ds_read2_b32 v[192:193], v115 offset0:212 offset1:213
	ds_read2_b32 v[194:195], v115 offset0:214 offset1:215
	ds_read2_b32 v[196:197], v115 offset0:221 offset1:222
	ds_read2_b32 v[198:199], v115 offset0:223 offset1:224
	ds_read2_b32 v[200:201], v115 offset0:229 offset1:230
	ds_read2_b32 v[202:203], v115 offset0:231 offset1:232
	v_mfma_f32_32x32x16_bf16 v[0:15], v[64:67], v[72:75], v[0:15]
	v_mfma_f32_32x32x16_bf16 v[16:31], v[64:67], v[76:79], v[16:31]
	v_mfma_f32_32x32x16_bf16 v[0:15], v[68:71], v[220:223], v[0:15]
	v_mfma_f32_32x32x16_bf16 v[16:31], v[68:71], v[224:227], v[16:31]
	s_add_i32 s90, s76, 384
	v_add_u32_e32 v80, s90, v235
	v_add_u32_e32 v83, s90, v236
	v_add_u32_e32 v99, s90, v237
	v_add_u32_e32 v253, s90, v238
	v_add_u32_e32 v254, s90, v100
	v_add_u32_e32 v255, s90, v149
	v_med3_i32 v80, v80, 0, s99
	v_med3_i32 v83, v83, 0, s99
	v_med3_i32 v99, v99, 0, s99
	v_med3_i32 v253, v253, 0, s99
	v_med3_i32 v254, v254, 0, s99
	v_med3_i32 v255, v255, 0, s99
	v_mad_u32_u24 v80, v80, s100, v252
	v_mad_u32_u24 v83, v83, s100, v252
	v_mad_u32_u24 v99, v99, s100, v252
	v_mad_u32_u24 v253, v253, s100, v252
	v_mad_u32_u24 v254, v254, s100, v153
	v_mad_u32_u24 v255, v255, s100, v153
	global_load_dwordx4 v[116:119], v80, s[82:83]
	global_load_dwordx4 v[120:123], v83, s[82:83]
	global_load_dwordx4 v[124:127], v99, s[82:83]
	global_load_dwordx4 v[128:131], v253, s[82:83]
	global_load_dwordx4 v[132:135], v254, s[82:83] offset:768
	global_load_dwordx4 v[136:139], v255, s[82:83] offset:768
	global_load_dwordx4 v[140:143], v254, s[82:83] offset:832
	global_load_dwordx4 v[144:147], v255, s[82:83] offset:832
	ds_read_b64_tr_b16 v[72:73], v231
	ds_read_b64_tr_b16 v[74:75], v231 offset:512
	ds_read_b64_tr_b16 v[76:77], v231 offset:2048
	ds_read_b64_tr_b16 v[78:79], v231 offset:2560
	ds_read_b64_tr_b16 v[220:221], v231 offset:1024
	ds_read_b64_tr_b16 v[222:223], v231 offset:1536
	ds_read_b64_tr_b16 v[224:225], v231 offset:3072
	ds_read_b64_tr_b16 v[226:227], v231 offset:3584
	s_waitcnt vmcnt(8)
	ds_write_b128 v247, v[156:159]
	ds_write_b128 v247, v[160:163] offset:1024
	ds_write_b128 v247, v[164:167] offset:2048
	ds_write_b128 v247, v[168:171] offset:3072
	ds_read_b128 v[156:159], v248
	ds_read_b128 v[160:163], v249
	ds_read_b128 v[164:167], v250
	ds_read_b128 v[168:171], v251
	ds_write_b128 v112, v[172:175]
	ds_write_b128 v112, v[176:179] offset:1024
	ds_write_b128 v112, v[180:183] offset:2048
	ds_write_b128 v112, v[184:187] offset:3072
	v_exp_f32_e32 v32, v32
	v_exp_f32_e32 v33, v33
	v_exp_f32_e32 v34, v34
	v_exp_f32_e32 v35, v35
	v_exp_f32_e32 v36, v36
	v_exp_f32_e32 v37, v37
	s_waitcnt lgkmcnt(4)
	v_mfma_f32_32x32x16_bf16 v[188:203], v[156:159], v[48:51], v[188:203]
	v_exp_f32_e32 v38, v38
	v_exp_f32_e32 v39, v39
	v_mfma_f32_32x32x16_bf16 v[188:203], v[160:163], v[52:55], v[188:203]
	v_exp_f32_e32 v40, v40
	v_exp_f32_e32 v41, v41
	v_exp_f32_e32 v42, v42
	v_mfma_f32_32x32x16_bf16 v[188:203], v[164:167], v[56:59], v[188:203]
	v_exp_f32_e32 v43, v43
	v_exp_f32_e32 v44, v44
	v_mfma_f32_32x32x16_bf16 v[188:203], v[168:171], v[60:63], v[188:203]
	v_exp_f32_e32 v45, v45
	v_exp_f32_e32 v46, v46
	v_exp_f32_e32 v47, v47
	s_add_i32 s90, s76, 320
	v_add_u32_e32 v84, s90, v107
	v_add_u32_e32 v85, 0, v84
	v_add_u32_e32 v86, 1, v84
	v_add_u32_e32 v87, 2, v84
	v_add_u32_e32 v88, 3, v84
	v_cmp_gt_u32_e64 s[30:31], s98, v85
	v_cmp_gt_u32_e64 s[36:37], s98, v86
	v_cmp_gt_u32_e64 s[78:79], s98, v87
	v_cmp_gt_u32_e64 s[50:51], s98, v88
	v_cndmask_b32_e64 v32, 0, v32, s[30:31]
	v_add_u32_e32 v85, 8, v84
	v_cmp_gt_u32_e64 s[30:31], s98, v85
	v_cndmask_b32_e64 v33, 0, v33, s[36:37]
	v_add_u32_e32 v86, 9, v84
	v_cmp_gt_u32_e64 s[36:37], s98, v86
	v_cndmask_b32_e64 v34, 0, v34, s[78:79]
	v_add_u32_e32 v87, 10, v84
	v_cmp_gt_u32_e64 s[78:79], s98, v87
	v_cndmask_b32_e64 v35, 0, v35, s[50:51]
	v_add_u32_e32 v88, 11, v84
	v_cmp_gt_u32_e64 s[50:51], s98, v88
	v_cndmask_b32_e64 v36, 0, v36, s[30:31]
	v_add_u32_e32 v85, 16, v84
	v_cmp_gt_u32_e64 s[30:31], s98, v85
	v_cndmask_b32_e64 v37, 0, v37, s[36:37]
	v_add_u32_e32 v86, 17, v84
	v_cmp_gt_u32_e64 s[36:37], s98, v86
	v_cndmask_b32_e64 v38, 0, v38, s[78:79]
	v_add_u32_e32 v87, 18, v84
	v_cmp_gt_u32_e64 s[78:79], s98, v87
	v_cndmask_b32_e64 v39, 0, v39, s[50:51]
	v_add_u32_e32 v88, 19, v84
	v_cmp_gt_u32_e64 s[50:51], s98, v88
	v_cndmask_b32_e64 v40, 0, v40, s[30:31]
	v_add_u32_e32 v85, 24, v84
	v_cmp_gt_u32_e64 s[30:31], s98, v85
	v_cndmask_b32_e64 v41, 0, v41, s[36:37]
	v_add_u32_e32 v86, 25, v84
	v_cmp_gt_u32_e64 s[36:37], s98, v86
	v_cndmask_b32_e64 v42, 0, v42, s[78:79]
	v_add_u32_e32 v87, 26, v84
	v_cmp_gt_u32_e64 s[78:79], s98, v87
	v_cndmask_b32_e64 v43, 0, v43, s[50:51]
	v_add_u32_e32 v88, 27, v84
	v_cmp_gt_u32_e64 s[50:51], s98, v88
	v_nop
	v_cndmask_b32_e64 v44, 0, v44, s[30:31]
	v_cndmask_b32_e64 v45, 0, v45, s[36:37]
	v_cndmask_b32_e64 v46, 0, v46, s[78:79]
	v_cndmask_b32_e64 v47, 0, v47, s[50:51]
	v_cvt_pk_bf16_f32 v64, v32, v33
	v_cvt_pk_bf16_f32 v65, v34, v35
	v_cvt_pk_bf16_f32 v66, v36, v37
	v_cvt_pk_bf16_f32 v67, v38, v39
	v_cvt_pk_bf16_f32 v68, v40, v41
	v_cvt_pk_bf16_f32 v69, v42, v43
	v_cvt_pk_bf16_f32 v70, v44, v45
	v_cvt_pk_bf16_f32 v71, v46, v47
	v_pk_add_f32 v[232:233], v[232:233], v[32:33]
	v_pk_add_f32 v[232:233], v[232:233], v[34:35]
	v_pk_add_f32 v[232:233], v[232:233], v[36:37]
	v_pk_add_f32 v[232:233], v[232:233], v[38:39]
	v_pk_add_f32 v[232:233], v[232:233], v[40:41]
	v_pk_add_f32 v[232:233], v[232:233], v[42:43]
	v_pk_add_f32 v[232:233], v[232:233], v[44:45]
	v_pk_add_f32 v[232:233], v[232:233], v[46:47]
	v_add_u32_e32 v115, 952, v115
	ds_read2_b32 v[32:33], v115 offset0:0 offset1:1
	ds_read2_b32 v[34:35], v115 offset0:2 offset1:3
	ds_read2_b32 v[36:37], v115 offset0:8 offset1:9
	ds_read2_b32 v[38:39], v115 offset0:10 offset1:11
	ds_read2_b32 v[40:41], v115 offset0:17 offset1:18
	ds_read2_b32 v[42:43], v115 offset0:19 offset1:20
	ds_read2_b32 v[44:45], v115 offset0:25 offset1:26
	ds_read2_b32 v[46:47], v115 offset0:27 offset1:28
	v_mfma_f32_32x32x16_bf16 v[0:15], v[64:67], v[72:75], v[0:15]
	v_mfma_f32_32x32x16_bf16 v[16:31], v[64:67], v[76:79], v[16:31]
	v_mfma_f32_32x32x16_bf16 v[0:15], v[68:71], v[220:223], v[0:15]
	v_mfma_f32_32x32x16_bf16 v[16:31], v[68:71], v[224:227], v[16:31]
	s_add_i32 s90, s76, 416
	v_add_u32_e32 v80, s90, v235
	v_add_u32_e32 v83, s90, v236
	v_add_u32_e32 v99, s90, v237
	v_add_u32_e32 v253, s90, v238
	v_add_u32_e32 v254, s90, v100
	v_add_u32_e32 v255, s90, v149
	v_med3_i32 v80, v80, 0, s99
	v_med3_i32 v83, v83, 0, s99
	v_med3_i32 v99, v99, 0, s99
	v_med3_i32 v253, v253, 0, s99
	v_med3_i32 v254, v254, 0, s99
	v_med3_i32 v255, v255, 0, s99
	v_mad_u32_u24 v80, v80, s100, v252
	v_mad_u32_u24 v83, v83, s100, v252
	v_mad_u32_u24 v99, v99, s100, v252
	v_mad_u32_u24 v253, v253, s100, v252
	v_mad_u32_u24 v254, v254, s100, v153
	v_mad_u32_u24 v255, v255, s100, v153
	global_load_dwordx4 v[156:159], v80, s[82:83]
	global_load_dwordx4 v[160:163], v83, s[82:83]
	global_load_dwordx4 v[164:167], v99, s[82:83]
	global_load_dwordx4 v[168:171], v253, s[82:83]
	global_load_dwordx4 v[172:175], v254, s[82:83] offset:768
	global_load_dwordx4 v[176:179], v255, s[82:83] offset:768
	global_load_dwordx4 v[180:183], v254, s[82:83] offset:832
	global_load_dwordx4 v[184:187], v255, s[82:83] offset:832
	ds_read_b64_tr_b16 v[72:73], v231
	ds_read_b64_tr_b16 v[74:75], v231 offset:512
	ds_read_b64_tr_b16 v[76:77], v231 offset:2048
	ds_read_b64_tr_b16 v[78:79], v231 offset:2560
	ds_read_b64_tr_b16 v[220:221], v231 offset:1024
	ds_read_b64_tr_b16 v[222:223], v231 offset:1536
	ds_read_b64_tr_b16 v[224:225], v231 offset:3072
	ds_read_b64_tr_b16 v[226:227], v231 offset:3584
	s_waitcnt vmcnt(8)
	ds_write_b128 v247, v[116:119]
	ds_write_b128 v247, v[120:123] offset:1024
	ds_write_b128 v247, v[124:127] offset:2048
	ds_write_b128 v247, v[128:131] offset:3072
	ds_read_b128 v[116:119], v248
	ds_read_b128 v[120:123], v249
	ds_read_b128 v[124:127], v250
	ds_read_b128 v[128:131], v251
	ds_write_b128 v112, v[132:135]
	ds_write_b128 v112, v[136:139] offset:1024
	ds_write_b128 v112, v[140:143] offset:2048
	ds_write_b128 v112, v[144:147] offset:3072
	v_exp_f32_e32 v188, v188
	v_exp_f32_e32 v189, v189
	v_exp_f32_e32 v190, v190
	v_exp_f32_e32 v191, v191
	v_exp_f32_e32 v192, v192
	v_exp_f32_e32 v193, v193
	s_waitcnt lgkmcnt(4)
	v_mfma_f32_32x32x16_bf16 v[32:47], v[116:119], v[48:51], v[32:47]
	v_exp_f32_e32 v194, v194
	v_exp_f32_e32 v195, v195
	v_mfma_f32_32x32x16_bf16 v[32:47], v[120:123], v[52:55], v[32:47]
	v_exp_f32_e32 v196, v196
	v_exp_f32_e32 v197, v197
	v_exp_f32_e32 v198, v198
	v_mfma_f32_32x32x16_bf16 v[32:47], v[124:127], v[56:59], v[32:47]
	v_exp_f32_e32 v199, v199
	v_exp_f32_e32 v200, v200
	v_mfma_f32_32x32x16_bf16 v[32:47], v[128:131], v[60:63], v[32:47]
	v_exp_f32_e32 v201, v201
	v_exp_f32_e32 v202, v202
	v_exp_f32_e32 v203, v203
	s_add_i32 s90, s76, 352
	v_add_u32_e32 v84, s90, v107
	v_add_u32_e32 v85, 0, v84
	v_add_u32_e32 v86, 1, v84
	v_add_u32_e32 v87, 2, v84
	v_add_u32_e32 v88, 3, v84
	v_cmp_gt_u32_e64 s[30:31], s98, v85
	v_cmp_gt_u32_e64 s[36:37], s98, v86
	v_cmp_gt_u32_e64 s[78:79], s98, v87
	v_cmp_gt_u32_e64 s[50:51], s98, v88
	v_cndmask_b32_e64 v188, 0, v188, s[30:31]
	v_add_u32_e32 v85, 8, v84
	v_cmp_gt_u32_e64 s[30:31], s98, v85
	v_cndmask_b32_e64 v189, 0, v189, s[36:37]
	v_add_u32_e32 v86, 9, v84
	v_cmp_gt_u32_e64 s[36:37], s98, v86
	v_cndmask_b32_e64 v190, 0, v190, s[78:79]
	v_add_u32_e32 v87, 10, v84
	v_cmp_gt_u32_e64 s[78:79], s98, v87
	v_cndmask_b32_e64 v191, 0, v191, s[50:51]
	v_add_u32_e32 v88, 11, v84
	v_cmp_gt_u32_e64 s[50:51], s98, v88
	v_cndmask_b32_e64 v192, 0, v192, s[30:31]
	v_add_u32_e32 v85, 16, v84
	v_cmp_gt_u32_e64 s[30:31], s98, v85
	v_cndmask_b32_e64 v193, 0, v193, s[36:37]
	v_add_u32_e32 v86, 17, v84
	v_cmp_gt_u32_e64 s[36:37], s98, v86
	v_cndmask_b32_e64 v194, 0, v194, s[78:79]
	v_add_u32_e32 v87, 18, v84
	v_cmp_gt_u32_e64 s[78:79], s98, v87
	v_cndmask_b32_e64 v195, 0, v195, s[50:51]
	v_add_u32_e32 v88, 19, v84
	v_cmp_gt_u32_e64 s[50:51], s98, v88
	v_cndmask_b32_e64 v196, 0, v196, s[30:31]
	v_add_u32_e32 v85, 24, v84
	v_cmp_gt_u32_e64 s[30:31], s98, v85
	v_cndmask_b32_e64 v197, 0, v197, s[36:37]
	v_add_u32_e32 v86, 25, v84
	v_cmp_gt_u32_e64 s[36:37], s98, v86
	v_cndmask_b32_e64 v198, 0, v198, s[78:79]
	v_add_u32_e32 v87, 26, v84
	v_cmp_gt_u32_e64 s[78:79], s98, v87
	v_cndmask_b32_e64 v199, 0, v199, s[50:51]
	v_add_u32_e32 v88, 27, v84
	v_cmp_gt_u32_e64 s[50:51], s98, v88
	v_nop
	v_cndmask_b32_e64 v200, 0, v200, s[30:31]
	v_cndmask_b32_e64 v201, 0, v201, s[36:37]
	v_cndmask_b32_e64 v202, 0, v202, s[78:79]
	v_cndmask_b32_e64 v203, 0, v203, s[50:51]
	v_cvt_pk_bf16_f32 v64, v188, v189
	v_cvt_pk_bf16_f32 v65, v190, v191
	v_cvt_pk_bf16_f32 v66, v192, v193
	v_cvt_pk_bf16_f32 v67, v194, v195
	v_cvt_pk_bf16_f32 v68, v196, v197
	v_cvt_pk_bf16_f32 v69, v198, v199
	v_cvt_pk_bf16_f32 v70, v200, v201
	v_cvt_pk_bf16_f32 v71, v202, v203
	v_pk_add_f32 v[232:233], v[232:233], v[188:189]
	v_pk_add_f32 v[232:233], v[232:233], v[190:191]
	v_pk_add_f32 v[232:233], v[232:233], v[192:193]
	v_pk_add_f32 v[232:233], v[232:233], v[194:195]
	v_pk_add_f32 v[232:233], v[232:233], v[196:197]
	v_pk_add_f32 v[232:233], v[232:233], v[198:199]
	v_pk_add_f32 v[232:233], v[232:233], v[200:201]
	v_pk_add_f32 v[232:233], v[232:233], v[202:203]
	ds_read2_b32 v[188:189], v115 offset0:34 offset1:35
	ds_read2_b32 v[190:191], v115 offset0:36 offset1:37
	ds_read2_b32 v[192:193], v115 offset0:42 offset1:43
	ds_read2_b32 v[194:195], v115 offset0:44 offset1:45
	ds_read2_b32 v[196:197], v115 offset0:51 offset1:52
	ds_read2_b32 v[198:199], v115 offset0:53 offset1:54
	ds_read2_b32 v[200:201], v115 offset0:59 offset1:60
	ds_read2_b32 v[202:203], v115 offset0:61 offset1:62
	v_mfma_f32_32x32x16_bf16 v[0:15], v[64:67], v[72:75], v[0:15]
	v_mfma_f32_32x32x16_bf16 v[16:31], v[64:67], v[76:79], v[16:31]
	v_mfma_f32_32x32x16_bf16 v[0:15], v[68:71], v[220:223], v[0:15]
	v_mfma_f32_32x32x16_bf16 v[16:31], v[68:71], v[224:227], v[16:31]
	s_add_i32 s90, s76, 448
	v_add_u32_e32 v80, s90, v235
	v_add_u32_e32 v83, s90, v236
	v_add_u32_e32 v99, s90, v237
	v_add_u32_e32 v253, s90, v238
	v_add_u32_e32 v254, s90, v100
	v_add_u32_e32 v255, s90, v149
	v_med3_i32 v80, v80, 0, s99
	v_med3_i32 v83, v83, 0, s99
	v_med3_i32 v99, v99, 0, s99
	v_med3_i32 v253, v253, 0, s99
	v_med3_i32 v254, v254, 0, s99
	v_med3_i32 v255, v255, 0, s99
	v_mad_u32_u24 v80, v80, s100, v252
	v_mad_u32_u24 v83, v83, s100, v252
	v_mad_u32_u24 v99, v99, s100, v252
	v_mad_u32_u24 v253, v253, s100, v252
	v_mad_u32_u24 v254, v254, s100, v153
	v_mad_u32_u24 v255, v255, s100, v153
	global_load_dwordx4 v[116:119], v80, s[82:83]
	global_load_dwordx4 v[120:123], v83, s[82:83]
	global_load_dwordx4 v[124:127], v99, s[82:83]
	global_load_dwordx4 v[128:131], v253, s[82:83]
	global_load_dwordx4 v[132:135], v254, s[82:83] offset:768
	global_load_dwordx4 v[136:139], v255, s[82:83] offset:768
	global_load_dwordx4 v[140:143], v254, s[82:83] offset:832
	global_load_dwordx4 v[144:147], v255, s[82:83] offset:832
	ds_read_b64_tr_b16 v[72:73], v231
	ds_read_b64_tr_b16 v[74:75], v231 offset:512
	ds_read_b64_tr_b16 v[76:77], v231 offset:2048
	ds_read_b64_tr_b16 v[78:79], v231 offset:2560
	ds_read_b64_tr_b16 v[220:221], v231 offset:1024
	ds_read_b64_tr_b16 v[222:223], v231 offset:1536
	ds_read_b64_tr_b16 v[224:225], v231 offset:3072
	ds_read_b64_tr_b16 v[226:227], v231 offset:3584
	s_waitcnt vmcnt(8)
	ds_write_b128 v247, v[156:159]
	ds_write_b128 v247, v[160:163] offset:1024
	ds_write_b128 v247, v[164:167] offset:2048
	ds_write_b128 v247, v[168:171] offset:3072
	ds_read_b128 v[156:159], v248
	ds_read_b128 v[160:163], v249
	ds_read_b128 v[164:167], v250
	ds_read_b128 v[168:171], v251
	ds_write_b128 v112, v[172:175]
	ds_write_b128 v112, v[176:179] offset:1024
	ds_write_b128 v112, v[180:183] offset:2048
	ds_write_b128 v112, v[184:187] offset:3072
	v_exp_f32_e32 v32, v32
	v_exp_f32_e32 v33, v33
	v_exp_f32_e32 v34, v34
	v_exp_f32_e32 v35, v35
	v_exp_f32_e32 v36, v36
	v_exp_f32_e32 v37, v37
	s_waitcnt lgkmcnt(4)
	v_mfma_f32_32x32x16_bf16 v[188:203], v[156:159], v[48:51], v[188:203]
	v_exp_f32_e32 v38, v38
	v_exp_f32_e32 v39, v39
	v_mfma_f32_32x32x16_bf16 v[188:203], v[160:163], v[52:55], v[188:203]
	v_exp_f32_e32 v40, v40
	v_exp_f32_e32 v41, v41
	v_exp_f32_e32 v42, v42
	v_mfma_f32_32x32x16_bf16 v[188:203], v[164:167], v[56:59], v[188:203]
	v_exp_f32_e32 v43, v43
	v_exp_f32_e32 v44, v44
	v_mfma_f32_32x32x16_bf16 v[188:203], v[168:171], v[60:63], v[188:203]
	v_exp_f32_e32 v45, v45
	v_exp_f32_e32 v46, v46
	v_exp_f32_e32 v47, v47
	s_add_i32 s90, s76, 384
	v_add_u32_e32 v84, s90, v107
	v_add_u32_e32 v85, 0, v84
	v_add_u32_e32 v86, 1, v84
	v_add_u32_e32 v87, 2, v84
	v_add_u32_e32 v88, 3, v84
	v_cmp_gt_u32_e64 s[30:31], s98, v85
	v_cmp_gt_u32_e64 s[36:37], s98, v86
	v_cmp_gt_u32_e64 s[78:79], s98, v87
	v_cmp_gt_u32_e64 s[50:51], s98, v88
	v_cndmask_b32_e64 v32, 0, v32, s[30:31]
	v_add_u32_e32 v85, 8, v84
	v_cmp_gt_u32_e64 s[30:31], s98, v85
	v_cndmask_b32_e64 v33, 0, v33, s[36:37]
	v_add_u32_e32 v86, 9, v84
	v_cmp_gt_u32_e64 s[36:37], s98, v86
	v_cndmask_b32_e64 v34, 0, v34, s[78:79]
	v_add_u32_e32 v87, 10, v84
	v_cmp_gt_u32_e64 s[78:79], s98, v87
	v_cndmask_b32_e64 v35, 0, v35, s[50:51]
	v_add_u32_e32 v88, 11, v84
	v_cmp_gt_u32_e64 s[50:51], s98, v88
	v_cndmask_b32_e64 v36, 0, v36, s[30:31]
	v_add_u32_e32 v85, 16, v84
	v_cmp_gt_u32_e64 s[30:31], s98, v85
	v_cndmask_b32_e64 v37, 0, v37, s[36:37]
	v_add_u32_e32 v86, 17, v84
	v_cmp_gt_u32_e64 s[36:37], s98, v86
	v_cndmask_b32_e64 v38, 0, v38, s[78:79]
	v_add_u32_e32 v87, 18, v84
	v_cmp_gt_u32_e64 s[78:79], s98, v87
	v_cndmask_b32_e64 v39, 0, v39, s[50:51]
	v_add_u32_e32 v88, 19, v84
	v_cmp_gt_u32_e64 s[50:51], s98, v88
	v_cndmask_b32_e64 v40, 0, v40, s[30:31]
	v_add_u32_e32 v85, 24, v84
	v_cmp_gt_u32_e64 s[30:31], s98, v85
	v_cndmask_b32_e64 v41, 0, v41, s[36:37]
	v_add_u32_e32 v86, 25, v84
	v_cmp_gt_u32_e64 s[36:37], s98, v86
	v_cndmask_b32_e64 v42, 0, v42, s[78:79]
	v_add_u32_e32 v87, 26, v84
	v_cmp_gt_u32_e64 s[78:79], s98, v87
	v_cndmask_b32_e64 v43, 0, v43, s[50:51]
	v_add_u32_e32 v88, 27, v84
	v_cmp_gt_u32_e64 s[50:51], s98, v88
	v_nop
	v_cndmask_b32_e64 v44, 0, v44, s[30:31]
	v_cndmask_b32_e64 v45, 0, v45, s[36:37]
	v_cndmask_b32_e64 v46, 0, v46, s[78:79]
	v_cndmask_b32_e64 v47, 0, v47, s[50:51]
	v_cvt_pk_bf16_f32 v64, v32, v33
	v_cvt_pk_bf16_f32 v65, v34, v35
	v_cvt_pk_bf16_f32 v66, v36, v37
	v_cvt_pk_bf16_f32 v67, v38, v39
	v_cvt_pk_bf16_f32 v68, v40, v41
	v_cvt_pk_bf16_f32 v69, v42, v43
	v_cvt_pk_bf16_f32 v70, v44, v45
	v_cvt_pk_bf16_f32 v71, v46, v47
	v_pk_add_f32 v[232:233], v[232:233], v[32:33]
	v_pk_add_f32 v[232:233], v[232:233], v[34:35]
	v_pk_add_f32 v[232:233], v[232:233], v[36:37]
	v_pk_add_f32 v[232:233], v[232:233], v[38:39]
	v_pk_add_f32 v[232:233], v[232:233], v[40:41]
	v_pk_add_f32 v[232:233], v[232:233], v[42:43]
	v_pk_add_f32 v[232:233], v[232:233], v[44:45]
	v_pk_add_f32 v[232:233], v[232:233], v[46:47]
	ds_read2_b32 v[32:33], v115 offset0:68 offset1:69
	ds_read2_b32 v[34:35], v115 offset0:70 offset1:71
	ds_read2_b32 v[36:37], v115 offset0:76 offset1:77
	ds_read2_b32 v[38:39], v115 offset0:78 offset1:79
	ds_read2_b32 v[40:41], v115 offset0:85 offset1:86
	ds_read2_b32 v[42:43], v115 offset0:87 offset1:88
	ds_read2_b32 v[44:45], v115 offset0:93 offset1:94
	ds_read2_b32 v[46:47], v115 offset0:95 offset1:96
	v_mfma_f32_32x32x16_bf16 v[0:15], v[64:67], v[72:75], v[0:15]
	v_mfma_f32_32x32x16_bf16 v[16:31], v[64:67], v[76:79], v[16:31]
	v_mfma_f32_32x32x16_bf16 v[0:15], v[68:71], v[220:223], v[0:15]
	v_mfma_f32_32x32x16_bf16 v[16:31], v[68:71], v[224:227], v[16:31]
	s_add_i32 s90, s76, 480
	v_add_u32_e32 v80, s90, v235
	v_add_u32_e32 v83, s90, v236
	v_add_u32_e32 v99, s90, v237
	v_add_u32_e32 v253, s90, v238
	v_add_u32_e32 v254, s90, v100
	v_add_u32_e32 v255, s90, v149
	v_med3_i32 v80, v80, 0, s99
	v_med3_i32 v83, v83, 0, s99
	v_med3_i32 v99, v99, 0, s99
	v_med3_i32 v253, v253, 0, s99
	v_med3_i32 v254, v254, 0, s99
	v_med3_i32 v255, v255, 0, s99
	v_mad_u32_u24 v80, v80, s100, v252
	v_mad_u32_u24 v83, v83, s100, v252
	v_mad_u32_u24 v99, v99, s100, v252
	v_mad_u32_u24 v253, v253, s100, v252
	v_mad_u32_u24 v254, v254, s100, v153
	v_mad_u32_u24 v255, v255, s100, v153
	global_load_dwordx4 v[156:159], v80, s[82:83]
	global_load_dwordx4 v[160:163], v83, s[82:83]
	global_load_dwordx4 v[164:167], v99, s[82:83]
	global_load_dwordx4 v[168:171], v253, s[82:83]
	global_load_dwordx4 v[172:175], v254, s[82:83] offset:768
	global_load_dwordx4 v[176:179], v255, s[82:83] offset:768
	global_load_dwordx4 v[180:183], v254, s[82:83] offset:832
	global_load_dwordx4 v[184:187], v255, s[82:83] offset:832
	ds_read_b64_tr_b16 v[72:73], v231
	ds_read_b64_tr_b16 v[74:75], v231 offset:512
	ds_read_b64_tr_b16 v[76:77], v231 offset:2048
	ds_read_b64_tr_b16 v[78:79], v231 offset:2560
	ds_read_b64_tr_b16 v[220:221], v231 offset:1024
	ds_read_b64_tr_b16 v[222:223], v231 offset:1536
	ds_read_b64_tr_b16 v[224:225], v231 offset:3072
	ds_read_b64_tr_b16 v[226:227], v231 offset:3584
	s_waitcnt vmcnt(8)
	ds_write_b128 v247, v[116:119]
	ds_write_b128 v247, v[120:123] offset:1024
	ds_write_b128 v247, v[124:127] offset:2048
	ds_write_b128 v247, v[128:131] offset:3072
	ds_read_b128 v[116:119], v248
	ds_read_b128 v[120:123], v249
	ds_read_b128 v[124:127], v250
	ds_read_b128 v[128:131], v251
	ds_write_b128 v112, v[132:135]
	ds_write_b128 v112, v[136:139] offset:1024
	ds_write_b128 v112, v[140:143] offset:2048
	ds_write_b128 v112, v[144:147] offset:3072
	v_exp_f32_e32 v188, v188
	v_exp_f32_e32 v189, v189
	v_exp_f32_e32 v190, v190
	v_exp_f32_e32 v191, v191
	v_exp_f32_e32 v192, v192
	v_exp_f32_e32 v193, v193
	s_waitcnt lgkmcnt(4)
	v_mfma_f32_32x32x16_bf16 v[32:47], v[116:119], v[48:51], v[32:47]
	v_exp_f32_e32 v194, v194
	v_exp_f32_e32 v195, v195
	v_mfma_f32_32x32x16_bf16 v[32:47], v[120:123], v[52:55], v[32:47]
	v_exp_f32_e32 v196, v196
	v_exp_f32_e32 v197, v197
	v_exp_f32_e32 v198, v198
	v_mfma_f32_32x32x16_bf16 v[32:47], v[124:127], v[56:59], v[32:47]
	v_exp_f32_e32 v199, v199
	v_exp_f32_e32 v200, v200
	v_mfma_f32_32x32x16_bf16 v[32:47], v[128:131], v[60:63], v[32:47]
	v_exp_f32_e32 v201, v201
	v_exp_f32_e32 v202, v202
	v_exp_f32_e32 v203, v203
	s_add_i32 s90, s76, 416
	v_add_u32_e32 v84, s90, v107
	v_add_u32_e32 v85, 0, v84
	v_add_u32_e32 v86, 1, v84
	v_add_u32_e32 v87, 2, v84
	v_add_u32_e32 v88, 3, v84
	v_cmp_gt_u32_e64 s[30:31], s98, v85
	v_cmp_gt_u32_e64 s[36:37], s98, v86
	v_cmp_gt_u32_e64 s[78:79], s98, v87
	v_cmp_gt_u32_e64 s[50:51], s98, v88
	v_cndmask_b32_e64 v188, 0, v188, s[30:31]
	v_add_u32_e32 v85, 8, v84
	v_cmp_gt_u32_e64 s[30:31], s98, v85
	v_cndmask_b32_e64 v189, 0, v189, s[36:37]
	v_add_u32_e32 v86, 9, v84
	v_cmp_gt_u32_e64 s[36:37], s98, v86
	v_cndmask_b32_e64 v190, 0, v190, s[78:79]
	v_add_u32_e32 v87, 10, v84
	v_cmp_gt_u32_e64 s[78:79], s98, v87
	v_cndmask_b32_e64 v191, 0, v191, s[50:51]
	v_add_u32_e32 v88, 11, v84
	v_cmp_gt_u32_e64 s[50:51], s98, v88
	v_cndmask_b32_e64 v192, 0, v192, s[30:31]
	v_add_u32_e32 v85, 16, v84
	v_cmp_gt_u32_e64 s[30:31], s98, v85
	v_cndmask_b32_e64 v193, 0, v193, s[36:37]
	v_add_u32_e32 v86, 17, v84
	v_cmp_gt_u32_e64 s[36:37], s98, v86
	v_cndmask_b32_e64 v194, 0, v194, s[78:79]
	v_add_u32_e32 v87, 18, v84
	v_cmp_gt_u32_e64 s[78:79], s98, v87
	v_cndmask_b32_e64 v195, 0, v195, s[50:51]
	v_add_u32_e32 v88, 19, v84
	v_cmp_gt_u32_e64 s[50:51], s98, v88
	v_cndmask_b32_e64 v196, 0, v196, s[30:31]
	v_add_u32_e32 v85, 24, v84
	v_cmp_gt_u32_e64 s[30:31], s98, v85
	v_cndmask_b32_e64 v197, 0, v197, s[36:37]
	v_add_u32_e32 v86, 25, v84
	v_cmp_gt_u32_e64 s[36:37], s98, v86
	v_cndmask_b32_e64 v198, 0, v198, s[78:79]
	v_add_u32_e32 v87, 26, v84
	v_cmp_gt_u32_e64 s[78:79], s98, v87
	v_cndmask_b32_e64 v199, 0, v199, s[50:51]
	v_add_u32_e32 v88, 27, v84
	v_cmp_gt_u32_e64 s[50:51], s98, v88
	v_nop
	v_cndmask_b32_e64 v200, 0, v200, s[30:31]
	v_cndmask_b32_e64 v201, 0, v201, s[36:37]
	v_cndmask_b32_e64 v202, 0, v202, s[78:79]
	v_cndmask_b32_e64 v203, 0, v203, s[50:51]
	v_cvt_pk_bf16_f32 v64, v188, v189
	v_cvt_pk_bf16_f32 v65, v190, v191
	v_cvt_pk_bf16_f32 v66, v192, v193
	v_cvt_pk_bf16_f32 v67, v194, v195
	v_cvt_pk_bf16_f32 v68, v196, v197
	v_cvt_pk_bf16_f32 v69, v198, v199
	v_cvt_pk_bf16_f32 v70, v200, v201
	v_cvt_pk_bf16_f32 v71, v202, v203
	v_pk_add_f32 v[232:233], v[232:233], v[188:189]
	v_pk_add_f32 v[232:233], v[232:233], v[190:191]
	v_pk_add_f32 v[232:233], v[232:233], v[192:193]
	v_pk_add_f32 v[232:233], v[232:233], v[194:195]
	v_pk_add_f32 v[232:233], v[232:233], v[196:197]
	v_pk_add_f32 v[232:233], v[232:233], v[198:199]
	v_pk_add_f32 v[232:233], v[232:233], v[200:201]
	v_pk_add_f32 v[232:233], v[232:233], v[202:203]
	ds_read2_b32 v[188:189], v115 offset0:102 offset1:103
	ds_read2_b32 v[190:191], v115 offset0:104 offset1:105
	ds_read2_b32 v[192:193], v115 offset0:110 offset1:111
	ds_read2_b32 v[194:195], v115 offset0:112 offset1:113
	ds_read2_b32 v[196:197], v115 offset0:119 offset1:120
	ds_read2_b32 v[198:199], v115 offset0:121 offset1:122
	ds_read2_b32 v[200:201], v115 offset0:127 offset1:128
	ds_read2_b32 v[202:203], v115 offset0:129 offset1:130
	v_mfma_f32_32x32x16_bf16 v[0:15], v[64:67], v[72:75], v[0:15]
	v_mfma_f32_32x32x16_bf16 v[16:31], v[64:67], v[76:79], v[16:31]
	v_mfma_f32_32x32x16_bf16 v[0:15], v[68:71], v[220:223], v[0:15]
	v_mfma_f32_32x32x16_bf16 v[16:31], v[68:71], v[224:227], v[16:31]
	s_add_i32 s90, s76, 512
	v_add_u32_e32 v80, s90, v235
	v_add_u32_e32 v83, s90, v236
	v_add_u32_e32 v99, s90, v237
	v_add_u32_e32 v253, s90, v238
	v_add_u32_e32 v254, s90, v100
	v_add_u32_e32 v255, s90, v149
	v_med3_i32 v80, v80, 0, s99
	v_med3_i32 v83, v83, 0, s99
	v_med3_i32 v99, v99, 0, s99
	v_med3_i32 v253, v253, 0, s99
	v_med3_i32 v254, v254, 0, s99
	v_med3_i32 v255, v255, 0, s99
	v_mad_u32_u24 v80, v80, s100, v252
	v_mad_u32_u24 v83, v83, s100, v252
	v_mad_u32_u24 v99, v99, s100, v252
	v_mad_u32_u24 v253, v253, s100, v252
	v_mad_u32_u24 v254, v254, s100, v153
	v_mad_u32_u24 v255, v255, s100, v153
	global_load_dwordx4 v[116:119], v80, s[82:83]
	global_load_dwordx4 v[120:123], v83, s[82:83]
	global_load_dwordx4 v[124:127], v99, s[82:83]
	global_load_dwordx4 v[128:131], v253, s[82:83]
	global_load_dwordx4 v[132:135], v254, s[82:83] offset:768
	global_load_dwordx4 v[136:139], v255, s[82:83] offset:768
	global_load_dwordx4 v[140:143], v254, s[82:83] offset:832
	global_load_dwordx4 v[144:147], v255, s[82:83] offset:832
	ds_read_b64_tr_b16 v[72:73], v231
	ds_read_b64_tr_b16 v[74:75], v231 offset:512
	ds_read_b64_tr_b16 v[76:77], v231 offset:2048
	ds_read_b64_tr_b16 v[78:79], v231 offset:2560
	ds_read_b64_tr_b16 v[220:221], v231 offset:1024
	ds_read_b64_tr_b16 v[222:223], v231 offset:1536
	ds_read_b64_tr_b16 v[224:225], v231 offset:3072
	ds_read_b64_tr_b16 v[226:227], v231 offset:3584
	s_waitcnt vmcnt(8)
	ds_write_b128 v247, v[156:159]
	ds_write_b128 v247, v[160:163] offset:1024
	ds_write_b128 v247, v[164:167] offset:2048
	ds_write_b128 v247, v[168:171] offset:3072
	ds_read_b128 v[156:159], v248
	ds_read_b128 v[160:163], v249
	ds_read_b128 v[164:167], v250
	ds_read_b128 v[168:171], v251
	ds_write_b128 v112, v[172:175]
	ds_write_b128 v112, v[176:179] offset:1024
	ds_write_b128 v112, v[180:183] offset:2048
	ds_write_b128 v112, v[184:187] offset:3072
	v_exp_f32_e32 v32, v32
	v_exp_f32_e32 v33, v33
	v_exp_f32_e32 v34, v34
	v_exp_f32_e32 v35, v35
	v_exp_f32_e32 v36, v36
	v_exp_f32_e32 v37, v37
	s_waitcnt lgkmcnt(4)
	v_mfma_f32_32x32x16_bf16 v[188:203], v[156:159], v[48:51], v[188:203]
	v_exp_f32_e32 v38, v38
	v_exp_f32_e32 v39, v39
	v_mfma_f32_32x32x16_bf16 v[188:203], v[160:163], v[52:55], v[188:203]
	v_exp_f32_e32 v40, v40
	v_exp_f32_e32 v41, v41
	v_exp_f32_e32 v42, v42
	v_mfma_f32_32x32x16_bf16 v[188:203], v[164:167], v[56:59], v[188:203]
	v_exp_f32_e32 v43, v43
	v_exp_f32_e32 v44, v44
	v_mfma_f32_32x32x16_bf16 v[188:203], v[168:171], v[60:63], v[188:203]
	v_exp_f32_e32 v45, v45
	v_exp_f32_e32 v46, v46
	v_exp_f32_e32 v47, v47
	s_add_i32 s90, s76, 448
	v_add_u32_e32 v84, s90, v107
	v_add_u32_e32 v85, 0, v84
	v_add_u32_e32 v86, 1, v84
	v_add_u32_e32 v87, 2, v84
	v_add_u32_e32 v88, 3, v84
	v_cmp_gt_u32_e64 s[30:31], s98, v85
	v_cmp_gt_u32_e64 s[36:37], s98, v86
	v_cmp_gt_u32_e64 s[78:79], s98, v87
	v_cmp_gt_u32_e64 s[50:51], s98, v88
	v_cndmask_b32_e64 v32, 0, v32, s[30:31]
	v_add_u32_e32 v85, 8, v84
	v_cmp_gt_u32_e64 s[30:31], s98, v85
	v_cndmask_b32_e64 v33, 0, v33, s[36:37]
	v_add_u32_e32 v86, 9, v84
	v_cmp_gt_u32_e64 s[36:37], s98, v86
	v_cndmask_b32_e64 v34, 0, v34, s[78:79]
	v_add_u32_e32 v87, 10, v84
	v_cmp_gt_u32_e64 s[78:79], s98, v87
	v_cndmask_b32_e64 v35, 0, v35, s[50:51]
	v_add_u32_e32 v88, 11, v84
	v_cmp_gt_u32_e64 s[50:51], s98, v88
	v_cndmask_b32_e64 v36, 0, v36, s[30:31]
	v_add_u32_e32 v85, 16, v84
	v_cmp_gt_u32_e64 s[30:31], s98, v85
	v_cndmask_b32_e64 v37, 0, v37, s[36:37]
	v_add_u32_e32 v86, 17, v84
	v_cmp_gt_u32_e64 s[36:37], s98, v86
	v_cndmask_b32_e64 v38, 0, v38, s[78:79]
	v_add_u32_e32 v87, 18, v84
	v_cmp_gt_u32_e64 s[78:79], s98, v87
	v_cndmask_b32_e64 v39, 0, v39, s[50:51]
	v_add_u32_e32 v88, 19, v84
	v_cmp_gt_u32_e64 s[50:51], s98, v88
	v_cndmask_b32_e64 v40, 0, v40, s[30:31]
	v_add_u32_e32 v85, 24, v84
	v_cmp_gt_u32_e64 s[30:31], s98, v85
	v_cndmask_b32_e64 v41, 0, v41, s[36:37]
	v_add_u32_e32 v86, 25, v84
	v_cmp_gt_u32_e64 s[36:37], s98, v86
	v_cndmask_b32_e64 v42, 0, v42, s[78:79]
	v_add_u32_e32 v87, 26, v84
	v_cmp_gt_u32_e64 s[78:79], s98, v87
	v_cndmask_b32_e64 v43, 0, v43, s[50:51]
	v_add_u32_e32 v88, 27, v84
	v_cmp_gt_u32_e64 s[50:51], s98, v88
	v_nop
	v_cndmask_b32_e64 v44, 0, v44, s[30:31]
	v_cndmask_b32_e64 v45, 0, v45, s[36:37]
	v_cndmask_b32_e64 v46, 0, v46, s[78:79]
	v_cndmask_b32_e64 v47, 0, v47, s[50:51]
	v_cvt_pk_bf16_f32 v64, v32, v33
	v_cvt_pk_bf16_f32 v65, v34, v35
	v_cvt_pk_bf16_f32 v66, v36, v37
	v_cvt_pk_bf16_f32 v67, v38, v39
	v_cvt_pk_bf16_f32 v68, v40, v41
	v_cvt_pk_bf16_f32 v69, v42, v43
	v_cvt_pk_bf16_f32 v70, v44, v45
	v_cvt_pk_bf16_f32 v71, v46, v47
	v_pk_add_f32 v[232:233], v[232:233], v[32:33]
	v_pk_add_f32 v[232:233], v[232:233], v[34:35]
	v_pk_add_f32 v[232:233], v[232:233], v[36:37]
	v_pk_add_f32 v[232:233], v[232:233], v[38:39]
	v_pk_add_f32 v[232:233], v[232:233], v[40:41]
	v_pk_add_f32 v[232:233], v[232:233], v[42:43]
	v_pk_add_f32 v[232:233], v[232:233], v[44:45]
	v_pk_add_f32 v[232:233], v[232:233], v[46:47]
	ds_read2_b32 v[32:33], v115 offset0:136 offset1:137
	ds_read2_b32 v[34:35], v115 offset0:138 offset1:139
	ds_read2_b32 v[36:37], v115 offset0:144 offset1:145
	ds_read2_b32 v[38:39], v115 offset0:146 offset1:147
	ds_read2_b32 v[40:41], v115 offset0:153 offset1:154
	ds_read2_b32 v[42:43], v115 offset0:155 offset1:156
	ds_read2_b32 v[44:45], v115 offset0:161 offset1:162
	ds_read2_b32 v[46:47], v115 offset0:163 offset1:164
	v_mfma_f32_32x32x16_bf16 v[0:15], v[64:67], v[72:75], v[0:15]
	v_mfma_f32_32x32x16_bf16 v[16:31], v[64:67], v[76:79], v[16:31]
	v_mfma_f32_32x32x16_bf16 v[0:15], v[68:71], v[220:223], v[0:15]
	v_mfma_f32_32x32x16_bf16 v[16:31], v[68:71], v[224:227], v[16:31]
	s_add_i32 s90, s76, 544
	v_add_u32_e32 v80, s90, v235
	v_add_u32_e32 v83, s90, v236
	v_add_u32_e32 v99, s90, v237
	v_add_u32_e32 v253, s90, v238
	v_add_u32_e32 v254, s90, v100
	v_add_u32_e32 v255, s90, v149
	v_med3_i32 v80, v80, 0, s99
	v_med3_i32 v83, v83, 0, s99
	v_med3_i32 v99, v99, 0, s99
	v_med3_i32 v253, v253, 0, s99
	v_med3_i32 v254, v254, 0, s99
	v_med3_i32 v255, v255, 0, s99
	v_mad_u32_u24 v80, v80, s100, v252
	v_mad_u32_u24 v83, v83, s100, v252
	v_mad_u32_u24 v99, v99, s100, v252
	v_mad_u32_u24 v253, v253, s100, v252
	v_mad_u32_u24 v254, v254, s100, v153
	v_mad_u32_u24 v255, v255, s100, v153
	global_load_dwordx4 v[156:159], v80, s[82:83]
	global_load_dwordx4 v[160:163], v83, s[82:83]
	global_load_dwordx4 v[164:167], v99, s[82:83]
	global_load_dwordx4 v[168:171], v253, s[82:83]
	global_load_dwordx4 v[172:175], v254, s[82:83] offset:768
	global_load_dwordx4 v[176:179], v255, s[82:83] offset:768
	global_load_dwordx4 v[180:183], v254, s[82:83] offset:832
	global_load_dwordx4 v[184:187], v255, s[82:83] offset:832
	ds_read_b64_tr_b16 v[72:73], v231
	ds_read_b64_tr_b16 v[74:75], v231 offset:512
	ds_read_b64_tr_b16 v[76:77], v231 offset:2048
	ds_read_b64_tr_b16 v[78:79], v231 offset:2560
	ds_read_b64_tr_b16 v[220:221], v231 offset:1024
	ds_read_b64_tr_b16 v[222:223], v231 offset:1536
	ds_read_b64_tr_b16 v[224:225], v231 offset:3072
	ds_read_b64_tr_b16 v[226:227], v231 offset:3584
	s_waitcnt vmcnt(8)
	ds_write_b128 v247, v[116:119]
	ds_write_b128 v247, v[120:123] offset:1024
	ds_write_b128 v247, v[124:127] offset:2048
	ds_write_b128 v247, v[128:131] offset:3072
	ds_read_b128 v[116:119], v248
	ds_read_b128 v[120:123], v249
	ds_read_b128 v[124:127], v250
	ds_read_b128 v[128:131], v251
	ds_write_b128 v112, v[132:135]
	ds_write_b128 v112, v[136:139] offset:1024
	ds_write_b128 v112, v[140:143] offset:2048
	ds_write_b128 v112, v[144:147] offset:3072
	v_exp_f32_e32 v188, v188
	v_exp_f32_e32 v189, v189
	v_exp_f32_e32 v190, v190
	v_exp_f32_e32 v191, v191
	v_exp_f32_e32 v192, v192
	v_exp_f32_e32 v193, v193
	s_waitcnt lgkmcnt(4)
	v_mfma_f32_32x32x16_bf16 v[32:47], v[116:119], v[48:51], v[32:47]
	v_exp_f32_e32 v194, v194
	v_exp_f32_e32 v195, v195
	v_mfma_f32_32x32x16_bf16 v[32:47], v[120:123], v[52:55], v[32:47]
	v_exp_f32_e32 v196, v196
	v_exp_f32_e32 v197, v197
	v_exp_f32_e32 v198, v198
	v_mfma_f32_32x32x16_bf16 v[32:47], v[124:127], v[56:59], v[32:47]
	v_exp_f32_e32 v199, v199
	v_exp_f32_e32 v200, v200
	v_mfma_f32_32x32x16_bf16 v[32:47], v[128:131], v[60:63], v[32:47]
	v_exp_f32_e32 v201, v201
	v_exp_f32_e32 v202, v202
	v_exp_f32_e32 v203, v203
	s_add_i32 s90, s76, 480
	v_add_u32_e32 v84, s90, v107
	v_add_u32_e32 v85, 0, v84
	v_add_u32_e32 v86, 1, v84
	v_add_u32_e32 v87, 2, v84
	v_add_u32_e32 v88, 3, v84
	v_cmp_gt_u32_e64 s[30:31], s98, v85
	v_cmp_gt_u32_e64 s[36:37], s98, v86
	v_cmp_gt_u32_e64 s[78:79], s98, v87
	v_cmp_gt_u32_e64 s[50:51], s98, v88
	v_cndmask_b32_e64 v188, 0, v188, s[30:31]
	v_add_u32_e32 v85, 8, v84
	v_cmp_gt_u32_e64 s[30:31], s98, v85
	v_cndmask_b32_e64 v189, 0, v189, s[36:37]
	v_add_u32_e32 v86, 9, v84
	v_cmp_gt_u32_e64 s[36:37], s98, v86
	v_cndmask_b32_e64 v190, 0, v190, s[78:79]
	v_add_u32_e32 v87, 10, v84
	v_cmp_gt_u32_e64 s[78:79], s98, v87
	v_cndmask_b32_e64 v191, 0, v191, s[50:51]
	v_add_u32_e32 v88, 11, v84
	v_cmp_gt_u32_e64 s[50:51], s98, v88
	v_cndmask_b32_e64 v192, 0, v192, s[30:31]
	v_add_u32_e32 v85, 16, v84
	v_cmp_gt_u32_e64 s[30:31], s98, v85
	v_cndmask_b32_e64 v193, 0, v193, s[36:37]
	v_add_u32_e32 v86, 17, v84
	v_cmp_gt_u32_e64 s[36:37], s98, v86
	v_cndmask_b32_e64 v194, 0, v194, s[78:79]
	v_add_u32_e32 v87, 18, v84
	v_cmp_gt_u32_e64 s[78:79], s98, v87
	v_cndmask_b32_e64 v195, 0, v195, s[50:51]
	v_add_u32_e32 v88, 19, v84
	v_cmp_gt_u32_e64 s[50:51], s98, v88
	v_cndmask_b32_e64 v196, 0, v196, s[30:31]
	v_add_u32_e32 v85, 24, v84
	v_cmp_gt_u32_e64 s[30:31], s98, v85
	v_cndmask_b32_e64 v197, 0, v197, s[36:37]
	v_add_u32_e32 v86, 25, v84
	v_cmp_gt_u32_e64 s[36:37], s98, v86
	v_cndmask_b32_e64 v198, 0, v198, s[78:79]
	v_add_u32_e32 v87, 26, v84
	v_cmp_gt_u32_e64 s[78:79], s98, v87
	v_cndmask_b32_e64 v199, 0, v199, s[50:51]
	v_add_u32_e32 v88, 27, v84
	v_cmp_gt_u32_e64 s[50:51], s98, v88
	v_nop
	v_cndmask_b32_e64 v200, 0, v200, s[30:31]
	v_cndmask_b32_e64 v201, 0, v201, s[36:37]
	v_cndmask_b32_e64 v202, 0, v202, s[78:79]
	v_cndmask_b32_e64 v203, 0, v203, s[50:51]
	v_cvt_pk_bf16_f32 v64, v188, v189
	v_cvt_pk_bf16_f32 v65, v190, v191
	v_cvt_pk_bf16_f32 v66, v192, v193
	v_cvt_pk_bf16_f32 v67, v194, v195
	v_cvt_pk_bf16_f32 v68, v196, v197
	v_cvt_pk_bf16_f32 v69, v198, v199
	v_cvt_pk_bf16_f32 v70, v200, v201
	v_cvt_pk_bf16_f32 v71, v202, v203
	v_pk_add_f32 v[232:233], v[232:233], v[188:189]
	v_pk_add_f32 v[232:233], v[232:233], v[190:191]
	v_pk_add_f32 v[232:233], v[232:233], v[192:193]
	v_pk_add_f32 v[232:233], v[232:233], v[194:195]
	v_pk_add_f32 v[232:233], v[232:233], v[196:197]
	v_pk_add_f32 v[232:233], v[232:233], v[198:199]
	v_pk_add_f32 v[232:233], v[232:233], v[200:201]
	v_pk_add_f32 v[232:233], v[232:233], v[202:203]
	ds_read2_b32 v[188:189], v115 offset0:170 offset1:171
	ds_read2_b32 v[190:191], v115 offset0:172 offset1:173
	ds_read2_b32 v[192:193], v115 offset0:178 offset1:179
	ds_read2_b32 v[194:195], v115 offset0:180 offset1:181
	ds_read2_b32 v[196:197], v115 offset0:187 offset1:188
	ds_read2_b32 v[198:199], v115 offset0:189 offset1:190
	ds_read2_b32 v[200:201], v115 offset0:195 offset1:196
	ds_read2_b32 v[202:203], v115 offset0:197 offset1:198
	v_mfma_f32_32x32x16_bf16 v[0:15], v[64:67], v[72:75], v[0:15]
	v_mfma_f32_32x32x16_bf16 v[16:31], v[64:67], v[76:79], v[16:31]
	v_mfma_f32_32x32x16_bf16 v[0:15], v[68:71], v[220:223], v[0:15]
	v_mfma_f32_32x32x16_bf16 v[16:31], v[68:71], v[224:227], v[16:31]
	s_add_i32 s90, s76, -256
	v_add_u32_e32 v80, s90, v239
	v_add_u32_e32 v83, s90, v240
	v_add_u32_e32 v99, s90, v241
	v_add_u32_e32 v253, s90, v242
	v_add_u32_e32 v254, s90, v101
	v_add_u32_e32 v255, s90, v150
	v_med3_i32 v80, v80, 0, s99
	v_med3_i32 v83, v83, 0, s99
	v_med3_i32 v99, v99, 0, s99
	v_med3_i32 v253, v253, 0, s99
	v_med3_i32 v254, v254, 0, s99
	v_med3_i32 v255, v255, 0, s99
	v_mad_u32_u24 v80, v80, s100, v252
	v_mad_u32_u24 v83, v83, s100, v252
	v_mad_u32_u24 v99, v99, s100, v252
	v_mad_u32_u24 v253, v253, s100, v252
	v_mad_u32_u24 v254, v254, s100, v153
	v_mad_u32_u24 v255, v255, s100, v153
	global_load_dwordx4 v[116:119], v80, s[82:83]
	global_load_dwordx4 v[120:123], v83, s[82:83]
	global_load_dwordx4 v[124:127], v99, s[82:83]
	global_load_dwordx4 v[128:131], v253, s[82:83]
	global_load_dwordx4 v[132:135], v254, s[82:83] offset:768
	global_load_dwordx4 v[136:139], v255, s[82:83] offset:768
	global_load_dwordx4 v[140:143], v254, s[82:83] offset:832
	global_load_dwordx4 v[144:147], v255, s[82:83] offset:832
	ds_read_b64_tr_b16 v[72:73], v231
	ds_read_b64_tr_b16 v[74:75], v231 offset:512
	ds_read_b64_tr_b16 v[76:77], v231 offset:2048
	ds_read_b64_tr_b16 v[78:79], v231 offset:2560
	ds_read_b64_tr_b16 v[220:221], v231 offset:1024
	ds_read_b64_tr_b16 v[222:223], v231 offset:1536
	ds_read_b64_tr_b16 v[224:225], v231 offset:3072
	ds_read_b64_tr_b16 v[226:227], v231 offset:3584
	s_waitcnt vmcnt(8)
	ds_write_b128 v247, v[156:159]
	ds_write_b128 v247, v[160:163] offset:1024
	ds_write_b128 v247, v[164:167] offset:2048
	ds_write_b128 v247, v[168:171] offset:3072
	ds_read_b128 v[156:159], v248
	ds_read_b128 v[160:163], v249
	ds_read_b128 v[164:167], v250
	ds_read_b128 v[168:171], v251
	ds_write_b128 v112, v[172:175]
	ds_write_b128 v112, v[176:179] offset:1024
	ds_write_b128 v112, v[180:183] offset:2048
	ds_write_b128 v112, v[184:187] offset:3072
	v_exp_f32_e32 v32, v32
	v_exp_f32_e32 v33, v33
	v_exp_f32_e32 v34, v34
	v_exp_f32_e32 v35, v35
	v_exp_f32_e32 v36, v36
	v_exp_f32_e32 v37, v37
	s_waitcnt lgkmcnt(4)
	v_mfma_f32_32x32x16_bf16 v[188:203], v[156:159], v[48:51], v[188:203]
	v_exp_f32_e32 v38, v38
	v_exp_f32_e32 v39, v39
	v_mfma_f32_32x32x16_bf16 v[188:203], v[160:163], v[52:55], v[188:203]
	v_exp_f32_e32 v40, v40
	v_exp_f32_e32 v41, v41
	v_exp_f32_e32 v42, v42
	v_mfma_f32_32x32x16_bf16 v[188:203], v[164:167], v[56:59], v[188:203]
	v_exp_f32_e32 v43, v43
	v_exp_f32_e32 v44, v44
	v_mfma_f32_32x32x16_bf16 v[188:203], v[168:171], v[60:63], v[188:203]
	v_exp_f32_e32 v45, v45
	v_exp_f32_e32 v46, v46
	v_exp_f32_e32 v47, v47
	s_add_i32 s90, s76, 512
	v_add_u32_e32 v84, s90, v107
	v_add_u32_e32 v85, 0, v84
	v_add_u32_e32 v86, 1, v84
	v_add_u32_e32 v87, 2, v84
	v_add_u32_e32 v88, 3, v84
	v_cmp_gt_u32_e64 s[30:31], s98, v85
	v_cmp_gt_u32_e64 s[36:37], s98, v86
	v_cmp_gt_u32_e64 s[78:79], s98, v87
	v_cmp_gt_u32_e64 s[50:51], s98, v88
	v_cndmask_b32_e64 v32, 0, v32, s[30:31]
	v_add_u32_e32 v85, 8, v84
	v_cmp_gt_u32_e64 s[30:31], s98, v85
	v_cndmask_b32_e64 v33, 0, v33, s[36:37]
	v_add_u32_e32 v86, 9, v84
	v_cmp_gt_u32_e64 s[36:37], s98, v86
	v_cndmask_b32_e64 v34, 0, v34, s[78:79]
	v_add_u32_e32 v87, 10, v84
	v_cmp_gt_u32_e64 s[78:79], s98, v87
	v_cndmask_b32_e64 v35, 0, v35, s[50:51]
	v_add_u32_e32 v88, 11, v84
	v_cmp_gt_u32_e64 s[50:51], s98, v88
	v_cndmask_b32_e64 v36, 0, v36, s[30:31]
	v_add_u32_e32 v85, 16, v84
	v_cmp_gt_u32_e64 s[30:31], s98, v85
	v_cndmask_b32_e64 v37, 0, v37, s[36:37]
	v_add_u32_e32 v86, 17, v84
	v_cmp_gt_u32_e64 s[36:37], s98, v86
	v_cndmask_b32_e64 v38, 0, v38, s[78:79]
	v_add_u32_e32 v87, 18, v84
	v_cmp_gt_u32_e64 s[78:79], s98, v87
	v_cndmask_b32_e64 v39, 0, v39, s[50:51]
	v_add_u32_e32 v88, 19, v84
	v_cmp_gt_u32_e64 s[50:51], s98, v88
	v_cndmask_b32_e64 v40, 0, v40, s[30:31]
	v_add_u32_e32 v85, 24, v84
	v_cmp_gt_u32_e64 s[30:31], s98, v85
	v_cndmask_b32_e64 v41, 0, v41, s[36:37]
	v_add_u32_e32 v86, 25, v84
	v_cmp_gt_u32_e64 s[36:37], s98, v86
	v_cndmask_b32_e64 v42, 0, v42, s[78:79]
	v_add_u32_e32 v87, 26, v84
	v_cmp_gt_u32_e64 s[78:79], s98, v87
	v_cndmask_b32_e64 v43, 0, v43, s[50:51]
	v_add_u32_e32 v88, 27, v84
	v_cmp_gt_u32_e64 s[50:51], s98, v88
	v_nop
	v_cndmask_b32_e64 v44, 0, v44, s[30:31]
	v_cndmask_b32_e64 v45, 0, v45, s[36:37]
	v_cndmask_b32_e64 v46, 0, v46, s[78:79]
	v_cndmask_b32_e64 v47, 0, v47, s[50:51]
	v_cvt_pk_bf16_f32 v64, v32, v33
	v_cvt_pk_bf16_f32 v65, v34, v35
	v_cvt_pk_bf16_f32 v66, v36, v37
	v_cvt_pk_bf16_f32 v67, v38, v39
	v_cvt_pk_bf16_f32 v68, v40, v41
	v_cvt_pk_bf16_f32 v69, v42, v43
	v_cvt_pk_bf16_f32 v70, v44, v45
	v_cvt_pk_bf16_f32 v71, v46, v47
	v_pk_add_f32 v[232:233], v[232:233], v[32:33]
	v_pk_add_f32 v[232:233], v[232:233], v[34:35]
	v_pk_add_f32 v[232:233], v[232:233], v[36:37]
	v_pk_add_f32 v[232:233], v[232:233], v[38:39]
	v_pk_add_f32 v[232:233], v[232:233], v[40:41]
	v_pk_add_f32 v[232:233], v[232:233], v[42:43]
	v_pk_add_f32 v[232:233], v[232:233], v[44:45]
	v_pk_add_f32 v[232:233], v[232:233], v[46:47]
	v_mov_b32_e32 v115, v229
	ds_read2_b32 v[32:33], v115 offset0:0 offset1:1
	ds_read2_b32 v[34:35], v115 offset0:2 offset1:3
	ds_read2_b32 v[36:37], v115 offset0:8 offset1:9
	ds_read2_b32 v[38:39], v115 offset0:10 offset1:11
	ds_read2_b32 v[40:41], v115 offset0:16 offset1:17
	ds_read2_b32 v[42:43], v115 offset0:18 offset1:19
	ds_read2_b32 v[44:45], v115 offset0:24 offset1:25
	ds_read2_b32 v[46:47], v115 offset0:26 offset1:27
	v_mfma_f32_32x32x16_bf16 v[0:15], v[64:67], v[72:75], v[0:15]
	v_mfma_f32_32x32x16_bf16 v[16:31], v[64:67], v[76:79], v[16:31]
	v_mfma_f32_32x32x16_bf16 v[0:15], v[68:71], v[220:223], v[0:15]
	v_mfma_f32_32x32x16_bf16 v[16:31], v[68:71], v[224:227], v[16:31]
	s_add_i32 s90, s76, -128
	v_add_u32_e32 v80, s90, v239
	v_add_u32_e32 v83, s90, v240
	v_add_u32_e32 v99, s90, v241
	v_add_u32_e32 v253, s90, v242
	v_add_u32_e32 v254, s90, v101
	v_add_u32_e32 v255, s90, v150
	v_med3_i32 v80, v80, 0, s99
	v_med3_i32 v83, v83, 0, s99
	v_med3_i32 v99, v99, 0, s99
	v_med3_i32 v253, v253, 0, s99
	v_med3_i32 v254, v254, 0, s99
	v_med3_i32 v255, v255, 0, s99
	v_mad_u32_u24 v80, v80, s100, v252
	v_mad_u32_u24 v83, v83, s100, v252
	v_mad_u32_u24 v99, v99, s100, v252
	v_mad_u32_u24 v253, v253, s100, v252
	v_mad_u32_u24 v254, v254, s100, v153
	v_mad_u32_u24 v255, v255, s100, v153
	global_load_dwordx4 v[156:159], v80, s[82:83]
	global_load_dwordx4 v[160:163], v83, s[82:83]
	global_load_dwordx4 v[164:167], v99, s[82:83]
	global_load_dwordx4 v[168:171], v253, s[82:83]
	global_load_dwordx4 v[172:175], v254, s[82:83] offset:768
	global_load_dwordx4 v[176:179], v255, s[82:83] offset:768
	global_load_dwordx4 v[180:183], v254, s[82:83] offset:832
	global_load_dwordx4 v[184:187], v255, s[82:83] offset:832
	ds_read_b64_tr_b16 v[72:73], v231
	ds_read_b64_tr_b16 v[74:75], v231 offset:512
	ds_read_b64_tr_b16 v[76:77], v231 offset:2048
	ds_read_b64_tr_b16 v[78:79], v231 offset:2560
	ds_read_b64_tr_b16 v[220:221], v231 offset:1024
	ds_read_b64_tr_b16 v[222:223], v231 offset:1536
	ds_read_b64_tr_b16 v[224:225], v231 offset:3072
	ds_read_b64_tr_b16 v[226:227], v231 offset:3584
	s_waitcnt vmcnt(8)
	ds_write_b128 v247, v[116:119]
	ds_write_b128 v247, v[120:123] offset:1024
	ds_write_b128 v247, v[124:127] offset:2048
	ds_write_b128 v247, v[128:131] offset:3072
	ds_read_b128 v[116:119], v248
	ds_read_b128 v[120:123], v249
	ds_read_b128 v[124:127], v250
	ds_read_b128 v[128:131], v251
	ds_write_b128 v112, v[132:135]
	ds_write_b128 v112, v[136:139] offset:1024
	ds_write_b128 v112, v[140:143] offset:2048
	ds_write_b128 v112, v[144:147] offset:3072
	v_exp_f32_e32 v188, v188
	v_exp_f32_e32 v189, v189
	v_exp_f32_e32 v190, v190
	v_exp_f32_e32 v191, v191
	v_exp_f32_e32 v192, v192
	v_exp_f32_e32 v193, v193
	s_waitcnt lgkmcnt(4)
	v_mfma_f32_32x32x16_bf16 v[32:47], v[116:119], v[48:51], v[32:47]
	v_exp_f32_e32 v194, v194
	v_exp_f32_e32 v195, v195
	v_mfma_f32_32x32x16_bf16 v[32:47], v[120:123], v[52:55], v[32:47]
	v_exp_f32_e32 v196, v196
	v_exp_f32_e32 v197, v197
	v_exp_f32_e32 v198, v198
	v_mfma_f32_32x32x16_bf16 v[32:47], v[124:127], v[56:59], v[32:47]
	v_exp_f32_e32 v199, v199
	v_exp_f32_e32 v200, v200
	v_mfma_f32_32x32x16_bf16 v[32:47], v[128:131], v[60:63], v[32:47]
	v_exp_f32_e32 v201, v201
	v_exp_f32_e32 v202, v202
	v_exp_f32_e32 v203, v203
	s_add_i32 s90, s76, 544
	v_add_u32_e32 v84, s90, v107
	v_add_u32_e32 v85, 0, v84
	v_add_u32_e32 v86, 1, v84
	v_add_u32_e32 v87, 2, v84
	v_add_u32_e32 v88, 3, v84
	v_cmp_gt_u32_e64 s[30:31], s98, v85
	v_cmp_gt_u32_e64 s[36:37], s98, v86
	v_cmp_gt_u32_e64 s[78:79], s98, v87
	v_cmp_gt_u32_e64 s[50:51], s98, v88
	v_cndmask_b32_e64 v188, 0, v188, s[30:31]
	v_add_u32_e32 v85, 8, v84
	v_cmp_gt_u32_e64 s[30:31], s98, v85
	v_cndmask_b32_e64 v189, 0, v189, s[36:37]
	v_add_u32_e32 v86, 9, v84
	v_cmp_gt_u32_e64 s[36:37], s98, v86
	v_cndmask_b32_e64 v190, 0, v190, s[78:79]
	v_add_u32_e32 v87, 10, v84
	v_cmp_gt_u32_e64 s[78:79], s98, v87
	v_cndmask_b32_e64 v191, 0, v191, s[50:51]
	v_add_u32_e32 v88, 11, v84
	v_cmp_gt_u32_e64 s[50:51], s98, v88
	v_cndmask_b32_e64 v192, 0, v192, s[30:31]
	v_add_u32_e32 v85, 16, v84
	v_cmp_gt_u32_e64 s[30:31], s98, v85
	v_cndmask_b32_e64 v193, 0, v193, s[36:37]
	v_add_u32_e32 v86, 17, v84
	v_cmp_gt_u32_e64 s[36:37], s98, v86
	v_cndmask_b32_e64 v194, 0, v194, s[78:79]
	v_add_u32_e32 v87, 18, v84
	v_cmp_gt_u32_e64 s[78:79], s98, v87
	v_cndmask_b32_e64 v195, 0, v195, s[50:51]
	v_add_u32_e32 v88, 19, v84
	v_cmp_gt_u32_e64 s[50:51], s98, v88
	v_cndmask_b32_e64 v196, 0, v196, s[30:31]
	v_add_u32_e32 v85, 24, v84
	v_cmp_gt_u32_e64 s[30:31], s98, v85
	v_cndmask_b32_e64 v197, 0, v197, s[36:37]
	v_add_u32_e32 v86, 25, v84
	v_cmp_gt_u32_e64 s[36:37], s98, v86
	v_cndmask_b32_e64 v198, 0, v198, s[78:79]
	v_add_u32_e32 v87, 26, v84
	v_cmp_gt_u32_e64 s[78:79], s98, v87
	v_cndmask_b32_e64 v199, 0, v199, s[50:51]
	v_add_u32_e32 v88, 27, v84
	v_cmp_gt_u32_e64 s[50:51], s98, v88
	v_nop
	v_cndmask_b32_e64 v200, 0, v200, s[30:31]
	v_cndmask_b32_e64 v201, 0, v201, s[36:37]
	v_cndmask_b32_e64 v202, 0, v202, s[78:79]
	v_cndmask_b32_e64 v203, 0, v203, s[50:51]
	v_cvt_pk_bf16_f32 v64, v188, v189
	v_cvt_pk_bf16_f32 v65, v190, v191
	v_cvt_pk_bf16_f32 v66, v192, v193
	v_cvt_pk_bf16_f32 v67, v194, v195
	v_cvt_pk_bf16_f32 v68, v196, v197
	v_cvt_pk_bf16_f32 v69, v198, v199
	v_cvt_pk_bf16_f32 v70, v200, v201
	v_cvt_pk_bf16_f32 v71, v202, v203
	v_pk_add_f32 v[232:233], v[232:233], v[188:189]
	v_pk_add_f32 v[232:233], v[232:233], v[190:191]
	v_pk_add_f32 v[232:233], v[232:233], v[192:193]
	v_pk_add_f32 v[232:233], v[232:233], v[194:195]
	v_pk_add_f32 v[232:233], v[232:233], v[196:197]
	v_pk_add_f32 v[232:233], v[232:233], v[198:199]
	v_pk_add_f32 v[232:233], v[232:233], v[200:201]
	v_pk_add_f32 v[232:233], v[232:233], v[202:203]
	ds_read2_b32 v[188:189], v115 offset0:32 offset1:33
	ds_read2_b32 v[190:191], v115 offset0:34 offset1:35
	ds_read2_b32 v[192:193], v115 offset0:40 offset1:41
	ds_read2_b32 v[194:195], v115 offset0:42 offset1:43
	ds_read2_b32 v[196:197], v115 offset0:48 offset1:49
	ds_read2_b32 v[198:199], v115 offset0:50 offset1:51
	ds_read2_b32 v[200:201], v115 offset0:56 offset1:57
	ds_read2_b32 v[202:203], v115 offset0:58 offset1:59
	v_mfma_f32_32x32x16_bf16 v[0:15], v[64:67], v[72:75], v[0:15]
	v_mfma_f32_32x32x16_bf16 v[16:31], v[64:67], v[76:79], v[16:31]
	v_mfma_f32_32x32x16_bf16 v[0:15], v[68:71], v[220:223], v[0:15]
	v_mfma_f32_32x32x16_bf16 v[16:31], v[68:71], v[224:227], v[16:31]
	s_add_i32 s90, s76, 0
	v_add_u32_e32 v80, s90, v239
	v_add_u32_e32 v83, s90, v240
	v_add_u32_e32 v99, s90, v241
	v_add_u32_e32 v253, s90, v242
	v_add_u32_e32 v254, s90, v101
	v_add_u32_e32 v255, s90, v150
	v_med3_i32 v80, v80, 0, s99
	v_med3_i32 v83, v83, 0, s99
	v_med3_i32 v99, v99, 0, s99
	v_med3_i32 v253, v253, 0, s99
	v_med3_i32 v254, v254, 0, s99
	v_med3_i32 v255, v255, 0, s99
	v_mad_u32_u24 v80, v80, s100, v252
	v_mad_u32_u24 v83, v83, s100, v252
	v_mad_u32_u24 v99, v99, s100, v252
	v_mad_u32_u24 v253, v253, s100, v252
	v_mad_u32_u24 v254, v254, s100, v153
	v_mad_u32_u24 v255, v255, s100, v153
	global_load_dwordx4 v[116:119], v80, s[82:83]
	global_load_dwordx4 v[120:123], v83, s[82:83]
	global_load_dwordx4 v[124:127], v99, s[82:83]
	global_load_dwordx4 v[128:131], v253, s[82:83]
	global_load_dwordx4 v[132:135], v254, s[82:83] offset:768
	global_load_dwordx4 v[136:139], v255, s[82:83] offset:768
	global_load_dwordx4 v[140:143], v254, s[82:83] offset:832
	global_load_dwordx4 v[144:147], v255, s[82:83] offset:832
	ds_read_b64_tr_b16 v[72:73], v231
	ds_read_b64_tr_b16 v[74:75], v231 offset:512
	ds_read_b64_tr_b16 v[76:77], v231 offset:2048
	ds_read_b64_tr_b16 v[78:79], v231 offset:2560
	ds_read_b64_tr_b16 v[220:221], v231 offset:1024
	ds_read_b64_tr_b16 v[222:223], v231 offset:1536
	ds_read_b64_tr_b16 v[224:225], v231 offset:3072
	ds_read_b64_tr_b16 v[226:227], v231 offset:3584
	s_waitcnt vmcnt(8)
	ds_write_b128 v247, v[156:159]
	ds_write_b128 v247, v[160:163] offset:1024
	ds_write_b128 v247, v[164:167] offset:2048
	ds_write_b128 v247, v[168:171] offset:3072
	ds_read_b128 v[156:159], v248
	ds_read_b128 v[160:163], v249
	ds_read_b128 v[164:167], v250
	ds_read_b128 v[168:171], v251
	ds_write_b128 v112, v[172:175]
	ds_write_b128 v112, v[176:179] offset:1024
	ds_write_b128 v112, v[180:183] offset:2048
	ds_write_b128 v112, v[184:187] offset:3072
	v_exp_f32_e32 v32, v32
	v_exp_f32_e32 v33, v33
	v_exp_f32_e32 v34, v34
	v_exp_f32_e32 v35, v35
	v_exp_f32_e32 v36, v36
	v_exp_f32_e32 v37, v37
	s_waitcnt lgkmcnt(4)
	v_mfma_f32_32x32x16_bf16 v[188:203], v[156:159], v[48:51], v[188:203]
	v_exp_f32_e32 v38, v38
	v_exp_f32_e32 v39, v39
	v_mfma_f32_32x32x16_bf16 v[188:203], v[160:163], v[52:55], v[188:203]
	v_exp_f32_e32 v40, v40
	v_exp_f32_e32 v41, v41
	v_exp_f32_e32 v42, v42
	v_mfma_f32_32x32x16_bf16 v[188:203], v[164:167], v[56:59], v[188:203]
	v_exp_f32_e32 v43, v43
	v_exp_f32_e32 v44, v44
	v_mfma_f32_32x32x16_bf16 v[188:203], v[168:171], v[60:63], v[188:203]
	v_exp_f32_e32 v45, v45
	v_exp_f32_e32 v46, v46
	v_exp_f32_e32 v47, v47
	s_add_i32 s90, s76, -256
	v_lshlrev_b32_e32 v84, 2, v107
	v_add_u32_e32 v84, s90, v84
	v_add_u32_e32 v85, 0, v84
	v_add_u32_e32 v86, 4, v84
	v_add_u32_e32 v87, 8, v84
	v_add_u32_e32 v88, 12, v84
	v_cmp_gt_u32_e64 s[30:31], s98, v85
	v_cmp_gt_u32_e64 s[36:37], s98, v86
	v_cmp_gt_u32_e64 s[78:79], s98, v87
	v_cmp_gt_u32_e64 s[50:51], s98, v88
	v_cndmask_b32_e64 v32, 0, v32, s[30:31]
	v_add_u32_e32 v85, 32, v84
	v_cmp_gt_u32_e64 s[30:31], s98, v85
	v_cndmask_b32_e64 v33, 0, v33, s[36:37]
	v_add_u32_e32 v86, 36, v84
	v_cmp_gt_u32_e64 s[36:37], s98, v86
	v_cndmask_b32_e64 v34, 0, v34, s[78:79]
	v_add_u32_e32 v87, 40, v84
	v_cmp_gt_u32_e64 s[78:79], s98, v87
	v_cndmask_b32_e64 v35, 0, v35, s[50:51]
	v_add_u32_e32 v88, 44, v84
	v_cmp_gt_u32_e64 s[50:51], s98, v88
	v_cndmask_b32_e64 v36, 0, v36, s[30:31]
	v_add_u32_e32 v85, 64, v84
	v_cmp_gt_u32_e64 s[30:31], s98, v85
	v_cndmask_b32_e64 v37, 0, v37, s[36:37]
	v_add_u32_e32 v86, 68, v84
	v_cmp_gt_u32_e64 s[36:37], s98, v86
	v_cndmask_b32_e64 v38, 0, v38, s[78:79]
	v_add_u32_e32 v87, 72, v84
	v_cmp_gt_u32_e64 s[78:79], s98, v87
	v_cndmask_b32_e64 v39, 0, v39, s[50:51]
	v_add_u32_e32 v88, 76, v84
	v_cmp_gt_u32_e64 s[50:51], s98, v88
	v_cndmask_b32_e64 v40, 0, v40, s[30:31]
	v_add_u32_e32 v85, 96, v84
	v_cmp_gt_u32_e64 s[30:31], s98, v85
	v_cndmask_b32_e64 v41, 0, v41, s[36:37]
	v_add_u32_e32 v86, 100, v84
	v_cmp_gt_u32_e64 s[36:37], s98, v86
	v_cndmask_b32_e64 v42, 0, v42, s[78:79]
	v_add_u32_e32 v87, 104, v84
	v_cmp_gt_u32_e64 s[78:79], s98, v87
	v_cndmask_b32_e64 v43, 0, v43, s[50:51]
	v_add_u32_e32 v88, 108, v84
	v_cmp_gt_u32_e64 s[50:51], s98, v88
	v_nop
	v_cndmask_b32_e64 v44, 0, v44, s[30:31]
	v_cndmask_b32_e64 v45, 0, v45, s[36:37]
	v_cndmask_b32_e64 v46, 0, v46, s[78:79]
	v_cndmask_b32_e64 v47, 0, v47, s[50:51]
	v_cvt_pk_bf16_f32 v64, v32, v33
	v_cvt_pk_bf16_f32 v65, v34, v35
	v_cvt_pk_bf16_f32 v66, v36, v37
	v_cvt_pk_bf16_f32 v67, v38, v39
	v_cvt_pk_bf16_f32 v68, v40, v41
	v_cvt_pk_bf16_f32 v69, v42, v43
	v_cvt_pk_bf16_f32 v70, v44, v45
	v_cvt_pk_bf16_f32 v71, v46, v47
	v_pk_add_f32 v[232:233], v[232:233], v[32:33]
	v_pk_add_f32 v[232:233], v[232:233], v[34:35]
	v_pk_add_f32 v[232:233], v[232:233], v[36:37]
	v_pk_add_f32 v[232:233], v[232:233], v[38:39]
	v_pk_add_f32 v[232:233], v[232:233], v[40:41]
	v_pk_add_f32 v[232:233], v[232:233], v[42:43]
	v_pk_add_f32 v[232:233], v[232:233], v[44:45]
	v_pk_add_f32 v[232:233], v[232:233], v[46:47]
	ds_read2_b32 v[32:33], v115 offset0:64 offset1:65
	ds_read2_b32 v[34:35], v115 offset0:66 offset1:67
	ds_read2_b32 v[36:37], v115 offset0:72 offset1:73
	ds_read2_b32 v[38:39], v115 offset0:74 offset1:75
	ds_read2_b32 v[40:41], v115 offset0:80 offset1:81
	ds_read2_b32 v[42:43], v115 offset0:82 offset1:83
	ds_read2_b32 v[44:45], v115 offset0:88 offset1:89
	ds_read2_b32 v[46:47], v115 offset0:90 offset1:91
	v_mfma_f32_32x32x16_bf16 v[0:15], v[64:67], v[72:75], v[0:15]
	v_mfma_f32_32x32x16_bf16 v[16:31], v[64:67], v[76:79], v[16:31]
	v_mfma_f32_32x32x16_bf16 v[0:15], v[68:71], v[220:223], v[0:15]
	v_mfma_f32_32x32x16_bf16 v[16:31], v[68:71], v[224:227], v[16:31]
	s_add_i32 s90, s76, 128
	v_add_u32_e32 v80, s90, v239
	v_add_u32_e32 v83, s90, v240
	v_add_u32_e32 v99, s90, v241
	v_add_u32_e32 v253, s90, v242
	v_add_u32_e32 v254, s90, v101
	v_add_u32_e32 v255, s90, v150
	v_med3_i32 v80, v80, 0, s99
	v_med3_i32 v83, v83, 0, s99
	v_med3_i32 v99, v99, 0, s99
	v_med3_i32 v253, v253, 0, s99
	v_med3_i32 v254, v254, 0, s99
	v_med3_i32 v255, v255, 0, s99
	v_mad_u32_u24 v80, v80, s100, v252
	v_mad_u32_u24 v83, v83, s100, v252
	v_mad_u32_u24 v99, v99, s100, v252
	v_mad_u32_u24 v253, v253, s100, v252
	v_mad_u32_u24 v254, v254, s100, v153
	v_mad_u32_u24 v255, v255, s100, v153
	global_load_dwordx4 v[156:159], v80, s[82:83]
	global_load_dwordx4 v[160:163], v83, s[82:83]
	global_load_dwordx4 v[164:167], v99, s[82:83]
	global_load_dwordx4 v[168:171], v253, s[82:83]
	global_load_dwordx4 v[172:175], v254, s[82:83] offset:768
	global_load_dwordx4 v[176:179], v255, s[82:83] offset:768
	global_load_dwordx4 v[180:183], v254, s[82:83] offset:832
	global_load_dwordx4 v[184:187], v255, s[82:83] offset:832
	ds_read_b64_tr_b16 v[72:73], v231
	ds_read_b64_tr_b16 v[74:75], v231 offset:512
	ds_read_b64_tr_b16 v[76:77], v231 offset:2048
	ds_read_b64_tr_b16 v[78:79], v231 offset:2560
	ds_read_b64_tr_b16 v[220:221], v231 offset:1024
	ds_read_b64_tr_b16 v[222:223], v231 offset:1536
	ds_read_b64_tr_b16 v[224:225], v231 offset:3072
	ds_read_b64_tr_b16 v[226:227], v231 offset:3584
	s_waitcnt vmcnt(8)
	ds_write_b128 v247, v[116:119]
	ds_write_b128 v247, v[120:123] offset:1024
	ds_write_b128 v247, v[124:127] offset:2048
	ds_write_b128 v247, v[128:131] offset:3072
	ds_read_b128 v[116:119], v248
	ds_read_b128 v[120:123], v249
	ds_read_b128 v[124:127], v250
	ds_read_b128 v[128:131], v251
	ds_write_b128 v112, v[132:135]
	ds_write_b128 v112, v[136:139] offset:1024
	ds_write_b128 v112, v[140:143] offset:2048
	ds_write_b128 v112, v[144:147] offset:3072
	v_exp_f32_e32 v188, v188
	v_exp_f32_e32 v189, v189
	v_exp_f32_e32 v190, v190
	v_exp_f32_e32 v191, v191
	v_exp_f32_e32 v192, v192
	v_exp_f32_e32 v193, v193
	s_waitcnt lgkmcnt(4)
	v_mfma_f32_32x32x16_bf16 v[32:47], v[116:119], v[48:51], v[32:47]
	v_exp_f32_e32 v194, v194
	v_exp_f32_e32 v195, v195
	v_mfma_f32_32x32x16_bf16 v[32:47], v[120:123], v[52:55], v[32:47]
	v_exp_f32_e32 v196, v196
	v_exp_f32_e32 v197, v197
	v_exp_f32_e32 v198, v198
	v_mfma_f32_32x32x16_bf16 v[32:47], v[124:127], v[56:59], v[32:47]
	v_exp_f32_e32 v199, v199
	v_exp_f32_e32 v200, v200
	v_mfma_f32_32x32x16_bf16 v[32:47], v[128:131], v[60:63], v[32:47]
	v_exp_f32_e32 v201, v201
	v_exp_f32_e32 v202, v202
	v_exp_f32_e32 v203, v203
	s_add_i32 s90, s76, -128
	v_lshlrev_b32_e32 v84, 2, v107
	v_add_u32_e32 v84, s90, v84
	v_add_u32_e32 v85, 0, v84
	v_add_u32_e32 v86, 4, v84
	v_add_u32_e32 v87, 8, v84
	v_add_u32_e32 v88, 12, v84
	v_cmp_gt_u32_e64 s[30:31], s98, v85
	v_cmp_gt_u32_e64 s[36:37], s98, v86
	v_cmp_gt_u32_e64 s[78:79], s98, v87
	v_cmp_gt_u32_e64 s[50:51], s98, v88
	v_cndmask_b32_e64 v188, 0, v188, s[30:31]
	v_add_u32_e32 v85, 32, v84
	v_cmp_gt_u32_e64 s[30:31], s98, v85
	v_cndmask_b32_e64 v189, 0, v189, s[36:37]
	v_add_u32_e32 v86, 36, v84
	v_cmp_gt_u32_e64 s[36:37], s98, v86
	v_cndmask_b32_e64 v190, 0, v190, s[78:79]
	v_add_u32_e32 v87, 40, v84
	v_cmp_gt_u32_e64 s[78:79], s98, v87
	v_cndmask_b32_e64 v191, 0, v191, s[50:51]
	v_add_u32_e32 v88, 44, v84
	v_cmp_gt_u32_e64 s[50:51], s98, v88
	v_cndmask_b32_e64 v192, 0, v192, s[30:31]
	v_add_u32_e32 v85, 64, v84
	v_cmp_gt_u32_e64 s[30:31], s98, v85
	v_cndmask_b32_e64 v193, 0, v193, s[36:37]
	v_add_u32_e32 v86, 68, v84
	v_cmp_gt_u32_e64 s[36:37], s98, v86
	v_cndmask_b32_e64 v194, 0, v194, s[78:79]
	v_add_u32_e32 v87, 72, v84
	v_cmp_gt_u32_e64 s[78:79], s98, v87
	v_cndmask_b32_e64 v195, 0, v195, s[50:51]
	v_add_u32_e32 v88, 76, v84
	v_cmp_gt_u32_e64 s[50:51], s98, v88
	v_cndmask_b32_e64 v196, 0, v196, s[30:31]
	v_add_u32_e32 v85, 96, v84
	v_cmp_gt_u32_e64 s[30:31], s98, v85
	v_cndmask_b32_e64 v197, 0, v197, s[36:37]
	v_add_u32_e32 v86, 100, v84
	v_cmp_gt_u32_e64 s[36:37], s98, v86
	v_cndmask_b32_e64 v198, 0, v198, s[78:79]
	v_add_u32_e32 v87, 104, v84
	v_cmp_gt_u32_e64 s[78:79], s98, v87
	v_cndmask_b32_e64 v199, 0, v199, s[50:51]
	v_add_u32_e32 v88, 108, v84
	v_cmp_gt_u32_e64 s[50:51], s98, v88
	v_nop
	v_cndmask_b32_e64 v200, 0, v200, s[30:31]
	v_cndmask_b32_e64 v201, 0, v201, s[36:37]
	v_cndmask_b32_e64 v202, 0, v202, s[78:79]
	v_cndmask_b32_e64 v203, 0, v203, s[50:51]
	v_cvt_pk_bf16_f32 v64, v188, v189
	v_cvt_pk_bf16_f32 v65, v190, v191
	v_cvt_pk_bf16_f32 v66, v192, v193
	v_cvt_pk_bf16_f32 v67, v194, v195
	v_cvt_pk_bf16_f32 v68, v196, v197
	v_cvt_pk_bf16_f32 v69, v198, v199
	v_cvt_pk_bf16_f32 v70, v200, v201
	v_cvt_pk_bf16_f32 v71, v202, v203
	v_pk_add_f32 v[232:233], v[232:233], v[188:189]
	v_pk_add_f32 v[232:233], v[232:233], v[190:191]
	v_pk_add_f32 v[232:233], v[232:233], v[192:193]
	v_pk_add_f32 v[232:233], v[232:233], v[194:195]
	v_pk_add_f32 v[232:233], v[232:233], v[196:197]
	v_pk_add_f32 v[232:233], v[232:233], v[198:199]
	v_pk_add_f32 v[232:233], v[232:233], v[200:201]
	v_pk_add_f32 v[232:233], v[232:233], v[202:203]
	ds_read2_b32 v[188:189], v115 offset0:96 offset1:97
	ds_read2_b32 v[190:191], v115 offset0:98 offset1:99
	ds_read2_b32 v[192:193], v115 offset0:104 offset1:105
	ds_read2_b32 v[194:195], v115 offset0:106 offset1:107
	ds_read2_b32 v[196:197], v115 offset0:112 offset1:113
	ds_read2_b32 v[198:199], v115 offset0:114 offset1:115
	ds_read2_b32 v[200:201], v115 offset0:120 offset1:121
	ds_read2_b32 v[202:203], v115 offset0:122 offset1:123
	v_mfma_f32_32x32x16_bf16 v[0:15], v[64:67], v[72:75], v[0:15]
	v_mfma_f32_32x32x16_bf16 v[16:31], v[64:67], v[76:79], v[16:31]
	v_mfma_f32_32x32x16_bf16 v[0:15], v[68:71], v[220:223], v[0:15]
	v_mfma_f32_32x32x16_bf16 v[16:31], v[68:71], v[224:227], v[16:31]
	s_add_i32 s90, s76, 256
	v_add_u32_e32 v80, s90, v239
	v_add_u32_e32 v83, s90, v240
	v_add_u32_e32 v99, s90, v241
	v_add_u32_e32 v253, s90, v242
	v_add_u32_e32 v254, s90, v101
	v_add_u32_e32 v255, s90, v150
	v_med3_i32 v80, v80, 0, s99
	v_med3_i32 v83, v83, 0, s99
	v_med3_i32 v99, v99, 0, s99
	v_med3_i32 v253, v253, 0, s99
	v_med3_i32 v254, v254, 0, s99
	v_med3_i32 v255, v255, 0, s99
	v_mad_u32_u24 v80, v80, s100, v252
	v_mad_u32_u24 v83, v83, s100, v252
	v_mad_u32_u24 v99, v99, s100, v252
	v_mad_u32_u24 v253, v253, s100, v252
	v_mad_u32_u24 v254, v254, s100, v153
	v_mad_u32_u24 v255, v255, s100, v153
	global_load_dwordx4 v[116:119], v80, s[82:83]
	global_load_dwordx4 v[120:123], v83, s[82:83]
	global_load_dwordx4 v[124:127], v99, s[82:83]
	global_load_dwordx4 v[128:131], v253, s[82:83]
	global_load_dwordx4 v[132:135], v254, s[82:83] offset:768
	global_load_dwordx4 v[136:139], v255, s[82:83] offset:768
	global_load_dwordx4 v[140:143], v254, s[82:83] offset:832
	global_load_dwordx4 v[144:147], v255, s[82:83] offset:832
	ds_read_b64_tr_b16 v[72:73], v231
	ds_read_b64_tr_b16 v[74:75], v231 offset:512
	ds_read_b64_tr_b16 v[76:77], v231 offset:2048
	ds_read_b64_tr_b16 v[78:79], v231 offset:2560
	ds_read_b64_tr_b16 v[220:221], v231 offset:1024
	ds_read_b64_tr_b16 v[222:223], v231 offset:1536
	ds_read_b64_tr_b16 v[224:225], v231 offset:3072
	ds_read_b64_tr_b16 v[226:227], v231 offset:3584
	s_waitcnt vmcnt(8)
	ds_write_b128 v247, v[156:159]
	ds_write_b128 v247, v[160:163] offset:1024
	ds_write_b128 v247, v[164:167] offset:2048
	ds_write_b128 v247, v[168:171] offset:3072
	ds_read_b128 v[156:159], v248
	ds_read_b128 v[160:163], v249
	ds_read_b128 v[164:167], v250
	ds_read_b128 v[168:171], v251
	ds_write_b128 v112, v[172:175]
	ds_write_b128 v112, v[176:179] offset:1024
	ds_write_b128 v112, v[180:183] offset:2048
	ds_write_b128 v112, v[184:187] offset:3072
	v_exp_f32_e32 v32, v32
	v_exp_f32_e32 v33, v33
	v_exp_f32_e32 v34, v34
	v_exp_f32_e32 v35, v35
	v_exp_f32_e32 v36, v36
	v_exp_f32_e32 v37, v37
	s_waitcnt lgkmcnt(4)
	v_mfma_f32_32x32x16_bf16 v[188:203], v[156:159], v[48:51], v[188:203]
	v_exp_f32_e32 v38, v38
	v_exp_f32_e32 v39, v39
	v_mfma_f32_32x32x16_bf16 v[188:203], v[160:163], v[52:55], v[188:203]
	v_exp_f32_e32 v40, v40
	v_exp_f32_e32 v41, v41
	v_exp_f32_e32 v42, v42
	v_mfma_f32_32x32x16_bf16 v[188:203], v[164:167], v[56:59], v[188:203]
	v_exp_f32_e32 v43, v43
	v_exp_f32_e32 v44, v44
	v_mfma_f32_32x32x16_bf16 v[188:203], v[168:171], v[60:63], v[188:203]
	v_exp_f32_e32 v45, v45
	v_exp_f32_e32 v46, v46
	v_exp_f32_e32 v47, v47
	s_add_i32 s90, s76, 0
	v_lshlrev_b32_e32 v84, 2, v107
	v_add_u32_e32 v84, s90, v84
	v_add_u32_e32 v85, 0, v84
	v_add_u32_e32 v86, 4, v84
	v_add_u32_e32 v87, 8, v84
	v_add_u32_e32 v88, 12, v84
	v_cmp_gt_u32_e64 s[30:31], s98, v85
	v_cmp_gt_u32_e64 s[36:37], s98, v86
	v_cmp_gt_u32_e64 s[78:79], s98, v87
	v_cmp_gt_u32_e64 s[50:51], s98, v88
	v_cndmask_b32_e64 v32, 0, v32, s[30:31]
	v_add_u32_e32 v85, 32, v84
	v_cmp_gt_u32_e64 s[30:31], s98, v85
	v_cndmask_b32_e64 v33, 0, v33, s[36:37]
	v_add_u32_e32 v86, 36, v84
	v_cmp_gt_u32_e64 s[36:37], s98, v86
	v_cndmask_b32_e64 v34, 0, v34, s[78:79]
	v_add_u32_e32 v87, 40, v84
	v_cmp_gt_u32_e64 s[78:79], s98, v87
	v_cndmask_b32_e64 v35, 0, v35, s[50:51]
	v_add_u32_e32 v88, 44, v84
	v_cmp_gt_u32_e64 s[50:51], s98, v88
	v_cndmask_b32_e64 v36, 0, v36, s[30:31]
	v_add_u32_e32 v85, 64, v84
	v_cmp_gt_u32_e64 s[30:31], s98, v85
	v_cndmask_b32_e64 v37, 0, v37, s[36:37]
	v_add_u32_e32 v86, 68, v84
	v_cmp_gt_u32_e64 s[36:37], s98, v86
	v_cndmask_b32_e64 v38, 0, v38, s[78:79]
	v_add_u32_e32 v87, 72, v84
	v_cmp_gt_u32_e64 s[78:79], s98, v87
	v_cndmask_b32_e64 v39, 0, v39, s[50:51]
	v_add_u32_e32 v88, 76, v84
	v_cmp_gt_u32_e64 s[50:51], s98, v88
	v_cndmask_b32_e64 v40, 0, v40, s[30:31]
	v_add_u32_e32 v85, 96, v84
	v_cmp_gt_u32_e64 s[30:31], s98, v85
	v_cndmask_b32_e64 v41, 0, v41, s[36:37]
	v_add_u32_e32 v86, 100, v84
	v_cmp_gt_u32_e64 s[36:37], s98, v86
	v_cndmask_b32_e64 v42, 0, v42, s[78:79]
	v_add_u32_e32 v87, 104, v84
	v_cmp_gt_u32_e64 s[78:79], s98, v87
	v_cndmask_b32_e64 v43, 0, v43, s[50:51]
	v_add_u32_e32 v88, 108, v84
	v_cmp_gt_u32_e64 s[50:51], s98, v88
	v_nop
	v_cndmask_b32_e64 v44, 0, v44, s[30:31]
	v_cndmask_b32_e64 v45, 0, v45, s[36:37]
	v_cndmask_b32_e64 v46, 0, v46, s[78:79]
	v_cndmask_b32_e64 v47, 0, v47, s[50:51]
	v_cvt_pk_bf16_f32 v64, v32, v33
	v_cvt_pk_bf16_f32 v65, v34, v35
	v_cvt_pk_bf16_f32 v66, v36, v37
	v_cvt_pk_bf16_f32 v67, v38, v39
	v_cvt_pk_bf16_f32 v68, v40, v41
	v_cvt_pk_bf16_f32 v69, v42, v43
	v_cvt_pk_bf16_f32 v70, v44, v45
	v_cvt_pk_bf16_f32 v71, v46, v47
	v_pk_add_f32 v[232:233], v[232:233], v[32:33]
	v_pk_add_f32 v[232:233], v[232:233], v[34:35]
	v_pk_add_f32 v[232:233], v[232:233], v[36:37]
	v_pk_add_f32 v[232:233], v[232:233], v[38:39]
	v_pk_add_f32 v[232:233], v[232:233], v[40:41]
	v_pk_add_f32 v[232:233], v[232:233], v[42:43]
	v_pk_add_f32 v[232:233], v[232:233], v[44:45]
	v_pk_add_f32 v[232:233], v[232:233], v[46:47]
	ds_read2_b32 v[32:33], v115 offset0:128 offset1:129
	ds_read2_b32 v[34:35], v115 offset0:130 offset1:131
	ds_read2_b32 v[36:37], v115 offset0:136 offset1:137
	ds_read2_b32 v[38:39], v115 offset0:138 offset1:139
	ds_read2_b32 v[40:41], v115 offset0:144 offset1:145
	ds_read2_b32 v[42:43], v115 offset0:146 offset1:147
	ds_read2_b32 v[44:45], v115 offset0:152 offset1:153
	ds_read2_b32 v[46:47], v115 offset0:154 offset1:155
	v_mfma_f32_32x32x16_bf16 v[0:15], v[64:67], v[72:75], v[0:15]
	v_mfma_f32_32x32x16_bf16 v[16:31], v[64:67], v[76:79], v[16:31]
	v_mfma_f32_32x32x16_bf16 v[0:15], v[68:71], v[220:223], v[0:15]
	v_mfma_f32_32x32x16_bf16 v[16:31], v[68:71], v[224:227], v[16:31]
	s_add_i32 s90, s76, 384
	v_add_u32_e32 v80, s90, v239
	v_add_u32_e32 v83, s90, v240
	v_add_u32_e32 v99, s90, v241
	v_add_u32_e32 v253, s90, v242
	v_add_u32_e32 v254, s90, v101
	v_add_u32_e32 v255, s90, v150
	v_med3_i32 v80, v80, 0, s99
	v_med3_i32 v83, v83, 0, s99
	v_med3_i32 v99, v99, 0, s99
	v_med3_i32 v253, v253, 0, s99
	v_med3_i32 v254, v254, 0, s99
	v_med3_i32 v255, v255, 0, s99
	v_mad_u32_u24 v80, v80, s100, v252
	v_mad_u32_u24 v83, v83, s100, v252
	v_mad_u32_u24 v99, v99, s100, v252
	v_mad_u32_u24 v253, v253, s100, v252
	v_mad_u32_u24 v254, v254, s100, v153
	v_mad_u32_u24 v255, v255, s100, v153
	global_load_dwordx4 v[156:159], v80, s[82:83]
	global_load_dwordx4 v[160:163], v83, s[82:83]
	global_load_dwordx4 v[164:167], v99, s[82:83]
	global_load_dwordx4 v[168:171], v253, s[82:83]
	global_load_dwordx4 v[172:175], v254, s[82:83] offset:768
	global_load_dwordx4 v[176:179], v255, s[82:83] offset:768
	global_load_dwordx4 v[180:183], v254, s[82:83] offset:832
	global_load_dwordx4 v[184:187], v255, s[82:83] offset:832
	ds_read_b64_tr_b16 v[72:73], v231
	ds_read_b64_tr_b16 v[74:75], v231 offset:512
	ds_read_b64_tr_b16 v[76:77], v231 offset:2048
	ds_read_b64_tr_b16 v[78:79], v231 offset:2560
	ds_read_b64_tr_b16 v[220:221], v231 offset:1024
	ds_read_b64_tr_b16 v[222:223], v231 offset:1536
	ds_read_b64_tr_b16 v[224:225], v231 offset:3072
	ds_read_b64_tr_b16 v[226:227], v231 offset:3584
	s_waitcnt vmcnt(8)
	ds_write_b128 v247, v[116:119]
	ds_write_b128 v247, v[120:123] offset:1024
	ds_write_b128 v247, v[124:127] offset:2048
	ds_write_b128 v247, v[128:131] offset:3072
	ds_read_b128 v[116:119], v248
	ds_read_b128 v[120:123], v249
	ds_read_b128 v[124:127], v250
	ds_read_b128 v[128:131], v251
	ds_write_b128 v112, v[132:135]
	ds_write_b128 v112, v[136:139] offset:1024
	ds_write_b128 v112, v[140:143] offset:2048
	ds_write_b128 v112, v[144:147] offset:3072
	v_exp_f32_e32 v188, v188
	v_exp_f32_e32 v189, v189
	v_exp_f32_e32 v190, v190
	v_exp_f32_e32 v191, v191
	v_exp_f32_e32 v192, v192
	v_exp_f32_e32 v193, v193
	s_waitcnt lgkmcnt(4)
	v_mfma_f32_32x32x16_bf16 v[32:47], v[116:119], v[48:51], v[32:47]
	v_exp_f32_e32 v194, v194
	v_exp_f32_e32 v195, v195
	v_mfma_f32_32x32x16_bf16 v[32:47], v[120:123], v[52:55], v[32:47]
	v_exp_f32_e32 v196, v196
	v_exp_f32_e32 v197, v197
	v_exp_f32_e32 v198, v198
	v_mfma_f32_32x32x16_bf16 v[32:47], v[124:127], v[56:59], v[32:47]
	v_exp_f32_e32 v199, v199
	v_exp_f32_e32 v200, v200
	v_mfma_f32_32x32x16_bf16 v[32:47], v[128:131], v[60:63], v[32:47]
	v_exp_f32_e32 v201, v201
	v_exp_f32_e32 v202, v202
	v_exp_f32_e32 v203, v203
	s_add_i32 s90, s76, 128
	v_lshlrev_b32_e32 v84, 2, v107
	v_add_u32_e32 v84, s90, v84
	v_add_u32_e32 v85, 0, v84
	v_add_u32_e32 v86, 4, v84
	v_add_u32_e32 v87, 8, v84
	v_add_u32_e32 v88, 12, v84
	v_cmp_gt_u32_e64 s[30:31], s98, v85
	v_cmp_gt_u32_e64 s[36:37], s98, v86
	v_cmp_gt_u32_e64 s[78:79], s98, v87
	v_cmp_gt_u32_e64 s[50:51], s98, v88
	v_cndmask_b32_e64 v188, 0, v188, s[30:31]
	v_add_u32_e32 v85, 32, v84
	v_cmp_gt_u32_e64 s[30:31], s98, v85
	v_cndmask_b32_e64 v189, 0, v189, s[36:37]
	v_add_u32_e32 v86, 36, v84
	v_cmp_gt_u32_e64 s[36:37], s98, v86
	v_cndmask_b32_e64 v190, 0, v190, s[78:79]
	v_add_u32_e32 v87, 40, v84
	v_cmp_gt_u32_e64 s[78:79], s98, v87
	v_cndmask_b32_e64 v191, 0, v191, s[50:51]
	v_add_u32_e32 v88, 44, v84
	v_cmp_gt_u32_e64 s[50:51], s98, v88
	v_cndmask_b32_e64 v192, 0, v192, s[30:31]
	v_add_u32_e32 v85, 64, v84
	v_cmp_gt_u32_e64 s[30:31], s98, v85
	v_cndmask_b32_e64 v193, 0, v193, s[36:37]
	v_add_u32_e32 v86, 68, v84
	v_cmp_gt_u32_e64 s[36:37], s98, v86
	v_cndmask_b32_e64 v194, 0, v194, s[78:79]
	v_add_u32_e32 v87, 72, v84
	v_cmp_gt_u32_e64 s[78:79], s98, v87
	v_cndmask_b32_e64 v195, 0, v195, s[50:51]
	v_add_u32_e32 v88, 76, v84
	v_cmp_gt_u32_e64 s[50:51], s98, v88
	v_cndmask_b32_e64 v196, 0, v196, s[30:31]
	v_add_u32_e32 v85, 96, v84
	v_cmp_gt_u32_e64 s[30:31], s98, v85
	v_cndmask_b32_e64 v197, 0, v197, s[36:37]
	v_add_u32_e32 v86, 100, v84
	v_cmp_gt_u32_e64 s[36:37], s98, v86
	v_cndmask_b32_e64 v198, 0, v198, s[78:79]
	v_add_u32_e32 v87, 104, v84
	v_cmp_gt_u32_e64 s[78:79], s98, v87
	v_cndmask_b32_e64 v199, 0, v199, s[50:51]
	v_add_u32_e32 v88, 108, v84
	v_cmp_gt_u32_e64 s[50:51], s98, v88
	v_nop
	v_cndmask_b32_e64 v200, 0, v200, s[30:31]
	v_cndmask_b32_e64 v201, 0, v201, s[36:37]
	v_cndmask_b32_e64 v202, 0, v202, s[78:79]
	v_cndmask_b32_e64 v203, 0, v203, s[50:51]
	v_cvt_pk_bf16_f32 v64, v188, v189
	v_cvt_pk_bf16_f32 v65, v190, v191
	v_cvt_pk_bf16_f32 v66, v192, v193
	v_cvt_pk_bf16_f32 v67, v194, v195
	v_cvt_pk_bf16_f32 v68, v196, v197
	v_cvt_pk_bf16_f32 v69, v198, v199
	v_cvt_pk_bf16_f32 v70, v200, v201
	v_cvt_pk_bf16_f32 v71, v202, v203
	v_pk_add_f32 v[232:233], v[232:233], v[188:189]
	v_pk_add_f32 v[232:233], v[232:233], v[190:191]
	v_pk_add_f32 v[232:233], v[232:233], v[192:193]
	v_pk_add_f32 v[232:233], v[232:233], v[194:195]
	v_pk_add_f32 v[232:233], v[232:233], v[196:197]
	v_pk_add_f32 v[232:233], v[232:233], v[198:199]
	v_pk_add_f32 v[232:233], v[232:233], v[200:201]
	v_pk_add_f32 v[232:233], v[232:233], v[202:203]
	ds_read2_b32 v[188:189], v115 offset0:160 offset1:161
	ds_read2_b32 v[190:191], v115 offset0:162 offset1:163
	ds_read2_b32 v[192:193], v115 offset0:168 offset1:169
	ds_read2_b32 v[194:195], v115 offset0:170 offset1:171
	ds_read2_b32 v[196:197], v115 offset0:176 offset1:177
	ds_read2_b32 v[198:199], v115 offset0:178 offset1:179
	ds_read2_b32 v[200:201], v115 offset0:184 offset1:185
	ds_read2_b32 v[202:203], v115 offset0:186 offset1:187
	v_mfma_f32_32x32x16_bf16 v[0:15], v[64:67], v[72:75], v[0:15]
	v_mfma_f32_32x32x16_bf16 v[16:31], v[64:67], v[76:79], v[16:31]
	v_mfma_f32_32x32x16_bf16 v[0:15], v[68:71], v[220:223], v[0:15]
	v_mfma_f32_32x32x16_bf16 v[16:31], v[68:71], v[224:227], v[16:31]
	s_add_i32 s90, s76, 512
	v_add_u32_e32 v80, s90, v239
	v_add_u32_e32 v83, s90, v240
	v_add_u32_e32 v99, s90, v241
	v_add_u32_e32 v253, s90, v242
	v_add_u32_e32 v254, s90, v101
	v_add_u32_e32 v255, s90, v150
	v_med3_i32 v80, v80, 0, s99
	v_med3_i32 v83, v83, 0, s99
	v_med3_i32 v99, v99, 0, s99
	v_med3_i32 v253, v253, 0, s99
	v_med3_i32 v254, v254, 0, s99
	v_med3_i32 v255, v255, 0, s99
	v_mad_u32_u24 v80, v80, s100, v252
	v_mad_u32_u24 v83, v83, s100, v252
	v_mad_u32_u24 v99, v99, s100, v252
	v_mad_u32_u24 v253, v253, s100, v252
	v_mad_u32_u24 v254, v254, s100, v153
	v_mad_u32_u24 v255, v255, s100, v153
	global_load_dwordx4 v[116:119], v80, s[82:83]
	global_load_dwordx4 v[120:123], v83, s[82:83]
	global_load_dwordx4 v[124:127], v99, s[82:83]
	global_load_dwordx4 v[128:131], v253, s[82:83]
	global_load_dwordx4 v[132:135], v254, s[82:83] offset:768
	global_load_dwordx4 v[136:139], v255, s[82:83] offset:768
	global_load_dwordx4 v[140:143], v254, s[82:83] offset:832
	global_load_dwordx4 v[144:147], v255, s[82:83] offset:832
	ds_read_b64_tr_b16 v[72:73], v231
	ds_read_b64_tr_b16 v[74:75], v231 offset:512
	ds_read_b64_tr_b16 v[76:77], v231 offset:2048
	ds_read_b64_tr_b16 v[78:79], v231 offset:2560
	ds_read_b64_tr_b16 v[220:221], v231 offset:1024
	ds_read_b64_tr_b16 v[222:223], v231 offset:1536
	ds_read_b64_tr_b16 v[224:225], v231 offset:3072
	ds_read_b64_tr_b16 v[226:227], v231 offset:3584
	s_waitcnt vmcnt(8)
	ds_write_b128 v247, v[156:159]
	ds_write_b128 v247, v[160:163] offset:1024
	ds_write_b128 v247, v[164:167] offset:2048
	ds_write_b128 v247, v[168:171] offset:3072
	ds_read_b128 v[156:159], v248
	ds_read_b128 v[160:163], v249
	ds_read_b128 v[164:167], v250
	ds_read_b128 v[168:171], v251
	ds_write_b128 v112, v[172:175]
	ds_write_b128 v112, v[176:179] offset:1024
	ds_write_b128 v112, v[180:183] offset:2048
	ds_write_b128 v112, v[184:187] offset:3072
	v_exp_f32_e32 v32, v32
	v_exp_f32_e32 v33, v33
	v_exp_f32_e32 v34, v34
	v_exp_f32_e32 v35, v35
	v_exp_f32_e32 v36, v36
	v_exp_f32_e32 v37, v37
	s_waitcnt lgkmcnt(4)
	v_mfma_f32_32x32x16_bf16 v[188:203], v[156:159], v[48:51], v[188:203]
	v_exp_f32_e32 v38, v38
	v_exp_f32_e32 v39, v39
	v_mfma_f32_32x32x16_bf16 v[188:203], v[160:163], v[52:55], v[188:203]
	v_exp_f32_e32 v40, v40
	v_exp_f32_e32 v41, v41
	v_exp_f32_e32 v42, v42
	v_mfma_f32_32x32x16_bf16 v[188:203], v[164:167], v[56:59], v[188:203]
	v_exp_f32_e32 v43, v43
	v_exp_f32_e32 v44, v44
	v_mfma_f32_32x32x16_bf16 v[188:203], v[168:171], v[60:63], v[188:203]
	v_exp_f32_e32 v45, v45
	v_exp_f32_e32 v46, v46
	v_exp_f32_e32 v47, v47
	s_add_i32 s90, s76, 256
	v_lshlrev_b32_e32 v84, 2, v107
	v_add_u32_e32 v84, s90, v84
	v_add_u32_e32 v85, 0, v84
	v_add_u32_e32 v86, 4, v84
	v_add_u32_e32 v87, 8, v84
	v_add_u32_e32 v88, 12, v84
	v_cmp_gt_u32_e64 s[30:31], s98, v85
	v_cmp_gt_u32_e64 s[36:37], s98, v86
	v_cmp_gt_u32_e64 s[78:79], s98, v87
	v_cmp_gt_u32_e64 s[50:51], s98, v88
	v_cndmask_b32_e64 v32, 0, v32, s[30:31]
	v_add_u32_e32 v85, 32, v84
	v_cmp_gt_u32_e64 s[30:31], s98, v85
	v_cndmask_b32_e64 v33, 0, v33, s[36:37]
	v_add_u32_e32 v86, 36, v84
	v_cmp_gt_u32_e64 s[36:37], s98, v86
	v_cndmask_b32_e64 v34, 0, v34, s[78:79]
	v_add_u32_e32 v87, 40, v84
	v_cmp_gt_u32_e64 s[78:79], s98, v87
	v_cndmask_b32_e64 v35, 0, v35, s[50:51]
	v_add_u32_e32 v88, 44, v84
	v_cmp_gt_u32_e64 s[50:51], s98, v88
	v_cndmask_b32_e64 v36, 0, v36, s[30:31]
	v_add_u32_e32 v85, 64, v84
	v_cmp_gt_u32_e64 s[30:31], s98, v85
	v_cndmask_b32_e64 v37, 0, v37, s[36:37]
	v_add_u32_e32 v86, 68, v84
	v_cmp_gt_u32_e64 s[36:37], s98, v86
	v_cndmask_b32_e64 v38, 0, v38, s[78:79]
	v_add_u32_e32 v87, 72, v84
	v_cmp_gt_u32_e64 s[78:79], s98, v87
	v_cndmask_b32_e64 v39, 0, v39, s[50:51]
	v_add_u32_e32 v88, 76, v84
	v_cmp_gt_u32_e64 s[50:51], s98, v88
	v_cndmask_b32_e64 v40, 0, v40, s[30:31]
	v_add_u32_e32 v85, 96, v84
	v_cmp_gt_u32_e64 s[30:31], s98, v85
	v_cndmask_b32_e64 v41, 0, v41, s[36:37]
	v_add_u32_e32 v86, 100, v84
	v_cmp_gt_u32_e64 s[36:37], s98, v86
	v_cndmask_b32_e64 v42, 0, v42, s[78:79]
	v_add_u32_e32 v87, 104, v84
	v_cmp_gt_u32_e64 s[78:79], s98, v87
	v_cndmask_b32_e64 v43, 0, v43, s[50:51]
	v_add_u32_e32 v88, 108, v84
	v_cmp_gt_u32_e64 s[50:51], s98, v88
	v_nop
	v_cndmask_b32_e64 v44, 0, v44, s[30:31]
	v_cndmask_b32_e64 v45, 0, v45, s[36:37]
	v_cndmask_b32_e64 v46, 0, v46, s[78:79]
	v_cndmask_b32_e64 v47, 0, v47, s[50:51]
	v_cvt_pk_bf16_f32 v64, v32, v33
	v_cvt_pk_bf16_f32 v65, v34, v35
	v_cvt_pk_bf16_f32 v66, v36, v37
	v_cvt_pk_bf16_f32 v67, v38, v39
	v_cvt_pk_bf16_f32 v68, v40, v41
	v_cvt_pk_bf16_f32 v69, v42, v43
	v_cvt_pk_bf16_f32 v70, v44, v45
	v_cvt_pk_bf16_f32 v71, v46, v47
	v_pk_add_f32 v[232:233], v[232:233], v[32:33]
	v_pk_add_f32 v[232:233], v[232:233], v[34:35]
	v_pk_add_f32 v[232:233], v[232:233], v[36:37]
	v_pk_add_f32 v[232:233], v[232:233], v[38:39]
	v_pk_add_f32 v[232:233], v[232:233], v[40:41]
	v_pk_add_f32 v[232:233], v[232:233], v[42:43]
	v_pk_add_f32 v[232:233], v[232:233], v[44:45]
	v_pk_add_f32 v[232:233], v[232:233], v[46:47]
	ds_read2_b32 v[32:33], v115 offset0:192 offset1:193
	ds_read2_b32 v[34:35], v115 offset0:194 offset1:195
	ds_read2_b32 v[36:37], v115 offset0:200 offset1:201
	ds_read2_b32 v[38:39], v115 offset0:202 offset1:203
	ds_read2_b32 v[40:41], v115 offset0:208 offset1:209
	ds_read2_b32 v[42:43], v115 offset0:210 offset1:211
	ds_read2_b32 v[44:45], v115 offset0:216 offset1:217
	ds_read2_b32 v[46:47], v115 offset0:218 offset1:219
	v_mfma_f32_32x32x16_bf16 v[0:15], v[64:67], v[72:75], v[0:15]
	v_mfma_f32_32x32x16_bf16 v[16:31], v[64:67], v[76:79], v[16:31]
	v_mfma_f32_32x32x16_bf16 v[0:15], v[68:71], v[220:223], v[0:15]
	v_mfma_f32_32x32x16_bf16 v[16:31], v[68:71], v[224:227], v[16:31]
	s_add_i32 s90, s76, 640
	v_add_u32_e32 v80, s90, v239
	v_add_u32_e32 v83, s90, v240
	v_add_u32_e32 v99, s90, v241
	v_add_u32_e32 v253, s90, v242
	v_add_u32_e32 v254, s90, v101
	v_add_u32_e32 v255, s90, v150
	v_med3_i32 v80, v80, 0, s99
	v_med3_i32 v83, v83, 0, s99
	v_med3_i32 v99, v99, 0, s99
	v_med3_i32 v253, v253, 0, s99
	v_med3_i32 v254, v254, 0, s99
	v_med3_i32 v255, v255, 0, s99
	v_mad_u32_u24 v80, v80, s100, v252
	v_mad_u32_u24 v83, v83, s100, v252
	v_mad_u32_u24 v99, v99, s100, v252
	v_mad_u32_u24 v253, v253, s100, v252
	v_mad_u32_u24 v254, v254, s100, v153
	v_mad_u32_u24 v255, v255, s100, v153
	global_load_dwordx4 v[156:159], v80, s[82:83]
	global_load_dwordx4 v[160:163], v83, s[82:83]
	global_load_dwordx4 v[164:167], v99, s[82:83]
	global_load_dwordx4 v[168:171], v253, s[82:83]
	global_load_dwordx4 v[172:175], v254, s[82:83] offset:768
	global_load_dwordx4 v[176:179], v255, s[82:83] offset:768
	global_load_dwordx4 v[180:183], v254, s[82:83] offset:832
	global_load_dwordx4 v[184:187], v255, s[82:83] offset:832
	ds_read_b64_tr_b16 v[72:73], v231
	ds_read_b64_tr_b16 v[74:75], v231 offset:512
	ds_read_b64_tr_b16 v[76:77], v231 offset:2048
	ds_read_b64_tr_b16 v[78:79], v231 offset:2560
	ds_read_b64_tr_b16 v[220:221], v231 offset:1024
	ds_read_b64_tr_b16 v[222:223], v231 offset:1536
	ds_read_b64_tr_b16 v[224:225], v231 offset:3072
	ds_read_b64_tr_b16 v[226:227], v231 offset:3584
	s_waitcnt vmcnt(8)
	ds_write_b128 v247, v[116:119]
	ds_write_b128 v247, v[120:123] offset:1024
	ds_write_b128 v247, v[124:127] offset:2048
	ds_write_b128 v247, v[128:131] offset:3072
	ds_read_b128 v[116:119], v248
	ds_read_b128 v[120:123], v249
	ds_read_b128 v[124:127], v250
	ds_read_b128 v[128:131], v251
	ds_write_b128 v112, v[132:135]
	ds_write_b128 v112, v[136:139] offset:1024
	ds_write_b128 v112, v[140:143] offset:2048
	ds_write_b128 v112, v[144:147] offset:3072
	v_exp_f32_e32 v188, v188
	v_exp_f32_e32 v189, v189
	v_exp_f32_e32 v190, v190
	v_exp_f32_e32 v191, v191
	v_exp_f32_e32 v192, v192
	v_exp_f32_e32 v193, v193
	s_waitcnt lgkmcnt(4)
	v_mfma_f32_32x32x16_bf16 v[32:47], v[116:119], v[48:51], v[32:47]
	v_exp_f32_e32 v194, v194
	v_exp_f32_e32 v195, v195
	v_mfma_f32_32x32x16_bf16 v[32:47], v[120:123], v[52:55], v[32:47]
	v_exp_f32_e32 v196, v196
	v_exp_f32_e32 v197, v197
	v_exp_f32_e32 v198, v198
	v_mfma_f32_32x32x16_bf16 v[32:47], v[124:127], v[56:59], v[32:47]
	v_exp_f32_e32 v199, v199
	v_exp_f32_e32 v200, v200
	v_mfma_f32_32x32x16_bf16 v[32:47], v[128:131], v[60:63], v[32:47]
	v_exp_f32_e32 v201, v201
	v_exp_f32_e32 v202, v202
	v_exp_f32_e32 v203, v203
	s_add_i32 s90, s76, 384
	v_lshlrev_b32_e32 v84, 2, v107
	v_add_u32_e32 v84, s90, v84
	v_add_u32_e32 v85, 0, v84
	v_add_u32_e32 v86, 4, v84
	v_add_u32_e32 v87, 8, v84
	v_add_u32_e32 v88, 12, v84
	v_cmp_gt_u32_e64 s[30:31], s98, v85
	v_cmp_gt_u32_e64 s[36:37], s98, v86
	v_cmp_gt_u32_e64 s[78:79], s98, v87
	v_cmp_gt_u32_e64 s[50:51], s98, v88
	v_cndmask_b32_e64 v188, 0, v188, s[30:31]
	v_add_u32_e32 v85, 32, v84
	v_cmp_gt_u32_e64 s[30:31], s98, v85
	v_cndmask_b32_e64 v189, 0, v189, s[36:37]
	v_add_u32_e32 v86, 36, v84
	v_cmp_gt_u32_e64 s[36:37], s98, v86
	v_cndmask_b32_e64 v190, 0, v190, s[78:79]
	v_add_u32_e32 v87, 40, v84
	v_cmp_gt_u32_e64 s[78:79], s98, v87
	v_cndmask_b32_e64 v191, 0, v191, s[50:51]
	v_add_u32_e32 v88, 44, v84
	v_cmp_gt_u32_e64 s[50:51], s98, v88
	v_cndmask_b32_e64 v192, 0, v192, s[30:31]
	v_add_u32_e32 v85, 64, v84
	v_cmp_gt_u32_e64 s[30:31], s98, v85
	v_cndmask_b32_e64 v193, 0, v193, s[36:37]
	v_add_u32_e32 v86, 68, v84
	v_cmp_gt_u32_e64 s[36:37], s98, v86
	v_cndmask_b32_e64 v194, 0, v194, s[78:79]
	v_add_u32_e32 v87, 72, v84
	v_cmp_gt_u32_e64 s[78:79], s98, v87
	v_cndmask_b32_e64 v195, 0, v195, s[50:51]
	v_add_u32_e32 v88, 76, v84
	v_cmp_gt_u32_e64 s[50:51], s98, v88
	v_cndmask_b32_e64 v196, 0, v196, s[30:31]
	v_add_u32_e32 v85, 96, v84
	v_cmp_gt_u32_e64 s[30:31], s98, v85
	v_cndmask_b32_e64 v197, 0, v197, s[36:37]
	v_add_u32_e32 v86, 100, v84
	v_cmp_gt_u32_e64 s[36:37], s98, v86
	v_cndmask_b32_e64 v198, 0, v198, s[78:79]
	v_add_u32_e32 v87, 104, v84
	v_cmp_gt_u32_e64 s[78:79], s98, v87
	v_cndmask_b32_e64 v199, 0, v199, s[50:51]
	v_add_u32_e32 v88, 108, v84
	v_cmp_gt_u32_e64 s[50:51], s98, v88
	v_nop
	v_cndmask_b32_e64 v200, 0, v200, s[30:31]
	v_cndmask_b32_e64 v201, 0, v201, s[36:37]
	v_cndmask_b32_e64 v202, 0, v202, s[78:79]
	v_cndmask_b32_e64 v203, 0, v203, s[50:51]
	v_cvt_pk_bf16_f32 v64, v188, v189
	v_cvt_pk_bf16_f32 v65, v190, v191
	v_cvt_pk_bf16_f32 v66, v192, v193
	v_cvt_pk_bf16_f32 v67, v194, v195
	v_cvt_pk_bf16_f32 v68, v196, v197
	v_cvt_pk_bf16_f32 v69, v198, v199
	v_cvt_pk_bf16_f32 v70, v200, v201
	v_cvt_pk_bf16_f32 v71, v202, v203
	v_pk_add_f32 v[232:233], v[232:233], v[188:189]
	v_pk_add_f32 v[232:233], v[232:233], v[190:191]
	v_pk_add_f32 v[232:233], v[232:233], v[192:193]
	v_pk_add_f32 v[232:233], v[232:233], v[194:195]
	v_pk_add_f32 v[232:233], v[232:233], v[196:197]
	v_pk_add_f32 v[232:233], v[232:233], v[198:199]
	v_pk_add_f32 v[232:233], v[232:233], v[200:201]
	v_pk_add_f32 v[232:233], v[232:233], v[202:203]
	ds_read2_b32 v[188:189], v115 offset0:224 offset1:225
	ds_read2_b32 v[190:191], v115 offset0:226 offset1:227
	ds_read2_b32 v[192:193], v115 offset0:232 offset1:233
	ds_read2_b32 v[194:195], v115 offset0:234 offset1:235
	ds_read2_b32 v[196:197], v115 offset0:240 offset1:241
	ds_read2_b32 v[198:199], v115 offset0:242 offset1:243
	ds_read2_b32 v[200:201], v115 offset0:248 offset1:249
	ds_read2_b32 v[202:203], v115 offset0:250 offset1:251
	v_mfma_f32_32x32x16_bf16 v[0:15], v[64:67], v[72:75], v[0:15]
	v_mfma_f32_32x32x16_bf16 v[16:31], v[64:67], v[76:79], v[16:31]
	v_mfma_f32_32x32x16_bf16 v[0:15], v[68:71], v[220:223], v[0:15]
	v_mfma_f32_32x32x16_bf16 v[16:31], v[68:71], v[224:227], v[16:31]
	s_add_i32 s90, s76, -1024
	v_add_u32_e32 v80, s90, v243
	v_add_u32_e32 v83, s90, v244
	v_add_u32_e32 v99, s90, v245
	v_add_u32_e32 v253, s90, v246
	v_add_u32_e32 v254, s90, v148
	v_add_u32_e32 v255, s90, v151
	v_med3_i32 v80, v80, 0, s99
	v_med3_i32 v83, v83, 0, s99
	v_med3_i32 v99, v99, 0, s99
	v_med3_i32 v253, v253, 0, s99
	v_med3_i32 v254, v254, 0, s99
	v_med3_i32 v255, v255, 0, s99
	v_mad_u32_u24 v80, v80, s100, v252
	v_mad_u32_u24 v83, v83, s100, v252
	v_mad_u32_u24 v99, v99, s100, v252
	v_mad_u32_u24 v253, v253, s100, v252
	v_mad_u32_u24 v254, v254, s100, v153
	v_mad_u32_u24 v255, v255, s100, v153
	global_load_dwordx4 v[116:119], v80, s[82:83]
	global_load_dwordx4 v[120:123], v83, s[82:83]
	global_load_dwordx4 v[124:127], v99, s[82:83]
	global_load_dwordx4 v[128:131], v253, s[82:83]
	global_load_dwordx4 v[132:135], v254, s[82:83] offset:768
	global_load_dwordx4 v[136:139], v255, s[82:83] offset:768
	global_load_dwordx4 v[140:143], v254, s[82:83] offset:832
	global_load_dwordx4 v[144:147], v255, s[82:83] offset:832
	ds_read_b64_tr_b16 v[72:73], v231
	ds_read_b64_tr_b16 v[74:75], v231 offset:512
	ds_read_b64_tr_b16 v[76:77], v231 offset:2048
	ds_read_b64_tr_b16 v[78:79], v231 offset:2560
	ds_read_b64_tr_b16 v[220:221], v231 offset:1024
	ds_read_b64_tr_b16 v[222:223], v231 offset:1536
	ds_read_b64_tr_b16 v[224:225], v231 offset:3072
	ds_read_b64_tr_b16 v[226:227], v231 offset:3584
	s_waitcnt vmcnt(8)
	ds_write_b128 v247, v[156:159]
	ds_write_b128 v247, v[160:163] offset:1024
	ds_write_b128 v247, v[164:167] offset:2048
	ds_write_b128 v247, v[168:171] offset:3072
	ds_read_b128 v[156:159], v248
	ds_read_b128 v[160:163], v249
	ds_read_b128 v[164:167], v250
	ds_read_b128 v[168:171], v251
	ds_write_b128 v112, v[172:175]
	ds_write_b128 v112, v[176:179] offset:1024
	ds_write_b128 v112, v[180:183] offset:2048
	ds_write_b128 v112, v[184:187] offset:3072
	v_exp_f32_e32 v32, v32
	v_exp_f32_e32 v33, v33
	v_exp_f32_e32 v34, v34
	v_exp_f32_e32 v35, v35
	v_exp_f32_e32 v36, v36
	v_exp_f32_e32 v37, v37
	s_waitcnt lgkmcnt(4)
	v_mfma_f32_32x32x16_bf16 v[188:203], v[156:159], v[48:51], v[188:203]
	v_exp_f32_e32 v38, v38
	v_exp_f32_e32 v39, v39
	v_mfma_f32_32x32x16_bf16 v[188:203], v[160:163], v[52:55], v[188:203]
	v_exp_f32_e32 v40, v40
	v_exp_f32_e32 v41, v41
	v_exp_f32_e32 v42, v42
	v_mfma_f32_32x32x16_bf16 v[188:203], v[164:167], v[56:59], v[188:203]
	v_exp_f32_e32 v43, v43
	v_exp_f32_e32 v44, v44
	v_mfma_f32_32x32x16_bf16 v[188:203], v[168:171], v[60:63], v[188:203]
	v_exp_f32_e32 v45, v45
	v_exp_f32_e32 v46, v46
	v_exp_f32_e32 v47, v47
	s_add_i32 s90, s76, 512
	v_lshlrev_b32_e32 v84, 2, v107
	v_add_u32_e32 v84, s90, v84
	v_add_u32_e32 v85, 0, v84
	v_add_u32_e32 v86, 4, v84
	v_add_u32_e32 v87, 8, v84
	v_add_u32_e32 v88, 12, v84
	v_cmp_gt_u32_e64 s[30:31], s98, v85
	v_cmp_gt_u32_e64 s[36:37], s98, v86
	v_cmp_gt_u32_e64 s[78:79], s98, v87
	v_cmp_gt_u32_e64 s[50:51], s98, v88
	v_cndmask_b32_e64 v32, 0, v32, s[30:31]
	v_add_u32_e32 v85, 32, v84
	v_cmp_gt_u32_e64 s[30:31], s98, v85
	v_cndmask_b32_e64 v33, 0, v33, s[36:37]
	v_add_u32_e32 v86, 36, v84
	v_cmp_gt_u32_e64 s[36:37], s98, v86
	v_cndmask_b32_e64 v34, 0, v34, s[78:79]
	v_add_u32_e32 v87, 40, v84
	v_cmp_gt_u32_e64 s[78:79], s98, v87
	v_cndmask_b32_e64 v35, 0, v35, s[50:51]
	v_add_u32_e32 v88, 44, v84
	v_cmp_gt_u32_e64 s[50:51], s98, v88
	v_cndmask_b32_e64 v36, 0, v36, s[30:31]
	v_add_u32_e32 v85, 64, v84
	v_cmp_gt_u32_e64 s[30:31], s98, v85
	v_cndmask_b32_e64 v37, 0, v37, s[36:37]
	v_add_u32_e32 v86, 68, v84
	v_cmp_gt_u32_e64 s[36:37], s98, v86
	v_cndmask_b32_e64 v38, 0, v38, s[78:79]
	v_add_u32_e32 v87, 72, v84
	v_cmp_gt_u32_e64 s[78:79], s98, v87
	v_cndmask_b32_e64 v39, 0, v39, s[50:51]
	v_add_u32_e32 v88, 76, v84
	v_cmp_gt_u32_e64 s[50:51], s98, v88
	v_cndmask_b32_e64 v40, 0, v40, s[30:31]
	v_add_u32_e32 v85, 96, v84
	v_cmp_gt_u32_e64 s[30:31], s98, v85
	v_cndmask_b32_e64 v41, 0, v41, s[36:37]
	v_add_u32_e32 v86, 100, v84
	v_cmp_gt_u32_e64 s[36:37], s98, v86
	v_cndmask_b32_e64 v42, 0, v42, s[78:79]
	v_add_u32_e32 v87, 104, v84
	v_cmp_gt_u32_e64 s[78:79], s98, v87
	v_cndmask_b32_e64 v43, 0, v43, s[50:51]
	v_add_u32_e32 v88, 108, v84
	v_cmp_gt_u32_e64 s[50:51], s98, v88
	v_nop
	v_cndmask_b32_e64 v44, 0, v44, s[30:31]
	v_cndmask_b32_e64 v45, 0, v45, s[36:37]
	v_cndmask_b32_e64 v46, 0, v46, s[78:79]
	v_cndmask_b32_e64 v47, 0, v47, s[50:51]
	v_cvt_pk_bf16_f32 v64, v32, v33
	v_cvt_pk_bf16_f32 v65, v34, v35
	v_cvt_pk_bf16_f32 v66, v36, v37
	v_cvt_pk_bf16_f32 v67, v38, v39
	v_cvt_pk_bf16_f32 v68, v40, v41
	v_cvt_pk_bf16_f32 v69, v42, v43
	v_cvt_pk_bf16_f32 v70, v44, v45
	v_cvt_pk_bf16_f32 v71, v46, v47
	v_pk_add_f32 v[232:233], v[232:233], v[32:33]
	v_pk_add_f32 v[232:233], v[232:233], v[34:35]
	v_pk_add_f32 v[232:233], v[232:233], v[36:37]
	v_pk_add_f32 v[232:233], v[232:233], v[38:39]
	v_pk_add_f32 v[232:233], v[232:233], v[40:41]
	v_pk_add_f32 v[232:233], v[232:233], v[42:43]
	v_pk_add_f32 v[232:233], v[232:233], v[44:45]
	v_pk_add_f32 v[232:233], v[232:233], v[46:47]
	v_mov_b32_e32 v115, v230
	ds_read2_b32 v[32:33], v115 offset0:0 offset1:1
	ds_read2_b32 v[34:35], v115 offset0:2 offset1:3
	ds_read2_b32 v[36:37], v115 offset0:8 offset1:9
	ds_read2_b32 v[38:39], v115 offset0:10 offset1:11
	ds_read2_b32 v[40:41], v115 offset0:16 offset1:17
	ds_read2_b32 v[42:43], v115 offset0:18 offset1:19
	ds_read2_b32 v[44:45], v115 offset0:24 offset1:25
	ds_read2_b32 v[46:47], v115 offset0:26 offset1:27
	v_mfma_f32_32x32x16_bf16 v[0:15], v[64:67], v[72:75], v[0:15]
	v_mfma_f32_32x32x16_bf16 v[16:31], v[64:67], v[76:79], v[16:31]
	v_mfma_f32_32x32x16_bf16 v[0:15], v[68:71], v[220:223], v[0:15]
	v_mfma_f32_32x32x16_bf16 v[16:31], v[68:71], v[224:227], v[16:31]
	s_add_i32 s90, s76, -512
	v_add_u32_e32 v80, s90, v243
	v_add_u32_e32 v83, s90, v244
	v_add_u32_e32 v99, s90, v245
	v_add_u32_e32 v253, s90, v246
	v_add_u32_e32 v254, s90, v148
	v_add_u32_e32 v255, s90, v151
	v_med3_i32 v80, v80, 0, s99
	v_med3_i32 v83, v83, 0, s99
	v_med3_i32 v99, v99, 0, s99
	v_med3_i32 v253, v253, 0, s99
	v_med3_i32 v254, v254, 0, s99
	v_med3_i32 v255, v255, 0, s99
	v_mad_u32_u24 v80, v80, s100, v252
	v_mad_u32_u24 v83, v83, s100, v252
	v_mad_u32_u24 v99, v99, s100, v252
	v_mad_u32_u24 v253, v253, s100, v252
	v_mad_u32_u24 v254, v254, s100, v153
	v_mad_u32_u24 v255, v255, s100, v153
	global_load_dwordx4 v[156:159], v80, s[82:83]
	global_load_dwordx4 v[160:163], v83, s[82:83]
	global_load_dwordx4 v[164:167], v99, s[82:83]
	global_load_dwordx4 v[168:171], v253, s[82:83]
	global_load_dwordx4 v[172:175], v254, s[82:83] offset:768
	global_load_dwordx4 v[176:179], v255, s[82:83] offset:768
	global_load_dwordx4 v[180:183], v254, s[82:83] offset:832
	global_load_dwordx4 v[184:187], v255, s[82:83] offset:832
	ds_read_b64_tr_b16 v[72:73], v231
	ds_read_b64_tr_b16 v[74:75], v231 offset:512
	ds_read_b64_tr_b16 v[76:77], v231 offset:2048
	ds_read_b64_tr_b16 v[78:79], v231 offset:2560
	ds_read_b64_tr_b16 v[220:221], v231 offset:1024
	ds_read_b64_tr_b16 v[222:223], v231 offset:1536
	ds_read_b64_tr_b16 v[224:225], v231 offset:3072
	ds_read_b64_tr_b16 v[226:227], v231 offset:3584
	s_waitcnt vmcnt(8)
	ds_write_b128 v247, v[116:119]
	ds_write_b128 v247, v[120:123] offset:1024
	ds_write_b128 v247, v[124:127] offset:2048
	ds_write_b128 v247, v[128:131] offset:3072
	ds_read_b128 v[116:119], v248
	ds_read_b128 v[120:123], v249
	ds_read_b128 v[124:127], v250
	ds_read_b128 v[128:131], v251
	ds_write_b128 v112, v[132:135]
	ds_write_b128 v112, v[136:139] offset:1024
	ds_write_b128 v112, v[140:143] offset:2048
	ds_write_b128 v112, v[144:147] offset:3072
	v_exp_f32_e32 v188, v188
	v_exp_f32_e32 v189, v189
	v_exp_f32_e32 v190, v190
	v_exp_f32_e32 v191, v191
	v_exp_f32_e32 v192, v192
	v_exp_f32_e32 v193, v193
	s_waitcnt lgkmcnt(4)
	v_mfma_f32_32x32x16_bf16 v[32:47], v[116:119], v[48:51], v[32:47]
	v_exp_f32_e32 v194, v194
	v_exp_f32_e32 v195, v195
	v_mfma_f32_32x32x16_bf16 v[32:47], v[120:123], v[52:55], v[32:47]
	v_exp_f32_e32 v196, v196
	v_exp_f32_e32 v197, v197
	v_exp_f32_e32 v198, v198
	v_mfma_f32_32x32x16_bf16 v[32:47], v[124:127], v[56:59], v[32:47]
	v_exp_f32_e32 v199, v199
	v_exp_f32_e32 v200, v200
	v_mfma_f32_32x32x16_bf16 v[32:47], v[128:131], v[60:63], v[32:47]
	v_exp_f32_e32 v201, v201
	v_exp_f32_e32 v202, v202
	v_exp_f32_e32 v203, v203
	s_add_i32 s90, s76, 640
	v_lshlrev_b32_e32 v84, 2, v107
	v_add_u32_e32 v84, s90, v84
	v_add_u32_e32 v85, 0, v84
	v_add_u32_e32 v86, 4, v84
	v_add_u32_e32 v87, 8, v84
	v_add_u32_e32 v88, 12, v84
	v_cmp_gt_u32_e64 s[30:31], s98, v85
	v_cmp_gt_u32_e64 s[36:37], s98, v86
	v_cmp_gt_u32_e64 s[78:79], s98, v87
	v_cmp_gt_u32_e64 s[50:51], s98, v88
	v_cndmask_b32_e64 v188, 0, v188, s[30:31]
	v_add_u32_e32 v85, 32, v84
	v_cmp_gt_u32_e64 s[30:31], s98, v85
	v_cndmask_b32_e64 v189, 0, v189, s[36:37]
	v_add_u32_e32 v86, 36, v84
	v_cmp_gt_u32_e64 s[36:37], s98, v86
	v_cndmask_b32_e64 v190, 0, v190, s[78:79]
	v_add_u32_e32 v87, 40, v84
	v_cmp_gt_u32_e64 s[78:79], s98, v87
	v_cndmask_b32_e64 v191, 0, v191, s[50:51]
	v_add_u32_e32 v88, 44, v84
	v_cmp_gt_u32_e64 s[50:51], s98, v88
	v_cndmask_b32_e64 v192, 0, v192, s[30:31]
	v_add_u32_e32 v85, 64, v84
	v_cmp_gt_u32_e64 s[30:31], s98, v85
	v_cndmask_b32_e64 v193, 0, v193, s[36:37]
	v_add_u32_e32 v86, 68, v84
	v_cmp_gt_u32_e64 s[36:37], s98, v86
	v_cndmask_b32_e64 v194, 0, v194, s[78:79]
	v_add_u32_e32 v87, 72, v84
	v_cmp_gt_u32_e64 s[78:79], s98, v87
	v_cndmask_b32_e64 v195, 0, v195, s[50:51]
	v_add_u32_e32 v88, 76, v84
	v_cmp_gt_u32_e64 s[50:51], s98, v88
	v_cndmask_b32_e64 v196, 0, v196, s[30:31]
	v_add_u32_e32 v85, 96, v84
	v_cmp_gt_u32_e64 s[30:31], s98, v85
	v_cndmask_b32_e64 v197, 0, v197, s[36:37]
	v_add_u32_e32 v86, 100, v84
	v_cmp_gt_u32_e64 s[36:37], s98, v86
	v_cndmask_b32_e64 v198, 0, v198, s[78:79]
	v_add_u32_e32 v87, 104, v84
	v_cmp_gt_u32_e64 s[78:79], s98, v87
	v_cndmask_b32_e64 v199, 0, v199, s[50:51]
	v_add_u32_e32 v88, 108, v84
	v_cmp_gt_u32_e64 s[50:51], s98, v88
	v_nop
	v_cndmask_b32_e64 v200, 0, v200, s[30:31]
	v_cndmask_b32_e64 v201, 0, v201, s[36:37]
	v_cndmask_b32_e64 v202, 0, v202, s[78:79]
	v_cndmask_b32_e64 v203, 0, v203, s[50:51]
	v_cvt_pk_bf16_f32 v64, v188, v189
	v_cvt_pk_bf16_f32 v65, v190, v191
	v_cvt_pk_bf16_f32 v66, v192, v193
	v_cvt_pk_bf16_f32 v67, v194, v195
	v_cvt_pk_bf16_f32 v68, v196, v197
	v_cvt_pk_bf16_f32 v69, v198, v199
	v_cvt_pk_bf16_f32 v70, v200, v201
	v_cvt_pk_bf16_f32 v71, v202, v203
	v_pk_add_f32 v[232:233], v[232:233], v[188:189]
	v_pk_add_f32 v[232:233], v[232:233], v[190:191]
	v_pk_add_f32 v[232:233], v[232:233], v[192:193]
	v_pk_add_f32 v[232:233], v[232:233], v[194:195]
	v_pk_add_f32 v[232:233], v[232:233], v[196:197]
	v_pk_add_f32 v[232:233], v[232:233], v[198:199]
	v_pk_add_f32 v[232:233], v[232:233], v[200:201]
	v_pk_add_f32 v[232:233], v[232:233], v[202:203]
	ds_read2_b32 v[188:189], v115 offset0:32 offset1:33
	ds_read2_b32 v[190:191], v115 offset0:34 offset1:35
	ds_read2_b32 v[192:193], v115 offset0:40 offset1:41
	ds_read2_b32 v[194:195], v115 offset0:42 offset1:43
	ds_read2_b32 v[196:197], v115 offset0:48 offset1:49
	ds_read2_b32 v[198:199], v115 offset0:50 offset1:51
	ds_read2_b32 v[200:201], v115 offset0:56 offset1:57
	ds_read2_b32 v[202:203], v115 offset0:58 offset1:59
	v_mfma_f32_32x32x16_bf16 v[0:15], v[64:67], v[72:75], v[0:15]
	v_mfma_f32_32x32x16_bf16 v[16:31], v[64:67], v[76:79], v[16:31]
	v_mfma_f32_32x32x16_bf16 v[0:15], v[68:71], v[220:223], v[0:15]
	v_mfma_f32_32x32x16_bf16 v[16:31], v[68:71], v[224:227], v[16:31]
	s_add_i32 s90, s76, 0
	v_add_u32_e32 v80, s90, v243
	v_add_u32_e32 v83, s90, v244
	v_add_u32_e32 v99, s90, v245
	v_add_u32_e32 v253, s90, v246
	v_add_u32_e32 v254, s90, v148
	v_add_u32_e32 v255, s90, v151
	v_med3_i32 v80, v80, 0, s99
	v_med3_i32 v83, v83, 0, s99
	v_med3_i32 v99, v99, 0, s99
	v_med3_i32 v253, v253, 0, s99
	v_med3_i32 v254, v254, 0, s99
	v_med3_i32 v255, v255, 0, s99
	v_mad_u32_u24 v80, v80, s100, v252
	v_mad_u32_u24 v83, v83, s100, v252
	v_mad_u32_u24 v99, v99, s100, v252
	v_mad_u32_u24 v253, v253, s100, v252
	v_mad_u32_u24 v254, v254, s100, v153
	v_mad_u32_u24 v255, v255, s100, v153
	global_load_dwordx4 v[116:119], v80, s[82:83]
	global_load_dwordx4 v[120:123], v83, s[82:83]
	global_load_dwordx4 v[124:127], v99, s[82:83]
	global_load_dwordx4 v[128:131], v253, s[82:83]
	global_load_dwordx4 v[132:135], v254, s[82:83] offset:768
	global_load_dwordx4 v[136:139], v255, s[82:83] offset:768
	global_load_dwordx4 v[140:143], v254, s[82:83] offset:832
	global_load_dwordx4 v[144:147], v255, s[82:83] offset:832
	ds_read_b64_tr_b16 v[72:73], v231
	ds_read_b64_tr_b16 v[74:75], v231 offset:512
	ds_read_b64_tr_b16 v[76:77], v231 offset:2048
	ds_read_b64_tr_b16 v[78:79], v231 offset:2560
	ds_read_b64_tr_b16 v[220:221], v231 offset:1024
	ds_read_b64_tr_b16 v[222:223], v231 offset:1536
	ds_read_b64_tr_b16 v[224:225], v231 offset:3072
	ds_read_b64_tr_b16 v[226:227], v231 offset:3584
	s_waitcnt vmcnt(8)
	ds_write_b128 v247, v[156:159]
	ds_write_b128 v247, v[160:163] offset:1024
	ds_write_b128 v247, v[164:167] offset:2048
	ds_write_b128 v247, v[168:171] offset:3072
	ds_read_b128 v[156:159], v248
	ds_read_b128 v[160:163], v249
	ds_read_b128 v[164:167], v250
	ds_read_b128 v[168:171], v251
	ds_write_b128 v112, v[172:175]
	ds_write_b128 v112, v[176:179] offset:1024
	ds_write_b128 v112, v[180:183] offset:2048
	ds_write_b128 v112, v[184:187] offset:3072
	v_exp_f32_e32 v32, v32
	v_exp_f32_e32 v33, v33
	v_exp_f32_e32 v34, v34
	v_exp_f32_e32 v35, v35
	v_exp_f32_e32 v36, v36
	v_exp_f32_e32 v37, v37
	s_waitcnt lgkmcnt(4)
	v_mfma_f32_32x32x16_bf16 v[188:203], v[156:159], v[48:51], v[188:203]
	v_exp_f32_e32 v38, v38
	v_exp_f32_e32 v39, v39
	v_mfma_f32_32x32x16_bf16 v[188:203], v[160:163], v[52:55], v[188:203]
	v_exp_f32_e32 v40, v40
	v_exp_f32_e32 v41, v41
	v_exp_f32_e32 v42, v42
	v_mfma_f32_32x32x16_bf16 v[188:203], v[164:167], v[56:59], v[188:203]
	v_exp_f32_e32 v43, v43
	v_exp_f32_e32 v44, v44
	v_mfma_f32_32x32x16_bf16 v[188:203], v[168:171], v[60:63], v[188:203]
	v_exp_f32_e32 v45, v45
	v_exp_f32_e32 v46, v46
	v_exp_f32_e32 v47, v47
	s_add_i32 s90, s76, -1024
	v_lshlrev_b32_e32 v84, 4, v107
	v_add_u32_e32 v84, s90, v84
	v_add_u32_e32 v85, 0, v84
	v_add_u32_e32 v86, 16, v84
	v_add_u32_e32 v87, 32, v84
	v_add_u32_e32 v88, 48, v84
	v_cmp_gt_u32_e64 s[30:31], s98, v85
	v_cmp_gt_u32_e64 s[36:37], s98, v86
	v_cmp_gt_u32_e64 s[78:79], s98, v87
	v_cmp_gt_u32_e64 s[50:51], s98, v88
	v_cndmask_b32_e64 v32, 0, v32, s[30:31]
	v_add_u32_e32 v85, 128, v84
	v_cmp_gt_u32_e64 s[30:31], s98, v85
	v_cndmask_b32_e64 v33, 0, v33, s[36:37]
	v_add_u32_e32 v86, 144, v84
	v_cmp_gt_u32_e64 s[36:37], s98, v86
	v_cndmask_b32_e64 v34, 0, v34, s[78:79]
	v_add_u32_e32 v87, 160, v84
	v_cmp_gt_u32_e64 s[78:79], s98, v87
	v_cndmask_b32_e64 v35, 0, v35, s[50:51]
	v_add_u32_e32 v88, 176, v84
	v_cmp_gt_u32_e64 s[50:51], s98, v88
	v_cndmask_b32_e64 v36, 0, v36, s[30:31]
	v_add_u32_e32 v85, 256, v84
	v_cmp_gt_u32_e64 s[30:31], s98, v85
	v_cndmask_b32_e64 v37, 0, v37, s[36:37]
	v_add_u32_e32 v86, 272, v84
	v_cmp_gt_u32_e64 s[36:37], s98, v86
	v_cndmask_b32_e64 v38, 0, v38, s[78:79]
	v_add_u32_e32 v87, 288, v84
	v_cmp_gt_u32_e64 s[78:79], s98, v87
	v_cndmask_b32_e64 v39, 0, v39, s[50:51]
	v_add_u32_e32 v88, 304, v84
	v_cmp_gt_u32_e64 s[50:51], s98, v88
	v_cndmask_b32_e64 v40, 0, v40, s[30:31]
	v_add_u32_e32 v85, 384, v84
	v_cmp_gt_u32_e64 s[30:31], s98, v85
	v_cndmask_b32_e64 v41, 0, v41, s[36:37]
	v_add_u32_e32 v86, 400, v84
	v_cmp_gt_u32_e64 s[36:37], s98, v86
	v_cndmask_b32_e64 v42, 0, v42, s[78:79]
	v_add_u32_e32 v87, 416, v84
	v_cmp_gt_u32_e64 s[78:79], s98, v87
	v_cndmask_b32_e64 v43, 0, v43, s[50:51]
	v_add_u32_e32 v88, 432, v84
	v_cmp_gt_u32_e64 s[50:51], s98, v88
	v_nop
	v_cndmask_b32_e64 v44, 0, v44, s[30:31]
	v_cndmask_b32_e64 v45, 0, v45, s[36:37]
	v_cndmask_b32_e64 v46, 0, v46, s[78:79]
	v_cndmask_b32_e64 v47, 0, v47, s[50:51]
	v_cvt_pk_bf16_f32 v64, v32, v33
	v_cvt_pk_bf16_f32 v65, v34, v35
	v_cvt_pk_bf16_f32 v66, v36, v37
	v_cvt_pk_bf16_f32 v67, v38, v39
	v_cvt_pk_bf16_f32 v68, v40, v41
	v_cvt_pk_bf16_f32 v69, v42, v43
	v_cvt_pk_bf16_f32 v70, v44, v45
	v_cvt_pk_bf16_f32 v71, v46, v47
	v_pk_add_f32 v[232:233], v[232:233], v[32:33]
	v_pk_add_f32 v[232:233], v[232:233], v[34:35]
	v_pk_add_f32 v[232:233], v[232:233], v[36:37]
	v_pk_add_f32 v[232:233], v[232:233], v[38:39]
	v_pk_add_f32 v[232:233], v[232:233], v[40:41]
	v_pk_add_f32 v[232:233], v[232:233], v[42:43]
	v_pk_add_f32 v[232:233], v[232:233], v[44:45]
	v_pk_add_f32 v[232:233], v[232:233], v[46:47]
	ds_read2_b32 v[32:33], v115 offset0:64 offset1:65
	ds_read2_b32 v[34:35], v115 offset0:66 offset1:67
	ds_read2_b32 v[36:37], v115 offset0:72 offset1:73
	ds_read2_b32 v[38:39], v115 offset0:74 offset1:75
	ds_read2_b32 v[40:41], v115 offset0:80 offset1:81
	ds_read2_b32 v[42:43], v115 offset0:82 offset1:83
	ds_read2_b32 v[44:45], v115 offset0:88 offset1:89
	ds_read2_b32 v[46:47], v115 offset0:90 offset1:91
	v_mfma_f32_32x32x16_bf16 v[0:15], v[64:67], v[72:75], v[0:15]
	v_mfma_f32_32x32x16_bf16 v[16:31], v[64:67], v[76:79], v[16:31]
	v_mfma_f32_32x32x16_bf16 v[0:15], v[68:71], v[220:223], v[0:15]
	v_mfma_f32_32x32x16_bf16 v[16:31], v[68:71], v[224:227], v[16:31]
	s_add_i32 s90, s76, 512
	v_add_u32_e32 v80, s90, v243
	v_add_u32_e32 v83, s90, v244
	v_add_u32_e32 v99, s90, v245
	v_add_u32_e32 v253, s90, v246
	v_add_u32_e32 v254, s90, v148
	v_add_u32_e32 v255, s90, v151
	v_med3_i32 v80, v80, 0, s99
	v_med3_i32 v83, v83, 0, s99
	v_med3_i32 v99, v99, 0, s99
	v_med3_i32 v253, v253, 0, s99
	v_med3_i32 v254, v254, 0, s99
	v_med3_i32 v255, v255, 0, s99
	v_mad_u32_u24 v80, v80, s100, v252
	v_mad_u32_u24 v83, v83, s100, v252
	v_mad_u32_u24 v99, v99, s100, v252
	v_mad_u32_u24 v253, v253, s100, v252
	v_mad_u32_u24 v254, v254, s100, v153
	v_mad_u32_u24 v255, v255, s100, v153
	global_load_dwordx4 v[156:159], v80, s[82:83]
	global_load_dwordx4 v[160:163], v83, s[82:83]
	global_load_dwordx4 v[164:167], v99, s[82:83]
	global_load_dwordx4 v[168:171], v253, s[82:83]
	global_load_dwordx4 v[172:175], v254, s[82:83] offset:768
	global_load_dwordx4 v[176:179], v255, s[82:83] offset:768
	global_load_dwordx4 v[180:183], v254, s[82:83] offset:832
	global_load_dwordx4 v[184:187], v255, s[82:83] offset:832
	ds_read_b64_tr_b16 v[72:73], v231
	ds_read_b64_tr_b16 v[74:75], v231 offset:512
	ds_read_b64_tr_b16 v[76:77], v231 offset:2048
	ds_read_b64_tr_b16 v[78:79], v231 offset:2560
	ds_read_b64_tr_b16 v[220:221], v231 offset:1024
	ds_read_b64_tr_b16 v[222:223], v231 offset:1536
	ds_read_b64_tr_b16 v[224:225], v231 offset:3072
	ds_read_b64_tr_b16 v[226:227], v231 offset:3584
	s_waitcnt vmcnt(8)
	ds_write_b128 v247, v[116:119]
	ds_write_b128 v247, v[120:123] offset:1024
	ds_write_b128 v247, v[124:127] offset:2048
	ds_write_b128 v247, v[128:131] offset:3072
	ds_read_b128 v[116:119], v248
	ds_read_b128 v[120:123], v249
	ds_read_b128 v[124:127], v250
	ds_read_b128 v[128:131], v251
	ds_write_b128 v112, v[132:135]
	ds_write_b128 v112, v[136:139] offset:1024
	ds_write_b128 v112, v[140:143] offset:2048
	ds_write_b128 v112, v[144:147] offset:3072
	v_exp_f32_e32 v188, v188
	v_exp_f32_e32 v189, v189
	v_exp_f32_e32 v190, v190
	v_exp_f32_e32 v191, v191
	v_exp_f32_e32 v192, v192
	v_exp_f32_e32 v193, v193
	s_waitcnt lgkmcnt(4)
	v_mfma_f32_32x32x16_bf16 v[32:47], v[116:119], v[48:51], v[32:47]
	v_exp_f32_e32 v194, v194
	v_exp_f32_e32 v195, v195
	v_mfma_f32_32x32x16_bf16 v[32:47], v[120:123], v[52:55], v[32:47]
	v_exp_f32_e32 v196, v196
	v_exp_f32_e32 v197, v197
	v_exp_f32_e32 v198, v198
	v_mfma_f32_32x32x16_bf16 v[32:47], v[124:127], v[56:59], v[32:47]
	v_exp_f32_e32 v199, v199
	v_exp_f32_e32 v200, v200
	v_mfma_f32_32x32x16_bf16 v[32:47], v[128:131], v[60:63], v[32:47]
	v_exp_f32_e32 v201, v201
	v_exp_f32_e32 v202, v202
	v_exp_f32_e32 v203, v203
	s_add_i32 s90, s76, -512
	v_lshlrev_b32_e32 v84, 4, v107
	v_add_u32_e32 v84, s90, v84
	v_add_u32_e32 v85, 0, v84
	v_add_u32_e32 v86, 16, v84
	v_add_u32_e32 v87, 32, v84
	v_add_u32_e32 v88, 48, v84
	v_cmp_gt_u32_e64 s[30:31], s98, v85
	v_cmp_gt_u32_e64 s[36:37], s98, v86
	v_cmp_gt_u32_e64 s[78:79], s98, v87
	v_cmp_gt_u32_e64 s[50:51], s98, v88
	v_cndmask_b32_e64 v188, 0, v188, s[30:31]
	v_add_u32_e32 v85, 128, v84
	v_cmp_gt_u32_e64 s[30:31], s98, v85
	v_cndmask_b32_e64 v189, 0, v189, s[36:37]
	v_add_u32_e32 v86, 144, v84
	v_cmp_gt_u32_e64 s[36:37], s98, v86
	v_cndmask_b32_e64 v190, 0, v190, s[78:79]
	v_add_u32_e32 v87, 160, v84
	v_cmp_gt_u32_e64 s[78:79], s98, v87
	v_cndmask_b32_e64 v191, 0, v191, s[50:51]
	v_add_u32_e32 v88, 176, v84
	v_cmp_gt_u32_e64 s[50:51], s98, v88
	v_cndmask_b32_e64 v192, 0, v192, s[30:31]
	v_add_u32_e32 v85, 256, v84
	v_cmp_gt_u32_e64 s[30:31], s98, v85
	v_cndmask_b32_e64 v193, 0, v193, s[36:37]
	v_add_u32_e32 v86, 272, v84
	v_cmp_gt_u32_e64 s[36:37], s98, v86
	v_cndmask_b32_e64 v194, 0, v194, s[78:79]
	v_add_u32_e32 v87, 288, v84
	v_cmp_gt_u32_e64 s[78:79], s98, v87
	v_cndmask_b32_e64 v195, 0, v195, s[50:51]
	v_add_u32_e32 v88, 304, v84
	v_cmp_gt_u32_e64 s[50:51], s98, v88
	v_cndmask_b32_e64 v196, 0, v196, s[30:31]
	v_add_u32_e32 v85, 384, v84
	v_cmp_gt_u32_e64 s[30:31], s98, v85
	v_cndmask_b32_e64 v197, 0, v197, s[36:37]
	v_add_u32_e32 v86, 400, v84
	v_cmp_gt_u32_e64 s[36:37], s98, v86
	v_cndmask_b32_e64 v198, 0, v198, s[78:79]
	v_add_u32_e32 v87, 416, v84
	v_cmp_gt_u32_e64 s[78:79], s98, v87
	v_cndmask_b32_e64 v199, 0, v199, s[50:51]
	v_add_u32_e32 v88, 432, v84
	v_cmp_gt_u32_e64 s[50:51], s98, v88
	v_nop
	v_cndmask_b32_e64 v200, 0, v200, s[30:31]
	v_cndmask_b32_e64 v201, 0, v201, s[36:37]
	v_cndmask_b32_e64 v202, 0, v202, s[78:79]
	v_cndmask_b32_e64 v203, 0, v203, s[50:51]
	v_cvt_pk_bf16_f32 v64, v188, v189
	v_cvt_pk_bf16_f32 v65, v190, v191
	v_cvt_pk_bf16_f32 v66, v192, v193
	v_cvt_pk_bf16_f32 v67, v194, v195
	v_cvt_pk_bf16_f32 v68, v196, v197
	v_cvt_pk_bf16_f32 v69, v198, v199
	v_cvt_pk_bf16_f32 v70, v200, v201
	v_cvt_pk_bf16_f32 v71, v202, v203
	v_pk_add_f32 v[232:233], v[232:233], v[188:189]
	v_pk_add_f32 v[232:233], v[232:233], v[190:191]
	v_pk_add_f32 v[232:233], v[232:233], v[192:193]
	v_pk_add_f32 v[232:233], v[232:233], v[194:195]
	v_pk_add_f32 v[232:233], v[232:233], v[196:197]
	v_pk_add_f32 v[232:233], v[232:233], v[198:199]
	v_pk_add_f32 v[232:233], v[232:233], v[200:201]
	v_pk_add_f32 v[232:233], v[232:233], v[202:203]
	ds_read2_b32 v[188:189], v115 offset0:96 offset1:97
	ds_read2_b32 v[190:191], v115 offset0:98 offset1:99
	ds_read2_b32 v[192:193], v115 offset0:104 offset1:105
	ds_read2_b32 v[194:195], v115 offset0:106 offset1:107
	ds_read2_b32 v[196:197], v115 offset0:112 offset1:113
	ds_read2_b32 v[198:199], v115 offset0:114 offset1:115
	ds_read2_b32 v[200:201], v115 offset0:120 offset1:121
	ds_read2_b32 v[202:203], v115 offset0:122 offset1:123
	v_mfma_f32_32x32x16_bf16 v[0:15], v[64:67], v[72:75], v[0:15]
	v_mfma_f32_32x32x16_bf16 v[16:31], v[64:67], v[76:79], v[16:31]
	v_mfma_f32_32x32x16_bf16 v[0:15], v[68:71], v[220:223], v[0:15]
	v_mfma_f32_32x32x16_bf16 v[16:31], v[68:71], v[224:227], v[16:31]
	s_add_i32 s90, s76, 1024
	v_add_u32_e32 v80, s90, v243
	v_add_u32_e32 v83, s90, v244
	v_add_u32_e32 v99, s90, v245
	v_add_u32_e32 v253, s90, v246
	v_add_u32_e32 v254, s90, v148
	v_add_u32_e32 v255, s90, v151
	v_med3_i32 v80, v80, 0, s99
	v_med3_i32 v83, v83, 0, s99
	v_med3_i32 v99, v99, 0, s99
	v_med3_i32 v253, v253, 0, s99
	v_med3_i32 v254, v254, 0, s99
	v_med3_i32 v255, v255, 0, s99
	v_mad_u32_u24 v80, v80, s100, v252
	v_mad_u32_u24 v83, v83, s100, v252
	v_mad_u32_u24 v99, v99, s100, v252
	v_mad_u32_u24 v253, v253, s100, v252
	v_mad_u32_u24 v254, v254, s100, v153
	v_mad_u32_u24 v255, v255, s100, v153
	global_load_dwordx4 v[116:119], v80, s[82:83]
	global_load_dwordx4 v[120:123], v83, s[82:83]
	global_load_dwordx4 v[124:127], v99, s[82:83]
	global_load_dwordx4 v[128:131], v253, s[82:83]
	global_load_dwordx4 v[132:135], v254, s[82:83] offset:768
	global_load_dwordx4 v[136:139], v255, s[82:83] offset:768
	global_load_dwordx4 v[140:143], v254, s[82:83] offset:832
	global_load_dwordx4 v[144:147], v255, s[82:83] offset:832
	ds_read_b64_tr_b16 v[72:73], v231
	ds_read_b64_tr_b16 v[74:75], v231 offset:512
	ds_read_b64_tr_b16 v[76:77], v231 offset:2048
	ds_read_b64_tr_b16 v[78:79], v231 offset:2560
	ds_read_b64_tr_b16 v[220:221], v231 offset:1024
	ds_read_b64_tr_b16 v[222:223], v231 offset:1536
	ds_read_b64_tr_b16 v[224:225], v231 offset:3072
	ds_read_b64_tr_b16 v[226:227], v231 offset:3584
	s_waitcnt vmcnt(8)
	ds_write_b128 v247, v[156:159]
	ds_write_b128 v247, v[160:163] offset:1024
	ds_write_b128 v247, v[164:167] offset:2048
	ds_write_b128 v247, v[168:171] offset:3072
	ds_read_b128 v[156:159], v248
	ds_read_b128 v[160:163], v249
	ds_read_b128 v[164:167], v250
	ds_read_b128 v[168:171], v251
	ds_write_b128 v112, v[172:175]
	ds_write_b128 v112, v[176:179] offset:1024
	ds_write_b128 v112, v[180:183] offset:2048
	ds_write_b128 v112, v[184:187] offset:3072
	v_exp_f32_e32 v32, v32
	v_exp_f32_e32 v33, v33
	v_exp_f32_e32 v34, v34
	v_exp_f32_e32 v35, v35
	v_exp_f32_e32 v36, v36
	v_exp_f32_e32 v37, v37
	s_waitcnt lgkmcnt(4)
	v_mfma_f32_32x32x16_bf16 v[188:203], v[156:159], v[48:51], v[188:203]
	v_exp_f32_e32 v38, v38
	v_exp_f32_e32 v39, v39
	v_mfma_f32_32x32x16_bf16 v[188:203], v[160:163], v[52:55], v[188:203]
	v_exp_f32_e32 v40, v40
	v_exp_f32_e32 v41, v41
	v_exp_f32_e32 v42, v42
	v_mfma_f32_32x32x16_bf16 v[188:203], v[164:167], v[56:59], v[188:203]
	v_exp_f32_e32 v43, v43
	v_exp_f32_e32 v44, v44
	v_mfma_f32_32x32x16_bf16 v[188:203], v[168:171], v[60:63], v[188:203]
	v_exp_f32_e32 v45, v45
	v_exp_f32_e32 v46, v46
	v_exp_f32_e32 v47, v47
	s_add_i32 s90, s76, 0
	v_lshlrev_b32_e32 v84, 4, v107
	v_add_u32_e32 v84, s90, v84
	v_add_u32_e32 v85, 0, v84
	v_add_u32_e32 v86, 16, v84
	v_add_u32_e32 v87, 32, v84
	v_add_u32_e32 v88, 48, v84
	v_cmp_gt_u32_e64 s[30:31], s98, v85
	v_cmp_gt_u32_e64 s[36:37], s98, v86
	v_cmp_gt_u32_e64 s[78:79], s98, v87
	v_cmp_gt_u32_e64 s[50:51], s98, v88
	v_cndmask_b32_e64 v32, 0, v32, s[30:31]
	v_add_u32_e32 v85, 128, v84
	v_cmp_gt_u32_e64 s[30:31], s98, v85
	v_cndmask_b32_e64 v33, 0, v33, s[36:37]
	v_add_u32_e32 v86, 144, v84
	v_cmp_gt_u32_e64 s[36:37], s98, v86
	v_cndmask_b32_e64 v34, 0, v34, s[78:79]
	v_add_u32_e32 v87, 160, v84
	v_cmp_gt_u32_e64 s[78:79], s98, v87
	v_cndmask_b32_e64 v35, 0, v35, s[50:51]
	v_add_u32_e32 v88, 176, v84
	v_cmp_gt_u32_e64 s[50:51], s98, v88
	v_cndmask_b32_e64 v36, 0, v36, s[30:31]
	v_add_u32_e32 v85, 256, v84
	v_cmp_gt_u32_e64 s[30:31], s98, v85
	v_cndmask_b32_e64 v37, 0, v37, s[36:37]
	v_add_u32_e32 v86, 272, v84
	v_cmp_gt_u32_e64 s[36:37], s98, v86
	v_cndmask_b32_e64 v38, 0, v38, s[78:79]
	v_add_u32_e32 v87, 288, v84
	v_cmp_gt_u32_e64 s[78:79], s98, v87
	v_cndmask_b32_e64 v39, 0, v39, s[50:51]
	v_add_u32_e32 v88, 304, v84
	v_cmp_gt_u32_e64 s[50:51], s98, v88
	v_cndmask_b32_e64 v40, 0, v40, s[30:31]
	v_add_u32_e32 v85, 384, v84
	v_cmp_gt_u32_e64 s[30:31], s98, v85
	v_cndmask_b32_e64 v41, 0, v41, s[36:37]
	v_add_u32_e32 v86, 400, v84
	v_cmp_gt_u32_e64 s[36:37], s98, v86
	v_cndmask_b32_e64 v42, 0, v42, s[78:79]
	v_add_u32_e32 v87, 416, v84
	v_cmp_gt_u32_e64 s[78:79], s98, v87
	v_cndmask_b32_e64 v43, 0, v43, s[50:51]
	v_add_u32_e32 v88, 432, v84
	v_cmp_gt_u32_e64 s[50:51], s98, v88
	v_nop
	v_cndmask_b32_e64 v44, 0, v44, s[30:31]
	v_cndmask_b32_e64 v45, 0, v45, s[36:37]
	v_cndmask_b32_e64 v46, 0, v46, s[78:79]
	v_cndmask_b32_e64 v47, 0, v47, s[50:51]
	v_cvt_pk_bf16_f32 v64, v32, v33
	v_cvt_pk_bf16_f32 v65, v34, v35
	v_cvt_pk_bf16_f32 v66, v36, v37
	v_cvt_pk_bf16_f32 v67, v38, v39
	v_cvt_pk_bf16_f32 v68, v40, v41
	v_cvt_pk_bf16_f32 v69, v42, v43
	v_cvt_pk_bf16_f32 v70, v44, v45
	v_cvt_pk_bf16_f32 v71, v46, v47
	v_pk_add_f32 v[232:233], v[232:233], v[32:33]
	v_pk_add_f32 v[232:233], v[232:233], v[34:35]
	v_pk_add_f32 v[232:233], v[232:233], v[36:37]
	v_pk_add_f32 v[232:233], v[232:233], v[38:39]
	v_pk_add_f32 v[232:233], v[232:233], v[40:41]
	v_pk_add_f32 v[232:233], v[232:233], v[42:43]
	v_pk_add_f32 v[232:233], v[232:233], v[44:45]
	v_pk_add_f32 v[232:233], v[232:233], v[46:47]
	ds_read2_b32 v[32:33], v115 offset0:128 offset1:129
	ds_read2_b32 v[34:35], v115 offset0:130 offset1:131
	ds_read2_b32 v[36:37], v115 offset0:136 offset1:137
	ds_read2_b32 v[38:39], v115 offset0:138 offset1:139
	ds_read2_b32 v[40:41], v115 offset0:144 offset1:145
	ds_read2_b32 v[42:43], v115 offset0:146 offset1:147
	ds_read2_b32 v[44:45], v115 offset0:152 offset1:153
	ds_read2_b32 v[46:47], v115 offset0:154 offset1:155
	v_mfma_f32_32x32x16_bf16 v[0:15], v[64:67], v[72:75], v[0:15]
	v_mfma_f32_32x32x16_bf16 v[16:31], v[64:67], v[76:79], v[16:31]
	v_mfma_f32_32x32x16_bf16 v[0:15], v[68:71], v[220:223], v[0:15]
	v_mfma_f32_32x32x16_bf16 v[16:31], v[68:71], v[224:227], v[16:31]
	ds_read_b64_tr_b16 v[72:73], v231
	ds_read_b64_tr_b16 v[74:75], v231 offset:512
	ds_read_b64_tr_b16 v[76:77], v231 offset:2048
	ds_read_b64_tr_b16 v[78:79], v231 offset:2560
	ds_read_b64_tr_b16 v[220:221], v231 offset:1024
	ds_read_b64_tr_b16 v[222:223], v231 offset:1536
	ds_read_b64_tr_b16 v[224:225], v231 offset:3072
	ds_read_b64_tr_b16 v[226:227], v231 offset:3584
	s_waitcnt vmcnt(0)
	ds_write_b128 v247, v[116:119]
	ds_write_b128 v247, v[120:123] offset:1024
	ds_write_b128 v247, v[124:127] offset:2048
	ds_write_b128 v247, v[128:131] offset:3072
	ds_read_b128 v[116:119], v248
	ds_read_b128 v[120:123], v249
	ds_read_b128 v[124:127], v250
	ds_read_b128 v[128:131], v251
	ds_write_b128 v112, v[132:135]
	ds_write_b128 v112, v[136:139] offset:1024
	ds_write_b128 v112, v[140:143] offset:2048
	ds_write_b128 v112, v[144:147] offset:3072
	v_exp_f32_e32 v188, v188
	v_exp_f32_e32 v189, v189
	v_exp_f32_e32 v190, v190
	v_exp_f32_e32 v191, v191
	v_exp_f32_e32 v192, v192
	v_exp_f32_e32 v193, v193
	s_waitcnt lgkmcnt(4)
	v_mfma_f32_32x32x16_bf16 v[32:47], v[116:119], v[48:51], v[32:47]
	v_exp_f32_e32 v194, v194
	v_exp_f32_e32 v195, v195
	v_mfma_f32_32x32x16_bf16 v[32:47], v[120:123], v[52:55], v[32:47]
	v_exp_f32_e32 v196, v196
	v_exp_f32_e32 v197, v197
	v_exp_f32_e32 v198, v198
	v_mfma_f32_32x32x16_bf16 v[32:47], v[124:127], v[56:59], v[32:47]
	v_exp_f32_e32 v199, v199
	v_exp_f32_e32 v200, v200
	v_mfma_f32_32x32x16_bf16 v[32:47], v[128:131], v[60:63], v[32:47]
	v_exp_f32_e32 v201, v201
	v_exp_f32_e32 v202, v202
	v_exp_f32_e32 v203, v203
	s_add_i32 s90, s76, 512
	v_lshlrev_b32_e32 v84, 4, v107
	v_add_u32_e32 v84, s90, v84
	v_add_u32_e32 v85, 0, v84
	v_add_u32_e32 v86, 16, v84
	v_add_u32_e32 v87, 32, v84
	v_add_u32_e32 v88, 48, v84
	v_cmp_gt_u32_e64 s[30:31], s98, v85
	v_cmp_gt_u32_e64 s[36:37], s98, v86
	v_cmp_gt_u32_e64 s[78:79], s98, v87
	v_cmp_gt_u32_e64 s[50:51], s98, v88
	v_cndmask_b32_e64 v188, 0, v188, s[30:31]
	v_add_u32_e32 v85, 128, v84
	v_cmp_gt_u32_e64 s[30:31], s98, v85
	v_cndmask_b32_e64 v189, 0, v189, s[36:37]
	v_add_u32_e32 v86, 144, v84
	v_cmp_gt_u32_e64 s[36:37], s98, v86
	v_cndmask_b32_e64 v190, 0, v190, s[78:79]
	v_add_u32_e32 v87, 160, v84
	v_cmp_gt_u32_e64 s[78:79], s98, v87
	v_cndmask_b32_e64 v191, 0, v191, s[50:51]
	v_add_u32_e32 v88, 176, v84
	v_cmp_gt_u32_e64 s[50:51], s98, v88
	v_cndmask_b32_e64 v192, 0, v192, s[30:31]
	v_add_u32_e32 v85, 256, v84
	v_cmp_gt_u32_e64 s[30:31], s98, v85
	v_cndmask_b32_e64 v193, 0, v193, s[36:37]
	v_add_u32_e32 v86, 272, v84
	v_cmp_gt_u32_e64 s[36:37], s98, v86
	v_cndmask_b32_e64 v194, 0, v194, s[78:79]
	v_add_u32_e32 v87, 288, v84
	v_cmp_gt_u32_e64 s[78:79], s98, v87
	v_cndmask_b32_e64 v195, 0, v195, s[50:51]
	v_add_u32_e32 v88, 304, v84
	v_cmp_gt_u32_e64 s[50:51], s98, v88
	v_cndmask_b32_e64 v196, 0, v196, s[30:31]
	v_add_u32_e32 v85, 384, v84
	v_cmp_gt_u32_e64 s[30:31], s98, v85
	v_cndmask_b32_e64 v197, 0, v197, s[36:37]
	v_add_u32_e32 v86, 400, v84
	v_cmp_gt_u32_e64 s[36:37], s98, v86
	v_cndmask_b32_e64 v198, 0, v198, s[78:79]
	v_add_u32_e32 v87, 416, v84
	v_cmp_gt_u32_e64 s[78:79], s98, v87
	v_cndmask_b32_e64 v199, 0, v199, s[50:51]
	v_add_u32_e32 v88, 432, v84
	v_cmp_gt_u32_e64 s[50:51], s98, v88
	v_nop
	v_cndmask_b32_e64 v200, 0, v200, s[30:31]
	v_cndmask_b32_e64 v201, 0, v201, s[36:37]
	v_cndmask_b32_e64 v202, 0, v202, s[78:79]
	v_cndmask_b32_e64 v203, 0, v203, s[50:51]
	v_cvt_pk_bf16_f32 v64, v188, v189
	v_cvt_pk_bf16_f32 v65, v190, v191
	v_cvt_pk_bf16_f32 v66, v192, v193
	v_cvt_pk_bf16_f32 v67, v194, v195
	v_cvt_pk_bf16_f32 v68, v196, v197
	v_cvt_pk_bf16_f32 v69, v198, v199
	v_cvt_pk_bf16_f32 v70, v200, v201
	v_cvt_pk_bf16_f32 v71, v202, v203
	v_pk_add_f32 v[232:233], v[232:233], v[188:189]
	v_pk_add_f32 v[232:233], v[232:233], v[190:191]
	v_pk_add_f32 v[232:233], v[232:233], v[192:193]
	v_pk_add_f32 v[232:233], v[232:233], v[194:195]
	v_pk_add_f32 v[232:233], v[232:233], v[196:197]
	v_pk_add_f32 v[232:233], v[232:233], v[198:199]
	v_pk_add_f32 v[232:233], v[232:233], v[200:201]
	v_pk_add_f32 v[232:233], v[232:233], v[202:203]
	v_mfma_f32_32x32x16_bf16 v[0:15], v[64:67], v[72:75], v[0:15]
	v_mfma_f32_32x32x16_bf16 v[16:31], v[64:67], v[76:79], v[16:31]
	v_mfma_f32_32x32x16_bf16 v[0:15], v[68:71], v[220:223], v[0:15]
	v_mfma_f32_32x32x16_bf16 v[16:31], v[68:71], v[224:227], v[16:31]
	ds_read_b64_tr_b16 v[72:73], v231
	ds_read_b64_tr_b16 v[74:75], v231 offset:512
	ds_read_b64_tr_b16 v[76:77], v231 offset:2048
	ds_read_b64_tr_b16 v[78:79], v231 offset:2560
	ds_read_b64_tr_b16 v[220:221], v231 offset:1024
	ds_read_b64_tr_b16 v[222:223], v231 offset:1536
	ds_read_b64_tr_b16 v[224:225], v231 offset:3072
	ds_read_b64_tr_b16 v[226:227], v231 offset:3584
	s_waitcnt lgkmcnt(0)
; #define LAS __attribute__((address_space(3)))
; __device__ __forceinline__ int crow(int r, int hi) { return (r & 3) + 8 * (r >> 2) + 4 * hi; }
; __device__ __forceinline__ void dil_unit(LAS unsigned char* lds, bf16_t* proj, int seq, int hd, int T0, int rho) {
;     ...
;     LAS bf16_t* stg = (LAS bf16_t*)wbuf;
;     l += __shfl_xor(l, 32);
; #pragma unroll
;     for (int rr = 0; rr < 16; ++rr) {
;         const int j = crow(rr, hi);
;         const float il = __builtin_amdgcn_rcpf(__shfl(l, j));
	v_exp_f32_e32 v32, v32
	v_exp_f32_e32 v33, v33
	v_exp_f32_e32 v34, v34
	v_exp_f32_e32 v35, v35
	v_exp_f32_e32 v36, v36
	v_exp_f32_e32 v37, v37
	v_exp_f32_e32 v38, v38
	v_exp_f32_e32 v39, v39
	v_exp_f32_e32 v40, v40
	v_exp_f32_e32 v41, v41
	v_exp_f32_e32 v42, v42
	v_exp_f32_e32 v43, v43
	v_exp_f32_e32 v44, v44
	v_exp_f32_e32 v45, v45
	v_exp_f32_e32 v46, v46
	v_exp_f32_e32 v47, v47
	s_add_i32 s90, s76, 1024
	v_lshlrev_b32_e32 v84, 4, v107
	v_add_u32_e32 v84, s90, v84
	v_add_u32_e32 v85, 0, v84
	v_add_u32_e32 v86, 16, v84
	v_add_u32_e32 v87, 32, v84
	v_add_u32_e32 v88, 48, v84
	v_cmp_gt_u32_e64 s[30:31], s98, v85
	v_cmp_gt_u32_e64 s[36:37], s98, v86
	v_cmp_gt_u32_e64 s[78:79], s98, v87
	v_cmp_gt_u32_e64 s[50:51], s98, v88
	v_cndmask_b32_e64 v32, 0, v32, s[30:31]
	v_add_u32_e32 v85, 128, v84
	v_cmp_gt_u32_e64 s[30:31], s98, v85
	v_cndmask_b32_e64 v33, 0, v33, s[36:37]
	v_add_u32_e32 v86, 144, v84
	v_cmp_gt_u32_e64 s[36:37], s98, v86
	v_cndmask_b32_e64 v34, 0, v34, s[78:79]
	v_add_u32_e32 v87, 160, v84
	v_cmp_gt_u32_e64 s[78:79], s98, v87
	v_cndmask_b32_e64 v35, 0, v35, s[50:51]
	v_add_u32_e32 v88, 176, v84
	v_cmp_gt_u32_e64 s[50:51], s98, v88
	v_cndmask_b32_e64 v36, 0, v36, s[30:31]
	v_add_u32_e32 v85, 256, v84
	v_cmp_gt_u32_e64 s[30:31], s98, v85
	v_cndmask_b32_e64 v37, 0, v37, s[36:37]
	v_add_u32_e32 v86, 272, v84
	v_cmp_gt_u32_e64 s[36:37], s98, v86
	v_cndmask_b32_e64 v38, 0, v38, s[78:79]
	v_add_u32_e32 v87, 288, v84
	v_cmp_gt_u32_e64 s[78:79], s98, v87
	v_cndmask_b32_e64 v39, 0, v39, s[50:51]
	v_add_u32_e32 v88, 304, v84
	v_cmp_gt_u32_e64 s[50:51], s98, v88
	v_cndmask_b32_e64 v40, 0, v40, s[30:31]
	v_add_u32_e32 v85, 384, v84
	v_cmp_gt_u32_e64 s[30:31], s98, v85
	v_cndmask_b32_e64 v41, 0, v41, s[36:37]
	v_add_u32_e32 v86, 400, v84
	v_cmp_gt_u32_e64 s[36:37], s98, v86
	v_cndmask_b32_e64 v42, 0, v42, s[78:79]
	v_add_u32_e32 v87, 416, v84
	v_cmp_gt_u32_e64 s[78:79], s98, v87
	v_cndmask_b32_e64 v43, 0, v43, s[50:51]
	v_add_u32_e32 v88, 432, v84
	v_cmp_gt_u32_e64 s[50:51], s98, v88
	v_nop
	v_cndmask_b32_e64 v44, 0, v44, s[30:31]
	v_cndmask_b32_e64 v45, 0, v45, s[36:37]
	v_cndmask_b32_e64 v46, 0, v46, s[78:79]
	v_cndmask_b32_e64 v47, 0, v47, s[50:51]
	v_cvt_pk_bf16_f32 v64, v32, v33
	v_cvt_pk_bf16_f32 v65, v34, v35
	v_cvt_pk_bf16_f32 v66, v36, v37
	v_cvt_pk_bf16_f32 v67, v38, v39
	v_cvt_pk_bf16_f32 v68, v40, v41
	v_cvt_pk_bf16_f32 v69, v42, v43
	v_cvt_pk_bf16_f32 v70, v44, v45
	v_cvt_pk_bf16_f32 v71, v46, v47
	v_pk_add_f32 v[232:233], v[232:233], v[32:33]
	v_pk_add_f32 v[232:233], v[232:233], v[34:35]
	v_pk_add_f32 v[232:233], v[232:233], v[36:37]
	v_pk_add_f32 v[232:233], v[232:233], v[38:39]
	v_pk_add_f32 v[232:233], v[232:233], v[40:41]
	v_pk_add_f32 v[232:233], v[232:233], v[42:43]
	v_pk_add_f32 v[232:233], v[232:233], v[44:45]
	v_pk_add_f32 v[232:233], v[232:233], v[46:47]
	v_mfma_f32_32x32x16_bf16 v[0:15], v[64:67], v[72:75], v[0:15]
	v_mfma_f32_32x32x16_bf16 v[16:31], v[64:67], v[76:79], v[16:31]
	v_mfma_f32_32x32x16_bf16 v[0:15], v[68:71], v[220:223], v[0:15]
	v_mfma_f32_32x32x16_bf16 v[16:31], v[68:71], v[224:227], v[16:31]
	v_add_f32_e32 v113, v232, v233
	v_or_b32_e32 v114, 1, v107
	v_or_b32_e32 v97, 2, v107
	v_or_b32_e32 v96, 3, v107
	v_or_b32_e32 v95, 8, v107
	v_or_b32_e32 v94, 9, v107
	v_or_b32_e32 v93, 10, v107
	v_or_b32_e32 v92, 11, v107
	v_or_b32_e32 v91, 16, v107
	v_or_b32_e32 v90, 17, v107
	v_or_b32_e32 v89, 18, v107
	v_or_b32_e32 v88, 19, v107
	v_or_b32_e32 v87, 24, v107
	v_or_b32_e32 v86, 25, v107
	v_or_b32_e32 v85, 26, v107
	v_or_b32_e32 v84, 27, v107
	s_nop 11
	s_branch .LBB0_553

; #define LAS __attribute__((address_space(3)))
; #define GAS __attribute__((address_space(1)))
; __device__ __forceinline__ void dil_unit(LAS unsigned char* lds, bf16_t* proj, int seq, int hd, int T0, int rho) {
;     int tid_ = threadIdx.x; asm volatile("" : "+v"(tid_));
;     const int tid = tid_, lane = tid & 63, r32 = lane & 31, hi = lane >> 5, wid = __builtin_amdgcn_readfirstlane(tid >> 6);
;     bf16_t* base = proj + (size_t)seq * SEQ * NIN;
;     LAS unsigned char* wbuf = lds + wid * 4096;
;     const LAS unsigned char* vp = wbuf + ((lane >> 4) & 1) * 32 + (lane & 3) * 8 + (4 * hi + ((lane & 15) >> 2)) * 64;
;     const int P0 = T0 + rho;
;     bf16x8 qr[4];
; #pragma unroll
;     for (int ks = 0; ks < 4; ++ks) qr[ks] = *(const GAS bf16x8*)(base + (size_t)(P0 + 16 * r32) * NIN + PC_LQ + hd * 64 + 16 * ks + 8 * hi);
;     f32x16 o0 = {}, o1 = {}; float l = 0.f;
;     const bool bound = (T0 < 1024) || (T0 >= 15360);
.LBB0_1266:
	s_lshr_b32 s82, s60, 8
	s_mul_i32 s82, s82, 13
	s_add_i32 s82, s82, s60
	s_ashr_i32 s4, s60, 6
	s_mul_hi_i32 s9, s4, 0x2aaaaaab
	s_lshl_b32 s5, s82, 8
	s_lshr_b32 s10, s9, 31
	s_and_b32 s8, s5, 0x3e00
	s_lshl_b32 s5, s82, 3
	s_add_i32 s9, s9, s10
	s_and_b32 s5, s5, 8
	s_mul_i32 s10, s9, 6
	s_add_i32 s5, s5, s61
	s_sub_i32 s10, s4, s10
	s_mul_hi_i32 s4, s9, 0x6000000
	s_mul_i32 s9, s9, 0x6000000
	v_mov_b32_e32 v2, v154
	s_add_u32 s52, s44, s9
	s_addc_u32 s53, s45, s4
	v_and_b32_e32 v105, 31, v2
	s_add_i32 s67, s5, s8
	v_lshl_add_u32 v3, v105, 4, s67
	v_mov_b64_e32 v[0:1], s[52:53]
	s_lshl_b32 s54, s10, 6
	v_bfe_u32 v106, v2, 5, 1
	v_mad_u64_u32 v[0:1], s[4:5], v3, s62, v[0:1]
	s_ashr_i32 s55, s54, 31
	v_lshl_add_u64 v[0:1], s[54:55], 1, v[0:1]
	v_lshlrev_b32_e32 v80, 4, v106
	v_lshl_add_u64 v[0:1], v[0:1], 0, v[80:81]
	global_load_dwordx4 v[48:51], v[0:1], off offset:1280
	global_load_dwordx4 v[52:55], v[0:1], off offset:1312
	global_load_dwordx4 v[56:59], v[0:1], off offset:1344
	global_load_dwordx4 v[60:63], v[0:1], off offset:1376
	v_readfirstlane_b32 s4, v2
	s_lshl_b32 s4, s4, 6
	s_and_b32 s4, s4, 0xfffff000
	v_lshlrev_b32_e32 v0, 1, v2
	v_lshlrev_b32_e32 v104, 3, v2
	v_lshlrev_b32_e32 v107, 2, v106
	v_lshrrev_b32_e32 v1, 2, v2
	v_and_b32_e32 v103, 63, v2
	v_and_b32_e32 v0, 32, v0
	v_and_b32_e32 v98, 24, v104
	v_and_or_b32 v1, v1, 3, v107
	s_add_i32 s69, s4, 0
	v_lshlrev_b32_e32 v108, 6, v1
	v_lshlrev_b32_e32 v1, 3, v106
	v_add3_u32 v109, s69, v0, v98
	s_addk_i32 s8, 0xc400
	v_lshrrev_b32_e32 v110, 2, v103
	v_lshlrev_b32_e32 v0, 4, v103
	s_mov_b64 s[4:5], -1
	s_cmp_gt_u32 s8, 0xffffc7ff
	v_lshlrev_b32_e32 v100, 1, v98
	s_mul_i32 s8, s10, 0x1c00
	v_lshlrev_b32_e32 v82, 1, v1
	v_or_b32_e32 v111, 16, v110
	v_add_u32_e32 v112, s69, v0
	s_cbranch_scc0 .LBB0_1270
	s_movk_i32 s100, 0x1800
	s_add_i32 s101, s8, 0x15c00
	s_lshl_b32 s90, s54, 1
	s_add_u32 s82, s52, s90
	s_addc_u32 s83, s53, 0
	s_add_u32 s82, s82, 0x1200
	s_addc_u32 s83, s83, 0
	s_sub_i32 s90, s67, 64
	s_mul_i32 s90, s90, 0x1800
	s_add_u32 s84, s82, s90
	s_addc_u32 s85, s83, 0
	s_sub_i32 s90, s67, 256
	s_mul_i32 s90, s90, 0x1800
	s_add_u32 s86, s82, s90
	s_addc_u32 s87, s83, 0
	s_sub_i32 s90, s67, 1024
	s_mul_i32 s90, s90, 0x1800
	s_add_u32 s88, s82, s90
	s_addc_u32 s89, s83, 0
	v_lshlrev_b32_e32 v153, 1, v98
	v_mad_u32_u24 v80, v105, s100, v82
	v_mad_u32_u24 v100, v110, s100, v153
	v_add_u32_e32 v149, 0x18000, v100
	v_lshlrev_b32_e32 v83, 2, v105
	v_mad_u32_u24 v83, v83, s100, v82
	v_lshlrev_b32_e32 v101, 2, v110
	v_mad_u32_u24 v101, v101, s100, v153
	v_add_u32_e32 v150, 0x60000, v101
	v_lshlrev_b32_e32 v99, 4, v105
	v_mad_u32_u24 v99, v99, s100, v82
	v_lshlrev_b32_e32 v148, 4, v110
	v_mad_u32_u24 v148, v148, s100, v153
	v_add_u32_e32 v151, 0x180000, v148
	v_lshrrev_b32_e32 v249, 3, v103
	v_and_b32_e32 v250, 7, v103
	v_lshlrev_b32_e32 v250, 4, v250
	v_add_u32_e32 v235, 0, v249
	v_mad_u32_u24 v235, v235, s100, v250
	v_add_u32_e32 v236, 8, v249
	v_mad_u32_u24 v236, v236, s100, v250
	v_add_u32_e32 v237, 16, v249
	v_mad_u32_u24 v237, v237, s100, v250
	v_add_u32_e32 v238, 24, v249
	v_mad_u32_u24 v238, v238, s100, v250
	v_add_u32_e32 v239, 0, v249
	v_lshlrev_b32_e32 v239, 2, v239
	v_mad_u32_u24 v239, v239, s100, v250
	v_add_u32_e32 v240, 8, v249
	v_lshlrev_b32_e32 v240, 2, v240
	v_mad_u32_u24 v240, v240, s100, v250
	v_add_u32_e32 v241, 16, v249
	v_lshlrev_b32_e32 v241, 2, v241
	v_mad_u32_u24 v241, v241, s100, v250
	v_add_u32_e32 v242, 24, v249
	v_lshlrev_b32_e32 v242, 2, v242
	v_mad_u32_u24 v242, v242, s100, v250
	v_add_u32_e32 v243, 0, v249
	v_lshlrev_b32_e32 v243, 4, v243
	v_mad_u32_u24 v243, v243, s100, v250
	v_add_u32_e32 v244, 8, v249
	v_lshlrev_b32_e32 v244, 4, v244
	v_mad_u32_u24 v244, v244, s100, v250
	v_add_u32_e32 v245, 16, v249
	v_lshlrev_b32_e32 v245, 4, v245
	v_mad_u32_u24 v245, v245, s100, v250
	v_add_u32_e32 v246, 24, v249
	v_lshlrev_b32_e32 v246, 4, v246
	v_mad_u32_u24 v246, v246, s100, v250
	v_and_b32_e32 v247, 7, v249
	v_lshlrev_b32_e32 v247, 4, v247
	v_xor_b32_e32 v247, v247, v112
	v_and_b32_e32 v153, 7, v105
	v_or_b32_e32 v248, 0, v106
	v_xor_b32_e32 v248, v248, v153
	v_lshlrev_b32_e32 v248, 4, v248
	v_lshl_add_u32 v248, v105, 7, v248
	v_add_u32_e32 v248, s69, v248
	v_or_b32_e32 v249, 2, v106
	v_xor_b32_e32 v249, v249, v153
	v_lshlrev_b32_e32 v249, 4, v249
	v_lshl_add_u32 v249, v105, 7, v249
	v_add_u32_e32 v249, s69, v249
	v_or_b32_e32 v250, 4, v106
	v_xor_b32_e32 v250, v250, v153
	v_lshlrev_b32_e32 v250, 4, v250
	v_lshl_add_u32 v250, v105, 7, v250
	v_add_u32_e32 v250, s69, v250
	v_or_b32_e32 v251, 6, v106
	v_xor_b32_e32 v251, v251, v153
	v_lshlrev_b32_e32 v251, 4, v251
	v_lshl_add_u32 v251, v105, 7, v251
	v_add_u32_e32 v251, s69, v251
	v_lshlrev_b32_e32 v153, 1, v98
	v_mul_u32_u24_e32 v228, 17, v105
	v_sub_u32_e32 v228, v107, v228
	s_mul_i32 s90, s54, 153
	s_lshr_b32 s90, s90, 1
	s_add_i32 s90, s90, 34876
	v_lshl_add_u32 v228, v228, 2, s90
	v_lshlrev_b32_e32 v229, 2, v105
	v_sub_u32_e32 v229, v107, v229
	s_add_i32 s90, s101, 5104
	v_lshl_add_u32 v229, v229, 2, s90
	v_sub_u32_e32 v230, v107, v105
	s_add_i32 s90, s101, 6364
	v_lshl_add_u32 v230, v230, 2, s90
	v_add_u32_e32 v231, v109, v108
	v_mov_b64_e32 v[232:233], 0
	v_mov_b64_e32 v[0:1], 0
	v_mov_b64_e32 v[2:3], 0
	v_mov_b64_e32 v[4:5], 0
	v_mov_b64_e32 v[6:7], 0
	v_mov_b64_e32 v[8:9], 0
	v_mov_b64_e32 v[10:11], 0
	v_mov_b64_e32 v[12:13], 0
	v_mov_b64_e32 v[14:15], 0
	v_mov_b64_e32 v[16:17], 0
	v_mov_b64_e32 v[18:19], 0
	v_mov_b64_e32 v[20:21], 0
	v_mov_b64_e32 v[22:23], 0
	v_mov_b64_e32 v[24:25], 0
	v_mov_b64_e32 v[26:27], 0
	v_mov_b64_e32 v[28:29], 0
	v_mov_b64_e32 v[30:31], 0
	global_load_dwordx4 v[116:119], v235, s[84:85]
	global_load_dwordx4 v[120:123], v236, s[84:85]
	global_load_dwordx4 v[124:127], v237, s[84:85]
	global_load_dwordx4 v[128:131], v238, s[84:85]
	global_load_dwordx4 v[132:135], v100, s[84:85] offset:768
	global_load_dwordx4 v[136:139], v149, s[84:85] offset:768
	global_load_dwordx4 v[140:143], v100, s[84:85] offset:832
	global_load_dwordx4 v[144:147], v149, s[84:85] offset:832
	s_add_u32 s84, s84, 0x30000
	s_addc_u32 s85, s85, 0
	global_load_dwordx4 v[156:159], v235, s[84:85]
	global_load_dwordx4 v[160:163], v236, s[84:85]
	global_load_dwordx4 v[164:167], v237, s[84:85]
	global_load_dwordx4 v[168:171], v238, s[84:85]
	global_load_dwordx4 v[172:175], v100, s[84:85] offset:768
	global_load_dwordx4 v[176:179], v149, s[84:85] offset:768
	global_load_dwordx4 v[180:183], v100, s[84:85] offset:832
	global_load_dwordx4 v[184:187], v149, s[84:85] offset:832
	s_add_u32 s84, s84, 0x30000
	s_addc_u32 s85, s85, 0
	v_mov_b32_e32 v115, v228
	ds_read2_b32 v[32:33], v115 offset0:0 offset1:1
	ds_read2_b32 v[34:35], v115 offset0:2 offset1:3
	ds_read2_b32 v[36:37], v115 offset0:8 offset1:9
	ds_read2_b32 v[38:39], v115 offset0:10 offset1:11
	ds_read2_b32 v[40:41], v115 offset0:17 offset1:18
	ds_read2_b32 v[42:43], v115 offset0:19 offset1:20
	ds_read2_b32 v[44:45], v115 offset0:25 offset1:26
	ds_read2_b32 v[46:47], v115 offset0:27 offset1:28
	s_waitcnt vmcnt(8)
	ds_write_b128 v247, v[116:119]
	ds_write_b128 v247, v[120:123] offset:1024
	ds_write_b128 v247, v[124:127] offset:2048
	ds_write_b128 v247, v[128:131] offset:3072
	ds_read_b128 v[116:119], v248
	ds_read_b128 v[120:123], v249
	ds_read_b128 v[124:127], v250
	ds_read_b128 v[128:131], v251
	ds_write_b128 v112, v[132:135]
	ds_write_b128 v112, v[136:139] offset:1024
	ds_write_b128 v112, v[140:143] offset:2048
	ds_write_b128 v112, v[144:147] offset:3072
	s_waitcnt lgkmcnt(4)
	v_mfma_f32_32x32x16_bf16 v[32:47], v[116:119], v[48:51], v[32:47]
	v_mfma_f32_32x32x16_bf16 v[32:47], v[120:123], v[52:55], v[32:47]
	v_mfma_f32_32x32x16_bf16 v[32:47], v[124:127], v[56:59], v[32:47]
	v_mfma_f32_32x32x16_bf16 v[32:47], v[128:131], v[60:63], v[32:47]
	ds_read2_b32 v[188:189], v115 offset0:34 offset1:35
	ds_read2_b32 v[190:191], v115 offset0:36 offset1:37
	ds_read2_b32 v[192:193], v115 offset0:42 offset1:43
	ds_read2_b32 v[194:195], v115 offset0:44 offset1:45
	ds_read2_b32 v[196:197], v115 offset0:51 offset1:52
	ds_read2_b32 v[198:199], v115 offset0:53 offset1:54
	ds_read2_b32 v[200:201], v115 offset0:59 offset1:60
	ds_read2_b32 v[202:203], v115 offset0:61 offset1:62
	global_load_dwordx4 v[116:119], v235, s[84:85]
	global_load_dwordx4 v[120:123], v236, s[84:85]
	global_load_dwordx4 v[124:127], v237, s[84:85]
	global_load_dwordx4 v[128:131], v238, s[84:85]
	global_load_dwordx4 v[132:135], v100, s[84:85] offset:768
	global_load_dwordx4 v[136:139], v149, s[84:85] offset:768
	global_load_dwordx4 v[140:143], v100, s[84:85] offset:832
	global_load_dwordx4 v[144:147], v149, s[84:85] offset:832
	s_add_u32 s84, s84, 0x30000
	s_addc_u32 s85, s85, 0
	ds_read_b64_tr_b16 v[72:73], v231
	ds_read_b64_tr_b16 v[74:75], v231 offset:512
	ds_read_b64_tr_b16 v[76:77], v231 offset:2048
	ds_read_b64_tr_b16 v[78:79], v231 offset:2560
	ds_read_b64_tr_b16 v[220:221], v231 offset:1024
	ds_read_b64_tr_b16 v[222:223], v231 offset:1536
	ds_read_b64_tr_b16 v[224:225], v231 offset:3072
	ds_read_b64_tr_b16 v[226:227], v231 offset:3584
	s_waitcnt vmcnt(8)
	ds_write_b128 v247, v[156:159]
	ds_write_b128 v247, v[160:163] offset:1024
	ds_write_b128 v247, v[164:167] offset:2048
	ds_write_b128 v247, v[168:171] offset:3072
	ds_read_b128 v[156:159], v248
	ds_read_b128 v[160:163], v249
	ds_read_b128 v[164:167], v250
	ds_read_b128 v[168:171], v251
	ds_write_b128 v112, v[172:175]
	ds_write_b128 v112, v[176:179] offset:1024
	ds_write_b128 v112, v[180:183] offset:2048
	ds_write_b128 v112, v[184:187] offset:3072
	v_exp_f32_e32 v32, v32
	v_exp_f32_e32 v33, v33
	v_exp_f32_e32 v34, v34
	v_exp_f32_e32 v35, v35
	v_exp_f32_e32 v36, v36
	v_exp_f32_e32 v37, v37
	s_waitcnt lgkmcnt(4)
	v_mfma_f32_32x32x16_bf16 v[188:203], v[156:159], v[48:51], v[188:203]
	v_exp_f32_e32 v38, v38
	v_exp_f32_e32 v39, v39
	v_mfma_f32_32x32x16_bf16 v[188:203], v[160:163], v[52:55], v[188:203]
	v_exp_f32_e32 v40, v40
	v_exp_f32_e32 v41, v41
	v_exp_f32_e32 v42, v42
	v_mfma_f32_32x32x16_bf16 v[188:203], v[164:167], v[56:59], v[188:203]
	v_exp_f32_e32 v43, v43
	v_exp_f32_e32 v44, v44
	v_mfma_f32_32x32x16_bf16 v[188:203], v[168:171], v[60:63], v[188:203]
	v_exp_f32_e32 v45, v45
	v_exp_f32_e32 v46, v46
	v_exp_f32_e32 v47, v47
	v_cvt_pk_bf16_f32 v64, v32, v33
	v_cvt_pk_bf16_f32 v65, v34, v35
	v_cvt_pk_bf16_f32 v66, v36, v37
	v_cvt_pk_bf16_f32 v67, v38, v39
	v_cvt_pk_bf16_f32 v68, v40, v41
	v_cvt_pk_bf16_f32 v69, v42, v43
	v_cvt_pk_bf16_f32 v70, v44, v45
	v_cvt_pk_bf16_f32 v71, v46, v47
	v_pk_add_f32 v[232:233], v[232:233], v[32:33]
	v_pk_add_f32 v[232:233], v[232:233], v[34:35]
	v_pk_add_f32 v[232:233], v[232:233], v[36:37]
	v_pk_add_f32 v[232:233], v[232:233], v[38:39]
	v_pk_add_f32 v[232:233], v[232:233], v[40:41]
	v_pk_add_f32 v[232:233], v[232:233], v[42:43]
	v_pk_add_f32 v[232:233], v[232:233], v[44:45]
	v_pk_add_f32 v[232:233], v[232:233], v[46:47]
	ds_read2_b32 v[32:33], v115 offset0:68 offset1:69
	ds_read2_b32 v[34:35], v115 offset0:70 offset1:71
	ds_read2_b32 v[36:37], v115 offset0:76 offset1:77
	ds_read2_b32 v[38:39], v115 offset0:78 offset1:79
	ds_read2_b32 v[40:41], v115 offset0:85 offset1:86
	ds_read2_b32 v[42:43], v115 offset0:87 offset1:88
	ds_read2_b32 v[44:45], v115 offset0:93 offset1:94
	ds_read2_b32 v[46:47], v115 offset0:95 offset1:96
	v_mfma_f32_32x32x16_bf16 v[0:15], v[64:67], v[72:75], v[0:15]
	v_mfma_f32_32x32x16_bf16 v[16:31], v[64:67], v[76:79], v[16:31]
	v_mfma_f32_32x32x16_bf16 v[0:15], v[68:71], v[220:223], v[0:15]
	v_mfma_f32_32x32x16_bf16 v[16:31], v[68:71], v[224:227], v[16:31]
	global_load_dwordx4 v[156:159], v235, s[84:85]
	global_load_dwordx4 v[160:163], v236, s[84:85]
	global_load_dwordx4 v[164:167], v237, s[84:85]
	global_load_dwordx4 v[168:171], v238, s[84:85]
	global_load_dwordx4 v[172:175], v100, s[84:85] offset:768
	global_load_dwordx4 v[176:179], v149, s[84:85] offset:768
	global_load_dwordx4 v[180:183], v100, s[84:85] offset:832
	global_load_dwordx4 v[184:187], v149, s[84:85] offset:832
	s_add_u32 s84, s84, 0x30000
	s_addc_u32 s85, s85, 0
	ds_read_b64_tr_b16 v[72:73], v231
	ds_read_b64_tr_b16 v[74:75], v231 offset:512
	ds_read_b64_tr_b16 v[76:77], v231 offset:2048
	ds_read_b64_tr_b16 v[78:79], v231 offset:2560
	ds_read_b64_tr_b16 v[220:221], v231 offset:1024
	ds_read_b64_tr_b16 v[222:223], v231 offset:1536
	ds_read_b64_tr_b16 v[224:225], v231 offset:3072
	ds_read_b64_tr_b16 v[226:227], v231 offset:3584
	s_waitcnt vmcnt(8)
	ds_write_b128 v247, v[116:119]
	ds_write_b128 v247, v[120:123] offset:1024
	ds_write_b128 v247, v[124:127] offset:2048
	ds_write_b128 v247, v[128:131] offset:3072
	ds_read_b128 v[116:119], v248
	ds_read_b128 v[120:123], v249
	ds_read_b128 v[124:127], v250
	ds_read_b128 v[128:131], v251
	ds_write_b128 v112, v[132:135]
	ds_write_b128 v112, v[136:139] offset:1024
	ds_write_b128 v112, v[140:143] offset:2048
	ds_write_b128 v112, v[144:147] offset:3072
	v_exp_f32_e32 v188, v188
	v_exp_f32_e32 v189, v189
	v_exp_f32_e32 v190, v190
	v_exp_f32_e32 v191, v191
	v_exp_f32_e32 v192, v192
	v_exp_f32_e32 v193, v193
	s_waitcnt lgkmcnt(4)
	v_mfma_f32_32x32x16_bf16 v[32:47], v[116:119], v[48:51], v[32:47]
	v_exp_f32_e32 v194, v194
	v_exp_f32_e32 v195, v195
	v_mfma_f32_32x32x16_bf16 v[32:47], v[120:123], v[52:55], v[32:47]
	v_exp_f32_e32 v196, v196
	v_exp_f32_e32 v197, v197
	v_exp_f32_e32 v198, v198
	v_mfma_f32_32x32x16_bf16 v[32:47], v[124:127], v[56:59], v[32:47]
	v_exp_f32_e32 v199, v199
	v_exp_f32_e32 v200, v200
	v_mfma_f32_32x32x16_bf16 v[32:47], v[128:131], v[60:63], v[32:47]
	v_exp_f32_e32 v201, v201
	v_exp_f32_e32 v202, v202
	v_exp_f32_e32 v203, v203
	v_cvt_pk_bf16_f32 v64, v188, v189
	v_cvt_pk_bf16_f32 v65, v190, v191
	v_cvt_pk_bf16_f32 v66, v192, v193
	v_cvt_pk_bf16_f32 v67, v194, v195
	v_cvt_pk_bf16_f32 v68, v196, v197
	v_cvt_pk_bf16_f32 v69, v198, v199
	v_cvt_pk_bf16_f32 v70, v200, v201
	v_cvt_pk_bf16_f32 v71, v202, v203
	v_pk_add_f32 v[232:233], v[232:233], v[188:189]
	v_pk_add_f32 v[232:233], v[232:233], v[190:191]
	v_pk_add_f32 v[232:233], v[232:233], v[192:193]
	v_pk_add_f32 v[232:233], v[232:233], v[194:195]
	v_pk_add_f32 v[232:233], v[232:233], v[196:197]
	v_pk_add_f32 v[232:233], v[232:233], v[198:199]
	v_pk_add_f32 v[232:233], v[232:233], v[200:201]
	v_pk_add_f32 v[232:233], v[232:233], v[202:203]
	ds_read2_b32 v[188:189], v115 offset0:102 offset1:103
	ds_read2_b32 v[190:191], v115 offset0:104 offset1:105
	ds_read2_b32 v[192:193], v115 offset0:110 offset1:111
	ds_read2_b32 v[194:195], v115 offset0:112 offset1:113
	ds_read2_b32 v[196:197], v115 offset0:119 offset1:120
	ds_read2_b32 v[198:199], v115 offset0:121 offset1:122
	ds_read2_b32 v[200:201], v115 offset0:127 offset1:128
	ds_read2_b32 v[202:203], v115 offset0:129 offset1:130
	v_mfma_f32_32x32x16_bf16 v[0:15], v[64:67], v[72:75], v[0:15]
	v_mfma_f32_32x32x16_bf16 v[16:31], v[64:67], v[76:79], v[16:31]
	v_mfma_f32_32x32x16_bf16 v[0:15], v[68:71], v[220:223], v[0:15]
	v_mfma_f32_32x32x16_bf16 v[16:31], v[68:71], v[224:227], v[16:31]
	global_load_dwordx4 v[116:119], v235, s[84:85]
	global_load_dwordx4 v[120:123], v236, s[84:85]
	global_load_dwordx4 v[124:127], v237, s[84:85]
	global_load_dwordx4 v[128:131], v238, s[84:85]
	global_load_dwordx4 v[132:135], v100, s[84:85] offset:768
	global_load_dwordx4 v[136:139], v149, s[84:85] offset:768
	global_load_dwordx4 v[140:143], v100, s[84:85] offset:832
	global_load_dwordx4 v[144:147], v149, s[84:85] offset:832
	s_add_u32 s84, s84, 0x30000
	s_addc_u32 s85, s85, 0
	ds_read_b64_tr_b16 v[72:73], v231
	ds_read_b64_tr_b16 v[74:75], v231 offset:512
	ds_read_b64_tr_b16 v[76:77], v231 offset:2048
	ds_read_b64_tr_b16 v[78:79], v231 offset:2560
	ds_read_b64_tr_b16 v[220:221], v231 offset:1024
	ds_read_b64_tr_b16 v[222:223], v231 offset:1536
	ds_read_b64_tr_b16 v[224:225], v231 offset:3072
	ds_read_b64_tr_b16 v[226:227], v231 offset:3584
	s_waitcnt vmcnt(8)
	ds_write_b128 v247, v[156:159]
	ds_write_b128 v247, v[160:163] offset:1024
	ds_write_b128 v247, v[164:167] offset:2048
	ds_write_b128 v247, v[168:171] offset:3072
	ds_read_b128 v[156:159], v248
	ds_read_b128 v[160:163], v249
	ds_read_b128 v[164:167], v250
	ds_read_b128 v[168:171], v251
	ds_write_b128 v112, v[172:175]
	ds_write_b128 v112, v[176:179] offset:1024
	ds_write_b128 v112, v[180:183] offset:2048
	ds_write_b128 v112, v[184:187] offset:3072
	v_exp_f32_e32 v32, v32
	v_exp_f32_e32 v33, v33
	v_exp_f32_e32 v34, v34
	v_exp_f32_e32 v35, v35
	v_exp_f32_e32 v36, v36
	v_exp_f32_e32 v37, v37
	s_waitcnt lgkmcnt(4)
	v_mfma_f32_32x32x16_bf16 v[188:203], v[156:159], v[48:51], v[188:203]
	v_exp_f32_e32 v38, v38
	v_exp_f32_e32 v39, v39
	v_mfma_f32_32x32x16_bf16 v[188:203], v[160:163], v[52:55], v[188:203]
	v_exp_f32_e32 v40, v40
	v_exp_f32_e32 v41, v41
	v_exp_f32_e32 v42, v42
	v_mfma_f32_32x32x16_bf16 v[188:203], v[164:167], v[56:59], v[188:203]
	v_exp_f32_e32 v43, v43
	v_exp_f32_e32 v44, v44
	v_mfma_f32_32x32x16_bf16 v[188:203], v[168:171], v[60:63], v[188:203]
	v_exp_f32_e32 v45, v45
	v_exp_f32_e32 v46, v46
	v_exp_f32_e32 v47, v47
	v_cvt_pk_bf16_f32 v64, v32, v33
	v_cvt_pk_bf16_f32 v65, v34, v35
	v_cvt_pk_bf16_f32 v66, v36, v37
	v_cvt_pk_bf16_f32 v67, v38, v39
	v_cvt_pk_bf16_f32 v68, v40, v41
	v_cvt_pk_bf16_f32 v69, v42, v43
	v_cvt_pk_bf16_f32 v70, v44, v45
	v_cvt_pk_bf16_f32 v71, v46, v47
	v_pk_add_f32 v[232:233], v[232:233], v[32:33]
	v_pk_add_f32 v[232:233], v[232:233], v[34:35]
	v_pk_add_f32 v[232:233], v[232:233], v[36:37]
	v_pk_add_f32 v[232:233], v[232:233], v[38:39]
	v_pk_add_f32 v[232:233], v[232:233], v[40:41]
	v_pk_add_f32 v[232:233], v[232:233], v[42:43]
	v_pk_add_f32 v[232:233], v[232:233], v[44:45]
	v_pk_add_f32 v[232:233], v[232:233], v[46:47]
	ds_read2_b32 v[32:33], v115 offset0:136 offset1:137
	ds_read2_b32 v[34:35], v115 offset0:138 offset1:139
	ds_read2_b32 v[36:37], v115 offset0:144 offset1:145
	ds_read2_b32 v[38:39], v115 offset0:146 offset1:147
	ds_read2_b32 v[40:41], v115 offset0:153 offset1:154
	ds_read2_b32 v[42:43], v115 offset0:155 offset1:156
	ds_read2_b32 v[44:45], v115 offset0:161 offset1:162
	ds_read2_b32 v[46:47], v115 offset0:163 offset1:164
	v_mfma_f32_32x32x16_bf16 v[0:15], v[64:67], v[72:75], v[0:15]
	v_mfma_f32_32x32x16_bf16 v[16:31], v[64:67], v[76:79], v[16:31]
	v_mfma_f32_32x32x16_bf16 v[0:15], v[68:71], v[220:223], v[0:15]
	v_mfma_f32_32x32x16_bf16 v[16:31], v[68:71], v[224:227], v[16:31]
	global_load_dwordx4 v[156:159], v235, s[84:85]
	global_load_dwordx4 v[160:163], v236, s[84:85]
	global_load_dwordx4 v[164:167], v237, s[84:85]
	global_load_dwordx4 v[168:171], v238, s[84:85]
	global_load_dwordx4 v[172:175], v100, s[84:85] offset:768
	global_load_dwordx4 v[176:179], v149, s[84:85] offset:768
	global_load_dwordx4 v[180:183], v100, s[84:85] offset:832
	global_load_dwordx4 v[184:187], v149, s[84:85] offset:832
	s_add_u32 s84, s84, 0x30000
	s_addc_u32 s85, s85, 0
	ds_read_b64_tr_b16 v[72:73], v231
	ds_read_b64_tr_b16 v[74:75], v231 offset:512
	ds_read_b64_tr_b16 v[76:77], v231 offset:2048
	ds_read_b64_tr_b16 v[78:79], v231 offset:2560
	ds_read_b64_tr_b16 v[220:221], v231 offset:1024
	ds_read_b64_tr_b16 v[222:223], v231 offset:1536
	ds_read_b64_tr_b16 v[224:225], v231 offset:3072
	ds_read_b64_tr_b16 v[226:227], v231 offset:3584
	s_waitcnt vmcnt(8)
	ds_write_b128 v247, v[116:119]
	ds_write_b128 v247, v[120:123] offset:1024
	ds_write_b128 v247, v[124:127] offset:2048
	ds_write_b128 v247, v[128:131] offset:3072
	ds_read_b128 v[116:119], v248
	ds_read_b128 v[120:123], v249
	ds_read_b128 v[124:127], v250
	ds_read_b128 v[128:131], v251
	ds_write_b128 v112, v[132:135]
	ds_write_b128 v112, v[136:139] offset:1024
	ds_write_b128 v112, v[140:143] offset:2048
	ds_write_b128 v112, v[144:147] offset:3072
	v_exp_f32_e32 v188, v188
	v_exp_f32_e32 v189, v189
	v_exp_f32_e32 v190, v190
	v_exp_f32_e32 v191, v191
	v_exp_f32_e32 v192, v192
	v_exp_f32_e32 v193, v193
	s_waitcnt lgkmcnt(4)
	v_mfma_f32_32x32x16_bf16 v[32:47], v[116:119], v[48:51], v[32:47]
	v_exp_f32_e32 v194, v194
	v_exp_f32_e32 v195, v195
	v_mfma_f32_32x32x16_bf16 v[32:47], v[120:123], v[52:55], v[32:47]
	v_exp_f32_e32 v196, v196
	v_exp_f32_e32 v197, v197
	v_exp_f32_e32 v198, v198
	v_mfma_f32_32x32x16_bf16 v[32:47], v[124:127], v[56:59], v[32:47]
	v_exp_f32_e32 v199, v199
	v_exp_f32_e32 v200, v200
	v_mfma_f32_32x32x16_bf16 v[32:47], v[128:131], v[60:63], v[32:47]
	v_exp_f32_e32 v201, v201
	v_exp_f32_e32 v202, v202
	v_exp_f32_e32 v203, v203
	v_cvt_pk_bf16_f32 v64, v188, v189
	v_cvt_pk_bf16_f32 v65, v190, v191
	v_cvt_pk_bf16_f32 v66, v192, v193
	v_cvt_pk_bf16_f32 v67, v194, v195
	v_cvt_pk_bf16_f32 v68, v196, v197
	v_cvt_pk_bf16_f32 v69, v198, v199
	v_cvt_pk_bf16_f32 v70, v200, v201
	v_cvt_pk_bf16_f32 v71, v202, v203
	v_pk_add_f32 v[232:233], v[232:233], v[188:189]
	v_pk_add_f32 v[232:233], v[232:233], v[190:191]
	v_pk_add_f32 v[232:233], v[232:233], v[192:193]
	v_pk_add_f32 v[232:233], v[232:233], v[194:195]
	v_pk_add_f32 v[232:233], v[232:233], v[196:197]
	v_pk_add_f32 v[232:233], v[232:233], v[198:199]
	v_pk_add_f32 v[232:233], v[232:233], v[200:201]
	v_pk_add_f32 v[232:233], v[232:233], v[202:203]
	ds_read2_b32 v[188:189], v115 offset0:170 offset1:171
	ds_read2_b32 v[190:191], v115 offset0:172 offset1:173
	ds_read2_b32 v[192:193], v115 offset0:178 offset1:179
	ds_read2_b32 v[194:195], v115 offset0:180 offset1:181
	ds_read2_b32 v[196:197], v115 offset0:187 offset1:188
	ds_read2_b32 v[198:199], v115 offset0:189 offset1:190
	ds_read2_b32 v[200:201], v115 offset0:195 offset1:196
	ds_read2_b32 v[202:203], v115 offset0:197 offset1:198
	v_mfma_f32_32x32x16_bf16 v[0:15], v[64:67], v[72:75], v[0:15]
	v_mfma_f32_32x32x16_bf16 v[16:31], v[64:67], v[76:79], v[16:31]
	v_mfma_f32_32x32x16_bf16 v[0:15], v[68:71], v[220:223], v[0:15]
	v_mfma_f32_32x32x16_bf16 v[16:31], v[68:71], v[224:227], v[16:31]
	global_load_dwordx4 v[116:119], v235, s[84:85]
	global_load_dwordx4 v[120:123], v236, s[84:85]
	global_load_dwordx4 v[124:127], v237, s[84:85]
	global_load_dwordx4 v[128:131], v238, s[84:85]
	global_load_dwordx4 v[132:135], v100, s[84:85] offset:768
	global_load_dwordx4 v[136:139], v149, s[84:85] offset:768
	global_load_dwordx4 v[140:143], v100, s[84:85] offset:832
	global_load_dwordx4 v[144:147], v149, s[84:85] offset:832
	s_add_u32 s84, s84, 0x30000
	s_addc_u32 s85, s85, 0
	ds_read_b64_tr_b16 v[72:73], v231
	ds_read_b64_tr_b16 v[74:75], v231 offset:512
	ds_read_b64_tr_b16 v[76:77], v231 offset:2048
	ds_read_b64_tr_b16 v[78:79], v231 offset:2560
	ds_read_b64_tr_b16 v[220:221], v231 offset:1024
	ds_read_b64_tr_b16 v[222:223], v231 offset:1536
	ds_read_b64_tr_b16 v[224:225], v231 offset:3072
	ds_read_b64_tr_b16 v[226:227], v231 offset:3584
	s_waitcnt vmcnt(8)
	ds_write_b128 v247, v[156:159]
	ds_write_b128 v247, v[160:163] offset:1024
	ds_write_b128 v247, v[164:167] offset:2048
	ds_write_b128 v247, v[168:171] offset:3072
	ds_read_b128 v[156:159], v248
	ds_read_b128 v[160:163], v249
	ds_read_b128 v[164:167], v250
	ds_read_b128 v[168:171], v251
	ds_write_b128 v112, v[172:175]
	ds_write_b128 v112, v[176:179] offset:1024
	ds_write_b128 v112, v[180:183] offset:2048
	ds_write_b128 v112, v[184:187] offset:3072
	v_exp_f32_e32 v32, v32
	v_exp_f32_e32 v33, v33
	v_exp_f32_e32 v34, v34
	v_exp_f32_e32 v35, v35
	v_exp_f32_e32 v36, v36
	v_exp_f32_e32 v37, v37
	s_waitcnt lgkmcnt(4)
	v_mfma_f32_32x32x16_bf16 v[188:203], v[156:159], v[48:51], v[188:203]
	v_exp_f32_e32 v38, v38
	v_exp_f32_e32 v39, v39
	v_mfma_f32_32x32x16_bf16 v[188:203], v[160:163], v[52:55], v[188:203]
	v_exp_f32_e32 v40, v40
	v_exp_f32_e32 v41, v41
	v_exp_f32_e32 v42, v42
	v_mfma_f32_32x32x16_bf16 v[188:203], v[164:167], v[56:59], v[188:203]
	v_exp_f32_e32 v43, v43
	v_exp_f32_e32 v44, v44
	v_mfma_f32_32x32x16_bf16 v[188:203], v[168:171], v[60:63], v[188:203]
	v_exp_f32_e32 v45, v45
	v_exp_f32_e32 v46, v46
	v_exp_f32_e32 v47, v47
	v_cvt_pk_bf16_f32 v64, v32, v33
	v_cvt_pk_bf16_f32 v65, v34, v35
	v_cvt_pk_bf16_f32 v66, v36, v37
	v_cvt_pk_bf16_f32 v67, v38, v39
	v_cvt_pk_bf16_f32 v68, v40, v41
	v_cvt_pk_bf16_f32 v69, v42, v43
	v_cvt_pk_bf16_f32 v70, v44, v45
	v_cvt_pk_bf16_f32 v71, v46, v47
	v_pk_add_f32 v[232:233], v[232:233], v[32:33]
	v_pk_add_f32 v[232:233], v[232:233], v[34:35]
	v_pk_add_f32 v[232:233], v[232:233], v[36:37]
	v_pk_add_f32 v[232:233], v[232:233], v[38:39]
	v_pk_add_f32 v[232:233], v[232:233], v[40:41]
	v_pk_add_f32 v[232:233], v[232:233], v[42:43]
	v_pk_add_f32 v[232:233], v[232:233], v[44:45]
	v_pk_add_f32 v[232:233], v[232:233], v[46:47]
	ds_read2_b32 v[32:33], v115 offset0:204 offset1:205
	ds_read2_b32 v[34:35], v115 offset0:206 offset1:207
	ds_read2_b32 v[36:37], v115 offset0:212 offset1:213
	ds_read2_b32 v[38:39], v115 offset0:214 offset1:215
	ds_read2_b32 v[40:41], v115 offset0:221 offset1:222
	ds_read2_b32 v[42:43], v115 offset0:223 offset1:224
	ds_read2_b32 v[44:45], v115 offset0:229 offset1:230
	ds_read2_b32 v[46:47], v115 offset0:231 offset1:232
	v_mfma_f32_32x32x16_bf16 v[0:15], v[64:67], v[72:75], v[0:15]
	v_mfma_f32_32x32x16_bf16 v[16:31], v[64:67], v[76:79], v[16:31]
	v_mfma_f32_32x32x16_bf16 v[0:15], v[68:71], v[220:223], v[0:15]
	v_mfma_f32_32x32x16_bf16 v[16:31], v[68:71], v[224:227], v[16:31]
	global_load_dwordx4 v[156:159], v235, s[84:85]
	global_load_dwordx4 v[160:163], v236, s[84:85]
	global_load_dwordx4 v[164:167], v237, s[84:85]
	global_load_dwordx4 v[168:171], v238, s[84:85]
	global_load_dwordx4 v[172:175], v100, s[84:85] offset:768
	global_load_dwordx4 v[176:179], v149, s[84:85] offset:768
	global_load_dwordx4 v[180:183], v100, s[84:85] offset:832
	global_load_dwordx4 v[184:187], v149, s[84:85] offset:832
	s_add_u32 s84, s84, 0x30000
	s_addc_u32 s85, s85, 0
	ds_read_b64_tr_b16 v[72:73], v231
	ds_read_b64_tr_b16 v[74:75], v231 offset:512
	ds_read_b64_tr_b16 v[76:77], v231 offset:2048
	ds_read_b64_tr_b16 v[78:79], v231 offset:2560
	ds_read_b64_tr_b16 v[220:221], v231 offset:1024
	ds_read_b64_tr_b16 v[222:223], v231 offset:1536
	ds_read_b64_tr_b16 v[224:225], v231 offset:3072
	ds_read_b64_tr_b16 v[226:227], v231 offset:3584
	s_waitcnt vmcnt(8)
	ds_write_b128 v247, v[116:119]
	ds_write_b128 v247, v[120:123] offset:1024
	ds_write_b128 v247, v[124:127] offset:2048
	ds_write_b128 v247, v[128:131] offset:3072
	ds_read_b128 v[116:119], v248
	ds_read_b128 v[120:123], v249
	ds_read_b128 v[124:127], v250
	ds_read_b128 v[128:131], v251
	ds_write_b128 v112, v[132:135]
	ds_write_b128 v112, v[136:139] offset:1024
	ds_write_b128 v112, v[140:143] offset:2048
	ds_write_b128 v112, v[144:147] offset:3072
	v_exp_f32_e32 v188, v188
	v_exp_f32_e32 v189, v189
	v_exp_f32_e32 v190, v190
	v_exp_f32_e32 v191, v191
	v_exp_f32_e32 v192, v192
	v_exp_f32_e32 v193, v193
	s_waitcnt lgkmcnt(4)
	v_mfma_f32_32x32x16_bf16 v[32:47], v[116:119], v[48:51], v[32:47]
	v_exp_f32_e32 v194, v194
	v_exp_f32_e32 v195, v195
	v_mfma_f32_32x32x16_bf16 v[32:47], v[120:123], v[52:55], v[32:47]
	v_exp_f32_e32 v196, v196
	v_exp_f32_e32 v197, v197
	v_exp_f32_e32 v198, v198
	v_mfma_f32_32x32x16_bf16 v[32:47], v[124:127], v[56:59], v[32:47]
	v_exp_f32_e32 v199, v199
	v_exp_f32_e32 v200, v200
	v_mfma_f32_32x32x16_bf16 v[32:47], v[128:131], v[60:63], v[32:47]
	v_exp_f32_e32 v201, v201
	v_exp_f32_e32 v202, v202
	v_exp_f32_e32 v203, v203
	v_cvt_pk_bf16_f32 v64, v188, v189
	v_cvt_pk_bf16_f32 v65, v190, v191
	v_cvt_pk_bf16_f32 v66, v192, v193
	v_cvt_pk_bf16_f32 v67, v194, v195
	v_cvt_pk_bf16_f32 v68, v196, v197
	v_cvt_pk_bf16_f32 v69, v198, v199
	v_cvt_pk_bf16_f32 v70, v200, v201
	v_cvt_pk_bf16_f32 v71, v202, v203
	v_pk_add_f32 v[232:233], v[232:233], v[188:189]
	v_pk_add_f32 v[232:233], v[232:233], v[190:191]
	v_pk_add_f32 v[232:233], v[232:233], v[192:193]
	v_pk_add_f32 v[232:233], v[232:233], v[194:195]
	v_pk_add_f32 v[232:233], v[232:233], v[196:197]
	v_pk_add_f32 v[232:233], v[232:233], v[198:199]
	v_pk_add_f32 v[232:233], v[232:233], v[200:201]
	v_pk_add_f32 v[232:233], v[232:233], v[202:203]
	v_add_u32_e32 v115, 952, v115
	ds_read2_b32 v[188:189], v115 offset0:0 offset1:1
	ds_read2_b32 v[190:191], v115 offset0:2 offset1:3
	ds_read2_b32 v[192:193], v115 offset0:8 offset1:9
	ds_read2_b32 v[194:195], v115 offset0:10 offset1:11
	ds_read2_b32 v[196:197], v115 offset0:17 offset1:18
	ds_read2_b32 v[198:199], v115 offset0:19 offset1:20
	ds_read2_b32 v[200:201], v115 offset0:25 offset1:26
	ds_read2_b32 v[202:203], v115 offset0:27 offset1:28
	v_mfma_f32_32x32x16_bf16 v[0:15], v[64:67], v[72:75], v[0:15]
	v_mfma_f32_32x32x16_bf16 v[16:31], v[64:67], v[76:79], v[16:31]
	v_mfma_f32_32x32x16_bf16 v[0:15], v[68:71], v[220:223], v[0:15]
	v_mfma_f32_32x32x16_bf16 v[16:31], v[68:71], v[224:227], v[16:31]
	global_load_dwordx4 v[116:119], v235, s[84:85]
	global_load_dwordx4 v[120:123], v236, s[84:85]
	global_load_dwordx4 v[124:127], v237, s[84:85]
	global_load_dwordx4 v[128:131], v238, s[84:85]
	global_load_dwordx4 v[132:135], v100, s[84:85] offset:768
	global_load_dwordx4 v[136:139], v149, s[84:85] offset:768
	global_load_dwordx4 v[140:143], v100, s[84:85] offset:832
	global_load_dwordx4 v[144:147], v149, s[84:85] offset:832
	s_add_u32 s84, s84, 0x30000
	s_addc_u32 s85, s85, 0
	ds_read_b64_tr_b16 v[72:73], v231
	ds_read_b64_tr_b16 v[74:75], v231 offset:512
	ds_read_b64_tr_b16 v[76:77], v231 offset:2048
	ds_read_b64_tr_b16 v[78:79], v231 offset:2560
	ds_read_b64_tr_b16 v[220:221], v231 offset:1024
	ds_read_b64_tr_b16 v[222:223], v231 offset:1536
	ds_read_b64_tr_b16 v[224:225], v231 offset:3072
	ds_read_b64_tr_b16 v[226:227], v231 offset:3584
	s_waitcnt vmcnt(8)
	ds_write_b128 v247, v[156:159]
	ds_write_b128 v247, v[160:163] offset:1024
	ds_write_b128 v247, v[164:167] offset:2048
	ds_write_b128 v247, v[168:171] offset:3072
	ds_read_b128 v[156:159], v248
	ds_read_b128 v[160:163], v249
	ds_read_b128 v[164:167], v250
	ds_read_b128 v[168:171], v251
	ds_write_b128 v112, v[172:175]
	ds_write_b128 v112, v[176:179] offset:1024
	ds_write_b128 v112, v[180:183] offset:2048
	ds_write_b128 v112, v[184:187] offset:3072
	v_exp_f32_e32 v32, v32
	v_exp_f32_e32 v33, v33
	v_exp_f32_e32 v34, v34
	v_exp_f32_e32 v35, v35
	v_exp_f32_e32 v36, v36
	v_exp_f32_e32 v37, v37
	s_waitcnt lgkmcnt(4)
	v_mfma_f32_32x32x16_bf16 v[188:203], v[156:159], v[48:51], v[188:203]
	v_exp_f32_e32 v38, v38
	v_exp_f32_e32 v39, v39
	v_mfma_f32_32x32x16_bf16 v[188:203], v[160:163], v[52:55], v[188:203]
	v_exp_f32_e32 v40, v40
	v_exp_f32_e32 v41, v41
	v_exp_f32_e32 v42, v42
	v_mfma_f32_32x32x16_bf16 v[188:203], v[164:167], v[56:59], v[188:203]
	v_exp_f32_e32 v43, v43
	v_exp_f32_e32 v44, v44
	v_mfma_f32_32x32x16_bf16 v[188:203], v[168:171], v[60:63], v[188:203]
	v_exp_f32_e32 v45, v45
	v_exp_f32_e32 v46, v46
	v_exp_f32_e32 v47, v47
	v_cvt_pk_bf16_f32 v64, v32, v33
	v_cvt_pk_bf16_f32 v65, v34, v35
	v_cvt_pk_bf16_f32 v66, v36, v37
	v_cvt_pk_bf16_f32 v67, v38, v39
	v_cvt_pk_bf16_f32 v68, v40, v41
	v_cvt_pk_bf16_f32 v69, v42, v43
	v_cvt_pk_bf16_f32 v70, v44, v45
	v_cvt_pk_bf16_f32 v71, v46, v47
	v_pk_add_f32 v[232:233], v[232:233], v[32:33]
	v_pk_add_f32 v[232:233], v[232:233], v[34:35]
	v_pk_add_f32 v[232:233], v[232:233], v[36:37]
	v_pk_add_f32 v[232:233], v[232:233], v[38:39]
	v_pk_add_f32 v[232:233], v[232:233], v[40:41]
	v_pk_add_f32 v[232:233], v[232:233], v[42:43]
	v_pk_add_f32 v[232:233], v[232:233], v[44:45]
	v_pk_add_f32 v[232:233], v[232:233], v[46:47]
	ds_read2_b32 v[32:33], v115 offset0:34 offset1:35
	ds_read2_b32 v[34:35], v115 offset0:36 offset1:37
	ds_read2_b32 v[36:37], v115 offset0:42 offset1:43
	ds_read2_b32 v[38:39], v115 offset0:44 offset1:45
	ds_read2_b32 v[40:41], v115 offset0:51 offset1:52
	ds_read2_b32 v[42:43], v115 offset0:53 offset1:54
	ds_read2_b32 v[44:45], v115 offset0:59 offset1:60
	ds_read2_b32 v[46:47], v115 offset0:61 offset1:62
	v_mfma_f32_32x32x16_bf16 v[0:15], v[64:67], v[72:75], v[0:15]
	v_mfma_f32_32x32x16_bf16 v[16:31], v[64:67], v[76:79], v[16:31]
	v_mfma_f32_32x32x16_bf16 v[0:15], v[68:71], v[220:223], v[0:15]
	v_mfma_f32_32x32x16_bf16 v[16:31], v[68:71], v[224:227], v[16:31]
	global_load_dwordx4 v[156:159], v235, s[84:85]
	global_load_dwordx4 v[160:163], v236, s[84:85]
	global_load_dwordx4 v[164:167], v237, s[84:85]
	global_load_dwordx4 v[168:171], v238, s[84:85]
	global_load_dwordx4 v[172:175], v100, s[84:85] offset:768
	global_load_dwordx4 v[176:179], v149, s[84:85] offset:768
	global_load_dwordx4 v[180:183], v100, s[84:85] offset:832
	global_load_dwordx4 v[184:187], v149, s[84:85] offset:832
	s_add_u32 s84, s84, 0x30000
	s_addc_u32 s85, s85, 0
	ds_read_b64_tr_b16 v[72:73], v231
	ds_read_b64_tr_b16 v[74:75], v231 offset:512
	ds_read_b64_tr_b16 v[76:77], v231 offset:2048
	ds_read_b64_tr_b16 v[78:79], v231 offset:2560
	ds_read_b64_tr_b16 v[220:221], v231 offset:1024
	ds_read_b64_tr_b16 v[222:223], v231 offset:1536
	ds_read_b64_tr_b16 v[224:225], v231 offset:3072
	ds_read_b64_tr_b16 v[226:227], v231 offset:3584
	s_waitcnt vmcnt(8)
	ds_write_b128 v247, v[116:119]
	ds_write_b128 v247, v[120:123] offset:1024
	ds_write_b128 v247, v[124:127] offset:2048
	ds_write_b128 v247, v[128:131] offset:3072
	ds_read_b128 v[116:119], v248
	ds_read_b128 v[120:123], v249
	ds_read_b128 v[124:127], v250
	ds_read_b128 v[128:131], v251
	ds_write_b128 v112, v[132:135]
	ds_write_b128 v112, v[136:139] offset:1024
	ds_write_b128 v112, v[140:143] offset:2048
	ds_write_b128 v112, v[144:147] offset:3072
	v_exp_f32_e32 v188, v188
	v_exp_f32_e32 v189, v189
	v_exp_f32_e32 v190, v190
	v_exp_f32_e32 v191, v191
	v_exp_f32_e32 v192, v192
	v_exp_f32_e32 v193, v193
	s_waitcnt lgkmcnt(4)
	v_mfma_f32_32x32x16_bf16 v[32:47], v[116:119], v[48:51], v[32:47]
	v_exp_f32_e32 v194, v194
	v_exp_f32_e32 v195, v195
	v_mfma_f32_32x32x16_bf16 v[32:47], v[120:123], v[52:55], v[32:47]
	v_exp_f32_e32 v196, v196
	v_exp_f32_e32 v197, v197
	v_exp_f32_e32 v198, v198
	v_mfma_f32_32x32x16_bf16 v[32:47], v[124:127], v[56:59], v[32:47]
	v_exp_f32_e32 v199, v199
	v_exp_f32_e32 v200, v200
	v_mfma_f32_32x32x16_bf16 v[32:47], v[128:131], v[60:63], v[32:47]
	v_exp_f32_e32 v201, v201
	v_exp_f32_e32 v202, v202
	v_exp_f32_e32 v203, v203
	v_cvt_pk_bf16_f32 v64, v188, v189
	v_cvt_pk_bf16_f32 v65, v190, v191
	v_cvt_pk_bf16_f32 v66, v192, v193
	v_cvt_pk_bf16_f32 v67, v194, v195
	v_cvt_pk_bf16_f32 v68, v196, v197
	v_cvt_pk_bf16_f32 v69, v198, v199
	v_cvt_pk_bf16_f32 v70, v200, v201
	v_cvt_pk_bf16_f32 v71, v202, v203
	v_pk_add_f32 v[232:233], v[232:233], v[188:189]
	v_pk_add_f32 v[232:233], v[232:233], v[190:191]
	v_pk_add_f32 v[232:233], v[232:233], v[192:193]
	v_pk_add_f32 v[232:233], v[232:233], v[194:195]
	v_pk_add_f32 v[232:233], v[232:233], v[196:197]
	v_pk_add_f32 v[232:233], v[232:233], v[198:199]
	v_pk_add_f32 v[232:233], v[232:233], v[200:201]
	v_pk_add_f32 v[232:233], v[232:233], v[202:203]
	ds_read2_b32 v[188:189], v115 offset0:68 offset1:69
	ds_read2_b32 v[190:191], v115 offset0:70 offset1:71
	ds_read2_b32 v[192:193], v115 offset0:76 offset1:77
	ds_read2_b32 v[194:195], v115 offset0:78 offset1:79
	ds_read2_b32 v[196:197], v115 offset0:85 offset1:86
	ds_read2_b32 v[198:199], v115 offset0:87 offset1:88
	ds_read2_b32 v[200:201], v115 offset0:93 offset1:94
	ds_read2_b32 v[202:203], v115 offset0:95 offset1:96
	v_mfma_f32_32x32x16_bf16 v[0:15], v[64:67], v[72:75], v[0:15]
	v_mfma_f32_32x32x16_bf16 v[16:31], v[64:67], v[76:79], v[16:31]
	v_mfma_f32_32x32x16_bf16 v[0:15], v[68:71], v[220:223], v[0:15]
	v_mfma_f32_32x32x16_bf16 v[16:31], v[68:71], v[224:227], v[16:31]
	global_load_dwordx4 v[116:119], v235, s[84:85]
	global_load_dwordx4 v[120:123], v236, s[84:85]
	global_load_dwordx4 v[124:127], v237, s[84:85]
	global_load_dwordx4 v[128:131], v238, s[84:85]
	global_load_dwordx4 v[132:135], v100, s[84:85] offset:768
	global_load_dwordx4 v[136:139], v149, s[84:85] offset:768
	global_load_dwordx4 v[140:143], v100, s[84:85] offset:832
	global_load_dwordx4 v[144:147], v149, s[84:85] offset:832
	s_add_u32 s84, s84, 0x30000
	s_addc_u32 s85, s85, 0
	ds_read_b64_tr_b16 v[72:73], v231
	ds_read_b64_tr_b16 v[74:75], v231 offset:512
	ds_read_b64_tr_b16 v[76:77], v231 offset:2048
	ds_read_b64_tr_b16 v[78:79], v231 offset:2560
	ds_read_b64_tr_b16 v[220:221], v231 offset:1024
	ds_read_b64_tr_b16 v[222:223], v231 offset:1536
	ds_read_b64_tr_b16 v[224:225], v231 offset:3072
	ds_read_b64_tr_b16 v[226:227], v231 offset:3584
	s_waitcnt vmcnt(8)
	ds_write_b128 v247, v[156:159]
	ds_write_b128 v247, v[160:163] offset:1024
	ds_write_b128 v247, v[164:167] offset:2048
	ds_write_b128 v247, v[168:171] offset:3072
	ds_read_b128 v[156:159], v248
	ds_read_b128 v[160:163], v249
	ds_read_b128 v[164:167], v250
	ds_read_b128 v[168:171], v251
	ds_write_b128 v112, v[172:175]
	ds_write_b128 v112, v[176:179] offset:1024
	ds_write_b128 v112, v[180:183] offset:2048
	ds_write_b128 v112, v[184:187] offset:3072
	v_exp_f32_e32 v32, v32
	v_exp_f32_e32 v33, v33
	v_exp_f32_e32 v34, v34
	v_exp_f32_e32 v35, v35
	v_exp_f32_e32 v36, v36
	v_exp_f32_e32 v37, v37
	s_waitcnt lgkmcnt(4)
	v_mfma_f32_32x32x16_bf16 v[188:203], v[156:159], v[48:51], v[188:203]
	v_exp_f32_e32 v38, v38
	v_exp_f32_e32 v39, v39
	v_mfma_f32_32x32x16_bf16 v[188:203], v[160:163], v[52:55], v[188:203]
	v_exp_f32_e32 v40, v40
	v_exp_f32_e32 v41, v41
	v_exp_f32_e32 v42, v42
	v_mfma_f32_32x32x16_bf16 v[188:203], v[164:167], v[56:59], v[188:203]
	v_exp_f32_e32 v43, v43
	v_exp_f32_e32 v44, v44
	v_mfma_f32_32x32x16_bf16 v[188:203], v[168:171], v[60:63], v[188:203]
	v_exp_f32_e32 v45, v45
	v_exp_f32_e32 v46, v46
	v_exp_f32_e32 v47, v47
	v_cvt_pk_bf16_f32 v64, v32, v33
	v_cvt_pk_bf16_f32 v65, v34, v35
	v_cvt_pk_bf16_f32 v66, v36, v37
	v_cvt_pk_bf16_f32 v67, v38, v39
	v_cvt_pk_bf16_f32 v68, v40, v41
	v_cvt_pk_bf16_f32 v69, v42, v43
	v_cvt_pk_bf16_f32 v70, v44, v45
	v_cvt_pk_bf16_f32 v71, v46, v47
	v_pk_add_f32 v[232:233], v[232:233], v[32:33]
	v_pk_add_f32 v[232:233], v[232:233], v[34:35]
	v_pk_add_f32 v[232:233], v[232:233], v[36:37]
	v_pk_add_f32 v[232:233], v[232:233], v[38:39]
	v_pk_add_f32 v[232:233], v[232:233], v[40:41]
	v_pk_add_f32 v[232:233], v[232:233], v[42:43]
	v_pk_add_f32 v[232:233], v[232:233], v[44:45]
	v_pk_add_f32 v[232:233], v[232:233], v[46:47]
	ds_read2_b32 v[32:33], v115 offset0:102 offset1:103
	ds_read2_b32 v[34:35], v115 offset0:104 offset1:105
	ds_read2_b32 v[36:37], v115 offset0:110 offset1:111
	ds_read2_b32 v[38:39], v115 offset0:112 offset1:113
	ds_read2_b32 v[40:41], v115 offset0:119 offset1:120
	ds_read2_b32 v[42:43], v115 offset0:121 offset1:122
	ds_read2_b32 v[44:45], v115 offset0:127 offset1:128
	ds_read2_b32 v[46:47], v115 offset0:129 offset1:130
	v_mfma_f32_32x32x16_bf16 v[0:15], v[64:67], v[72:75], v[0:15]
	v_mfma_f32_32x32x16_bf16 v[16:31], v[64:67], v[76:79], v[16:31]
	v_mfma_f32_32x32x16_bf16 v[0:15], v[68:71], v[220:223], v[0:15]
	v_mfma_f32_32x32x16_bf16 v[16:31], v[68:71], v[224:227], v[16:31]
	global_load_dwordx4 v[156:159], v235, s[84:85]
	global_load_dwordx4 v[160:163], v236, s[84:85]
	global_load_dwordx4 v[164:167], v237, s[84:85]
	global_load_dwordx4 v[168:171], v238, s[84:85]
	global_load_dwordx4 v[172:175], v100, s[84:85] offset:768
	global_load_dwordx4 v[176:179], v149, s[84:85] offset:768
	global_load_dwordx4 v[180:183], v100, s[84:85] offset:832
	global_load_dwordx4 v[184:187], v149, s[84:85] offset:832
	s_add_u32 s84, s84, 0x30000
	s_addc_u32 s85, s85, 0
	ds_read_b64_tr_b16 v[72:73], v231
	ds_read_b64_tr_b16 v[74:75], v231 offset:512
	ds_read_b64_tr_b16 v[76:77], v231 offset:2048
	ds_read_b64_tr_b16 v[78:79], v231 offset:2560
	ds_read_b64_tr_b16 v[220:221], v231 offset:1024
	ds_read_b64_tr_b16 v[222:223], v231 offset:1536
	ds_read_b64_tr_b16 v[224:225], v231 offset:3072
	ds_read_b64_tr_b16 v[226:227], v231 offset:3584
	s_waitcnt vmcnt(8)
	ds_write_b128 v247, v[116:119]
	ds_write_b128 v247, v[120:123] offset:1024
	ds_write_b128 v247, v[124:127] offset:2048
	ds_write_b128 v247, v[128:131] offset:3072
	ds_read_b128 v[116:119], v248
	ds_read_b128 v[120:123], v249
	ds_read_b128 v[124:127], v250
	ds_read_b128 v[128:131], v251
	ds_write_b128 v112, v[132:135]
	ds_write_b128 v112, v[136:139] offset:1024
	ds_write_b128 v112, v[140:143] offset:2048
	ds_write_b128 v112, v[144:147] offset:3072
	v_exp_f32_e32 v188, v188
	v_exp_f32_e32 v189, v189
	v_exp_f32_e32 v190, v190
	v_exp_f32_e32 v191, v191
	v_exp_f32_e32 v192, v192
	v_exp_f32_e32 v193, v193
	s_waitcnt lgkmcnt(4)
	v_mfma_f32_32x32x16_bf16 v[32:47], v[116:119], v[48:51], v[32:47]
	v_exp_f32_e32 v194, v194
	v_exp_f32_e32 v195, v195
	v_mfma_f32_32x32x16_bf16 v[32:47], v[120:123], v[52:55], v[32:47]
	v_exp_f32_e32 v196, v196
	v_exp_f32_e32 v197, v197
	v_exp_f32_e32 v198, v198
	v_mfma_f32_32x32x16_bf16 v[32:47], v[124:127], v[56:59], v[32:47]
	v_exp_f32_e32 v199, v199
	v_exp_f32_e32 v200, v200
	v_mfma_f32_32x32x16_bf16 v[32:47], v[128:131], v[60:63], v[32:47]
	v_exp_f32_e32 v201, v201
	v_exp_f32_e32 v202, v202
	v_exp_f32_e32 v203, v203
	v_cvt_pk_bf16_f32 v64, v188, v189
	v_cvt_pk_bf16_f32 v65, v190, v191
	v_cvt_pk_bf16_f32 v66, v192, v193
	v_cvt_pk_bf16_f32 v67, v194, v195
	v_cvt_pk_bf16_f32 v68, v196, v197
	v_cvt_pk_bf16_f32 v69, v198, v199
	v_cvt_pk_bf16_f32 v70, v200, v201
	v_cvt_pk_bf16_f32 v71, v202, v203
	v_pk_add_f32 v[232:233], v[232:233], v[188:189]
	v_pk_add_f32 v[232:233], v[232:233], v[190:191]
	v_pk_add_f32 v[232:233], v[232:233], v[192:193]
	v_pk_add_f32 v[232:233], v[232:233], v[194:195]
	v_pk_add_f32 v[232:233], v[232:233], v[196:197]
	v_pk_add_f32 v[232:233], v[232:233], v[198:199]
	v_pk_add_f32 v[232:233], v[232:233], v[200:201]
	v_pk_add_f32 v[232:233], v[232:233], v[202:203]
	ds_read2_b32 v[188:189], v115 offset0:136 offset1:137
	ds_read2_b32 v[190:191], v115 offset0:138 offset1:139
	ds_read2_b32 v[192:193], v115 offset0:144 offset1:145
	ds_read2_b32 v[194:195], v115 offset0:146 offset1:147
	ds_read2_b32 v[196:197], v115 offset0:153 offset1:154
	ds_read2_b32 v[198:199], v115 offset0:155 offset1:156
	ds_read2_b32 v[200:201], v115 offset0:161 offset1:162
	ds_read2_b32 v[202:203], v115 offset0:163 offset1:164
	v_mfma_f32_32x32x16_bf16 v[0:15], v[64:67], v[72:75], v[0:15]
	v_mfma_f32_32x32x16_bf16 v[16:31], v[64:67], v[76:79], v[16:31]
	v_mfma_f32_32x32x16_bf16 v[0:15], v[68:71], v[220:223], v[0:15]
	v_mfma_f32_32x32x16_bf16 v[16:31], v[68:71], v[224:227], v[16:31]
	global_load_dwordx4 v[116:119], v235, s[84:85]
	global_load_dwordx4 v[120:123], v236, s[84:85]
	global_load_dwordx4 v[124:127], v237, s[84:85]
	global_load_dwordx4 v[128:131], v238, s[84:85]
	global_load_dwordx4 v[132:135], v100, s[84:85] offset:768
	global_load_dwordx4 v[136:139], v149, s[84:85] offset:768
	global_load_dwordx4 v[140:143], v100, s[84:85] offset:832
	global_load_dwordx4 v[144:147], v149, s[84:85] offset:832
	s_add_u32 s84, s84, 0x30000
	s_addc_u32 s85, s85, 0
	ds_read_b64_tr_b16 v[72:73], v231
	ds_read_b64_tr_b16 v[74:75], v231 offset:512
	ds_read_b64_tr_b16 v[76:77], v231 offset:2048
	ds_read_b64_tr_b16 v[78:79], v231 offset:2560
	ds_read_b64_tr_b16 v[220:221], v231 offset:1024
	ds_read_b64_tr_b16 v[222:223], v231 offset:1536
	ds_read_b64_tr_b16 v[224:225], v231 offset:3072
	ds_read_b64_tr_b16 v[226:227], v231 offset:3584
	s_waitcnt vmcnt(8)
	ds_write_b128 v247, v[156:159]
	ds_write_b128 v247, v[160:163] offset:1024
	ds_write_b128 v247, v[164:167] offset:2048
	ds_write_b128 v247, v[168:171] offset:3072
	ds_read_b128 v[156:159], v248
	ds_read_b128 v[160:163], v249
	ds_read_b128 v[164:167], v250
	ds_read_b128 v[168:171], v251
	ds_write_b128 v112, v[172:175]
	ds_write_b128 v112, v[176:179] offset:1024
	ds_write_b128 v112, v[180:183] offset:2048
	ds_write_b128 v112, v[184:187] offset:3072
	v_exp_f32_e32 v32, v32
	v_exp_f32_e32 v33, v33
	v_exp_f32_e32 v34, v34
	v_exp_f32_e32 v35, v35
	v_exp_f32_e32 v36, v36
	v_exp_f32_e32 v37, v37
	s_waitcnt lgkmcnt(4)
	v_mfma_f32_32x32x16_bf16 v[188:203], v[156:159], v[48:51], v[188:203]
	v_exp_f32_e32 v38, v38
	v_exp_f32_e32 v39, v39
	v_mfma_f32_32x32x16_bf16 v[188:203], v[160:163], v[52:55], v[188:203]
	v_exp_f32_e32 v40, v40
	v_exp_f32_e32 v41, v41
	v_exp_f32_e32 v42, v42
	v_mfma_f32_32x32x16_bf16 v[188:203], v[164:167], v[56:59], v[188:203]
	v_exp_f32_e32 v43, v43
	v_exp_f32_e32 v44, v44
	v_mfma_f32_32x32x16_bf16 v[188:203], v[168:171], v[60:63], v[188:203]
	v_exp_f32_e32 v45, v45
	v_exp_f32_e32 v46, v46
	v_exp_f32_e32 v47, v47
	v_cvt_pk_bf16_f32 v64, v32, v33
	v_cvt_pk_bf16_f32 v65, v34, v35
	v_cvt_pk_bf16_f32 v66, v36, v37
	v_cvt_pk_bf16_f32 v67, v38, v39
	v_cvt_pk_bf16_f32 v68, v40, v41
	v_cvt_pk_bf16_f32 v69, v42, v43
	v_cvt_pk_bf16_f32 v70, v44, v45
	v_cvt_pk_bf16_f32 v71, v46, v47
	v_pk_add_f32 v[232:233], v[232:233], v[32:33]
	v_pk_add_f32 v[232:233], v[232:233], v[34:35]
	v_pk_add_f32 v[232:233], v[232:233], v[36:37]
	v_pk_add_f32 v[232:233], v[232:233], v[38:39]
	v_pk_add_f32 v[232:233], v[232:233], v[40:41]
	v_pk_add_f32 v[232:233], v[232:233], v[42:43]
	v_pk_add_f32 v[232:233], v[232:233], v[44:45]
	v_pk_add_f32 v[232:233], v[232:233], v[46:47]
	ds_read2_b32 v[32:33], v115 offset0:170 offset1:171
	ds_read2_b32 v[34:35], v115 offset0:172 offset1:173
	ds_read2_b32 v[36:37], v115 offset0:178 offset1:179
	ds_read2_b32 v[38:39], v115 offset0:180 offset1:181
	ds_read2_b32 v[40:41], v115 offset0:187 offset1:188
	ds_read2_b32 v[42:43], v115 offset0:189 offset1:190
	ds_read2_b32 v[44:45], v115 offset0:195 offset1:196
	ds_read2_b32 v[46:47], v115 offset0:197 offset1:198
	v_mfma_f32_32x32x16_bf16 v[0:15], v[64:67], v[72:75], v[0:15]
	v_mfma_f32_32x32x16_bf16 v[16:31], v[64:67], v[76:79], v[16:31]
	v_mfma_f32_32x32x16_bf16 v[0:15], v[68:71], v[220:223], v[0:15]
	v_mfma_f32_32x32x16_bf16 v[16:31], v[68:71], v[224:227], v[16:31]
	global_load_dwordx4 v[156:159], v235, s[84:85]
	global_load_dwordx4 v[160:163], v236, s[84:85]
	global_load_dwordx4 v[164:167], v237, s[84:85]
	global_load_dwordx4 v[168:171], v238, s[84:85]
	global_load_dwordx4 v[172:175], v100, s[84:85] offset:768
	global_load_dwordx4 v[176:179], v149, s[84:85] offset:768
	global_load_dwordx4 v[180:183], v100, s[84:85] offset:832
	global_load_dwordx4 v[184:187], v149, s[84:85] offset:832
	s_add_u32 s84, s84, 0x30000
	s_addc_u32 s85, s85, 0
	ds_read_b64_tr_b16 v[72:73], v231
	ds_read_b64_tr_b16 v[74:75], v231 offset:512
	ds_read_b64_tr_b16 v[76:77], v231 offset:2048
	ds_read_b64_tr_b16 v[78:79], v231 offset:2560
	ds_read_b64_tr_b16 v[220:221], v231 offset:1024
	ds_read_b64_tr_b16 v[222:223], v231 offset:1536
	ds_read_b64_tr_b16 v[224:225], v231 offset:3072
	ds_read_b64_tr_b16 v[226:227], v231 offset:3584
	s_waitcnt vmcnt(8)
	ds_write_b128 v247, v[116:119]
	ds_write_b128 v247, v[120:123] offset:1024
	ds_write_b128 v247, v[124:127] offset:2048
	ds_write_b128 v247, v[128:131] offset:3072
	ds_read_b128 v[116:119], v248
	ds_read_b128 v[120:123], v249
	ds_read_b128 v[124:127], v250
	ds_read_b128 v[128:131], v251
	ds_write_b128 v112, v[132:135]
	ds_write_b128 v112, v[136:139] offset:1024
	ds_write_b128 v112, v[140:143] offset:2048
	ds_write_b128 v112, v[144:147] offset:3072
	v_exp_f32_e32 v188, v188
	v_exp_f32_e32 v189, v189
	v_exp_f32_e32 v190, v190
	v_exp_f32_e32 v191, v191
	v_exp_f32_e32 v192, v192
	v_exp_f32_e32 v193, v193
	s_waitcnt lgkmcnt(4)
	v_mfma_f32_32x32x16_bf16 v[32:47], v[116:119], v[48:51], v[32:47]
	v_exp_f32_e32 v194, v194
	v_exp_f32_e32 v195, v195
	v_mfma_f32_32x32x16_bf16 v[32:47], v[120:123], v[52:55], v[32:47]
	v_exp_f32_e32 v196, v196
	v_exp_f32_e32 v197, v197
	v_exp_f32_e32 v198, v198
	v_mfma_f32_32x32x16_bf16 v[32:47], v[124:127], v[56:59], v[32:47]
	v_exp_f32_e32 v199, v199
	v_exp_f32_e32 v200, v200
	v_mfma_f32_32x32x16_bf16 v[32:47], v[128:131], v[60:63], v[32:47]
	v_exp_f32_e32 v201, v201
	v_exp_f32_e32 v202, v202
	v_exp_f32_e32 v203, v203
	v_cvt_pk_bf16_f32 v64, v188, v189
	v_cvt_pk_bf16_f32 v65, v190, v191
	v_cvt_pk_bf16_f32 v66, v192, v193
	v_cvt_pk_bf16_f32 v67, v194, v195
	v_cvt_pk_bf16_f32 v68, v196, v197
	v_cvt_pk_bf16_f32 v69, v198, v199
	v_cvt_pk_bf16_f32 v70, v200, v201
	v_cvt_pk_bf16_f32 v71, v202, v203
	v_pk_add_f32 v[232:233], v[232:233], v[188:189]
	v_pk_add_f32 v[232:233], v[232:233], v[190:191]
	v_pk_add_f32 v[232:233], v[232:233], v[192:193]
	v_pk_add_f32 v[232:233], v[232:233], v[194:195]
	v_pk_add_f32 v[232:233], v[232:233], v[196:197]
	v_pk_add_f32 v[232:233], v[232:233], v[198:199]
	v_pk_add_f32 v[232:233], v[232:233], v[200:201]
	v_pk_add_f32 v[232:233], v[232:233], v[202:203]
	ds_read2_b32 v[188:189], v115 offset0:204 offset1:205
	ds_read2_b32 v[190:191], v115 offset0:206 offset1:207
	ds_read2_b32 v[192:193], v115 offset0:212 offset1:213
	ds_read2_b32 v[194:195], v115 offset0:214 offset1:215
	ds_read2_b32 v[196:197], v115 offset0:221 offset1:222
	ds_read2_b32 v[198:199], v115 offset0:223 offset1:224
	ds_read2_b32 v[200:201], v115 offset0:229 offset1:230
	ds_read2_b32 v[202:203], v115 offset0:231 offset1:232
	v_mfma_f32_32x32x16_bf16 v[0:15], v[64:67], v[72:75], v[0:15]
	v_mfma_f32_32x32x16_bf16 v[16:31], v[64:67], v[76:79], v[16:31]
	v_mfma_f32_32x32x16_bf16 v[0:15], v[68:71], v[220:223], v[0:15]
	v_mfma_f32_32x32x16_bf16 v[16:31], v[68:71], v[224:227], v[16:31]
	global_load_dwordx4 v[116:119], v235, s[84:85]
	global_load_dwordx4 v[120:123], v236, s[84:85]
	global_load_dwordx4 v[124:127], v237, s[84:85]
	global_load_dwordx4 v[128:131], v238, s[84:85]
	global_load_dwordx4 v[132:135], v100, s[84:85] offset:768
	global_load_dwordx4 v[136:139], v149, s[84:85] offset:768
	global_load_dwordx4 v[140:143], v100, s[84:85] offset:832
	global_load_dwordx4 v[144:147], v149, s[84:85] offset:832
	s_add_u32 s84, s84, 0x30000
	s_addc_u32 s85, s85, 0
	ds_read_b64_tr_b16 v[72:73], v231
	ds_read_b64_tr_b16 v[74:75], v231 offset:512
	ds_read_b64_tr_b16 v[76:77], v231 offset:2048
	ds_read_b64_tr_b16 v[78:79], v231 offset:2560
	ds_read_b64_tr_b16 v[220:221], v231 offset:1024
	ds_read_b64_tr_b16 v[222:223], v231 offset:1536
	ds_read_b64_tr_b16 v[224:225], v231 offset:3072
	ds_read_b64_tr_b16 v[226:227], v231 offset:3584
	s_waitcnt vmcnt(8)
	ds_write_b128 v247, v[156:159]
	ds_write_b128 v247, v[160:163] offset:1024
	ds_write_b128 v247, v[164:167] offset:2048
	ds_write_b128 v247, v[168:171] offset:3072
	ds_read_b128 v[156:159], v248
	ds_read_b128 v[160:163], v249
	ds_read_b128 v[164:167], v250
	ds_read_b128 v[168:171], v251
	ds_write_b128 v112, v[172:175]
	ds_write_b128 v112, v[176:179] offset:1024
	ds_write_b128 v112, v[180:183] offset:2048
	ds_write_b128 v112, v[184:187] offset:3072
	v_exp_f32_e32 v32, v32
	v_exp_f32_e32 v33, v33
	v_exp_f32_e32 v34, v34
	v_exp_f32_e32 v35, v35
	v_exp_f32_e32 v36, v36
	v_exp_f32_e32 v37, v37
	s_waitcnt lgkmcnt(4)
	v_mfma_f32_32x32x16_bf16 v[188:203], v[156:159], v[48:51], v[188:203]
	v_exp_f32_e32 v38, v38
	v_exp_f32_e32 v39, v39
	v_mfma_f32_32x32x16_bf16 v[188:203], v[160:163], v[52:55], v[188:203]
	v_exp_f32_e32 v40, v40
	v_exp_f32_e32 v41, v41
	v_exp_f32_e32 v42, v42
	v_mfma_f32_32x32x16_bf16 v[188:203], v[164:167], v[56:59], v[188:203]
	v_exp_f32_e32 v43, v43
	v_exp_f32_e32 v44, v44
	v_mfma_f32_32x32x16_bf16 v[188:203], v[168:171], v[60:63], v[188:203]
	v_exp_f32_e32 v45, v45
	v_exp_f32_e32 v46, v46
	v_exp_f32_e32 v47, v47
	v_cvt_pk_bf16_f32 v64, v32, v33
	v_cvt_pk_bf16_f32 v65, v34, v35
	v_cvt_pk_bf16_f32 v66, v36, v37
	v_cvt_pk_bf16_f32 v67, v38, v39
	v_cvt_pk_bf16_f32 v68, v40, v41
	v_cvt_pk_bf16_f32 v69, v42, v43
	v_cvt_pk_bf16_f32 v70, v44, v45
	v_cvt_pk_bf16_f32 v71, v46, v47
	v_pk_add_f32 v[232:233], v[232:233], v[32:33]
	v_pk_add_f32 v[232:233], v[232:233], v[34:35]
	v_pk_add_f32 v[232:233], v[232:233], v[36:37]
	v_pk_add_f32 v[232:233], v[232:233], v[38:39]
	v_pk_add_f32 v[232:233], v[232:233], v[40:41]
	v_pk_add_f32 v[232:233], v[232:233], v[42:43]
	v_pk_add_f32 v[232:233], v[232:233], v[44:45]
	v_pk_add_f32 v[232:233], v[232:233], v[46:47]
	v_add_u32_e32 v115, 952, v115
	ds_read2_b32 v[32:33], v115 offset0:0 offset1:1
	ds_read2_b32 v[34:35], v115 offset0:2 offset1:3
	ds_read2_b32 v[36:37], v115 offset0:8 offset1:9
	ds_read2_b32 v[38:39], v115 offset0:10 offset1:11
	ds_read2_b32 v[40:41], v115 offset0:17 offset1:18
	ds_read2_b32 v[42:43], v115 offset0:19 offset1:20
	ds_read2_b32 v[44:45], v115 offset0:25 offset1:26
	ds_read2_b32 v[46:47], v115 offset0:27 offset1:28
	v_mfma_f32_32x32x16_bf16 v[0:15], v[64:67], v[72:75], v[0:15]
	v_mfma_f32_32x32x16_bf16 v[16:31], v[64:67], v[76:79], v[16:31]
	v_mfma_f32_32x32x16_bf16 v[0:15], v[68:71], v[220:223], v[0:15]
	v_mfma_f32_32x32x16_bf16 v[16:31], v[68:71], v[224:227], v[16:31]
	global_load_dwordx4 v[156:159], v235, s[84:85]
	global_load_dwordx4 v[160:163], v236, s[84:85]
	global_load_dwordx4 v[164:167], v237, s[84:85]
	global_load_dwordx4 v[168:171], v238, s[84:85]
	global_load_dwordx4 v[172:175], v100, s[84:85] offset:768
	global_load_dwordx4 v[176:179], v149, s[84:85] offset:768
	global_load_dwordx4 v[180:183], v100, s[84:85] offset:832
	global_load_dwordx4 v[184:187], v149, s[84:85] offset:832
	s_add_u32 s84, s84, 0x30000
	s_addc_u32 s85, s85, 0
	ds_read_b64_tr_b16 v[72:73], v231
	ds_read_b64_tr_b16 v[74:75], v231 offset:512
	ds_read_b64_tr_b16 v[76:77], v231 offset:2048
	ds_read_b64_tr_b16 v[78:79], v231 offset:2560
	ds_read_b64_tr_b16 v[220:221], v231 offset:1024
	ds_read_b64_tr_b16 v[222:223], v231 offset:1536
	ds_read_b64_tr_b16 v[224:225], v231 offset:3072
	ds_read_b64_tr_b16 v[226:227], v231 offset:3584
	s_waitcnt vmcnt(8)
	ds_write_b128 v247, v[116:119]
	ds_write_b128 v247, v[120:123] offset:1024
	ds_write_b128 v247, v[124:127] offset:2048
	ds_write_b128 v247, v[128:131] offset:3072
	ds_read_b128 v[116:119], v248
	ds_read_b128 v[120:123], v249
	ds_read_b128 v[124:127], v250
	ds_read_b128 v[128:131], v251
	ds_write_b128 v112, v[132:135]
	ds_write_b128 v112, v[136:139] offset:1024
	ds_write_b128 v112, v[140:143] offset:2048
	ds_write_b128 v112, v[144:147] offset:3072
	v_exp_f32_e32 v188, v188
	v_exp_f32_e32 v189, v189
	v_exp_f32_e32 v190, v190
	v_exp_f32_e32 v191, v191
	v_exp_f32_e32 v192, v192
	v_exp_f32_e32 v193, v193
	s_waitcnt lgkmcnt(4)
	v_mfma_f32_32x32x16_bf16 v[32:47], v[116:119], v[48:51], v[32:47]
	v_exp_f32_e32 v194, v194
	v_exp_f32_e32 v195, v195
	v_mfma_f32_32x32x16_bf16 v[32:47], v[120:123], v[52:55], v[32:47]
	v_exp_f32_e32 v196, v196
	v_exp_f32_e32 v197, v197
	v_exp_f32_e32 v198, v198
	v_mfma_f32_32x32x16_bf16 v[32:47], v[124:127], v[56:59], v[32:47]
	v_exp_f32_e32 v199, v199
	v_exp_f32_e32 v200, v200
	v_mfma_f32_32x32x16_bf16 v[32:47], v[128:131], v[60:63], v[32:47]
	v_exp_f32_e32 v201, v201
	v_exp_f32_e32 v202, v202
	v_exp_f32_e32 v203, v203
	v_cvt_pk_bf16_f32 v64, v188, v189
	v_cvt_pk_bf16_f32 v65, v190, v191
	v_cvt_pk_bf16_f32 v66, v192, v193
	v_cvt_pk_bf16_f32 v67, v194, v195
	v_cvt_pk_bf16_f32 v68, v196, v197
	v_cvt_pk_bf16_f32 v69, v198, v199
	v_cvt_pk_bf16_f32 v70, v200, v201
	v_cvt_pk_bf16_f32 v71, v202, v203
	v_pk_add_f32 v[232:233], v[232:233], v[188:189]
	v_pk_add_f32 v[232:233], v[232:233], v[190:191]
	v_pk_add_f32 v[232:233], v[232:233], v[192:193]
	v_pk_add_f32 v[232:233], v[232:233], v[194:195]
	v_pk_add_f32 v[232:233], v[232:233], v[196:197]
	v_pk_add_f32 v[232:233], v[232:233], v[198:199]
	v_pk_add_f32 v[232:233], v[232:233], v[200:201]
	v_pk_add_f32 v[232:233], v[232:233], v[202:203]
	ds_read2_b32 v[188:189], v115 offset0:34 offset1:35
	ds_read2_b32 v[190:191], v115 offset0:36 offset1:37
	ds_read2_b32 v[192:193], v115 offset0:42 offset1:43
	ds_read2_b32 v[194:195], v115 offset0:44 offset1:45
	ds_read2_b32 v[196:197], v115 offset0:51 offset1:52
	ds_read2_b32 v[198:199], v115 offset0:53 offset1:54
	ds_read2_b32 v[200:201], v115 offset0:59 offset1:60
	ds_read2_b32 v[202:203], v115 offset0:61 offset1:62
	v_mfma_f32_32x32x16_bf16 v[0:15], v[64:67], v[72:75], v[0:15]
	v_mfma_f32_32x32x16_bf16 v[16:31], v[64:67], v[76:79], v[16:31]
	v_mfma_f32_32x32x16_bf16 v[0:15], v[68:71], v[220:223], v[0:15]
	v_mfma_f32_32x32x16_bf16 v[16:31], v[68:71], v[224:227], v[16:31]
	global_load_dwordx4 v[116:119], v235, s[84:85]
	global_load_dwordx4 v[120:123], v236, s[84:85]
	global_load_dwordx4 v[124:127], v237, s[84:85]
	global_load_dwordx4 v[128:131], v238, s[84:85]
	global_load_dwordx4 v[132:135], v100, s[84:85] offset:768
	global_load_dwordx4 v[136:139], v149, s[84:85] offset:768
	global_load_dwordx4 v[140:143], v100, s[84:85] offset:832
	global_load_dwordx4 v[144:147], v149, s[84:85] offset:832
	s_add_u32 s84, s84, 0x30000
	s_addc_u32 s85, s85, 0
	ds_read_b64_tr_b16 v[72:73], v231
	ds_read_b64_tr_b16 v[74:75], v231 offset:512
	ds_read_b64_tr_b16 v[76:77], v231 offset:2048
	ds_read_b64_tr_b16 v[78:79], v231 offset:2560
	ds_read_b64_tr_b16 v[220:221], v231 offset:1024
	ds_read_b64_tr_b16 v[222:223], v231 offset:1536
	ds_read_b64_tr_b16 v[224:225], v231 offset:3072
	ds_read_b64_tr_b16 v[226:227], v231 offset:3584
	s_waitcnt vmcnt(8)
	ds_write_b128 v247, v[156:159]
	ds_write_b128 v247, v[160:163] offset:1024
	ds_write_b128 v247, v[164:167] offset:2048
	ds_write_b128 v247, v[168:171] offset:3072
	ds_read_b128 v[156:159], v248
	ds_read_b128 v[160:163], v249
	ds_read_b128 v[164:167], v250
	ds_read_b128 v[168:171], v251
	ds_write_b128 v112, v[172:175]
	ds_write_b128 v112, v[176:179] offset:1024
	ds_write_b128 v112, v[180:183] offset:2048
	ds_write_b128 v112, v[184:187] offset:3072
	v_exp_f32_e32 v32, v32
	v_exp_f32_e32 v33, v33
	v_exp_f32_e32 v34, v34
	v_exp_f32_e32 v35, v35
	v_exp_f32_e32 v36, v36
	v_exp_f32_e32 v37, v37
	s_waitcnt lgkmcnt(4)
	v_mfma_f32_32x32x16_bf16 v[188:203], v[156:159], v[48:51], v[188:203]
	v_exp_f32_e32 v38, v38
	v_exp_f32_e32 v39, v39
	v_mfma_f32_32x32x16_bf16 v[188:203], v[160:163], v[52:55], v[188:203]
	v_exp_f32_e32 v40, v40
	v_exp_f32_e32 v41, v41
	v_exp_f32_e32 v42, v42
	v_mfma_f32_32x32x16_bf16 v[188:203], v[164:167], v[56:59], v[188:203]
	v_exp_f32_e32 v43, v43
	v_exp_f32_e32 v44, v44
	v_mfma_f32_32x32x16_bf16 v[188:203], v[168:171], v[60:63], v[188:203]
	v_exp_f32_e32 v45, v45
	v_exp_f32_e32 v46, v46
	v_exp_f32_e32 v47, v47
	v_cvt_pk_bf16_f32 v64, v32, v33
	v_cvt_pk_bf16_f32 v65, v34, v35
	v_cvt_pk_bf16_f32 v66, v36, v37
	v_cvt_pk_bf16_f32 v67, v38, v39
	v_cvt_pk_bf16_f32 v68, v40, v41
	v_cvt_pk_bf16_f32 v69, v42, v43
	v_cvt_pk_bf16_f32 v70, v44, v45
	v_cvt_pk_bf16_f32 v71, v46, v47
	v_pk_add_f32 v[232:233], v[232:233], v[32:33]
	v_pk_add_f32 v[232:233], v[232:233], v[34:35]
	v_pk_add_f32 v[232:233], v[232:233], v[36:37]
	v_pk_add_f32 v[232:233], v[232:233], v[38:39]
	v_pk_add_f32 v[232:233], v[232:233], v[40:41]
	v_pk_add_f32 v[232:233], v[232:233], v[42:43]
	v_pk_add_f32 v[232:233], v[232:233], v[44:45]
	v_pk_add_f32 v[232:233], v[232:233], v[46:47]
	ds_read2_b32 v[32:33], v115 offset0:68 offset1:69
	ds_read2_b32 v[34:35], v115 offset0:70 offset1:71
	ds_read2_b32 v[36:37], v115 offset0:76 offset1:77
	ds_read2_b32 v[38:39], v115 offset0:78 offset1:79
	ds_read2_b32 v[40:41], v115 offset0:85 offset1:86
	ds_read2_b32 v[42:43], v115 offset0:87 offset1:88
	ds_read2_b32 v[44:45], v115 offset0:93 offset1:94
	ds_read2_b32 v[46:47], v115 offset0:95 offset1:96
	v_mfma_f32_32x32x16_bf16 v[0:15], v[64:67], v[72:75], v[0:15]
	v_mfma_f32_32x32x16_bf16 v[16:31], v[64:67], v[76:79], v[16:31]
	v_mfma_f32_32x32x16_bf16 v[0:15], v[68:71], v[220:223], v[0:15]
	v_mfma_f32_32x32x16_bf16 v[16:31], v[68:71], v[224:227], v[16:31]
	global_load_dwordx4 v[156:159], v235, s[84:85]
	global_load_dwordx4 v[160:163], v236, s[84:85]
	global_load_dwordx4 v[164:167], v237, s[84:85]
	global_load_dwordx4 v[168:171], v238, s[84:85]
	global_load_dwordx4 v[172:175], v100, s[84:85] offset:768
	global_load_dwordx4 v[176:179], v149, s[84:85] offset:768
	global_load_dwordx4 v[180:183], v100, s[84:85] offset:832
	global_load_dwordx4 v[184:187], v149, s[84:85] offset:832
	s_add_u32 s84, s84, 0x30000
	s_addc_u32 s85, s85, 0
	ds_read_b64_tr_b16 v[72:73], v231
	ds_read_b64_tr_b16 v[74:75], v231 offset:512
	ds_read_b64_tr_b16 v[76:77], v231 offset:2048
	ds_read_b64_tr_b16 v[78:79], v231 offset:2560
	ds_read_b64_tr_b16 v[220:221], v231 offset:1024
	ds_read_b64_tr_b16 v[222:223], v231 offset:1536
	ds_read_b64_tr_b16 v[224:225], v231 offset:3072
	ds_read_b64_tr_b16 v[226:227], v231 offset:3584
	s_waitcnt vmcnt(8)
	ds_write_b128 v247, v[116:119]
	ds_write_b128 v247, v[120:123] offset:1024
	ds_write_b128 v247, v[124:127] offset:2048
	ds_write_b128 v247, v[128:131] offset:3072
	ds_read_b128 v[116:119], v248
	ds_read_b128 v[120:123], v249
	ds_read_b128 v[124:127], v250
	ds_read_b128 v[128:131], v251
	ds_write_b128 v112, v[132:135]
	ds_write_b128 v112, v[136:139] offset:1024
	ds_write_b128 v112, v[140:143] offset:2048
	ds_write_b128 v112, v[144:147] offset:3072
	v_exp_f32_e32 v188, v188
	v_exp_f32_e32 v189, v189
	v_exp_f32_e32 v190, v190
	v_exp_f32_e32 v191, v191
	v_exp_f32_e32 v192, v192
	v_exp_f32_e32 v193, v193
	s_waitcnt lgkmcnt(4)
	v_mfma_f32_32x32x16_bf16 v[32:47], v[116:119], v[48:51], v[32:47]
	v_exp_f32_e32 v194, v194
	v_exp_f32_e32 v195, v195
	v_mfma_f32_32x32x16_bf16 v[32:47], v[120:123], v[52:55], v[32:47]
	v_exp_f32_e32 v196, v196
	v_exp_f32_e32 v197, v197
	v_exp_f32_e32 v198, v198
	v_mfma_f32_32x32x16_bf16 v[32:47], v[124:127], v[56:59], v[32:47]
	v_exp_f32_e32 v199, v199
	v_exp_f32_e32 v200, v200
	v_mfma_f32_32x32x16_bf16 v[32:47], v[128:131], v[60:63], v[32:47]
	v_exp_f32_e32 v201, v201
	v_exp_f32_e32 v202, v202
	v_exp_f32_e32 v203, v203
	v_cvt_pk_bf16_f32 v64, v188, v189
	v_cvt_pk_bf16_f32 v65, v190, v191
	v_cvt_pk_bf16_f32 v66, v192, v193
	v_cvt_pk_bf16_f32 v67, v194, v195
	v_cvt_pk_bf16_f32 v68, v196, v197
	v_cvt_pk_bf16_f32 v69, v198, v199
	v_cvt_pk_bf16_f32 v70, v200, v201
	v_cvt_pk_bf16_f32 v71, v202, v203
	v_pk_add_f32 v[232:233], v[232:233], v[188:189]
	v_pk_add_f32 v[232:233], v[232:233], v[190:191]
	v_pk_add_f32 v[232:233], v[232:233], v[192:193]
	v_pk_add_f32 v[232:233], v[232:233], v[194:195]
	v_pk_add_f32 v[232:233], v[232:233], v[196:197]
	v_pk_add_f32 v[232:233], v[232:233], v[198:199]
	v_pk_add_f32 v[232:233], v[232:233], v[200:201]
	v_pk_add_f32 v[232:233], v[232:233], v[202:203]
	ds_read2_b32 v[188:189], v115 offset0:102 offset1:103
	ds_read2_b32 v[190:191], v115 offset0:104 offset1:105
	ds_read2_b32 v[192:193], v115 offset0:110 offset1:111
	ds_read2_b32 v[194:195], v115 offset0:112 offset1:113
	ds_read2_b32 v[196:197], v115 offset0:119 offset1:120
	ds_read2_b32 v[198:199], v115 offset0:121 offset1:122
	ds_read2_b32 v[200:201], v115 offset0:127 offset1:128
	ds_read2_b32 v[202:203], v115 offset0:129 offset1:130
	v_mfma_f32_32x32x16_bf16 v[0:15], v[64:67], v[72:75], v[0:15]
	v_mfma_f32_32x32x16_bf16 v[16:31], v[64:67], v[76:79], v[16:31]
	v_mfma_f32_32x32x16_bf16 v[0:15], v[68:71], v[220:223], v[0:15]
	v_mfma_f32_32x32x16_bf16 v[16:31], v[68:71], v[224:227], v[16:31]
	global_load_dwordx4 v[116:119], v235, s[84:85]
	global_load_dwordx4 v[120:123], v236, s[84:85]
	global_load_dwordx4 v[124:127], v237, s[84:85]
	global_load_dwordx4 v[128:131], v238, s[84:85]
	global_load_dwordx4 v[132:135], v100, s[84:85] offset:768
	global_load_dwordx4 v[136:139], v149, s[84:85] offset:768
	global_load_dwordx4 v[140:143], v100, s[84:85] offset:832
	global_load_dwordx4 v[144:147], v149, s[84:85] offset:832
	s_add_u32 s84, s84, 0x30000
	s_addc_u32 s85, s85, 0
	ds_read_b64_tr_b16 v[72:73], v231
	ds_read_b64_tr_b16 v[74:75], v231 offset:512
	ds_read_b64_tr_b16 v[76:77], v231 offset:2048
	ds_read_b64_tr_b16 v[78:79], v231 offset:2560
	ds_read_b64_tr_b16 v[220:221], v231 offset:1024
	ds_read_b64_tr_b16 v[222:223], v231 offset:1536
	ds_read_b64_tr_b16 v[224:225], v231 offset:3072
	ds_read_b64_tr_b16 v[226:227], v231 offset:3584
	s_waitcnt vmcnt(8)
	ds_write_b128 v247, v[156:159]
	ds_write_b128 v247, v[160:163] offset:1024
	ds_write_b128 v247, v[164:167] offset:2048
	ds_write_b128 v247, v[168:171] offset:3072
	ds_read_b128 v[156:159], v248
	ds_read_b128 v[160:163], v249
	ds_read_b128 v[164:167], v250
	ds_read_b128 v[168:171], v251
	ds_write_b128 v112, v[172:175]
	ds_write_b128 v112, v[176:179] offset:1024
	ds_write_b128 v112, v[180:183] offset:2048
	ds_write_b128 v112, v[184:187] offset:3072
	v_exp_f32_e32 v32, v32
	v_exp_f32_e32 v33, v33
	v_exp_f32_e32 v34, v34
	v_exp_f32_e32 v35, v35
	v_exp_f32_e32 v36, v36
	v_exp_f32_e32 v37, v37
	s_waitcnt lgkmcnt(4)
	v_mfma_f32_32x32x16_bf16 v[188:203], v[156:159], v[48:51], v[188:203]
	v_exp_f32_e32 v38, v38
	v_exp_f32_e32 v39, v39
	v_mfma_f32_32x32x16_bf16 v[188:203], v[160:163], v[52:55], v[188:203]
	v_exp_f32_e32 v40, v40
	v_exp_f32_e32 v41, v41
	v_exp_f32_e32 v42, v42
	v_mfma_f32_32x32x16_bf16 v[188:203], v[164:167], v[56:59], v[188:203]
	v_exp_f32_e32 v43, v43
	v_exp_f32_e32 v44, v44
	v_mfma_f32_32x32x16_bf16 v[188:203], v[168:171], v[60:63], v[188:203]
	v_exp_f32_e32 v45, v45
	v_exp_f32_e32 v46, v46
	v_exp_f32_e32 v47, v47
	v_cvt_pk_bf16_f32 v64, v32, v33
	v_cvt_pk_bf16_f32 v65, v34, v35
	v_cvt_pk_bf16_f32 v66, v36, v37
	v_cvt_pk_bf16_f32 v67, v38, v39
	v_cvt_pk_bf16_f32 v68, v40, v41
	v_cvt_pk_bf16_f32 v69, v42, v43
	v_cvt_pk_bf16_f32 v70, v44, v45
	v_cvt_pk_bf16_f32 v71, v46, v47
	v_pk_add_f32 v[232:233], v[232:233], v[32:33]
	v_pk_add_f32 v[232:233], v[232:233], v[34:35]
	v_pk_add_f32 v[232:233], v[232:233], v[36:37]
	v_pk_add_f32 v[232:233], v[232:233], v[38:39]
	v_pk_add_f32 v[232:233], v[232:233], v[40:41]
	v_pk_add_f32 v[232:233], v[232:233], v[42:43]
	v_pk_add_f32 v[232:233], v[232:233], v[44:45]
	v_pk_add_f32 v[232:233], v[232:233], v[46:47]
	ds_read2_b32 v[32:33], v115 offset0:136 offset1:137
	ds_read2_b32 v[34:35], v115 offset0:138 offset1:139
	ds_read2_b32 v[36:37], v115 offset0:144 offset1:145
	ds_read2_b32 v[38:39], v115 offset0:146 offset1:147
	ds_read2_b32 v[40:41], v115 offset0:153 offset1:154
	ds_read2_b32 v[42:43], v115 offset0:155 offset1:156
	ds_read2_b32 v[44:45], v115 offset0:161 offset1:162
	ds_read2_b32 v[46:47], v115 offset0:163 offset1:164
	v_mfma_f32_32x32x16_bf16 v[0:15], v[64:67], v[72:75], v[0:15]
	v_mfma_f32_32x32x16_bf16 v[16:31], v[64:67], v[76:79], v[16:31]
	v_mfma_f32_32x32x16_bf16 v[0:15], v[68:71], v[220:223], v[0:15]
	v_mfma_f32_32x32x16_bf16 v[16:31], v[68:71], v[224:227], v[16:31]
	global_load_dwordx4 v[156:159], v235, s[84:85]
	global_load_dwordx4 v[160:163], v236, s[84:85]
	global_load_dwordx4 v[164:167], v237, s[84:85]
	global_load_dwordx4 v[168:171], v238, s[84:85]
	global_load_dwordx4 v[172:175], v100, s[84:85] offset:768
	global_load_dwordx4 v[176:179], v149, s[84:85] offset:768
	global_load_dwordx4 v[180:183], v100, s[84:85] offset:832
	global_load_dwordx4 v[184:187], v149, s[84:85] offset:832
	ds_read_b64_tr_b16 v[72:73], v231
	ds_read_b64_tr_b16 v[74:75], v231 offset:512
	ds_read_b64_tr_b16 v[76:77], v231 offset:2048
	ds_read_b64_tr_b16 v[78:79], v231 offset:2560
	ds_read_b64_tr_b16 v[220:221], v231 offset:1024
	ds_read_b64_tr_b16 v[222:223], v231 offset:1536
	ds_read_b64_tr_b16 v[224:225], v231 offset:3072
	ds_read_b64_tr_b16 v[226:227], v231 offset:3584
	s_waitcnt vmcnt(8)
	ds_write_b128 v247, v[116:119]
	ds_write_b128 v247, v[120:123] offset:1024
	ds_write_b128 v247, v[124:127] offset:2048
	ds_write_b128 v247, v[128:131] offset:3072
	ds_read_b128 v[116:119], v248
	ds_read_b128 v[120:123], v249
	ds_read_b128 v[124:127], v250
	ds_read_b128 v[128:131], v251
	ds_write_b128 v112, v[132:135]
	ds_write_b128 v112, v[136:139] offset:1024
	ds_write_b128 v112, v[140:143] offset:2048
	ds_write_b128 v112, v[144:147] offset:3072
	v_exp_f32_e32 v188, v188
	v_exp_f32_e32 v189, v189
	v_exp_f32_e32 v190, v190
	v_exp_f32_e32 v191, v191
	v_exp_f32_e32 v192, v192
	v_exp_f32_e32 v193, v193
	s_waitcnt lgkmcnt(4)
	v_mfma_f32_32x32x16_bf16 v[32:47], v[116:119], v[48:51], v[32:47]
	v_exp_f32_e32 v194, v194
	v_exp_f32_e32 v195, v195
	v_mfma_f32_32x32x16_bf16 v[32:47], v[120:123], v[52:55], v[32:47]
	v_exp_f32_e32 v196, v196
	v_exp_f32_e32 v197, v197
	v_exp_f32_e32 v198, v198
	v_mfma_f32_32x32x16_bf16 v[32:47], v[124:127], v[56:59], v[32:47]
	v_exp_f32_e32 v199, v199
	v_exp_f32_e32 v200, v200
	v_mfma_f32_32x32x16_bf16 v[32:47], v[128:131], v[60:63], v[32:47]
	v_exp_f32_e32 v201, v201
	v_exp_f32_e32 v202, v202
	v_exp_f32_e32 v203, v203
	v_cvt_pk_bf16_f32 v64, v188, v189
	v_cvt_pk_bf16_f32 v65, v190, v191
	v_cvt_pk_bf16_f32 v66, v192, v193
	v_cvt_pk_bf16_f32 v67, v194, v195
	v_cvt_pk_bf16_f32 v68, v196, v197
	v_cvt_pk_bf16_f32 v69, v198, v199
	v_cvt_pk_bf16_f32 v70, v200, v201
	v_cvt_pk_bf16_f32 v71, v202, v203
	v_pk_add_f32 v[232:233], v[232:233], v[188:189]
	v_pk_add_f32 v[232:233], v[232:233], v[190:191]
	v_pk_add_f32 v[232:233], v[232:233], v[192:193]
	v_pk_add_f32 v[232:233], v[232:233], v[194:195]
	v_pk_add_f32 v[232:233], v[232:233], v[196:197]
	v_pk_add_f32 v[232:233], v[232:233], v[198:199]
	v_pk_add_f32 v[232:233], v[232:233], v[200:201]
	v_pk_add_f32 v[232:233], v[232:233], v[202:203]
	ds_read2_b32 v[188:189], v115 offset0:170 offset1:171
	ds_read2_b32 v[190:191], v115 offset0:172 offset1:173
	ds_read2_b32 v[192:193], v115 offset0:178 offset1:179
	ds_read2_b32 v[194:195], v115 offset0:180 offset1:181
	ds_read2_b32 v[196:197], v115 offset0:187 offset1:188
	ds_read2_b32 v[198:199], v115 offset0:189 offset1:190
	ds_read2_b32 v[200:201], v115 offset0:195 offset1:196
	ds_read2_b32 v[202:203], v115 offset0:197 offset1:198
	v_mfma_f32_32x32x16_bf16 v[0:15], v[64:67], v[72:75], v[0:15]
	v_mfma_f32_32x32x16_bf16 v[16:31], v[64:67], v[76:79], v[16:31]
	v_mfma_f32_32x32x16_bf16 v[0:15], v[68:71], v[220:223], v[0:15]
	v_mfma_f32_32x32x16_bf16 v[16:31], v[68:71], v[224:227], v[16:31]
	global_load_dwordx4 v[116:119], v239, s[86:87]
	global_load_dwordx4 v[120:123], v240, s[86:87]
	global_load_dwordx4 v[124:127], v241, s[86:87]
	global_load_dwordx4 v[128:131], v242, s[86:87]
	global_load_dwordx4 v[132:135], v101, s[86:87] offset:768
	global_load_dwordx4 v[136:139], v150, s[86:87] offset:768
	global_load_dwordx4 v[140:143], v101, s[86:87] offset:832
	global_load_dwordx4 v[144:147], v150, s[86:87] offset:832
	s_add_u32 s86, s86, 0xc0000
	s_addc_u32 s87, s87, 0
	ds_read_b64_tr_b16 v[72:73], v231
	ds_read_b64_tr_b16 v[74:75], v231 offset:512
	ds_read_b64_tr_b16 v[76:77], v231 offset:2048
	ds_read_b64_tr_b16 v[78:79], v231 offset:2560
	ds_read_b64_tr_b16 v[220:221], v231 offset:1024
	ds_read_b64_tr_b16 v[222:223], v231 offset:1536
	ds_read_b64_tr_b16 v[224:225], v231 offset:3072
	ds_read_b64_tr_b16 v[226:227], v231 offset:3584
	s_waitcnt vmcnt(8)
	ds_write_b128 v247, v[156:159]
	ds_write_b128 v247, v[160:163] offset:1024
	ds_write_b128 v247, v[164:167] offset:2048
	ds_write_b128 v247, v[168:171] offset:3072
	ds_read_b128 v[156:159], v248
	ds_read_b128 v[160:163], v249
	ds_read_b128 v[164:167], v250
	ds_read_b128 v[168:171], v251
	ds_write_b128 v112, v[172:175]
	ds_write_b128 v112, v[176:179] offset:1024
	ds_write_b128 v112, v[180:183] offset:2048
	ds_write_b128 v112, v[184:187] offset:3072
	v_exp_f32_e32 v32, v32
	v_exp_f32_e32 v33, v33
	v_exp_f32_e32 v34, v34
	v_exp_f32_e32 v35, v35
	v_exp_f32_e32 v36, v36
	v_exp_f32_e32 v37, v37
	s_waitcnt lgkmcnt(4)
	v_mfma_f32_32x32x16_bf16 v[188:203], v[156:159], v[48:51], v[188:203]
	v_exp_f32_e32 v38, v38
	v_exp_f32_e32 v39, v39
	v_mfma_f32_32x32x16_bf16 v[188:203], v[160:163], v[52:55], v[188:203]
	v_exp_f32_e32 v40, v40
	v_exp_f32_e32 v41, v41
	v_exp_f32_e32 v42, v42
	v_mfma_f32_32x32x16_bf16 v[188:203], v[164:167], v[56:59], v[188:203]
	v_exp_f32_e32 v43, v43
	v_exp_f32_e32 v44, v44
	v_mfma_f32_32x32x16_bf16 v[188:203], v[168:171], v[60:63], v[188:203]
	v_exp_f32_e32 v45, v45
	v_exp_f32_e32 v46, v46
	v_exp_f32_e32 v47, v47
	v_cvt_pk_bf16_f32 v64, v32, v33
	v_cvt_pk_bf16_f32 v65, v34, v35
	v_cvt_pk_bf16_f32 v66, v36, v37
	v_cvt_pk_bf16_f32 v67, v38, v39
	v_cvt_pk_bf16_f32 v68, v40, v41
	v_cvt_pk_bf16_f32 v69, v42, v43
	v_cvt_pk_bf16_f32 v70, v44, v45
	v_cvt_pk_bf16_f32 v71, v46, v47
	v_pk_add_f32 v[232:233], v[232:233], v[32:33]
	v_pk_add_f32 v[232:233], v[232:233], v[34:35]
	v_pk_add_f32 v[232:233], v[232:233], v[36:37]
	v_pk_add_f32 v[232:233], v[232:233], v[38:39]
	v_pk_add_f32 v[232:233], v[232:233], v[40:41]
	v_pk_add_f32 v[232:233], v[232:233], v[42:43]
	v_pk_add_f32 v[232:233], v[232:233], v[44:45]
	v_pk_add_f32 v[232:233], v[232:233], v[46:47]
	v_mov_b32_e32 v115, v229
	ds_read2_b32 v[32:33], v115 offset0:0 offset1:1
	ds_read2_b32 v[34:35], v115 offset0:2 offset1:3
	ds_read2_b32 v[36:37], v115 offset0:8 offset1:9
	ds_read2_b32 v[38:39], v115 offset0:10 offset1:11
	ds_read2_b32 v[40:41], v115 offset0:16 offset1:17
	ds_read2_b32 v[42:43], v115 offset0:18 offset1:19
	ds_read2_b32 v[44:45], v115 offset0:24 offset1:25
	ds_read2_b32 v[46:47], v115 offset0:26 offset1:27
	v_mfma_f32_32x32x16_bf16 v[0:15], v[64:67], v[72:75], v[0:15]
	v_mfma_f32_32x32x16_bf16 v[16:31], v[64:67], v[76:79], v[16:31]
	v_mfma_f32_32x32x16_bf16 v[0:15], v[68:71], v[220:223], v[0:15]
	v_mfma_f32_32x32x16_bf16 v[16:31], v[68:71], v[224:227], v[16:31]
	global_load_dwordx4 v[156:159], v239, s[86:87]
	global_load_dwordx4 v[160:163], v240, s[86:87]
	global_load_dwordx4 v[164:167], v241, s[86:87]
	global_load_dwordx4 v[168:171], v242, s[86:87]
	global_load_dwordx4 v[172:175], v101, s[86:87] offset:768
	global_load_dwordx4 v[176:179], v150, s[86:87] offset:768
	global_load_dwordx4 v[180:183], v101, s[86:87] offset:832
	global_load_dwordx4 v[184:187], v150, s[86:87] offset:832
	s_add_u32 s86, s86, 0xc0000
	s_addc_u32 s87, s87, 0
	ds_read_b64_tr_b16 v[72:73], v231
	ds_read_b64_tr_b16 v[74:75], v231 offset:512
	ds_read_b64_tr_b16 v[76:77], v231 offset:2048
	ds_read_b64_tr_b16 v[78:79], v231 offset:2560
	ds_read_b64_tr_b16 v[220:221], v231 offset:1024
	ds_read_b64_tr_b16 v[222:223], v231 offset:1536
	ds_read_b64_tr_b16 v[224:225], v231 offset:3072
	ds_read_b64_tr_b16 v[226:227], v231 offset:3584
	s_waitcnt vmcnt(8)
	ds_write_b128 v247, v[116:119]
	ds_write_b128 v247, v[120:123] offset:1024
	ds_write_b128 v247, v[124:127] offset:2048
	ds_write_b128 v247, v[128:131] offset:3072
	ds_read_b128 v[116:119], v248
	ds_read_b128 v[120:123], v249
	ds_read_b128 v[124:127], v250
	ds_read_b128 v[128:131], v251
	ds_write_b128 v112, v[132:135]
	ds_write_b128 v112, v[136:139] offset:1024
	ds_write_b128 v112, v[140:143] offset:2048
	ds_write_b128 v112, v[144:147] offset:3072
	v_exp_f32_e32 v188, v188
	v_exp_f32_e32 v189, v189
	v_exp_f32_e32 v190, v190
	v_exp_f32_e32 v191, v191
	v_exp_f32_e32 v192, v192
	v_exp_f32_e32 v193, v193
	s_waitcnt lgkmcnt(4)
	v_mfma_f32_32x32x16_bf16 v[32:47], v[116:119], v[48:51], v[32:47]
	v_exp_f32_e32 v194, v194
	v_exp_f32_e32 v195, v195
	v_mfma_f32_32x32x16_bf16 v[32:47], v[120:123], v[52:55], v[32:47]
	v_exp_f32_e32 v196, v196
	v_exp_f32_e32 v197, v197
	v_exp_f32_e32 v198, v198
	v_mfma_f32_32x32x16_bf16 v[32:47], v[124:127], v[56:59], v[32:47]
	v_exp_f32_e32 v199, v199
	v_exp_f32_e32 v200, v200
	v_mfma_f32_32x32x16_bf16 v[32:47], v[128:131], v[60:63], v[32:47]
	v_exp_f32_e32 v201, v201
	v_exp_f32_e32 v202, v202
	v_exp_f32_e32 v203, v203
	v_cvt_pk_bf16_f32 v64, v188, v189
	v_cvt_pk_bf16_f32 v65, v190, v191
	v_cvt_pk_bf16_f32 v66, v192, v193
	v_cvt_pk_bf16_f32 v67, v194, v195
	v_cvt_pk_bf16_f32 v68, v196, v197
	v_cvt_pk_bf16_f32 v69, v198, v199
	v_cvt_pk_bf16_f32 v70, v200, v201
	v_cvt_pk_bf16_f32 v71, v202, v203
	v_pk_add_f32 v[232:233], v[232:233], v[188:189]
	v_pk_add_f32 v[232:233], v[232:233], v[190:191]
	v_pk_add_f32 v[232:233], v[232:233], v[192:193]
	v_pk_add_f32 v[232:233], v[232:233], v[194:195]
	v_pk_add_f32 v[232:233], v[232:233], v[196:197]
	v_pk_add_f32 v[232:233], v[232:233], v[198:199]
	v_pk_add_f32 v[232:233], v[232:233], v[200:201]
	v_pk_add_f32 v[232:233], v[232:233], v[202:203]
	ds_read2_b32 v[188:189], v115 offset0:32 offset1:33
	ds_read2_b32 v[190:191], v115 offset0:34 offset1:35
	ds_read2_b32 v[192:193], v115 offset0:40 offset1:41
	ds_read2_b32 v[194:195], v115 offset0:42 offset1:43
	ds_read2_b32 v[196:197], v115 offset0:48 offset1:49
	ds_read2_b32 v[198:199], v115 offset0:50 offset1:51
	ds_read2_b32 v[200:201], v115 offset0:56 offset1:57
	ds_read2_b32 v[202:203], v115 offset0:58 offset1:59
	v_mfma_f32_32x32x16_bf16 v[0:15], v[64:67], v[72:75], v[0:15]
	v_mfma_f32_32x32x16_bf16 v[16:31], v[64:67], v[76:79], v[16:31]
	v_mfma_f32_32x32x16_bf16 v[0:15], v[68:71], v[220:223], v[0:15]
	v_mfma_f32_32x32x16_bf16 v[16:31], v[68:71], v[224:227], v[16:31]
	global_load_dwordx4 v[116:119], v239, s[86:87]
	global_load_dwordx4 v[120:123], v240, s[86:87]
	global_load_dwordx4 v[124:127], v241, s[86:87]
	global_load_dwordx4 v[128:131], v242, s[86:87]
	global_load_dwordx4 v[132:135], v101, s[86:87] offset:768
	global_load_dwordx4 v[136:139], v150, s[86:87] offset:768
	global_load_dwordx4 v[140:143], v101, s[86:87] offset:832
	global_load_dwordx4 v[144:147], v150, s[86:87] offset:832
	s_add_u32 s86, s86, 0xc0000
	s_addc_u32 s87, s87, 0
	ds_read_b64_tr_b16 v[72:73], v231
	ds_read_b64_tr_b16 v[74:75], v231 offset:512
	ds_read_b64_tr_b16 v[76:77], v231 offset:2048
	ds_read_b64_tr_b16 v[78:79], v231 offset:2560
	ds_read_b64_tr_b16 v[220:221], v231 offset:1024
	ds_read_b64_tr_b16 v[222:223], v231 offset:1536
	ds_read_b64_tr_b16 v[224:225], v231 offset:3072
	ds_read_b64_tr_b16 v[226:227], v231 offset:3584
	s_waitcnt vmcnt(8)
	ds_write_b128 v247, v[156:159]
	ds_write_b128 v247, v[160:163] offset:1024
	ds_write_b128 v247, v[164:167] offset:2048
	ds_write_b128 v247, v[168:171] offset:3072
	ds_read_b128 v[156:159], v248
	ds_read_b128 v[160:163], v249
	ds_read_b128 v[164:167], v250
	ds_read_b128 v[168:171], v251
	ds_write_b128 v112, v[172:175]
	ds_write_b128 v112, v[176:179] offset:1024
	ds_write_b128 v112, v[180:183] offset:2048
	ds_write_b128 v112, v[184:187] offset:3072
	v_exp_f32_e32 v32, v32
	v_exp_f32_e32 v33, v33
	v_exp_f32_e32 v34, v34
	v_exp_f32_e32 v35, v35
	v_exp_f32_e32 v36, v36
	v_exp_f32_e32 v37, v37
	s_waitcnt lgkmcnt(4)
	v_mfma_f32_32x32x16_bf16 v[188:203], v[156:159], v[48:51], v[188:203]
	v_exp_f32_e32 v38, v38
	v_exp_f32_e32 v39, v39
	v_mfma_f32_32x32x16_bf16 v[188:203], v[160:163], v[52:55], v[188:203]
	v_exp_f32_e32 v40, v40
	v_exp_f32_e32 v41, v41
	v_exp_f32_e32 v42, v42
	v_mfma_f32_32x32x16_bf16 v[188:203], v[164:167], v[56:59], v[188:203]
	v_exp_f32_e32 v43, v43
	v_exp_f32_e32 v44, v44
	v_mfma_f32_32x32x16_bf16 v[188:203], v[168:171], v[60:63], v[188:203]
	v_exp_f32_e32 v45, v45
	v_exp_f32_e32 v46, v46
	v_exp_f32_e32 v47, v47
	v_cvt_pk_bf16_f32 v64, v32, v33
	v_cvt_pk_bf16_f32 v65, v34, v35
	v_cvt_pk_bf16_f32 v66, v36, v37
	v_cvt_pk_bf16_f32 v67, v38, v39
	v_cvt_pk_bf16_f32 v68, v40, v41
	v_cvt_pk_bf16_f32 v69, v42, v43
	v_cvt_pk_bf16_f32 v70, v44, v45
	v_cvt_pk_bf16_f32 v71, v46, v47
	v_pk_add_f32 v[232:233], v[232:233], v[32:33]
	v_pk_add_f32 v[232:233], v[232:233], v[34:35]
	v_pk_add_f32 v[232:233], v[232:233], v[36:37]
	v_pk_add_f32 v[232:233], v[232:233], v[38:39]
	v_pk_add_f32 v[232:233], v[232:233], v[40:41]
	v_pk_add_f32 v[232:233], v[232:233], v[42:43]
	v_pk_add_f32 v[232:233], v[232:233], v[44:45]
	v_pk_add_f32 v[232:233], v[232:233], v[46:47]
	ds_read2_b32 v[32:33], v115 offset0:64 offset1:65
	ds_read2_b32 v[34:35], v115 offset0:66 offset1:67
	ds_read2_b32 v[36:37], v115 offset0:72 offset1:73
	ds_read2_b32 v[38:39], v115 offset0:74 offset1:75
	ds_read2_b32 v[40:41], v115 offset0:80 offset1:81
	ds_read2_b32 v[42:43], v115 offset0:82 offset1:83
	ds_read2_b32 v[44:45], v115 offset0:88 offset1:89
	ds_read2_b32 v[46:47], v115 offset0:90 offset1:91
	v_mfma_f32_32x32x16_bf16 v[0:15], v[64:67], v[72:75], v[0:15]
	v_mfma_f32_32x32x16_bf16 v[16:31], v[64:67], v[76:79], v[16:31]
	v_mfma_f32_32x32x16_bf16 v[0:15], v[68:71], v[220:223], v[0:15]
	v_mfma_f32_32x32x16_bf16 v[16:31], v[68:71], v[224:227], v[16:31]
	global_load_dwordx4 v[156:159], v239, s[86:87]
	global_load_dwordx4 v[160:163], v240, s[86:87]
	global_load_dwordx4 v[164:167], v241, s[86:87]
	global_load_dwordx4 v[168:171], v242, s[86:87]
	global_load_dwordx4 v[172:175], v101, s[86:87] offset:768
	global_load_dwordx4 v[176:179], v150, s[86:87] offset:768
	global_load_dwordx4 v[180:183], v101, s[86:87] offset:832
	global_load_dwordx4 v[184:187], v150, s[86:87] offset:832
	s_add_u32 s86, s86, 0xc0000
	s_addc_u32 s87, s87, 0
	ds_read_b64_tr_b16 v[72:73], v231
	ds_read_b64_tr_b16 v[74:75], v231 offset:512
	ds_read_b64_tr_b16 v[76:77], v231 offset:2048
	ds_read_b64_tr_b16 v[78:79], v231 offset:2560
	ds_read_b64_tr_b16 v[220:221], v231 offset:1024
	ds_read_b64_tr_b16 v[222:223], v231 offset:1536
	ds_read_b64_tr_b16 v[224:225], v231 offset:3072
	ds_read_b64_tr_b16 v[226:227], v231 offset:3584
	s_waitcnt vmcnt(8)
	ds_write_b128 v247, v[116:119]
	ds_write_b128 v247, v[120:123] offset:1024
	ds_write_b128 v247, v[124:127] offset:2048
	ds_write_b128 v247, v[128:131] offset:3072
	ds_read_b128 v[116:119], v248
	ds_read_b128 v[120:123], v249
	ds_read_b128 v[124:127], v250
	ds_read_b128 v[128:131], v251
	ds_write_b128 v112, v[132:135]
	ds_write_b128 v112, v[136:139] offset:1024
	ds_write_b128 v112, v[140:143] offset:2048
	ds_write_b128 v112, v[144:147] offset:3072
	v_exp_f32_e32 v188, v188
	v_exp_f32_e32 v189, v189
	v_exp_f32_e32 v190, v190
	v_exp_f32_e32 v191, v191
	v_exp_f32_e32 v192, v192
	v_exp_f32_e32 v193, v193
	s_waitcnt lgkmcnt(4)
	v_mfma_f32_32x32x16_bf16 v[32:47], v[116:119], v[48:51], v[32:47]
	v_exp_f32_e32 v194, v194
	v_exp_f32_e32 v195, v195
	v_mfma_f32_32x32x16_bf16 v[32:47], v[120:123], v[52:55], v[32:47]
	v_exp_f32_e32 v196, v196
	v_exp_f32_e32 v197, v197
	v_exp_f32_e32 v198, v198
	v_mfma_f32_32x32x16_bf16 v[32:47], v[124:127], v[56:59], v[32:47]
	v_exp_f32_e32 v199, v199
	v_exp_f32_e32 v200, v200
	v_mfma_f32_32x32x16_bf16 v[32:47], v[128:131], v[60:63], v[32:47]
	v_exp_f32_e32 v201, v201
	v_exp_f32_e32 v202, v202
	v_exp_f32_e32 v203, v203
	v_cvt_pk_bf16_f32 v64, v188, v189
	v_cvt_pk_bf16_f32 v65, v190, v191
	v_cvt_pk_bf16_f32 v66, v192, v193
	v_cvt_pk_bf16_f32 v67, v194, v195
	v_cvt_pk_bf16_f32 v68, v196, v197
	v_cvt_pk_bf16_f32 v69, v198, v199
	v_cvt_pk_bf16_f32 v70, v200, v201
	v_cvt_pk_bf16_f32 v71, v202, v203
	v_pk_add_f32 v[232:233], v[232:233], v[188:189]
	v_pk_add_f32 v[232:233], v[232:233], v[190:191]
	v_pk_add_f32 v[232:233], v[232:233], v[192:193]
	v_pk_add_f32 v[232:233], v[232:233], v[194:195]
	v_pk_add_f32 v[232:233], v[232:233], v[196:197]
	v_pk_add_f32 v[232:233], v[232:233], v[198:199]
	v_pk_add_f32 v[232:233], v[232:233], v[200:201]
	v_pk_add_f32 v[232:233], v[232:233], v[202:203]
	ds_read2_b32 v[188:189], v115 offset0:96 offset1:97
	ds_read2_b32 v[190:191], v115 offset0:98 offset1:99
	ds_read2_b32 v[192:193], v115 offset0:104 offset1:105
	ds_read2_b32 v[194:195], v115 offset0:106 offset1:107
	ds_read2_b32 v[196:197], v115 offset0:112 offset1:113
	ds_read2_b32 v[198:199], v115 offset0:114 offset1:115
	ds_read2_b32 v[200:201], v115 offset0:120 offset1:121
	ds_read2_b32 v[202:203], v115 offset0:122 offset1:123
	v_mfma_f32_32x32x16_bf16 v[0:15], v[64:67], v[72:75], v[0:15]
	v_mfma_f32_32x32x16_bf16 v[16:31], v[64:67], v[76:79], v[16:31]
	v_mfma_f32_32x32x16_bf16 v[0:15], v[68:71], v[220:223], v[0:15]
	v_mfma_f32_32x32x16_bf16 v[16:31], v[68:71], v[224:227], v[16:31]
	global_load_dwordx4 v[116:119], v239, s[86:87]
	global_load_dwordx4 v[120:123], v240, s[86:87]
	global_load_dwordx4 v[124:127], v241, s[86:87]
	global_load_dwordx4 v[128:131], v242, s[86:87]
	global_load_dwordx4 v[132:135], v101, s[86:87] offset:768
	global_load_dwordx4 v[136:139], v150, s[86:87] offset:768
	global_load_dwordx4 v[140:143], v101, s[86:87] offset:832
	global_load_dwordx4 v[144:147], v150, s[86:87] offset:832
	s_add_u32 s86, s86, 0xc0000
	s_addc_u32 s87, s87, 0
	ds_read_b64_tr_b16 v[72:73], v231
	ds_read_b64_tr_b16 v[74:75], v231 offset:512
	ds_read_b64_tr_b16 v[76:77], v231 offset:2048
	ds_read_b64_tr_b16 v[78:79], v231 offset:2560
	ds_read_b64_tr_b16 v[220:221], v231 offset:1024
	ds_read_b64_tr_b16 v[222:223], v231 offset:1536
	ds_read_b64_tr_b16 v[224:225], v231 offset:3072
	ds_read_b64_tr_b16 v[226:227], v231 offset:3584
	s_waitcnt vmcnt(8)
	ds_write_b128 v247, v[156:159]
	ds_write_b128 v247, v[160:163] offset:1024
	ds_write_b128 v247, v[164:167] offset:2048
	ds_write_b128 v247, v[168:171] offset:3072
	ds_read_b128 v[156:159], v248
	ds_read_b128 v[160:163], v249
	ds_read_b128 v[164:167], v250
	ds_read_b128 v[168:171], v251
	ds_write_b128 v112, v[172:175]
	ds_write_b128 v112, v[176:179] offset:1024
	ds_write_b128 v112, v[180:183] offset:2048
	ds_write_b128 v112, v[184:187] offset:3072
	v_exp_f32_e32 v32, v32
	v_exp_f32_e32 v33, v33
	v_exp_f32_e32 v34, v34
	v_exp_f32_e32 v35, v35
	v_exp_f32_e32 v36, v36
	v_exp_f32_e32 v37, v37
	s_waitcnt lgkmcnt(4)
	v_mfma_f32_32x32x16_bf16 v[188:203], v[156:159], v[48:51], v[188:203]
	v_exp_f32_e32 v38, v38
	v_exp_f32_e32 v39, v39
	v_mfma_f32_32x32x16_bf16 v[188:203], v[160:163], v[52:55], v[188:203]
	v_exp_f32_e32 v40, v40
	v_exp_f32_e32 v41, v41
	v_exp_f32_e32 v42, v42
	v_mfma_f32_32x32x16_bf16 v[188:203], v[164:167], v[56:59], v[188:203]
	v_exp_f32_e32 v43, v43
	v_exp_f32_e32 v44, v44
	v_mfma_f32_32x32x16_bf16 v[188:203], v[168:171], v[60:63], v[188:203]
	v_exp_f32_e32 v45, v45
	v_exp_f32_e32 v46, v46
	v_exp_f32_e32 v47, v47
	v_cvt_pk_bf16_f32 v64, v32, v33
	v_cvt_pk_bf16_f32 v65, v34, v35
	v_cvt_pk_bf16_f32 v66, v36, v37
	v_cvt_pk_bf16_f32 v67, v38, v39
	v_cvt_pk_bf16_f32 v68, v40, v41
	v_cvt_pk_bf16_f32 v69, v42, v43
	v_cvt_pk_bf16_f32 v70, v44, v45
	v_cvt_pk_bf16_f32 v71, v46, v47
	v_pk_add_f32 v[232:233], v[232:233], v[32:33]
	v_pk_add_f32 v[232:233], v[232:233], v[34:35]
	v_pk_add_f32 v[232:233], v[232:233], v[36:37]
	v_pk_add_f32 v[232:233], v[232:233], v[38:39]
	v_pk_add_f32 v[232:233], v[232:233], v[40:41]
	v_pk_add_f32 v[232:233], v[232:233], v[42:43]
	v_pk_add_f32 v[232:233], v[232:233], v[44:45]
	v_pk_add_f32 v[232:233], v[232:233], v[46:47]
	ds_read2_b32 v[32:33], v115 offset0:128 offset1:129
	ds_read2_b32 v[34:35], v115 offset0:130 offset1:131
	ds_read2_b32 v[36:37], v115 offset0:136 offset1:137
	ds_read2_b32 v[38:39], v115 offset0:138 offset1:139
	ds_read2_b32 v[40:41], v115 offset0:144 offset1:145
	ds_read2_b32 v[42:43], v115 offset0:146 offset1:147
	ds_read2_b32 v[44:45], v115 offset0:152 offset1:153
	ds_read2_b32 v[46:47], v115 offset0:154 offset1:155
	v_mfma_f32_32x32x16_bf16 v[0:15], v[64:67], v[72:75], v[0:15]
	v_mfma_f32_32x32x16_bf16 v[16:31], v[64:67], v[76:79], v[16:31]
	v_mfma_f32_32x32x16_bf16 v[0:15], v[68:71], v[220:223], v[0:15]
	v_mfma_f32_32x32x16_bf16 v[16:31], v[68:71], v[224:227], v[16:31]
	global_load_dwordx4 v[156:159], v239, s[86:87]
	global_load_dwordx4 v[160:163], v240, s[86:87]
	global_load_dwordx4 v[164:167], v241, s[86:87]
	global_load_dwordx4 v[168:171], v242, s[86:87]
	global_load_dwordx4 v[172:175], v101, s[86:87] offset:768
	global_load_dwordx4 v[176:179], v150, s[86:87] offset:768
	global_load_dwordx4 v[180:183], v101, s[86:87] offset:832
	global_load_dwordx4 v[184:187], v150, s[86:87] offset:832
	s_add_u32 s86, s86, 0xc0000
	s_addc_u32 s87, s87, 0
	ds_read_b64_tr_b16 v[72:73], v231
	ds_read_b64_tr_b16 v[74:75], v231 offset:512
	ds_read_b64_tr_b16 v[76:77], v231 offset:2048
	ds_read_b64_tr_b16 v[78:79], v231 offset:2560
	ds_read_b64_tr_b16 v[220:221], v231 offset:1024
	ds_read_b64_tr_b16 v[222:223], v231 offset:1536
	ds_read_b64_tr_b16 v[224:225], v231 offset:3072
	ds_read_b64_tr_b16 v[226:227], v231 offset:3584
	s_waitcnt vmcnt(8)
	ds_write_b128 v247, v[116:119]
	ds_write_b128 v247, v[120:123] offset:1024
	ds_write_b128 v247, v[124:127] offset:2048
	ds_write_b128 v247, v[128:131] offset:3072
	ds_read_b128 v[116:119], v248
	ds_read_b128 v[120:123], v249
	ds_read_b128 v[124:127], v250
	ds_read_b128 v[128:131], v251
	ds_write_b128 v112, v[132:135]
	ds_write_b128 v112, v[136:139] offset:1024
	ds_write_b128 v112, v[140:143] offset:2048
	ds_write_b128 v112, v[144:147] offset:3072
	v_exp_f32_e32 v188, v188
	v_exp_f32_e32 v189, v189
	v_exp_f32_e32 v190, v190
	v_exp_f32_e32 v191, v191
	v_exp_f32_e32 v192, v192
	v_exp_f32_e32 v193, v193
	s_waitcnt lgkmcnt(4)
	v_mfma_f32_32x32x16_bf16 v[32:47], v[116:119], v[48:51], v[32:47]
	v_exp_f32_e32 v194, v194
	v_exp_f32_e32 v195, v195
	v_mfma_f32_32x32x16_bf16 v[32:47], v[120:123], v[52:55], v[32:47]
	v_exp_f32_e32 v196, v196
	v_exp_f32_e32 v197, v197
	v_exp_f32_e32 v198, v198
	v_mfma_f32_32x32x16_bf16 v[32:47], v[124:127], v[56:59], v[32:47]
	v_exp_f32_e32 v199, v199
	v_exp_f32_e32 v200, v200
	v_mfma_f32_32x32x16_bf16 v[32:47], v[128:131], v[60:63], v[32:47]
	v_exp_f32_e32 v201, v201
	v_exp_f32_e32 v202, v202
	v_exp_f32_e32 v203, v203
	v_cvt_pk_bf16_f32 v64, v188, v189
	v_cvt_pk_bf16_f32 v65, v190, v191
	v_cvt_pk_bf16_f32 v66, v192, v193
	v_cvt_pk_bf16_f32 v67, v194, v195
	v_cvt_pk_bf16_f32 v68, v196, v197
	v_cvt_pk_bf16_f32 v69, v198, v199
	v_cvt_pk_bf16_f32 v70, v200, v201
	v_cvt_pk_bf16_f32 v71, v202, v203
	v_pk_add_f32 v[232:233], v[232:233], v[188:189]
	v_pk_add_f32 v[232:233], v[232:233], v[190:191]
	v_pk_add_f32 v[232:233], v[232:233], v[192:193]
	v_pk_add_f32 v[232:233], v[232:233], v[194:195]
	v_pk_add_f32 v[232:233], v[232:233], v[196:197]
	v_pk_add_f32 v[232:233], v[232:233], v[198:199]
	v_pk_add_f32 v[232:233], v[232:233], v[200:201]
	v_pk_add_f32 v[232:233], v[232:233], v[202:203]
	ds_read2_b32 v[188:189], v115 offset0:160 offset1:161
	ds_read2_b32 v[190:191], v115 offset0:162 offset1:163
	ds_read2_b32 v[192:193], v115 offset0:168 offset1:169
	ds_read2_b32 v[194:195], v115 offset0:170 offset1:171
	ds_read2_b32 v[196:197], v115 offset0:176 offset1:177
	ds_read2_b32 v[198:199], v115 offset0:178 offset1:179
	ds_read2_b32 v[200:201], v115 offset0:184 offset1:185
	ds_read2_b32 v[202:203], v115 offset0:186 offset1:187
	v_mfma_f32_32x32x16_bf16 v[0:15], v[64:67], v[72:75], v[0:15]
	v_mfma_f32_32x32x16_bf16 v[16:31], v[64:67], v[76:79], v[16:31]
	v_mfma_f32_32x32x16_bf16 v[0:15], v[68:71], v[220:223], v[0:15]
	v_mfma_f32_32x32x16_bf16 v[16:31], v[68:71], v[224:227], v[16:31]
	global_load_dwordx4 v[116:119], v239, s[86:87]
	global_load_dwordx4 v[120:123], v240, s[86:87]
	global_load_dwordx4 v[124:127], v241, s[86:87]
	global_load_dwordx4 v[128:131], v242, s[86:87]
	global_load_dwordx4 v[132:135], v101, s[86:87] offset:768
	global_load_dwordx4 v[136:139], v150, s[86:87] offset:768
	global_load_dwordx4 v[140:143], v101, s[86:87] offset:832
	global_load_dwordx4 v[144:147], v150, s[86:87] offset:832
	s_add_u32 s86, s86, 0xc0000
	s_addc_u32 s87, s87, 0
	ds_read_b64_tr_b16 v[72:73], v231
	ds_read_b64_tr_b16 v[74:75], v231 offset:512
	ds_read_b64_tr_b16 v[76:77], v231 offset:2048
	ds_read_b64_tr_b16 v[78:79], v231 offset:2560
	ds_read_b64_tr_b16 v[220:221], v231 offset:1024
	ds_read_b64_tr_b16 v[222:223], v231 offset:1536
	ds_read_b64_tr_b16 v[224:225], v231 offset:3072
	ds_read_b64_tr_b16 v[226:227], v231 offset:3584
	s_waitcnt vmcnt(8)
	ds_write_b128 v247, v[156:159]
	ds_write_b128 v247, v[160:163] offset:1024
	ds_write_b128 v247, v[164:167] offset:2048
	ds_write_b128 v247, v[168:171] offset:3072
	ds_read_b128 v[156:159], v248
	ds_read_b128 v[160:163], v249
	ds_read_b128 v[164:167], v250
	ds_read_b128 v[168:171], v251
	ds_write_b128 v112, v[172:175]
	ds_write_b128 v112, v[176:179] offset:1024
	ds_write_b128 v112, v[180:183] offset:2048
	ds_write_b128 v112, v[184:187] offset:3072
	v_exp_f32_e32 v32, v32
	v_exp_f32_e32 v33, v33
	v_exp_f32_e32 v34, v34
	v_exp_f32_e32 v35, v35
	v_exp_f32_e32 v36, v36
	v_exp_f32_e32 v37, v37
	s_waitcnt lgkmcnt(4)
	v_mfma_f32_32x32x16_bf16 v[188:203], v[156:159], v[48:51], v[188:203]
	v_exp_f32_e32 v38, v38
	v_exp_f32_e32 v39, v39
	v_mfma_f32_32x32x16_bf16 v[188:203], v[160:163], v[52:55], v[188:203]
	v_exp_f32_e32 v40, v40
	v_exp_f32_e32 v41, v41
	v_exp_f32_e32 v42, v42
	v_mfma_f32_32x32x16_bf16 v[188:203], v[164:167], v[56:59], v[188:203]
	v_exp_f32_e32 v43, v43
	v_exp_f32_e32 v44, v44
	v_mfma_f32_32x32x16_bf16 v[188:203], v[168:171], v[60:63], v[188:203]
	v_exp_f32_e32 v45, v45
	v_exp_f32_e32 v46, v46
	v_exp_f32_e32 v47, v47
	v_cvt_pk_bf16_f32 v64, v32, v33
	v_cvt_pk_bf16_f32 v65, v34, v35
	v_cvt_pk_bf16_f32 v66, v36, v37
	v_cvt_pk_bf16_f32 v67, v38, v39
	v_cvt_pk_bf16_f32 v68, v40, v41
	v_cvt_pk_bf16_f32 v69, v42, v43
	v_cvt_pk_bf16_f32 v70, v44, v45
	v_cvt_pk_bf16_f32 v71, v46, v47
	v_pk_add_f32 v[232:233], v[232:233], v[32:33]
	v_pk_add_f32 v[232:233], v[232:233], v[34:35]
	v_pk_add_f32 v[232:233], v[232:233], v[36:37]
	v_pk_add_f32 v[232:233], v[232:233], v[38:39]
	v_pk_add_f32 v[232:233], v[232:233], v[40:41]
	v_pk_add_f32 v[232:233], v[232:233], v[42:43]
	v_pk_add_f32 v[232:233], v[232:233], v[44:45]
	v_pk_add_f32 v[232:233], v[232:233], v[46:47]
	ds_read2_b32 v[32:33], v115 offset0:192 offset1:193
	ds_read2_b32 v[34:35], v115 offset0:194 offset1:195
	ds_read2_b32 v[36:37], v115 offset0:200 offset1:201
	ds_read2_b32 v[38:39], v115 offset0:202 offset1:203
	ds_read2_b32 v[40:41], v115 offset0:208 offset1:209
	ds_read2_b32 v[42:43], v115 offset0:210 offset1:211
	ds_read2_b32 v[44:45], v115 offset0:216 offset1:217
	ds_read2_b32 v[46:47], v115 offset0:218 offset1:219
	v_mfma_f32_32x32x16_bf16 v[0:15], v[64:67], v[72:75], v[0:15]
	v_mfma_f32_32x32x16_bf16 v[16:31], v[64:67], v[76:79], v[16:31]
	v_mfma_f32_32x32x16_bf16 v[0:15], v[68:71], v[220:223], v[0:15]
	v_mfma_f32_32x32x16_bf16 v[16:31], v[68:71], v[224:227], v[16:31]
	global_load_dwordx4 v[156:159], v239, s[86:87]
	global_load_dwordx4 v[160:163], v240, s[86:87]
	global_load_dwordx4 v[164:167], v241, s[86:87]
	global_load_dwordx4 v[168:171], v242, s[86:87]
	global_load_dwordx4 v[172:175], v101, s[86:87] offset:768
	global_load_dwordx4 v[176:179], v150, s[86:87] offset:768
	global_load_dwordx4 v[180:183], v101, s[86:87] offset:832
	global_load_dwordx4 v[184:187], v150, s[86:87] offset:832
	ds_read_b64_tr_b16 v[72:73], v231
	ds_read_b64_tr_b16 v[74:75], v231 offset:512
	ds_read_b64_tr_b16 v[76:77], v231 offset:2048
	ds_read_b64_tr_b16 v[78:79], v231 offset:2560
	ds_read_b64_tr_b16 v[220:221], v231 offset:1024
	ds_read_b64_tr_b16 v[222:223], v231 offset:1536
	ds_read_b64_tr_b16 v[224:225], v231 offset:3072
	ds_read_b64_tr_b16 v[226:227], v231 offset:3584
	s_waitcnt vmcnt(8)
	ds_write_b128 v247, v[116:119]
	ds_write_b128 v247, v[120:123] offset:1024
	ds_write_b128 v247, v[124:127] offset:2048
	ds_write_b128 v247, v[128:131] offset:3072
	ds_read_b128 v[116:119], v248
	ds_read_b128 v[120:123], v249
	ds_read_b128 v[124:127], v250
	ds_read_b128 v[128:131], v251
	ds_write_b128 v112, v[132:135]
	ds_write_b128 v112, v[136:139] offset:1024
	ds_write_b128 v112, v[140:143] offset:2048
	ds_write_b128 v112, v[144:147] offset:3072
	v_exp_f32_e32 v188, v188
	v_exp_f32_e32 v189, v189
	v_exp_f32_e32 v190, v190
	v_exp_f32_e32 v191, v191
	v_exp_f32_e32 v192, v192
	v_exp_f32_e32 v193, v193
	s_waitcnt lgkmcnt(4)
	v_mfma_f32_32x32x16_bf16 v[32:47], v[116:119], v[48:51], v[32:47]
	v_exp_f32_e32 v194, v194
	v_exp_f32_e32 v195, v195
	v_mfma_f32_32x32x16_bf16 v[32:47], v[120:123], v[52:55], v[32:47]
	v_exp_f32_e32 v196, v196
	v_exp_f32_e32 v197, v197
	v_exp_f32_e32 v198, v198
	v_mfma_f32_32x32x16_bf16 v[32:47], v[124:127], v[56:59], v[32:47]
	v_exp_f32_e32 v199, v199
	v_exp_f32_e32 v200, v200
	v_mfma_f32_32x32x16_bf16 v[32:47], v[128:131], v[60:63], v[32:47]
	v_exp_f32_e32 v201, v201
	v_exp_f32_e32 v202, v202
	v_exp_f32_e32 v203, v203
	v_cvt_pk_bf16_f32 v64, v188, v189
	v_cvt_pk_bf16_f32 v65, v190, v191
	v_cvt_pk_bf16_f32 v66, v192, v193
	v_cvt_pk_bf16_f32 v67, v194, v195
	v_cvt_pk_bf16_f32 v68, v196, v197
	v_cvt_pk_bf16_f32 v69, v198, v199
	v_cvt_pk_bf16_f32 v70, v200, v201
	v_cvt_pk_bf16_f32 v71, v202, v203
	v_pk_add_f32 v[232:233], v[232:233], v[188:189]
	v_pk_add_f32 v[232:233], v[232:233], v[190:191]
	v_pk_add_f32 v[232:233], v[232:233], v[192:193]
	v_pk_add_f32 v[232:233], v[232:233], v[194:195]
	v_pk_add_f32 v[232:233], v[232:233], v[196:197]
	v_pk_add_f32 v[232:233], v[232:233], v[198:199]
	v_pk_add_f32 v[232:233], v[232:233], v[200:201]
	v_pk_add_f32 v[232:233], v[232:233], v[202:203]
	ds_read2_b32 v[188:189], v115 offset0:224 offset1:225
	ds_read2_b32 v[190:191], v115 offset0:226 offset1:227
	ds_read2_b32 v[192:193], v115 offset0:232 offset1:233
	ds_read2_b32 v[194:195], v115 offset0:234 offset1:235
	ds_read2_b32 v[196:197], v115 offset0:240 offset1:241
	ds_read2_b32 v[198:199], v115 offset0:242 offset1:243
	ds_read2_b32 v[200:201], v115 offset0:248 offset1:249
	ds_read2_b32 v[202:203], v115 offset0:250 offset1:251
	v_mfma_f32_32x32x16_bf16 v[0:15], v[64:67], v[72:75], v[0:15]
	v_mfma_f32_32x32x16_bf16 v[16:31], v[64:67], v[76:79], v[16:31]
	v_mfma_f32_32x32x16_bf16 v[0:15], v[68:71], v[220:223], v[0:15]
	v_mfma_f32_32x32x16_bf16 v[16:31], v[68:71], v[224:227], v[16:31]
	global_load_dwordx4 v[116:119], v243, s[88:89]
	global_load_dwordx4 v[120:123], v244, s[88:89]
	global_load_dwordx4 v[124:127], v245, s[88:89]
	global_load_dwordx4 v[128:131], v246, s[88:89]
	global_load_dwordx4 v[132:135], v148, s[88:89] offset:768
	global_load_dwordx4 v[136:139], v151, s[88:89] offset:768
	global_load_dwordx4 v[140:143], v148, s[88:89] offset:832
	global_load_dwordx4 v[144:147], v151, s[88:89] offset:832
	s_add_u32 s88, s88, 0x300000
	s_addc_u32 s89, s89, 0
	ds_read_b64_tr_b16 v[72:73], v231
	ds_read_b64_tr_b16 v[74:75], v231 offset:512
	ds_read_b64_tr_b16 v[76:77], v231 offset:2048
	ds_read_b64_tr_b16 v[78:79], v231 offset:2560
	ds_read_b64_tr_b16 v[220:221], v231 offset:1024
	ds_read_b64_tr_b16 v[222:223], v231 offset:1536
	ds_read_b64_tr_b16 v[224:225], v231 offset:3072
	ds_read_b64_tr_b16 v[226:227], v231 offset:3584
	s_waitcnt vmcnt(8)
	ds_write_b128 v247, v[156:159]
	ds_write_b128 v247, v[160:163] offset:1024
	ds_write_b128 v247, v[164:167] offset:2048
	ds_write_b128 v247, v[168:171] offset:3072
	ds_read_b128 v[156:159], v248
	ds_read_b128 v[160:163], v249
	ds_read_b128 v[164:167], v250
	ds_read_b128 v[168:171], v251
	ds_write_b128 v112, v[172:175]
	ds_write_b128 v112, v[176:179] offset:1024
	ds_write_b128 v112, v[180:183] offset:2048
	ds_write_b128 v112, v[184:187] offset:3072
	v_exp_f32_e32 v32, v32
	v_exp_f32_e32 v33, v33
	v_exp_f32_e32 v34, v34
	v_exp_f32_e32 v35, v35
	v_exp_f32_e32 v36, v36
	v_exp_f32_e32 v37, v37
	s_waitcnt lgkmcnt(4)
	v_mfma_f32_32x32x16_bf16 v[188:203], v[156:159], v[48:51], v[188:203]
	v_exp_f32_e32 v38, v38
	v_exp_f32_e32 v39, v39
	v_mfma_f32_32x32x16_bf16 v[188:203], v[160:163], v[52:55], v[188:203]
	v_exp_f32_e32 v40, v40
	v_exp_f32_e32 v41, v41
	v_exp_f32_e32 v42, v42
	v_mfma_f32_32x32x16_bf16 v[188:203], v[164:167], v[56:59], v[188:203]
	v_exp_f32_e32 v43, v43
	v_exp_f32_e32 v44, v44
	v_mfma_f32_32x32x16_bf16 v[188:203], v[168:171], v[60:63], v[188:203]
	v_exp_f32_e32 v45, v45
	v_exp_f32_e32 v46, v46
	v_exp_f32_e32 v47, v47
	v_cvt_pk_bf16_f32 v64, v32, v33
	v_cvt_pk_bf16_f32 v65, v34, v35
	v_cvt_pk_bf16_f32 v66, v36, v37
	v_cvt_pk_bf16_f32 v67, v38, v39
	v_cvt_pk_bf16_f32 v68, v40, v41
	v_cvt_pk_bf16_f32 v69, v42, v43
	v_cvt_pk_bf16_f32 v70, v44, v45
	v_cvt_pk_bf16_f32 v71, v46, v47
	v_pk_add_f32 v[232:233], v[232:233], v[32:33]
	v_pk_add_f32 v[232:233], v[232:233], v[34:35]
	v_pk_add_f32 v[232:233], v[232:233], v[36:37]
	v_pk_add_f32 v[232:233], v[232:233], v[38:39]
	v_pk_add_f32 v[232:233], v[232:233], v[40:41]
	v_pk_add_f32 v[232:233], v[232:233], v[42:43]
	v_pk_add_f32 v[232:233], v[232:233], v[44:45]
	v_pk_add_f32 v[232:233], v[232:233], v[46:47]
	v_mov_b32_e32 v115, v230
	ds_read2_b32 v[32:33], v115 offset0:0 offset1:1
	ds_read2_b32 v[34:35], v115 offset0:2 offset1:3
	ds_read2_b32 v[36:37], v115 offset0:8 offset1:9
	ds_read2_b32 v[38:39], v115 offset0:10 offset1:11
	ds_read2_b32 v[40:41], v115 offset0:16 offset1:17
	ds_read2_b32 v[42:43], v115 offset0:18 offset1:19
	ds_read2_b32 v[44:45], v115 offset0:24 offset1:25
	ds_read2_b32 v[46:47], v115 offset0:26 offset1:27
	v_mfma_f32_32x32x16_bf16 v[0:15], v[64:67], v[72:75], v[0:15]
	v_mfma_f32_32x32x16_bf16 v[16:31], v[64:67], v[76:79], v[16:31]
	v_mfma_f32_32x32x16_bf16 v[0:15], v[68:71], v[220:223], v[0:15]
	v_mfma_f32_32x32x16_bf16 v[16:31], v[68:71], v[224:227], v[16:31]
	global_load_dwordx4 v[156:159], v243, s[88:89]
	global_load_dwordx4 v[160:163], v244, s[88:89]
	global_load_dwordx4 v[164:167], v245, s[88:89]
	global_load_dwordx4 v[168:171], v246, s[88:89]
	global_load_dwordx4 v[172:175], v148, s[88:89] offset:768
	global_load_dwordx4 v[176:179], v151, s[88:89] offset:768
	global_load_dwordx4 v[180:183], v148, s[88:89] offset:832
	global_load_dwordx4 v[184:187], v151, s[88:89] offset:832
	s_add_u32 s88, s88, 0x300000
	s_addc_u32 s89, s89, 0
	ds_read_b64_tr_b16 v[72:73], v231
	ds_read_b64_tr_b16 v[74:75], v231 offset:512
	ds_read_b64_tr_b16 v[76:77], v231 offset:2048
	ds_read_b64_tr_b16 v[78:79], v231 offset:2560
	ds_read_b64_tr_b16 v[220:221], v231 offset:1024
	ds_read_b64_tr_b16 v[222:223], v231 offset:1536
	ds_read_b64_tr_b16 v[224:225], v231 offset:3072
	ds_read_b64_tr_b16 v[226:227], v231 offset:3584
	s_waitcnt vmcnt(8)
	ds_write_b128 v247, v[116:119]
	ds_write_b128 v247, v[120:123] offset:1024
	ds_write_b128 v247, v[124:127] offset:2048
	ds_write_b128 v247, v[128:131] offset:3072
	ds_read_b128 v[116:119], v248
	ds_read_b128 v[120:123], v249
	ds_read_b128 v[124:127], v250
	ds_read_b128 v[128:131], v251
	ds_write_b128 v112, v[132:135]
	ds_write_b128 v112, v[136:139] offset:1024
	ds_write_b128 v112, v[140:143] offset:2048
	ds_write_b128 v112, v[144:147] offset:3072
	v_exp_f32_e32 v188, v188
	v_exp_f32_e32 v189, v189
	v_exp_f32_e32 v190, v190
	v_exp_f32_e32 v191, v191
	v_exp_f32_e32 v192, v192
	v_exp_f32_e32 v193, v193
	s_waitcnt lgkmcnt(4)
	v_mfma_f32_32x32x16_bf16 v[32:47], v[116:119], v[48:51], v[32:47]
	v_exp_f32_e32 v194, v194
	v_exp_f32_e32 v195, v195
	v_mfma_f32_32x32x16_bf16 v[32:47], v[120:123], v[52:55], v[32:47]
	v_exp_f32_e32 v196, v196
	v_exp_f32_e32 v197, v197
	v_exp_f32_e32 v198, v198
	v_mfma_f32_32x32x16_bf16 v[32:47], v[124:127], v[56:59], v[32:47]
	v_exp_f32_e32 v199, v199
	v_exp_f32_e32 v200, v200
	v_mfma_f32_32x32x16_bf16 v[32:47], v[128:131], v[60:63], v[32:47]
	v_exp_f32_e32 v201, v201
	v_exp_f32_e32 v202, v202
	v_exp_f32_e32 v203, v203
	v_cvt_pk_bf16_f32 v64, v188, v189
	v_cvt_pk_bf16_f32 v65, v190, v191
	v_cvt_pk_bf16_f32 v66, v192, v193
	v_cvt_pk_bf16_f32 v67, v194, v195
	v_cvt_pk_bf16_f32 v68, v196, v197
	v_cvt_pk_bf16_f32 v69, v198, v199
	v_cvt_pk_bf16_f32 v70, v200, v201
	v_cvt_pk_bf16_f32 v71, v202, v203
	v_pk_add_f32 v[232:233], v[232:233], v[188:189]
	v_pk_add_f32 v[232:233], v[232:233], v[190:191]
	v_pk_add_f32 v[232:233], v[232:233], v[192:193]
	v_pk_add_f32 v[232:233], v[232:233], v[194:195]
	v_pk_add_f32 v[232:233], v[232:233], v[196:197]
	v_pk_add_f32 v[232:233], v[232:233], v[198:199]
	v_pk_add_f32 v[232:233], v[232:233], v[200:201]
	v_pk_add_f32 v[232:233], v[232:233], v[202:203]
	ds_read2_b32 v[188:189], v115 offset0:32 offset1:33
	ds_read2_b32 v[190:191], v115 offset0:34 offset1:35
	ds_read2_b32 v[192:193], v115 offset0:40 offset1:41
	ds_read2_b32 v[194:195], v115 offset0:42 offset1:43
	ds_read2_b32 v[196:197], v115 offset0:48 offset1:49
	ds_read2_b32 v[198:199], v115 offset0:50 offset1:51
	ds_read2_b32 v[200:201], v115 offset0:56 offset1:57
	ds_read2_b32 v[202:203], v115 offset0:58 offset1:59
	v_mfma_f32_32x32x16_bf16 v[0:15], v[64:67], v[72:75], v[0:15]
	v_mfma_f32_32x32x16_bf16 v[16:31], v[64:67], v[76:79], v[16:31]
	v_mfma_f32_32x32x16_bf16 v[0:15], v[68:71], v[220:223], v[0:15]
	v_mfma_f32_32x32x16_bf16 v[16:31], v[68:71], v[224:227], v[16:31]
	global_load_dwordx4 v[116:119], v243, s[88:89]
	global_load_dwordx4 v[120:123], v244, s[88:89]
	global_load_dwordx4 v[124:127], v245, s[88:89]
	global_load_dwordx4 v[128:131], v246, s[88:89]
	global_load_dwordx4 v[132:135], v148, s[88:89] offset:768
	global_load_dwordx4 v[136:139], v151, s[88:89] offset:768
	global_load_dwordx4 v[140:143], v148, s[88:89] offset:832
	global_load_dwordx4 v[144:147], v151, s[88:89] offset:832
	s_add_u32 s88, s88, 0x300000
	s_addc_u32 s89, s89, 0
	ds_read_b64_tr_b16 v[72:73], v231
	ds_read_b64_tr_b16 v[74:75], v231 offset:512
	ds_read_b64_tr_b16 v[76:77], v231 offset:2048
	ds_read_b64_tr_b16 v[78:79], v231 offset:2560
	ds_read_b64_tr_b16 v[220:221], v231 offset:1024
	ds_read_b64_tr_b16 v[222:223], v231 offset:1536
	ds_read_b64_tr_b16 v[224:225], v231 offset:3072
	ds_read_b64_tr_b16 v[226:227], v231 offset:3584
	s_waitcnt vmcnt(8)
	ds_write_b128 v247, v[156:159]
	ds_write_b128 v247, v[160:163] offset:1024
	ds_write_b128 v247, v[164:167] offset:2048
	ds_write_b128 v247, v[168:171] offset:3072
	ds_read_b128 v[156:159], v248
	ds_read_b128 v[160:163], v249
	ds_read_b128 v[164:167], v250
	ds_read_b128 v[168:171], v251
	ds_write_b128 v112, v[172:175]
	ds_write_b128 v112, v[176:179] offset:1024
	ds_write_b128 v112, v[180:183] offset:2048
	ds_write_b128 v112, v[184:187] offset:3072
	v_exp_f32_e32 v32, v32
	v_exp_f32_e32 v33, v33
	v_exp_f32_e32 v34, v34
	v_exp_f32_e32 v35, v35
	v_exp_f32_e32 v36, v36
	v_exp_f32_e32 v37, v37
	s_waitcnt lgkmcnt(4)
	v_mfma_f32_32x32x16_bf16 v[188:203], v[156:159], v[48:51], v[188:203]
	v_exp_f32_e32 v38, v38
	v_exp_f32_e32 v39, v39
	v_mfma_f32_32x32x16_bf16 v[188:203], v[160:163], v[52:55], v[188:203]
	v_exp_f32_e32 v40, v40
	v_exp_f32_e32 v41, v41
	v_exp_f32_e32 v42, v42
	v_mfma_f32_32x32x16_bf16 v[188:203], v[164:167], v[56:59], v[188:203]
	v_exp_f32_e32 v43, v43
	v_exp_f32_e32 v44, v44
	v_mfma_f32_32x32x16_bf16 v[188:203], v[168:171], v[60:63], v[188:203]
	v_exp_f32_e32 v45, v45
	v_exp_f32_e32 v46, v46
	v_exp_f32_e32 v47, v47
	v_cvt_pk_bf16_f32 v64, v32, v33
	v_cvt_pk_bf16_f32 v65, v34, v35
	v_cvt_pk_bf16_f32 v66, v36, v37
	v_cvt_pk_bf16_f32 v67, v38, v39
	v_cvt_pk_bf16_f32 v68, v40, v41
	v_cvt_pk_bf16_f32 v69, v42, v43
	v_cvt_pk_bf16_f32 v70, v44, v45
	v_cvt_pk_bf16_f32 v71, v46, v47
	v_pk_add_f32 v[232:233], v[232:233], v[32:33]
	v_pk_add_f32 v[232:233], v[232:233], v[34:35]
	v_pk_add_f32 v[232:233], v[232:233], v[36:37]
	v_pk_add_f32 v[232:233], v[232:233], v[38:39]
	v_pk_add_f32 v[232:233], v[232:233], v[40:41]
	v_pk_add_f32 v[232:233], v[232:233], v[42:43]
	v_pk_add_f32 v[232:233], v[232:233], v[44:45]
	v_pk_add_f32 v[232:233], v[232:233], v[46:47]
	ds_read2_b32 v[32:33], v115 offset0:64 offset1:65
	ds_read2_b32 v[34:35], v115 offset0:66 offset1:67
	ds_read2_b32 v[36:37], v115 offset0:72 offset1:73
	ds_read2_b32 v[38:39], v115 offset0:74 offset1:75
	ds_read2_b32 v[40:41], v115 offset0:80 offset1:81
	ds_read2_b32 v[42:43], v115 offset0:82 offset1:83
	ds_read2_b32 v[44:45], v115 offset0:88 offset1:89
	ds_read2_b32 v[46:47], v115 offset0:90 offset1:91
	v_mfma_f32_32x32x16_bf16 v[0:15], v[64:67], v[72:75], v[0:15]
	v_mfma_f32_32x32x16_bf16 v[16:31], v[64:67], v[76:79], v[16:31]
	v_mfma_f32_32x32x16_bf16 v[0:15], v[68:71], v[220:223], v[0:15]
	v_mfma_f32_32x32x16_bf16 v[16:31], v[68:71], v[224:227], v[16:31]
	global_load_dwordx4 v[156:159], v243, s[88:89]
	global_load_dwordx4 v[160:163], v244, s[88:89]
	global_load_dwordx4 v[164:167], v245, s[88:89]
	global_load_dwordx4 v[168:171], v246, s[88:89]
	global_load_dwordx4 v[172:175], v148, s[88:89] offset:768
	global_load_dwordx4 v[176:179], v151, s[88:89] offset:768
	global_load_dwordx4 v[180:183], v148, s[88:89] offset:832
	global_load_dwordx4 v[184:187], v151, s[88:89] offset:832
	s_add_u32 s88, s88, 0x300000
	s_addc_u32 s89, s89, 0
	ds_read_b64_tr_b16 v[72:73], v231
	ds_read_b64_tr_b16 v[74:75], v231 offset:512
	ds_read_b64_tr_b16 v[76:77], v231 offset:2048
	ds_read_b64_tr_b16 v[78:79], v231 offset:2560
	ds_read_b64_tr_b16 v[220:221], v231 offset:1024
	ds_read_b64_tr_b16 v[222:223], v231 offset:1536
	ds_read_b64_tr_b16 v[224:225], v231 offset:3072
	ds_read_b64_tr_b16 v[226:227], v231 offset:3584
	s_waitcnt vmcnt(8)
	ds_write_b128 v247, v[116:119]
	ds_write_b128 v247, v[120:123] offset:1024
	ds_write_b128 v247, v[124:127] offset:2048
	ds_write_b128 v247, v[128:131] offset:3072
	ds_read_b128 v[116:119], v248
	ds_read_b128 v[120:123], v249
	ds_read_b128 v[124:127], v250
	ds_read_b128 v[128:131], v251
	ds_write_b128 v112, v[132:135]
	ds_write_b128 v112, v[136:139] offset:1024
	ds_write_b128 v112, v[140:143] offset:2048
	ds_write_b128 v112, v[144:147] offset:3072
	v_exp_f32_e32 v188, v188
	v_exp_f32_e32 v189, v189
	v_exp_f32_e32 v190, v190
	v_exp_f32_e32 v191, v191
	v_exp_f32_e32 v192, v192
	v_exp_f32_e32 v193, v193
	s_waitcnt lgkmcnt(4)
	v_mfma_f32_32x32x16_bf16 v[32:47], v[116:119], v[48:51], v[32:47]
	v_exp_f32_e32 v194, v194
	v_exp_f32_e32 v195, v195
	v_mfma_f32_32x32x16_bf16 v[32:47], v[120:123], v[52:55], v[32:47]
	v_exp_f32_e32 v196, v196
	v_exp_f32_e32 v197, v197
	v_exp_f32_e32 v198, v198
	v_mfma_f32_32x32x16_bf16 v[32:47], v[124:127], v[56:59], v[32:47]
	v_exp_f32_e32 v199, v199
	v_exp_f32_e32 v200, v200
	v_mfma_f32_32x32x16_bf16 v[32:47], v[128:131], v[60:63], v[32:47]
	v_exp_f32_e32 v201, v201
	v_exp_f32_e32 v202, v202
	v_exp_f32_e32 v203, v203
	v_cvt_pk_bf16_f32 v64, v188, v189
	v_cvt_pk_bf16_f32 v65, v190, v191
	v_cvt_pk_bf16_f32 v66, v192, v193
	v_cvt_pk_bf16_f32 v67, v194, v195
	v_cvt_pk_bf16_f32 v68, v196, v197
	v_cvt_pk_bf16_f32 v69, v198, v199
	v_cvt_pk_bf16_f32 v70, v200, v201
	v_cvt_pk_bf16_f32 v71, v202, v203
	v_pk_add_f32 v[232:233], v[232:233], v[188:189]
	v_pk_add_f32 v[232:233], v[232:233], v[190:191]
	v_pk_add_f32 v[232:233], v[232:233], v[192:193]
	v_pk_add_f32 v[232:233], v[232:233], v[194:195]
	v_pk_add_f32 v[232:233], v[232:233], v[196:197]
	v_pk_add_f32 v[232:233], v[232:233], v[198:199]
	v_pk_add_f32 v[232:233], v[232:233], v[200:201]
	v_pk_add_f32 v[232:233], v[232:233], v[202:203]
	ds_read2_b32 v[188:189], v115 offset0:96 offset1:97
	ds_read2_b32 v[190:191], v115 offset0:98 offset1:99
	ds_read2_b32 v[192:193], v115 offset0:104 offset1:105
	ds_read2_b32 v[194:195], v115 offset0:106 offset1:107
	ds_read2_b32 v[196:197], v115 offset0:112 offset1:113
	ds_read2_b32 v[198:199], v115 offset0:114 offset1:115
	ds_read2_b32 v[200:201], v115 offset0:120 offset1:121
	ds_read2_b32 v[202:203], v115 offset0:122 offset1:123
	v_mfma_f32_32x32x16_bf16 v[0:15], v[64:67], v[72:75], v[0:15]
	v_mfma_f32_32x32x16_bf16 v[16:31], v[64:67], v[76:79], v[16:31]
	v_mfma_f32_32x32x16_bf16 v[0:15], v[68:71], v[220:223], v[0:15]
	v_mfma_f32_32x32x16_bf16 v[16:31], v[68:71], v[224:227], v[16:31]
	global_load_dwordx4 v[116:119], v243, s[88:89]
	global_load_dwordx4 v[120:123], v244, s[88:89]
	global_load_dwordx4 v[124:127], v245, s[88:89]
	global_load_dwordx4 v[128:131], v246, s[88:89]
	global_load_dwordx4 v[132:135], v148, s[88:89] offset:768
	global_load_dwordx4 v[136:139], v151, s[88:89] offset:768
	global_load_dwordx4 v[140:143], v148, s[88:89] offset:832
	global_load_dwordx4 v[144:147], v151, s[88:89] offset:832
	ds_read_b64_tr_b16 v[72:73], v231
	ds_read_b64_tr_b16 v[74:75], v231 offset:512
	ds_read_b64_tr_b16 v[76:77], v231 offset:2048
	ds_read_b64_tr_b16 v[78:79], v231 offset:2560
	ds_read_b64_tr_b16 v[220:221], v231 offset:1024
	ds_read_b64_tr_b16 v[222:223], v231 offset:1536
	ds_read_b64_tr_b16 v[224:225], v231 offset:3072
	ds_read_b64_tr_b16 v[226:227], v231 offset:3584
	s_waitcnt vmcnt(8)
	ds_write_b128 v247, v[156:159]
	ds_write_b128 v247, v[160:163] offset:1024
	ds_write_b128 v247, v[164:167] offset:2048
	ds_write_b128 v247, v[168:171] offset:3072
	ds_read_b128 v[156:159], v248
	ds_read_b128 v[160:163], v249
	ds_read_b128 v[164:167], v250
	ds_read_b128 v[168:171], v251
	ds_write_b128 v112, v[172:175]
	ds_write_b128 v112, v[176:179] offset:1024
	ds_write_b128 v112, v[180:183] offset:2048
	ds_write_b128 v112, v[184:187] offset:3072
	v_exp_f32_e32 v32, v32
	v_exp_f32_e32 v33, v33
	v_exp_f32_e32 v34, v34
	v_exp_f32_e32 v35, v35
	v_exp_f32_e32 v36, v36
	v_exp_f32_e32 v37, v37
	s_waitcnt lgkmcnt(4)
	v_mfma_f32_32x32x16_bf16 v[188:203], v[156:159], v[48:51], v[188:203]
	v_exp_f32_e32 v38, v38
	v_exp_f32_e32 v39, v39
	v_mfma_f32_32x32x16_bf16 v[188:203], v[160:163], v[52:55], v[188:203]
	v_exp_f32_e32 v40, v40
	v_exp_f32_e32 v41, v41
	v_exp_f32_e32 v42, v42
	v_mfma_f32_32x32x16_bf16 v[188:203], v[164:167], v[56:59], v[188:203]
	v_exp_f32_e32 v43, v43
	v_exp_f32_e32 v44, v44
	v_mfma_f32_32x32x16_bf16 v[188:203], v[168:171], v[60:63], v[188:203]
	v_exp_f32_e32 v45, v45
	v_exp_f32_e32 v46, v46
	v_exp_f32_e32 v47, v47
	v_cvt_pk_bf16_f32 v64, v32, v33
	v_cvt_pk_bf16_f32 v65, v34, v35
	v_cvt_pk_bf16_f32 v66, v36, v37
	v_cvt_pk_bf16_f32 v67, v38, v39
	v_cvt_pk_bf16_f32 v68, v40, v41
	v_cvt_pk_bf16_f32 v69, v42, v43
	v_cvt_pk_bf16_f32 v70, v44, v45
	v_cvt_pk_bf16_f32 v71, v46, v47
	v_pk_add_f32 v[232:233], v[232:233], v[32:33]
	v_pk_add_f32 v[232:233], v[232:233], v[34:35]
	v_pk_add_f32 v[232:233], v[232:233], v[36:37]
	v_pk_add_f32 v[232:233], v[232:233], v[38:39]
	v_pk_add_f32 v[232:233], v[232:233], v[40:41]
	v_pk_add_f32 v[232:233], v[232:233], v[42:43]
	v_pk_add_f32 v[232:233], v[232:233], v[44:45]
	v_pk_add_f32 v[232:233], v[232:233], v[46:47]
	ds_read2_b32 v[32:33], v115 offset0:128 offset1:129
	ds_read2_b32 v[34:35], v115 offset0:130 offset1:131
	ds_read2_b32 v[36:37], v115 offset0:136 offset1:137
	ds_read2_b32 v[38:39], v115 offset0:138 offset1:139
	ds_read2_b32 v[40:41], v115 offset0:144 offset1:145
	ds_read2_b32 v[42:43], v115 offset0:146 offset1:147
	ds_read2_b32 v[44:45], v115 offset0:152 offset1:153
	ds_read2_b32 v[46:47], v115 offset0:154 offset1:155
	v_mfma_f32_32x32x16_bf16 v[0:15], v[64:67], v[72:75], v[0:15]
	v_mfma_f32_32x32x16_bf16 v[16:31], v[64:67], v[76:79], v[16:31]
	v_mfma_f32_32x32x16_bf16 v[0:15], v[68:71], v[220:223], v[0:15]
	v_mfma_f32_32x32x16_bf16 v[16:31], v[68:71], v[224:227], v[16:31]
	ds_read_b64_tr_b16 v[72:73], v231
	ds_read_b64_tr_b16 v[74:75], v231 offset:512
	ds_read_b64_tr_b16 v[76:77], v231 offset:2048
	ds_read_b64_tr_b16 v[78:79], v231 offset:2560
	ds_read_b64_tr_b16 v[220:221], v231 offset:1024
	ds_read_b64_tr_b16 v[222:223], v231 offset:1536
	ds_read_b64_tr_b16 v[224:225], v231 offset:3072
	ds_read_b64_tr_b16 v[226:227], v231 offset:3584
	s_waitcnt vmcnt(0)
; __device__ __forceinline__ int crow(int r, int hi) { return (r & 3) + 8 * (r >> 2) + 4 * hi; }
; __device__ __forceinline__ void dil_unit(LAS unsigned char* lds, bf16_t* proj, int seq, int hd, int T0, int rho) {
;     ...
;     l += __shfl_xor(l, 32);
; #pragma unroll
;     for (int rr = 0; rr < 16; ++rr) {
;         const int j = crow(rr, hi);
	ds_write_b128 v247, v[116:119]
	ds_write_b128 v247, v[120:123] offset:1024
	ds_write_b128 v247, v[124:127] offset:2048
	ds_write_b128 v247, v[128:131] offset:3072
	ds_read_b128 v[116:119], v248
	ds_read_b128 v[120:123], v249
	ds_read_b128 v[124:127], v250
	ds_read_b128 v[128:131], v251
	ds_write_b128 v112, v[132:135]
	ds_write_b128 v112, v[136:139] offset:1024
	ds_write_b128 v112, v[140:143] offset:2048
	ds_write_b128 v112, v[144:147] offset:3072
	v_exp_f32_e32 v188, v188
	v_exp_f32_e32 v189, v189
	v_exp_f32_e32 v190, v190
	v_exp_f32_e32 v191, v191
	v_exp_f32_e32 v192, v192
	v_exp_f32_e32 v193, v193
	s_waitcnt lgkmcnt(4)
	v_mfma_f32_32x32x16_bf16 v[32:47], v[116:119], v[48:51], v[32:47]
	v_exp_f32_e32 v194, v194
	v_exp_f32_e32 v195, v195
	v_mfma_f32_32x32x16_bf16 v[32:47], v[120:123], v[52:55], v[32:47]
	v_exp_f32_e32 v196, v196
	v_exp_f32_e32 v197, v197
	v_exp_f32_e32 v198, v198
	v_mfma_f32_32x32x16_bf16 v[32:47], v[124:127], v[56:59], v[32:47]
	v_exp_f32_e32 v199, v199
	v_exp_f32_e32 v200, v200
	v_mfma_f32_32x32x16_bf16 v[32:47], v[128:131], v[60:63], v[32:47]
	v_exp_f32_e32 v201, v201
	v_exp_f32_e32 v202, v202
	v_exp_f32_e32 v203, v203
	v_cvt_pk_bf16_f32 v64, v188, v189
	v_cvt_pk_bf16_f32 v65, v190, v191
	v_cvt_pk_bf16_f32 v66, v192, v193
	v_cvt_pk_bf16_f32 v67, v194, v195
	v_cvt_pk_bf16_f32 v68, v196, v197
	v_cvt_pk_bf16_f32 v69, v198, v199
	v_cvt_pk_bf16_f32 v70, v200, v201
	v_cvt_pk_bf16_f32 v71, v202, v203
	v_pk_add_f32 v[232:233], v[232:233], v[188:189]
	v_pk_add_f32 v[232:233], v[232:233], v[190:191]
	v_pk_add_f32 v[232:233], v[232:233], v[192:193]
	v_pk_add_f32 v[232:233], v[232:233], v[194:195]
	v_pk_add_f32 v[232:233], v[232:233], v[196:197]
	v_pk_add_f32 v[232:233], v[232:233], v[198:199]
	v_pk_add_f32 v[232:233], v[232:233], v[200:201]
	v_pk_add_f32 v[232:233], v[232:233], v[202:203]
	v_mfma_f32_32x32x16_bf16 v[0:15], v[64:67], v[72:75], v[0:15]
	v_mfma_f32_32x32x16_bf16 v[16:31], v[64:67], v[76:79], v[16:31]
	v_mfma_f32_32x32x16_bf16 v[0:15], v[68:71], v[220:223], v[0:15]
	v_mfma_f32_32x32x16_bf16 v[16:31], v[68:71], v[224:227], v[16:31]
	ds_read_b64_tr_b16 v[72:73], v231
	ds_read_b64_tr_b16 v[74:75], v231 offset:512
	ds_read_b64_tr_b16 v[76:77], v231 offset:2048
	ds_read_b64_tr_b16 v[78:79], v231 offset:2560
	ds_read_b64_tr_b16 v[220:221], v231 offset:1024
	ds_read_b64_tr_b16 v[222:223], v231 offset:1536
	ds_read_b64_tr_b16 v[224:225], v231 offset:3072
	ds_read_b64_tr_b16 v[226:227], v231 offset:3584
	s_waitcnt lgkmcnt(0)
	v_exp_f32_e32 v32, v32
	v_exp_f32_e32 v33, v33
	v_exp_f32_e32 v34, v34
	v_exp_f32_e32 v35, v35
	v_exp_f32_e32 v36, v36
	v_exp_f32_e32 v37, v37
	v_exp_f32_e32 v38, v38
	v_exp_f32_e32 v39, v39
	v_exp_f32_e32 v40, v40
	v_exp_f32_e32 v41, v41
	v_exp_f32_e32 v42, v42
	v_exp_f32_e32 v43, v43
	v_exp_f32_e32 v44, v44
	v_exp_f32_e32 v45, v45
	v_exp_f32_e32 v46, v46
	v_exp_f32_e32 v47, v47
	v_cvt_pk_bf16_f32 v64, v32, v33
	v_cvt_pk_bf16_f32 v65, v34, v35
	v_cvt_pk_bf16_f32 v66, v36, v37
	v_cvt_pk_bf16_f32 v67, v38, v39
	v_cvt_pk_bf16_f32 v68, v40, v41
	v_cvt_pk_bf16_f32 v69, v42, v43
	v_cvt_pk_bf16_f32 v70, v44, v45
	v_cvt_pk_bf16_f32 v71, v46, v47
	v_pk_add_f32 v[232:233], v[232:233], v[32:33]
	v_pk_add_f32 v[232:233], v[232:233], v[34:35]
	v_pk_add_f32 v[232:233], v[232:233], v[36:37]
	v_pk_add_f32 v[232:233], v[232:233], v[38:39]
	v_pk_add_f32 v[232:233], v[232:233], v[40:41]
	v_pk_add_f32 v[232:233], v[232:233], v[42:43]
	v_pk_add_f32 v[232:233], v[232:233], v[44:45]
	v_pk_add_f32 v[232:233], v[232:233], v[46:47]
	v_mfma_f32_32x32x16_bf16 v[0:15], v[64:67], v[72:75], v[0:15]
	v_mfma_f32_32x32x16_bf16 v[16:31], v[64:67], v[76:79], v[16:31]
	v_mfma_f32_32x32x16_bf16 v[0:15], v[68:71], v[220:223], v[0:15]
	v_mfma_f32_32x32x16_bf16 v[16:31], v[68:71], v[224:227], v[16:31]
	v_add_f32_e32 v113, v232, v233
	v_or_b32_e32 v114, 1, v107
	v_or_b32_e32 v97, 2, v107
	v_or_b32_e32 v96, 3, v107
	v_or_b32_e32 v95, 8, v107
	v_or_b32_e32 v94, 9, v107
	v_or_b32_e32 v93, 10, v107
	v_or_b32_e32 v92, 11, v107
	v_or_b32_e32 v91, 16, v107
	v_or_b32_e32 v90, 17, v107
	v_or_b32_e32 v89, 18, v107
	v_or_b32_e32 v88, 19, v107
	v_or_b32_e32 v87, 24, v107
	v_or_b32_e32 v86, 25, v107
	v_or_b32_e32 v85, 26, v107
	v_or_b32_e32 v84, 27, v107
	s_nop 11
	s_branch .LBB0_1265
; __device__ __forceinline__ void dil_unit(LAS unsigned char* lds, bf16_t* proj, int seq, int hd, int T0, int rho) {
;     ...
;     f32x16 o0 = {}, o1 = {}; float l = 0.f;
;     const bool bound = (T0 < 1024) || (T0 >= 15360);
.LBB0_1270:
	s_movk_i32 s100, 0x1800
	s_add_i32 s101, s8, 0x15c00
	s_lshl_b32 s90, s54, 1
	s_add_u32 s82, s52, s90
	s_addc_u32 s83, s53, 0
	s_add_u32 s82, s82, 0x1200
	s_addc_u32 s83, s83, 0
	s_sub_i32 s90, s67, 64
	s_mul_i32 s90, s90, 0x1800
	s_add_u32 s84, s82, s90
	s_addc_u32 s85, s83, 0
	s_sub_i32 s90, s67, 256
	s_mul_i32 s90, s90, 0x1800
	s_add_u32 s86, s82, s90
	s_addc_u32 s87, s83, 0
	s_sub_i32 s90, s67, 1024
	s_mul_i32 s90, s90, 0x1800
	s_add_u32 s88, s82, s90
	s_addc_u32 s89, s83, 0
	v_lshlrev_b32_e32 v153, 1, v98
	v_mad_u32_u24 v80, v105, s100, v82
	v_mad_u32_u24 v100, v110, s100, v153
	v_add_u32_e32 v149, 0x18000, v100
	v_lshlrev_b32_e32 v83, 2, v105
	v_mad_u32_u24 v83, v83, s100, v82
	v_lshlrev_b32_e32 v101, 2, v110
	v_mad_u32_u24 v101, v101, s100, v153
	v_add_u32_e32 v150, 0x60000, v101
	v_lshlrev_b32_e32 v99, 4, v105
	v_mad_u32_u24 v99, v99, s100, v82
	v_lshlrev_b32_e32 v148, 4, v110
	v_mad_u32_u24 v148, v148, s100, v153
	v_add_u32_e32 v151, 0x180000, v148
	v_lshrrev_b32_e32 v249, 3, v103
	v_and_b32_e32 v250, 7, v103
	v_lshlrev_b32_e32 v250, 4, v250
	v_add_u32_e32 v235, 0, v249
	v_add_u32_e32 v236, 8, v249
	v_add_u32_e32 v237, 16, v249
	v_add_u32_e32 v238, 24, v249
	v_add_u32_e32 v239, 0, v249
	v_lshlrev_b32_e32 v239, 2, v239
	v_add_u32_e32 v240, 8, v249
	v_lshlrev_b32_e32 v240, 2, v240
	v_add_u32_e32 v241, 16, v249
	v_lshlrev_b32_e32 v241, 2, v241
	v_add_u32_e32 v242, 24, v249
	v_lshlrev_b32_e32 v242, 2, v242
	v_add_u32_e32 v243, 0, v249
	v_lshlrev_b32_e32 v243, 4, v243
	v_add_u32_e32 v244, 8, v249
	v_lshlrev_b32_e32 v244, 4, v244
	v_add_u32_e32 v245, 16, v249
	v_lshlrev_b32_e32 v245, 4, v245
	v_add_u32_e32 v246, 24, v249
	v_lshlrev_b32_e32 v246, 4, v246
	v_mov_b32_e32 v252, v250
	v_mov_b32_e32 v100, v110
	v_add_u32_e32 v149, 16, v100
	v_lshlrev_b32_e32 v101, 2, v110
	v_add_u32_e32 v150, 64, v101
	v_lshlrev_b32_e32 v148, 4, v110
	v_add_u32_e32 v151, 256, v148
	s_mov_b32 s98, 0x4000
	s_mov_b32 s99, 0x3fff
	v_and_b32_e32 v247, 7, v249
	v_lshlrev_b32_e32 v247, 4, v247
	v_xor_b32_e32 v247, v247, v112
	v_and_b32_e32 v153, 7, v105
	v_or_b32_e32 v248, 0, v106
	v_xor_b32_e32 v248, v248, v153
	v_lshlrev_b32_e32 v248, 4, v248
	v_lshl_add_u32 v248, v105, 7, v248
	v_add_u32_e32 v248, s69, v248
	v_or_b32_e32 v249, 2, v106
	v_xor_b32_e32 v249, v249, v153
	v_lshlrev_b32_e32 v249, 4, v249
	v_lshl_add_u32 v249, v105, 7, v249
	v_add_u32_e32 v249, s69, v249
	v_or_b32_e32 v250, 4, v106
	v_xor_b32_e32 v250, v250, v153
	v_lshlrev_b32_e32 v250, 4, v250
	v_lshl_add_u32 v250, v105, 7, v250
	v_add_u32_e32 v250, s69, v250
	v_or_b32_e32 v251, 6, v106
	v_xor_b32_e32 v251, v251, v153
	v_lshlrev_b32_e32 v251, 4, v251
	v_lshl_add_u32 v251, v105, 7, v251
	v_add_u32_e32 v251, s69, v251
	v_lshlrev_b32_e32 v153, 1, v98
	v_mul_u32_u24_e32 v228, 17, v105
	v_sub_u32_e32 v228, v107, v228
	s_mul_i32 s90, s54, 153
	s_lshr_b32 s90, s90, 1
	s_add_i32 s90, s90, 34876
	v_lshl_add_u32 v228, v228, 2, s90
	v_lshlrev_b32_e32 v229, 2, v105
	v_sub_u32_e32 v229, v107, v229
	s_add_i32 s90, s101, 5104
	v_lshl_add_u32 v229, v229, 2, s90
	v_sub_u32_e32 v230, v107, v105
	s_add_i32 s90, s101, 6364
	v_lshl_add_u32 v230, v230, 2, s90
	v_add_u32_e32 v231, v109, v108
	v_mov_b64_e32 v[232:233], 0
	v_mov_b64_e32 v[0:1], 0
	v_mov_b64_e32 v[2:3], 0
	v_mov_b64_e32 v[4:5], 0
	v_mov_b64_e32 v[6:7], 0
	v_mov_b64_e32 v[8:9], 0
	v_mov_b64_e32 v[10:11], 0
	v_mov_b64_e32 v[12:13], 0
	v_mov_b64_e32 v[14:15], 0
	v_mov_b64_e32 v[16:17], 0
	v_mov_b64_e32 v[18:19], 0
	v_mov_b64_e32 v[20:21], 0
	v_mov_b64_e32 v[22:23], 0
	v_mov_b64_e32 v[24:25], 0
	v_mov_b64_e32 v[26:27], 0
	v_mov_b64_e32 v[28:29], 0
	v_mov_b64_e32 v[30:31], 0
	s_add_i32 s90, s67, -64
	v_add_u32_e32 v80, s90, v235
	v_add_u32_e32 v83, s90, v236
	v_add_u32_e32 v99, s90, v237
	v_add_u32_e32 v253, s90, v238
	v_add_u32_e32 v254, s90, v100
	v_add_u32_e32 v255, s90, v149
	v_med3_i32 v80, v80, 0, s99
	v_med3_i32 v83, v83, 0, s99
	v_med3_i32 v99, v99, 0, s99
	v_med3_i32 v253, v253, 0, s99
	v_med3_i32 v254, v254, 0, s99
	v_med3_i32 v255, v255, 0, s99
	v_mad_u32_u24 v80, v80, s100, v252
	v_mad_u32_u24 v83, v83, s100, v252
	v_mad_u32_u24 v99, v99, s100, v252
	v_mad_u32_u24 v253, v253, s100, v252
	v_mad_u32_u24 v254, v254, s100, v153
	v_mad_u32_u24 v255, v255, s100, v153
	global_load_dwordx4 v[116:119], v80, s[82:83]
	global_load_dwordx4 v[120:123], v83, s[82:83]
	global_load_dwordx4 v[124:127], v99, s[82:83]
	global_load_dwordx4 v[128:131], v253, s[82:83]
	global_load_dwordx4 v[132:135], v254, s[82:83] offset:768
	global_load_dwordx4 v[136:139], v255, s[82:83] offset:768
	global_load_dwordx4 v[140:143], v254, s[82:83] offset:832
	global_load_dwordx4 v[144:147], v255, s[82:83] offset:832
	s_add_i32 s90, s67, -32
	v_add_u32_e32 v80, s90, v235
	v_add_u32_e32 v83, s90, v236
	v_add_u32_e32 v99, s90, v237
	v_add_u32_e32 v253, s90, v238
	v_add_u32_e32 v254, s90, v100
	v_add_u32_e32 v255, s90, v149
	v_med3_i32 v80, v80, 0, s99
	v_med3_i32 v83, v83, 0, s99
	v_med3_i32 v99, v99, 0, s99
	v_med3_i32 v253, v253, 0, s99
	v_med3_i32 v254, v254, 0, s99
	v_med3_i32 v255, v255, 0, s99
	v_mad_u32_u24 v80, v80, s100, v252
	v_mad_u32_u24 v83, v83, s100, v252
	v_mad_u32_u24 v99, v99, s100, v252
	v_mad_u32_u24 v253, v253, s100, v252
	v_mad_u32_u24 v254, v254, s100, v153
	v_mad_u32_u24 v255, v255, s100, v153
	global_load_dwordx4 v[156:159], v80, s[82:83]
	global_load_dwordx4 v[160:163], v83, s[82:83]
	global_load_dwordx4 v[164:167], v99, s[82:83]
	global_load_dwordx4 v[168:171], v253, s[82:83]
	global_load_dwordx4 v[172:175], v254, s[82:83] offset:768
	global_load_dwordx4 v[176:179], v255, s[82:83] offset:768
	global_load_dwordx4 v[180:183], v254, s[82:83] offset:832
	global_load_dwordx4 v[184:187], v255, s[82:83] offset:832
	v_mov_b32_e32 v115, v228
	ds_read2_b32 v[32:33], v115 offset0:0 offset1:1
	ds_read2_b32 v[34:35], v115 offset0:2 offset1:3
	ds_read2_b32 v[36:37], v115 offset0:8 offset1:9
	ds_read2_b32 v[38:39], v115 offset0:10 offset1:11
	ds_read2_b32 v[40:41], v115 offset0:17 offset1:18
	ds_read2_b32 v[42:43], v115 offset0:19 offset1:20
	ds_read2_b32 v[44:45], v115 offset0:25 offset1:26
	ds_read2_b32 v[46:47], v115 offset0:27 offset1:28
	s_waitcnt vmcnt(8)
	ds_write_b128 v247, v[116:119]
	ds_write_b128 v247, v[120:123] offset:1024
	ds_write_b128 v247, v[124:127] offset:2048
	ds_write_b128 v247, v[128:131] offset:3072
	ds_read_b128 v[116:119], v248
	ds_read_b128 v[120:123], v249
	ds_read_b128 v[124:127], v250
	ds_read_b128 v[128:131], v251
	ds_write_b128 v112, v[132:135]
	ds_write_b128 v112, v[136:139] offset:1024
	ds_write_b128 v112, v[140:143] offset:2048
	ds_write_b128 v112, v[144:147] offset:3072
	s_waitcnt lgkmcnt(4)
	v_mfma_f32_32x32x16_bf16 v[32:47], v[116:119], v[48:51], v[32:47]
	v_mfma_f32_32x32x16_bf16 v[32:47], v[120:123], v[52:55], v[32:47]
	v_mfma_f32_32x32x16_bf16 v[32:47], v[124:127], v[56:59], v[32:47]
	v_mfma_f32_32x32x16_bf16 v[32:47], v[128:131], v[60:63], v[32:47]
	ds_read2_b32 v[188:189], v115 offset0:34 offset1:35
	ds_read2_b32 v[190:191], v115 offset0:36 offset1:37
	ds_read2_b32 v[192:193], v115 offset0:42 offset1:43
	ds_read2_b32 v[194:195], v115 offset0:44 offset1:45
	ds_read2_b32 v[196:197], v115 offset0:51 offset1:52
	ds_read2_b32 v[198:199], v115 offset0:53 offset1:54
	ds_read2_b32 v[200:201], v115 offset0:59 offset1:60
	ds_read2_b32 v[202:203], v115 offset0:61 offset1:62
	s_add_i32 s90, s67, 0
	v_add_u32_e32 v80, s90, v235
	v_add_u32_e32 v83, s90, v236
	v_add_u32_e32 v99, s90, v237
	v_add_u32_e32 v253, s90, v238
	v_add_u32_e32 v254, s90, v100
	v_add_u32_e32 v255, s90, v149
	v_med3_i32 v80, v80, 0, s99
	v_med3_i32 v83, v83, 0, s99
	v_med3_i32 v99, v99, 0, s99
	v_med3_i32 v253, v253, 0, s99
	v_med3_i32 v254, v254, 0, s99
	v_med3_i32 v255, v255, 0, s99
	v_mad_u32_u24 v80, v80, s100, v252
	v_mad_u32_u24 v83, v83, s100, v252
	v_mad_u32_u24 v99, v99, s100, v252
	v_mad_u32_u24 v253, v253, s100, v252
	v_mad_u32_u24 v254, v254, s100, v153
	v_mad_u32_u24 v255, v255, s100, v153
	global_load_dwordx4 v[116:119], v80, s[82:83]
	global_load_dwordx4 v[120:123], v83, s[82:83]
	global_load_dwordx4 v[124:127], v99, s[82:83]
	global_load_dwordx4 v[128:131], v253, s[82:83]
	global_load_dwordx4 v[132:135], v254, s[82:83] offset:768
	global_load_dwordx4 v[136:139], v255, s[82:83] offset:768
	global_load_dwordx4 v[140:143], v254, s[82:83] offset:832
	global_load_dwordx4 v[144:147], v255, s[82:83] offset:832
	ds_read_b64_tr_b16 v[72:73], v231
	ds_read_b64_tr_b16 v[74:75], v231 offset:512
	ds_read_b64_tr_b16 v[76:77], v231 offset:2048
	ds_read_b64_tr_b16 v[78:79], v231 offset:2560
	ds_read_b64_tr_b16 v[220:221], v231 offset:1024
	ds_read_b64_tr_b16 v[222:223], v231 offset:1536
	ds_read_b64_tr_b16 v[224:225], v231 offset:3072
	ds_read_b64_tr_b16 v[226:227], v231 offset:3584
	s_waitcnt vmcnt(8)
	ds_write_b128 v247, v[156:159]
	ds_write_b128 v247, v[160:163] offset:1024
	ds_write_b128 v247, v[164:167] offset:2048
	ds_write_b128 v247, v[168:171] offset:3072
	ds_read_b128 v[156:159], v248
	ds_read_b128 v[160:163], v249
	ds_read_b128 v[164:167], v250
	ds_read_b128 v[168:171], v251
	ds_write_b128 v112, v[172:175]
	ds_write_b128 v112, v[176:179] offset:1024
	ds_write_b128 v112, v[180:183] offset:2048
	ds_write_b128 v112, v[184:187] offset:3072
	v_exp_f32_e32 v32, v32
	v_exp_f32_e32 v33, v33
	v_exp_f32_e32 v34, v34
	v_exp_f32_e32 v35, v35
	v_exp_f32_e32 v36, v36
	v_exp_f32_e32 v37, v37
	s_waitcnt lgkmcnt(4)
	v_mfma_f32_32x32x16_bf16 v[188:203], v[156:159], v[48:51], v[188:203]
	v_exp_f32_e32 v38, v38
	v_exp_f32_e32 v39, v39
	v_mfma_f32_32x32x16_bf16 v[188:203], v[160:163], v[52:55], v[188:203]
	v_exp_f32_e32 v40, v40
	v_exp_f32_e32 v41, v41
	v_exp_f32_e32 v42, v42
	v_mfma_f32_32x32x16_bf16 v[188:203], v[164:167], v[56:59], v[188:203]
	v_exp_f32_e32 v43, v43
	v_exp_f32_e32 v44, v44
	v_mfma_f32_32x32x16_bf16 v[188:203], v[168:171], v[60:63], v[188:203]
	v_exp_f32_e32 v45, v45
	v_exp_f32_e32 v46, v46
	v_exp_f32_e32 v47, v47
	s_add_i32 s90, s67, -64
	v_add_u32_e32 v84, s90, v107
	v_add_u32_e32 v85, 0, v84
	v_add_u32_e32 v86, 1, v84
	v_add_u32_e32 v87, 2, v84
	v_add_u32_e32 v88, 3, v84
	v_cmp_gt_u32_e64 s[30:31], s98, v85
	v_cmp_gt_u32_e64 s[36:37], s98, v86
	v_cmp_gt_u32_e64 s[78:79], s98, v87
	v_cmp_gt_u32_e64 s[50:51], s98, v88
	v_cndmask_b32_e64 v32, 0, v32, s[30:31]
	v_add_u32_e32 v85, 8, v84
	v_cmp_gt_u32_e64 s[30:31], s98, v85
	v_cndmask_b32_e64 v33, 0, v33, s[36:37]
	v_add_u32_e32 v86, 9, v84
	v_cmp_gt_u32_e64 s[36:37], s98, v86
	v_cndmask_b32_e64 v34, 0, v34, s[78:79]
	v_add_u32_e32 v87, 10, v84
	v_cmp_gt_u32_e64 s[78:79], s98, v87
	v_cndmask_b32_e64 v35, 0, v35, s[50:51]
	v_add_u32_e32 v88, 11, v84
	v_cmp_gt_u32_e64 s[50:51], s98, v88
	v_cndmask_b32_e64 v36, 0, v36, s[30:31]
	v_add_u32_e32 v85, 16, v84
	v_cmp_gt_u32_e64 s[30:31], s98, v85
	v_cndmask_b32_e64 v37, 0, v37, s[36:37]
	v_add_u32_e32 v86, 17, v84
	v_cmp_gt_u32_e64 s[36:37], s98, v86
	v_cndmask_b32_e64 v38, 0, v38, s[78:79]
	v_add_u32_e32 v87, 18, v84
	v_cmp_gt_u32_e64 s[78:79], s98, v87
	v_cndmask_b32_e64 v39, 0, v39, s[50:51]
	v_add_u32_e32 v88, 19, v84
	v_cmp_gt_u32_e64 s[50:51], s98, v88
	v_cndmask_b32_e64 v40, 0, v40, s[30:31]
	v_add_u32_e32 v85, 24, v84
	v_cmp_gt_u32_e64 s[30:31], s98, v85
	v_cndmask_b32_e64 v41, 0, v41, s[36:37]
	v_add_u32_e32 v86, 25, v84
	v_cmp_gt_u32_e64 s[36:37], s98, v86
	v_cndmask_b32_e64 v42, 0, v42, s[78:79]
	v_add_u32_e32 v87, 26, v84
	v_cmp_gt_u32_e64 s[78:79], s98, v87
	v_cndmask_b32_e64 v43, 0, v43, s[50:51]
	v_add_u32_e32 v88, 27, v84
	v_cmp_gt_u32_e64 s[50:51], s98, v88
	v_nop
	v_cndmask_b32_e64 v44, 0, v44, s[30:31]
	v_cndmask_b32_e64 v45, 0, v45, s[36:37]
	v_cndmask_b32_e64 v46, 0, v46, s[78:79]
	v_cndmask_b32_e64 v47, 0, v47, s[50:51]
	v_cvt_pk_bf16_f32 v64, v32, v33
	v_cvt_pk_bf16_f32 v65, v34, v35
	v_cvt_pk_bf16_f32 v66, v36, v37
	v_cvt_pk_bf16_f32 v67, v38, v39
	v_cvt_pk_bf16_f32 v68, v40, v41
	v_cvt_pk_bf16_f32 v69, v42, v43
	v_cvt_pk_bf16_f32 v70, v44, v45
	v_cvt_pk_bf16_f32 v71, v46, v47
	v_pk_add_f32 v[232:233], v[232:233], v[32:33]
	v_pk_add_f32 v[232:233], v[232:233], v[34:35]
	v_pk_add_f32 v[232:233], v[232:233], v[36:37]
	v_pk_add_f32 v[232:233], v[232:233], v[38:39]
	v_pk_add_f32 v[232:233], v[232:233], v[40:41]
	v_pk_add_f32 v[232:233], v[232:233], v[42:43]
	v_pk_add_f32 v[232:233], v[232:233], v[44:45]
	v_pk_add_f32 v[232:233], v[232:233], v[46:47]
	ds_read2_b32 v[32:33], v115 offset0:68 offset1:69
	ds_read2_b32 v[34:35], v115 offset0:70 offset1:71
	ds_read2_b32 v[36:37], v115 offset0:76 offset1:77
	ds_read2_b32 v[38:39], v115 offset0:78 offset1:79
	ds_read2_b32 v[40:41], v115 offset0:85 offset1:86
	ds_read2_b32 v[42:43], v115 offset0:87 offset1:88
	ds_read2_b32 v[44:45], v115 offset0:93 offset1:94
	ds_read2_b32 v[46:47], v115 offset0:95 offset1:96
	v_mfma_f32_32x32x16_bf16 v[0:15], v[64:67], v[72:75], v[0:15]
	v_mfma_f32_32x32x16_bf16 v[16:31], v[64:67], v[76:79], v[16:31]
	v_mfma_f32_32x32x16_bf16 v[0:15], v[68:71], v[220:223], v[0:15]
	v_mfma_f32_32x32x16_bf16 v[16:31], v[68:71], v[224:227], v[16:31]
	s_add_i32 s90, s67, 32
	v_add_u32_e32 v80, s90, v235
	v_add_u32_e32 v83, s90, v236
	v_add_u32_e32 v99, s90, v237
	v_add_u32_e32 v253, s90, v238
	v_add_u32_e32 v254, s90, v100
	v_add_u32_e32 v255, s90, v149
	v_med3_i32 v80, v80, 0, s99
	v_med3_i32 v83, v83, 0, s99
	v_med3_i32 v99, v99, 0, s99
	v_med3_i32 v253, v253, 0, s99
	v_med3_i32 v254, v254, 0, s99
	v_med3_i32 v255, v255, 0, s99
	v_mad_u32_u24 v80, v80, s100, v252
	v_mad_u32_u24 v83, v83, s100, v252
	v_mad_u32_u24 v99, v99, s100, v252
	v_mad_u32_u24 v253, v253, s100, v252
	v_mad_u32_u24 v254, v254, s100, v153
	v_mad_u32_u24 v255, v255, s100, v153
	global_load_dwordx4 v[156:159], v80, s[82:83]
	global_load_dwordx4 v[160:163], v83, s[82:83]
	global_load_dwordx4 v[164:167], v99, s[82:83]
	global_load_dwordx4 v[168:171], v253, s[82:83]
	global_load_dwordx4 v[172:175], v254, s[82:83] offset:768
	global_load_dwordx4 v[176:179], v255, s[82:83] offset:768
	global_load_dwordx4 v[180:183], v254, s[82:83] offset:832
	global_load_dwordx4 v[184:187], v255, s[82:83] offset:832
	ds_read_b64_tr_b16 v[72:73], v231
	ds_read_b64_tr_b16 v[74:75], v231 offset:512
	ds_read_b64_tr_b16 v[76:77], v231 offset:2048
	ds_read_b64_tr_b16 v[78:79], v231 offset:2560
	ds_read_b64_tr_b16 v[220:221], v231 offset:1024
	ds_read_b64_tr_b16 v[222:223], v231 offset:1536
	ds_read_b64_tr_b16 v[224:225], v231 offset:3072
	ds_read_b64_tr_b16 v[226:227], v231 offset:3584
	s_waitcnt vmcnt(8)
	ds_write_b128 v247, v[116:119]
	ds_write_b128 v247, v[120:123] offset:1024
	ds_write_b128 v247, v[124:127] offset:2048
	ds_write_b128 v247, v[128:131] offset:3072
	ds_read_b128 v[116:119], v248
	ds_read_b128 v[120:123], v249
	ds_read_b128 v[124:127], v250
	ds_read_b128 v[128:131], v251
	ds_write_b128 v112, v[132:135]
	ds_write_b128 v112, v[136:139] offset:1024
	ds_write_b128 v112, v[140:143] offset:2048
	ds_write_b128 v112, v[144:147] offset:3072
	v_exp_f32_e32 v188, v188
	v_exp_f32_e32 v189, v189
	v_exp_f32_e32 v190, v190
	v_exp_f32_e32 v191, v191
	v_exp_f32_e32 v192, v192
	v_exp_f32_e32 v193, v193
	s_waitcnt lgkmcnt(4)
	v_mfma_f32_32x32x16_bf16 v[32:47], v[116:119], v[48:51], v[32:47]
	v_exp_f32_e32 v194, v194
	v_exp_f32_e32 v195, v195
	v_mfma_f32_32x32x16_bf16 v[32:47], v[120:123], v[52:55], v[32:47]
	v_exp_f32_e32 v196, v196
	v_exp_f32_e32 v197, v197
	v_exp_f32_e32 v198, v198
	v_mfma_f32_32x32x16_bf16 v[32:47], v[124:127], v[56:59], v[32:47]
	v_exp_f32_e32 v199, v199
	v_exp_f32_e32 v200, v200
	v_mfma_f32_32x32x16_bf16 v[32:47], v[128:131], v[60:63], v[32:47]
	v_exp_f32_e32 v201, v201
	v_exp_f32_e32 v202, v202
	v_exp_f32_e32 v203, v203
	s_add_i32 s90, s67, -32
	v_add_u32_e32 v84, s90, v107
	v_add_u32_e32 v85, 0, v84
	v_add_u32_e32 v86, 1, v84
	v_add_u32_e32 v87, 2, v84
	v_add_u32_e32 v88, 3, v84
	v_cmp_gt_u32_e64 s[30:31], s98, v85
	v_cmp_gt_u32_e64 s[36:37], s98, v86
	v_cmp_gt_u32_e64 s[78:79], s98, v87
	v_cmp_gt_u32_e64 s[50:51], s98, v88
	v_cndmask_b32_e64 v188, 0, v188, s[30:31]
	v_add_u32_e32 v85, 8, v84
	v_cmp_gt_u32_e64 s[30:31], s98, v85
	v_cndmask_b32_e64 v189, 0, v189, s[36:37]
	v_add_u32_e32 v86, 9, v84
	v_cmp_gt_u32_e64 s[36:37], s98, v86
	v_cndmask_b32_e64 v190, 0, v190, s[78:79]
	v_add_u32_e32 v87, 10, v84
	v_cmp_gt_u32_e64 s[78:79], s98, v87
	v_cndmask_b32_e64 v191, 0, v191, s[50:51]
	v_add_u32_e32 v88, 11, v84
	v_cmp_gt_u32_e64 s[50:51], s98, v88
	v_cndmask_b32_e64 v192, 0, v192, s[30:31]
	v_add_u32_e32 v85, 16, v84
	v_cmp_gt_u32_e64 s[30:31], s98, v85
	v_cndmask_b32_e64 v193, 0, v193, s[36:37]
	v_add_u32_e32 v86, 17, v84
	v_cmp_gt_u32_e64 s[36:37], s98, v86
	v_cndmask_b32_e64 v194, 0, v194, s[78:79]
	v_add_u32_e32 v87, 18, v84
	v_cmp_gt_u32_e64 s[78:79], s98, v87
	v_cndmask_b32_e64 v195, 0, v195, s[50:51]
	v_add_u32_e32 v88, 19, v84
	v_cmp_gt_u32_e64 s[50:51], s98, v88
	v_cndmask_b32_e64 v196, 0, v196, s[30:31]
	v_add_u32_e32 v85, 24, v84
	v_cmp_gt_u32_e64 s[30:31], s98, v85
	v_cndmask_b32_e64 v197, 0, v197, s[36:37]
	v_add_u32_e32 v86, 25, v84
	v_cmp_gt_u32_e64 s[36:37], s98, v86
	v_cndmask_b32_e64 v198, 0, v198, s[78:79]
	v_add_u32_e32 v87, 26, v84
	v_cmp_gt_u32_e64 s[78:79], s98, v87
	v_cndmask_b32_e64 v199, 0, v199, s[50:51]
	v_add_u32_e32 v88, 27, v84
	v_cmp_gt_u32_e64 s[50:51], s98, v88
	v_nop
	v_cndmask_b32_e64 v200, 0, v200, s[30:31]
	v_cndmask_b32_e64 v201, 0, v201, s[36:37]
	v_cndmask_b32_e64 v202, 0, v202, s[78:79]
	v_cndmask_b32_e64 v203, 0, v203, s[50:51]
	v_cvt_pk_bf16_f32 v64, v188, v189
	v_cvt_pk_bf16_f32 v65, v190, v191
	v_cvt_pk_bf16_f32 v66, v192, v193
	v_cvt_pk_bf16_f32 v67, v194, v195
	v_cvt_pk_bf16_f32 v68, v196, v197
	v_cvt_pk_bf16_f32 v69, v198, v199
	v_cvt_pk_bf16_f32 v70, v200, v201
	v_cvt_pk_bf16_f32 v71, v202, v203
	v_pk_add_f32 v[232:233], v[232:233], v[188:189]
	v_pk_add_f32 v[232:233], v[232:233], v[190:191]
	v_pk_add_f32 v[232:233], v[232:233], v[192:193]
	v_pk_add_f32 v[232:233], v[232:233], v[194:195]
	v_pk_add_f32 v[232:233], v[232:233], v[196:197]
	v_pk_add_f32 v[232:233], v[232:233], v[198:199]
	v_pk_add_f32 v[232:233], v[232:233], v[200:201]
	v_pk_add_f32 v[232:233], v[232:233], v[202:203]
	ds_read2_b32 v[188:189], v115 offset0:102 offset1:103
	ds_read2_b32 v[190:191], v115 offset0:104 offset1:105
	ds_read2_b32 v[192:193], v115 offset0:110 offset1:111
	ds_read2_b32 v[194:195], v115 offset0:112 offset1:113
	ds_read2_b32 v[196:197], v115 offset0:119 offset1:120
	ds_read2_b32 v[198:199], v115 offset0:121 offset1:122
	ds_read2_b32 v[200:201], v115 offset0:127 offset1:128
	ds_read2_b32 v[202:203], v115 offset0:129 offset1:130
	v_mfma_f32_32x32x16_bf16 v[0:15], v[64:67], v[72:75], v[0:15]
	v_mfma_f32_32x32x16_bf16 v[16:31], v[64:67], v[76:79], v[16:31]
	v_mfma_f32_32x32x16_bf16 v[0:15], v[68:71], v[220:223], v[0:15]
	v_mfma_f32_32x32x16_bf16 v[16:31], v[68:71], v[224:227], v[16:31]
	s_add_i32 s90, s67, 64
	v_add_u32_e32 v80, s90, v235
	v_add_u32_e32 v83, s90, v236
	v_add_u32_e32 v99, s90, v237
	v_add_u32_e32 v253, s90, v238
	v_add_u32_e32 v254, s90, v100
	v_add_u32_e32 v255, s90, v149
	v_med3_i32 v80, v80, 0, s99
	v_med3_i32 v83, v83, 0, s99
	v_med3_i32 v99, v99, 0, s99
	v_med3_i32 v253, v253, 0, s99
	v_med3_i32 v254, v254, 0, s99
	v_med3_i32 v255, v255, 0, s99
	v_mad_u32_u24 v80, v80, s100, v252
	v_mad_u32_u24 v83, v83, s100, v252
	v_mad_u32_u24 v99, v99, s100, v252
	v_mad_u32_u24 v253, v253, s100, v252
	v_mad_u32_u24 v254, v254, s100, v153
	v_mad_u32_u24 v255, v255, s100, v153
	global_load_dwordx4 v[116:119], v80, s[82:83]
	global_load_dwordx4 v[120:123], v83, s[82:83]
	global_load_dwordx4 v[124:127], v99, s[82:83]
	global_load_dwordx4 v[128:131], v253, s[82:83]
	global_load_dwordx4 v[132:135], v254, s[82:83] offset:768
	global_load_dwordx4 v[136:139], v255, s[82:83] offset:768
	global_load_dwordx4 v[140:143], v254, s[82:83] offset:832
	global_load_dwordx4 v[144:147], v255, s[82:83] offset:832
	ds_read_b64_tr_b16 v[72:73], v231
	ds_read_b64_tr_b16 v[74:75], v231 offset:512
	ds_read_b64_tr_b16 v[76:77], v231 offset:2048
	ds_read_b64_tr_b16 v[78:79], v231 offset:2560
	ds_read_b64_tr_b16 v[220:221], v231 offset:1024
	ds_read_b64_tr_b16 v[222:223], v231 offset:1536
	ds_read_b64_tr_b16 v[224:225], v231 offset:3072
	ds_read_b64_tr_b16 v[226:227], v231 offset:3584
	s_waitcnt vmcnt(8)
	ds_write_b128 v247, v[156:159]
	ds_write_b128 v247, v[160:163] offset:1024
	ds_write_b128 v247, v[164:167] offset:2048
	ds_write_b128 v247, v[168:171] offset:3072
	ds_read_b128 v[156:159], v248
	ds_read_b128 v[160:163], v249
	ds_read_b128 v[164:167], v250
	ds_read_b128 v[168:171], v251
	ds_write_b128 v112, v[172:175]
	ds_write_b128 v112, v[176:179] offset:1024
	ds_write_b128 v112, v[180:183] offset:2048
	ds_write_b128 v112, v[184:187] offset:3072
	v_exp_f32_e32 v32, v32
	v_exp_f32_e32 v33, v33
	v_exp_f32_e32 v34, v34
	v_exp_f32_e32 v35, v35
	v_exp_f32_e32 v36, v36
	v_exp_f32_e32 v37, v37
	s_waitcnt lgkmcnt(4)
	v_mfma_f32_32x32x16_bf16 v[188:203], v[156:159], v[48:51], v[188:203]
	v_exp_f32_e32 v38, v38
	v_exp_f32_e32 v39, v39
	v_mfma_f32_32x32x16_bf16 v[188:203], v[160:163], v[52:55], v[188:203]
	v_exp_f32_e32 v40, v40
	v_exp_f32_e32 v41, v41
	v_exp_f32_e32 v42, v42
	v_mfma_f32_32x32x16_bf16 v[188:203], v[164:167], v[56:59], v[188:203]
	v_exp_f32_e32 v43, v43
	v_exp_f32_e32 v44, v44
	v_mfma_f32_32x32x16_bf16 v[188:203], v[168:171], v[60:63], v[188:203]
	v_exp_f32_e32 v45, v45
	v_exp_f32_e32 v46, v46
	v_exp_f32_e32 v47, v47
	s_add_i32 s90, s67, 0
	v_add_u32_e32 v84, s90, v107
	v_add_u32_e32 v85, 0, v84
	v_add_u32_e32 v86, 1, v84
	v_add_u32_e32 v87, 2, v84
	v_add_u32_e32 v88, 3, v84
	v_cmp_gt_u32_e64 s[30:31], s98, v85
	v_cmp_gt_u32_e64 s[36:37], s98, v86
	v_cmp_gt_u32_e64 s[78:79], s98, v87
	v_cmp_gt_u32_e64 s[50:51], s98, v88
	v_cndmask_b32_e64 v32, 0, v32, s[30:31]
	v_add_u32_e32 v85, 8, v84
	v_cmp_gt_u32_e64 s[30:31], s98, v85
	v_cndmask_b32_e64 v33, 0, v33, s[36:37]
	v_add_u32_e32 v86, 9, v84
	v_cmp_gt_u32_e64 s[36:37], s98, v86
	v_cndmask_b32_e64 v34, 0, v34, s[78:79]
	v_add_u32_e32 v87, 10, v84
	v_cmp_gt_u32_e64 s[78:79], s98, v87
	v_cndmask_b32_e64 v35, 0, v35, s[50:51]
	v_add_u32_e32 v88, 11, v84
	v_cmp_gt_u32_e64 s[50:51], s98, v88
	v_cndmask_b32_e64 v36, 0, v36, s[30:31]
	v_add_u32_e32 v85, 16, v84
	v_cmp_gt_u32_e64 s[30:31], s98, v85
	v_cndmask_b32_e64 v37, 0, v37, s[36:37]
	v_add_u32_e32 v86, 17, v84
	v_cmp_gt_u32_e64 s[36:37], s98, v86
	v_cndmask_b32_e64 v38, 0, v38, s[78:79]
	v_add_u32_e32 v87, 18, v84
	v_cmp_gt_u32_e64 s[78:79], s98, v87
	v_cndmask_b32_e64 v39, 0, v39, s[50:51]
	v_add_u32_e32 v88, 19, v84
	v_cmp_gt_u32_e64 s[50:51], s98, v88
	v_cndmask_b32_e64 v40, 0, v40, s[30:31]
	v_add_u32_e32 v85, 24, v84
	v_cmp_gt_u32_e64 s[30:31], s98, v85
	v_cndmask_b32_e64 v41, 0, v41, s[36:37]
	v_add_u32_e32 v86, 25, v84
	v_cmp_gt_u32_e64 s[36:37], s98, v86
	v_cndmask_b32_e64 v42, 0, v42, s[78:79]
	v_add_u32_e32 v87, 26, v84
	v_cmp_gt_u32_e64 s[78:79], s98, v87
	v_cndmask_b32_e64 v43, 0, v43, s[50:51]
	v_add_u32_e32 v88, 27, v84
	v_cmp_gt_u32_e64 s[50:51], s98, v88
	v_nop
	v_cndmask_b32_e64 v44, 0, v44, s[30:31]
	v_cndmask_b32_e64 v45, 0, v45, s[36:37]
	v_cndmask_b32_e64 v46, 0, v46, s[78:79]
	v_cndmask_b32_e64 v47, 0, v47, s[50:51]
	v_cvt_pk_bf16_f32 v64, v32, v33
	v_cvt_pk_bf16_f32 v65, v34, v35
	v_cvt_pk_bf16_f32 v66, v36, v37
	v_cvt_pk_bf16_f32 v67, v38, v39
	v_cvt_pk_bf16_f32 v68, v40, v41
	v_cvt_pk_bf16_f32 v69, v42, v43
	v_cvt_pk_bf16_f32 v70, v44, v45
	v_cvt_pk_bf16_f32 v71, v46, v47
	v_pk_add_f32 v[232:233], v[232:233], v[32:33]
	v_pk_add_f32 v[232:233], v[232:233], v[34:35]
	v_pk_add_f32 v[232:233], v[232:233], v[36:37]
	v_pk_add_f32 v[232:233], v[232:233], v[38:39]
	v_pk_add_f32 v[232:233], v[232:233], v[40:41]
	v_pk_add_f32 v[232:233], v[232:233], v[42:43]
	v_pk_add_f32 v[232:233], v[232:233], v[44:45]
	v_pk_add_f32 v[232:233], v[232:233], v[46:47]
	ds_read2_b32 v[32:33], v115 offset0:136 offset1:137
	ds_read2_b32 v[34:35], v115 offset0:138 offset1:139
	ds_read2_b32 v[36:37], v115 offset0:144 offset1:145
	ds_read2_b32 v[38:39], v115 offset0:146 offset1:147
	ds_read2_b32 v[40:41], v115 offset0:153 offset1:154
	ds_read2_b32 v[42:43], v115 offset0:155 offset1:156
	ds_read2_b32 v[44:45], v115 offset0:161 offset1:162
	ds_read2_b32 v[46:47], v115 offset0:163 offset1:164
	v_mfma_f32_32x32x16_bf16 v[0:15], v[64:67], v[72:75], v[0:15]
	v_mfma_f32_32x32x16_bf16 v[16:31], v[64:67], v[76:79], v[16:31]
	v_mfma_f32_32x32x16_bf16 v[0:15], v[68:71], v[220:223], v[0:15]
	v_mfma_f32_32x32x16_bf16 v[16:31], v[68:71], v[224:227], v[16:31]
	s_add_i32 s90, s67, 96
	v_add_u32_e32 v80, s90, v235
	v_add_u32_e32 v83, s90, v236
	v_add_u32_e32 v99, s90, v237
	v_add_u32_e32 v253, s90, v238
	v_add_u32_e32 v254, s90, v100
	v_add_u32_e32 v255, s90, v149
	v_med3_i32 v80, v80, 0, s99
	v_med3_i32 v83, v83, 0, s99
	v_med3_i32 v99, v99, 0, s99
	v_med3_i32 v253, v253, 0, s99
	v_med3_i32 v254, v254, 0, s99
	v_med3_i32 v255, v255, 0, s99
	v_mad_u32_u24 v80, v80, s100, v252
	v_mad_u32_u24 v83, v83, s100, v252
	v_mad_u32_u24 v99, v99, s100, v252
	v_mad_u32_u24 v253, v253, s100, v252
	v_mad_u32_u24 v254, v254, s100, v153
	v_mad_u32_u24 v255, v255, s100, v153
	global_load_dwordx4 v[156:159], v80, s[82:83]
	global_load_dwordx4 v[160:163], v83, s[82:83]
	global_load_dwordx4 v[164:167], v99, s[82:83]
	global_load_dwordx4 v[168:171], v253, s[82:83]
	global_load_dwordx4 v[172:175], v254, s[82:83] offset:768
	global_load_dwordx4 v[176:179], v255, s[82:83] offset:768
	global_load_dwordx4 v[180:183], v254, s[82:83] offset:832
	global_load_dwordx4 v[184:187], v255, s[82:83] offset:832
	ds_read_b64_tr_b16 v[72:73], v231
	ds_read_b64_tr_b16 v[74:75], v231 offset:512
	ds_read_b64_tr_b16 v[76:77], v231 offset:2048
	ds_read_b64_tr_b16 v[78:79], v231 offset:2560
	ds_read_b64_tr_b16 v[220:221], v231 offset:1024
	ds_read_b64_tr_b16 v[222:223], v231 offset:1536
	ds_read_b64_tr_b16 v[224:225], v231 offset:3072
	ds_read_b64_tr_b16 v[226:227], v231 offset:3584
	s_waitcnt vmcnt(8)
	ds_write_b128 v247, v[116:119]
	ds_write_b128 v247, v[120:123] offset:1024
	ds_write_b128 v247, v[124:127] offset:2048
	ds_write_b128 v247, v[128:131] offset:3072
	ds_read_b128 v[116:119], v248
	ds_read_b128 v[120:123], v249
	ds_read_b128 v[124:127], v250
	ds_read_b128 v[128:131], v251
	ds_write_b128 v112, v[132:135]
	ds_write_b128 v112, v[136:139] offset:1024
	ds_write_b128 v112, v[140:143] offset:2048
	ds_write_b128 v112, v[144:147] offset:3072
	v_exp_f32_e32 v188, v188
	v_exp_f32_e32 v189, v189
	v_exp_f32_e32 v190, v190
	v_exp_f32_e32 v191, v191
	v_exp_f32_e32 v192, v192
	v_exp_f32_e32 v193, v193
	s_waitcnt lgkmcnt(4)
	v_mfma_f32_32x32x16_bf16 v[32:47], v[116:119], v[48:51], v[32:47]
	v_exp_f32_e32 v194, v194
	v_exp_f32_e32 v195, v195
	v_mfma_f32_32x32x16_bf16 v[32:47], v[120:123], v[52:55], v[32:47]
	v_exp_f32_e32 v196, v196
	v_exp_f32_e32 v197, v197
	v_exp_f32_e32 v198, v198
	v_mfma_f32_32x32x16_bf16 v[32:47], v[124:127], v[56:59], v[32:47]
	v_exp_f32_e32 v199, v199
	v_exp_f32_e32 v200, v200
	v_mfma_f32_32x32x16_bf16 v[32:47], v[128:131], v[60:63], v[32:47]
	v_exp_f32_e32 v201, v201
	v_exp_f32_e32 v202, v202
	v_exp_f32_e32 v203, v203
	s_add_i32 s90, s67, 32
	v_add_u32_e32 v84, s90, v107
	v_add_u32_e32 v85, 0, v84
	v_add_u32_e32 v86, 1, v84
	v_add_u32_e32 v87, 2, v84
	v_add_u32_e32 v88, 3, v84
	v_cmp_gt_u32_e64 s[30:31], s98, v85
	v_cmp_gt_u32_e64 s[36:37], s98, v86
	v_cmp_gt_u32_e64 s[78:79], s98, v87
	v_cmp_gt_u32_e64 s[50:51], s98, v88
	v_cndmask_b32_e64 v188, 0, v188, s[30:31]
	v_add_u32_e32 v85, 8, v84
	v_cmp_gt_u32_e64 s[30:31], s98, v85
	v_cndmask_b32_e64 v189, 0, v189, s[36:37]
	v_add_u32_e32 v86, 9, v84
	v_cmp_gt_u32_e64 s[36:37], s98, v86
	v_cndmask_b32_e64 v190, 0, v190, s[78:79]
	v_add_u32_e32 v87, 10, v84
	v_cmp_gt_u32_e64 s[78:79], s98, v87
	v_cndmask_b32_e64 v191, 0, v191, s[50:51]
	v_add_u32_e32 v88, 11, v84
	v_cmp_gt_u32_e64 s[50:51], s98, v88
	v_cndmask_b32_e64 v192, 0, v192, s[30:31]
	v_add_u32_e32 v85, 16, v84
	v_cmp_gt_u32_e64 s[30:31], s98, v85
	v_cndmask_b32_e64 v193, 0, v193, s[36:37]
	v_add_u32_e32 v86, 17, v84
	v_cmp_gt_u32_e64 s[36:37], s98, v86
	v_cndmask_b32_e64 v194, 0, v194, s[78:79]
	v_add_u32_e32 v87, 18, v84
	v_cmp_gt_u32_e64 s[78:79], s98, v87
	v_cndmask_b32_e64 v195, 0, v195, s[50:51]
	v_add_u32_e32 v88, 19, v84
	v_cmp_gt_u32_e64 s[50:51], s98, v88
	v_cndmask_b32_e64 v196, 0, v196, s[30:31]
	v_add_u32_e32 v85, 24, v84
	v_cmp_gt_u32_e64 s[30:31], s98, v85
	v_cndmask_b32_e64 v197, 0, v197, s[36:37]
	v_add_u32_e32 v86, 25, v84
	v_cmp_gt_u32_e64 s[36:37], s98, v86
	v_cndmask_b32_e64 v198, 0, v198, s[78:79]
	v_add_u32_e32 v87, 26, v84
	v_cmp_gt_u32_e64 s[78:79], s98, v87
	v_cndmask_b32_e64 v199, 0, v199, s[50:51]
	v_add_u32_e32 v88, 27, v84
	v_cmp_gt_u32_e64 s[50:51], s98, v88
	v_nop
	v_cndmask_b32_e64 v200, 0, v200, s[30:31]
	v_cndmask_b32_e64 v201, 0, v201, s[36:37]
	v_cndmask_b32_e64 v202, 0, v202, s[78:79]
	v_cndmask_b32_e64 v203, 0, v203, s[50:51]
	v_cvt_pk_bf16_f32 v64, v188, v189
	v_cvt_pk_bf16_f32 v65, v190, v191
	v_cvt_pk_bf16_f32 v66, v192, v193
	v_cvt_pk_bf16_f32 v67, v194, v195
	v_cvt_pk_bf16_f32 v68, v196, v197
	v_cvt_pk_bf16_f32 v69, v198, v199
	v_cvt_pk_bf16_f32 v70, v200, v201
	v_cvt_pk_bf16_f32 v71, v202, v203
	v_pk_add_f32 v[232:233], v[232:233], v[188:189]
	v_pk_add_f32 v[232:233], v[232:233], v[190:191]
	v_pk_add_f32 v[232:233], v[232:233], v[192:193]
	v_pk_add_f32 v[232:233], v[232:233], v[194:195]
	v_pk_add_f32 v[232:233], v[232:233], v[196:197]
	v_pk_add_f32 v[232:233], v[232:233], v[198:199]
	v_pk_add_f32 v[232:233], v[232:233], v[200:201]
	v_pk_add_f32 v[232:233], v[232:233], v[202:203]
	ds_read2_b32 v[188:189], v115 offset0:170 offset1:171
	ds_read2_b32 v[190:191], v115 offset0:172 offset1:173
	ds_read2_b32 v[192:193], v115 offset0:178 offset1:179
	ds_read2_b32 v[194:195], v115 offset0:180 offset1:181
	ds_read2_b32 v[196:197], v115 offset0:187 offset1:188
	ds_read2_b32 v[198:199], v115 offset0:189 offset1:190
	ds_read2_b32 v[200:201], v115 offset0:195 offset1:196
	ds_read2_b32 v[202:203], v115 offset0:197 offset1:198
	v_mfma_f32_32x32x16_bf16 v[0:15], v[64:67], v[72:75], v[0:15]
	v_mfma_f32_32x32x16_bf16 v[16:31], v[64:67], v[76:79], v[16:31]
	v_mfma_f32_32x32x16_bf16 v[0:15], v[68:71], v[220:223], v[0:15]
	v_mfma_f32_32x32x16_bf16 v[16:31], v[68:71], v[224:227], v[16:31]
	s_add_i32 s90, s67, 128
	v_add_u32_e32 v80, s90, v235
	v_add_u32_e32 v83, s90, v236
	v_add_u32_e32 v99, s90, v237
	v_add_u32_e32 v253, s90, v238
	v_add_u32_e32 v254, s90, v100
	v_add_u32_e32 v255, s90, v149
	v_med3_i32 v80, v80, 0, s99
	v_med3_i32 v83, v83, 0, s99
	v_med3_i32 v99, v99, 0, s99
	v_med3_i32 v253, v253, 0, s99
	v_med3_i32 v254, v254, 0, s99
	v_med3_i32 v255, v255, 0, s99
	v_mad_u32_u24 v80, v80, s100, v252
	v_mad_u32_u24 v83, v83, s100, v252
	v_mad_u32_u24 v99, v99, s100, v252
	v_mad_u32_u24 v253, v253, s100, v252
	v_mad_u32_u24 v254, v254, s100, v153
	v_mad_u32_u24 v255, v255, s100, v153
	global_load_dwordx4 v[116:119], v80, s[82:83]
	global_load_dwordx4 v[120:123], v83, s[82:83]
	global_load_dwordx4 v[124:127], v99, s[82:83]
	global_load_dwordx4 v[128:131], v253, s[82:83]
	global_load_dwordx4 v[132:135], v254, s[82:83] offset:768
	global_load_dwordx4 v[136:139], v255, s[82:83] offset:768
	global_load_dwordx4 v[140:143], v254, s[82:83] offset:832
	global_load_dwordx4 v[144:147], v255, s[82:83] offset:832
	ds_read_b64_tr_b16 v[72:73], v231
	ds_read_b64_tr_b16 v[74:75], v231 offset:512
	ds_read_b64_tr_b16 v[76:77], v231 offset:2048
	ds_read_b64_tr_b16 v[78:79], v231 offset:2560
	ds_read_b64_tr_b16 v[220:221], v231 offset:1024
	ds_read_b64_tr_b16 v[222:223], v231 offset:1536
	ds_read_b64_tr_b16 v[224:225], v231 offset:3072
	ds_read_b64_tr_b16 v[226:227], v231 offset:3584
	s_waitcnt vmcnt(8)
	ds_write_b128 v247, v[156:159]
	ds_write_b128 v247, v[160:163] offset:1024
	ds_write_b128 v247, v[164:167] offset:2048
	ds_write_b128 v247, v[168:171] offset:3072
	ds_read_b128 v[156:159], v248
	ds_read_b128 v[160:163], v249
	ds_read_b128 v[164:167], v250
	ds_read_b128 v[168:171], v251
	ds_write_b128 v112, v[172:175]
	ds_write_b128 v112, v[176:179] offset:1024
	ds_write_b128 v112, v[180:183] offset:2048
	ds_write_b128 v112, v[184:187] offset:3072
	v_exp_f32_e32 v32, v32
	v_exp_f32_e32 v33, v33
	v_exp_f32_e32 v34, v34
	v_exp_f32_e32 v35, v35
	v_exp_f32_e32 v36, v36
	v_exp_f32_e32 v37, v37
	s_waitcnt lgkmcnt(4)
	v_mfma_f32_32x32x16_bf16 v[188:203], v[156:159], v[48:51], v[188:203]
	v_exp_f32_e32 v38, v38
	v_exp_f32_e32 v39, v39
	v_mfma_f32_32x32x16_bf16 v[188:203], v[160:163], v[52:55], v[188:203]
	v_exp_f32_e32 v40, v40
	v_exp_f32_e32 v41, v41
	v_exp_f32_e32 v42, v42
	v_mfma_f32_32x32x16_bf16 v[188:203], v[164:167], v[56:59], v[188:203]
	v_exp_f32_e32 v43, v43
	v_exp_f32_e32 v44, v44
	v_mfma_f32_32x32x16_bf16 v[188:203], v[168:171], v[60:63], v[188:203]
	v_exp_f32_e32 v45, v45
	v_exp_f32_e32 v46, v46
	v_exp_f32_e32 v47, v47
	s_add_i32 s90, s67, 64
	v_add_u32_e32 v84, s90, v107
	v_add_u32_e32 v85, 0, v84
	v_add_u32_e32 v86, 1, v84
	v_add_u32_e32 v87, 2, v84
	v_add_u32_e32 v88, 3, v84
	v_cmp_gt_u32_e64 s[30:31], s98, v85
	v_cmp_gt_u32_e64 s[36:37], s98, v86
	v_cmp_gt_u32_e64 s[78:79], s98, v87
	v_cmp_gt_u32_e64 s[50:51], s98, v88
	v_cndmask_b32_e64 v32, 0, v32, s[30:31]
	v_add_u32_e32 v85, 8, v84
	v_cmp_gt_u32_e64 s[30:31], s98, v85
	v_cndmask_b32_e64 v33, 0, v33, s[36:37]
	v_add_u32_e32 v86, 9, v84
	v_cmp_gt_u32_e64 s[36:37], s98, v86
	v_cndmask_b32_e64 v34, 0, v34, s[78:79]
	v_add_u32_e32 v87, 10, v84
	v_cmp_gt_u32_e64 s[78:79], s98, v87
	v_cndmask_b32_e64 v35, 0, v35, s[50:51]
	v_add_u32_e32 v88, 11, v84
	v_cmp_gt_u32_e64 s[50:51], s98, v88
	v_cndmask_b32_e64 v36, 0, v36, s[30:31]
	v_add_u32_e32 v85, 16, v84
	v_cmp_gt_u32_e64 s[30:31], s98, v85
	v_cndmask_b32_e64 v37, 0, v37, s[36:37]
	v_add_u32_e32 v86, 17, v84
	v_cmp_gt_u32_e64 s[36:37], s98, v86
	v_cndmask_b32_e64 v38, 0, v38, s[78:79]
	v_add_u32_e32 v87, 18, v84
	v_cmp_gt_u32_e64 s[78:79], s98, v87
	v_cndmask_b32_e64 v39, 0, v39, s[50:51]
	v_add_u32_e32 v88, 19, v84
	v_cmp_gt_u32_e64 s[50:51], s98, v88
	v_cndmask_b32_e64 v40, 0, v40, s[30:31]
	v_add_u32_e32 v85, 24, v84
	v_cmp_gt_u32_e64 s[30:31], s98, v85
	v_cndmask_b32_e64 v41, 0, v41, s[36:37]
	v_add_u32_e32 v86, 25, v84
	v_cmp_gt_u32_e64 s[36:37], s98, v86
	v_cndmask_b32_e64 v42, 0, v42, s[78:79]
	v_add_u32_e32 v87, 26, v84
	v_cmp_gt_u32_e64 s[78:79], s98, v87
	v_cndmask_b32_e64 v43, 0, v43, s[50:51]
	v_add_u32_e32 v88, 27, v84
	v_cmp_gt_u32_e64 s[50:51], s98, v88
	v_nop
	v_cndmask_b32_e64 v44, 0, v44, s[30:31]
	v_cndmask_b32_e64 v45, 0, v45, s[36:37]
	v_cndmask_b32_e64 v46, 0, v46, s[78:79]
	v_cndmask_b32_e64 v47, 0, v47, s[50:51]
	v_cvt_pk_bf16_f32 v64, v32, v33
	v_cvt_pk_bf16_f32 v65, v34, v35
	v_cvt_pk_bf16_f32 v66, v36, v37
	v_cvt_pk_bf16_f32 v67, v38, v39
	v_cvt_pk_bf16_f32 v68, v40, v41
	v_cvt_pk_bf16_f32 v69, v42, v43
	v_cvt_pk_bf16_f32 v70, v44, v45
	v_cvt_pk_bf16_f32 v71, v46, v47
	v_pk_add_f32 v[232:233], v[232:233], v[32:33]
	v_pk_add_f32 v[232:233], v[232:233], v[34:35]
	v_pk_add_f32 v[232:233], v[232:233], v[36:37]
	v_pk_add_f32 v[232:233], v[232:233], v[38:39]
	v_pk_add_f32 v[232:233], v[232:233], v[40:41]
	v_pk_add_f32 v[232:233], v[232:233], v[42:43]
	v_pk_add_f32 v[232:233], v[232:233], v[44:45]
	v_pk_add_f32 v[232:233], v[232:233], v[46:47]
	ds_read2_b32 v[32:33], v115 offset0:204 offset1:205
	ds_read2_b32 v[34:35], v115 offset0:206 offset1:207
	ds_read2_b32 v[36:37], v115 offset0:212 offset1:213
	ds_read2_b32 v[38:39], v115 offset0:214 offset1:215
	ds_read2_b32 v[40:41], v115 offset0:221 offset1:222
	ds_read2_b32 v[42:43], v115 offset0:223 offset1:224
	ds_read2_b32 v[44:45], v115 offset0:229 offset1:230
	ds_read2_b32 v[46:47], v115 offset0:231 offset1:232
	v_mfma_f32_32x32x16_bf16 v[0:15], v[64:67], v[72:75], v[0:15]
	v_mfma_f32_32x32x16_bf16 v[16:31], v[64:67], v[76:79], v[16:31]
	v_mfma_f32_32x32x16_bf16 v[0:15], v[68:71], v[220:223], v[0:15]
	v_mfma_f32_32x32x16_bf16 v[16:31], v[68:71], v[224:227], v[16:31]
	s_add_i32 s90, s67, 160
	v_add_u32_e32 v80, s90, v235
	v_add_u32_e32 v83, s90, v236
	v_add_u32_e32 v99, s90, v237
	v_add_u32_e32 v253, s90, v238
	v_add_u32_e32 v254, s90, v100
	v_add_u32_e32 v255, s90, v149
	v_med3_i32 v80, v80, 0, s99
	v_med3_i32 v83, v83, 0, s99
	v_med3_i32 v99, v99, 0, s99
	v_med3_i32 v253, v253, 0, s99
	v_med3_i32 v254, v254, 0, s99
	v_med3_i32 v255, v255, 0, s99
	v_mad_u32_u24 v80, v80, s100, v252
	v_mad_u32_u24 v83, v83, s100, v252
	v_mad_u32_u24 v99, v99, s100, v252
	v_mad_u32_u24 v253, v253, s100, v252
	v_mad_u32_u24 v254, v254, s100, v153
	v_mad_u32_u24 v255, v255, s100, v153
	global_load_dwordx4 v[156:159], v80, s[82:83]
	global_load_dwordx4 v[160:163], v83, s[82:83]
	global_load_dwordx4 v[164:167], v99, s[82:83]
	global_load_dwordx4 v[168:171], v253, s[82:83]
	global_load_dwordx4 v[172:175], v254, s[82:83] offset:768
	global_load_dwordx4 v[176:179], v255, s[82:83] offset:768
	global_load_dwordx4 v[180:183], v254, s[82:83] offset:832
	global_load_dwordx4 v[184:187], v255, s[82:83] offset:832
	ds_read_b64_tr_b16 v[72:73], v231
	ds_read_b64_tr_b16 v[74:75], v231 offset:512
	ds_read_b64_tr_b16 v[76:77], v231 offset:2048
	ds_read_b64_tr_b16 v[78:79], v231 offset:2560
	ds_read_b64_tr_b16 v[220:221], v231 offset:1024
	ds_read_b64_tr_b16 v[222:223], v231 offset:1536
	ds_read_b64_tr_b16 v[224:225], v231 offset:3072
	ds_read_b64_tr_b16 v[226:227], v231 offset:3584
	s_waitcnt vmcnt(8)
	ds_write_b128 v247, v[116:119]
	ds_write_b128 v247, v[120:123] offset:1024
	ds_write_b128 v247, v[124:127] offset:2048
	ds_write_b128 v247, v[128:131] offset:3072
	ds_read_b128 v[116:119], v248
	ds_read_b128 v[120:123], v249
	ds_read_b128 v[124:127], v250
	ds_read_b128 v[128:131], v251
	ds_write_b128 v112, v[132:135]
	ds_write_b128 v112, v[136:139] offset:1024
	ds_write_b128 v112, v[140:143] offset:2048
	ds_write_b128 v112, v[144:147] offset:3072
	v_exp_f32_e32 v188, v188
	v_exp_f32_e32 v189, v189
	v_exp_f32_e32 v190, v190
	v_exp_f32_e32 v191, v191
	v_exp_f32_e32 v192, v192
	v_exp_f32_e32 v193, v193
	s_waitcnt lgkmcnt(4)
	v_mfma_f32_32x32x16_bf16 v[32:47], v[116:119], v[48:51], v[32:47]
	v_exp_f32_e32 v194, v194
	v_exp_f32_e32 v195, v195
	v_mfma_f32_32x32x16_bf16 v[32:47], v[120:123], v[52:55], v[32:47]
	v_exp_f32_e32 v196, v196
	v_exp_f32_e32 v197, v197
	v_exp_f32_e32 v198, v198
	v_mfma_f32_32x32x16_bf16 v[32:47], v[124:127], v[56:59], v[32:47]
	v_exp_f32_e32 v199, v199
	v_exp_f32_e32 v200, v200
	v_mfma_f32_32x32x16_bf16 v[32:47], v[128:131], v[60:63], v[32:47]
	v_exp_f32_e32 v201, v201
	v_exp_f32_e32 v202, v202
	v_exp_f32_e32 v203, v203
	s_add_i32 s90, s67, 96
	v_add_u32_e32 v84, s90, v107
	v_add_u32_e32 v85, 0, v84
	v_add_u32_e32 v86, 1, v84
	v_add_u32_e32 v87, 2, v84
	v_add_u32_e32 v88, 3, v84
	v_cmp_gt_u32_e64 s[30:31], s98, v85
	v_cmp_gt_u32_e64 s[36:37], s98, v86
	v_cmp_gt_u32_e64 s[78:79], s98, v87
	v_cmp_gt_u32_e64 s[50:51], s98, v88
	v_cndmask_b32_e64 v188, 0, v188, s[30:31]
	v_add_u32_e32 v85, 8, v84
	v_cmp_gt_u32_e64 s[30:31], s98, v85
	v_cndmask_b32_e64 v189, 0, v189, s[36:37]
	v_add_u32_e32 v86, 9, v84
	v_cmp_gt_u32_e64 s[36:37], s98, v86
	v_cndmask_b32_e64 v190, 0, v190, s[78:79]
	v_add_u32_e32 v87, 10, v84
	v_cmp_gt_u32_e64 s[78:79], s98, v87
	v_cndmask_b32_e64 v191, 0, v191, s[50:51]
	v_add_u32_e32 v88, 11, v84
	v_cmp_gt_u32_e64 s[50:51], s98, v88
	v_cndmask_b32_e64 v192, 0, v192, s[30:31]
	v_add_u32_e32 v85, 16, v84
	v_cmp_gt_u32_e64 s[30:31], s98, v85
	v_cndmask_b32_e64 v193, 0, v193, s[36:37]
	v_add_u32_e32 v86, 17, v84
	v_cmp_gt_u32_e64 s[36:37], s98, v86
	v_cndmask_b32_e64 v194, 0, v194, s[78:79]
	v_add_u32_e32 v87, 18, v84
	v_cmp_gt_u32_e64 s[78:79], s98, v87
	v_cndmask_b32_e64 v195, 0, v195, s[50:51]
	v_add_u32_e32 v88, 19, v84
	v_cmp_gt_u32_e64 s[50:51], s98, v88
	v_cndmask_b32_e64 v196, 0, v196, s[30:31]
	v_add_u32_e32 v85, 24, v84
	v_cmp_gt_u32_e64 s[30:31], s98, v85
	v_cndmask_b32_e64 v197, 0, v197, s[36:37]
	v_add_u32_e32 v86, 25, v84
	v_cmp_gt_u32_e64 s[36:37], s98, v86
	v_cndmask_b32_e64 v198, 0, v198, s[78:79]
	v_add_u32_e32 v87, 26, v84
	v_cmp_gt_u32_e64 s[78:79], s98, v87
	v_cndmask_b32_e64 v199, 0, v199, s[50:51]
	v_add_u32_e32 v88, 27, v84
	v_cmp_gt_u32_e64 s[50:51], s98, v88
	v_nop
	v_cndmask_b32_e64 v200, 0, v200, s[30:31]
	v_cndmask_b32_e64 v201, 0, v201, s[36:37]
	v_cndmask_b32_e64 v202, 0, v202, s[78:79]
	v_cndmask_b32_e64 v203, 0, v203, s[50:51]
	v_cvt_pk_bf16_f32 v64, v188, v189
	v_cvt_pk_bf16_f32 v65, v190, v191
	v_cvt_pk_bf16_f32 v66, v192, v193
	v_cvt_pk_bf16_f32 v67, v194, v195
	v_cvt_pk_bf16_f32 v68, v196, v197
	v_cvt_pk_bf16_f32 v69, v198, v199
	v_cvt_pk_bf16_f32 v70, v200, v201
	v_cvt_pk_bf16_f32 v71, v202, v203
	v_pk_add_f32 v[232:233], v[232:233], v[188:189]
	v_pk_add_f32 v[232:233], v[232:233], v[190:191]
	v_pk_add_f32 v[232:233], v[232:233], v[192:193]
	v_pk_add_f32 v[232:233], v[232:233], v[194:195]
	v_pk_add_f32 v[232:233], v[232:233], v[196:197]
	v_pk_add_f32 v[232:233], v[232:233], v[198:199]
	v_pk_add_f32 v[232:233], v[232:233], v[200:201]
	v_pk_add_f32 v[232:233], v[232:233], v[202:203]
	v_add_u32_e32 v115, 952, v115
	ds_read2_b32 v[188:189], v115 offset0:0 offset1:1
	ds_read2_b32 v[190:191], v115 offset0:2 offset1:3
	ds_read2_b32 v[192:193], v115 offset0:8 offset1:9
	ds_read2_b32 v[194:195], v115 offset0:10 offset1:11
	ds_read2_b32 v[196:197], v115 offset0:17 offset1:18
	ds_read2_b32 v[198:199], v115 offset0:19 offset1:20
	ds_read2_b32 v[200:201], v115 offset0:25 offset1:26
	ds_read2_b32 v[202:203], v115 offset0:27 offset1:28
	v_mfma_f32_32x32x16_bf16 v[0:15], v[64:67], v[72:75], v[0:15]
	v_mfma_f32_32x32x16_bf16 v[16:31], v[64:67], v[76:79], v[16:31]
	v_mfma_f32_32x32x16_bf16 v[0:15], v[68:71], v[220:223], v[0:15]
	v_mfma_f32_32x32x16_bf16 v[16:31], v[68:71], v[224:227], v[16:31]
	s_add_i32 s90, s67, 192
	v_add_u32_e32 v80, s90, v235
	v_add_u32_e32 v83, s90, v236
	v_add_u32_e32 v99, s90, v237
	v_add_u32_e32 v253, s90, v238
	v_add_u32_e32 v254, s90, v100
	v_add_u32_e32 v255, s90, v149
	v_med3_i32 v80, v80, 0, s99
	v_med3_i32 v83, v83, 0, s99
	v_med3_i32 v99, v99, 0, s99
	v_med3_i32 v253, v253, 0, s99
	v_med3_i32 v254, v254, 0, s99
	v_med3_i32 v255, v255, 0, s99
	v_mad_u32_u24 v80, v80, s100, v252
	v_mad_u32_u24 v83, v83, s100, v252
	v_mad_u32_u24 v99, v99, s100, v252
	v_mad_u32_u24 v253, v253, s100, v252
	v_mad_u32_u24 v254, v254, s100, v153
	v_mad_u32_u24 v255, v255, s100, v153
	global_load_dwordx4 v[116:119], v80, s[82:83]
	global_load_dwordx4 v[120:123], v83, s[82:83]
	global_load_dwordx4 v[124:127], v99, s[82:83]
	global_load_dwordx4 v[128:131], v253, s[82:83]
	global_load_dwordx4 v[132:135], v254, s[82:83] offset:768
	global_load_dwordx4 v[136:139], v255, s[82:83] offset:768
	global_load_dwordx4 v[140:143], v254, s[82:83] offset:832
	global_load_dwordx4 v[144:147], v255, s[82:83] offset:832
	ds_read_b64_tr_b16 v[72:73], v231
	ds_read_b64_tr_b16 v[74:75], v231 offset:512
	ds_read_b64_tr_b16 v[76:77], v231 offset:2048
	ds_read_b64_tr_b16 v[78:79], v231 offset:2560
	ds_read_b64_tr_b16 v[220:221], v231 offset:1024
	ds_read_b64_tr_b16 v[222:223], v231 offset:1536
	ds_read_b64_tr_b16 v[224:225], v231 offset:3072
	ds_read_b64_tr_b16 v[226:227], v231 offset:3584
	s_waitcnt vmcnt(8)
	ds_write_b128 v247, v[156:159]
	ds_write_b128 v247, v[160:163] offset:1024
	ds_write_b128 v247, v[164:167] offset:2048
	ds_write_b128 v247, v[168:171] offset:3072
	ds_read_b128 v[156:159], v248
	ds_read_b128 v[160:163], v249
	ds_read_b128 v[164:167], v250
	ds_read_b128 v[168:171], v251
	ds_write_b128 v112, v[172:175]
	ds_write_b128 v112, v[176:179] offset:1024
	ds_write_b128 v112, v[180:183] offset:2048
	ds_write_b128 v112, v[184:187] offset:3072
	v_exp_f32_e32 v32, v32
	v_exp_f32_e32 v33, v33
	v_exp_f32_e32 v34, v34
	v_exp_f32_e32 v35, v35
	v_exp_f32_e32 v36, v36
	v_exp_f32_e32 v37, v37
	s_waitcnt lgkmcnt(4)
	v_mfma_f32_32x32x16_bf16 v[188:203], v[156:159], v[48:51], v[188:203]
	v_exp_f32_e32 v38, v38
	v_exp_f32_e32 v39, v39
	v_mfma_f32_32x32x16_bf16 v[188:203], v[160:163], v[52:55], v[188:203]
	v_exp_f32_e32 v40, v40
	v_exp_f32_e32 v41, v41
	v_exp_f32_e32 v42, v42
	v_mfma_f32_32x32x16_bf16 v[188:203], v[164:167], v[56:59], v[188:203]
	v_exp_f32_e32 v43, v43
	v_exp_f32_e32 v44, v44
	v_mfma_f32_32x32x16_bf16 v[188:203], v[168:171], v[60:63], v[188:203]
	v_exp_f32_e32 v45, v45
	v_exp_f32_e32 v46, v46
	v_exp_f32_e32 v47, v47
	s_add_i32 s90, s67, 128
	v_add_u32_e32 v84, s90, v107
	v_add_u32_e32 v85, 0, v84
	v_add_u32_e32 v86, 1, v84
	v_add_u32_e32 v87, 2, v84
	v_add_u32_e32 v88, 3, v84
	v_cmp_gt_u32_e64 s[30:31], s98, v85
	v_cmp_gt_u32_e64 s[36:37], s98, v86
	v_cmp_gt_u32_e64 s[78:79], s98, v87
	v_cmp_gt_u32_e64 s[50:51], s98, v88
	v_cndmask_b32_e64 v32, 0, v32, s[30:31]
	v_add_u32_e32 v85, 8, v84
	v_cmp_gt_u32_e64 s[30:31], s98, v85
	v_cndmask_b32_e64 v33, 0, v33, s[36:37]
	v_add_u32_e32 v86, 9, v84
	v_cmp_gt_u32_e64 s[36:37], s98, v86
	v_cndmask_b32_e64 v34, 0, v34, s[78:79]
	v_add_u32_e32 v87, 10, v84
	v_cmp_gt_u32_e64 s[78:79], s98, v87
	v_cndmask_b32_e64 v35, 0, v35, s[50:51]
	v_add_u32_e32 v88, 11, v84
	v_cmp_gt_u32_e64 s[50:51], s98, v88
	v_cndmask_b32_e64 v36, 0, v36, s[30:31]
	v_add_u32_e32 v85, 16, v84
	v_cmp_gt_u32_e64 s[30:31], s98, v85
	v_cndmask_b32_e64 v37, 0, v37, s[36:37]
	v_add_u32_e32 v86, 17, v84
	v_cmp_gt_u32_e64 s[36:37], s98, v86
	v_cndmask_b32_e64 v38, 0, v38, s[78:79]
	v_add_u32_e32 v87, 18, v84
	v_cmp_gt_u32_e64 s[78:79], s98, v87
	v_cndmask_b32_e64 v39, 0, v39, s[50:51]
	v_add_u32_e32 v88, 19, v84
	v_cmp_gt_u32_e64 s[50:51], s98, v88
	v_cndmask_b32_e64 v40, 0, v40, s[30:31]
	v_add_u32_e32 v85, 24, v84
	v_cmp_gt_u32_e64 s[30:31], s98, v85
	v_cndmask_b32_e64 v41, 0, v41, s[36:37]
	v_add_u32_e32 v86, 25, v84
	v_cmp_gt_u32_e64 s[36:37], s98, v86
	v_cndmask_b32_e64 v42, 0, v42, s[78:79]
	v_add_u32_e32 v87, 26, v84
	v_cmp_gt_u32_e64 s[78:79], s98, v87
	v_cndmask_b32_e64 v43, 0, v43, s[50:51]
	v_add_u32_e32 v88, 27, v84
	v_cmp_gt_u32_e64 s[50:51], s98, v88
	v_nop
	v_cndmask_b32_e64 v44, 0, v44, s[30:31]
	v_cndmask_b32_e64 v45, 0, v45, s[36:37]
	v_cndmask_b32_e64 v46, 0, v46, s[78:79]
	v_cndmask_b32_e64 v47, 0, v47, s[50:51]
	v_cvt_pk_bf16_f32 v64, v32, v33
	v_cvt_pk_bf16_f32 v65, v34, v35
	v_cvt_pk_bf16_f32 v66, v36, v37
	v_cvt_pk_bf16_f32 v67, v38, v39
	v_cvt_pk_bf16_f32 v68, v40, v41
	v_cvt_pk_bf16_f32 v69, v42, v43
	v_cvt_pk_bf16_f32 v70, v44, v45
	v_cvt_pk_bf16_f32 v71, v46, v47
	v_pk_add_f32 v[232:233], v[232:233], v[32:33]
	v_pk_add_f32 v[232:233], v[232:233], v[34:35]
	v_pk_add_f32 v[232:233], v[232:233], v[36:37]
	v_pk_add_f32 v[232:233], v[232:233], v[38:39]
	v_pk_add_f32 v[232:233], v[232:233], v[40:41]
	v_pk_add_f32 v[232:233], v[232:233], v[42:43]
	v_pk_add_f32 v[232:233], v[232:233], v[44:45]
	v_pk_add_f32 v[232:233], v[232:233], v[46:47]
	ds_read2_b32 v[32:33], v115 offset0:34 offset1:35
	ds_read2_b32 v[34:35], v115 offset0:36 offset1:37
	ds_read2_b32 v[36:37], v115 offset0:42 offset1:43
	ds_read2_b32 v[38:39], v115 offset0:44 offset1:45
	ds_read2_b32 v[40:41], v115 offset0:51 offset1:52
	ds_read2_b32 v[42:43], v115 offset0:53 offset1:54
	ds_read2_b32 v[44:45], v115 offset0:59 offset1:60
	ds_read2_b32 v[46:47], v115 offset0:61 offset1:62
	v_mfma_f32_32x32x16_bf16 v[0:15], v[64:67], v[72:75], v[0:15]
	v_mfma_f32_32x32x16_bf16 v[16:31], v[64:67], v[76:79], v[16:31]
	v_mfma_f32_32x32x16_bf16 v[0:15], v[68:71], v[220:223], v[0:15]
	v_mfma_f32_32x32x16_bf16 v[16:31], v[68:71], v[224:227], v[16:31]
	s_add_i32 s90, s67, 224
	v_add_u32_e32 v80, s90, v235
	v_add_u32_e32 v83, s90, v236
	v_add_u32_e32 v99, s90, v237
	v_add_u32_e32 v253, s90, v238
	v_add_u32_e32 v254, s90, v100
	v_add_u32_e32 v255, s90, v149
	v_med3_i32 v80, v80, 0, s99
	v_med3_i32 v83, v83, 0, s99
	v_med3_i32 v99, v99, 0, s99
	v_med3_i32 v253, v253, 0, s99
	v_med3_i32 v254, v254, 0, s99
	v_med3_i32 v255, v255, 0, s99
	v_mad_u32_u24 v80, v80, s100, v252
	v_mad_u32_u24 v83, v83, s100, v252
	v_mad_u32_u24 v99, v99, s100, v252
	v_mad_u32_u24 v253, v253, s100, v252
	v_mad_u32_u24 v254, v254, s100, v153
	v_mad_u32_u24 v255, v255, s100, v153
	global_load_dwordx4 v[156:159], v80, s[82:83]
	global_load_dwordx4 v[160:163], v83, s[82:83]
	global_load_dwordx4 v[164:167], v99, s[82:83]
	global_load_dwordx4 v[168:171], v253, s[82:83]
	global_load_dwordx4 v[172:175], v254, s[82:83] offset:768
	global_load_dwordx4 v[176:179], v255, s[82:83] offset:768
	global_load_dwordx4 v[180:183], v254, s[82:83] offset:832
	global_load_dwordx4 v[184:187], v255, s[82:83] offset:832
	ds_read_b64_tr_b16 v[72:73], v231
	ds_read_b64_tr_b16 v[74:75], v231 offset:512
	ds_read_b64_tr_b16 v[76:77], v231 offset:2048
	ds_read_b64_tr_b16 v[78:79], v231 offset:2560
	ds_read_b64_tr_b16 v[220:221], v231 offset:1024
	ds_read_b64_tr_b16 v[222:223], v231 offset:1536
	ds_read_b64_tr_b16 v[224:225], v231 offset:3072
	ds_read_b64_tr_b16 v[226:227], v231 offset:3584
	s_waitcnt vmcnt(8)
	ds_write_b128 v247, v[116:119]
	ds_write_b128 v247, v[120:123] offset:1024
	ds_write_b128 v247, v[124:127] offset:2048
	ds_write_b128 v247, v[128:131] offset:3072
	ds_read_b128 v[116:119], v248
	ds_read_b128 v[120:123], v249
	ds_read_b128 v[124:127], v250
	ds_read_b128 v[128:131], v251
	ds_write_b128 v112, v[132:135]
	ds_write_b128 v112, v[136:139] offset:1024
	ds_write_b128 v112, v[140:143] offset:2048
	ds_write_b128 v112, v[144:147] offset:3072
	v_exp_f32_e32 v188, v188
	v_exp_f32_e32 v189, v189
	v_exp_f32_e32 v190, v190
	v_exp_f32_e32 v191, v191
	v_exp_f32_e32 v192, v192
	v_exp_f32_e32 v193, v193
	s_waitcnt lgkmcnt(4)
	v_mfma_f32_32x32x16_bf16 v[32:47], v[116:119], v[48:51], v[32:47]
	v_exp_f32_e32 v194, v194
	v_exp_f32_e32 v195, v195
	v_mfma_f32_32x32x16_bf16 v[32:47], v[120:123], v[52:55], v[32:47]
	v_exp_f32_e32 v196, v196
	v_exp_f32_e32 v197, v197
	v_exp_f32_e32 v198, v198
	v_mfma_f32_32x32x16_bf16 v[32:47], v[124:127], v[56:59], v[32:47]
	v_exp_f32_e32 v199, v199
	v_exp_f32_e32 v200, v200
	v_mfma_f32_32x32x16_bf16 v[32:47], v[128:131], v[60:63], v[32:47]
	v_exp_f32_e32 v201, v201
	v_exp_f32_e32 v202, v202
	v_exp_f32_e32 v203, v203
	s_add_i32 s90, s67, 160
	v_add_u32_e32 v84, s90, v107
	v_add_u32_e32 v85, 0, v84
	v_add_u32_e32 v86, 1, v84
	v_add_u32_e32 v87, 2, v84
	v_add_u32_e32 v88, 3, v84
	v_cmp_gt_u32_e64 s[30:31], s98, v85
	v_cmp_gt_u32_e64 s[36:37], s98, v86
	v_cmp_gt_u32_e64 s[78:79], s98, v87
	v_cmp_gt_u32_e64 s[50:51], s98, v88
	v_cndmask_b32_e64 v188, 0, v188, s[30:31]
	v_add_u32_e32 v85, 8, v84
	v_cmp_gt_u32_e64 s[30:31], s98, v85
	v_cndmask_b32_e64 v189, 0, v189, s[36:37]
	v_add_u32_e32 v86, 9, v84
	v_cmp_gt_u32_e64 s[36:37], s98, v86
	v_cndmask_b32_e64 v190, 0, v190, s[78:79]
	v_add_u32_e32 v87, 10, v84
	v_cmp_gt_u32_e64 s[78:79], s98, v87
	v_cndmask_b32_e64 v191, 0, v191, s[50:51]
	v_add_u32_e32 v88, 11, v84
	v_cmp_gt_u32_e64 s[50:51], s98, v88
	v_cndmask_b32_e64 v192, 0, v192, s[30:31]
	v_add_u32_e32 v85, 16, v84
	v_cmp_gt_u32_e64 s[30:31], s98, v85
	v_cndmask_b32_e64 v193, 0, v193, s[36:37]
	v_add_u32_e32 v86, 17, v84
	v_cmp_gt_u32_e64 s[36:37], s98, v86
	v_cndmask_b32_e64 v194, 0, v194, s[78:79]
	v_add_u32_e32 v87, 18, v84
	v_cmp_gt_u32_e64 s[78:79], s98, v87
	v_cndmask_b32_e64 v195, 0, v195, s[50:51]
	v_add_u32_e32 v88, 19, v84
	v_cmp_gt_u32_e64 s[50:51], s98, v88
	v_cndmask_b32_e64 v196, 0, v196, s[30:31]
	v_add_u32_e32 v85, 24, v84
	v_cmp_gt_u32_e64 s[30:31], s98, v85
	v_cndmask_b32_e64 v197, 0, v197, s[36:37]
	v_add_u32_e32 v86, 25, v84
	v_cmp_gt_u32_e64 s[36:37], s98, v86
	v_cndmask_b32_e64 v198, 0, v198, s[78:79]
	v_add_u32_e32 v87, 26, v84
	v_cmp_gt_u32_e64 s[78:79], s98, v87
	v_cndmask_b32_e64 v199, 0, v199, s[50:51]
	v_add_u32_e32 v88, 27, v84
	v_cmp_gt_u32_e64 s[50:51], s98, v88
	v_nop
	v_cndmask_b32_e64 v200, 0, v200, s[30:31]
	v_cndmask_b32_e64 v201, 0, v201, s[36:37]
	v_cndmask_b32_e64 v202, 0, v202, s[78:79]
	v_cndmask_b32_e64 v203, 0, v203, s[50:51]
	v_cvt_pk_bf16_f32 v64, v188, v189
	v_cvt_pk_bf16_f32 v65, v190, v191
	v_cvt_pk_bf16_f32 v66, v192, v193
	v_cvt_pk_bf16_f32 v67, v194, v195
	v_cvt_pk_bf16_f32 v68, v196, v197
	v_cvt_pk_bf16_f32 v69, v198, v199
	v_cvt_pk_bf16_f32 v70, v200, v201
	v_cvt_pk_bf16_f32 v71, v202, v203
	v_pk_add_f32 v[232:233], v[232:233], v[188:189]
	v_pk_add_f32 v[232:233], v[232:233], v[190:191]
	v_pk_add_f32 v[232:233], v[232:233], v[192:193]
	v_pk_add_f32 v[232:233], v[232:233], v[194:195]
	v_pk_add_f32 v[232:233], v[232:233], v[196:197]
	v_pk_add_f32 v[232:233], v[232:233], v[198:199]
	v_pk_add_f32 v[232:233], v[232:233], v[200:201]
	v_pk_add_f32 v[232:233], v[232:233], v[202:203]
	ds_read2_b32 v[188:189], v115 offset0:68 offset1:69
	ds_read2_b32 v[190:191], v115 offset0:70 offset1:71
	ds_read2_b32 v[192:193], v115 offset0:76 offset1:77
	ds_read2_b32 v[194:195], v115 offset0:78 offset1:79
	ds_read2_b32 v[196:197], v115 offset0:85 offset1:86
	ds_read2_b32 v[198:199], v115 offset0:87 offset1:88
	ds_read2_b32 v[200:201], v115 offset0:93 offset1:94
	ds_read2_b32 v[202:203], v115 offset0:95 offset1:96
	v_mfma_f32_32x32x16_bf16 v[0:15], v[64:67], v[72:75], v[0:15]
	v_mfma_f32_32x32x16_bf16 v[16:31], v[64:67], v[76:79], v[16:31]
	v_mfma_f32_32x32x16_bf16 v[0:15], v[68:71], v[220:223], v[0:15]
	v_mfma_f32_32x32x16_bf16 v[16:31], v[68:71], v[224:227], v[16:31]
	s_add_i32 s90, s67, 256
	v_add_u32_e32 v80, s90, v235
	v_add_u32_e32 v83, s90, v236
	v_add_u32_e32 v99, s90, v237
	v_add_u32_e32 v253, s90, v238
	v_add_u32_e32 v254, s90, v100
	v_add_u32_e32 v255, s90, v149
	v_med3_i32 v80, v80, 0, s99
	v_med3_i32 v83, v83, 0, s99
	v_med3_i32 v99, v99, 0, s99
	v_med3_i32 v253, v253, 0, s99
	v_med3_i32 v254, v254, 0, s99
	v_med3_i32 v255, v255, 0, s99
	v_mad_u32_u24 v80, v80, s100, v252
	v_mad_u32_u24 v83, v83, s100, v252
	v_mad_u32_u24 v99, v99, s100, v252
	v_mad_u32_u24 v253, v253, s100, v252
	v_mad_u32_u24 v254, v254, s100, v153
	v_mad_u32_u24 v255, v255, s100, v153
	global_load_dwordx4 v[116:119], v80, s[82:83]
	global_load_dwordx4 v[120:123], v83, s[82:83]
	global_load_dwordx4 v[124:127], v99, s[82:83]
	global_load_dwordx4 v[128:131], v253, s[82:83]
	global_load_dwordx4 v[132:135], v254, s[82:83] offset:768
	global_load_dwordx4 v[136:139], v255, s[82:83] offset:768
	global_load_dwordx4 v[140:143], v254, s[82:83] offset:832
	global_load_dwordx4 v[144:147], v255, s[82:83] offset:832
	ds_read_b64_tr_b16 v[72:73], v231
	ds_read_b64_tr_b16 v[74:75], v231 offset:512
	ds_read_b64_tr_b16 v[76:77], v231 offset:2048
	ds_read_b64_tr_b16 v[78:79], v231 offset:2560
	ds_read_b64_tr_b16 v[220:221], v231 offset:1024
	ds_read_b64_tr_b16 v[222:223], v231 offset:1536
	ds_read_b64_tr_b16 v[224:225], v231 offset:3072
	ds_read_b64_tr_b16 v[226:227], v231 offset:3584
	s_waitcnt vmcnt(8)
	ds_write_b128 v247, v[156:159]
	ds_write_b128 v247, v[160:163] offset:1024
	ds_write_b128 v247, v[164:167] offset:2048
	ds_write_b128 v247, v[168:171] offset:3072
	ds_read_b128 v[156:159], v248
	ds_read_b128 v[160:163], v249
	ds_read_b128 v[164:167], v250
	ds_read_b128 v[168:171], v251
	ds_write_b128 v112, v[172:175]
	ds_write_b128 v112, v[176:179] offset:1024
	ds_write_b128 v112, v[180:183] offset:2048
	ds_write_b128 v112, v[184:187] offset:3072
	v_exp_f32_e32 v32, v32
	v_exp_f32_e32 v33, v33
	v_exp_f32_e32 v34, v34
	v_exp_f32_e32 v35, v35
	v_exp_f32_e32 v36, v36
	v_exp_f32_e32 v37, v37
	s_waitcnt lgkmcnt(4)
	v_mfma_f32_32x32x16_bf16 v[188:203], v[156:159], v[48:51], v[188:203]
	v_exp_f32_e32 v38, v38
	v_exp_f32_e32 v39, v39
	v_mfma_f32_32x32x16_bf16 v[188:203], v[160:163], v[52:55], v[188:203]
	v_exp_f32_e32 v40, v40
	v_exp_f32_e32 v41, v41
	v_exp_f32_e32 v42, v42
	v_mfma_f32_32x32x16_bf16 v[188:203], v[164:167], v[56:59], v[188:203]
	v_exp_f32_e32 v43, v43
	v_exp_f32_e32 v44, v44
	v_mfma_f32_32x32x16_bf16 v[188:203], v[168:171], v[60:63], v[188:203]
	v_exp_f32_e32 v45, v45
	v_exp_f32_e32 v46, v46
	v_exp_f32_e32 v47, v47
	s_add_i32 s90, s67, 192
	v_add_u32_e32 v84, s90, v107
	v_add_u32_e32 v85, 0, v84
	v_add_u32_e32 v86, 1, v84
	v_add_u32_e32 v87, 2, v84
	v_add_u32_e32 v88, 3, v84
	v_cmp_gt_u32_e64 s[30:31], s98, v85
	v_cmp_gt_u32_e64 s[36:37], s98, v86
	v_cmp_gt_u32_e64 s[78:79], s98, v87
	v_cmp_gt_u32_e64 s[50:51], s98, v88
	v_cndmask_b32_e64 v32, 0, v32, s[30:31]
	v_add_u32_e32 v85, 8, v84
	v_cmp_gt_u32_e64 s[30:31], s98, v85
	v_cndmask_b32_e64 v33, 0, v33, s[36:37]
	v_add_u32_e32 v86, 9, v84
	v_cmp_gt_u32_e64 s[36:37], s98, v86
	v_cndmask_b32_e64 v34, 0, v34, s[78:79]
	v_add_u32_e32 v87, 10, v84
	v_cmp_gt_u32_e64 s[78:79], s98, v87
	v_cndmask_b32_e64 v35, 0, v35, s[50:51]
	v_add_u32_e32 v88, 11, v84
	v_cmp_gt_u32_e64 s[50:51], s98, v88
	v_cndmask_b32_e64 v36, 0, v36, s[30:31]
	v_add_u32_e32 v85, 16, v84
	v_cmp_gt_u32_e64 s[30:31], s98, v85
	v_cndmask_b32_e64 v37, 0, v37, s[36:37]
	v_add_u32_e32 v86, 17, v84
	v_cmp_gt_u32_e64 s[36:37], s98, v86
	v_cndmask_b32_e64 v38, 0, v38, s[78:79]
	v_add_u32_e32 v87, 18, v84
	v_cmp_gt_u32_e64 s[78:79], s98, v87
	v_cndmask_b32_e64 v39, 0, v39, s[50:51]
	v_add_u32_e32 v88, 19, v84
	v_cmp_gt_u32_e64 s[50:51], s98, v88
	v_cndmask_b32_e64 v40, 0, v40, s[30:31]
	v_add_u32_e32 v85, 24, v84
	v_cmp_gt_u32_e64 s[30:31], s98, v85
	v_cndmask_b32_e64 v41, 0, v41, s[36:37]
	v_add_u32_e32 v86, 25, v84
	v_cmp_gt_u32_e64 s[36:37], s98, v86
	v_cndmask_b32_e64 v42, 0, v42, s[78:79]
	v_add_u32_e32 v87, 26, v84
	v_cmp_gt_u32_e64 s[78:79], s98, v87
	v_cndmask_b32_e64 v43, 0, v43, s[50:51]
	v_add_u32_e32 v88, 27, v84
	v_cmp_gt_u32_e64 s[50:51], s98, v88
	v_nop
	v_cndmask_b32_e64 v44, 0, v44, s[30:31]
	v_cndmask_b32_e64 v45, 0, v45, s[36:37]
	v_cndmask_b32_e64 v46, 0, v46, s[78:79]
	v_cndmask_b32_e64 v47, 0, v47, s[50:51]
	v_cvt_pk_bf16_f32 v64, v32, v33
	v_cvt_pk_bf16_f32 v65, v34, v35
	v_cvt_pk_bf16_f32 v66, v36, v37
	v_cvt_pk_bf16_f32 v67, v38, v39
	v_cvt_pk_bf16_f32 v68, v40, v41
	v_cvt_pk_bf16_f32 v69, v42, v43
	v_cvt_pk_bf16_f32 v70, v44, v45
	v_cvt_pk_bf16_f32 v71, v46, v47
	v_pk_add_f32 v[232:233], v[232:233], v[32:33]
	v_pk_add_f32 v[232:233], v[232:233], v[34:35]
	v_pk_add_f32 v[232:233], v[232:233], v[36:37]
	v_pk_add_f32 v[232:233], v[232:233], v[38:39]
	v_pk_add_f32 v[232:233], v[232:233], v[40:41]
	v_pk_add_f32 v[232:233], v[232:233], v[42:43]
	v_pk_add_f32 v[232:233], v[232:233], v[44:45]
	v_pk_add_f32 v[232:233], v[232:233], v[46:47]
	ds_read2_b32 v[32:33], v115 offset0:102 offset1:103
	ds_read2_b32 v[34:35], v115 offset0:104 offset1:105
	ds_read2_b32 v[36:37], v115 offset0:110 offset1:111
	ds_read2_b32 v[38:39], v115 offset0:112 offset1:113
	ds_read2_b32 v[40:41], v115 offset0:119 offset1:120
	ds_read2_b32 v[42:43], v115 offset0:121 offset1:122
	ds_read2_b32 v[44:45], v115 offset0:127 offset1:128
	ds_read2_b32 v[46:47], v115 offset0:129 offset1:130
	v_mfma_f32_32x32x16_bf16 v[0:15], v[64:67], v[72:75], v[0:15]
	v_mfma_f32_32x32x16_bf16 v[16:31], v[64:67], v[76:79], v[16:31]
	v_mfma_f32_32x32x16_bf16 v[0:15], v[68:71], v[220:223], v[0:15]
	v_mfma_f32_32x32x16_bf16 v[16:31], v[68:71], v[224:227], v[16:31]
	s_add_i32 s90, s67, 288
	v_add_u32_e32 v80, s90, v235
	v_add_u32_e32 v83, s90, v236
	v_add_u32_e32 v99, s90, v237
	v_add_u32_e32 v253, s90, v238
	v_add_u32_e32 v254, s90, v100
	v_add_u32_e32 v255, s90, v149
	v_med3_i32 v80, v80, 0, s99
	v_med3_i32 v83, v83, 0, s99
	v_med3_i32 v99, v99, 0, s99
	v_med3_i32 v253, v253, 0, s99
	v_med3_i32 v254, v254, 0, s99
	v_med3_i32 v255, v255, 0, s99
	v_mad_u32_u24 v80, v80, s100, v252
	v_mad_u32_u24 v83, v83, s100, v252
	v_mad_u32_u24 v99, v99, s100, v252
	v_mad_u32_u24 v253, v253, s100, v252
	v_mad_u32_u24 v254, v254, s100, v153
	v_mad_u32_u24 v255, v255, s100, v153
	global_load_dwordx4 v[156:159], v80, s[82:83]
	global_load_dwordx4 v[160:163], v83, s[82:83]
	global_load_dwordx4 v[164:167], v99, s[82:83]
	global_load_dwordx4 v[168:171], v253, s[82:83]
	global_load_dwordx4 v[172:175], v254, s[82:83] offset:768
	global_load_dwordx4 v[176:179], v255, s[82:83] offset:768
	global_load_dwordx4 v[180:183], v254, s[82:83] offset:832
	global_load_dwordx4 v[184:187], v255, s[82:83] offset:832
	ds_read_b64_tr_b16 v[72:73], v231
	ds_read_b64_tr_b16 v[74:75], v231 offset:512
	ds_read_b64_tr_b16 v[76:77], v231 offset:2048
	ds_read_b64_tr_b16 v[78:79], v231 offset:2560
	ds_read_b64_tr_b16 v[220:221], v231 offset:1024
	ds_read_b64_tr_b16 v[222:223], v231 offset:1536
	ds_read_b64_tr_b16 v[224:225], v231 offset:3072
	ds_read_b64_tr_b16 v[226:227], v231 offset:3584
	s_waitcnt vmcnt(8)
	ds_write_b128 v247, v[116:119]
	ds_write_b128 v247, v[120:123] offset:1024
	ds_write_b128 v247, v[124:127] offset:2048
	ds_write_b128 v247, v[128:131] offset:3072
	ds_read_b128 v[116:119], v248
	ds_read_b128 v[120:123], v249
	ds_read_b128 v[124:127], v250
	ds_read_b128 v[128:131], v251
	ds_write_b128 v112, v[132:135]
	ds_write_b128 v112, v[136:139] offset:1024
	ds_write_b128 v112, v[140:143] offset:2048
	ds_write_b128 v112, v[144:147] offset:3072
	v_exp_f32_e32 v188, v188
	v_exp_f32_e32 v189, v189
	v_exp_f32_e32 v190, v190
	v_exp_f32_e32 v191, v191
	v_exp_f32_e32 v192, v192
	v_exp_f32_e32 v193, v193
	s_waitcnt lgkmcnt(4)
	v_mfma_f32_32x32x16_bf16 v[32:47], v[116:119], v[48:51], v[32:47]
	v_exp_f32_e32 v194, v194
	v_exp_f32_e32 v195, v195
	v_mfma_f32_32x32x16_bf16 v[32:47], v[120:123], v[52:55], v[32:47]
	v_exp_f32_e32 v196, v196
	v_exp_f32_e32 v197, v197
	v_exp_f32_e32 v198, v198
	v_mfma_f32_32x32x16_bf16 v[32:47], v[124:127], v[56:59], v[32:47]
	v_exp_f32_e32 v199, v199
	v_exp_f32_e32 v200, v200
	v_mfma_f32_32x32x16_bf16 v[32:47], v[128:131], v[60:63], v[32:47]
	v_exp_f32_e32 v201, v201
	v_exp_f32_e32 v202, v202
	v_exp_f32_e32 v203, v203
	s_add_i32 s90, s67, 224
	v_add_u32_e32 v84, s90, v107
	v_add_u32_e32 v85, 0, v84
	v_add_u32_e32 v86, 1, v84
	v_add_u32_e32 v87, 2, v84
	v_add_u32_e32 v88, 3, v84
	v_cmp_gt_u32_e64 s[30:31], s98, v85
	v_cmp_gt_u32_e64 s[36:37], s98, v86
	v_cmp_gt_u32_e64 s[78:79], s98, v87
	v_cmp_gt_u32_e64 s[50:51], s98, v88
	v_cndmask_b32_e64 v188, 0, v188, s[30:31]
	v_add_u32_e32 v85, 8, v84
	v_cmp_gt_u32_e64 s[30:31], s98, v85
	v_cndmask_b32_e64 v189, 0, v189, s[36:37]
	v_add_u32_e32 v86, 9, v84
	v_cmp_gt_u32_e64 s[36:37], s98, v86
	v_cndmask_b32_e64 v190, 0, v190, s[78:79]
	v_add_u32_e32 v87, 10, v84
	v_cmp_gt_u32_e64 s[78:79], s98, v87
	v_cndmask_b32_e64 v191, 0, v191, s[50:51]
	v_add_u32_e32 v88, 11, v84
	v_cmp_gt_u32_e64 s[50:51], s98, v88
	v_cndmask_b32_e64 v192, 0, v192, s[30:31]
	v_add_u32_e32 v85, 16, v84
	v_cmp_gt_u32_e64 s[30:31], s98, v85
	v_cndmask_b32_e64 v193, 0, v193, s[36:37]
	v_add_u32_e32 v86, 17, v84
	v_cmp_gt_u32_e64 s[36:37], s98, v86
	v_cndmask_b32_e64 v194, 0, v194, s[78:79]
	v_add_u32_e32 v87, 18, v84
	v_cmp_gt_u32_e64 s[78:79], s98, v87
	v_cndmask_b32_e64 v195, 0, v195, s[50:51]
	v_add_u32_e32 v88, 19, v84
	v_cmp_gt_u32_e64 s[50:51], s98, v88
	v_cndmask_b32_e64 v196, 0, v196, s[30:31]
	v_add_u32_e32 v85, 24, v84
	v_cmp_gt_u32_e64 s[30:31], s98, v85
	v_cndmask_b32_e64 v197, 0, v197, s[36:37]
	v_add_u32_e32 v86, 25, v84
	v_cmp_gt_u32_e64 s[36:37], s98, v86
	v_cndmask_b32_e64 v198, 0, v198, s[78:79]
	v_add_u32_e32 v87, 26, v84
	v_cmp_gt_u32_e64 s[78:79], s98, v87
	v_cndmask_b32_e64 v199, 0, v199, s[50:51]
	v_add_u32_e32 v88, 27, v84
	v_cmp_gt_u32_e64 s[50:51], s98, v88
	v_nop
	v_cndmask_b32_e64 v200, 0, v200, s[30:31]
	v_cndmask_b32_e64 v201, 0, v201, s[36:37]
	v_cndmask_b32_e64 v202, 0, v202, s[78:79]
	v_cndmask_b32_e64 v203, 0, v203, s[50:51]
	v_cvt_pk_bf16_f32 v64, v188, v189
	v_cvt_pk_bf16_f32 v65, v190, v191
	v_cvt_pk_bf16_f32 v66, v192, v193
	v_cvt_pk_bf16_f32 v67, v194, v195
	v_cvt_pk_bf16_f32 v68, v196, v197
	v_cvt_pk_bf16_f32 v69, v198, v199
	v_cvt_pk_bf16_f32 v70, v200, v201
	v_cvt_pk_bf16_f32 v71, v202, v203
	v_pk_add_f32 v[232:233], v[232:233], v[188:189]
	v_pk_add_f32 v[232:233], v[232:233], v[190:191]
	v_pk_add_f32 v[232:233], v[232:233], v[192:193]
	v_pk_add_f32 v[232:233], v[232:233], v[194:195]
	v_pk_add_f32 v[232:233], v[232:233], v[196:197]
	v_pk_add_f32 v[232:233], v[232:233], v[198:199]
	v_pk_add_f32 v[232:233], v[232:233], v[200:201]
	v_pk_add_f32 v[232:233], v[232:233], v[202:203]
	ds_read2_b32 v[188:189], v115 offset0:136 offset1:137
	ds_read2_b32 v[190:191], v115 offset0:138 offset1:139
	ds_read2_b32 v[192:193], v115 offset0:144 offset1:145
	ds_read2_b32 v[194:195], v115 offset0:146 offset1:147
	ds_read2_b32 v[196:197], v115 offset0:153 offset1:154
	ds_read2_b32 v[198:199], v115 offset0:155 offset1:156
	ds_read2_b32 v[200:201], v115 offset0:161 offset1:162
	ds_read2_b32 v[202:203], v115 offset0:163 offset1:164
	v_mfma_f32_32x32x16_bf16 v[0:15], v[64:67], v[72:75], v[0:15]
	v_mfma_f32_32x32x16_bf16 v[16:31], v[64:67], v[76:79], v[16:31]
	v_mfma_f32_32x32x16_bf16 v[0:15], v[68:71], v[220:223], v[0:15]
	v_mfma_f32_32x32x16_bf16 v[16:31], v[68:71], v[224:227], v[16:31]
	s_add_i32 s90, s67, 320
	v_add_u32_e32 v80, s90, v235
	v_add_u32_e32 v83, s90, v236
	v_add_u32_e32 v99, s90, v237
	v_add_u32_e32 v253, s90, v238
	v_add_u32_e32 v254, s90, v100
	v_add_u32_e32 v255, s90, v149
	v_med3_i32 v80, v80, 0, s99
	v_med3_i32 v83, v83, 0, s99
	v_med3_i32 v99, v99, 0, s99
	v_med3_i32 v253, v253, 0, s99
	v_med3_i32 v254, v254, 0, s99
	v_med3_i32 v255, v255, 0, s99
	v_mad_u32_u24 v80, v80, s100, v252
	v_mad_u32_u24 v83, v83, s100, v252
	v_mad_u32_u24 v99, v99, s100, v252
	v_mad_u32_u24 v253, v253, s100, v252
	v_mad_u32_u24 v254, v254, s100, v153
	v_mad_u32_u24 v255, v255, s100, v153
	global_load_dwordx4 v[116:119], v80, s[82:83]
	global_load_dwordx4 v[120:123], v83, s[82:83]
	global_load_dwordx4 v[124:127], v99, s[82:83]
	global_load_dwordx4 v[128:131], v253, s[82:83]
	global_load_dwordx4 v[132:135], v254, s[82:83] offset:768
	global_load_dwordx4 v[136:139], v255, s[82:83] offset:768
	global_load_dwordx4 v[140:143], v254, s[82:83] offset:832
	global_load_dwordx4 v[144:147], v255, s[82:83] offset:832
	ds_read_b64_tr_b16 v[72:73], v231
	ds_read_b64_tr_b16 v[74:75], v231 offset:512
	ds_read_b64_tr_b16 v[76:77], v231 offset:2048
	ds_read_b64_tr_b16 v[78:79], v231 offset:2560
	ds_read_b64_tr_b16 v[220:221], v231 offset:1024
	ds_read_b64_tr_b16 v[222:223], v231 offset:1536
	ds_read_b64_tr_b16 v[224:225], v231 offset:3072
	ds_read_b64_tr_b16 v[226:227], v231 offset:3584
	s_waitcnt vmcnt(8)
	ds_write_b128 v247, v[156:159]
	ds_write_b128 v247, v[160:163] offset:1024
	ds_write_b128 v247, v[164:167] offset:2048
	ds_write_b128 v247, v[168:171] offset:3072
	ds_read_b128 v[156:159], v248
	ds_read_b128 v[160:163], v249
	ds_read_b128 v[164:167], v250
	ds_read_b128 v[168:171], v251
	ds_write_b128 v112, v[172:175]
	ds_write_b128 v112, v[176:179] offset:1024
	ds_write_b128 v112, v[180:183] offset:2048
	ds_write_b128 v112, v[184:187] offset:3072
	v_exp_f32_e32 v32, v32
	v_exp_f32_e32 v33, v33
	v_exp_f32_e32 v34, v34
	v_exp_f32_e32 v35, v35
	v_exp_f32_e32 v36, v36
	v_exp_f32_e32 v37, v37
	s_waitcnt lgkmcnt(4)
	v_mfma_f32_32x32x16_bf16 v[188:203], v[156:159], v[48:51], v[188:203]
	v_exp_f32_e32 v38, v38
	v_exp_f32_e32 v39, v39
	v_mfma_f32_32x32x16_bf16 v[188:203], v[160:163], v[52:55], v[188:203]
	v_exp_f32_e32 v40, v40
	v_exp_f32_e32 v41, v41
	v_exp_f32_e32 v42, v42
	v_mfma_f32_32x32x16_bf16 v[188:203], v[164:167], v[56:59], v[188:203]
	v_exp_f32_e32 v43, v43
	v_exp_f32_e32 v44, v44
	v_mfma_f32_32x32x16_bf16 v[188:203], v[168:171], v[60:63], v[188:203]
	v_exp_f32_e32 v45, v45
	v_exp_f32_e32 v46, v46
	v_exp_f32_e32 v47, v47
	s_add_i32 s90, s67, 256
	v_add_u32_e32 v84, s90, v107
	v_add_u32_e32 v85, 0, v84
	v_add_u32_e32 v86, 1, v84
	v_add_u32_e32 v87, 2, v84
	v_add_u32_e32 v88, 3, v84
	v_cmp_gt_u32_e64 s[30:31], s98, v85
	v_cmp_gt_u32_e64 s[36:37], s98, v86
	v_cmp_gt_u32_e64 s[78:79], s98, v87
	v_cmp_gt_u32_e64 s[50:51], s98, v88
	v_cndmask_b32_e64 v32, 0, v32, s[30:31]
	v_add_u32_e32 v85, 8, v84
	v_cmp_gt_u32_e64 s[30:31], s98, v85
	v_cndmask_b32_e64 v33, 0, v33, s[36:37]
	v_add_u32_e32 v86, 9, v84
	v_cmp_gt_u32_e64 s[36:37], s98, v86
	v_cndmask_b32_e64 v34, 0, v34, s[78:79]
	v_add_u32_e32 v87, 10, v84
	v_cmp_gt_u32_e64 s[78:79], s98, v87
	v_cndmask_b32_e64 v35, 0, v35, s[50:51]
	v_add_u32_e32 v88, 11, v84
	v_cmp_gt_u32_e64 s[50:51], s98, v88
	v_cndmask_b32_e64 v36, 0, v36, s[30:31]
	v_add_u32_e32 v85, 16, v84
	v_cmp_gt_u32_e64 s[30:31], s98, v85
	v_cndmask_b32_e64 v37, 0, v37, s[36:37]
	v_add_u32_e32 v86, 17, v84
	v_cmp_gt_u32_e64 s[36:37], s98, v86
	v_cndmask_b32_e64 v38, 0, v38, s[78:79]
	v_add_u32_e32 v87, 18, v84
	v_cmp_gt_u32_e64 s[78:79], s98, v87
	v_cndmask_b32_e64 v39, 0, v39, s[50:51]
	v_add_u32_e32 v88, 19, v84
	v_cmp_gt_u32_e64 s[50:51], s98, v88
	v_cndmask_b32_e64 v40, 0, v40, s[30:31]
	v_add_u32_e32 v85, 24, v84
	v_cmp_gt_u32_e64 s[30:31], s98, v85
	v_cndmask_b32_e64 v41, 0, v41, s[36:37]
	v_add_u32_e32 v86, 25, v84
	v_cmp_gt_u32_e64 s[36:37], s98, v86
	v_cndmask_b32_e64 v42, 0, v42, s[78:79]
	v_add_u32_e32 v87, 26, v84
	v_cmp_gt_u32_e64 s[78:79], s98, v87
	v_cndmask_b32_e64 v43, 0, v43, s[50:51]
	v_add_u32_e32 v88, 27, v84
	v_cmp_gt_u32_e64 s[50:51], s98, v88
	v_nop
	v_cndmask_b32_e64 v44, 0, v44, s[30:31]
	v_cndmask_b32_e64 v45, 0, v45, s[36:37]
	v_cndmask_b32_e64 v46, 0, v46, s[78:79]
	v_cndmask_b32_e64 v47, 0, v47, s[50:51]
	v_cvt_pk_bf16_f32 v64, v32, v33
	v_cvt_pk_bf16_f32 v65, v34, v35
	v_cvt_pk_bf16_f32 v66, v36, v37
	v_cvt_pk_bf16_f32 v67, v38, v39
	v_cvt_pk_bf16_f32 v68, v40, v41
	v_cvt_pk_bf16_f32 v69, v42, v43
	v_cvt_pk_bf16_f32 v70, v44, v45
	v_cvt_pk_bf16_f32 v71, v46, v47
	v_pk_add_f32 v[232:233], v[232:233], v[32:33]
	v_pk_add_f32 v[232:233], v[232:233], v[34:35]
	v_pk_add_f32 v[232:233], v[232:233], v[36:37]
	v_pk_add_f32 v[232:233], v[232:233], v[38:39]
	v_pk_add_f32 v[232:233], v[232:233], v[40:41]
	v_pk_add_f32 v[232:233], v[232:233], v[42:43]
	v_pk_add_f32 v[232:233], v[232:233], v[44:45]
	v_pk_add_f32 v[232:233], v[232:233], v[46:47]
	ds_read2_b32 v[32:33], v115 offset0:170 offset1:171
	ds_read2_b32 v[34:35], v115 offset0:172 offset1:173
	ds_read2_b32 v[36:37], v115 offset0:178 offset1:179
	ds_read2_b32 v[38:39], v115 offset0:180 offset1:181
	ds_read2_b32 v[40:41], v115 offset0:187 offset1:188
	ds_read2_b32 v[42:43], v115 offset0:189 offset1:190
	ds_read2_b32 v[44:45], v115 offset0:195 offset1:196
	ds_read2_b32 v[46:47], v115 offset0:197 offset1:198
	v_mfma_f32_32x32x16_bf16 v[0:15], v[64:67], v[72:75], v[0:15]
	v_mfma_f32_32x32x16_bf16 v[16:31], v[64:67], v[76:79], v[16:31]
	v_mfma_f32_32x32x16_bf16 v[0:15], v[68:71], v[220:223], v[0:15]
	v_mfma_f32_32x32x16_bf16 v[16:31], v[68:71], v[224:227], v[16:31]
	s_add_i32 s90, s67, 352
	v_add_u32_e32 v80, s90, v235
	v_add_u32_e32 v83, s90, v236
	v_add_u32_e32 v99, s90, v237
	v_add_u32_e32 v253, s90, v238
	v_add_u32_e32 v254, s90, v100
	v_add_u32_e32 v255, s90, v149
	v_med3_i32 v80, v80, 0, s99
	v_med3_i32 v83, v83, 0, s99
	v_med3_i32 v99, v99, 0, s99
	v_med3_i32 v253, v253, 0, s99
	v_med3_i32 v254, v254, 0, s99
	v_med3_i32 v255, v255, 0, s99
	v_mad_u32_u24 v80, v80, s100, v252
	v_mad_u32_u24 v83, v83, s100, v252
	v_mad_u32_u24 v99, v99, s100, v252
	v_mad_u32_u24 v253, v253, s100, v252
	v_mad_u32_u24 v254, v254, s100, v153
	v_mad_u32_u24 v255, v255, s100, v153
	global_load_dwordx4 v[156:159], v80, s[82:83]
	global_load_dwordx4 v[160:163], v83, s[82:83]
	global_load_dwordx4 v[164:167], v99, s[82:83]
	global_load_dwordx4 v[168:171], v253, s[82:83]
	global_load_dwordx4 v[172:175], v254, s[82:83] offset:768
	global_load_dwordx4 v[176:179], v255, s[82:83] offset:768
	global_load_dwordx4 v[180:183], v254, s[82:83] offset:832
	global_load_dwordx4 v[184:187], v255, s[82:83] offset:832
	ds_read_b64_tr_b16 v[72:73], v231
	ds_read_b64_tr_b16 v[74:75], v231 offset:512
	ds_read_b64_tr_b16 v[76:77], v231 offset:2048
	ds_read_b64_tr_b16 v[78:79], v231 offset:2560
	ds_read_b64_tr_b16 v[220:221], v231 offset:1024
	ds_read_b64_tr_b16 v[222:223], v231 offset:1536
	ds_read_b64_tr_b16 v[224:225], v231 offset:3072
	ds_read_b64_tr_b16 v[226:227], v231 offset:3584
	s_waitcnt vmcnt(8)
	ds_write_b128 v247, v[116:119]
	ds_write_b128 v247, v[120:123] offset:1024
	ds_write_b128 v247, v[124:127] offset:2048
	ds_write_b128 v247, v[128:131] offset:3072
	ds_read_b128 v[116:119], v248
	ds_read_b128 v[120:123], v249
	ds_read_b128 v[124:127], v250
	ds_read_b128 v[128:131], v251
	ds_write_b128 v112, v[132:135]
	ds_write_b128 v112, v[136:139] offset:1024
	ds_write_b128 v112, v[140:143] offset:2048
	ds_write_b128 v112, v[144:147] offset:3072
	v_exp_f32_e32 v188, v188
	v_exp_f32_e32 v189, v189
	v_exp_f32_e32 v190, v190
	v_exp_f32_e32 v191, v191
	v_exp_f32_e32 v192, v192
	v_exp_f32_e32 v193, v193
	s_waitcnt lgkmcnt(4)
	v_mfma_f32_32x32x16_bf16 v[32:47], v[116:119], v[48:51], v[32:47]
	v_exp_f32_e32 v194, v194
	v_exp_f32_e32 v195, v195
	v_mfma_f32_32x32x16_bf16 v[32:47], v[120:123], v[52:55], v[32:47]
	v_exp_f32_e32 v196, v196
	v_exp_f32_e32 v197, v197
	v_exp_f32_e32 v198, v198
	v_mfma_f32_32x32x16_bf16 v[32:47], v[124:127], v[56:59], v[32:47]
	v_exp_f32_e32 v199, v199
	v_exp_f32_e32 v200, v200
	v_mfma_f32_32x32x16_bf16 v[32:47], v[128:131], v[60:63], v[32:47]
	v_exp_f32_e32 v201, v201
	v_exp_f32_e32 v202, v202
	v_exp_f32_e32 v203, v203
	s_add_i32 s90, s67, 288
	v_add_u32_e32 v84, s90, v107
	v_add_u32_e32 v85, 0, v84
	v_add_u32_e32 v86, 1, v84
	v_add_u32_e32 v87, 2, v84
	v_add_u32_e32 v88, 3, v84
	v_cmp_gt_u32_e64 s[30:31], s98, v85
	v_cmp_gt_u32_e64 s[36:37], s98, v86
	v_cmp_gt_u32_e64 s[78:79], s98, v87
	v_cmp_gt_u32_e64 s[50:51], s98, v88
	v_cndmask_b32_e64 v188, 0, v188, s[30:31]
	v_add_u32_e32 v85, 8, v84
	v_cmp_gt_u32_e64 s[30:31], s98, v85
	v_cndmask_b32_e64 v189, 0, v189, s[36:37]
	v_add_u32_e32 v86, 9, v84
	v_cmp_gt_u32_e64 s[36:37], s98, v86
	v_cndmask_b32_e64 v190, 0, v190, s[78:79]
	v_add_u32_e32 v87, 10, v84
	v_cmp_gt_u32_e64 s[78:79], s98, v87
	v_cndmask_b32_e64 v191, 0, v191, s[50:51]
	v_add_u32_e32 v88, 11, v84
	v_cmp_gt_u32_e64 s[50:51], s98, v88
	v_cndmask_b32_e64 v192, 0, v192, s[30:31]
	v_add_u32_e32 v85, 16, v84
	v_cmp_gt_u32_e64 s[30:31], s98, v85
	v_cndmask_b32_e64 v193, 0, v193, s[36:37]
	v_add_u32_e32 v86, 17, v84
	v_cmp_gt_u32_e64 s[36:37], s98, v86
	v_cndmask_b32_e64 v194, 0, v194, s[78:79]
	v_add_u32_e32 v87, 18, v84
	v_cmp_gt_u32_e64 s[78:79], s98, v87
	v_cndmask_b32_e64 v195, 0, v195, s[50:51]
	v_add_u32_e32 v88, 19, v84
	v_cmp_gt_u32_e64 s[50:51], s98, v88
	v_cndmask_b32_e64 v196, 0, v196, s[30:31]
	v_add_u32_e32 v85, 24, v84
	v_cmp_gt_u32_e64 s[30:31], s98, v85
	v_cndmask_b32_e64 v197, 0, v197, s[36:37]
	v_add_u32_e32 v86, 25, v84
	v_cmp_gt_u32_e64 s[36:37], s98, v86
	v_cndmask_b32_e64 v198, 0, v198, s[78:79]
	v_add_u32_e32 v87, 26, v84
	v_cmp_gt_u32_e64 s[78:79], s98, v87
	v_cndmask_b32_e64 v199, 0, v199, s[50:51]
	v_add_u32_e32 v88, 27, v84
	v_cmp_gt_u32_e64 s[50:51], s98, v88
	v_nop
	v_cndmask_b32_e64 v200, 0, v200, s[30:31]
	v_cndmask_b32_e64 v201, 0, v201, s[36:37]
	v_cndmask_b32_e64 v202, 0, v202, s[78:79]
	v_cndmask_b32_e64 v203, 0, v203, s[50:51]
	v_cvt_pk_bf16_f32 v64, v188, v189
	v_cvt_pk_bf16_f32 v65, v190, v191
	v_cvt_pk_bf16_f32 v66, v192, v193
	v_cvt_pk_bf16_f32 v67, v194, v195
	v_cvt_pk_bf16_f32 v68, v196, v197
	v_cvt_pk_bf16_f32 v69, v198, v199
	v_cvt_pk_bf16_f32 v70, v200, v201
	v_cvt_pk_bf16_f32 v71, v202, v203
	v_pk_add_f32 v[232:233], v[232:233], v[188:189]
	v_pk_add_f32 v[232:233], v[232:233], v[190:191]
	v_pk_add_f32 v[232:233], v[232:233], v[192:193]
	v_pk_add_f32 v[232:233], v[232:233], v[194:195]
	v_pk_add_f32 v[232:233], v[232:233], v[196:197]
	v_pk_add_f32 v[232:233], v[232:233], v[198:199]
	v_pk_add_f32 v[232:233], v[232:233], v[200:201]
	v_pk_add_f32 v[232:233], v[232:233], v[202:203]
	ds_read2_b32 v[188:189], v115 offset0:204 offset1:205
	ds_read2_b32 v[190:191], v115 offset0:206 offset1:207
	ds_read2_b32 v[192:193], v115 offset0:212 offset1:213
	ds_read2_b32 v[194:195], v115 offset0:214 offset1:215
	ds_read2_b32 v[196:197], v115 offset0:221 offset1:222
	ds_read2_b32 v[198:199], v115 offset0:223 offset1:224
	ds_read2_b32 v[200:201], v115 offset0:229 offset1:230
	ds_read2_b32 v[202:203], v115 offset0:231 offset1:232
	v_mfma_f32_32x32x16_bf16 v[0:15], v[64:67], v[72:75], v[0:15]
	v_mfma_f32_32x32x16_bf16 v[16:31], v[64:67], v[76:79], v[16:31]
	v_mfma_f32_32x32x16_bf16 v[0:15], v[68:71], v[220:223], v[0:15]
	v_mfma_f32_32x32x16_bf16 v[16:31], v[68:71], v[224:227], v[16:31]
	s_add_i32 s90, s67, 384
	v_add_u32_e32 v80, s90, v235
	v_add_u32_e32 v83, s90, v236
	v_add_u32_e32 v99, s90, v237
	v_add_u32_e32 v253, s90, v238
	v_add_u32_e32 v254, s90, v100
	v_add_u32_e32 v255, s90, v149
	v_med3_i32 v80, v80, 0, s99
	v_med3_i32 v83, v83, 0, s99
	v_med3_i32 v99, v99, 0, s99
	v_med3_i32 v253, v253, 0, s99
	v_med3_i32 v254, v254, 0, s99
	v_med3_i32 v255, v255, 0, s99
	v_mad_u32_u24 v80, v80, s100, v252
	v_mad_u32_u24 v83, v83, s100, v252
	v_mad_u32_u24 v99, v99, s100, v252
	v_mad_u32_u24 v253, v253, s100, v252
	v_mad_u32_u24 v254, v254, s100, v153
	v_mad_u32_u24 v255, v255, s100, v153
	global_load_dwordx4 v[116:119], v80, s[82:83]
	global_load_dwordx4 v[120:123], v83, s[82:83]
	global_load_dwordx4 v[124:127], v99, s[82:83]
	global_load_dwordx4 v[128:131], v253, s[82:83]
	global_load_dwordx4 v[132:135], v254, s[82:83] offset:768
	global_load_dwordx4 v[136:139], v255, s[82:83] offset:768
	global_load_dwordx4 v[140:143], v254, s[82:83] offset:832
	global_load_dwordx4 v[144:147], v255, s[82:83] offset:832
	ds_read_b64_tr_b16 v[72:73], v231
	ds_read_b64_tr_b16 v[74:75], v231 offset:512
	ds_read_b64_tr_b16 v[76:77], v231 offset:2048
	ds_read_b64_tr_b16 v[78:79], v231 offset:2560
	ds_read_b64_tr_b16 v[220:221], v231 offset:1024
	ds_read_b64_tr_b16 v[222:223], v231 offset:1536
	ds_read_b64_tr_b16 v[224:225], v231 offset:3072
	ds_read_b64_tr_b16 v[226:227], v231 offset:3584
	s_waitcnt vmcnt(8)
	ds_write_b128 v247, v[156:159]
	ds_write_b128 v247, v[160:163] offset:1024
	ds_write_b128 v247, v[164:167] offset:2048
	ds_write_b128 v247, v[168:171] offset:3072
	ds_read_b128 v[156:159], v248
	ds_read_b128 v[160:163], v249
	ds_read_b128 v[164:167], v250
	ds_read_b128 v[168:171], v251
	ds_write_b128 v112, v[172:175]
	ds_write_b128 v112, v[176:179] offset:1024
	ds_write_b128 v112, v[180:183] offset:2048
	ds_write_b128 v112, v[184:187] offset:3072
	v_exp_f32_e32 v32, v32
	v_exp_f32_e32 v33, v33
	v_exp_f32_e32 v34, v34
	v_exp_f32_e32 v35, v35
	v_exp_f32_e32 v36, v36
	v_exp_f32_e32 v37, v37
	s_waitcnt lgkmcnt(4)
	v_mfma_f32_32x32x16_bf16 v[188:203], v[156:159], v[48:51], v[188:203]
	v_exp_f32_e32 v38, v38
	v_exp_f32_e32 v39, v39
	v_mfma_f32_32x32x16_bf16 v[188:203], v[160:163], v[52:55], v[188:203]
	v_exp_f32_e32 v40, v40
	v_exp_f32_e32 v41, v41
	v_exp_f32_e32 v42, v42
	v_mfma_f32_32x32x16_bf16 v[188:203], v[164:167], v[56:59], v[188:203]
	v_exp_f32_e32 v43, v43
	v_exp_f32_e32 v44, v44
	v_mfma_f32_32x32x16_bf16 v[188:203], v[168:171], v[60:63], v[188:203]
	v_exp_f32_e32 v45, v45
	v_exp_f32_e32 v46, v46
	v_exp_f32_e32 v47, v47
	s_add_i32 s90, s67, 320
	v_add_u32_e32 v84, s90, v107
	v_add_u32_e32 v85, 0, v84
	v_add_u32_e32 v86, 1, v84
	v_add_u32_e32 v87, 2, v84
	v_add_u32_e32 v88, 3, v84
	v_cmp_gt_u32_e64 s[30:31], s98, v85
	v_cmp_gt_u32_e64 s[36:37], s98, v86
	v_cmp_gt_u32_e64 s[78:79], s98, v87
	v_cmp_gt_u32_e64 s[50:51], s98, v88
	v_cndmask_b32_e64 v32, 0, v32, s[30:31]
	v_add_u32_e32 v85, 8, v84
	v_cmp_gt_u32_e64 s[30:31], s98, v85
	v_cndmask_b32_e64 v33, 0, v33, s[36:37]
	v_add_u32_e32 v86, 9, v84
	v_cmp_gt_u32_e64 s[36:37], s98, v86
	v_cndmask_b32_e64 v34, 0, v34, s[78:79]
	v_add_u32_e32 v87, 10, v84
	v_cmp_gt_u32_e64 s[78:79], s98, v87
	v_cndmask_b32_e64 v35, 0, v35, s[50:51]
	v_add_u32_e32 v88, 11, v84
	v_cmp_gt_u32_e64 s[50:51], s98, v88
	v_cndmask_b32_e64 v36, 0, v36, s[30:31]
	v_add_u32_e32 v85, 16, v84
	v_cmp_gt_u32_e64 s[30:31], s98, v85
	v_cndmask_b32_e64 v37, 0, v37, s[36:37]
	v_add_u32_e32 v86, 17, v84
	v_cmp_gt_u32_e64 s[36:37], s98, v86
	v_cndmask_b32_e64 v38, 0, v38, s[78:79]
	v_add_u32_e32 v87, 18, v84
	v_cmp_gt_u32_e64 s[78:79], s98, v87
	v_cndmask_b32_e64 v39, 0, v39, s[50:51]
	v_add_u32_e32 v88, 19, v84
	v_cmp_gt_u32_e64 s[50:51], s98, v88
	v_cndmask_b32_e64 v40, 0, v40, s[30:31]
	v_add_u32_e32 v85, 24, v84
	v_cmp_gt_u32_e64 s[30:31], s98, v85
	v_cndmask_b32_e64 v41, 0, v41, s[36:37]
	v_add_u32_e32 v86, 25, v84
	v_cmp_gt_u32_e64 s[36:37], s98, v86
	v_cndmask_b32_e64 v42, 0, v42, s[78:79]
	v_add_u32_e32 v87, 26, v84
	v_cmp_gt_u32_e64 s[78:79], s98, v87
	v_cndmask_b32_e64 v43, 0, v43, s[50:51]
	v_add_u32_e32 v88, 27, v84
	v_cmp_gt_u32_e64 s[50:51], s98, v88
	v_nop
	v_cndmask_b32_e64 v44, 0, v44, s[30:31]
	v_cndmask_b32_e64 v45, 0, v45, s[36:37]
	v_cndmask_b32_e64 v46, 0, v46, s[78:79]
	v_cndmask_b32_e64 v47, 0, v47, s[50:51]
	v_cvt_pk_bf16_f32 v64, v32, v33
	v_cvt_pk_bf16_f32 v65, v34, v35
	v_cvt_pk_bf16_f32 v66, v36, v37
	v_cvt_pk_bf16_f32 v67, v38, v39
	v_cvt_pk_bf16_f32 v68, v40, v41
	v_cvt_pk_bf16_f32 v69, v42, v43
	v_cvt_pk_bf16_f32 v70, v44, v45
	v_cvt_pk_bf16_f32 v71, v46, v47
	v_pk_add_f32 v[232:233], v[232:233], v[32:33]
	v_pk_add_f32 v[232:233], v[232:233], v[34:35]
	v_pk_add_f32 v[232:233], v[232:233], v[36:37]
	v_pk_add_f32 v[232:233], v[232:233], v[38:39]
	v_pk_add_f32 v[232:233], v[232:233], v[40:41]
	v_pk_add_f32 v[232:233], v[232:233], v[42:43]
	v_pk_add_f32 v[232:233], v[232:233], v[44:45]
	v_pk_add_f32 v[232:233], v[232:233], v[46:47]
	v_add_u32_e32 v115, 952, v115
	ds_read2_b32 v[32:33], v115 offset0:0 offset1:1
	ds_read2_b32 v[34:35], v115 offset0:2 offset1:3
	ds_read2_b32 v[36:37], v115 offset0:8 offset1:9
	ds_read2_b32 v[38:39], v115 offset0:10 offset1:11
	ds_read2_b32 v[40:41], v115 offset0:17 offset1:18
	ds_read2_b32 v[42:43], v115 offset0:19 offset1:20
	ds_read2_b32 v[44:45], v115 offset0:25 offset1:26
	ds_read2_b32 v[46:47], v115 offset0:27 offset1:28
	v_mfma_f32_32x32x16_bf16 v[0:15], v[64:67], v[72:75], v[0:15]
	v_mfma_f32_32x32x16_bf16 v[16:31], v[64:67], v[76:79], v[16:31]
	v_mfma_f32_32x32x16_bf16 v[0:15], v[68:71], v[220:223], v[0:15]
	v_mfma_f32_32x32x16_bf16 v[16:31], v[68:71], v[224:227], v[16:31]
	s_add_i32 s90, s67, 416
	v_add_u32_e32 v80, s90, v235
	v_add_u32_e32 v83, s90, v236
	v_add_u32_e32 v99, s90, v237
	v_add_u32_e32 v253, s90, v238
	v_add_u32_e32 v254, s90, v100
	v_add_u32_e32 v255, s90, v149
	v_med3_i32 v80, v80, 0, s99
	v_med3_i32 v83, v83, 0, s99
	v_med3_i32 v99, v99, 0, s99
	v_med3_i32 v253, v253, 0, s99
	v_med3_i32 v254, v254, 0, s99
	v_med3_i32 v255, v255, 0, s99
	v_mad_u32_u24 v80, v80, s100, v252
	v_mad_u32_u24 v83, v83, s100, v252
	v_mad_u32_u24 v99, v99, s100, v252
	v_mad_u32_u24 v253, v253, s100, v252
	v_mad_u32_u24 v254, v254, s100, v153
	v_mad_u32_u24 v255, v255, s100, v153
	global_load_dwordx4 v[156:159], v80, s[82:83]
	global_load_dwordx4 v[160:163], v83, s[82:83]
	global_load_dwordx4 v[164:167], v99, s[82:83]
	global_load_dwordx4 v[168:171], v253, s[82:83]
	global_load_dwordx4 v[172:175], v254, s[82:83] offset:768
	global_load_dwordx4 v[176:179], v255, s[82:83] offset:768
	global_load_dwordx4 v[180:183], v254, s[82:83] offset:832
	global_load_dwordx4 v[184:187], v255, s[82:83] offset:832
	ds_read_b64_tr_b16 v[72:73], v231
	ds_read_b64_tr_b16 v[74:75], v231 offset:512
	ds_read_b64_tr_b16 v[76:77], v231 offset:2048
	ds_read_b64_tr_b16 v[78:79], v231 offset:2560
	ds_read_b64_tr_b16 v[220:221], v231 offset:1024
	ds_read_b64_tr_b16 v[222:223], v231 offset:1536
	ds_read_b64_tr_b16 v[224:225], v231 offset:3072
	ds_read_b64_tr_b16 v[226:227], v231 offset:3584
	s_waitcnt vmcnt(8)
	ds_write_b128 v247, v[116:119]
	ds_write_b128 v247, v[120:123] offset:1024
	ds_write_b128 v247, v[124:127] offset:2048
	ds_write_b128 v247, v[128:131] offset:3072
	ds_read_b128 v[116:119], v248
	ds_read_b128 v[120:123], v249
	ds_read_b128 v[124:127], v250
	ds_read_b128 v[128:131], v251
	ds_write_b128 v112, v[132:135]
	ds_write_b128 v112, v[136:139] offset:1024
	ds_write_b128 v112, v[140:143] offset:2048
	ds_write_b128 v112, v[144:147] offset:3072
	v_exp_f32_e32 v188, v188
	v_exp_f32_e32 v189, v189
	v_exp_f32_e32 v190, v190
	v_exp_f32_e32 v191, v191
	v_exp_f32_e32 v192, v192
	v_exp_f32_e32 v193, v193
	s_waitcnt lgkmcnt(4)
	v_mfma_f32_32x32x16_bf16 v[32:47], v[116:119], v[48:51], v[32:47]
	v_exp_f32_e32 v194, v194
	v_exp_f32_e32 v195, v195
	v_mfma_f32_32x32x16_bf16 v[32:47], v[120:123], v[52:55], v[32:47]
	v_exp_f32_e32 v196, v196
	v_exp_f32_e32 v197, v197
	v_exp_f32_e32 v198, v198
	v_mfma_f32_32x32x16_bf16 v[32:47], v[124:127], v[56:59], v[32:47]
	v_exp_f32_e32 v199, v199
	v_exp_f32_e32 v200, v200
	v_mfma_f32_32x32x16_bf16 v[32:47], v[128:131], v[60:63], v[32:47]
	v_exp_f32_e32 v201, v201
	v_exp_f32_e32 v202, v202
	v_exp_f32_e32 v203, v203
	s_add_i32 s90, s67, 352
	v_add_u32_e32 v84, s90, v107
	v_add_u32_e32 v85, 0, v84
	v_add_u32_e32 v86, 1, v84
	v_add_u32_e32 v87, 2, v84
	v_add_u32_e32 v88, 3, v84
	v_cmp_gt_u32_e64 s[30:31], s98, v85
	v_cmp_gt_u32_e64 s[36:37], s98, v86
	v_cmp_gt_u32_e64 s[78:79], s98, v87
	v_cmp_gt_u32_e64 s[50:51], s98, v88
	v_cndmask_b32_e64 v188, 0, v188, s[30:31]
	v_add_u32_e32 v85, 8, v84
	v_cmp_gt_u32_e64 s[30:31], s98, v85
	v_cndmask_b32_e64 v189, 0, v189, s[36:37]
	v_add_u32_e32 v86, 9, v84
	v_cmp_gt_u32_e64 s[36:37], s98, v86
	v_cndmask_b32_e64 v190, 0, v190, s[78:79]
	v_add_u32_e32 v87, 10, v84
	v_cmp_gt_u32_e64 s[78:79], s98, v87
	v_cndmask_b32_e64 v191, 0, v191, s[50:51]
	v_add_u32_e32 v88, 11, v84
	v_cmp_gt_u32_e64 s[50:51], s98, v88
	v_cndmask_b32_e64 v192, 0, v192, s[30:31]
	v_add_u32_e32 v85, 16, v84
	v_cmp_gt_u32_e64 s[30:31], s98, v85
	v_cndmask_b32_e64 v193, 0, v193, s[36:37]
	v_add_u32_e32 v86, 17, v84
	v_cmp_gt_u32_e64 s[36:37], s98, v86
	v_cndmask_b32_e64 v194, 0, v194, s[78:79]
	v_add_u32_e32 v87, 18, v84
	v_cmp_gt_u32_e64 s[78:79], s98, v87
	v_cndmask_b32_e64 v195, 0, v195, s[50:51]
	v_add_u32_e32 v88, 19, v84
	v_cmp_gt_u32_e64 s[50:51], s98, v88
	v_cndmask_b32_e64 v196, 0, v196, s[30:31]
	v_add_u32_e32 v85, 24, v84
	v_cmp_gt_u32_e64 s[30:31], s98, v85
	v_cndmask_b32_e64 v197, 0, v197, s[36:37]
	v_add_u32_e32 v86, 25, v84
	v_cmp_gt_u32_e64 s[36:37], s98, v86
	v_cndmask_b32_e64 v198, 0, v198, s[78:79]
	v_add_u32_e32 v87, 26, v84
	v_cmp_gt_u32_e64 s[78:79], s98, v87
	v_cndmask_b32_e64 v199, 0, v199, s[50:51]
	v_add_u32_e32 v88, 27, v84
	v_cmp_gt_u32_e64 s[50:51], s98, v88
	v_nop
	v_cndmask_b32_e64 v200, 0, v200, s[30:31]
	v_cndmask_b32_e64 v201, 0, v201, s[36:37]
	v_cndmask_b32_e64 v202, 0, v202, s[78:79]
	v_cndmask_b32_e64 v203, 0, v203, s[50:51]
	v_cvt_pk_bf16_f32 v64, v188, v189
	v_cvt_pk_bf16_f32 v65, v190, v191
	v_cvt_pk_bf16_f32 v66, v192, v193
	v_cvt_pk_bf16_f32 v67, v194, v195
	v_cvt_pk_bf16_f32 v68, v196, v197
	v_cvt_pk_bf16_f32 v69, v198, v199
	v_cvt_pk_bf16_f32 v70, v200, v201
	v_cvt_pk_bf16_f32 v71, v202, v203
	v_pk_add_f32 v[232:233], v[232:233], v[188:189]
	v_pk_add_f32 v[232:233], v[232:233], v[190:191]
	v_pk_add_f32 v[232:233], v[232:233], v[192:193]
	v_pk_add_f32 v[232:233], v[232:233], v[194:195]
	v_pk_add_f32 v[232:233], v[232:233], v[196:197]
	v_pk_add_f32 v[232:233], v[232:233], v[198:199]
	v_pk_add_f32 v[232:233], v[232:233], v[200:201]
	v_pk_add_f32 v[232:233], v[232:233], v[202:203]
	ds_read2_b32 v[188:189], v115 offset0:34 offset1:35
	ds_read2_b32 v[190:191], v115 offset0:36 offset1:37
	ds_read2_b32 v[192:193], v115 offset0:42 offset1:43
	ds_read2_b32 v[194:195], v115 offset0:44 offset1:45
	ds_read2_b32 v[196:197], v115 offset0:51 offset1:52
	ds_read2_b32 v[198:199], v115 offset0:53 offset1:54
	ds_read2_b32 v[200:201], v115 offset0:59 offset1:60
	ds_read2_b32 v[202:203], v115 offset0:61 offset1:62
	v_mfma_f32_32x32x16_bf16 v[0:15], v[64:67], v[72:75], v[0:15]
	v_mfma_f32_32x32x16_bf16 v[16:31], v[64:67], v[76:79], v[16:31]
	v_mfma_f32_32x32x16_bf16 v[0:15], v[68:71], v[220:223], v[0:15]
	v_mfma_f32_32x32x16_bf16 v[16:31], v[68:71], v[224:227], v[16:31]
	s_add_i32 s90, s67, 448
	v_add_u32_e32 v80, s90, v235
	v_add_u32_e32 v83, s90, v236
	v_add_u32_e32 v99, s90, v237
	v_add_u32_e32 v253, s90, v238
	v_add_u32_e32 v254, s90, v100
	v_add_u32_e32 v255, s90, v149
	v_med3_i32 v80, v80, 0, s99
	v_med3_i32 v83, v83, 0, s99
	v_med3_i32 v99, v99, 0, s99
	v_med3_i32 v253, v253, 0, s99
	v_med3_i32 v254, v254, 0, s99
	v_med3_i32 v255, v255, 0, s99
	v_mad_u32_u24 v80, v80, s100, v252
	v_mad_u32_u24 v83, v83, s100, v252
	v_mad_u32_u24 v99, v99, s100, v252
	v_mad_u32_u24 v253, v253, s100, v252
	v_mad_u32_u24 v254, v254, s100, v153
	v_mad_u32_u24 v255, v255, s100, v153
	global_load_dwordx4 v[116:119], v80, s[82:83]
	global_load_dwordx4 v[120:123], v83, s[82:83]
	global_load_dwordx4 v[124:127], v99, s[82:83]
	global_load_dwordx4 v[128:131], v253, s[82:83]
	global_load_dwordx4 v[132:135], v254, s[82:83] offset:768
	global_load_dwordx4 v[136:139], v255, s[82:83] offset:768
	global_load_dwordx4 v[140:143], v254, s[82:83] offset:832
	global_load_dwordx4 v[144:147], v255, s[82:83] offset:832
	ds_read_b64_tr_b16 v[72:73], v231
	ds_read_b64_tr_b16 v[74:75], v231 offset:512
	ds_read_b64_tr_b16 v[76:77], v231 offset:2048
	ds_read_b64_tr_b16 v[78:79], v231 offset:2560
	ds_read_b64_tr_b16 v[220:221], v231 offset:1024
	ds_read_b64_tr_b16 v[222:223], v231 offset:1536
	ds_read_b64_tr_b16 v[224:225], v231 offset:3072
	ds_read_b64_tr_b16 v[226:227], v231 offset:3584
	s_waitcnt vmcnt(8)
	ds_write_b128 v247, v[156:159]
	ds_write_b128 v247, v[160:163] offset:1024
	ds_write_b128 v247, v[164:167] offset:2048
	ds_write_b128 v247, v[168:171] offset:3072
	ds_read_b128 v[156:159], v248
	ds_read_b128 v[160:163], v249
	ds_read_b128 v[164:167], v250
	ds_read_b128 v[168:171], v251
	ds_write_b128 v112, v[172:175]
	ds_write_b128 v112, v[176:179] offset:1024
	ds_write_b128 v112, v[180:183] offset:2048
	ds_write_b128 v112, v[184:187] offset:3072
	v_exp_f32_e32 v32, v32
	v_exp_f32_e32 v33, v33
	v_exp_f32_e32 v34, v34
	v_exp_f32_e32 v35, v35
	v_exp_f32_e32 v36, v36
	v_exp_f32_e32 v37, v37
	s_waitcnt lgkmcnt(4)
	v_mfma_f32_32x32x16_bf16 v[188:203], v[156:159], v[48:51], v[188:203]
	v_exp_f32_e32 v38, v38
	v_exp_f32_e32 v39, v39
	v_mfma_f32_32x32x16_bf16 v[188:203], v[160:163], v[52:55], v[188:203]
	v_exp_f32_e32 v40, v40
	v_exp_f32_e32 v41, v41
	v_exp_f32_e32 v42, v42
	v_mfma_f32_32x32x16_bf16 v[188:203], v[164:167], v[56:59], v[188:203]
	v_exp_f32_e32 v43, v43
	v_exp_f32_e32 v44, v44
	v_mfma_f32_32x32x16_bf16 v[188:203], v[168:171], v[60:63], v[188:203]
	v_exp_f32_e32 v45, v45
	v_exp_f32_e32 v46, v46
	v_exp_f32_e32 v47, v47
	s_add_i32 s90, s67, 384
	v_add_u32_e32 v84, s90, v107
	v_add_u32_e32 v85, 0, v84
	v_add_u32_e32 v86, 1, v84
	v_add_u32_e32 v87, 2, v84
	v_add_u32_e32 v88, 3, v84
	v_cmp_gt_u32_e64 s[30:31], s98, v85
	v_cmp_gt_u32_e64 s[36:37], s98, v86
	v_cmp_gt_u32_e64 s[78:79], s98, v87
	v_cmp_gt_u32_e64 s[50:51], s98, v88
	v_cndmask_b32_e64 v32, 0, v32, s[30:31]
	v_add_u32_e32 v85, 8, v84
	v_cmp_gt_u32_e64 s[30:31], s98, v85
	v_cndmask_b32_e64 v33, 0, v33, s[36:37]
	v_add_u32_e32 v86, 9, v84
	v_cmp_gt_u32_e64 s[36:37], s98, v86
	v_cndmask_b32_e64 v34, 0, v34, s[78:79]
	v_add_u32_e32 v87, 10, v84
	v_cmp_gt_u32_e64 s[78:79], s98, v87
	v_cndmask_b32_e64 v35, 0, v35, s[50:51]
	v_add_u32_e32 v88, 11, v84
	v_cmp_gt_u32_e64 s[50:51], s98, v88
	v_cndmask_b32_e64 v36, 0, v36, s[30:31]
	v_add_u32_e32 v85, 16, v84
	v_cmp_gt_u32_e64 s[30:31], s98, v85
	v_cndmask_b32_e64 v37, 0, v37, s[36:37]
	v_add_u32_e32 v86, 17, v84
	v_cmp_gt_u32_e64 s[36:37], s98, v86
	v_cndmask_b32_e64 v38, 0, v38, s[78:79]
	v_add_u32_e32 v87, 18, v84
	v_cmp_gt_u32_e64 s[78:79], s98, v87
	v_cndmask_b32_e64 v39, 0, v39, s[50:51]
	v_add_u32_e32 v88, 19, v84
	v_cmp_gt_u32_e64 s[50:51], s98, v88
	v_cndmask_b32_e64 v40, 0, v40, s[30:31]
	v_add_u32_e32 v85, 24, v84
	v_cmp_gt_u32_e64 s[30:31], s98, v85
	v_cndmask_b32_e64 v41, 0, v41, s[36:37]
	v_add_u32_e32 v86, 25, v84
	v_cmp_gt_u32_e64 s[36:37], s98, v86
	v_cndmask_b32_e64 v42, 0, v42, s[78:79]
	v_add_u32_e32 v87, 26, v84
	v_cmp_gt_u32_e64 s[78:79], s98, v87
	v_cndmask_b32_e64 v43, 0, v43, s[50:51]
	v_add_u32_e32 v88, 27, v84
	v_cmp_gt_u32_e64 s[50:51], s98, v88
	v_nop
	v_cndmask_b32_e64 v44, 0, v44, s[30:31]
	v_cndmask_b32_e64 v45, 0, v45, s[36:37]
	v_cndmask_b32_e64 v46, 0, v46, s[78:79]
	v_cndmask_b32_e64 v47, 0, v47, s[50:51]
	v_cvt_pk_bf16_f32 v64, v32, v33
	v_cvt_pk_bf16_f32 v65, v34, v35
	v_cvt_pk_bf16_f32 v66, v36, v37
	v_cvt_pk_bf16_f32 v67, v38, v39
	v_cvt_pk_bf16_f32 v68, v40, v41
	v_cvt_pk_bf16_f32 v69, v42, v43
	v_cvt_pk_bf16_f32 v70, v44, v45
	v_cvt_pk_bf16_f32 v71, v46, v47
	v_pk_add_f32 v[232:233], v[232:233], v[32:33]
	v_pk_add_f32 v[232:233], v[232:233], v[34:35]
	v_pk_add_f32 v[232:233], v[232:233], v[36:37]
	v_pk_add_f32 v[232:233], v[232:233], v[38:39]
	v_pk_add_f32 v[232:233], v[232:233], v[40:41]
	v_pk_add_f32 v[232:233], v[232:233], v[42:43]
	v_pk_add_f32 v[232:233], v[232:233], v[44:45]
	v_pk_add_f32 v[232:233], v[232:233], v[46:47]
	ds_read2_b32 v[32:33], v115 offset0:68 offset1:69
	ds_read2_b32 v[34:35], v115 offset0:70 offset1:71
	ds_read2_b32 v[36:37], v115 offset0:76 offset1:77
	ds_read2_b32 v[38:39], v115 offset0:78 offset1:79
	ds_read2_b32 v[40:41], v115 offset0:85 offset1:86
	ds_read2_b32 v[42:43], v115 offset0:87 offset1:88
	ds_read2_b32 v[44:45], v115 offset0:93 offset1:94
	ds_read2_b32 v[46:47], v115 offset0:95 offset1:96
	v_mfma_f32_32x32x16_bf16 v[0:15], v[64:67], v[72:75], v[0:15]
	v_mfma_f32_32x32x16_bf16 v[16:31], v[64:67], v[76:79], v[16:31]
	v_mfma_f32_32x32x16_bf16 v[0:15], v[68:71], v[220:223], v[0:15]
	v_mfma_f32_32x32x16_bf16 v[16:31], v[68:71], v[224:227], v[16:31]
	s_add_i32 s90, s67, 480
	v_add_u32_e32 v80, s90, v235
	v_add_u32_e32 v83, s90, v236
	v_add_u32_e32 v99, s90, v237
	v_add_u32_e32 v253, s90, v238
	v_add_u32_e32 v254, s90, v100
	v_add_u32_e32 v255, s90, v149
	v_med3_i32 v80, v80, 0, s99
	v_med3_i32 v83, v83, 0, s99
	v_med3_i32 v99, v99, 0, s99
	v_med3_i32 v253, v253, 0, s99
	v_med3_i32 v254, v254, 0, s99
	v_med3_i32 v255, v255, 0, s99
	v_mad_u32_u24 v80, v80, s100, v252
	v_mad_u32_u24 v83, v83, s100, v252
	v_mad_u32_u24 v99, v99, s100, v252
	v_mad_u32_u24 v253, v253, s100, v252
	v_mad_u32_u24 v254, v254, s100, v153
	v_mad_u32_u24 v255, v255, s100, v153
	global_load_dwordx4 v[156:159], v80, s[82:83]
	global_load_dwordx4 v[160:163], v83, s[82:83]
	global_load_dwordx4 v[164:167], v99, s[82:83]
	global_load_dwordx4 v[168:171], v253, s[82:83]
	global_load_dwordx4 v[172:175], v254, s[82:83] offset:768
	global_load_dwordx4 v[176:179], v255, s[82:83] offset:768
	global_load_dwordx4 v[180:183], v254, s[82:83] offset:832
	global_load_dwordx4 v[184:187], v255, s[82:83] offset:832
	ds_read_b64_tr_b16 v[72:73], v231
	ds_read_b64_tr_b16 v[74:75], v231 offset:512
	ds_read_b64_tr_b16 v[76:77], v231 offset:2048
	ds_read_b64_tr_b16 v[78:79], v231 offset:2560
	ds_read_b64_tr_b16 v[220:221], v231 offset:1024
	ds_read_b64_tr_b16 v[222:223], v231 offset:1536
	ds_read_b64_tr_b16 v[224:225], v231 offset:3072
	ds_read_b64_tr_b16 v[226:227], v231 offset:3584
	s_waitcnt vmcnt(8)
	ds_write_b128 v247, v[116:119]
	ds_write_b128 v247, v[120:123] offset:1024
	ds_write_b128 v247, v[124:127] offset:2048
	ds_write_b128 v247, v[128:131] offset:3072
	ds_read_b128 v[116:119], v248
	ds_read_b128 v[120:123], v249
	ds_read_b128 v[124:127], v250
	ds_read_b128 v[128:131], v251
	ds_write_b128 v112, v[132:135]
	ds_write_b128 v112, v[136:139] offset:1024
	ds_write_b128 v112, v[140:143] offset:2048
	ds_write_b128 v112, v[144:147] offset:3072
	v_exp_f32_e32 v188, v188
	v_exp_f32_e32 v189, v189
	v_exp_f32_e32 v190, v190
	v_exp_f32_e32 v191, v191
	v_exp_f32_e32 v192, v192
	v_exp_f32_e32 v193, v193
	s_waitcnt lgkmcnt(4)
	v_mfma_f32_32x32x16_bf16 v[32:47], v[116:119], v[48:51], v[32:47]
	v_exp_f32_e32 v194, v194
	v_exp_f32_e32 v195, v195
	v_mfma_f32_32x32x16_bf16 v[32:47], v[120:123], v[52:55], v[32:47]
	v_exp_f32_e32 v196, v196
	v_exp_f32_e32 v197, v197
	v_exp_f32_e32 v198, v198
	v_mfma_f32_32x32x16_bf16 v[32:47], v[124:127], v[56:59], v[32:47]
	v_exp_f32_e32 v199, v199
	v_exp_f32_e32 v200, v200
	v_mfma_f32_32x32x16_bf16 v[32:47], v[128:131], v[60:63], v[32:47]
	v_exp_f32_e32 v201, v201
	v_exp_f32_e32 v202, v202
	v_exp_f32_e32 v203, v203
	s_add_i32 s90, s67, 416
	v_add_u32_e32 v84, s90, v107
	v_add_u32_e32 v85, 0, v84
	v_add_u32_e32 v86, 1, v84
	v_add_u32_e32 v87, 2, v84
	v_add_u32_e32 v88, 3, v84
	v_cmp_gt_u32_e64 s[30:31], s98, v85
	v_cmp_gt_u32_e64 s[36:37], s98, v86
	v_cmp_gt_u32_e64 s[78:79], s98, v87
	v_cmp_gt_u32_e64 s[50:51], s98, v88
	v_cndmask_b32_e64 v188, 0, v188, s[30:31]
	v_add_u32_e32 v85, 8, v84
	v_cmp_gt_u32_e64 s[30:31], s98, v85
	v_cndmask_b32_e64 v189, 0, v189, s[36:37]
	v_add_u32_e32 v86, 9, v84
	v_cmp_gt_u32_e64 s[36:37], s98, v86
	v_cndmask_b32_e64 v190, 0, v190, s[78:79]
	v_add_u32_e32 v87, 10, v84
	v_cmp_gt_u32_e64 s[78:79], s98, v87
	v_cndmask_b32_e64 v191, 0, v191, s[50:51]
	v_add_u32_e32 v88, 11, v84
	v_cmp_gt_u32_e64 s[50:51], s98, v88
	v_cndmask_b32_e64 v192, 0, v192, s[30:31]
	v_add_u32_e32 v85, 16, v84
	v_cmp_gt_u32_e64 s[30:31], s98, v85
	v_cndmask_b32_e64 v193, 0, v193, s[36:37]
	v_add_u32_e32 v86, 17, v84
	v_cmp_gt_u32_e64 s[36:37], s98, v86
	v_cndmask_b32_e64 v194, 0, v194, s[78:79]
	v_add_u32_e32 v87, 18, v84
	v_cmp_gt_u32_e64 s[78:79], s98, v87
	v_cndmask_b32_e64 v195, 0, v195, s[50:51]
	v_add_u32_e32 v88, 19, v84
	v_cmp_gt_u32_e64 s[50:51], s98, v88
	v_cndmask_b32_e64 v196, 0, v196, s[30:31]
	v_add_u32_e32 v85, 24, v84
	v_cmp_gt_u32_e64 s[30:31], s98, v85
	v_cndmask_b32_e64 v197, 0, v197, s[36:37]
	v_add_u32_e32 v86, 25, v84
	v_cmp_gt_u32_e64 s[36:37], s98, v86
	v_cndmask_b32_e64 v198, 0, v198, s[78:79]
	v_add_u32_e32 v87, 26, v84
	v_cmp_gt_u32_e64 s[78:79], s98, v87
	v_cndmask_b32_e64 v199, 0, v199, s[50:51]
	v_add_u32_e32 v88, 27, v84
	v_cmp_gt_u32_e64 s[50:51], s98, v88
	v_nop
	v_cndmask_b32_e64 v200, 0, v200, s[30:31]
	v_cndmask_b32_e64 v201, 0, v201, s[36:37]
	v_cndmask_b32_e64 v202, 0, v202, s[78:79]
	v_cndmask_b32_e64 v203, 0, v203, s[50:51]
	v_cvt_pk_bf16_f32 v64, v188, v189
	v_cvt_pk_bf16_f32 v65, v190, v191
	v_cvt_pk_bf16_f32 v66, v192, v193
	v_cvt_pk_bf16_f32 v67, v194, v195
	v_cvt_pk_bf16_f32 v68, v196, v197
	v_cvt_pk_bf16_f32 v69, v198, v199
	v_cvt_pk_bf16_f32 v70, v200, v201
	v_cvt_pk_bf16_f32 v71, v202, v203
	v_pk_add_f32 v[232:233], v[232:233], v[188:189]
	v_pk_add_f32 v[232:233], v[232:233], v[190:191]
	v_pk_add_f32 v[232:233], v[232:233], v[192:193]
	v_pk_add_f32 v[232:233], v[232:233], v[194:195]
	v_pk_add_f32 v[232:233], v[232:233], v[196:197]
	v_pk_add_f32 v[232:233], v[232:233], v[198:199]
	v_pk_add_f32 v[232:233], v[232:233], v[200:201]
	v_pk_add_f32 v[232:233], v[232:233], v[202:203]
	ds_read2_b32 v[188:189], v115 offset0:102 offset1:103
	ds_read2_b32 v[190:191], v115 offset0:104 offset1:105
	ds_read2_b32 v[192:193], v115 offset0:110 offset1:111
	ds_read2_b32 v[194:195], v115 offset0:112 offset1:113
	ds_read2_b32 v[196:197], v115 offset0:119 offset1:120
	ds_read2_b32 v[198:199], v115 offset0:121 offset1:122
	ds_read2_b32 v[200:201], v115 offset0:127 offset1:128
	ds_read2_b32 v[202:203], v115 offset0:129 offset1:130
	v_mfma_f32_32x32x16_bf16 v[0:15], v[64:67], v[72:75], v[0:15]
	v_mfma_f32_32x32x16_bf16 v[16:31], v[64:67], v[76:79], v[16:31]
	v_mfma_f32_32x32x16_bf16 v[0:15], v[68:71], v[220:223], v[0:15]
	v_mfma_f32_32x32x16_bf16 v[16:31], v[68:71], v[224:227], v[16:31]
	s_add_i32 s90, s67, 512
	v_add_u32_e32 v80, s90, v235
	v_add_u32_e32 v83, s90, v236
	v_add_u32_e32 v99, s90, v237
	v_add_u32_e32 v253, s90, v238
	v_add_u32_e32 v254, s90, v100
	v_add_u32_e32 v255, s90, v149
	v_med3_i32 v80, v80, 0, s99
	v_med3_i32 v83, v83, 0, s99
	v_med3_i32 v99, v99, 0, s99
	v_med3_i32 v253, v253, 0, s99
	v_med3_i32 v254, v254, 0, s99
	v_med3_i32 v255, v255, 0, s99
	v_mad_u32_u24 v80, v80, s100, v252
	v_mad_u32_u24 v83, v83, s100, v252
	v_mad_u32_u24 v99, v99, s100, v252
	v_mad_u32_u24 v253, v253, s100, v252
	v_mad_u32_u24 v254, v254, s100, v153
	v_mad_u32_u24 v255, v255, s100, v153
	global_load_dwordx4 v[116:119], v80, s[82:83]
	global_load_dwordx4 v[120:123], v83, s[82:83]
	global_load_dwordx4 v[124:127], v99, s[82:83]
	global_load_dwordx4 v[128:131], v253, s[82:83]
	global_load_dwordx4 v[132:135], v254, s[82:83] offset:768
	global_load_dwordx4 v[136:139], v255, s[82:83] offset:768
	global_load_dwordx4 v[140:143], v254, s[82:83] offset:832
	global_load_dwordx4 v[144:147], v255, s[82:83] offset:832
	ds_read_b64_tr_b16 v[72:73], v231
	ds_read_b64_tr_b16 v[74:75], v231 offset:512
	ds_read_b64_tr_b16 v[76:77], v231 offset:2048
	ds_read_b64_tr_b16 v[78:79], v231 offset:2560
	ds_read_b64_tr_b16 v[220:221], v231 offset:1024
	ds_read_b64_tr_b16 v[222:223], v231 offset:1536
	ds_read_b64_tr_b16 v[224:225], v231 offset:3072
	ds_read_b64_tr_b16 v[226:227], v231 offset:3584
	s_waitcnt vmcnt(8)
	ds_write_b128 v247, v[156:159]
	ds_write_b128 v247, v[160:163] offset:1024
	ds_write_b128 v247, v[164:167] offset:2048
	ds_write_b128 v247, v[168:171] offset:3072
	ds_read_b128 v[156:159], v248
	ds_read_b128 v[160:163], v249
	ds_read_b128 v[164:167], v250
	ds_read_b128 v[168:171], v251
	ds_write_b128 v112, v[172:175]
	ds_write_b128 v112, v[176:179] offset:1024
	ds_write_b128 v112, v[180:183] offset:2048
	ds_write_b128 v112, v[184:187] offset:3072
	v_exp_f32_e32 v32, v32
	v_exp_f32_e32 v33, v33
	v_exp_f32_e32 v34, v34
	v_exp_f32_e32 v35, v35
	v_exp_f32_e32 v36, v36
	v_exp_f32_e32 v37, v37
	s_waitcnt lgkmcnt(4)
	v_mfma_f32_32x32x16_bf16 v[188:203], v[156:159], v[48:51], v[188:203]
	v_exp_f32_e32 v38, v38
	v_exp_f32_e32 v39, v39
	v_mfma_f32_32x32x16_bf16 v[188:203], v[160:163], v[52:55], v[188:203]
	v_exp_f32_e32 v40, v40
	v_exp_f32_e32 v41, v41
	v_exp_f32_e32 v42, v42
	v_mfma_f32_32x32x16_bf16 v[188:203], v[164:167], v[56:59], v[188:203]
	v_exp_f32_e32 v43, v43
	v_exp_f32_e32 v44, v44
	v_mfma_f32_32x32x16_bf16 v[188:203], v[168:171], v[60:63], v[188:203]
	v_exp_f32_e32 v45, v45
	v_exp_f32_e32 v46, v46
	v_exp_f32_e32 v47, v47
	s_add_i32 s90, s67, 448
	v_add_u32_e32 v84, s90, v107
	v_add_u32_e32 v85, 0, v84
	v_add_u32_e32 v86, 1, v84
	v_add_u32_e32 v87, 2, v84
	v_add_u32_e32 v88, 3, v84
	v_cmp_gt_u32_e64 s[30:31], s98, v85
	v_cmp_gt_u32_e64 s[36:37], s98, v86
	v_cmp_gt_u32_e64 s[78:79], s98, v87
	v_cmp_gt_u32_e64 s[50:51], s98, v88
	v_cndmask_b32_e64 v32, 0, v32, s[30:31]
	v_add_u32_e32 v85, 8, v84
	v_cmp_gt_u32_e64 s[30:31], s98, v85
	v_cndmask_b32_e64 v33, 0, v33, s[36:37]
	v_add_u32_e32 v86, 9, v84
	v_cmp_gt_u32_e64 s[36:37], s98, v86
	v_cndmask_b32_e64 v34, 0, v34, s[78:79]
	v_add_u32_e32 v87, 10, v84
	v_cmp_gt_u32_e64 s[78:79], s98, v87
	v_cndmask_b32_e64 v35, 0, v35, s[50:51]
	v_add_u32_e32 v88, 11, v84
	v_cmp_gt_u32_e64 s[50:51], s98, v88
	v_cndmask_b32_e64 v36, 0, v36, s[30:31]
	v_add_u32_e32 v85, 16, v84
	v_cmp_gt_u32_e64 s[30:31], s98, v85
	v_cndmask_b32_e64 v37, 0, v37, s[36:37]
	v_add_u32_e32 v86, 17, v84
	v_cmp_gt_u32_e64 s[36:37], s98, v86
	v_cndmask_b32_e64 v38, 0, v38, s[78:79]
	v_add_u32_e32 v87, 18, v84
	v_cmp_gt_u32_e64 s[78:79], s98, v87
	v_cndmask_b32_e64 v39, 0, v39, s[50:51]
	v_add_u32_e32 v88, 19, v84
	v_cmp_gt_u32_e64 s[50:51], s98, v88
	v_cndmask_b32_e64 v40, 0, v40, s[30:31]
	v_add_u32_e32 v85, 24, v84
	v_cmp_gt_u32_e64 s[30:31], s98, v85
	v_cndmask_b32_e64 v41, 0, v41, s[36:37]
	v_add_u32_e32 v86, 25, v84
	v_cmp_gt_u32_e64 s[36:37], s98, v86
	v_cndmask_b32_e64 v42, 0, v42, s[78:79]
	v_add_u32_e32 v87, 26, v84
	v_cmp_gt_u32_e64 s[78:79], s98, v87
	v_cndmask_b32_e64 v43, 0, v43, s[50:51]
	v_add_u32_e32 v88, 27, v84
	v_cmp_gt_u32_e64 s[50:51], s98, v88
	v_nop
	v_cndmask_b32_e64 v44, 0, v44, s[30:31]
	v_cndmask_b32_e64 v45, 0, v45, s[36:37]
	v_cndmask_b32_e64 v46, 0, v46, s[78:79]
	v_cndmask_b32_e64 v47, 0, v47, s[50:51]
	v_cvt_pk_bf16_f32 v64, v32, v33
	v_cvt_pk_bf16_f32 v65, v34, v35
	v_cvt_pk_bf16_f32 v66, v36, v37
	v_cvt_pk_bf16_f32 v67, v38, v39
	v_cvt_pk_bf16_f32 v68, v40, v41
	v_cvt_pk_bf16_f32 v69, v42, v43
	v_cvt_pk_bf16_f32 v70, v44, v45
	v_cvt_pk_bf16_f32 v71, v46, v47
	v_pk_add_f32 v[232:233], v[232:233], v[32:33]
	v_pk_add_f32 v[232:233], v[232:233], v[34:35]
	v_pk_add_f32 v[232:233], v[232:233], v[36:37]
	v_pk_add_f32 v[232:233], v[232:233], v[38:39]
	v_pk_add_f32 v[232:233], v[232:233], v[40:41]
	v_pk_add_f32 v[232:233], v[232:233], v[42:43]
	v_pk_add_f32 v[232:233], v[232:233], v[44:45]
	v_pk_add_f32 v[232:233], v[232:233], v[46:47]
	ds_read2_b32 v[32:33], v115 offset0:136 offset1:137
	ds_read2_b32 v[34:35], v115 offset0:138 offset1:139
	ds_read2_b32 v[36:37], v115 offset0:144 offset1:145
	ds_read2_b32 v[38:39], v115 offset0:146 offset1:147
	ds_read2_b32 v[40:41], v115 offset0:153 offset1:154
	ds_read2_b32 v[42:43], v115 offset0:155 offset1:156
	ds_read2_b32 v[44:45], v115 offset0:161 offset1:162
	ds_read2_b32 v[46:47], v115 offset0:163 offset1:164
	v_mfma_f32_32x32x16_bf16 v[0:15], v[64:67], v[72:75], v[0:15]
	v_mfma_f32_32x32x16_bf16 v[16:31], v[64:67], v[76:79], v[16:31]
	v_mfma_f32_32x32x16_bf16 v[0:15], v[68:71], v[220:223], v[0:15]
	v_mfma_f32_32x32x16_bf16 v[16:31], v[68:71], v[224:227], v[16:31]
	s_add_i32 s90, s67, 544
	v_add_u32_e32 v80, s90, v235
	v_add_u32_e32 v83, s90, v236
	v_add_u32_e32 v99, s90, v237
	v_add_u32_e32 v253, s90, v238
	v_add_u32_e32 v254, s90, v100
	v_add_u32_e32 v255, s90, v149
	v_med3_i32 v80, v80, 0, s99
	v_med3_i32 v83, v83, 0, s99
	v_med3_i32 v99, v99, 0, s99
	v_med3_i32 v253, v253, 0, s99
	v_med3_i32 v254, v254, 0, s99
	v_med3_i32 v255, v255, 0, s99
	v_mad_u32_u24 v80, v80, s100, v252
	v_mad_u32_u24 v83, v83, s100, v252
	v_mad_u32_u24 v99, v99, s100, v252
	v_mad_u32_u24 v253, v253, s100, v252
	v_mad_u32_u24 v254, v254, s100, v153
	v_mad_u32_u24 v255, v255, s100, v153
	global_load_dwordx4 v[156:159], v80, s[82:83]
	global_load_dwordx4 v[160:163], v83, s[82:83]
	global_load_dwordx4 v[164:167], v99, s[82:83]
	global_load_dwordx4 v[168:171], v253, s[82:83]
	global_load_dwordx4 v[172:175], v254, s[82:83] offset:768
	global_load_dwordx4 v[176:179], v255, s[82:83] offset:768
	global_load_dwordx4 v[180:183], v254, s[82:83] offset:832
	global_load_dwordx4 v[184:187], v255, s[82:83] offset:832
	ds_read_b64_tr_b16 v[72:73], v231
	ds_read_b64_tr_b16 v[74:75], v231 offset:512
	ds_read_b64_tr_b16 v[76:77], v231 offset:2048
	ds_read_b64_tr_b16 v[78:79], v231 offset:2560
	ds_read_b64_tr_b16 v[220:221], v231 offset:1024
	ds_read_b64_tr_b16 v[222:223], v231 offset:1536
	ds_read_b64_tr_b16 v[224:225], v231 offset:3072
	ds_read_b64_tr_b16 v[226:227], v231 offset:3584
	s_waitcnt vmcnt(8)
	ds_write_b128 v247, v[116:119]
	ds_write_b128 v247, v[120:123] offset:1024
	ds_write_b128 v247, v[124:127] offset:2048
	ds_write_b128 v247, v[128:131] offset:3072
	ds_read_b128 v[116:119], v248
	ds_read_b128 v[120:123], v249
	ds_read_b128 v[124:127], v250
	ds_read_b128 v[128:131], v251
	ds_write_b128 v112, v[132:135]
	ds_write_b128 v112, v[136:139] offset:1024
	ds_write_b128 v112, v[140:143] offset:2048
	ds_write_b128 v112, v[144:147] offset:3072
	v_exp_f32_e32 v188, v188
	v_exp_f32_e32 v189, v189
	v_exp_f32_e32 v190, v190
	v_exp_f32_e32 v191, v191
	v_exp_f32_e32 v192, v192
	v_exp_f32_e32 v193, v193
	s_waitcnt lgkmcnt(4)
	v_mfma_f32_32x32x16_bf16 v[32:47], v[116:119], v[48:51], v[32:47]
	v_exp_f32_e32 v194, v194
	v_exp_f32_e32 v195, v195
	v_mfma_f32_32x32x16_bf16 v[32:47], v[120:123], v[52:55], v[32:47]
	v_exp_f32_e32 v196, v196
	v_exp_f32_e32 v197, v197
	v_exp_f32_e32 v198, v198
	v_mfma_f32_32x32x16_bf16 v[32:47], v[124:127], v[56:59], v[32:47]
	v_exp_f32_e32 v199, v199
	v_exp_f32_e32 v200, v200
	v_mfma_f32_32x32x16_bf16 v[32:47], v[128:131], v[60:63], v[32:47]
	v_exp_f32_e32 v201, v201
	v_exp_f32_e32 v202, v202
	v_exp_f32_e32 v203, v203
	s_add_i32 s90, s67, 480
	v_add_u32_e32 v84, s90, v107
	v_add_u32_e32 v85, 0, v84
	v_add_u32_e32 v86, 1, v84
	v_add_u32_e32 v87, 2, v84
	v_add_u32_e32 v88, 3, v84
	v_cmp_gt_u32_e64 s[30:31], s98, v85
	v_cmp_gt_u32_e64 s[36:37], s98, v86
	v_cmp_gt_u32_e64 s[78:79], s98, v87
	v_cmp_gt_u32_e64 s[50:51], s98, v88
	v_cndmask_b32_e64 v188, 0, v188, s[30:31]
	v_add_u32_e32 v85, 8, v84
	v_cmp_gt_u32_e64 s[30:31], s98, v85
	v_cndmask_b32_e64 v189, 0, v189, s[36:37]
	v_add_u32_e32 v86, 9, v84
	v_cmp_gt_u32_e64 s[36:37], s98, v86
	v_cndmask_b32_e64 v190, 0, v190, s[78:79]
	v_add_u32_e32 v87, 10, v84
	v_cmp_gt_u32_e64 s[78:79], s98, v87
	v_cndmask_b32_e64 v191, 0, v191, s[50:51]
	v_add_u32_e32 v88, 11, v84
	v_cmp_gt_u32_e64 s[50:51], s98, v88
	v_cndmask_b32_e64 v192, 0, v192, s[30:31]
	v_add_u32_e32 v85, 16, v84
	v_cmp_gt_u32_e64 s[30:31], s98, v85
	v_cndmask_b32_e64 v193, 0, v193, s[36:37]
	v_add_u32_e32 v86, 17, v84
	v_cmp_gt_u32_e64 s[36:37], s98, v86
	v_cndmask_b32_e64 v194, 0, v194, s[78:79]
	v_add_u32_e32 v87, 18, v84
	v_cmp_gt_u32_e64 s[78:79], s98, v87
	v_cndmask_b32_e64 v195, 0, v195, s[50:51]
	v_add_u32_e32 v88, 19, v84
	v_cmp_gt_u32_e64 s[50:51], s98, v88
	v_cndmask_b32_e64 v196, 0, v196, s[30:31]
	v_add_u32_e32 v85, 24, v84
	v_cmp_gt_u32_e64 s[30:31], s98, v85
	v_cndmask_b32_e64 v197, 0, v197, s[36:37]
	v_add_u32_e32 v86, 25, v84
	v_cmp_gt_u32_e64 s[36:37], s98, v86
	v_cndmask_b32_e64 v198, 0, v198, s[78:79]
	v_add_u32_e32 v87, 26, v84
	v_cmp_gt_u32_e64 s[78:79], s98, v87
	v_cndmask_b32_e64 v199, 0, v199, s[50:51]
	v_add_u32_e32 v88, 27, v84
	v_cmp_gt_u32_e64 s[50:51], s98, v88
	v_nop
	v_cndmask_b32_e64 v200, 0, v200, s[30:31]
	v_cndmask_b32_e64 v201, 0, v201, s[36:37]
	v_cndmask_b32_e64 v202, 0, v202, s[78:79]
	v_cndmask_b32_e64 v203, 0, v203, s[50:51]
	v_cvt_pk_bf16_f32 v64, v188, v189
	v_cvt_pk_bf16_f32 v65, v190, v191
	v_cvt_pk_bf16_f32 v66, v192, v193
	v_cvt_pk_bf16_f32 v67, v194, v195
	v_cvt_pk_bf16_f32 v68, v196, v197
	v_cvt_pk_bf16_f32 v69, v198, v199
	v_cvt_pk_bf16_f32 v70, v200, v201
	v_cvt_pk_bf16_f32 v71, v202, v203
	v_pk_add_f32 v[232:233], v[232:233], v[188:189]
	v_pk_add_f32 v[232:233], v[232:233], v[190:191]
	v_pk_add_f32 v[232:233], v[232:233], v[192:193]
	v_pk_add_f32 v[232:233], v[232:233], v[194:195]
	v_pk_add_f32 v[232:233], v[232:233], v[196:197]
	v_pk_add_f32 v[232:233], v[232:233], v[198:199]
	v_pk_add_f32 v[232:233], v[232:233], v[200:201]
	v_pk_add_f32 v[232:233], v[232:233], v[202:203]
	ds_read2_b32 v[188:189], v115 offset0:170 offset1:171
	ds_read2_b32 v[190:191], v115 offset0:172 offset1:173
	ds_read2_b32 v[192:193], v115 offset0:178 offset1:179
	ds_read2_b32 v[194:195], v115 offset0:180 offset1:181
	ds_read2_b32 v[196:197], v115 offset0:187 offset1:188
	ds_read2_b32 v[198:199], v115 offset0:189 offset1:190
	ds_read2_b32 v[200:201], v115 offset0:195 offset1:196
	ds_read2_b32 v[202:203], v115 offset0:197 offset1:198
	v_mfma_f32_32x32x16_bf16 v[0:15], v[64:67], v[72:75], v[0:15]
	v_mfma_f32_32x32x16_bf16 v[16:31], v[64:67], v[76:79], v[16:31]
	v_mfma_f32_32x32x16_bf16 v[0:15], v[68:71], v[220:223], v[0:15]
	v_mfma_f32_32x32x16_bf16 v[16:31], v[68:71], v[224:227], v[16:31]
	s_add_i32 s90, s67, -256
	v_add_u32_e32 v80, s90, v239
	v_add_u32_e32 v83, s90, v240
	v_add_u32_e32 v99, s90, v241
	v_add_u32_e32 v253, s90, v242
	v_add_u32_e32 v254, s90, v101
	v_add_u32_e32 v255, s90, v150
	v_med3_i32 v80, v80, 0, s99
	v_med3_i32 v83, v83, 0, s99
	v_med3_i32 v99, v99, 0, s99
	v_med3_i32 v253, v253, 0, s99
	v_med3_i32 v254, v254, 0, s99
	v_med3_i32 v255, v255, 0, s99
	v_mad_u32_u24 v80, v80, s100, v252
	v_mad_u32_u24 v83, v83, s100, v252
	v_mad_u32_u24 v99, v99, s100, v252
	v_mad_u32_u24 v253, v253, s100, v252
	v_mad_u32_u24 v254, v254, s100, v153
	v_mad_u32_u24 v255, v255, s100, v153
	global_load_dwordx4 v[116:119], v80, s[82:83]
	global_load_dwordx4 v[120:123], v83, s[82:83]
	global_load_dwordx4 v[124:127], v99, s[82:83]
	global_load_dwordx4 v[128:131], v253, s[82:83]
	global_load_dwordx4 v[132:135], v254, s[82:83] offset:768
	global_load_dwordx4 v[136:139], v255, s[82:83] offset:768
	global_load_dwordx4 v[140:143], v254, s[82:83] offset:832
	global_load_dwordx4 v[144:147], v255, s[82:83] offset:832
	ds_read_b64_tr_b16 v[72:73], v231
	ds_read_b64_tr_b16 v[74:75], v231 offset:512
	ds_read_b64_tr_b16 v[76:77], v231 offset:2048
	ds_read_b64_tr_b16 v[78:79], v231 offset:2560
	ds_read_b64_tr_b16 v[220:221], v231 offset:1024
	ds_read_b64_tr_b16 v[222:223], v231 offset:1536
	ds_read_b64_tr_b16 v[224:225], v231 offset:3072
	ds_read_b64_tr_b16 v[226:227], v231 offset:3584
	s_waitcnt vmcnt(8)
	ds_write_b128 v247, v[156:159]
	ds_write_b128 v247, v[160:163] offset:1024
	ds_write_b128 v247, v[164:167] offset:2048
	ds_write_b128 v247, v[168:171] offset:3072
	ds_read_b128 v[156:159], v248
	ds_read_b128 v[160:163], v249
	ds_read_b128 v[164:167], v250
	ds_read_b128 v[168:171], v251
	ds_write_b128 v112, v[172:175]
	ds_write_b128 v112, v[176:179] offset:1024
	ds_write_b128 v112, v[180:183] offset:2048
	ds_write_b128 v112, v[184:187] offset:3072
	v_exp_f32_e32 v32, v32
	v_exp_f32_e32 v33, v33
	v_exp_f32_e32 v34, v34
	v_exp_f32_e32 v35, v35
	v_exp_f32_e32 v36, v36
	v_exp_f32_e32 v37, v37
	s_waitcnt lgkmcnt(4)
	v_mfma_f32_32x32x16_bf16 v[188:203], v[156:159], v[48:51], v[188:203]
	v_exp_f32_e32 v38, v38
	v_exp_f32_e32 v39, v39
	v_mfma_f32_32x32x16_bf16 v[188:203], v[160:163], v[52:55], v[188:203]
	v_exp_f32_e32 v40, v40
	v_exp_f32_e32 v41, v41
	v_exp_f32_e32 v42, v42
	v_mfma_f32_32x32x16_bf16 v[188:203], v[164:167], v[56:59], v[188:203]
	v_exp_f32_e32 v43, v43
	v_exp_f32_e32 v44, v44
	v_mfma_f32_32x32x16_bf16 v[188:203], v[168:171], v[60:63], v[188:203]
	v_exp_f32_e32 v45, v45
	v_exp_f32_e32 v46, v46
	v_exp_f32_e32 v47, v47
	s_add_i32 s90, s67, 512
	v_add_u32_e32 v84, s90, v107
	v_add_u32_e32 v85, 0, v84
	v_add_u32_e32 v86, 1, v84
	v_add_u32_e32 v87, 2, v84
	v_add_u32_e32 v88, 3, v84
	v_cmp_gt_u32_e64 s[30:31], s98, v85
	v_cmp_gt_u32_e64 s[36:37], s98, v86
	v_cmp_gt_u32_e64 s[78:79], s98, v87
	v_cmp_gt_u32_e64 s[50:51], s98, v88
	v_cndmask_b32_e64 v32, 0, v32, s[30:31]
	v_add_u32_e32 v85, 8, v84
	v_cmp_gt_u32_e64 s[30:31], s98, v85
	v_cndmask_b32_e64 v33, 0, v33, s[36:37]
	v_add_u32_e32 v86, 9, v84
	v_cmp_gt_u32_e64 s[36:37], s98, v86
	v_cndmask_b32_e64 v34, 0, v34, s[78:79]
	v_add_u32_e32 v87, 10, v84
	v_cmp_gt_u32_e64 s[78:79], s98, v87
	v_cndmask_b32_e64 v35, 0, v35, s[50:51]
	v_add_u32_e32 v88, 11, v84
	v_cmp_gt_u32_e64 s[50:51], s98, v88
	v_cndmask_b32_e64 v36, 0, v36, s[30:31]
	v_add_u32_e32 v85, 16, v84
	v_cmp_gt_u32_e64 s[30:31], s98, v85
	v_cndmask_b32_e64 v37, 0, v37, s[36:37]
	v_add_u32_e32 v86, 17, v84
	v_cmp_gt_u32_e64 s[36:37], s98, v86
	v_cndmask_b32_e64 v38, 0, v38, s[78:79]
	v_add_u32_e32 v87, 18, v84
	v_cmp_gt_u32_e64 s[78:79], s98, v87
	v_cndmask_b32_e64 v39, 0, v39, s[50:51]
	v_add_u32_e32 v88, 19, v84
	v_cmp_gt_u32_e64 s[50:51], s98, v88
	v_cndmask_b32_e64 v40, 0, v40, s[30:31]
	v_add_u32_e32 v85, 24, v84
	v_cmp_gt_u32_e64 s[30:31], s98, v85
	v_cndmask_b32_e64 v41, 0, v41, s[36:37]
	v_add_u32_e32 v86, 25, v84
	v_cmp_gt_u32_e64 s[36:37], s98, v86
	v_cndmask_b32_e64 v42, 0, v42, s[78:79]
	v_add_u32_e32 v87, 26, v84
	v_cmp_gt_u32_e64 s[78:79], s98, v87
	v_cndmask_b32_e64 v43, 0, v43, s[50:51]
	v_add_u32_e32 v88, 27, v84
	v_cmp_gt_u32_e64 s[50:51], s98, v88
	v_nop
	v_cndmask_b32_e64 v44, 0, v44, s[30:31]
	v_cndmask_b32_e64 v45, 0, v45, s[36:37]
	v_cndmask_b32_e64 v46, 0, v46, s[78:79]
	v_cndmask_b32_e64 v47, 0, v47, s[50:51]
	v_cvt_pk_bf16_f32 v64, v32, v33
	v_cvt_pk_bf16_f32 v65, v34, v35
	v_cvt_pk_bf16_f32 v66, v36, v37
	v_cvt_pk_bf16_f32 v67, v38, v39
	v_cvt_pk_bf16_f32 v68, v40, v41
	v_cvt_pk_bf16_f32 v69, v42, v43
	v_cvt_pk_bf16_f32 v70, v44, v45
	v_cvt_pk_bf16_f32 v71, v46, v47
	v_pk_add_f32 v[232:233], v[232:233], v[32:33]
	v_pk_add_f32 v[232:233], v[232:233], v[34:35]
	v_pk_add_f32 v[232:233], v[232:233], v[36:37]
	v_pk_add_f32 v[232:233], v[232:233], v[38:39]
	v_pk_add_f32 v[232:233], v[232:233], v[40:41]
	v_pk_add_f32 v[232:233], v[232:233], v[42:43]
	v_pk_add_f32 v[232:233], v[232:233], v[44:45]
	v_pk_add_f32 v[232:233], v[232:233], v[46:47]
	v_mov_b32_e32 v115, v229
	ds_read2_b32 v[32:33], v115 offset0:0 offset1:1
	ds_read2_b32 v[34:35], v115 offset0:2 offset1:3
	ds_read2_b32 v[36:37], v115 offset0:8 offset1:9
	ds_read2_b32 v[38:39], v115 offset0:10 offset1:11
	ds_read2_b32 v[40:41], v115 offset0:16 offset1:17
	ds_read2_b32 v[42:43], v115 offset0:18 offset1:19
	ds_read2_b32 v[44:45], v115 offset0:24 offset1:25
	ds_read2_b32 v[46:47], v115 offset0:26 offset1:27
	v_mfma_f32_32x32x16_bf16 v[0:15], v[64:67], v[72:75], v[0:15]
	v_mfma_f32_32x32x16_bf16 v[16:31], v[64:67], v[76:79], v[16:31]
	v_mfma_f32_32x32x16_bf16 v[0:15], v[68:71], v[220:223], v[0:15]
	v_mfma_f32_32x32x16_bf16 v[16:31], v[68:71], v[224:227], v[16:31]
	s_add_i32 s90, s67, -128
	v_add_u32_e32 v80, s90, v239
	v_add_u32_e32 v83, s90, v240
	v_add_u32_e32 v99, s90, v241
	v_add_u32_e32 v253, s90, v242
	v_add_u32_e32 v254, s90, v101
	v_add_u32_e32 v255, s90, v150
	v_med3_i32 v80, v80, 0, s99
	v_med3_i32 v83, v83, 0, s99
	v_med3_i32 v99, v99, 0, s99
	v_med3_i32 v253, v253, 0, s99
	v_med3_i32 v254, v254, 0, s99
	v_med3_i32 v255, v255, 0, s99
	v_mad_u32_u24 v80, v80, s100, v252
	v_mad_u32_u24 v83, v83, s100, v252
	v_mad_u32_u24 v99, v99, s100, v252
	v_mad_u32_u24 v253, v253, s100, v252
	v_mad_u32_u24 v254, v254, s100, v153
	v_mad_u32_u24 v255, v255, s100, v153
	global_load_dwordx4 v[156:159], v80, s[82:83]
	global_load_dwordx4 v[160:163], v83, s[82:83]
	global_load_dwordx4 v[164:167], v99, s[82:83]
	global_load_dwordx4 v[168:171], v253, s[82:83]
	global_load_dwordx4 v[172:175], v254, s[82:83] offset:768
	global_load_dwordx4 v[176:179], v255, s[82:83] offset:768
	global_load_dwordx4 v[180:183], v254, s[82:83] offset:832
	global_load_dwordx4 v[184:187], v255, s[82:83] offset:832
	ds_read_b64_tr_b16 v[72:73], v231
	ds_read_b64_tr_b16 v[74:75], v231 offset:512
	ds_read_b64_tr_b16 v[76:77], v231 offset:2048
	ds_read_b64_tr_b16 v[78:79], v231 offset:2560
	ds_read_b64_tr_b16 v[220:221], v231 offset:1024
	ds_read_b64_tr_b16 v[222:223], v231 offset:1536
	ds_read_b64_tr_b16 v[224:225], v231 offset:3072
	ds_read_b64_tr_b16 v[226:227], v231 offset:3584
	s_waitcnt vmcnt(8)
	ds_write_b128 v247, v[116:119]
	ds_write_b128 v247, v[120:123] offset:1024
	ds_write_b128 v247, v[124:127] offset:2048
	ds_write_b128 v247, v[128:131] offset:3072
	ds_read_b128 v[116:119], v248
	ds_read_b128 v[120:123], v249
	ds_read_b128 v[124:127], v250
	ds_read_b128 v[128:131], v251
	ds_write_b128 v112, v[132:135]
	ds_write_b128 v112, v[136:139] offset:1024
	ds_write_b128 v112, v[140:143] offset:2048
	ds_write_b128 v112, v[144:147] offset:3072
	v_exp_f32_e32 v188, v188
	v_exp_f32_e32 v189, v189
	v_exp_f32_e32 v190, v190
	v_exp_f32_e32 v191, v191
	v_exp_f32_e32 v192, v192
	v_exp_f32_e32 v193, v193
	s_waitcnt lgkmcnt(4)
	v_mfma_f32_32x32x16_bf16 v[32:47], v[116:119], v[48:51], v[32:47]
	v_exp_f32_e32 v194, v194
	v_exp_f32_e32 v195, v195
	v_mfma_f32_32x32x16_bf16 v[32:47], v[120:123], v[52:55], v[32:47]
	v_exp_f32_e32 v196, v196
	v_exp_f32_e32 v197, v197
	v_exp_f32_e32 v198, v198
	v_mfma_f32_32x32x16_bf16 v[32:47], v[124:127], v[56:59], v[32:47]
	v_exp_f32_e32 v199, v199
	v_exp_f32_e32 v200, v200
	v_mfma_f32_32x32x16_bf16 v[32:47], v[128:131], v[60:63], v[32:47]
	v_exp_f32_e32 v201, v201
	v_exp_f32_e32 v202, v202
	v_exp_f32_e32 v203, v203
	s_add_i32 s90, s67, 544
	v_add_u32_e32 v84, s90, v107
	v_add_u32_e32 v85, 0, v84
	v_add_u32_e32 v86, 1, v84
	v_add_u32_e32 v87, 2, v84
	v_add_u32_e32 v88, 3, v84
	v_cmp_gt_u32_e64 s[30:31], s98, v85
	v_cmp_gt_u32_e64 s[36:37], s98, v86
	v_cmp_gt_u32_e64 s[78:79], s98, v87
	v_cmp_gt_u32_e64 s[50:51], s98, v88
	v_cndmask_b32_e64 v188, 0, v188, s[30:31]
	v_add_u32_e32 v85, 8, v84
	v_cmp_gt_u32_e64 s[30:31], s98, v85
	v_cndmask_b32_e64 v189, 0, v189, s[36:37]
	v_add_u32_e32 v86, 9, v84
	v_cmp_gt_u32_e64 s[36:37], s98, v86
	v_cndmask_b32_e64 v190, 0, v190, s[78:79]
	v_add_u32_e32 v87, 10, v84
	v_cmp_gt_u32_e64 s[78:79], s98, v87
	v_cndmask_b32_e64 v191, 0, v191, s[50:51]
	v_add_u32_e32 v88, 11, v84
	v_cmp_gt_u32_e64 s[50:51], s98, v88
	v_cndmask_b32_e64 v192, 0, v192, s[30:31]
	v_add_u32_e32 v85, 16, v84
	v_cmp_gt_u32_e64 s[30:31], s98, v85
	v_cndmask_b32_e64 v193, 0, v193, s[36:37]
	v_add_u32_e32 v86, 17, v84
	v_cmp_gt_u32_e64 s[36:37], s98, v86
	v_cndmask_b32_e64 v194, 0, v194, s[78:79]
	v_add_u32_e32 v87, 18, v84
	v_cmp_gt_u32_e64 s[78:79], s98, v87
	v_cndmask_b32_e64 v195, 0, v195, s[50:51]
	v_add_u32_e32 v88, 19, v84
	v_cmp_gt_u32_e64 s[50:51], s98, v88
	v_cndmask_b32_e64 v196, 0, v196, s[30:31]
	v_add_u32_e32 v85, 24, v84
	v_cmp_gt_u32_e64 s[30:31], s98, v85
	v_cndmask_b32_e64 v197, 0, v197, s[36:37]
	v_add_u32_e32 v86, 25, v84
	v_cmp_gt_u32_e64 s[36:37], s98, v86
	v_cndmask_b32_e64 v198, 0, v198, s[78:79]
	v_add_u32_e32 v87, 26, v84
	v_cmp_gt_u32_e64 s[78:79], s98, v87
	v_cndmask_b32_e64 v199, 0, v199, s[50:51]
	v_add_u32_e32 v88, 27, v84
	v_cmp_gt_u32_e64 s[50:51], s98, v88
	v_nop
	v_cndmask_b32_e64 v200, 0, v200, s[30:31]
	v_cndmask_b32_e64 v201, 0, v201, s[36:37]
	v_cndmask_b32_e64 v202, 0, v202, s[78:79]
	v_cndmask_b32_e64 v203, 0, v203, s[50:51]
	v_cvt_pk_bf16_f32 v64, v188, v189
	v_cvt_pk_bf16_f32 v65, v190, v191
	v_cvt_pk_bf16_f32 v66, v192, v193
	v_cvt_pk_bf16_f32 v67, v194, v195
	v_cvt_pk_bf16_f32 v68, v196, v197
	v_cvt_pk_bf16_f32 v69, v198, v199
	v_cvt_pk_bf16_f32 v70, v200, v201
	v_cvt_pk_bf16_f32 v71, v202, v203
	v_pk_add_f32 v[232:233], v[232:233], v[188:189]
	v_pk_add_f32 v[232:233], v[232:233], v[190:191]
	v_pk_add_f32 v[232:233], v[232:233], v[192:193]
	v_pk_add_f32 v[232:233], v[232:233], v[194:195]
	v_pk_add_f32 v[232:233], v[232:233], v[196:197]
	v_pk_add_f32 v[232:233], v[232:233], v[198:199]
	v_pk_add_f32 v[232:233], v[232:233], v[200:201]
	v_pk_add_f32 v[232:233], v[232:233], v[202:203]
	ds_read2_b32 v[188:189], v115 offset0:32 offset1:33
	ds_read2_b32 v[190:191], v115 offset0:34 offset1:35
	ds_read2_b32 v[192:193], v115 offset0:40 offset1:41
	ds_read2_b32 v[194:195], v115 offset0:42 offset1:43
	ds_read2_b32 v[196:197], v115 offset0:48 offset1:49
	ds_read2_b32 v[198:199], v115 offset0:50 offset1:51
	ds_read2_b32 v[200:201], v115 offset0:56 offset1:57
	ds_read2_b32 v[202:203], v115 offset0:58 offset1:59
	v_mfma_f32_32x32x16_bf16 v[0:15], v[64:67], v[72:75], v[0:15]
	v_mfma_f32_32x32x16_bf16 v[16:31], v[64:67], v[76:79], v[16:31]
	v_mfma_f32_32x32x16_bf16 v[0:15], v[68:71], v[220:223], v[0:15]
	v_mfma_f32_32x32x16_bf16 v[16:31], v[68:71], v[224:227], v[16:31]
	s_add_i32 s90, s67, 0
	v_add_u32_e32 v80, s90, v239
	v_add_u32_e32 v83, s90, v240
	v_add_u32_e32 v99, s90, v241
	v_add_u32_e32 v253, s90, v242
	v_add_u32_e32 v254, s90, v101
	v_add_u32_e32 v255, s90, v150
	v_med3_i32 v80, v80, 0, s99
	v_med3_i32 v83, v83, 0, s99
	v_med3_i32 v99, v99, 0, s99
	v_med3_i32 v253, v253, 0, s99
	v_med3_i32 v254, v254, 0, s99
	v_med3_i32 v255, v255, 0, s99
	v_mad_u32_u24 v80, v80, s100, v252
	v_mad_u32_u24 v83, v83, s100, v252
	v_mad_u32_u24 v99, v99, s100, v252
	v_mad_u32_u24 v253, v253, s100, v252
	v_mad_u32_u24 v254, v254, s100, v153
	v_mad_u32_u24 v255, v255, s100, v153
	global_load_dwordx4 v[116:119], v80, s[82:83]
	global_load_dwordx4 v[120:123], v83, s[82:83]
	global_load_dwordx4 v[124:127], v99, s[82:83]
	global_load_dwordx4 v[128:131], v253, s[82:83]
	global_load_dwordx4 v[132:135], v254, s[82:83] offset:768
	global_load_dwordx4 v[136:139], v255, s[82:83] offset:768
	global_load_dwordx4 v[140:143], v254, s[82:83] offset:832
	global_load_dwordx4 v[144:147], v255, s[82:83] offset:832
	ds_read_b64_tr_b16 v[72:73], v231
	ds_read_b64_tr_b16 v[74:75], v231 offset:512
	ds_read_b64_tr_b16 v[76:77], v231 offset:2048
	ds_read_b64_tr_b16 v[78:79], v231 offset:2560
	ds_read_b64_tr_b16 v[220:221], v231 offset:1024
	ds_read_b64_tr_b16 v[222:223], v231 offset:1536
	ds_read_b64_tr_b16 v[224:225], v231 offset:3072
	ds_read_b64_tr_b16 v[226:227], v231 offset:3584
	s_waitcnt vmcnt(8)
	ds_write_b128 v247, v[156:159]
	ds_write_b128 v247, v[160:163] offset:1024
	ds_write_b128 v247, v[164:167] offset:2048
	ds_write_b128 v247, v[168:171] offset:3072
	ds_read_b128 v[156:159], v248
	ds_read_b128 v[160:163], v249
	ds_read_b128 v[164:167], v250
	ds_read_b128 v[168:171], v251
	ds_write_b128 v112, v[172:175]
	ds_write_b128 v112, v[176:179] offset:1024
	ds_write_b128 v112, v[180:183] offset:2048
	ds_write_b128 v112, v[184:187] offset:3072
	v_exp_f32_e32 v32, v32
	v_exp_f32_e32 v33, v33
	v_exp_f32_e32 v34, v34
	v_exp_f32_e32 v35, v35
	v_exp_f32_e32 v36, v36
	v_exp_f32_e32 v37, v37
	s_waitcnt lgkmcnt(4)
	v_mfma_f32_32x32x16_bf16 v[188:203], v[156:159], v[48:51], v[188:203]
	v_exp_f32_e32 v38, v38
	v_exp_f32_e32 v39, v39
	v_mfma_f32_32x32x16_bf16 v[188:203], v[160:163], v[52:55], v[188:203]
	v_exp_f32_e32 v40, v40
	v_exp_f32_e32 v41, v41
	v_exp_f32_e32 v42, v42
	v_mfma_f32_32x32x16_bf16 v[188:203], v[164:167], v[56:59], v[188:203]
	v_exp_f32_e32 v43, v43
	v_exp_f32_e32 v44, v44
	v_mfma_f32_32x32x16_bf16 v[188:203], v[168:171], v[60:63], v[188:203]
	v_exp_f32_e32 v45, v45
	v_exp_f32_e32 v46, v46
	v_exp_f32_e32 v47, v47
	s_add_i32 s90, s67, -256
	v_lshlrev_b32_e32 v84, 2, v107
	v_add_u32_e32 v84, s90, v84
	v_add_u32_e32 v85, 0, v84
	v_add_u32_e32 v86, 4, v84
	v_add_u32_e32 v87, 8, v84
	v_add_u32_e32 v88, 12, v84
	v_cmp_gt_u32_e64 s[30:31], s98, v85
	v_cmp_gt_u32_e64 s[36:37], s98, v86
	v_cmp_gt_u32_e64 s[78:79], s98, v87
	v_cmp_gt_u32_e64 s[50:51], s98, v88
	v_cndmask_b32_e64 v32, 0, v32, s[30:31]
	v_add_u32_e32 v85, 32, v84
	v_cmp_gt_u32_e64 s[30:31], s98, v85
	v_cndmask_b32_e64 v33, 0, v33, s[36:37]
	v_add_u32_e32 v86, 36, v84
	v_cmp_gt_u32_e64 s[36:37], s98, v86
	v_cndmask_b32_e64 v34, 0, v34, s[78:79]
	v_add_u32_e32 v87, 40, v84
	v_cmp_gt_u32_e64 s[78:79], s98, v87
	v_cndmask_b32_e64 v35, 0, v35, s[50:51]
	v_add_u32_e32 v88, 44, v84
	v_cmp_gt_u32_e64 s[50:51], s98, v88
	v_cndmask_b32_e64 v36, 0, v36, s[30:31]
	v_add_u32_e32 v85, 64, v84
	v_cmp_gt_u32_e64 s[30:31], s98, v85
	v_cndmask_b32_e64 v37, 0, v37, s[36:37]
	v_add_u32_e32 v86, 68, v84
	v_cmp_gt_u32_e64 s[36:37], s98, v86
	v_cndmask_b32_e64 v38, 0, v38, s[78:79]
	v_add_u32_e32 v87, 72, v84
	v_cmp_gt_u32_e64 s[78:79], s98, v87
	v_cndmask_b32_e64 v39, 0, v39, s[50:51]
	v_add_u32_e32 v88, 76, v84
	v_cmp_gt_u32_e64 s[50:51], s98, v88
	v_cndmask_b32_e64 v40, 0, v40, s[30:31]
	v_add_u32_e32 v85, 96, v84
	v_cmp_gt_u32_e64 s[30:31], s98, v85
	v_cndmask_b32_e64 v41, 0, v41, s[36:37]
	v_add_u32_e32 v86, 100, v84
	v_cmp_gt_u32_e64 s[36:37], s98, v86
	v_cndmask_b32_e64 v42, 0, v42, s[78:79]
	v_add_u32_e32 v87, 104, v84
	v_cmp_gt_u32_e64 s[78:79], s98, v87
	v_cndmask_b32_e64 v43, 0, v43, s[50:51]
	v_add_u32_e32 v88, 108, v84
	v_cmp_gt_u32_e64 s[50:51], s98, v88
	v_nop
	v_cndmask_b32_e64 v44, 0, v44, s[30:31]
	v_cndmask_b32_e64 v45, 0, v45, s[36:37]
	v_cndmask_b32_e64 v46, 0, v46, s[78:79]
	v_cndmask_b32_e64 v47, 0, v47, s[50:51]
	v_cvt_pk_bf16_f32 v64, v32, v33
	v_cvt_pk_bf16_f32 v65, v34, v35
	v_cvt_pk_bf16_f32 v66, v36, v37
	v_cvt_pk_bf16_f32 v67, v38, v39
	v_cvt_pk_bf16_f32 v68, v40, v41
	v_cvt_pk_bf16_f32 v69, v42, v43
	v_cvt_pk_bf16_f32 v70, v44, v45
	v_cvt_pk_bf16_f32 v71, v46, v47
	v_pk_add_f32 v[232:233], v[232:233], v[32:33]
	v_pk_add_f32 v[232:233], v[232:233], v[34:35]
	v_pk_add_f32 v[232:233], v[232:233], v[36:37]
	v_pk_add_f32 v[232:233], v[232:233], v[38:39]
	v_pk_add_f32 v[232:233], v[232:233], v[40:41]
	v_pk_add_f32 v[232:233], v[232:233], v[42:43]
	v_pk_add_f32 v[232:233], v[232:233], v[44:45]
	v_pk_add_f32 v[232:233], v[232:233], v[46:47]
	ds_read2_b32 v[32:33], v115 offset0:64 offset1:65
	ds_read2_b32 v[34:35], v115 offset0:66 offset1:67
	ds_read2_b32 v[36:37], v115 offset0:72 offset1:73
	ds_read2_b32 v[38:39], v115 offset0:74 offset1:75
	ds_read2_b32 v[40:41], v115 offset0:80 offset1:81
	ds_read2_b32 v[42:43], v115 offset0:82 offset1:83
	ds_read2_b32 v[44:45], v115 offset0:88 offset1:89
	ds_read2_b32 v[46:47], v115 offset0:90 offset1:91
	v_mfma_f32_32x32x16_bf16 v[0:15], v[64:67], v[72:75], v[0:15]
	v_mfma_f32_32x32x16_bf16 v[16:31], v[64:67], v[76:79], v[16:31]
	v_mfma_f32_32x32x16_bf16 v[0:15], v[68:71], v[220:223], v[0:15]
	v_mfma_f32_32x32x16_bf16 v[16:31], v[68:71], v[224:227], v[16:31]
	s_add_i32 s90, s67, 128
	v_add_u32_e32 v80, s90, v239
	v_add_u32_e32 v83, s90, v240
	v_add_u32_e32 v99, s90, v241
	v_add_u32_e32 v253, s90, v242
	v_add_u32_e32 v254, s90, v101
	v_add_u32_e32 v255, s90, v150
	v_med3_i32 v80, v80, 0, s99
	v_med3_i32 v83, v83, 0, s99
	v_med3_i32 v99, v99, 0, s99
	v_med3_i32 v253, v253, 0, s99
	v_med3_i32 v254, v254, 0, s99
	v_med3_i32 v255, v255, 0, s99
	v_mad_u32_u24 v80, v80, s100, v252
	v_mad_u32_u24 v83, v83, s100, v252
	v_mad_u32_u24 v99, v99, s100, v252
	v_mad_u32_u24 v253, v253, s100, v252
	v_mad_u32_u24 v254, v254, s100, v153
	v_mad_u32_u24 v255, v255, s100, v153
	global_load_dwordx4 v[156:159], v80, s[82:83]
	global_load_dwordx4 v[160:163], v83, s[82:83]
	global_load_dwordx4 v[164:167], v99, s[82:83]
	global_load_dwordx4 v[168:171], v253, s[82:83]
	global_load_dwordx4 v[172:175], v254, s[82:83] offset:768
	global_load_dwordx4 v[176:179], v255, s[82:83] offset:768
	global_load_dwordx4 v[180:183], v254, s[82:83] offset:832
	global_load_dwordx4 v[184:187], v255, s[82:83] offset:832
	ds_read_b64_tr_b16 v[72:73], v231
	ds_read_b64_tr_b16 v[74:75], v231 offset:512
	ds_read_b64_tr_b16 v[76:77], v231 offset:2048
	ds_read_b64_tr_b16 v[78:79], v231 offset:2560
	ds_read_b64_tr_b16 v[220:221], v231 offset:1024
	ds_read_b64_tr_b16 v[222:223], v231 offset:1536
	ds_read_b64_tr_b16 v[224:225], v231 offset:3072
	ds_read_b64_tr_b16 v[226:227], v231 offset:3584
	s_waitcnt vmcnt(8)
	ds_write_b128 v247, v[116:119]
	ds_write_b128 v247, v[120:123] offset:1024
	ds_write_b128 v247, v[124:127] offset:2048
	ds_write_b128 v247, v[128:131] offset:3072
	ds_read_b128 v[116:119], v248
	ds_read_b128 v[120:123], v249
	ds_read_b128 v[124:127], v250
	ds_read_b128 v[128:131], v251
	ds_write_b128 v112, v[132:135]
	ds_write_b128 v112, v[136:139] offset:1024
	ds_write_b128 v112, v[140:143] offset:2048
	ds_write_b128 v112, v[144:147] offset:3072
	v_exp_f32_e32 v188, v188
	v_exp_f32_e32 v189, v189
	v_exp_f32_e32 v190, v190
	v_exp_f32_e32 v191, v191
	v_exp_f32_e32 v192, v192
	v_exp_f32_e32 v193, v193
	s_waitcnt lgkmcnt(4)
	v_mfma_f32_32x32x16_bf16 v[32:47], v[116:119], v[48:51], v[32:47]
	v_exp_f32_e32 v194, v194
	v_exp_f32_e32 v195, v195
	v_mfma_f32_32x32x16_bf16 v[32:47], v[120:123], v[52:55], v[32:47]
	v_exp_f32_e32 v196, v196
	v_exp_f32_e32 v197, v197
	v_exp_f32_e32 v198, v198
	v_mfma_f32_32x32x16_bf16 v[32:47], v[124:127], v[56:59], v[32:47]
	v_exp_f32_e32 v199, v199
	v_exp_f32_e32 v200, v200
	v_mfma_f32_32x32x16_bf16 v[32:47], v[128:131], v[60:63], v[32:47]
	v_exp_f32_e32 v201, v201
	v_exp_f32_e32 v202, v202
	v_exp_f32_e32 v203, v203
	s_add_i32 s90, s67, -128
	v_lshlrev_b32_e32 v84, 2, v107
	v_add_u32_e32 v84, s90, v84
	v_add_u32_e32 v85, 0, v84
	v_add_u32_e32 v86, 4, v84
	v_add_u32_e32 v87, 8, v84
	v_add_u32_e32 v88, 12, v84
	v_cmp_gt_u32_e64 s[30:31], s98, v85
	v_cmp_gt_u32_e64 s[36:37], s98, v86
	v_cmp_gt_u32_e64 s[78:79], s98, v87
	v_cmp_gt_u32_e64 s[50:51], s98, v88
	v_cndmask_b32_e64 v188, 0, v188, s[30:31]
	v_add_u32_e32 v85, 32, v84
	v_cmp_gt_u32_e64 s[30:31], s98, v85
	v_cndmask_b32_e64 v189, 0, v189, s[36:37]
	v_add_u32_e32 v86, 36, v84
	v_cmp_gt_u32_e64 s[36:37], s98, v86
	v_cndmask_b32_e64 v190, 0, v190, s[78:79]
	v_add_u32_e32 v87, 40, v84
	v_cmp_gt_u32_e64 s[78:79], s98, v87
	v_cndmask_b32_e64 v191, 0, v191, s[50:51]
	v_add_u32_e32 v88, 44, v84
	v_cmp_gt_u32_e64 s[50:51], s98, v88
	v_cndmask_b32_e64 v192, 0, v192, s[30:31]
	v_add_u32_e32 v85, 64, v84
	v_cmp_gt_u32_e64 s[30:31], s98, v85
	v_cndmask_b32_e64 v193, 0, v193, s[36:37]
	v_add_u32_e32 v86, 68, v84
	v_cmp_gt_u32_e64 s[36:37], s98, v86
	v_cndmask_b32_e64 v194, 0, v194, s[78:79]
	v_add_u32_e32 v87, 72, v84
	v_cmp_gt_u32_e64 s[78:79], s98, v87
	v_cndmask_b32_e64 v195, 0, v195, s[50:51]
	v_add_u32_e32 v88, 76, v84
	v_cmp_gt_u32_e64 s[50:51], s98, v88
	v_cndmask_b32_e64 v196, 0, v196, s[30:31]
	v_add_u32_e32 v85, 96, v84
	v_cmp_gt_u32_e64 s[30:31], s98, v85
	v_cndmask_b32_e64 v197, 0, v197, s[36:37]
	v_add_u32_e32 v86, 100, v84
	v_cmp_gt_u32_e64 s[36:37], s98, v86
	v_cndmask_b32_e64 v198, 0, v198, s[78:79]
	v_add_u32_e32 v87, 104, v84
	v_cmp_gt_u32_e64 s[78:79], s98, v87
	v_cndmask_b32_e64 v199, 0, v199, s[50:51]
	v_add_u32_e32 v88, 108, v84
	v_cmp_gt_u32_e64 s[50:51], s98, v88
	v_nop
	v_cndmask_b32_e64 v200, 0, v200, s[30:31]
	v_cndmask_b32_e64 v201, 0, v201, s[36:37]
	v_cndmask_b32_e64 v202, 0, v202, s[78:79]
	v_cndmask_b32_e64 v203, 0, v203, s[50:51]
	v_cvt_pk_bf16_f32 v64, v188, v189
	v_cvt_pk_bf16_f32 v65, v190, v191
	v_cvt_pk_bf16_f32 v66, v192, v193
	v_cvt_pk_bf16_f32 v67, v194, v195
	v_cvt_pk_bf16_f32 v68, v196, v197
	v_cvt_pk_bf16_f32 v69, v198, v199
	v_cvt_pk_bf16_f32 v70, v200, v201
	v_cvt_pk_bf16_f32 v71, v202, v203
	v_pk_add_f32 v[232:233], v[232:233], v[188:189]
	v_pk_add_f32 v[232:233], v[232:233], v[190:191]
	v_pk_add_f32 v[232:233], v[232:233], v[192:193]
	v_pk_add_f32 v[232:233], v[232:233], v[194:195]
	v_pk_add_f32 v[232:233], v[232:233], v[196:197]
	v_pk_add_f32 v[232:233], v[232:233], v[198:199]
	v_pk_add_f32 v[232:233], v[232:233], v[200:201]
	v_pk_add_f32 v[232:233], v[232:233], v[202:203]
	ds_read2_b32 v[188:189], v115 offset0:96 offset1:97
	ds_read2_b32 v[190:191], v115 offset0:98 offset1:99
	ds_read2_b32 v[192:193], v115 offset0:104 offset1:105
	ds_read2_b32 v[194:195], v115 offset0:106 offset1:107
	ds_read2_b32 v[196:197], v115 offset0:112 offset1:113
	ds_read2_b32 v[198:199], v115 offset0:114 offset1:115
	ds_read2_b32 v[200:201], v115 offset0:120 offset1:121
	ds_read2_b32 v[202:203], v115 offset0:122 offset1:123
	v_mfma_f32_32x32x16_bf16 v[0:15], v[64:67], v[72:75], v[0:15]
	v_mfma_f32_32x32x16_bf16 v[16:31], v[64:67], v[76:79], v[16:31]
	v_mfma_f32_32x32x16_bf16 v[0:15], v[68:71], v[220:223], v[0:15]
	v_mfma_f32_32x32x16_bf16 v[16:31], v[68:71], v[224:227], v[16:31]
	s_add_i32 s90, s67, 256
	v_add_u32_e32 v80, s90, v239
	v_add_u32_e32 v83, s90, v240
	v_add_u32_e32 v99, s90, v241
	v_add_u32_e32 v253, s90, v242
	v_add_u32_e32 v254, s90, v101
	v_add_u32_e32 v255, s90, v150
	v_med3_i32 v80, v80, 0, s99
	v_med3_i32 v83, v83, 0, s99
	v_med3_i32 v99, v99, 0, s99
	v_med3_i32 v253, v253, 0, s99
	v_med3_i32 v254, v254, 0, s99
	v_med3_i32 v255, v255, 0, s99
	v_mad_u32_u24 v80, v80, s100, v252
	v_mad_u32_u24 v83, v83, s100, v252
	v_mad_u32_u24 v99, v99, s100, v252
	v_mad_u32_u24 v253, v253, s100, v252
	v_mad_u32_u24 v254, v254, s100, v153
	v_mad_u32_u24 v255, v255, s100, v153
	global_load_dwordx4 v[116:119], v80, s[82:83]
	global_load_dwordx4 v[120:123], v83, s[82:83]
	global_load_dwordx4 v[124:127], v99, s[82:83]
	global_load_dwordx4 v[128:131], v253, s[82:83]
	global_load_dwordx4 v[132:135], v254, s[82:83] offset:768
	global_load_dwordx4 v[136:139], v255, s[82:83] offset:768
	global_load_dwordx4 v[140:143], v254, s[82:83] offset:832
	global_load_dwordx4 v[144:147], v255, s[82:83] offset:832
	ds_read_b64_tr_b16 v[72:73], v231
	ds_read_b64_tr_b16 v[74:75], v231 offset:512
	ds_read_b64_tr_b16 v[76:77], v231 offset:2048
	ds_read_b64_tr_b16 v[78:79], v231 offset:2560
	ds_read_b64_tr_b16 v[220:221], v231 offset:1024
	ds_read_b64_tr_b16 v[222:223], v231 offset:1536
	ds_read_b64_tr_b16 v[224:225], v231 offset:3072
	ds_read_b64_tr_b16 v[226:227], v231 offset:3584
	s_waitcnt vmcnt(8)
	ds_write_b128 v247, v[156:159]
	ds_write_b128 v247, v[160:163] offset:1024
	ds_write_b128 v247, v[164:167] offset:2048
	ds_write_b128 v247, v[168:171] offset:3072
	ds_read_b128 v[156:159], v248
	ds_read_b128 v[160:163], v249
	ds_read_b128 v[164:167], v250
	ds_read_b128 v[168:171], v251
	ds_write_b128 v112, v[172:175]
	ds_write_b128 v112, v[176:179] offset:1024
	ds_write_b128 v112, v[180:183] offset:2048
	ds_write_b128 v112, v[184:187] offset:3072
	v_exp_f32_e32 v32, v32
	v_exp_f32_e32 v33, v33
	v_exp_f32_e32 v34, v34
	v_exp_f32_e32 v35, v35
	v_exp_f32_e32 v36, v36
	v_exp_f32_e32 v37, v37
	s_waitcnt lgkmcnt(4)
	v_mfma_f32_32x32x16_bf16 v[188:203], v[156:159], v[48:51], v[188:203]
	v_exp_f32_e32 v38, v38
	v_exp_f32_e32 v39, v39
	v_mfma_f32_32x32x16_bf16 v[188:203], v[160:163], v[52:55], v[188:203]
	v_exp_f32_e32 v40, v40
	v_exp_f32_e32 v41, v41
	v_exp_f32_e32 v42, v42
	v_mfma_f32_32x32x16_bf16 v[188:203], v[164:167], v[56:59], v[188:203]
	v_exp_f32_e32 v43, v43
	v_exp_f32_e32 v44, v44
	v_mfma_f32_32x32x16_bf16 v[188:203], v[168:171], v[60:63], v[188:203]
	v_exp_f32_e32 v45, v45
	v_exp_f32_e32 v46, v46
	v_exp_f32_e32 v47, v47
	s_add_i32 s90, s67, 0
	v_lshlrev_b32_e32 v84, 2, v107
	v_add_u32_e32 v84, s90, v84
	v_add_u32_e32 v85, 0, v84
	v_add_u32_e32 v86, 4, v84
	v_add_u32_e32 v87, 8, v84
	v_add_u32_e32 v88, 12, v84
	v_cmp_gt_u32_e64 s[30:31], s98, v85
	v_cmp_gt_u32_e64 s[36:37], s98, v86
	v_cmp_gt_u32_e64 s[78:79], s98, v87
	v_cmp_gt_u32_e64 s[50:51], s98, v88
	v_cndmask_b32_e64 v32, 0, v32, s[30:31]
	v_add_u32_e32 v85, 32, v84
	v_cmp_gt_u32_e64 s[30:31], s98, v85
	v_cndmask_b32_e64 v33, 0, v33, s[36:37]
	v_add_u32_e32 v86, 36, v84
	v_cmp_gt_u32_e64 s[36:37], s98, v86
	v_cndmask_b32_e64 v34, 0, v34, s[78:79]
	v_add_u32_e32 v87, 40, v84
	v_cmp_gt_u32_e64 s[78:79], s98, v87
	v_cndmask_b32_e64 v35, 0, v35, s[50:51]
	v_add_u32_e32 v88, 44, v84
	v_cmp_gt_u32_e64 s[50:51], s98, v88
	v_cndmask_b32_e64 v36, 0, v36, s[30:31]
	v_add_u32_e32 v85, 64, v84
	v_cmp_gt_u32_e64 s[30:31], s98, v85
	v_cndmask_b32_e64 v37, 0, v37, s[36:37]
	v_add_u32_e32 v86, 68, v84
	v_cmp_gt_u32_e64 s[36:37], s98, v86
	v_cndmask_b32_e64 v38, 0, v38, s[78:79]
	v_add_u32_e32 v87, 72, v84
	v_cmp_gt_u32_e64 s[78:79], s98, v87
	v_cndmask_b32_e64 v39, 0, v39, s[50:51]
	v_add_u32_e32 v88, 76, v84
	v_cmp_gt_u32_e64 s[50:51], s98, v88
	v_cndmask_b32_e64 v40, 0, v40, s[30:31]
	v_add_u32_e32 v85, 96, v84
	v_cmp_gt_u32_e64 s[30:31], s98, v85
	v_cndmask_b32_e64 v41, 0, v41, s[36:37]
	v_add_u32_e32 v86, 100, v84
	v_cmp_gt_u32_e64 s[36:37], s98, v86
	v_cndmask_b32_e64 v42, 0, v42, s[78:79]
	v_add_u32_e32 v87, 104, v84
	v_cmp_gt_u32_e64 s[78:79], s98, v87
	v_cndmask_b32_e64 v43, 0, v43, s[50:51]
	v_add_u32_e32 v88, 108, v84
	v_cmp_gt_u32_e64 s[50:51], s98, v88
	v_nop
	v_cndmask_b32_e64 v44, 0, v44, s[30:31]
	v_cndmask_b32_e64 v45, 0, v45, s[36:37]
	v_cndmask_b32_e64 v46, 0, v46, s[78:79]
	v_cndmask_b32_e64 v47, 0, v47, s[50:51]
	v_cvt_pk_bf16_f32 v64, v32, v33
	v_cvt_pk_bf16_f32 v65, v34, v35
	v_cvt_pk_bf16_f32 v66, v36, v37
	v_cvt_pk_bf16_f32 v67, v38, v39
	v_cvt_pk_bf16_f32 v68, v40, v41
	v_cvt_pk_bf16_f32 v69, v42, v43
	v_cvt_pk_bf16_f32 v70, v44, v45
	v_cvt_pk_bf16_f32 v71, v46, v47
	v_pk_add_f32 v[232:233], v[232:233], v[32:33]
	v_pk_add_f32 v[232:233], v[232:233], v[34:35]
	v_pk_add_f32 v[232:233], v[232:233], v[36:37]
	v_pk_add_f32 v[232:233], v[232:233], v[38:39]
	v_pk_add_f32 v[232:233], v[232:233], v[40:41]
	v_pk_add_f32 v[232:233], v[232:233], v[42:43]
	v_pk_add_f32 v[232:233], v[232:233], v[44:45]
	v_pk_add_f32 v[232:233], v[232:233], v[46:47]
	ds_read2_b32 v[32:33], v115 offset0:128 offset1:129
	ds_read2_b32 v[34:35], v115 offset0:130 offset1:131
	ds_read2_b32 v[36:37], v115 offset0:136 offset1:137
	ds_read2_b32 v[38:39], v115 offset0:138 offset1:139
	ds_read2_b32 v[40:41], v115 offset0:144 offset1:145
	ds_read2_b32 v[42:43], v115 offset0:146 offset1:147
	ds_read2_b32 v[44:45], v115 offset0:152 offset1:153
	ds_read2_b32 v[46:47], v115 offset0:154 offset1:155
	v_mfma_f32_32x32x16_bf16 v[0:15], v[64:67], v[72:75], v[0:15]
	v_mfma_f32_32x32x16_bf16 v[16:31], v[64:67], v[76:79], v[16:31]
	v_mfma_f32_32x32x16_bf16 v[0:15], v[68:71], v[220:223], v[0:15]
	v_mfma_f32_32x32x16_bf16 v[16:31], v[68:71], v[224:227], v[16:31]
	s_add_i32 s90, s67, 384
	v_add_u32_e32 v80, s90, v239
	v_add_u32_e32 v83, s90, v240
	v_add_u32_e32 v99, s90, v241
	v_add_u32_e32 v253, s90, v242
	v_add_u32_e32 v254, s90, v101
	v_add_u32_e32 v255, s90, v150
	v_med3_i32 v80, v80, 0, s99
	v_med3_i32 v83, v83, 0, s99
	v_med3_i32 v99, v99, 0, s99
	v_med3_i32 v253, v253, 0, s99
	v_med3_i32 v254, v254, 0, s99
	v_med3_i32 v255, v255, 0, s99
	v_mad_u32_u24 v80, v80, s100, v252
	v_mad_u32_u24 v83, v83, s100, v252
	v_mad_u32_u24 v99, v99, s100, v252
	v_mad_u32_u24 v253, v253, s100, v252
	v_mad_u32_u24 v254, v254, s100, v153
	v_mad_u32_u24 v255, v255, s100, v153
	global_load_dwordx4 v[156:159], v80, s[82:83]
	global_load_dwordx4 v[160:163], v83, s[82:83]
	global_load_dwordx4 v[164:167], v99, s[82:83]
	global_load_dwordx4 v[168:171], v253, s[82:83]
	global_load_dwordx4 v[172:175], v254, s[82:83] offset:768
	global_load_dwordx4 v[176:179], v255, s[82:83] offset:768
	global_load_dwordx4 v[180:183], v254, s[82:83] offset:832
	global_load_dwordx4 v[184:187], v255, s[82:83] offset:832
	ds_read_b64_tr_b16 v[72:73], v231
	ds_read_b64_tr_b16 v[74:75], v231 offset:512
	ds_read_b64_tr_b16 v[76:77], v231 offset:2048
	ds_read_b64_tr_b16 v[78:79], v231 offset:2560
	ds_read_b64_tr_b16 v[220:221], v231 offset:1024
	ds_read_b64_tr_b16 v[222:223], v231 offset:1536
	ds_read_b64_tr_b16 v[224:225], v231 offset:3072
	ds_read_b64_tr_b16 v[226:227], v231 offset:3584
	s_waitcnt vmcnt(8)
	ds_write_b128 v247, v[116:119]
	ds_write_b128 v247, v[120:123] offset:1024
	ds_write_b128 v247, v[124:127] offset:2048
	ds_write_b128 v247, v[128:131] offset:3072
	ds_read_b128 v[116:119], v248
	ds_read_b128 v[120:123], v249
	ds_read_b128 v[124:127], v250
	ds_read_b128 v[128:131], v251
	ds_write_b128 v112, v[132:135]
	ds_write_b128 v112, v[136:139] offset:1024
	ds_write_b128 v112, v[140:143] offset:2048
	ds_write_b128 v112, v[144:147] offset:3072
	v_exp_f32_e32 v188, v188
	v_exp_f32_e32 v189, v189
	v_exp_f32_e32 v190, v190
	v_exp_f32_e32 v191, v191
	v_exp_f32_e32 v192, v192
	v_exp_f32_e32 v193, v193
	s_waitcnt lgkmcnt(4)
	v_mfma_f32_32x32x16_bf16 v[32:47], v[116:119], v[48:51], v[32:47]
	v_exp_f32_e32 v194, v194
	v_exp_f32_e32 v195, v195
	v_mfma_f32_32x32x16_bf16 v[32:47], v[120:123], v[52:55], v[32:47]
	v_exp_f32_e32 v196, v196
	v_exp_f32_e32 v197, v197
	v_exp_f32_e32 v198, v198
	v_mfma_f32_32x32x16_bf16 v[32:47], v[124:127], v[56:59], v[32:47]
	v_exp_f32_e32 v199, v199
	v_exp_f32_e32 v200, v200
	v_mfma_f32_32x32x16_bf16 v[32:47], v[128:131], v[60:63], v[32:47]
	v_exp_f32_e32 v201, v201
	v_exp_f32_e32 v202, v202
	v_exp_f32_e32 v203, v203
	s_add_i32 s90, s67, 128
	v_lshlrev_b32_e32 v84, 2, v107
	v_add_u32_e32 v84, s90, v84
	v_add_u32_e32 v85, 0, v84
	v_add_u32_e32 v86, 4, v84
	v_add_u32_e32 v87, 8, v84
	v_add_u32_e32 v88, 12, v84
	v_cmp_gt_u32_e64 s[30:31], s98, v85
	v_cmp_gt_u32_e64 s[36:37], s98, v86
	v_cmp_gt_u32_e64 s[78:79], s98, v87
	v_cmp_gt_u32_e64 s[50:51], s98, v88
	v_cndmask_b32_e64 v188, 0, v188, s[30:31]
	v_add_u32_e32 v85, 32, v84
	v_cmp_gt_u32_e64 s[30:31], s98, v85
	v_cndmask_b32_e64 v189, 0, v189, s[36:37]
	v_add_u32_e32 v86, 36, v84
	v_cmp_gt_u32_e64 s[36:37], s98, v86
	v_cndmask_b32_e64 v190, 0, v190, s[78:79]
	v_add_u32_e32 v87, 40, v84
	v_cmp_gt_u32_e64 s[78:79], s98, v87
	v_cndmask_b32_e64 v191, 0, v191, s[50:51]
	v_add_u32_e32 v88, 44, v84
	v_cmp_gt_u32_e64 s[50:51], s98, v88
	v_cndmask_b32_e64 v192, 0, v192, s[30:31]
	v_add_u32_e32 v85, 64, v84
	v_cmp_gt_u32_e64 s[30:31], s98, v85
	v_cndmask_b32_e64 v193, 0, v193, s[36:37]
	v_add_u32_e32 v86, 68, v84
	v_cmp_gt_u32_e64 s[36:37], s98, v86
	v_cndmask_b32_e64 v194, 0, v194, s[78:79]
	v_add_u32_e32 v87, 72, v84
	v_cmp_gt_u32_e64 s[78:79], s98, v87
	v_cndmask_b32_e64 v195, 0, v195, s[50:51]
	v_add_u32_e32 v88, 76, v84
	v_cmp_gt_u32_e64 s[50:51], s98, v88
	v_cndmask_b32_e64 v196, 0, v196, s[30:31]
	v_add_u32_e32 v85, 96, v84
	v_cmp_gt_u32_e64 s[30:31], s98, v85
	v_cndmask_b32_e64 v197, 0, v197, s[36:37]
	v_add_u32_e32 v86, 100, v84
	v_cmp_gt_u32_e64 s[36:37], s98, v86
	v_cndmask_b32_e64 v198, 0, v198, s[78:79]
	v_add_u32_e32 v87, 104, v84
	v_cmp_gt_u32_e64 s[78:79], s98, v87
	v_cndmask_b32_e64 v199, 0, v199, s[50:51]
	v_add_u32_e32 v88, 108, v84
	v_cmp_gt_u32_e64 s[50:51], s98, v88
	v_nop
	v_cndmask_b32_e64 v200, 0, v200, s[30:31]
	v_cndmask_b32_e64 v201, 0, v201, s[36:37]
	v_cndmask_b32_e64 v202, 0, v202, s[78:79]
	v_cndmask_b32_e64 v203, 0, v203, s[50:51]
	v_cvt_pk_bf16_f32 v64, v188, v189
	v_cvt_pk_bf16_f32 v65, v190, v191
	v_cvt_pk_bf16_f32 v66, v192, v193
	v_cvt_pk_bf16_f32 v67, v194, v195
	v_cvt_pk_bf16_f32 v68, v196, v197
	v_cvt_pk_bf16_f32 v69, v198, v199
	v_cvt_pk_bf16_f32 v70, v200, v201
	v_cvt_pk_bf16_f32 v71, v202, v203
	v_pk_add_f32 v[232:233], v[232:233], v[188:189]
	v_pk_add_f32 v[232:233], v[232:233], v[190:191]
	v_pk_add_f32 v[232:233], v[232:233], v[192:193]
	v_pk_add_f32 v[232:233], v[232:233], v[194:195]
	v_pk_add_f32 v[232:233], v[232:233], v[196:197]
	v_pk_add_f32 v[232:233], v[232:233], v[198:199]
	v_pk_add_f32 v[232:233], v[232:233], v[200:201]
	v_pk_add_f32 v[232:233], v[232:233], v[202:203]
	ds_read2_b32 v[188:189], v115 offset0:160 offset1:161
	ds_read2_b32 v[190:191], v115 offset0:162 offset1:163
	ds_read2_b32 v[192:193], v115 offset0:168 offset1:169
	ds_read2_b32 v[194:195], v115 offset0:170 offset1:171
	ds_read2_b32 v[196:197], v115 offset0:176 offset1:177
	ds_read2_b32 v[198:199], v115 offset0:178 offset1:179
	ds_read2_b32 v[200:201], v115 offset0:184 offset1:185
	ds_read2_b32 v[202:203], v115 offset0:186 offset1:187
	v_mfma_f32_32x32x16_bf16 v[0:15], v[64:67], v[72:75], v[0:15]
	v_mfma_f32_32x32x16_bf16 v[16:31], v[64:67], v[76:79], v[16:31]
	v_mfma_f32_32x32x16_bf16 v[0:15], v[68:71], v[220:223], v[0:15]
	v_mfma_f32_32x32x16_bf16 v[16:31], v[68:71], v[224:227], v[16:31]
	s_add_i32 s90, s67, 512
	v_add_u32_e32 v80, s90, v239
	v_add_u32_e32 v83, s90, v240
	v_add_u32_e32 v99, s90, v241
	v_add_u32_e32 v253, s90, v242
	v_add_u32_e32 v254, s90, v101
	v_add_u32_e32 v255, s90, v150
	v_med3_i32 v80, v80, 0, s99
	v_med3_i32 v83, v83, 0, s99
	v_med3_i32 v99, v99, 0, s99
	v_med3_i32 v253, v253, 0, s99
	v_med3_i32 v254, v254, 0, s99
	v_med3_i32 v255, v255, 0, s99
	v_mad_u32_u24 v80, v80, s100, v252
	v_mad_u32_u24 v83, v83, s100, v252
	v_mad_u32_u24 v99, v99, s100, v252
	v_mad_u32_u24 v253, v253, s100, v252
	v_mad_u32_u24 v254, v254, s100, v153
	v_mad_u32_u24 v255, v255, s100, v153
	global_load_dwordx4 v[116:119], v80, s[82:83]
	global_load_dwordx4 v[120:123], v83, s[82:83]
	global_load_dwordx4 v[124:127], v99, s[82:83]
	global_load_dwordx4 v[128:131], v253, s[82:83]
	global_load_dwordx4 v[132:135], v254, s[82:83] offset:768
	global_load_dwordx4 v[136:139], v255, s[82:83] offset:768
	global_load_dwordx4 v[140:143], v254, s[82:83] offset:832
	global_load_dwordx4 v[144:147], v255, s[82:83] offset:832
	ds_read_b64_tr_b16 v[72:73], v231
	ds_read_b64_tr_b16 v[74:75], v231 offset:512
	ds_read_b64_tr_b16 v[76:77], v231 offset:2048
	ds_read_b64_tr_b16 v[78:79], v231 offset:2560
	ds_read_b64_tr_b16 v[220:221], v231 offset:1024
	ds_read_b64_tr_b16 v[222:223], v231 offset:1536
	ds_read_b64_tr_b16 v[224:225], v231 offset:3072
	ds_read_b64_tr_b16 v[226:227], v231 offset:3584
	s_waitcnt vmcnt(8)
	ds_write_b128 v247, v[156:159]
	ds_write_b128 v247, v[160:163] offset:1024
	ds_write_b128 v247, v[164:167] offset:2048
	ds_write_b128 v247, v[168:171] offset:3072
	ds_read_b128 v[156:159], v248
	ds_read_b128 v[160:163], v249
	ds_read_b128 v[164:167], v250
	ds_read_b128 v[168:171], v251
	ds_write_b128 v112, v[172:175]
	ds_write_b128 v112, v[176:179] offset:1024
	ds_write_b128 v112, v[180:183] offset:2048
	ds_write_b128 v112, v[184:187] offset:3072
	v_exp_f32_e32 v32, v32
	v_exp_f32_e32 v33, v33
	v_exp_f32_e32 v34, v34
	v_exp_f32_e32 v35, v35
	v_exp_f32_e32 v36, v36
	v_exp_f32_e32 v37, v37
	s_waitcnt lgkmcnt(4)
	v_mfma_f32_32x32x16_bf16 v[188:203], v[156:159], v[48:51], v[188:203]
	v_exp_f32_e32 v38, v38
	v_exp_f32_e32 v39, v39
	v_mfma_f32_32x32x16_bf16 v[188:203], v[160:163], v[52:55], v[188:203]
	v_exp_f32_e32 v40, v40
	v_exp_f32_e32 v41, v41
	v_exp_f32_e32 v42, v42
	v_mfma_f32_32x32x16_bf16 v[188:203], v[164:167], v[56:59], v[188:203]
	v_exp_f32_e32 v43, v43
	v_exp_f32_e32 v44, v44
	v_mfma_f32_32x32x16_bf16 v[188:203], v[168:171], v[60:63], v[188:203]
	v_exp_f32_e32 v45, v45
	v_exp_f32_e32 v46, v46
	v_exp_f32_e32 v47, v47
	s_add_i32 s90, s67, 256
	v_lshlrev_b32_e32 v84, 2, v107
	v_add_u32_e32 v84, s90, v84
	v_add_u32_e32 v85, 0, v84
	v_add_u32_e32 v86, 4, v84
	v_add_u32_e32 v87, 8, v84
	v_add_u32_e32 v88, 12, v84
	v_cmp_gt_u32_e64 s[30:31], s98, v85
	v_cmp_gt_u32_e64 s[36:37], s98, v86
	v_cmp_gt_u32_e64 s[78:79], s98, v87
	v_cmp_gt_u32_e64 s[50:51], s98, v88
	v_cndmask_b32_e64 v32, 0, v32, s[30:31]
	v_add_u32_e32 v85, 32, v84
	v_cmp_gt_u32_e64 s[30:31], s98, v85
	v_cndmask_b32_e64 v33, 0, v33, s[36:37]
	v_add_u32_e32 v86, 36, v84
	v_cmp_gt_u32_e64 s[36:37], s98, v86
	v_cndmask_b32_e64 v34, 0, v34, s[78:79]
	v_add_u32_e32 v87, 40, v84
	v_cmp_gt_u32_e64 s[78:79], s98, v87
	v_cndmask_b32_e64 v35, 0, v35, s[50:51]
	v_add_u32_e32 v88, 44, v84
	v_cmp_gt_u32_e64 s[50:51], s98, v88
	v_cndmask_b32_e64 v36, 0, v36, s[30:31]
	v_add_u32_e32 v85, 64, v84
	v_cmp_gt_u32_e64 s[30:31], s98, v85
	v_cndmask_b32_e64 v37, 0, v37, s[36:37]
	v_add_u32_e32 v86, 68, v84
	v_cmp_gt_u32_e64 s[36:37], s98, v86
	v_cndmask_b32_e64 v38, 0, v38, s[78:79]
	v_add_u32_e32 v87, 72, v84
	v_cmp_gt_u32_e64 s[78:79], s98, v87
	v_cndmask_b32_e64 v39, 0, v39, s[50:51]
	v_add_u32_e32 v88, 76, v84
	v_cmp_gt_u32_e64 s[50:51], s98, v88
	v_cndmask_b32_e64 v40, 0, v40, s[30:31]
	v_add_u32_e32 v85, 96, v84
	v_cmp_gt_u32_e64 s[30:31], s98, v85
	v_cndmask_b32_e64 v41, 0, v41, s[36:37]
	v_add_u32_e32 v86, 100, v84
	v_cmp_gt_u32_e64 s[36:37], s98, v86
	v_cndmask_b32_e64 v42, 0, v42, s[78:79]
	v_add_u32_e32 v87, 104, v84
	v_cmp_gt_u32_e64 s[78:79], s98, v87
	v_cndmask_b32_e64 v43, 0, v43, s[50:51]
	v_add_u32_e32 v88, 108, v84
	v_cmp_gt_u32_e64 s[50:51], s98, v88
	v_nop
	v_cndmask_b32_e64 v44, 0, v44, s[30:31]
	v_cndmask_b32_e64 v45, 0, v45, s[36:37]
	v_cndmask_b32_e64 v46, 0, v46, s[78:79]
	v_cndmask_b32_e64 v47, 0, v47, s[50:51]
	v_cvt_pk_bf16_f32 v64, v32, v33
	v_cvt_pk_bf16_f32 v65, v34, v35
	v_cvt_pk_bf16_f32 v66, v36, v37
	v_cvt_pk_bf16_f32 v67, v38, v39
	v_cvt_pk_bf16_f32 v68, v40, v41
	v_cvt_pk_bf16_f32 v69, v42, v43
	v_cvt_pk_bf16_f32 v70, v44, v45
	v_cvt_pk_bf16_f32 v71, v46, v47
	v_pk_add_f32 v[232:233], v[232:233], v[32:33]
	v_pk_add_f32 v[232:233], v[232:233], v[34:35]
	v_pk_add_f32 v[232:233], v[232:233], v[36:37]
	v_pk_add_f32 v[232:233], v[232:233], v[38:39]
	v_pk_add_f32 v[232:233], v[232:233], v[40:41]
	v_pk_add_f32 v[232:233], v[232:233], v[42:43]
	v_pk_add_f32 v[232:233], v[232:233], v[44:45]
	v_pk_add_f32 v[232:233], v[232:233], v[46:47]
	ds_read2_b32 v[32:33], v115 offset0:192 offset1:193
	ds_read2_b32 v[34:35], v115 offset0:194 offset1:195
	ds_read2_b32 v[36:37], v115 offset0:200 offset1:201
	ds_read2_b32 v[38:39], v115 offset0:202 offset1:203
	ds_read2_b32 v[40:41], v115 offset0:208 offset1:209
	ds_read2_b32 v[42:43], v115 offset0:210 offset1:211
	ds_read2_b32 v[44:45], v115 offset0:216 offset1:217
	ds_read2_b32 v[46:47], v115 offset0:218 offset1:219
	v_mfma_f32_32x32x16_bf16 v[0:15], v[64:67], v[72:75], v[0:15]
	v_mfma_f32_32x32x16_bf16 v[16:31], v[64:67], v[76:79], v[16:31]
	v_mfma_f32_32x32x16_bf16 v[0:15], v[68:71], v[220:223], v[0:15]
	v_mfma_f32_32x32x16_bf16 v[16:31], v[68:71], v[224:227], v[16:31]
	s_add_i32 s90, s67, 640
	v_add_u32_e32 v80, s90, v239
	v_add_u32_e32 v83, s90, v240
	v_add_u32_e32 v99, s90, v241
	v_add_u32_e32 v253, s90, v242
	v_add_u32_e32 v254, s90, v101
	v_add_u32_e32 v255, s90, v150
	v_med3_i32 v80, v80, 0, s99
	v_med3_i32 v83, v83, 0, s99
	v_med3_i32 v99, v99, 0, s99
	v_med3_i32 v253, v253, 0, s99
	v_med3_i32 v254, v254, 0, s99
	v_med3_i32 v255, v255, 0, s99
	v_mad_u32_u24 v80, v80, s100, v252
	v_mad_u32_u24 v83, v83, s100, v252
	v_mad_u32_u24 v99, v99, s100, v252
	v_mad_u32_u24 v253, v253, s100, v252
	v_mad_u32_u24 v254, v254, s100, v153
	v_mad_u32_u24 v255, v255, s100, v153
	global_load_dwordx4 v[156:159], v80, s[82:83]
	global_load_dwordx4 v[160:163], v83, s[82:83]
	global_load_dwordx4 v[164:167], v99, s[82:83]
	global_load_dwordx4 v[168:171], v253, s[82:83]
	global_load_dwordx4 v[172:175], v254, s[82:83] offset:768
	global_load_dwordx4 v[176:179], v255, s[82:83] offset:768
	global_load_dwordx4 v[180:183], v254, s[82:83] offset:832
	global_load_dwordx4 v[184:187], v255, s[82:83] offset:832
	ds_read_b64_tr_b16 v[72:73], v231
	ds_read_b64_tr_b16 v[74:75], v231 offset:512
	ds_read_b64_tr_b16 v[76:77], v231 offset:2048
	ds_read_b64_tr_b16 v[78:79], v231 offset:2560
	ds_read_b64_tr_b16 v[220:221], v231 offset:1024
	ds_read_b64_tr_b16 v[222:223], v231 offset:1536
	ds_read_b64_tr_b16 v[224:225], v231 offset:3072
	ds_read_b64_tr_b16 v[226:227], v231 offset:3584
	s_waitcnt vmcnt(8)
	ds_write_b128 v247, v[116:119]
	ds_write_b128 v247, v[120:123] offset:1024
	ds_write_b128 v247, v[124:127] offset:2048
	ds_write_b128 v247, v[128:131] offset:3072
	ds_read_b128 v[116:119], v248
	ds_read_b128 v[120:123], v249
	ds_read_b128 v[124:127], v250
	ds_read_b128 v[128:131], v251
	ds_write_b128 v112, v[132:135]
	ds_write_b128 v112, v[136:139] offset:1024
	ds_write_b128 v112, v[140:143] offset:2048
	ds_write_b128 v112, v[144:147] offset:3072
	v_exp_f32_e32 v188, v188
	v_exp_f32_e32 v189, v189
	v_exp_f32_e32 v190, v190
	v_exp_f32_e32 v191, v191
	v_exp_f32_e32 v192, v192
	v_exp_f32_e32 v193, v193
	s_waitcnt lgkmcnt(4)
	v_mfma_f32_32x32x16_bf16 v[32:47], v[116:119], v[48:51], v[32:47]
	v_exp_f32_e32 v194, v194
	v_exp_f32_e32 v195, v195
	v_mfma_f32_32x32x16_bf16 v[32:47], v[120:123], v[52:55], v[32:47]
	v_exp_f32_e32 v196, v196
	v_exp_f32_e32 v197, v197
	v_exp_f32_e32 v198, v198
	v_mfma_f32_32x32x16_bf16 v[32:47], v[124:127], v[56:59], v[32:47]
	v_exp_f32_e32 v199, v199
	v_exp_f32_e32 v200, v200
	v_mfma_f32_32x32x16_bf16 v[32:47], v[128:131], v[60:63], v[32:47]
	v_exp_f32_e32 v201, v201
	v_exp_f32_e32 v202, v202
	v_exp_f32_e32 v203, v203
	s_add_i32 s90, s67, 384
	v_lshlrev_b32_e32 v84, 2, v107
	v_add_u32_e32 v84, s90, v84
	v_add_u32_e32 v85, 0, v84
	v_add_u32_e32 v86, 4, v84
	v_add_u32_e32 v87, 8, v84
	v_add_u32_e32 v88, 12, v84
	v_cmp_gt_u32_e64 s[30:31], s98, v85
	v_cmp_gt_u32_e64 s[36:37], s98, v86
	v_cmp_gt_u32_e64 s[78:79], s98, v87
	v_cmp_gt_u32_e64 s[50:51], s98, v88
	v_cndmask_b32_e64 v188, 0, v188, s[30:31]
	v_add_u32_e32 v85, 32, v84
	v_cmp_gt_u32_e64 s[30:31], s98, v85
	v_cndmask_b32_e64 v189, 0, v189, s[36:37]
	v_add_u32_e32 v86, 36, v84
	v_cmp_gt_u32_e64 s[36:37], s98, v86
	v_cndmask_b32_e64 v190, 0, v190, s[78:79]
	v_add_u32_e32 v87, 40, v84
	v_cmp_gt_u32_e64 s[78:79], s98, v87
	v_cndmask_b32_e64 v191, 0, v191, s[50:51]
	v_add_u32_e32 v88, 44, v84
	v_cmp_gt_u32_e64 s[50:51], s98, v88
	v_cndmask_b32_e64 v192, 0, v192, s[30:31]
	v_add_u32_e32 v85, 64, v84
	v_cmp_gt_u32_e64 s[30:31], s98, v85
	v_cndmask_b32_e64 v193, 0, v193, s[36:37]
	v_add_u32_e32 v86, 68, v84
	v_cmp_gt_u32_e64 s[36:37], s98, v86
	v_cndmask_b32_e64 v194, 0, v194, s[78:79]
	v_add_u32_e32 v87, 72, v84
	v_cmp_gt_u32_e64 s[78:79], s98, v87
	v_cndmask_b32_e64 v195, 0, v195, s[50:51]
	v_add_u32_e32 v88, 76, v84
	v_cmp_gt_u32_e64 s[50:51], s98, v88
	v_cndmask_b32_e64 v196, 0, v196, s[30:31]
	v_add_u32_e32 v85, 96, v84
	v_cmp_gt_u32_e64 s[30:31], s98, v85
	v_cndmask_b32_e64 v197, 0, v197, s[36:37]
	v_add_u32_e32 v86, 100, v84
	v_cmp_gt_u32_e64 s[36:37], s98, v86
	v_cndmask_b32_e64 v198, 0, v198, s[78:79]
	v_add_u32_e32 v87, 104, v84
	v_cmp_gt_u32_e64 s[78:79], s98, v87
	v_cndmask_b32_e64 v199, 0, v199, s[50:51]
	v_add_u32_e32 v88, 108, v84
	v_cmp_gt_u32_e64 s[50:51], s98, v88
	v_nop
	v_cndmask_b32_e64 v200, 0, v200, s[30:31]
	v_cndmask_b32_e64 v201, 0, v201, s[36:37]
	v_cndmask_b32_e64 v202, 0, v202, s[78:79]
	v_cndmask_b32_e64 v203, 0, v203, s[50:51]
	v_cvt_pk_bf16_f32 v64, v188, v189
	v_cvt_pk_bf16_f32 v65, v190, v191
	v_cvt_pk_bf16_f32 v66, v192, v193
	v_cvt_pk_bf16_f32 v67, v194, v195
	v_cvt_pk_bf16_f32 v68, v196, v197
	v_cvt_pk_bf16_f32 v69, v198, v199
	v_cvt_pk_bf16_f32 v70, v200, v201
	v_cvt_pk_bf16_f32 v71, v202, v203
	v_pk_add_f32 v[232:233], v[232:233], v[188:189]
	v_pk_add_f32 v[232:233], v[232:233], v[190:191]
	v_pk_add_f32 v[232:233], v[232:233], v[192:193]
	v_pk_add_f32 v[232:233], v[232:233], v[194:195]
	v_pk_add_f32 v[232:233], v[232:233], v[196:197]
	v_pk_add_f32 v[232:233], v[232:233], v[198:199]
	v_pk_add_f32 v[232:233], v[232:233], v[200:201]
	v_pk_add_f32 v[232:233], v[232:233], v[202:203]
	ds_read2_b32 v[188:189], v115 offset0:224 offset1:225
	ds_read2_b32 v[190:191], v115 offset0:226 offset1:227
	ds_read2_b32 v[192:193], v115 offset0:232 offset1:233
	ds_read2_b32 v[194:195], v115 offset0:234 offset1:235
	ds_read2_b32 v[196:197], v115 offset0:240 offset1:241
	ds_read2_b32 v[198:199], v115 offset0:242 offset1:243
	ds_read2_b32 v[200:201], v115 offset0:248 offset1:249
	ds_read2_b32 v[202:203], v115 offset0:250 offset1:251
	v_mfma_f32_32x32x16_bf16 v[0:15], v[64:67], v[72:75], v[0:15]
	v_mfma_f32_32x32x16_bf16 v[16:31], v[64:67], v[76:79], v[16:31]
	v_mfma_f32_32x32x16_bf16 v[0:15], v[68:71], v[220:223], v[0:15]
	v_mfma_f32_32x32x16_bf16 v[16:31], v[68:71], v[224:227], v[16:31]
	s_add_i32 s90, s67, -1024
	v_add_u32_e32 v80, s90, v243
	v_add_u32_e32 v83, s90, v244
	v_add_u32_e32 v99, s90, v245
	v_add_u32_e32 v253, s90, v246
	v_add_u32_e32 v254, s90, v148
	v_add_u32_e32 v255, s90, v151
	v_med3_i32 v80, v80, 0, s99
	v_med3_i32 v83, v83, 0, s99
	v_med3_i32 v99, v99, 0, s99
	v_med3_i32 v253, v253, 0, s99
	v_med3_i32 v254, v254, 0, s99
	v_med3_i32 v255, v255, 0, s99
	v_mad_u32_u24 v80, v80, s100, v252
	v_mad_u32_u24 v83, v83, s100, v252
	v_mad_u32_u24 v99, v99, s100, v252
	v_mad_u32_u24 v253, v253, s100, v252
	v_mad_u32_u24 v254, v254, s100, v153
	v_mad_u32_u24 v255, v255, s100, v153
	global_load_dwordx4 v[116:119], v80, s[82:83]
	global_load_dwordx4 v[120:123], v83, s[82:83]
	global_load_dwordx4 v[124:127], v99, s[82:83]
	global_load_dwordx4 v[128:131], v253, s[82:83]
	global_load_dwordx4 v[132:135], v254, s[82:83] offset:768
	global_load_dwordx4 v[136:139], v255, s[82:83] offset:768
	global_load_dwordx4 v[140:143], v254, s[82:83] offset:832
	global_load_dwordx4 v[144:147], v255, s[82:83] offset:832
	ds_read_b64_tr_b16 v[72:73], v231
	ds_read_b64_tr_b16 v[74:75], v231 offset:512
	ds_read_b64_tr_b16 v[76:77], v231 offset:2048
	ds_read_b64_tr_b16 v[78:79], v231 offset:2560
	ds_read_b64_tr_b16 v[220:221], v231 offset:1024
	ds_read_b64_tr_b16 v[222:223], v231 offset:1536
	ds_read_b64_tr_b16 v[224:225], v231 offset:3072
	ds_read_b64_tr_b16 v[226:227], v231 offset:3584
	s_waitcnt vmcnt(8)
	ds_write_b128 v247, v[156:159]
	ds_write_b128 v247, v[160:163] offset:1024
	ds_write_b128 v247, v[164:167] offset:2048
	ds_write_b128 v247, v[168:171] offset:3072
	ds_read_b128 v[156:159], v248
	ds_read_b128 v[160:163], v249
	ds_read_b128 v[164:167], v250
	ds_read_b128 v[168:171], v251
	ds_write_b128 v112, v[172:175]
	ds_write_b128 v112, v[176:179] offset:1024
	ds_write_b128 v112, v[180:183] offset:2048
	ds_write_b128 v112, v[184:187] offset:3072
	v_exp_f32_e32 v32, v32
	v_exp_f32_e32 v33, v33
	v_exp_f32_e32 v34, v34
	v_exp_f32_e32 v35, v35
	v_exp_f32_e32 v36, v36
	v_exp_f32_e32 v37, v37
	s_waitcnt lgkmcnt(4)
	v_mfma_f32_32x32x16_bf16 v[188:203], v[156:159], v[48:51], v[188:203]
	v_exp_f32_e32 v38, v38
	v_exp_f32_e32 v39, v39
	v_mfma_f32_32x32x16_bf16 v[188:203], v[160:163], v[52:55], v[188:203]
	v_exp_f32_e32 v40, v40
	v_exp_f32_e32 v41, v41
	v_exp_f32_e32 v42, v42
	v_mfma_f32_32x32x16_bf16 v[188:203], v[164:167], v[56:59], v[188:203]
	v_exp_f32_e32 v43, v43
	v_exp_f32_e32 v44, v44
	v_mfma_f32_32x32x16_bf16 v[188:203], v[168:171], v[60:63], v[188:203]
	v_exp_f32_e32 v45, v45
	v_exp_f32_e32 v46, v46
	v_exp_f32_e32 v47, v47
	s_add_i32 s90, s67, 512
	v_lshlrev_b32_e32 v84, 2, v107
	v_add_u32_e32 v84, s90, v84
	v_add_u32_e32 v85, 0, v84
	v_add_u32_e32 v86, 4, v84
	v_add_u32_e32 v87, 8, v84
	v_add_u32_e32 v88, 12, v84
	v_cmp_gt_u32_e64 s[30:31], s98, v85
	v_cmp_gt_u32_e64 s[36:37], s98, v86
	v_cmp_gt_u32_e64 s[78:79], s98, v87
	v_cmp_gt_u32_e64 s[50:51], s98, v88
	v_cndmask_b32_e64 v32, 0, v32, s[30:31]
	v_add_u32_e32 v85, 32, v84
	v_cmp_gt_u32_e64 s[30:31], s98, v85
	v_cndmask_b32_e64 v33, 0, v33, s[36:37]
	v_add_u32_e32 v86, 36, v84
	v_cmp_gt_u32_e64 s[36:37], s98, v86
	v_cndmask_b32_e64 v34, 0, v34, s[78:79]
	v_add_u32_e32 v87, 40, v84
	v_cmp_gt_u32_e64 s[78:79], s98, v87
	v_cndmask_b32_e64 v35, 0, v35, s[50:51]
	v_add_u32_e32 v88, 44, v84
	v_cmp_gt_u32_e64 s[50:51], s98, v88
	v_cndmask_b32_e64 v36, 0, v36, s[30:31]
	v_add_u32_e32 v85, 64, v84
	v_cmp_gt_u32_e64 s[30:31], s98, v85
	v_cndmask_b32_e64 v37, 0, v37, s[36:37]
	v_add_u32_e32 v86, 68, v84
	v_cmp_gt_u32_e64 s[36:37], s98, v86
	v_cndmask_b32_e64 v38, 0, v38, s[78:79]
	v_add_u32_e32 v87, 72, v84
	v_cmp_gt_u32_e64 s[78:79], s98, v87
	v_cndmask_b32_e64 v39, 0, v39, s[50:51]
	v_add_u32_e32 v88, 76, v84
	v_cmp_gt_u32_e64 s[50:51], s98, v88
	v_cndmask_b32_e64 v40, 0, v40, s[30:31]
	v_add_u32_e32 v85, 96, v84
	v_cmp_gt_u32_e64 s[30:31], s98, v85
	v_cndmask_b32_e64 v41, 0, v41, s[36:37]
	v_add_u32_e32 v86, 100, v84
	v_cmp_gt_u32_e64 s[36:37], s98, v86
	v_cndmask_b32_e64 v42, 0, v42, s[78:79]
	v_add_u32_e32 v87, 104, v84
	v_cmp_gt_u32_e64 s[78:79], s98, v87
	v_cndmask_b32_e64 v43, 0, v43, s[50:51]
	v_add_u32_e32 v88, 108, v84
	v_cmp_gt_u32_e64 s[50:51], s98, v88
	v_nop
	v_cndmask_b32_e64 v44, 0, v44, s[30:31]
	v_cndmask_b32_e64 v45, 0, v45, s[36:37]
	v_cndmask_b32_e64 v46, 0, v46, s[78:79]
	v_cndmask_b32_e64 v47, 0, v47, s[50:51]
	v_cvt_pk_bf16_f32 v64, v32, v33
	v_cvt_pk_bf16_f32 v65, v34, v35
	v_cvt_pk_bf16_f32 v66, v36, v37
	v_cvt_pk_bf16_f32 v67, v38, v39
	v_cvt_pk_bf16_f32 v68, v40, v41
	v_cvt_pk_bf16_f32 v69, v42, v43
	v_cvt_pk_bf16_f32 v70, v44, v45
	v_cvt_pk_bf16_f32 v71, v46, v47
	v_pk_add_f32 v[232:233], v[232:233], v[32:33]
	v_pk_add_f32 v[232:233], v[232:233], v[34:35]
	v_pk_add_f32 v[232:233], v[232:233], v[36:37]
	v_pk_add_f32 v[232:233], v[232:233], v[38:39]
	v_pk_add_f32 v[232:233], v[232:233], v[40:41]
	v_pk_add_f32 v[232:233], v[232:233], v[42:43]
	v_pk_add_f32 v[232:233], v[232:233], v[44:45]
	v_pk_add_f32 v[232:233], v[232:233], v[46:47]
	v_mov_b32_e32 v115, v230
	ds_read2_b32 v[32:33], v115 offset0:0 offset1:1
	ds_read2_b32 v[34:35], v115 offset0:2 offset1:3
	ds_read2_b32 v[36:37], v115 offset0:8 offset1:9
	ds_read2_b32 v[38:39], v115 offset0:10 offset1:11
	ds_read2_b32 v[40:41], v115 offset0:16 offset1:17
	ds_read2_b32 v[42:43], v115 offset0:18 offset1:19
	ds_read2_b32 v[44:45], v115 offset0:24 offset1:25
	ds_read2_b32 v[46:47], v115 offset0:26 offset1:27
	v_mfma_f32_32x32x16_bf16 v[0:15], v[64:67], v[72:75], v[0:15]
	v_mfma_f32_32x32x16_bf16 v[16:31], v[64:67], v[76:79], v[16:31]
	v_mfma_f32_32x32x16_bf16 v[0:15], v[68:71], v[220:223], v[0:15]
	v_mfma_f32_32x32x16_bf16 v[16:31], v[68:71], v[224:227], v[16:31]
	s_add_i32 s90, s67, -512
	v_add_u32_e32 v80, s90, v243
	v_add_u32_e32 v83, s90, v244
	v_add_u32_e32 v99, s90, v245
	v_add_u32_e32 v253, s90, v246
	v_add_u32_e32 v254, s90, v148
	v_add_u32_e32 v255, s90, v151
	v_med3_i32 v80, v80, 0, s99
	v_med3_i32 v83, v83, 0, s99
	v_med3_i32 v99, v99, 0, s99
	v_med3_i32 v253, v253, 0, s99
	v_med3_i32 v254, v254, 0, s99
	v_med3_i32 v255, v255, 0, s99
	v_mad_u32_u24 v80, v80, s100, v252
	v_mad_u32_u24 v83, v83, s100, v252
	v_mad_u32_u24 v99, v99, s100, v252
	v_mad_u32_u24 v253, v253, s100, v252
	v_mad_u32_u24 v254, v254, s100, v153
	v_mad_u32_u24 v255, v255, s100, v153
	global_load_dwordx4 v[156:159], v80, s[82:83]
	global_load_dwordx4 v[160:163], v83, s[82:83]
	global_load_dwordx4 v[164:167], v99, s[82:83]
	global_load_dwordx4 v[168:171], v253, s[82:83]
	global_load_dwordx4 v[172:175], v254, s[82:83] offset:768
	global_load_dwordx4 v[176:179], v255, s[82:83] offset:768
	global_load_dwordx4 v[180:183], v254, s[82:83] offset:832
	global_load_dwordx4 v[184:187], v255, s[82:83] offset:832
	ds_read_b64_tr_b16 v[72:73], v231
	ds_read_b64_tr_b16 v[74:75], v231 offset:512
	ds_read_b64_tr_b16 v[76:77], v231 offset:2048
	ds_read_b64_tr_b16 v[78:79], v231 offset:2560
	ds_read_b64_tr_b16 v[220:221], v231 offset:1024
	ds_read_b64_tr_b16 v[222:223], v231 offset:1536
	ds_read_b64_tr_b16 v[224:225], v231 offset:3072
	ds_read_b64_tr_b16 v[226:227], v231 offset:3584
	s_waitcnt vmcnt(8)
	ds_write_b128 v247, v[116:119]
	ds_write_b128 v247, v[120:123] offset:1024
	ds_write_b128 v247, v[124:127] offset:2048
	ds_write_b128 v247, v[128:131] offset:3072
	ds_read_b128 v[116:119], v248
	ds_read_b128 v[120:123], v249
	ds_read_b128 v[124:127], v250
	ds_read_b128 v[128:131], v251
	ds_write_b128 v112, v[132:135]
	ds_write_b128 v112, v[136:139] offset:1024
	ds_write_b128 v112, v[140:143] offset:2048
	ds_write_b128 v112, v[144:147] offset:3072
	v_exp_f32_e32 v188, v188
	v_exp_f32_e32 v189, v189
	v_exp_f32_e32 v190, v190
	v_exp_f32_e32 v191, v191
	v_exp_f32_e32 v192, v192
	v_exp_f32_e32 v193, v193
	s_waitcnt lgkmcnt(4)
	v_mfma_f32_32x32x16_bf16 v[32:47], v[116:119], v[48:51], v[32:47]
	v_exp_f32_e32 v194, v194
	v_exp_f32_e32 v195, v195
	v_mfma_f32_32x32x16_bf16 v[32:47], v[120:123], v[52:55], v[32:47]
	v_exp_f32_e32 v196, v196
	v_exp_f32_e32 v197, v197
	v_exp_f32_e32 v198, v198
	v_mfma_f32_32x32x16_bf16 v[32:47], v[124:127], v[56:59], v[32:47]
	v_exp_f32_e32 v199, v199
	v_exp_f32_e32 v200, v200
	v_mfma_f32_32x32x16_bf16 v[32:47], v[128:131], v[60:63], v[32:47]
	v_exp_f32_e32 v201, v201
	v_exp_f32_e32 v202, v202
	v_exp_f32_e32 v203, v203
	s_add_i32 s90, s67, 640
	v_lshlrev_b32_e32 v84, 2, v107
	v_add_u32_e32 v84, s90, v84
	v_add_u32_e32 v85, 0, v84
	v_add_u32_e32 v86, 4, v84
	v_add_u32_e32 v87, 8, v84
	v_add_u32_e32 v88, 12, v84
	v_cmp_gt_u32_e64 s[30:31], s98, v85
	v_cmp_gt_u32_e64 s[36:37], s98, v86
	v_cmp_gt_u32_e64 s[78:79], s98, v87
	v_cmp_gt_u32_e64 s[50:51], s98, v88
	v_cndmask_b32_e64 v188, 0, v188, s[30:31]
	v_add_u32_e32 v85, 32, v84
	v_cmp_gt_u32_e64 s[30:31], s98, v85
	v_cndmask_b32_e64 v189, 0, v189, s[36:37]
	v_add_u32_e32 v86, 36, v84
	v_cmp_gt_u32_e64 s[36:37], s98, v86
	v_cndmask_b32_e64 v190, 0, v190, s[78:79]
	v_add_u32_e32 v87, 40, v84
	v_cmp_gt_u32_e64 s[78:79], s98, v87
	v_cndmask_b32_e64 v191, 0, v191, s[50:51]
	v_add_u32_e32 v88, 44, v84
	v_cmp_gt_u32_e64 s[50:51], s98, v88
	v_cndmask_b32_e64 v192, 0, v192, s[30:31]
	v_add_u32_e32 v85, 64, v84
	v_cmp_gt_u32_e64 s[30:31], s98, v85
	v_cndmask_b32_e64 v193, 0, v193, s[36:37]
	v_add_u32_e32 v86, 68, v84
	v_cmp_gt_u32_e64 s[36:37], s98, v86
	v_cndmask_b32_e64 v194, 0, v194, s[78:79]
	v_add_u32_e32 v87, 72, v84
	v_cmp_gt_u32_e64 s[78:79], s98, v87
	v_cndmask_b32_e64 v195, 0, v195, s[50:51]
	v_add_u32_e32 v88, 76, v84
	v_cmp_gt_u32_e64 s[50:51], s98, v88
	v_cndmask_b32_e64 v196, 0, v196, s[30:31]
	v_add_u32_e32 v85, 96, v84
	v_cmp_gt_u32_e64 s[30:31], s98, v85
	v_cndmask_b32_e64 v197, 0, v197, s[36:37]
	v_add_u32_e32 v86, 100, v84
	v_cmp_gt_u32_e64 s[36:37], s98, v86
	v_cndmask_b32_e64 v198, 0, v198, s[78:79]
	v_add_u32_e32 v87, 104, v84
	v_cmp_gt_u32_e64 s[78:79], s98, v87
	v_cndmask_b32_e64 v199, 0, v199, s[50:51]
	v_add_u32_e32 v88, 108, v84
	v_cmp_gt_u32_e64 s[50:51], s98, v88
	v_nop
	v_cndmask_b32_e64 v200, 0, v200, s[30:31]
	v_cndmask_b32_e64 v201, 0, v201, s[36:37]
	v_cndmask_b32_e64 v202, 0, v202, s[78:79]
	v_cndmask_b32_e64 v203, 0, v203, s[50:51]
	v_cvt_pk_bf16_f32 v64, v188, v189
	v_cvt_pk_bf16_f32 v65, v190, v191
	v_cvt_pk_bf16_f32 v66, v192, v193
	v_cvt_pk_bf16_f32 v67, v194, v195
	v_cvt_pk_bf16_f32 v68, v196, v197
	v_cvt_pk_bf16_f32 v69, v198, v199
	v_cvt_pk_bf16_f32 v70, v200, v201
	v_cvt_pk_bf16_f32 v71, v202, v203
	v_pk_add_f32 v[232:233], v[232:233], v[188:189]
	v_pk_add_f32 v[232:233], v[232:233], v[190:191]
	v_pk_add_f32 v[232:233], v[232:233], v[192:193]
	v_pk_add_f32 v[232:233], v[232:233], v[194:195]
	v_pk_add_f32 v[232:233], v[232:233], v[196:197]
	v_pk_add_f32 v[232:233], v[232:233], v[198:199]
	v_pk_add_f32 v[232:233], v[232:233], v[200:201]
	v_pk_add_f32 v[232:233], v[232:233], v[202:203]
	ds_read2_b32 v[188:189], v115 offset0:32 offset1:33
	ds_read2_b32 v[190:191], v115 offset0:34 offset1:35
	ds_read2_b32 v[192:193], v115 offset0:40 offset1:41
	ds_read2_b32 v[194:195], v115 offset0:42 offset1:43
	ds_read2_b32 v[196:197], v115 offset0:48 offset1:49
	ds_read2_b32 v[198:199], v115 offset0:50 offset1:51
	ds_read2_b32 v[200:201], v115 offset0:56 offset1:57
	ds_read2_b32 v[202:203], v115 offset0:58 offset1:59
	v_mfma_f32_32x32x16_bf16 v[0:15], v[64:67], v[72:75], v[0:15]
	v_mfma_f32_32x32x16_bf16 v[16:31], v[64:67], v[76:79], v[16:31]
	v_mfma_f32_32x32x16_bf16 v[0:15], v[68:71], v[220:223], v[0:15]
	v_mfma_f32_32x32x16_bf16 v[16:31], v[68:71], v[224:227], v[16:31]
	s_add_i32 s90, s67, 0
	v_add_u32_e32 v80, s90, v243
	v_add_u32_e32 v83, s90, v244
	v_add_u32_e32 v99, s90, v245
	v_add_u32_e32 v253, s90, v246
	v_add_u32_e32 v254, s90, v148
	v_add_u32_e32 v255, s90, v151
	v_med3_i32 v80, v80, 0, s99
	v_med3_i32 v83, v83, 0, s99
	v_med3_i32 v99, v99, 0, s99
	v_med3_i32 v253, v253, 0, s99
	v_med3_i32 v254, v254, 0, s99
	v_med3_i32 v255, v255, 0, s99
	v_mad_u32_u24 v80, v80, s100, v252
	v_mad_u32_u24 v83, v83, s100, v252
	v_mad_u32_u24 v99, v99, s100, v252
	v_mad_u32_u24 v253, v253, s100, v252
	v_mad_u32_u24 v254, v254, s100, v153
	v_mad_u32_u24 v255, v255, s100, v153
	global_load_dwordx4 v[116:119], v80, s[82:83]
	global_load_dwordx4 v[120:123], v83, s[82:83]
	global_load_dwordx4 v[124:127], v99, s[82:83]
	global_load_dwordx4 v[128:131], v253, s[82:83]
	global_load_dwordx4 v[132:135], v254, s[82:83] offset:768
	global_load_dwordx4 v[136:139], v255, s[82:83] offset:768
	global_load_dwordx4 v[140:143], v254, s[82:83] offset:832
	global_load_dwordx4 v[144:147], v255, s[82:83] offset:832
	ds_read_b64_tr_b16 v[72:73], v231
	ds_read_b64_tr_b16 v[74:75], v231 offset:512
	ds_read_b64_tr_b16 v[76:77], v231 offset:2048
	ds_read_b64_tr_b16 v[78:79], v231 offset:2560
	ds_read_b64_tr_b16 v[220:221], v231 offset:1024
	ds_read_b64_tr_b16 v[222:223], v231 offset:1536
	ds_read_b64_tr_b16 v[224:225], v231 offset:3072
	ds_read_b64_tr_b16 v[226:227], v231 offset:3584
	s_waitcnt vmcnt(8)
	ds_write_b128 v247, v[156:159]
	ds_write_b128 v247, v[160:163] offset:1024
	ds_write_b128 v247, v[164:167] offset:2048
	ds_write_b128 v247, v[168:171] offset:3072
	ds_read_b128 v[156:159], v248
	ds_read_b128 v[160:163], v249
	ds_read_b128 v[164:167], v250
	ds_read_b128 v[168:171], v251
	ds_write_b128 v112, v[172:175]
	ds_write_b128 v112, v[176:179] offset:1024
	ds_write_b128 v112, v[180:183] offset:2048
	ds_write_b128 v112, v[184:187] offset:3072
	v_exp_f32_e32 v32, v32
	v_exp_f32_e32 v33, v33
	v_exp_f32_e32 v34, v34
	v_exp_f32_e32 v35, v35
	v_exp_f32_e32 v36, v36
	v_exp_f32_e32 v37, v37
	s_waitcnt lgkmcnt(4)
	v_mfma_f32_32x32x16_bf16 v[188:203], v[156:159], v[48:51], v[188:203]
	v_exp_f32_e32 v38, v38
	v_exp_f32_e32 v39, v39
	v_mfma_f32_32x32x16_bf16 v[188:203], v[160:163], v[52:55], v[188:203]
	v_exp_f32_e32 v40, v40
	v_exp_f32_e32 v41, v41
	v_exp_f32_e32 v42, v42
	v_mfma_f32_32x32x16_bf16 v[188:203], v[164:167], v[56:59], v[188:203]
	v_exp_f32_e32 v43, v43
	v_exp_f32_e32 v44, v44
	v_mfma_f32_32x32x16_bf16 v[188:203], v[168:171], v[60:63], v[188:203]
	v_exp_f32_e32 v45, v45
	v_exp_f32_e32 v46, v46
	v_exp_f32_e32 v47, v47
	s_add_i32 s90, s67, -1024
	v_lshlrev_b32_e32 v84, 4, v107
	v_add_u32_e32 v84, s90, v84
	v_add_u32_e32 v85, 0, v84
	v_add_u32_e32 v86, 16, v84
	v_add_u32_e32 v87, 32, v84
	v_add_u32_e32 v88, 48, v84
	v_cmp_gt_u32_e64 s[30:31], s98, v85
	v_cmp_gt_u32_e64 s[36:37], s98, v86
	v_cmp_gt_u32_e64 s[78:79], s98, v87
	v_cmp_gt_u32_e64 s[50:51], s98, v88
	v_cndmask_b32_e64 v32, 0, v32, s[30:31]
	v_add_u32_e32 v85, 128, v84
	v_cmp_gt_u32_e64 s[30:31], s98, v85
	v_cndmask_b32_e64 v33, 0, v33, s[36:37]
	v_add_u32_e32 v86, 144, v84
	v_cmp_gt_u32_e64 s[36:37], s98, v86
	v_cndmask_b32_e64 v34, 0, v34, s[78:79]
	v_add_u32_e32 v87, 160, v84
	v_cmp_gt_u32_e64 s[78:79], s98, v87
	v_cndmask_b32_e64 v35, 0, v35, s[50:51]
	v_add_u32_e32 v88, 176, v84
	v_cmp_gt_u32_e64 s[50:51], s98, v88
	v_cndmask_b32_e64 v36, 0, v36, s[30:31]
	v_add_u32_e32 v85, 256, v84
	v_cmp_gt_u32_e64 s[30:31], s98, v85
	v_cndmask_b32_e64 v37, 0, v37, s[36:37]
	v_add_u32_e32 v86, 272, v84
	v_cmp_gt_u32_e64 s[36:37], s98, v86
	v_cndmask_b32_e64 v38, 0, v38, s[78:79]
	v_add_u32_e32 v87, 288, v84
	v_cmp_gt_u32_e64 s[78:79], s98, v87
	v_cndmask_b32_e64 v39, 0, v39, s[50:51]
	v_add_u32_e32 v88, 304, v84
	v_cmp_gt_u32_e64 s[50:51], s98, v88
	v_cndmask_b32_e64 v40, 0, v40, s[30:31]
	v_add_u32_e32 v85, 384, v84
	v_cmp_gt_u32_e64 s[30:31], s98, v85
	v_cndmask_b32_e64 v41, 0, v41, s[36:37]
	v_add_u32_e32 v86, 400, v84
	v_cmp_gt_u32_e64 s[36:37], s98, v86
	v_cndmask_b32_e64 v42, 0, v42, s[78:79]
	v_add_u32_e32 v87, 416, v84
	v_cmp_gt_u32_e64 s[78:79], s98, v87
	v_cndmask_b32_e64 v43, 0, v43, s[50:51]
	v_add_u32_e32 v88, 432, v84
	v_cmp_gt_u32_e64 s[50:51], s98, v88
	v_nop
	v_cndmask_b32_e64 v44, 0, v44, s[30:31]
	v_cndmask_b32_e64 v45, 0, v45, s[36:37]
	v_cndmask_b32_e64 v46, 0, v46, s[78:79]
	v_cndmask_b32_e64 v47, 0, v47, s[50:51]
	v_cvt_pk_bf16_f32 v64, v32, v33
	v_cvt_pk_bf16_f32 v65, v34, v35
	v_cvt_pk_bf16_f32 v66, v36, v37
	v_cvt_pk_bf16_f32 v67, v38, v39
	v_cvt_pk_bf16_f32 v68, v40, v41
	v_cvt_pk_bf16_f32 v69, v42, v43
	v_cvt_pk_bf16_f32 v70, v44, v45
	v_cvt_pk_bf16_f32 v71, v46, v47
	v_pk_add_f32 v[232:233], v[232:233], v[32:33]
	v_pk_add_f32 v[232:233], v[232:233], v[34:35]
	v_pk_add_f32 v[232:233], v[232:233], v[36:37]
	v_pk_add_f32 v[232:233], v[232:233], v[38:39]
	v_pk_add_f32 v[232:233], v[232:233], v[40:41]
	v_pk_add_f32 v[232:233], v[232:233], v[42:43]
	v_pk_add_f32 v[232:233], v[232:233], v[44:45]
	v_pk_add_f32 v[232:233], v[232:233], v[46:47]
	ds_read2_b32 v[32:33], v115 offset0:64 offset1:65
	ds_read2_b32 v[34:35], v115 offset0:66 offset1:67
	ds_read2_b32 v[36:37], v115 offset0:72 offset1:73
	ds_read2_b32 v[38:39], v115 offset0:74 offset1:75
	ds_read2_b32 v[40:41], v115 offset0:80 offset1:81
	ds_read2_b32 v[42:43], v115 offset0:82 offset1:83
	ds_read2_b32 v[44:45], v115 offset0:88 offset1:89
	ds_read2_b32 v[46:47], v115 offset0:90 offset1:91
	v_mfma_f32_32x32x16_bf16 v[0:15], v[64:67], v[72:75], v[0:15]
	v_mfma_f32_32x32x16_bf16 v[16:31], v[64:67], v[76:79], v[16:31]
	v_mfma_f32_32x32x16_bf16 v[0:15], v[68:71], v[220:223], v[0:15]
	v_mfma_f32_32x32x16_bf16 v[16:31], v[68:71], v[224:227], v[16:31]
	s_add_i32 s90, s67, 512
	v_add_u32_e32 v80, s90, v243
	v_add_u32_e32 v83, s90, v244
	v_add_u32_e32 v99, s90, v245
	v_add_u32_e32 v253, s90, v246
	v_add_u32_e32 v254, s90, v148
	v_add_u32_e32 v255, s90, v151
	v_med3_i32 v80, v80, 0, s99
	v_med3_i32 v83, v83, 0, s99
	v_med3_i32 v99, v99, 0, s99
	v_med3_i32 v253, v253, 0, s99
	v_med3_i32 v254, v254, 0, s99
	v_med3_i32 v255, v255, 0, s99
	v_mad_u32_u24 v80, v80, s100, v252
	v_mad_u32_u24 v83, v83, s100, v252
	v_mad_u32_u24 v99, v99, s100, v252
	v_mad_u32_u24 v253, v253, s100, v252
	v_mad_u32_u24 v254, v254, s100, v153
	v_mad_u32_u24 v255, v255, s100, v153
	global_load_dwordx4 v[156:159], v80, s[82:83]
	global_load_dwordx4 v[160:163], v83, s[82:83]
	global_load_dwordx4 v[164:167], v99, s[82:83]
	global_load_dwordx4 v[168:171], v253, s[82:83]
	global_load_dwordx4 v[172:175], v254, s[82:83] offset:768
	global_load_dwordx4 v[176:179], v255, s[82:83] offset:768
	global_load_dwordx4 v[180:183], v254, s[82:83] offset:832
	global_load_dwordx4 v[184:187], v255, s[82:83] offset:832
	ds_read_b64_tr_b16 v[72:73], v231
	ds_read_b64_tr_b16 v[74:75], v231 offset:512
	ds_read_b64_tr_b16 v[76:77], v231 offset:2048
	ds_read_b64_tr_b16 v[78:79], v231 offset:2560
	ds_read_b64_tr_b16 v[220:221], v231 offset:1024
	ds_read_b64_tr_b16 v[222:223], v231 offset:1536
	ds_read_b64_tr_b16 v[224:225], v231 offset:3072
	ds_read_b64_tr_b16 v[226:227], v231 offset:3584
	s_waitcnt vmcnt(8)
	ds_write_b128 v247, v[116:119]
	ds_write_b128 v247, v[120:123] offset:1024
	ds_write_b128 v247, v[124:127] offset:2048
	ds_write_b128 v247, v[128:131] offset:3072
	ds_read_b128 v[116:119], v248
	ds_read_b128 v[120:123], v249
	ds_read_b128 v[124:127], v250
	ds_read_b128 v[128:131], v251
	ds_write_b128 v112, v[132:135]
	ds_write_b128 v112, v[136:139] offset:1024
	ds_write_b128 v112, v[140:143] offset:2048
	ds_write_b128 v112, v[144:147] offset:3072
	v_exp_f32_e32 v188, v188
	v_exp_f32_e32 v189, v189
	v_exp_f32_e32 v190, v190
	v_exp_f32_e32 v191, v191
	v_exp_f32_e32 v192, v192
	v_exp_f32_e32 v193, v193
	s_waitcnt lgkmcnt(4)
	v_mfma_f32_32x32x16_bf16 v[32:47], v[116:119], v[48:51], v[32:47]
	v_exp_f32_e32 v194, v194
	v_exp_f32_e32 v195, v195
	v_mfma_f32_32x32x16_bf16 v[32:47], v[120:123], v[52:55], v[32:47]
	v_exp_f32_e32 v196, v196
	v_exp_f32_e32 v197, v197
	v_exp_f32_e32 v198, v198
	v_mfma_f32_32x32x16_bf16 v[32:47], v[124:127], v[56:59], v[32:47]
	v_exp_f32_e32 v199, v199
	v_exp_f32_e32 v200, v200
	v_mfma_f32_32x32x16_bf16 v[32:47], v[128:131], v[60:63], v[32:47]
	v_exp_f32_e32 v201, v201
	v_exp_f32_e32 v202, v202
	v_exp_f32_e32 v203, v203
	s_add_i32 s90, s67, -512
	v_lshlrev_b32_e32 v84, 4, v107
	v_add_u32_e32 v84, s90, v84
	v_add_u32_e32 v85, 0, v84
	v_add_u32_e32 v86, 16, v84
	v_add_u32_e32 v87, 32, v84
	v_add_u32_e32 v88, 48, v84
	v_cmp_gt_u32_e64 s[30:31], s98, v85
	v_cmp_gt_u32_e64 s[36:37], s98, v86
	v_cmp_gt_u32_e64 s[78:79], s98, v87
	v_cmp_gt_u32_e64 s[50:51], s98, v88
	v_cndmask_b32_e64 v188, 0, v188, s[30:31]
	v_add_u32_e32 v85, 128, v84
	v_cmp_gt_u32_e64 s[30:31], s98, v85
	v_cndmask_b32_e64 v189, 0, v189, s[36:37]
	v_add_u32_e32 v86, 144, v84
	v_cmp_gt_u32_e64 s[36:37], s98, v86
	v_cndmask_b32_e64 v190, 0, v190, s[78:79]
	v_add_u32_e32 v87, 160, v84
	v_cmp_gt_u32_e64 s[78:79], s98, v87
	v_cndmask_b32_e64 v191, 0, v191, s[50:51]
	v_add_u32_e32 v88, 176, v84
	v_cmp_gt_u32_e64 s[50:51], s98, v88
	v_cndmask_b32_e64 v192, 0, v192, s[30:31]
	v_add_u32_e32 v85, 256, v84
	v_cmp_gt_u32_e64 s[30:31], s98, v85
	v_cndmask_b32_e64 v193, 0, v193, s[36:37]
	v_add_u32_e32 v86, 272, v84
	v_cmp_gt_u32_e64 s[36:37], s98, v86
	v_cndmask_b32_e64 v194, 0, v194, s[78:79]
	v_add_u32_e32 v87, 288, v84
	v_cmp_gt_u32_e64 s[78:79], s98, v87
	v_cndmask_b32_e64 v195, 0, v195, s[50:51]
	v_add_u32_e32 v88, 304, v84
	v_cmp_gt_u32_e64 s[50:51], s98, v88
	v_cndmask_b32_e64 v196, 0, v196, s[30:31]
	v_add_u32_e32 v85, 384, v84
	v_cmp_gt_u32_e64 s[30:31], s98, v85
	v_cndmask_b32_e64 v197, 0, v197, s[36:37]
	v_add_u32_e32 v86, 400, v84
	v_cmp_gt_u32_e64 s[36:37], s98, v86
	v_cndmask_b32_e64 v198, 0, v198, s[78:79]
	v_add_u32_e32 v87, 416, v84
	v_cmp_gt_u32_e64 s[78:79], s98, v87
	v_cndmask_b32_e64 v199, 0, v199, s[50:51]
	v_add_u32_e32 v88, 432, v84
	v_cmp_gt_u32_e64 s[50:51], s98, v88
	v_nop
	v_cndmask_b32_e64 v200, 0, v200, s[30:31]
	v_cndmask_b32_e64 v201, 0, v201, s[36:37]
	v_cndmask_b32_e64 v202, 0, v202, s[78:79]
	v_cndmask_b32_e64 v203, 0, v203, s[50:51]
	v_cvt_pk_bf16_f32 v64, v188, v189
	v_cvt_pk_bf16_f32 v65, v190, v191
	v_cvt_pk_bf16_f32 v66, v192, v193
	v_cvt_pk_bf16_f32 v67, v194, v195
	v_cvt_pk_bf16_f32 v68, v196, v197
	v_cvt_pk_bf16_f32 v69, v198, v199
	v_cvt_pk_bf16_f32 v70, v200, v201
	v_cvt_pk_bf16_f32 v71, v202, v203
	v_pk_add_f32 v[232:233], v[232:233], v[188:189]
	v_pk_add_f32 v[232:233], v[232:233], v[190:191]
	v_pk_add_f32 v[232:233], v[232:233], v[192:193]
	v_pk_add_f32 v[232:233], v[232:233], v[194:195]
	v_pk_add_f32 v[232:233], v[232:233], v[196:197]
	v_pk_add_f32 v[232:233], v[232:233], v[198:199]
	v_pk_add_f32 v[232:233], v[232:233], v[200:201]
	v_pk_add_f32 v[232:233], v[232:233], v[202:203]
	ds_read2_b32 v[188:189], v115 offset0:96 offset1:97
	ds_read2_b32 v[190:191], v115 offset0:98 offset1:99
	ds_read2_b32 v[192:193], v115 offset0:104 offset1:105
	ds_read2_b32 v[194:195], v115 offset0:106 offset1:107
	ds_read2_b32 v[196:197], v115 offset0:112 offset1:113
	ds_read2_b32 v[198:199], v115 offset0:114 offset1:115
	ds_read2_b32 v[200:201], v115 offset0:120 offset1:121
	ds_read2_b32 v[202:203], v115 offset0:122 offset1:123
	v_mfma_f32_32x32x16_bf16 v[0:15], v[64:67], v[72:75], v[0:15]
	v_mfma_f32_32x32x16_bf16 v[16:31], v[64:67], v[76:79], v[16:31]
	v_mfma_f32_32x32x16_bf16 v[0:15], v[68:71], v[220:223], v[0:15]
	v_mfma_f32_32x32x16_bf16 v[16:31], v[68:71], v[224:227], v[16:31]
	s_add_i32 s90, s67, 1024
	v_add_u32_e32 v80, s90, v243
	v_add_u32_e32 v83, s90, v244
	v_add_u32_e32 v99, s90, v245
	v_add_u32_e32 v253, s90, v246
	v_add_u32_e32 v254, s90, v148
	v_add_u32_e32 v255, s90, v151
	v_med3_i32 v80, v80, 0, s99
	v_med3_i32 v83, v83, 0, s99
	v_med3_i32 v99, v99, 0, s99
	v_med3_i32 v253, v253, 0, s99
	v_med3_i32 v254, v254, 0, s99
	v_med3_i32 v255, v255, 0, s99
	v_mad_u32_u24 v80, v80, s100, v252
	v_mad_u32_u24 v83, v83, s100, v252
	v_mad_u32_u24 v99, v99, s100, v252
	v_mad_u32_u24 v253, v253, s100, v252
	v_mad_u32_u24 v254, v254, s100, v153
	v_mad_u32_u24 v255, v255, s100, v153
	global_load_dwordx4 v[116:119], v80, s[82:83]
	global_load_dwordx4 v[120:123], v83, s[82:83]
	global_load_dwordx4 v[124:127], v99, s[82:83]
	global_load_dwordx4 v[128:131], v253, s[82:83]
	global_load_dwordx4 v[132:135], v254, s[82:83] offset:768
	global_load_dwordx4 v[136:139], v255, s[82:83] offset:768
	global_load_dwordx4 v[140:143], v254, s[82:83] offset:832
	global_load_dwordx4 v[144:147], v255, s[82:83] offset:832
	ds_read_b64_tr_b16 v[72:73], v231
	ds_read_b64_tr_b16 v[74:75], v231 offset:512
	ds_read_b64_tr_b16 v[76:77], v231 offset:2048
	ds_read_b64_tr_b16 v[78:79], v231 offset:2560
	ds_read_b64_tr_b16 v[220:221], v231 offset:1024
	ds_read_b64_tr_b16 v[222:223], v231 offset:1536
	ds_read_b64_tr_b16 v[224:225], v231 offset:3072
	ds_read_b64_tr_b16 v[226:227], v231 offset:3584
	s_waitcnt vmcnt(8)
	ds_write_b128 v247, v[156:159]
	ds_write_b128 v247, v[160:163] offset:1024
	ds_write_b128 v247, v[164:167] offset:2048
	ds_write_b128 v247, v[168:171] offset:3072
	ds_read_b128 v[156:159], v248
	ds_read_b128 v[160:163], v249
	ds_read_b128 v[164:167], v250
	ds_read_b128 v[168:171], v251
	ds_write_b128 v112, v[172:175]
	ds_write_b128 v112, v[176:179] offset:1024
	ds_write_b128 v112, v[180:183] offset:2048
	ds_write_b128 v112, v[184:187] offset:3072
	v_exp_f32_e32 v32, v32
	v_exp_f32_e32 v33, v33
	v_exp_f32_e32 v34, v34
	v_exp_f32_e32 v35, v35
	v_exp_f32_e32 v36, v36
	v_exp_f32_e32 v37, v37
	s_waitcnt lgkmcnt(4)
	v_mfma_f32_32x32x16_bf16 v[188:203], v[156:159], v[48:51], v[188:203]
	v_exp_f32_e32 v38, v38
	v_exp_f32_e32 v39, v39
	v_mfma_f32_32x32x16_bf16 v[188:203], v[160:163], v[52:55], v[188:203]
	v_exp_f32_e32 v40, v40
	v_exp_f32_e32 v41, v41
	v_exp_f32_e32 v42, v42
	v_mfma_f32_32x32x16_bf16 v[188:203], v[164:167], v[56:59], v[188:203]
	v_exp_f32_e32 v43, v43
	v_exp_f32_e32 v44, v44
	v_mfma_f32_32x32x16_bf16 v[188:203], v[168:171], v[60:63], v[188:203]
	v_exp_f32_e32 v45, v45
	v_exp_f32_e32 v46, v46
	v_exp_f32_e32 v47, v47
	s_add_i32 s90, s67, 0
	v_lshlrev_b32_e32 v84, 4, v107
	v_add_u32_e32 v84, s90, v84
	v_add_u32_e32 v85, 0, v84
	v_add_u32_e32 v86, 16, v84
	v_add_u32_e32 v87, 32, v84
	v_add_u32_e32 v88, 48, v84
	v_cmp_gt_u32_e64 s[30:31], s98, v85
	v_cmp_gt_u32_e64 s[36:37], s98, v86
	v_cmp_gt_u32_e64 s[78:79], s98, v87
	v_cmp_gt_u32_e64 s[50:51], s98, v88
	v_cndmask_b32_e64 v32, 0, v32, s[30:31]
	v_add_u32_e32 v85, 128, v84
	v_cmp_gt_u32_e64 s[30:31], s98, v85
	v_cndmask_b32_e64 v33, 0, v33, s[36:37]
	v_add_u32_e32 v86, 144, v84
	v_cmp_gt_u32_e64 s[36:37], s98, v86
	v_cndmask_b32_e64 v34, 0, v34, s[78:79]
	v_add_u32_e32 v87, 160, v84
	v_cmp_gt_u32_e64 s[78:79], s98, v87
	v_cndmask_b32_e64 v35, 0, v35, s[50:51]
	v_add_u32_e32 v88, 176, v84
	v_cmp_gt_u32_e64 s[50:51], s98, v88
	v_cndmask_b32_e64 v36, 0, v36, s[30:31]
	v_add_u32_e32 v85, 256, v84
	v_cmp_gt_u32_e64 s[30:31], s98, v85
	v_cndmask_b32_e64 v37, 0, v37, s[36:37]
	v_add_u32_e32 v86, 272, v84
	v_cmp_gt_u32_e64 s[36:37], s98, v86
	v_cndmask_b32_e64 v38, 0, v38, s[78:79]
	v_add_u32_e32 v87, 288, v84
	v_cmp_gt_u32_e64 s[78:79], s98, v87
	v_cndmask_b32_e64 v39, 0, v39, s[50:51]
	v_add_u32_e32 v88, 304, v84
	v_cmp_gt_u32_e64 s[50:51], s98, v88
	v_cndmask_b32_e64 v40, 0, v40, s[30:31]
	v_add_u32_e32 v85, 384, v84
	v_cmp_gt_u32_e64 s[30:31], s98, v85
	v_cndmask_b32_e64 v41, 0, v41, s[36:37]
	v_add_u32_e32 v86, 400, v84
	v_cmp_gt_u32_e64 s[36:37], s98, v86
	v_cndmask_b32_e64 v42, 0, v42, s[78:79]
	v_add_u32_e32 v87, 416, v84
	v_cmp_gt_u32_e64 s[78:79], s98, v87
	v_cndmask_b32_e64 v43, 0, v43, s[50:51]
	v_add_u32_e32 v88, 432, v84
	v_cmp_gt_u32_e64 s[50:51], s98, v88
	v_nop
	v_cndmask_b32_e64 v44, 0, v44, s[30:31]
	v_cndmask_b32_e64 v45, 0, v45, s[36:37]
	v_cndmask_b32_e64 v46, 0, v46, s[78:79]
	v_cndmask_b32_e64 v47, 0, v47, s[50:51]
	v_cvt_pk_bf16_f32 v64, v32, v33
	v_cvt_pk_bf16_f32 v65, v34, v35
	v_cvt_pk_bf16_f32 v66, v36, v37
	v_cvt_pk_bf16_f32 v67, v38, v39
	v_cvt_pk_bf16_f32 v68, v40, v41
	v_cvt_pk_bf16_f32 v69, v42, v43
	v_cvt_pk_bf16_f32 v70, v44, v45
	v_cvt_pk_bf16_f32 v71, v46, v47
	v_pk_add_f32 v[232:233], v[232:233], v[32:33]
	v_pk_add_f32 v[232:233], v[232:233], v[34:35]
	v_pk_add_f32 v[232:233], v[232:233], v[36:37]
	v_pk_add_f32 v[232:233], v[232:233], v[38:39]
	v_pk_add_f32 v[232:233], v[232:233], v[40:41]
	v_pk_add_f32 v[232:233], v[232:233], v[42:43]
	v_pk_add_f32 v[232:233], v[232:233], v[44:45]
	v_pk_add_f32 v[232:233], v[232:233], v[46:47]
	ds_read2_b32 v[32:33], v115 offset0:128 offset1:129
	ds_read2_b32 v[34:35], v115 offset0:130 offset1:131
	ds_read2_b32 v[36:37], v115 offset0:136 offset1:137
	ds_read2_b32 v[38:39], v115 offset0:138 offset1:139
	ds_read2_b32 v[40:41], v115 offset0:144 offset1:145
	ds_read2_b32 v[42:43], v115 offset0:146 offset1:147
	ds_read2_b32 v[44:45], v115 offset0:152 offset1:153
	ds_read2_b32 v[46:47], v115 offset0:154 offset1:155
	v_mfma_f32_32x32x16_bf16 v[0:15], v[64:67], v[72:75], v[0:15]
	v_mfma_f32_32x32x16_bf16 v[16:31], v[64:67], v[76:79], v[16:31]
	v_mfma_f32_32x32x16_bf16 v[0:15], v[68:71], v[220:223], v[0:15]
	v_mfma_f32_32x32x16_bf16 v[16:31], v[68:71], v[224:227], v[16:31]
	ds_read_b64_tr_b16 v[72:73], v231
	ds_read_b64_tr_b16 v[74:75], v231 offset:512
	ds_read_b64_tr_b16 v[76:77], v231 offset:2048
	ds_read_b64_tr_b16 v[78:79], v231 offset:2560
	ds_read_b64_tr_b16 v[220:221], v231 offset:1024
	ds_read_b64_tr_b16 v[222:223], v231 offset:1536
	ds_read_b64_tr_b16 v[224:225], v231 offset:3072
	ds_read_b64_tr_b16 v[226:227], v231 offset:3584
	s_waitcnt vmcnt(0)
	ds_write_b128 v247, v[116:119]
	ds_write_b128 v247, v[120:123] offset:1024
	ds_write_b128 v247, v[124:127] offset:2048
	ds_write_b128 v247, v[128:131] offset:3072
	ds_read_b128 v[116:119], v248
	ds_read_b128 v[120:123], v249
	ds_read_b128 v[124:127], v250
	ds_read_b128 v[128:131], v251
	ds_write_b128 v112, v[132:135]
	ds_write_b128 v112, v[136:139] offset:1024
	ds_write_b128 v112, v[140:143] offset:2048
	ds_write_b128 v112, v[144:147] offset:3072
	v_exp_f32_e32 v188, v188
	v_exp_f32_e32 v189, v189
	v_exp_f32_e32 v190, v190
	v_exp_f32_e32 v191, v191
	v_exp_f32_e32 v192, v192
	v_exp_f32_e32 v193, v193
	s_waitcnt lgkmcnt(4)
	v_mfma_f32_32x32x16_bf16 v[32:47], v[116:119], v[48:51], v[32:47]
	v_exp_f32_e32 v194, v194
	v_exp_f32_e32 v195, v195
	v_mfma_f32_32x32x16_bf16 v[32:47], v[120:123], v[52:55], v[32:47]
	v_exp_f32_e32 v196, v196
	v_exp_f32_e32 v197, v197
	v_exp_f32_e32 v198, v198
	v_mfma_f32_32x32x16_bf16 v[32:47], v[124:127], v[56:59], v[32:47]
	v_exp_f32_e32 v199, v199
	v_exp_f32_e32 v200, v200
	v_mfma_f32_32x32x16_bf16 v[32:47], v[128:131], v[60:63], v[32:47]
	v_exp_f32_e32 v201, v201
	v_exp_f32_e32 v202, v202
	v_exp_f32_e32 v203, v203
	s_add_i32 s90, s67, 512
	v_lshlrev_b32_e32 v84, 4, v107
	v_add_u32_e32 v84, s90, v84
	v_add_u32_e32 v85, 0, v84
	v_add_u32_e32 v86, 16, v84
	v_add_u32_e32 v87, 32, v84
	v_add_u32_e32 v88, 48, v84
	v_cmp_gt_u32_e64 s[30:31], s98, v85
	v_cmp_gt_u32_e64 s[36:37], s98, v86
	v_cmp_gt_u32_e64 s[78:79], s98, v87
	v_cmp_gt_u32_e64 s[50:51], s98, v88
	v_cndmask_b32_e64 v188, 0, v188, s[30:31]
	v_add_u32_e32 v85, 128, v84
	v_cmp_gt_u32_e64 s[30:31], s98, v85
	v_cndmask_b32_e64 v189, 0, v189, s[36:37]
	v_add_u32_e32 v86, 144, v84
	v_cmp_gt_u32_e64 s[36:37], s98, v86
	v_cndmask_b32_e64 v190, 0, v190, s[78:79]
	v_add_u32_e32 v87, 160, v84
	v_cmp_gt_u32_e64 s[78:79], s98, v87
	v_cndmask_b32_e64 v191, 0, v191, s[50:51]
	v_add_u32_e32 v88, 176, v84
	v_cmp_gt_u32_e64 s[50:51], s98, v88
	v_cndmask_b32_e64 v192, 0, v192, s[30:31]
	v_add_u32_e32 v85, 256, v84
	v_cmp_gt_u32_e64 s[30:31], s98, v85
	v_cndmask_b32_e64 v193, 0, v193, s[36:37]
	v_add_u32_e32 v86, 272, v84
	v_cmp_gt_u32_e64 s[36:37], s98, v86
	v_cndmask_b32_e64 v194, 0, v194, s[78:79]
	v_add_u32_e32 v87, 288, v84
	v_cmp_gt_u32_e64 s[78:79], s98, v87
	v_cndmask_b32_e64 v195, 0, v195, s[50:51]
	v_add_u32_e32 v88, 304, v84
	v_cmp_gt_u32_e64 s[50:51], s98, v88
	v_cndmask_b32_e64 v196, 0, v196, s[30:31]
	v_add_u32_e32 v85, 384, v84
	v_cmp_gt_u32_e64 s[30:31], s98, v85
	v_cndmask_b32_e64 v197, 0, v197, s[36:37]
	v_add_u32_e32 v86, 400, v84
	v_cmp_gt_u32_e64 s[36:37], s98, v86
	v_cndmask_b32_e64 v198, 0, v198, s[78:79]
	v_add_u32_e32 v87, 416, v84
	v_cmp_gt_u32_e64 s[78:79], s98, v87
	v_cndmask_b32_e64 v199, 0, v199, s[50:51]
	v_add_u32_e32 v88, 432, v84
	v_cmp_gt_u32_e64 s[50:51], s98, v88
	v_nop
	v_cndmask_b32_e64 v200, 0, v200, s[30:31]
	v_cndmask_b32_e64 v201, 0, v201, s[36:37]
	v_cndmask_b32_e64 v202, 0, v202, s[78:79]
	v_cndmask_b32_e64 v203, 0, v203, s[50:51]
	v_cvt_pk_bf16_f32 v64, v188, v189
	v_cvt_pk_bf16_f32 v65, v190, v191
	v_cvt_pk_bf16_f32 v66, v192, v193
	v_cvt_pk_bf16_f32 v67, v194, v195
	v_cvt_pk_bf16_f32 v68, v196, v197
	v_cvt_pk_bf16_f32 v69, v198, v199
	v_cvt_pk_bf16_f32 v70, v200, v201
	v_cvt_pk_bf16_f32 v71, v202, v203
	v_pk_add_f32 v[232:233], v[232:233], v[188:189]
	v_pk_add_f32 v[232:233], v[232:233], v[190:191]
	v_pk_add_f32 v[232:233], v[232:233], v[192:193]
	v_pk_add_f32 v[232:233], v[232:233], v[194:195]
	v_pk_add_f32 v[232:233], v[232:233], v[196:197]
	v_pk_add_f32 v[232:233], v[232:233], v[198:199]
	v_pk_add_f32 v[232:233], v[232:233], v[200:201]
	v_pk_add_f32 v[232:233], v[232:233], v[202:203]
	v_mfma_f32_32x32x16_bf16 v[0:15], v[64:67], v[72:75], v[0:15]
	v_mfma_f32_32x32x16_bf16 v[16:31], v[64:67], v[76:79], v[16:31]
	v_mfma_f32_32x32x16_bf16 v[0:15], v[68:71], v[220:223], v[0:15]
	v_mfma_f32_32x32x16_bf16 v[16:31], v[68:71], v[224:227], v[16:31]
	ds_read_b64_tr_b16 v[72:73], v231
	ds_read_b64_tr_b16 v[74:75], v231 offset:512
	ds_read_b64_tr_b16 v[76:77], v231 offset:2048
	ds_read_b64_tr_b16 v[78:79], v231 offset:2560
	ds_read_b64_tr_b16 v[220:221], v231 offset:1024
	ds_read_b64_tr_b16 v[222:223], v231 offset:1536
	ds_read_b64_tr_b16 v[224:225], v231 offset:3072
	ds_read_b64_tr_b16 v[226:227], v231 offset:3584
	s_waitcnt lgkmcnt(0)
; __device__ __forceinline__ int crow(int r, int hi) { return (r & 3) + 8 * (r >> 2) + 4 * hi; }
; __device__ __forceinline__ void dil_unit(LAS unsigned char* lds, bf16_t* proj, int seq, int hd, int T0, int rho) {
;     ...
;     for (int rr = 0; rr < 16; ++rr) {
;         const int j = crow(rr, hi);
;         const float il = __builtin_amdgcn_rcpf(__shfl(l, j));
	v_exp_f32_e32 v32, v32
	v_exp_f32_e32 v33, v33
	v_exp_f32_e32 v34, v34
	v_exp_f32_e32 v35, v35
	v_exp_f32_e32 v36, v36
	v_exp_f32_e32 v37, v37
	v_exp_f32_e32 v38, v38
	v_exp_f32_e32 v39, v39
	v_exp_f32_e32 v40, v40
	v_exp_f32_e32 v41, v41
	v_exp_f32_e32 v42, v42
	v_exp_f32_e32 v43, v43
	v_exp_f32_e32 v44, v44
	v_exp_f32_e32 v45, v45
	v_exp_f32_e32 v46, v46
	v_exp_f32_e32 v47, v47
	s_add_i32 s90, s67, 1024
	v_lshlrev_b32_e32 v84, 4, v107
	v_add_u32_e32 v84, s90, v84
	v_add_u32_e32 v85, 0, v84
	v_add_u32_e32 v86, 16, v84
	v_add_u32_e32 v87, 32, v84
	v_add_u32_e32 v88, 48, v84
	v_cmp_gt_u32_e64 s[30:31], s98, v85
	v_cmp_gt_u32_e64 s[36:37], s98, v86
	v_cmp_gt_u32_e64 s[78:79], s98, v87
	v_cmp_gt_u32_e64 s[50:51], s98, v88
	v_cndmask_b32_e64 v32, 0, v32, s[30:31]
	v_add_u32_e32 v85, 128, v84
	v_cmp_gt_u32_e64 s[30:31], s98, v85
	v_cndmask_b32_e64 v33, 0, v33, s[36:37]
	v_add_u32_e32 v86, 144, v84
	v_cmp_gt_u32_e64 s[36:37], s98, v86
	v_cndmask_b32_e64 v34, 0, v34, s[78:79]
	v_add_u32_e32 v87, 160, v84
	v_cmp_gt_u32_e64 s[78:79], s98, v87
	v_cndmask_b32_e64 v35, 0, v35, s[50:51]
	v_add_u32_e32 v88, 176, v84
	v_cmp_gt_u32_e64 s[50:51], s98, v88
	v_cndmask_b32_e64 v36, 0, v36, s[30:31]
	v_add_u32_e32 v85, 256, v84
	v_cmp_gt_u32_e64 s[30:31], s98, v85
	v_cndmask_b32_e64 v37, 0, v37, s[36:37]
	v_add_u32_e32 v86, 272, v84
	v_cmp_gt_u32_e64 s[36:37], s98, v86
	v_cndmask_b32_e64 v38, 0, v38, s[78:79]
	v_add_u32_e32 v87, 288, v84
	v_cmp_gt_u32_e64 s[78:79], s98, v87
	v_cndmask_b32_e64 v39, 0, v39, s[50:51]
	v_add_u32_e32 v88, 304, v84
	v_cmp_gt_u32_e64 s[50:51], s98, v88
	v_cndmask_b32_e64 v40, 0, v40, s[30:31]
	v_add_u32_e32 v85, 384, v84
	v_cmp_gt_u32_e64 s[30:31], s98, v85
	v_cndmask_b32_e64 v41, 0, v41, s[36:37]
	v_add_u32_e32 v86, 400, v84
	v_cmp_gt_u32_e64 s[36:37], s98, v86
	v_cndmask_b32_e64 v42, 0, v42, s[78:79]
	v_add_u32_e32 v87, 416, v84
	v_cmp_gt_u32_e64 s[78:79], s98, v87
	v_cndmask_b32_e64 v43, 0, v43, s[50:51]
	v_add_u32_e32 v88, 432, v84
	v_cmp_gt_u32_e64 s[50:51], s98, v88
	v_nop
	v_cndmask_b32_e64 v44, 0, v44, s[30:31]
	v_cndmask_b32_e64 v45, 0, v45, s[36:37]
	v_cndmask_b32_e64 v46, 0, v46, s[78:79]
	v_cndmask_b32_e64 v47, 0, v47, s[50:51]
	v_cvt_pk_bf16_f32 v64, v32, v33
	v_cvt_pk_bf16_f32 v65, v34, v35
	v_cvt_pk_bf16_f32 v66, v36, v37
	v_cvt_pk_bf16_f32 v67, v38, v39
	v_cvt_pk_bf16_f32 v68, v40, v41
	v_cvt_pk_bf16_f32 v69, v42, v43
	v_cvt_pk_bf16_f32 v70, v44, v45
	v_cvt_pk_bf16_f32 v71, v46, v47
	v_pk_add_f32 v[232:233], v[232:233], v[32:33]
	v_pk_add_f32 v[232:233], v[232:233], v[34:35]
	v_pk_add_f32 v[232:233], v[232:233], v[36:37]
	v_pk_add_f32 v[232:233], v[232:233], v[38:39]
	v_pk_add_f32 v[232:233], v[232:233], v[40:41]
	v_pk_add_f32 v[232:233], v[232:233], v[42:43]
	v_pk_add_f32 v[232:233], v[232:233], v[44:45]
	v_pk_add_f32 v[232:233], v[232:233], v[46:47]
	v_mfma_f32_32x32x16_bf16 v[0:15], v[64:67], v[72:75], v[0:15]
	v_mfma_f32_32x32x16_bf16 v[16:31], v[64:67], v[76:79], v[16:31]
	v_mfma_f32_32x32x16_bf16 v[0:15], v[68:71], v[220:223], v[0:15]
	v_mfma_f32_32x32x16_bf16 v[16:31], v[68:71], v[224:227], v[16:31]
	v_add_f32_e32 v113, v232, v233
	v_or_b32_e32 v114, 1, v107
	v_or_b32_e32 v97, 2, v107
	v_or_b32_e32 v96, 3, v107
	v_or_b32_e32 v95, 8, v107
	v_or_b32_e32 v94, 9, v107
	v_or_b32_e32 v93, 10, v107
	v_or_b32_e32 v92, 11, v107
	v_or_b32_e32 v91, 16, v107
	v_or_b32_e32 v90, 17, v107
	v_or_b32_e32 v89, 18, v107
	v_or_b32_e32 v88, 19, v107
	v_or_b32_e32 v87, 24, v107
	v_or_b32_e32 v86, 25, v107
	v_or_b32_e32 v85, 26, v107
	v_or_b32_e32 v84, 27, v107
	s_nop 11
	s_branch .LBB0_1265
